# hand-written row phases 1,7,10,14,17: unrolled rows, 2-deep prefetch, DPP/permlane reductions, folded gate/scale vectors
# speedup vs baseline: 1.2349x; 1.0382x over previous
; __device__ __forceinline__ void row_phase(const Params& P, int glayer, int layer, int xsrc, bool hasY, int gate_idx, const float* gpost,
;                           int xdst, bool doH, const float* gpre, int sh_idx, int nrows) {
;     ...
;         } else {
;           const float* xin_;
;           if (xsrc == 0) xin_ = R < N_X ? P.x + (long)R * 1024 : P.ctx + (long)(R - N_X) * 1024;
;           else           xin_ = P.xc + (long)(R - N_X) * 1024;
; #pragma unroll
;           for (int i = 0; i < 4; ++i) xr[u][i] = *reinterpret_cast<const uint4*>(xin_ + (i * 64 + lane) * 4);
;     ...
;         if (doH) {
;           float ss = 0.f;
; #pragma unroll
;           for (int i = 0; i < 4; ++i) ss += xv[i].x * xv[i].x + xv[i].y * xv[i].y + xv[i].z * xv[i].z + xv[i].w * xv[i].w;
;           ss = wave_sum(ss);
;           const float rstd = __builtin_amdgcn_rsqf(ss * (1.f / 1024.f) + EPSF);
;           u16* h = P.hy + (long)row * 1024;
; #pragma unroll
;           for (int i = 0; i < 4; ++i) {
;             const int col = (i * 64 + lane) * 4;
;             const float4 g = *reinterpret_cast<const float4*>(gpre + col);
;             const float4 sh = *reinterpret_cast<const float4*>(modp + sh_idx * 1024 + col);
;             const float4 sc = *reinterpret_cast<const float4*>(modp + (sh_idx + 1) * 1024 + col);
;             const unsigned h0 = f2bf(xv[i].x * rstd * g.x * (1.f + sc.x) + sh.x);
;             const unsigned h1 = f2bf(xv[i].y * rstd * g.y * (1.f + sc.y) + sh.y);
;             const unsigned h2 = f2bf(xv[i].z * rstd * g.z * (1.f + sc.z) + sh.z);
;             const unsigned h3 = f2bf(xv[i].w * rstd * g.w * (1.f + sc.w) + sh.w);
;             *reinterpret_cast<uint2*>(h + col) = make_uint2(h0 | (h1 << 16), h2 | (h3 << 16));
;           }
.LBB0_93:
	s_cmp_gt_i32 s6, 1
	s_cselect_b64 s[0:1], -1, 0
	s_cmp_lt_i32 s7, 2
	s_cselect_b64 s[4:5], -1, 0
	s_or_b64 s[0:1], s[0:1], s[4:5]
	v_readlane_b32 s66, v252, 18
	s_and_b64 vcc, exec, s[0:1]
	v_lshrrev_b32_e32 v204, 6, v152
	v_readlane_b32 s67, v252, 19
	s_mov_b64 s[34:35], s[6:7]
	s_cbranch_vccnz .LBB0_163
	v_lshl_add_u32 v64, s2, 3, v204
	s_mov_b32 s3, 0x8400
	v_mov_b32_e32 v0, v153
	v_cmp_gt_i32_e32 vcc, s3, v64
	s_and_saveexec_b64 s[8:9], vcc
	s_cbranch_execz .LBB0_109
	v_readlane_b32 s4, v252, 0
	v_readlane_b32 s5, v252, 1
	v_readfirstlane_b32 s19, v204
	s_nop 3
	s_sub_u32 s4, s4, 0x170
	s_subb_u32 s5, s5, 0
	s_load_dwordx2 s[12:13], s[4:5], 0x0
	s_load_dwordx2 s[14:15], s[4:5], 0x140
	s_load_dwordx2 s[20:21], s[4:5], 0x100
	s_lshl_b32 s98, s2, 3
	s_add_u32 s19, s98, s19
	v_and_b32_e32 v136, 63, v152
	v_lshlrev_b32_e32 v137, 3, v136
	v_lshlrev_b32_e32 v136, 4, v136
	s_waitcnt lgkmcnt(0)
	s_lshl_b32 vcc_lo, s19, 12
	s_add_u32 s100, s12, vcc_lo
	s_addc_u32 s101, s13, 0
	global_load_dwordx4 v[0:3], v136, s[100:101] offset:0
	global_load_dwordx4 v[4:7], v136, s[100:101] offset:1024
	global_load_dwordx4 v[8:11], v136, s[100:101] offset:2048
	global_load_dwordx4 v[12:15], v136, s[100:101] offset:3072
	s_lshl_b32 vcc_lo, s19, 12
	s_add_u32 vcc_lo, vcc_lo, 0x800000
	s_add_u32 s100, s12, vcc_lo
	s_addc_u32 s101, s13, 0
	global_load_dwordx4 v[16:19], v136, s[100:101] offset:0
	global_load_dwordx4 v[20:23], v136, s[100:101] offset:1024
	global_load_dwordx4 v[24:27], v136, s[100:101] offset:2048
	global_load_dwordx4 v[28:31], v136, s[100:101] offset:3072
	s_add_u32 s100, s20, 0x0
	s_addc_u32 s101, s21, 0
	global_load_dwordx4 v[104:107], v136, s[100:101] offset:0
	global_load_dwordx4 v[108:111], v136, s[100:101] offset:1024
	global_load_dwordx4 v[112:115], v136, s[100:101] offset:2048
	global_load_dwordx4 v[116:119], v136, s[100:101] offset:3072
	s_add_u32 s100, s100, 0x1000
	s_addc_u32 s101, s101, 0
	global_load_dwordx4 v[32:35], v136, s[100:101] offset:0
	global_load_dwordx4 v[36:39], v136, s[100:101] offset:1024
	global_load_dwordx4 v[40:43], v136, s[100:101] offset:2048
	global_load_dwordx4 v[44:47], v136, s[100:101] offset:3072
	s_load_dwordx2 s[98:99], s[4:5], 0x30
	s_waitcnt lgkmcnt(0)
	global_load_dwordx4 v[88:91], v136, s[98:99] offset:0
	global_load_dwordx4 v[92:95], v136, s[98:99] offset:1024
	global_load_dwordx4 v[96:99], v136, s[98:99] offset:2048
	global_load_dwordx4 v[100:103], v136, s[98:99] offset:3072
	s_waitcnt vmcnt(0)
	v_fma_f32 v88, v88, v32, v88
	v_fma_f32 v89, v89, v33, v89
	v_fma_f32 v90, v90, v34, v90
	v_fma_f32 v91, v91, v35, v91
	v_fma_f32 v92, v92, v36, v92
	v_fma_f32 v93, v93, v37, v93
	v_fma_f32 v94, v94, v38, v94
	v_fma_f32 v95, v95, v39, v95
	v_fma_f32 v96, v96, v40, v96
	v_fma_f32 v97, v97, v41, v97
	v_fma_f32 v98, v98, v42, v98
	v_fma_f32 v99, v99, v43, v99
	v_fma_f32 v100, v100, v44, v100
	v_fma_f32 v101, v101, v45, v101
	v_fma_f32 v102, v102, v46, v102
	v_fma_f32 v103, v103, v47, v103
	s_lshl_b32 vcc_lo, s19, 12
	s_add_u32 vcc_lo, vcc_lo, 0x1000000
	s_add_u32 s100, s12, vcc_lo
	s_addc_u32 s101, s13, 0
	global_load_dwordx4 v[32:35], v136, s[100:101] offset:0
	global_load_dwordx4 v[36:39], v136, s[100:101] offset:1024
	global_load_dwordx4 v[40:43], v136, s[100:101] offset:2048
	global_load_dwordx4 v[44:47], v136, s[100:101] offset:3072
	v_mul_f32_e32 v138, v0, v0
	v_mul_f32_e32 v149, v1, v1
	v_mul_f32_e32 v150, v2, v2
	v_mul_f32_e32 v154, v3, v3
	v_fma_f32 v138, v4, v4, v138
	v_fma_f32 v149, v5, v5, v149
	v_fma_f32 v150, v6, v6, v150
	v_fma_f32 v154, v7, v7, v154
	v_fma_f32 v138, v8, v8, v138
	v_fma_f32 v149, v9, v9, v149
	v_fma_f32 v150, v10, v10, v150
	v_fma_f32 v154, v11, v11, v154
	v_fma_f32 v138, v12, v12, v138
	v_fma_f32 v149, v13, v13, v149
	v_fma_f32 v150, v14, v14, v150
	v_fma_f32 v154, v15, v15, v154
	v_add_f32_e32 v138, v138, v149
	v_add_f32_e32 v150, v150, v154
	v_add_f32_e32 v138, v138, v150
	s_nop 1
	v_add_f32_dpp v138, v138, v138 quad_perm:[1,0,3,2] row_mask:0xf bank_mask:0xf
	s_nop 1
	v_add_f32_dpp v138, v138, v138 quad_perm:[2,3,0,1] row_mask:0xf bank_mask:0xf
	s_nop 1
	v_add_f32_dpp v138, v138, v138 row_half_mirror row_mask:0xf bank_mask:0xf
	s_nop 1
	v_add_f32_dpp v138, v138, v138 row_mirror row_mask:0xf bank_mask:0xf
	v_mov_b32_e32 v139, v138
	s_nop 1
	v_permlane16_swap_b32_e32 v138, v139
	v_add_f32_e32 v138, v138, v139
	v_mov_b32_e32 v139, v138
	s_nop 1
	v_permlane32_swap_b32_e32 v138, v139
	v_add_f32_e32 v138, v138, v139
	v_mul_f32_e32 v138, 0x3a800000, v138
	v_add_f32_e32 v138, 0x358637bd, v138
	v_rsq_f32_e32 v140, v138
	s_nop 0
	v_mul_f32_e32 v120, v0, v140
	v_mul_f32_e32 v121, v1, v140
	v_mul_f32_e32 v122, v2, v140
	v_mul_f32_e32 v123, v3, v140
	v_mul_f32_e32 v124, v4, v140
	v_mul_f32_e32 v125, v5, v140
	v_mul_f32_e32 v126, v6, v140
	v_mul_f32_e32 v127, v7, v140
	v_mul_f32_e32 v128, v8, v140
	v_mul_f32_e32 v129, v9, v140
	v_mul_f32_e32 v130, v10, v140
	v_mul_f32_e32 v131, v11, v140
	v_mul_f32_e32 v132, v12, v140
	v_mul_f32_e32 v133, v13, v140
	v_mul_f32_e32 v134, v14, v140
	v_mul_f32_e32 v135, v15, v140
	v_fma_f32 v120, v120, v88, v104
	v_fma_f32 v121, v121, v89, v105
	v_fma_f32 v122, v122, v90, v106
	v_fma_f32 v123, v123, v91, v107
	v_fma_f32 v124, v124, v92, v108
	v_fma_f32 v125, v125, v93, v109
	v_fma_f32 v126, v126, v94, v110
	v_fma_f32 v127, v127, v95, v111
	v_fma_f32 v128, v128, v96, v112
	v_fma_f32 v129, v129, v97, v113
	v_fma_f32 v130, v130, v98, v114
	v_fma_f32 v131, v131, v99, v115
	v_fma_f32 v132, v132, v100, v116
	v_fma_f32 v133, v133, v101, v117
	v_fma_f32 v134, v134, v102, v118
	v_fma_f32 v135, v135, v103, v119
	v_cvt_pk_bf16_f32 v156, v120, v121
; __device__ __forceinline__ void row_phase(const Params& P, int glayer, int layer, int xsrc, bool hasY, int gate_idx, const float* gpost,
;                           int xdst, bool doH, const float* gpre, int sh_idx, int nrows) {
;     ...
;         if (doH) {
;           float ss = 0.f;
; #pragma unroll
;           for (int i = 0; i < 4; ++i) ss += xv[i].x * xv[i].x + xv[i].y * xv[i].y + xv[i].z * xv[i].z + xv[i].w * xv[i].w;
;           ss = wave_sum(ss);
;           const float rstd = __builtin_amdgcn_rsqf(ss * (1.f / 1024.f) + EPSF);
;           u16* h = P.hy + (long)row * 1024;
; #pragma unroll
;           for (int i = 0; i < 4; ++i) {
;             const int col = (i * 64 + lane) * 4;
;             const float4 g = *reinterpret_cast<const float4*>(gpre + col);
;             const float4 sh = *reinterpret_cast<const float4*>(modp + sh_idx * 1024 + col);
;             const float4 sc = *reinterpret_cast<const float4*>(modp + (sh_idx + 1) * 1024 + col);
;             const unsigned h0 = f2bf(xv[i].x * rstd * g.x * (1.f + sc.x) + sh.x);
;             const unsigned h1 = f2bf(xv[i].y * rstd * g.y * (1.f + sc.y) + sh.y);
;             const unsigned h2 = f2bf(xv[i].z * rstd * g.z * (1.f + sc.z) + sh.z);
;             const unsigned h3 = f2bf(xv[i].w * rstd * g.w * (1.f + sc.w) + sh.w);
;             *reinterpret_cast<uint2*>(h + col) = make_uint2(h0 | (h1 << 16), h2 | (h3 << 16));
;           }
	v_cvt_pk_bf16_f32 v157, v122, v123
	v_cvt_pk_bf16_f32 v158, v124, v125
	v_cvt_pk_bf16_f32 v159, v126, v127
	v_cvt_pk_bf16_f32 v160, v128, v129
	v_cvt_pk_bf16_f32 v161, v130, v131
	v_cvt_pk_bf16_f32 v162, v132, v133
	v_cvt_pk_bf16_f32 v163, v134, v135
	s_lshl_b32 vcc_lo, s19, 11
	s_add_u32 s100, s14, vcc_lo
	s_addc_u32 s101, s15, 0
	global_store_dwordx2 v137, v[156:157], s[100:101] offset:0
	global_store_dwordx2 v137, v[158:159], s[100:101] offset:512
	global_store_dwordx2 v137, v[160:161], s[100:101] offset:1024
	global_store_dwordx2 v137, v[162:163], s[100:101] offset:1536
	s_lshl_b32 vcc_lo, s19, 12
	s_add_u32 vcc_lo, vcc_lo, 0x1800000
	s_add_u32 s100, s12, vcc_lo
	s_addc_u32 s101, s13, 0
	global_load_dwordx4 v[0:3], v136, s[100:101] offset:0
	global_load_dwordx4 v[4:7], v136, s[100:101] offset:1024
	global_load_dwordx4 v[8:11], v136, s[100:101] offset:2048
	global_load_dwordx4 v[12:15], v136, s[100:101] offset:3072
	v_mul_f32_e32 v138, v16, v16
	v_mul_f32_e32 v149, v17, v17
	v_mul_f32_e32 v150, v18, v18
	v_mul_f32_e32 v154, v19, v19
	v_fma_f32 v138, v20, v20, v138
	v_fma_f32 v149, v21, v21, v149
	v_fma_f32 v150, v22, v22, v150
	v_fma_f32 v154, v23, v23, v154
	v_fma_f32 v138, v24, v24, v138
	v_fma_f32 v149, v25, v25, v149
	v_fma_f32 v150, v26, v26, v150
	v_fma_f32 v154, v27, v27, v154
	v_fma_f32 v138, v28, v28, v138
	v_fma_f32 v149, v29, v29, v149
	v_fma_f32 v150, v30, v30, v150
	v_fma_f32 v154, v31, v31, v154
	v_add_f32_e32 v138, v138, v149
	v_add_f32_e32 v150, v150, v154
	v_add_f32_e32 v138, v138, v150
	s_nop 1
	v_add_f32_dpp v138, v138, v138 quad_perm:[1,0,3,2] row_mask:0xf bank_mask:0xf
	s_nop 1
	v_add_f32_dpp v138, v138, v138 quad_perm:[2,3,0,1] row_mask:0xf bank_mask:0xf
	s_nop 1
	v_add_f32_dpp v138, v138, v138 row_half_mirror row_mask:0xf bank_mask:0xf
	s_nop 1
	v_add_f32_dpp v138, v138, v138 row_mirror row_mask:0xf bank_mask:0xf
	v_mov_b32_e32 v139, v138
	s_nop 1
	v_permlane16_swap_b32_e32 v138, v139
	v_add_f32_e32 v138, v138, v139
	v_mov_b32_e32 v139, v138
	s_nop 1
	v_permlane32_swap_b32_e32 v138, v139
	v_add_f32_e32 v138, v138, v139
	v_mul_f32_e32 v138, 0x3a800000, v138
	v_add_f32_e32 v138, 0x358637bd, v138
	v_rsq_f32_e32 v140, v138
	s_nop 0
	v_mul_f32_e32 v120, v16, v140
	v_mul_f32_e32 v121, v17, v140
	v_mul_f32_e32 v122, v18, v140
	v_mul_f32_e32 v123, v19, v140
	v_mul_f32_e32 v124, v20, v140
	v_mul_f32_e32 v125, v21, v140
	v_mul_f32_e32 v126, v22, v140
	v_mul_f32_e32 v127, v23, v140
	v_mul_f32_e32 v128, v24, v140
	v_mul_f32_e32 v129, v25, v140
	v_mul_f32_e32 v130, v26, v140
	v_mul_f32_e32 v131, v27, v140
	v_mul_f32_e32 v132, v28, v140
	v_mul_f32_e32 v133, v29, v140
	v_mul_f32_e32 v134, v30, v140
	v_mul_f32_e32 v135, v31, v140
	v_fma_f32 v120, v120, v88, v104
	v_fma_f32 v121, v121, v89, v105
	v_fma_f32 v122, v122, v90, v106
	v_fma_f32 v123, v123, v91, v107
	v_fma_f32 v124, v124, v92, v108
	v_fma_f32 v125, v125, v93, v109
	v_fma_f32 v126, v126, v94, v110
	v_fma_f32 v127, v127, v95, v111
	v_fma_f32 v128, v128, v96, v112
	v_fma_f32 v129, v129, v97, v113
	v_fma_f32 v130, v130, v98, v114
	v_fma_f32 v131, v131, v99, v115
	v_fma_f32 v132, v132, v100, v116
	v_fma_f32 v133, v133, v101, v117
	v_fma_f32 v134, v134, v102, v118
	v_fma_f32 v135, v135, v103, v119
	v_cvt_pk_bf16_f32 v156, v120, v121
	v_cvt_pk_bf16_f32 v157, v122, v123
	v_cvt_pk_bf16_f32 v158, v124, v125
	v_cvt_pk_bf16_f32 v159, v126, v127
	v_cvt_pk_bf16_f32 v160, v128, v129
	v_cvt_pk_bf16_f32 v161, v130, v131
	v_cvt_pk_bf16_f32 v162, v132, v133
	v_cvt_pk_bf16_f32 v163, v134, v135
	s_lshl_b32 vcc_lo, s19, 11
	s_add_u32 vcc_lo, vcc_lo, 0x400000
	s_add_u32 s100, s14, vcc_lo
	s_addc_u32 s101, s15, 0
	global_store_dwordx2 v137, v[156:157], s[100:101] offset:0
	global_store_dwordx2 v137, v[158:159], s[100:101] offset:512
	global_store_dwordx2 v137, v[160:161], s[100:101] offset:1024
	global_store_dwordx2 v137, v[162:163], s[100:101] offset:1536
	s_lshl_b32 vcc_lo, s19, 12
	s_add_u32 vcc_lo, vcc_lo, 0x2000000
	s_add_u32 s100, s12, vcc_lo
	s_addc_u32 s101, s13, 0
	global_load_dwordx4 v[16:19], v136, s[100:101] offset:0
	global_load_dwordx4 v[20:23], v136, s[100:101] offset:1024
	global_load_dwordx4 v[24:27], v136, s[100:101] offset:2048
	global_load_dwordx4 v[28:31], v136, s[100:101] offset:3072
	s_waitcnt vmcnt(16)
; __device__ __forceinline__ void row_phase(const Params& P, int glayer, int layer, int xsrc, bool hasY, int gate_idx, const float* gpost,
;                           int xdst, bool doH, const float* gpre, int sh_idx, int nrows) {
;     ...
;         const int mi = row < N_X ? (row >> 13) : 4;
;         const float* modp = P.mod + (long)(layer * 5 + mi) * 6144;
;     ...
;         if (doH) {
;           float ss = 0.f;
; #pragma unroll
;           for (int i = 0; i < 4; ++i) ss += xv[i].x * xv[i].x + xv[i].y * xv[i].y + xv[i].z * xv[i].z + xv[i].w * xv[i].w;
;           ss = wave_sum(ss);
;           const float rstd = __builtin_amdgcn_rsqf(ss * (1.f / 1024.f) + EPSF);
;           u16* h = P.hy + (long)row * 1024;
; #pragma unroll
;           for (int i = 0; i < 4; ++i) {
;             const int col = (i * 64 + lane) * 4;
;             const float4 g = *reinterpret_cast<const float4*>(gpre + col);
;             const float4 sh = *reinterpret_cast<const float4*>(modp + sh_idx * 1024 + col);
;             const float4 sc = *reinterpret_cast<const float4*>(modp + (sh_idx + 1) * 1024 + col);
;             const unsigned h0 = f2bf(xv[i].x * rstd * g.x * (1.f + sc.x) + sh.x);
;             const unsigned h1 = f2bf(xv[i].y * rstd * g.y * (1.f + sc.y) + sh.y);
;             const unsigned h2 = f2bf(xv[i].z * rstd * g.z * (1.f + sc.z) + sh.z);
;             const unsigned h3 = f2bf(xv[i].w * rstd * g.w * (1.f + sc.w) + sh.w);
;             *reinterpret_cast<uint2*>(h + col) = make_uint2(h0 | (h1 << 16), h2 | (h3 << 16));
;           }
	v_mul_f32_e32 v138, v32, v32
	v_mul_f32_e32 v149, v33, v33
	v_mul_f32_e32 v150, v34, v34
	v_mul_f32_e32 v154, v35, v35
	v_fma_f32 v138, v36, v36, v138
	v_fma_f32 v149, v37, v37, v149
	v_fma_f32 v150, v38, v38, v150
	v_fma_f32 v154, v39, v39, v154
	v_fma_f32 v138, v40, v40, v138
	v_fma_f32 v149, v41, v41, v149
	v_fma_f32 v150, v42, v42, v150
	v_fma_f32 v154, v43, v43, v154
	v_fma_f32 v138, v44, v44, v138
	v_fma_f32 v149, v45, v45, v149
	v_fma_f32 v150, v46, v46, v150
	v_fma_f32 v154, v47, v47, v154
	v_add_f32_e32 v138, v138, v149
	v_add_f32_e32 v150, v150, v154
	v_add_f32_e32 v138, v138, v150
	s_nop 1
	v_add_f32_dpp v138, v138, v138 quad_perm:[1,0,3,2] row_mask:0xf bank_mask:0xf
	s_nop 1
	v_add_f32_dpp v138, v138, v138 quad_perm:[2,3,0,1] row_mask:0xf bank_mask:0xf
	s_nop 1
	v_add_f32_dpp v138, v138, v138 row_half_mirror row_mask:0xf bank_mask:0xf
	s_nop 1
	v_add_f32_dpp v138, v138, v138 row_mirror row_mask:0xf bank_mask:0xf
	v_mov_b32_e32 v139, v138
	s_nop 1
	v_permlane16_swap_b32_e32 v138, v139
	v_add_f32_e32 v138, v138, v139
	v_mov_b32_e32 v139, v138
	s_nop 1
	v_permlane32_swap_b32_e32 v138, v139
	v_add_f32_e32 v138, v138, v139
	v_mul_f32_e32 v138, 0x3a800000, v138
	v_add_f32_e32 v138, 0x358637bd, v138
	v_rsq_f32_e32 v140, v138
	s_nop 0
	v_mul_f32_e32 v120, v32, v140
	v_mul_f32_e32 v121, v33, v140
	v_mul_f32_e32 v122, v34, v140
	v_mul_f32_e32 v123, v35, v140
	v_mul_f32_e32 v124, v36, v140
	v_mul_f32_e32 v125, v37, v140
	v_mul_f32_e32 v126, v38, v140
	v_mul_f32_e32 v127, v39, v140
	v_mul_f32_e32 v128, v40, v140
	v_mul_f32_e32 v129, v41, v140
	v_mul_f32_e32 v130, v42, v140
	v_mul_f32_e32 v131, v43, v140
	v_mul_f32_e32 v132, v44, v140
	v_mul_f32_e32 v133, v45, v140
	v_mul_f32_e32 v134, v46, v140
	v_mul_f32_e32 v135, v47, v140
	v_fma_f32 v120, v120, v88, v104
	v_fma_f32 v121, v121, v89, v105
	v_fma_f32 v122, v122, v90, v106
	v_fma_f32 v123, v123, v91, v107
	v_fma_f32 v124, v124, v92, v108
	v_fma_f32 v125, v125, v93, v109
	v_fma_f32 v126, v126, v94, v110
	v_fma_f32 v127, v127, v95, v111
	v_fma_f32 v128, v128, v96, v112
	v_fma_f32 v129, v129, v97, v113
	v_fma_f32 v130, v130, v98, v114
	v_fma_f32 v131, v131, v99, v115
	v_fma_f32 v132, v132, v100, v116
	v_fma_f32 v133, v133, v101, v117
	v_fma_f32 v134, v134, v102, v118
	v_fma_f32 v135, v135, v103, v119
	v_cvt_pk_bf16_f32 v156, v120, v121
	v_cvt_pk_bf16_f32 v157, v122, v123
	v_cvt_pk_bf16_f32 v158, v124, v125
	v_cvt_pk_bf16_f32 v159, v126, v127
	v_cvt_pk_bf16_f32 v160, v128, v129
	v_cvt_pk_bf16_f32 v161, v130, v131
	v_cvt_pk_bf16_f32 v162, v132, v133
	v_cvt_pk_bf16_f32 v163, v134, v135
	s_lshl_b32 vcc_lo, s19, 11
	s_add_u32 vcc_lo, vcc_lo, 0x800000
	s_add_u32 s100, s14, vcc_lo
	s_addc_u32 s101, s15, 0
	global_store_dwordx2 v137, v[156:157], s[100:101] offset:0
	global_store_dwordx2 v137, v[158:159], s[100:101] offset:512
	global_store_dwordx2 v137, v[160:161], s[100:101] offset:1024
	global_store_dwordx2 v137, v[162:163], s[100:101] offset:1536
	s_lshl_b32 vcc_lo, s19, 12
	s_add_u32 vcc_lo, vcc_lo, 0x2800000
	s_add_u32 s100, s12, vcc_lo
	s_addc_u32 s101, s13, 0
	global_load_dwordx4 v[32:35], v136, s[100:101] offset:0
	global_load_dwordx4 v[36:39], v136, s[100:101] offset:1024
	global_load_dwordx4 v[40:43], v136, s[100:101] offset:2048
	global_load_dwordx4 v[44:47], v136, s[100:101] offset:3072
	s_waitcnt vmcnt(16)
	v_mul_f32_e32 v138, v0, v0
	v_mul_f32_e32 v149, v1, v1
	v_mul_f32_e32 v150, v2, v2
	v_mul_f32_e32 v154, v3, v3
	v_fma_f32 v138, v4, v4, v138
	v_fma_f32 v149, v5, v5, v149
	v_fma_f32 v150, v6, v6, v150
	v_fma_f32 v154, v7, v7, v154
	v_fma_f32 v138, v8, v8, v138
	v_fma_f32 v149, v9, v9, v149
	v_fma_f32 v150, v10, v10, v150
	v_fma_f32 v154, v11, v11, v154
	v_fma_f32 v138, v12, v12, v138
	v_fma_f32 v149, v13, v13, v149
	v_fma_f32 v150, v14, v14, v150
	v_fma_f32 v154, v15, v15, v154
	v_add_f32_e32 v138, v138, v149
	v_add_f32_e32 v150, v150, v154
	v_add_f32_e32 v138, v138, v150
	s_nop 1
	v_add_f32_dpp v138, v138, v138 quad_perm:[1,0,3,2] row_mask:0xf bank_mask:0xf
	s_nop 1
	v_add_f32_dpp v138, v138, v138 quad_perm:[2,3,0,1] row_mask:0xf bank_mask:0xf
	s_nop 1
	v_add_f32_dpp v138, v138, v138 row_half_mirror row_mask:0xf bank_mask:0xf
	s_nop 1
	v_add_f32_dpp v138, v138, v138 row_mirror row_mask:0xf bank_mask:0xf
	v_mov_b32_e32 v139, v138
	s_nop 1
	v_permlane16_swap_b32_e32 v138, v139
	v_add_f32_e32 v138, v138, v139
	v_mov_b32_e32 v139, v138
	s_nop 1
	v_permlane32_swap_b32_e32 v138, v139
	v_add_f32_e32 v138, v138, v139
	v_mul_f32_e32 v138, 0x3a800000, v138
	v_add_f32_e32 v138, 0x358637bd, v138
	v_rsq_f32_e32 v140, v138
	s_nop 0
	v_mul_f32_e32 v120, v0, v140
	v_mul_f32_e32 v121, v1, v140
	v_mul_f32_e32 v122, v2, v140
	v_mul_f32_e32 v123, v3, v140
	v_mul_f32_e32 v124, v4, v140
	v_mul_f32_e32 v125, v5, v140
	v_mul_f32_e32 v126, v6, v140
	v_mul_f32_e32 v127, v7, v140
	v_mul_f32_e32 v128, v8, v140
	v_mul_f32_e32 v129, v9, v140
	v_mul_f32_e32 v130, v10, v140
	v_mul_f32_e32 v131, v11, v140
	v_mul_f32_e32 v132, v12, v140
	v_mul_f32_e32 v133, v13, v140
	v_mul_f32_e32 v134, v14, v140
	v_mul_f32_e32 v135, v15, v140
	v_fma_f32 v120, v120, v88, v104
	v_fma_f32 v121, v121, v89, v105
	v_fma_f32 v122, v122, v90, v106
	v_fma_f32 v123, v123, v91, v107
	v_fma_f32 v124, v124, v92, v108
	v_fma_f32 v125, v125, v93, v109
	v_fma_f32 v126, v126, v94, v110
	v_fma_f32 v127, v127, v95, v111
	v_fma_f32 v128, v128, v96, v112
	v_fma_f32 v129, v129, v97, v113
	v_fma_f32 v130, v130, v98, v114
	v_fma_f32 v131, v131, v99, v115
	v_fma_f32 v132, v132, v100, v116
	v_fma_f32 v133, v133, v101, v117
	v_fma_f32 v134, v134, v102, v118
	v_fma_f32 v135, v135, v103, v119
	v_cvt_pk_bf16_f32 v156, v120, v121
	v_cvt_pk_bf16_f32 v157, v122, v123
	v_cvt_pk_bf16_f32 v158, v124, v125
	v_cvt_pk_bf16_f32 v159, v126, v127
	v_cvt_pk_bf16_f32 v160, v128, v129
	v_cvt_pk_bf16_f32 v161, v130, v131
	v_cvt_pk_bf16_f32 v162, v132, v133
	v_cvt_pk_bf16_f32 v163, v134, v135
	s_lshl_b32 vcc_lo, s19, 11
	s_add_u32 vcc_lo, vcc_lo, 0xc00000
	s_add_u32 s100, s14, vcc_lo
	s_addc_u32 s101, s15, 0
	global_store_dwordx2 v137, v[156:157], s[100:101] offset:0
	global_store_dwordx2 v137, v[158:159], s[100:101] offset:512
	global_store_dwordx2 v137, v[160:161], s[100:101] offset:1024
	global_store_dwordx2 v137, v[162:163], s[100:101] offset:1536
	s_add_u32 s100, s20, 0x6000
	s_addc_u32 s101, s21, 0
	global_load_dwordx4 v[104:107], v136, s[100:101] offset:0
	global_load_dwordx4 v[108:111], v136, s[100:101] offset:1024
	global_load_dwordx4 v[112:115], v136, s[100:101] offset:2048
	global_load_dwordx4 v[116:119], v136, s[100:101] offset:3072
	s_add_u32 s100, s100, 0x1000
	s_addc_u32 s101, s101, 0
	global_load_dwordx4 v[0:3], v136, s[100:101] offset:0
	global_load_dwordx4 v[4:7], v136, s[100:101] offset:1024
	global_load_dwordx4 v[8:11], v136, s[100:101] offset:2048
	global_load_dwordx4 v[12:15], v136, s[100:101] offset:3072
	s_load_dwordx2 s[98:99], s[4:5], 0x30
	s_waitcnt lgkmcnt(0)
; __device__ __forceinline__ void row_phase(const Params& P, int glayer, int layer, int xsrc, bool hasY, int gate_idx, const float* gpost,
;                           int xdst, bool doH, const float* gpre, int sh_idx, int nrows) {
;     ...
;         const int mi = row < N_X ? (row >> 13) : 4;
;         const float* modp = P.mod + (long)(layer * 5 + mi) * 6144;
;     ...
;         if (doH) {
;           float ss = 0.f;
; #pragma unroll
;           for (int i = 0; i < 4; ++i) ss += xv[i].x * xv[i].x + xv[i].y * xv[i].y + xv[i].z * xv[i].z + xv[i].w * xv[i].w;
;           ss = wave_sum(ss);
;           const float rstd = __builtin_amdgcn_rsqf(ss * (1.f / 1024.f) + EPSF);
;           u16* h = P.hy + (long)row * 1024;
; #pragma unroll
;           for (int i = 0; i < 4; ++i) {
;             const int col = (i * 64 + lane) * 4;
;             const float4 g = *reinterpret_cast<const float4*>(gpre + col);
;             const float4 sh = *reinterpret_cast<const float4*>(modp + sh_idx * 1024 + col);
;             const float4 sc = *reinterpret_cast<const float4*>(modp + (sh_idx + 1) * 1024 + col);
;             const unsigned h0 = f2bf(xv[i].x * rstd * g.x * (1.f + sc.x) + sh.x);
;             const unsigned h1 = f2bf(xv[i].y * rstd * g.y * (1.f + sc.y) + sh.y);
;             const unsigned h2 = f2bf(xv[i].z * rstd * g.z * (1.f + sc.z) + sh.z);
;             const unsigned h3 = f2bf(xv[i].w * rstd * g.w * (1.f + sc.w) + sh.w);
;             *reinterpret_cast<uint2*>(h + col) = make_uint2(h0 | (h1 << 16), h2 | (h3 << 16));
;           }
	global_load_dwordx4 v[88:91], v136, s[98:99] offset:0
	global_load_dwordx4 v[92:95], v136, s[98:99] offset:1024
	global_load_dwordx4 v[96:99], v136, s[98:99] offset:2048
	global_load_dwordx4 v[100:103], v136, s[98:99] offset:3072
	s_waitcnt vmcnt(0)
	v_fma_f32 v88, v88, v0, v88
	v_fma_f32 v89, v89, v1, v89
	v_fma_f32 v90, v90, v2, v90
	v_fma_f32 v91, v91, v3, v91
	v_fma_f32 v92, v92, v4, v92
	v_fma_f32 v93, v93, v5, v93
	v_fma_f32 v94, v94, v6, v94
	v_fma_f32 v95, v95, v7, v95
	v_fma_f32 v96, v96, v8, v96
	v_fma_f32 v97, v97, v9, v97
	v_fma_f32 v98, v98, v10, v98
	v_fma_f32 v99, v99, v11, v99
	v_fma_f32 v100, v100, v12, v100
	v_fma_f32 v101, v101, v13, v101
	v_fma_f32 v102, v102, v14, v102
	v_fma_f32 v103, v103, v15, v103
	s_lshl_b32 vcc_lo, s19, 12
	s_add_u32 vcc_lo, vcc_lo, 0x3000000
	s_add_u32 s100, s12, vcc_lo
	s_addc_u32 s101, s13, 0
	global_load_dwordx4 v[0:3], v136, s[100:101] offset:0
	global_load_dwordx4 v[4:7], v136, s[100:101] offset:1024
	global_load_dwordx4 v[8:11], v136, s[100:101] offset:2048
	global_load_dwordx4 v[12:15], v136, s[100:101] offset:3072
	v_mul_f32_e32 v138, v16, v16
	v_mul_f32_e32 v149, v17, v17
	v_mul_f32_e32 v150, v18, v18
	v_mul_f32_e32 v154, v19, v19
	v_fma_f32 v138, v20, v20, v138
	v_fma_f32 v149, v21, v21, v149
	v_fma_f32 v150, v22, v22, v150
	v_fma_f32 v154, v23, v23, v154
	v_fma_f32 v138, v24, v24, v138
	v_fma_f32 v149, v25, v25, v149
	v_fma_f32 v150, v26, v26, v150
	v_fma_f32 v154, v27, v27, v154
	v_fma_f32 v138, v28, v28, v138
	v_fma_f32 v149, v29, v29, v149
	v_fma_f32 v150, v30, v30, v150
	v_fma_f32 v154, v31, v31, v154
	v_add_f32_e32 v138, v138, v149
	v_add_f32_e32 v150, v150, v154
	v_add_f32_e32 v138, v138, v150
	s_nop 1
	v_add_f32_dpp v138, v138, v138 quad_perm:[1,0,3,2] row_mask:0xf bank_mask:0xf
	s_nop 1
	v_add_f32_dpp v138, v138, v138 quad_perm:[2,3,0,1] row_mask:0xf bank_mask:0xf
	s_nop 1
	v_add_f32_dpp v138, v138, v138 row_half_mirror row_mask:0xf bank_mask:0xf
	s_nop 1
	v_add_f32_dpp v138, v138, v138 row_mirror row_mask:0xf bank_mask:0xf
	v_mov_b32_e32 v139, v138
	s_nop 1
	v_permlane16_swap_b32_e32 v138, v139
	v_add_f32_e32 v138, v138, v139
	v_mov_b32_e32 v139, v138
	s_nop 1
	v_permlane32_swap_b32_e32 v138, v139
	v_add_f32_e32 v138, v138, v139
	v_mul_f32_e32 v138, 0x3a800000, v138
	v_add_f32_e32 v138, 0x358637bd, v138
	v_rsq_f32_e32 v140, v138
	s_nop 0
	v_mul_f32_e32 v120, v16, v140
	v_mul_f32_e32 v121, v17, v140
	v_mul_f32_e32 v122, v18, v140
	v_mul_f32_e32 v123, v19, v140
	v_mul_f32_e32 v124, v20, v140
	v_mul_f32_e32 v125, v21, v140
	v_mul_f32_e32 v126, v22, v140
	v_mul_f32_e32 v127, v23, v140
	v_mul_f32_e32 v128, v24, v140
	v_mul_f32_e32 v129, v25, v140
	v_mul_f32_e32 v130, v26, v140
	v_mul_f32_e32 v131, v27, v140
	v_mul_f32_e32 v132, v28, v140
	v_mul_f32_e32 v133, v29, v140
	v_mul_f32_e32 v134, v30, v140
	v_mul_f32_e32 v135, v31, v140
	v_fma_f32 v120, v120, v88, v104
	v_fma_f32 v121, v121, v89, v105
	v_fma_f32 v122, v122, v90, v106
	v_fma_f32 v123, v123, v91, v107
	v_fma_f32 v124, v124, v92, v108
	v_fma_f32 v125, v125, v93, v109
	v_fma_f32 v126, v126, v94, v110
	v_fma_f32 v127, v127, v95, v111
	v_fma_f32 v128, v128, v96, v112
	v_fma_f32 v129, v129, v97, v113
	v_fma_f32 v130, v130, v98, v114
	v_fma_f32 v131, v131, v99, v115
	v_fma_f32 v132, v132, v100, v116
	v_fma_f32 v133, v133, v101, v117
	v_fma_f32 v134, v134, v102, v118
	v_fma_f32 v135, v135, v103, v119
	v_cvt_pk_bf16_f32 v156, v120, v121
	v_cvt_pk_bf16_f32 v157, v122, v123
	v_cvt_pk_bf16_f32 v158, v124, v125
	v_cvt_pk_bf16_f32 v159, v126, v127
	v_cvt_pk_bf16_f32 v160, v128, v129
	v_cvt_pk_bf16_f32 v161, v130, v131
	v_cvt_pk_bf16_f32 v162, v132, v133
	v_cvt_pk_bf16_f32 v163, v134, v135
	s_lshl_b32 vcc_lo, s19, 11
	s_add_u32 vcc_lo, vcc_lo, 0x1000000
	s_add_u32 s100, s14, vcc_lo
	s_addc_u32 s101, s15, 0
	global_store_dwordx2 v137, v[156:157], s[100:101] offset:0
	global_store_dwordx2 v137, v[158:159], s[100:101] offset:512
	global_store_dwordx2 v137, v[160:161], s[100:101] offset:1024
	global_store_dwordx2 v137, v[162:163], s[100:101] offset:1536
	s_lshl_b32 vcc_lo, s19, 12
	s_add_u32 vcc_lo, vcc_lo, 0x3800000
	s_add_u32 s100, s12, vcc_lo
	s_addc_u32 s101, s13, 0
	global_load_dwordx4 v[16:19], v136, s[100:101] offset:0
	global_load_dwordx4 v[20:23], v136, s[100:101] offset:1024
	global_load_dwordx4 v[24:27], v136, s[100:101] offset:2048
	global_load_dwordx4 v[28:31], v136, s[100:101] offset:3072
	v_mul_f32_e32 v138, v32, v32
	v_mul_f32_e32 v149, v33, v33
	v_mul_f32_e32 v150, v34, v34
	v_mul_f32_e32 v154, v35, v35
	v_fma_f32 v138, v36, v36, v138
	v_fma_f32 v149, v37, v37, v149
	v_fma_f32 v150, v38, v38, v150
	v_fma_f32 v154, v39, v39, v154
	v_fma_f32 v138, v40, v40, v138
	v_fma_f32 v149, v41, v41, v149
	v_fma_f32 v150, v42, v42, v150
	v_fma_f32 v154, v43, v43, v154
	v_fma_f32 v138, v44, v44, v138
	v_fma_f32 v149, v45, v45, v149
	v_fma_f32 v150, v46, v46, v150
	v_fma_f32 v154, v47, v47, v154
	v_add_f32_e32 v138, v138, v149
	v_add_f32_e32 v150, v150, v154
	v_add_f32_e32 v138, v138, v150
	s_nop 1
	v_add_f32_dpp v138, v138, v138 quad_perm:[1,0,3,2] row_mask:0xf bank_mask:0xf
	s_nop 1
	v_add_f32_dpp v138, v138, v138 quad_perm:[2,3,0,1] row_mask:0xf bank_mask:0xf
	s_nop 1
	v_add_f32_dpp v138, v138, v138 row_half_mirror row_mask:0xf bank_mask:0xf
	s_nop 1
	v_add_f32_dpp v138, v138, v138 row_mirror row_mask:0xf bank_mask:0xf
	v_mov_b32_e32 v139, v138
	s_nop 1
	v_permlane16_swap_b32_e32 v138, v139
	v_add_f32_e32 v138, v138, v139
	v_mov_b32_e32 v139, v138
	s_nop 1
	v_permlane32_swap_b32_e32 v138, v139
	v_add_f32_e32 v138, v138, v139
	v_mul_f32_e32 v138, 0x3a800000, v138
	v_add_f32_e32 v138, 0x358637bd, v138
	v_rsq_f32_e32 v140, v138
	s_nop 0
; __device__ __forceinline__ void row_phase(const Params& P, int glayer, int layer, int xsrc, bool hasY, int gate_idx, const float* gpost,
;                           int xdst, bool doH, const float* gpre, int sh_idx, int nrows) {
;     ...
;         if (doH) {
;           float ss = 0.f;
; #pragma unroll
;           for (int i = 0; i < 4; ++i) ss += xv[i].x * xv[i].x + xv[i].y * xv[i].y + xv[i].z * xv[i].z + xv[i].w * xv[i].w;
;           ss = wave_sum(ss);
;           const float rstd = __builtin_amdgcn_rsqf(ss * (1.f / 1024.f) + EPSF);
;           u16* h = P.hy + (long)row * 1024;
; #pragma unroll
;           for (int i = 0; i < 4; ++i) {
;             const int col = (i * 64 + lane) * 4;
;             const float4 g = *reinterpret_cast<const float4*>(gpre + col);
;             const float4 sh = *reinterpret_cast<const float4*>(modp + sh_idx * 1024 + col);
;             const float4 sc = *reinterpret_cast<const float4*>(modp + (sh_idx + 1) * 1024 + col);
;             const unsigned h0 = f2bf(xv[i].x * rstd * g.x * (1.f + sc.x) + sh.x);
;             const unsigned h1 = f2bf(xv[i].y * rstd * g.y * (1.f + sc.y) + sh.y);
;             const unsigned h2 = f2bf(xv[i].z * rstd * g.z * (1.f + sc.z) + sh.z);
;             const unsigned h3 = f2bf(xv[i].w * rstd * g.w * (1.f + sc.w) + sh.w);
;             *reinterpret_cast<uint2*>(h + col) = make_uint2(h0 | (h1 << 16), h2 | (h3 << 16));
;           }
	v_mul_f32_e32 v120, v32, v140
	v_mul_f32_e32 v121, v33, v140
	v_mul_f32_e32 v122, v34, v140
	v_mul_f32_e32 v123, v35, v140
	v_mul_f32_e32 v124, v36, v140
	v_mul_f32_e32 v125, v37, v140
	v_mul_f32_e32 v126, v38, v140
	v_mul_f32_e32 v127, v39, v140
	v_mul_f32_e32 v128, v40, v140
	v_mul_f32_e32 v129, v41, v140
	v_mul_f32_e32 v130, v42, v140
	v_mul_f32_e32 v131, v43, v140
	v_mul_f32_e32 v132, v44, v140
	v_mul_f32_e32 v133, v45, v140
	v_mul_f32_e32 v134, v46, v140
	v_mul_f32_e32 v135, v47, v140
	v_fma_f32 v120, v120, v88, v104
	v_fma_f32 v121, v121, v89, v105
	v_fma_f32 v122, v122, v90, v106
	v_fma_f32 v123, v123, v91, v107
	v_fma_f32 v124, v124, v92, v108
	v_fma_f32 v125, v125, v93, v109
	v_fma_f32 v126, v126, v94, v110
	v_fma_f32 v127, v127, v95, v111
	v_fma_f32 v128, v128, v96, v112
	v_fma_f32 v129, v129, v97, v113
	v_fma_f32 v130, v130, v98, v114
	v_fma_f32 v131, v131, v99, v115
	v_fma_f32 v132, v132, v100, v116
	v_fma_f32 v133, v133, v101, v117
	v_fma_f32 v134, v134, v102, v118
	v_fma_f32 v135, v135, v103, v119
	v_cvt_pk_bf16_f32 v156, v120, v121
	v_cvt_pk_bf16_f32 v157, v122, v123
	v_cvt_pk_bf16_f32 v158, v124, v125
	v_cvt_pk_bf16_f32 v159, v126, v127
	v_cvt_pk_bf16_f32 v160, v128, v129
	v_cvt_pk_bf16_f32 v161, v130, v131
	v_cvt_pk_bf16_f32 v162, v132, v133
	v_cvt_pk_bf16_f32 v163, v134, v135
	s_lshl_b32 vcc_lo, s19, 11
	s_add_u32 vcc_lo, vcc_lo, 0x1400000
	s_add_u32 s100, s14, vcc_lo
	s_addc_u32 s101, s15, 0
	global_store_dwordx2 v137, v[156:157], s[100:101] offset:0
	global_store_dwordx2 v137, v[158:159], s[100:101] offset:512
	global_store_dwordx2 v137, v[160:161], s[100:101] offset:1024
	global_store_dwordx2 v137, v[162:163], s[100:101] offset:1536
	s_lshl_b32 vcc_lo, s19, 12
	s_add_u32 vcc_lo, vcc_lo, 0x4000000
	s_add_u32 s100, s12, vcc_lo
	s_addc_u32 s101, s13, 0
	global_load_dwordx4 v[32:35], v136, s[100:101] offset:0
	global_load_dwordx4 v[36:39], v136, s[100:101] offset:1024
	global_load_dwordx4 v[40:43], v136, s[100:101] offset:2048
	global_load_dwordx4 v[44:47], v136, s[100:101] offset:3072
	s_waitcnt vmcnt(16)
	v_mul_f32_e32 v138, v0, v0
	v_mul_f32_e32 v149, v1, v1
	v_mul_f32_e32 v150, v2, v2
	v_mul_f32_e32 v154, v3, v3
	v_fma_f32 v138, v4, v4, v138
	v_fma_f32 v149, v5, v5, v149
	v_fma_f32 v150, v6, v6, v150
	v_fma_f32 v154, v7, v7, v154
	v_fma_f32 v138, v8, v8, v138
	v_fma_f32 v149, v9, v9, v149
	v_fma_f32 v150, v10, v10, v150
	v_fma_f32 v154, v11, v11, v154
	v_fma_f32 v138, v12, v12, v138
	v_fma_f32 v149, v13, v13, v149
	v_fma_f32 v150, v14, v14, v150
	v_fma_f32 v154, v15, v15, v154
	v_add_f32_e32 v138, v138, v149
	v_add_f32_e32 v150, v150, v154
	v_add_f32_e32 v138, v138, v150
	s_nop 1
	v_add_f32_dpp v138, v138, v138 quad_perm:[1,0,3,2] row_mask:0xf bank_mask:0xf
	s_nop 1
	v_add_f32_dpp v138, v138, v138 quad_perm:[2,3,0,1] row_mask:0xf bank_mask:0xf
	s_nop 1
	v_add_f32_dpp v138, v138, v138 row_half_mirror row_mask:0xf bank_mask:0xf
	s_nop 1
	v_add_f32_dpp v138, v138, v138 row_mirror row_mask:0xf bank_mask:0xf
	v_mov_b32_e32 v139, v138
	s_nop 1
	v_permlane16_swap_b32_e32 v138, v139
	v_add_f32_e32 v138, v138, v139
	v_mov_b32_e32 v139, v138
	s_nop 1
	v_permlane32_swap_b32_e32 v138, v139
	v_add_f32_e32 v138, v138, v139
	v_mul_f32_e32 v138, 0x3a800000, v138
	v_add_f32_e32 v138, 0x358637bd, v138
	v_rsq_f32_e32 v140, v138
	s_nop 0
	v_mul_f32_e32 v120, v0, v140
	v_mul_f32_e32 v121, v1, v140
	v_mul_f32_e32 v122, v2, v140
	v_mul_f32_e32 v123, v3, v140
	v_mul_f32_e32 v124, v4, v140
	v_mul_f32_e32 v125, v5, v140
	v_mul_f32_e32 v126, v6, v140
	v_mul_f32_e32 v127, v7, v140
	v_mul_f32_e32 v128, v8, v140
	v_mul_f32_e32 v129, v9, v140
	v_mul_f32_e32 v130, v10, v140
	v_mul_f32_e32 v131, v11, v140
	v_mul_f32_e32 v132, v12, v140
	v_mul_f32_e32 v133, v13, v140
	v_mul_f32_e32 v134, v14, v140
	v_mul_f32_e32 v135, v15, v140
	v_fma_f32 v120, v120, v88, v104
	v_fma_f32 v121, v121, v89, v105
	v_fma_f32 v122, v122, v90, v106
	v_fma_f32 v123, v123, v91, v107
	v_fma_f32 v124, v124, v92, v108
	v_fma_f32 v125, v125, v93, v109
	v_fma_f32 v126, v126, v94, v110
	v_fma_f32 v127, v127, v95, v111
	v_fma_f32 v128, v128, v96, v112
	v_fma_f32 v129, v129, v97, v113
	v_fma_f32 v130, v130, v98, v114
	v_fma_f32 v131, v131, v99, v115
	v_fma_f32 v132, v132, v100, v116
	v_fma_f32 v133, v133, v101, v117
	v_fma_f32 v134, v134, v102, v118
	v_fma_f32 v135, v135, v103, v119
	v_cvt_pk_bf16_f32 v156, v120, v121
	v_cvt_pk_bf16_f32 v157, v122, v123
	v_cvt_pk_bf16_f32 v158, v124, v125
	v_cvt_pk_bf16_f32 v159, v126, v127
	v_cvt_pk_bf16_f32 v160, v128, v129
	v_cvt_pk_bf16_f32 v161, v130, v131
	v_cvt_pk_bf16_f32 v162, v132, v133
	v_cvt_pk_bf16_f32 v163, v134, v135
	s_lshl_b32 vcc_lo, s19, 11
	s_add_u32 vcc_lo, vcc_lo, 0x1800000
	s_add_u32 s100, s14, vcc_lo
	s_addc_u32 s101, s15, 0
	global_store_dwordx2 v137, v[156:157], s[100:101] offset:0
	global_store_dwordx2 v137, v[158:159], s[100:101] offset:512
	global_store_dwordx2 v137, v[160:161], s[100:101] offset:1024
	global_store_dwordx2 v137, v[162:163], s[100:101] offset:1536
	s_lshl_b32 vcc_lo, s19, 12
	s_add_u32 vcc_lo, vcc_lo, 0x4800000
	s_add_u32 s100, s12, vcc_lo
	s_addc_u32 s101, s13, 0
	global_load_dwordx4 v[0:3], v136, s[100:101] offset:0
	global_load_dwordx4 v[4:7], v136, s[100:101] offset:1024
	global_load_dwordx4 v[8:11], v136, s[100:101] offset:2048
	global_load_dwordx4 v[12:15], v136, s[100:101] offset:3072
	s_waitcnt vmcnt(16)
; __device__ __forceinline__ void row_phase(const Params& P, int glayer, int layer, int xsrc, bool hasY, int gate_idx, const float* gpost,
;                           int xdst, bool doH, const float* gpre, int sh_idx, int nrows) {
;     ...
;         const int mi = row < N_X ? (row >> 13) : 4;
;         const float* modp = P.mod + (long)(layer * 5 + mi) * 6144;
;     ...
;         if (doH) {
;           float ss = 0.f;
; #pragma unroll
;           for (int i = 0; i < 4; ++i) ss += xv[i].x * xv[i].x + xv[i].y * xv[i].y + xv[i].z * xv[i].z + xv[i].w * xv[i].w;
;           ss = wave_sum(ss);
;           const float rstd = __builtin_amdgcn_rsqf(ss * (1.f / 1024.f) + EPSF);
;           u16* h = P.hy + (long)row * 1024;
; #pragma unroll
;           for (int i = 0; i < 4; ++i) {
;             const int col = (i * 64 + lane) * 4;
;             const float4 g = *reinterpret_cast<const float4*>(gpre + col);
;             const float4 sh = *reinterpret_cast<const float4*>(modp + sh_idx * 1024 + col);
;             const float4 sc = *reinterpret_cast<const float4*>(modp + (sh_idx + 1) * 1024 + col);
;             const unsigned h0 = f2bf(xv[i].x * rstd * g.x * (1.f + sc.x) + sh.x);
;             const unsigned h1 = f2bf(xv[i].y * rstd * g.y * (1.f + sc.y) + sh.y);
;             const unsigned h2 = f2bf(xv[i].z * rstd * g.z * (1.f + sc.z) + sh.z);
;             const unsigned h3 = f2bf(xv[i].w * rstd * g.w * (1.f + sc.w) + sh.w);
;             *reinterpret_cast<uint2*>(h + col) = make_uint2(h0 | (h1 << 16), h2 | (h3 << 16));
;           }
	v_mul_f32_e32 v138, v16, v16
	v_mul_f32_e32 v149, v17, v17
	v_mul_f32_e32 v150, v18, v18
	v_mul_f32_e32 v154, v19, v19
	v_fma_f32 v138, v20, v20, v138
	v_fma_f32 v149, v21, v21, v149
	v_fma_f32 v150, v22, v22, v150
	v_fma_f32 v154, v23, v23, v154
	v_fma_f32 v138, v24, v24, v138
	v_fma_f32 v149, v25, v25, v149
	v_fma_f32 v150, v26, v26, v150
	v_fma_f32 v154, v27, v27, v154
	v_fma_f32 v138, v28, v28, v138
	v_fma_f32 v149, v29, v29, v149
	v_fma_f32 v150, v30, v30, v150
	v_fma_f32 v154, v31, v31, v154
	v_add_f32_e32 v138, v138, v149
	v_add_f32_e32 v150, v150, v154
	v_add_f32_e32 v138, v138, v150
	s_nop 1
	v_add_f32_dpp v138, v138, v138 quad_perm:[1,0,3,2] row_mask:0xf bank_mask:0xf
	s_nop 1
	v_add_f32_dpp v138, v138, v138 quad_perm:[2,3,0,1] row_mask:0xf bank_mask:0xf
	s_nop 1
	v_add_f32_dpp v138, v138, v138 row_half_mirror row_mask:0xf bank_mask:0xf
	s_nop 1
	v_add_f32_dpp v138, v138, v138 row_mirror row_mask:0xf bank_mask:0xf
	v_mov_b32_e32 v139, v138
	s_nop 1
	v_permlane16_swap_b32_e32 v138, v139
	v_add_f32_e32 v138, v138, v139
	v_mov_b32_e32 v139, v138
	s_nop 1
	v_permlane32_swap_b32_e32 v138, v139
	v_add_f32_e32 v138, v138, v139
	v_mul_f32_e32 v138, 0x3a800000, v138
	v_add_f32_e32 v138, 0x358637bd, v138
	v_rsq_f32_e32 v140, v138
	s_nop 0
	v_mul_f32_e32 v120, v16, v140
	v_mul_f32_e32 v121, v17, v140
	v_mul_f32_e32 v122, v18, v140
	v_mul_f32_e32 v123, v19, v140
	v_mul_f32_e32 v124, v20, v140
	v_mul_f32_e32 v125, v21, v140
	v_mul_f32_e32 v126, v22, v140
	v_mul_f32_e32 v127, v23, v140
	v_mul_f32_e32 v128, v24, v140
	v_mul_f32_e32 v129, v25, v140
	v_mul_f32_e32 v130, v26, v140
	v_mul_f32_e32 v131, v27, v140
	v_mul_f32_e32 v132, v28, v140
	v_mul_f32_e32 v133, v29, v140
	v_mul_f32_e32 v134, v30, v140
	v_mul_f32_e32 v135, v31, v140
	v_fma_f32 v120, v120, v88, v104
	v_fma_f32 v121, v121, v89, v105
	v_fma_f32 v122, v122, v90, v106
	v_fma_f32 v123, v123, v91, v107
	v_fma_f32 v124, v124, v92, v108
	v_fma_f32 v125, v125, v93, v109
	v_fma_f32 v126, v126, v94, v110
	v_fma_f32 v127, v127, v95, v111
	v_fma_f32 v128, v128, v96, v112
	v_fma_f32 v129, v129, v97, v113
	v_fma_f32 v130, v130, v98, v114
	v_fma_f32 v131, v131, v99, v115
	v_fma_f32 v132, v132, v100, v116
	v_fma_f32 v133, v133, v101, v117
	v_fma_f32 v134, v134, v102, v118
	v_fma_f32 v135, v135, v103, v119
	v_cvt_pk_bf16_f32 v156, v120, v121
	v_cvt_pk_bf16_f32 v157, v122, v123
	v_cvt_pk_bf16_f32 v158, v124, v125
	v_cvt_pk_bf16_f32 v159, v126, v127
	v_cvt_pk_bf16_f32 v160, v128, v129
	v_cvt_pk_bf16_f32 v161, v130, v131
	v_cvt_pk_bf16_f32 v162, v132, v133
	v_cvt_pk_bf16_f32 v163, v134, v135
	s_lshl_b32 vcc_lo, s19, 11
	s_add_u32 vcc_lo, vcc_lo, 0x1c00000
	s_add_u32 s100, s14, vcc_lo
	s_addc_u32 s101, s15, 0
	global_store_dwordx2 v137, v[156:157], s[100:101] offset:0
	global_store_dwordx2 v137, v[158:159], s[100:101] offset:512
	global_store_dwordx2 v137, v[160:161], s[100:101] offset:1024
	global_store_dwordx2 v137, v[162:163], s[100:101] offset:1536
	s_add_u32 s100, s20, 0xc000
	s_addc_u32 s101, s21, 0
	global_load_dwordx4 v[104:107], v136, s[100:101] offset:0
	global_load_dwordx4 v[108:111], v136, s[100:101] offset:1024
	global_load_dwordx4 v[112:115], v136, s[100:101] offset:2048
	global_load_dwordx4 v[116:119], v136, s[100:101] offset:3072
	s_add_u32 s100, s100, 0x1000
	s_addc_u32 s101, s101, 0
	global_load_dwordx4 v[16:19], v136, s[100:101] offset:0
	global_load_dwordx4 v[20:23], v136, s[100:101] offset:1024
	global_load_dwordx4 v[24:27], v136, s[100:101] offset:2048
	global_load_dwordx4 v[28:31], v136, s[100:101] offset:3072
	s_load_dwordx2 s[98:99], s[4:5], 0x30
	s_waitcnt lgkmcnt(0)
	global_load_dwordx4 v[88:91], v136, s[98:99] offset:0
	global_load_dwordx4 v[92:95], v136, s[98:99] offset:1024
	global_load_dwordx4 v[96:99], v136, s[98:99] offset:2048
	global_load_dwordx4 v[100:103], v136, s[98:99] offset:3072
	s_waitcnt vmcnt(0)
	v_fma_f32 v88, v88, v16, v88
	v_fma_f32 v89, v89, v17, v89
	v_fma_f32 v90, v90, v18, v90
	v_fma_f32 v91, v91, v19, v91
	v_fma_f32 v92, v92, v20, v92
	v_fma_f32 v93, v93, v21, v93
	v_fma_f32 v94, v94, v22, v94
	v_fma_f32 v95, v95, v23, v95
	v_fma_f32 v96, v96, v24, v96
	v_fma_f32 v97, v97, v25, v97
	v_fma_f32 v98, v98, v26, v98
	v_fma_f32 v99, v99, v27, v99
	v_fma_f32 v100, v100, v28, v100
	v_fma_f32 v101, v101, v29, v101
	v_fma_f32 v102, v102, v30, v102
	v_fma_f32 v103, v103, v31, v103
	s_lshl_b32 vcc_lo, s19, 12
	s_add_u32 vcc_lo, vcc_lo, 0x5000000
	s_add_u32 s100, s12, vcc_lo
	s_addc_u32 s101, s13, 0
	global_load_dwordx4 v[16:19], v136, s[100:101] offset:0
	global_load_dwordx4 v[20:23], v136, s[100:101] offset:1024
	global_load_dwordx4 v[24:27], v136, s[100:101] offset:2048
	global_load_dwordx4 v[28:31], v136, s[100:101] offset:3072
	v_mul_f32_e32 v138, v32, v32
	v_mul_f32_e32 v149, v33, v33
	v_mul_f32_e32 v150, v34, v34
	v_mul_f32_e32 v154, v35, v35
	v_fma_f32 v138, v36, v36, v138
	v_fma_f32 v149, v37, v37, v149
	v_fma_f32 v150, v38, v38, v150
	v_fma_f32 v154, v39, v39, v154
	v_fma_f32 v138, v40, v40, v138
	v_fma_f32 v149, v41, v41, v149
	v_fma_f32 v150, v42, v42, v150
	v_fma_f32 v154, v43, v43, v154
	v_fma_f32 v138, v44, v44, v138
	v_fma_f32 v149, v45, v45, v149
	v_fma_f32 v150, v46, v46, v150
	v_fma_f32 v154, v47, v47, v154
	v_add_f32_e32 v138, v138, v149
	v_add_f32_e32 v150, v150, v154
	v_add_f32_e32 v138, v138, v150
	s_nop 1
	v_add_f32_dpp v138, v138, v138 quad_perm:[1,0,3,2] row_mask:0xf bank_mask:0xf
	s_nop 1
	v_add_f32_dpp v138, v138, v138 quad_perm:[2,3,0,1] row_mask:0xf bank_mask:0xf
	s_nop 1
	v_add_f32_dpp v138, v138, v138 row_half_mirror row_mask:0xf bank_mask:0xf
	s_nop 1
	v_add_f32_dpp v138, v138, v138 row_mirror row_mask:0xf bank_mask:0xf
; __device__ __forceinline__ void row_phase(const Params& P, int glayer, int layer, int xsrc, bool hasY, int gate_idx, const float* gpost,
;                           int xdst, bool doH, const float* gpre, int sh_idx, int nrows) {
;     ...
;         if (doH) {
;           float ss = 0.f;
; #pragma unroll
;           for (int i = 0; i < 4; ++i) ss += xv[i].x * xv[i].x + xv[i].y * xv[i].y + xv[i].z * xv[i].z + xv[i].w * xv[i].w;
;           ss = wave_sum(ss);
;           const float rstd = __builtin_amdgcn_rsqf(ss * (1.f / 1024.f) + EPSF);
;           u16* h = P.hy + (long)row * 1024;
; #pragma unroll
;           for (int i = 0; i < 4; ++i) {
;             const int col = (i * 64 + lane) * 4;
;             const float4 g = *reinterpret_cast<const float4*>(gpre + col);
;             const float4 sh = *reinterpret_cast<const float4*>(modp + sh_idx * 1024 + col);
;             const float4 sc = *reinterpret_cast<const float4*>(modp + (sh_idx + 1) * 1024 + col);
;             const unsigned h0 = f2bf(xv[i].x * rstd * g.x * (1.f + sc.x) + sh.x);
;             const unsigned h1 = f2bf(xv[i].y * rstd * g.y * (1.f + sc.y) + sh.y);
;             const unsigned h2 = f2bf(xv[i].z * rstd * g.z * (1.f + sc.z) + sh.z);
;             const unsigned h3 = f2bf(xv[i].w * rstd * g.w * (1.f + sc.w) + sh.w);
;             *reinterpret_cast<uint2*>(h + col) = make_uint2(h0 | (h1 << 16), h2 | (h3 << 16));
;           }
	v_mov_b32_e32 v139, v138
	s_nop 1
	v_permlane16_swap_b32_e32 v138, v139
	v_add_f32_e32 v138, v138, v139
	v_mov_b32_e32 v139, v138
	s_nop 1
	v_permlane32_swap_b32_e32 v138, v139
	v_add_f32_e32 v138, v138, v139
	v_mul_f32_e32 v138, 0x3a800000, v138
	v_add_f32_e32 v138, 0x358637bd, v138
	v_rsq_f32_e32 v140, v138
	s_nop 0
	v_mul_f32_e32 v120, v32, v140
	v_mul_f32_e32 v121, v33, v140
	v_mul_f32_e32 v122, v34, v140
	v_mul_f32_e32 v123, v35, v140
	v_mul_f32_e32 v124, v36, v140
	v_mul_f32_e32 v125, v37, v140
	v_mul_f32_e32 v126, v38, v140
	v_mul_f32_e32 v127, v39, v140
	v_mul_f32_e32 v128, v40, v140
	v_mul_f32_e32 v129, v41, v140
	v_mul_f32_e32 v130, v42, v140
	v_mul_f32_e32 v131, v43, v140
	v_mul_f32_e32 v132, v44, v140
	v_mul_f32_e32 v133, v45, v140
	v_mul_f32_e32 v134, v46, v140
	v_mul_f32_e32 v135, v47, v140
	v_fma_f32 v120, v120, v88, v104
	v_fma_f32 v121, v121, v89, v105
	v_fma_f32 v122, v122, v90, v106
	v_fma_f32 v123, v123, v91, v107
	v_fma_f32 v124, v124, v92, v108
	v_fma_f32 v125, v125, v93, v109
	v_fma_f32 v126, v126, v94, v110
	v_fma_f32 v127, v127, v95, v111
	v_fma_f32 v128, v128, v96, v112
	v_fma_f32 v129, v129, v97, v113
	v_fma_f32 v130, v130, v98, v114
	v_fma_f32 v131, v131, v99, v115
	v_fma_f32 v132, v132, v100, v116
	v_fma_f32 v133, v133, v101, v117
	v_fma_f32 v134, v134, v102, v118
	v_fma_f32 v135, v135, v103, v119
	v_cvt_pk_bf16_f32 v156, v120, v121
	v_cvt_pk_bf16_f32 v157, v122, v123
	v_cvt_pk_bf16_f32 v158, v124, v125
	v_cvt_pk_bf16_f32 v159, v126, v127
	v_cvt_pk_bf16_f32 v160, v128, v129
	v_cvt_pk_bf16_f32 v161, v130, v131
	v_cvt_pk_bf16_f32 v162, v132, v133
	v_cvt_pk_bf16_f32 v163, v134, v135
	s_lshl_b32 vcc_lo, s19, 11
	s_add_u32 vcc_lo, vcc_lo, 0x2000000
	s_add_u32 s100, s14, vcc_lo
	s_addc_u32 s101, s15, 0
	global_store_dwordx2 v137, v[156:157], s[100:101] offset:0
	global_store_dwordx2 v137, v[158:159], s[100:101] offset:512
	global_store_dwordx2 v137, v[160:161], s[100:101] offset:1024
	global_store_dwordx2 v137, v[162:163], s[100:101] offset:1536
	s_lshl_b32 vcc_lo, s19, 12
	s_add_u32 vcc_lo, vcc_lo, 0x5800000
	s_add_u32 s100, s12, vcc_lo
	s_addc_u32 s101, s13, 0
	global_load_dwordx4 v[32:35], v136, s[100:101] offset:0
	global_load_dwordx4 v[36:39], v136, s[100:101] offset:1024
	global_load_dwordx4 v[40:43], v136, s[100:101] offset:2048
	global_load_dwordx4 v[44:47], v136, s[100:101] offset:3072
	v_mul_f32_e32 v138, v0, v0
	v_mul_f32_e32 v149, v1, v1
	v_mul_f32_e32 v150, v2, v2
	v_mul_f32_e32 v154, v3, v3
	v_fma_f32 v138, v4, v4, v138
	v_fma_f32 v149, v5, v5, v149
	v_fma_f32 v150, v6, v6, v150
	v_fma_f32 v154, v7, v7, v154
	v_fma_f32 v138, v8, v8, v138
	v_fma_f32 v149, v9, v9, v149
	v_fma_f32 v150, v10, v10, v150
	v_fma_f32 v154, v11, v11, v154
	v_fma_f32 v138, v12, v12, v138
	v_fma_f32 v149, v13, v13, v149
	v_fma_f32 v150, v14, v14, v150
	v_fma_f32 v154, v15, v15, v154
	v_add_f32_e32 v138, v138, v149
	v_add_f32_e32 v150, v150, v154
	v_add_f32_e32 v138, v138, v150
	s_nop 1
	v_add_f32_dpp v138, v138, v138 quad_perm:[1,0,3,2] row_mask:0xf bank_mask:0xf
	s_nop 1
	v_add_f32_dpp v138, v138, v138 quad_perm:[2,3,0,1] row_mask:0xf bank_mask:0xf
	s_nop 1
	v_add_f32_dpp v138, v138, v138 row_half_mirror row_mask:0xf bank_mask:0xf
	s_nop 1
	v_add_f32_dpp v138, v138, v138 row_mirror row_mask:0xf bank_mask:0xf
	v_mov_b32_e32 v139, v138
	s_nop 1
	v_permlane16_swap_b32_e32 v138, v139
	v_add_f32_e32 v138, v138, v139
	v_mov_b32_e32 v139, v138
	s_nop 1
	v_permlane32_swap_b32_e32 v138, v139
	v_add_f32_e32 v138, v138, v139
	v_mul_f32_e32 v138, 0x3a800000, v138
	v_add_f32_e32 v138, 0x358637bd, v138
	v_rsq_f32_e32 v140, v138
	s_nop 0
	v_mul_f32_e32 v120, v0, v140
	v_mul_f32_e32 v121, v1, v140
	v_mul_f32_e32 v122, v2, v140
	v_mul_f32_e32 v123, v3, v140
	v_mul_f32_e32 v124, v4, v140
	v_mul_f32_e32 v125, v5, v140
	v_mul_f32_e32 v126, v6, v140
	v_mul_f32_e32 v127, v7, v140
	v_mul_f32_e32 v128, v8, v140
	v_mul_f32_e32 v129, v9, v140
	v_mul_f32_e32 v130, v10, v140
	v_mul_f32_e32 v131, v11, v140
	v_mul_f32_e32 v132, v12, v140
	v_mul_f32_e32 v133, v13, v140
	v_mul_f32_e32 v134, v14, v140
	v_mul_f32_e32 v135, v15, v140
	v_fma_f32 v120, v120, v88, v104
	v_fma_f32 v121, v121, v89, v105
	v_fma_f32 v122, v122, v90, v106
	v_fma_f32 v123, v123, v91, v107
	v_fma_f32 v124, v124, v92, v108
	v_fma_f32 v125, v125, v93, v109
	v_fma_f32 v126, v126, v94, v110
	v_fma_f32 v127, v127, v95, v111
	v_fma_f32 v128, v128, v96, v112
	v_fma_f32 v129, v129, v97, v113
	v_fma_f32 v130, v130, v98, v114
	v_fma_f32 v131, v131, v99, v115
	v_fma_f32 v132, v132, v100, v116
	v_fma_f32 v133, v133, v101, v117
	v_fma_f32 v134, v134, v102, v118
	v_fma_f32 v135, v135, v103, v119
	v_cvt_pk_bf16_f32 v156, v120, v121
	v_cvt_pk_bf16_f32 v157, v122, v123
	v_cvt_pk_bf16_f32 v158, v124, v125
	v_cvt_pk_bf16_f32 v159, v126, v127
	v_cvt_pk_bf16_f32 v160, v128, v129
	v_cvt_pk_bf16_f32 v161, v130, v131
	v_cvt_pk_bf16_f32 v162, v132, v133
	v_cvt_pk_bf16_f32 v163, v134, v135
	s_lshl_b32 vcc_lo, s19, 11
	s_add_u32 vcc_lo, vcc_lo, 0x2400000
	s_add_u32 s100, s14, vcc_lo
	s_addc_u32 s101, s15, 0
	global_store_dwordx2 v137, v[156:157], s[100:101] offset:0
	global_store_dwordx2 v137, v[158:159], s[100:101] offset:512
	global_store_dwordx2 v137, v[160:161], s[100:101] offset:1024
	global_store_dwordx2 v137, v[162:163], s[100:101] offset:1536
	s_lshl_b32 vcc_lo, s19, 12
	s_add_u32 vcc_lo, vcc_lo, 0x6000000
	s_add_u32 s100, s12, vcc_lo
	s_addc_u32 s101, s13, 0
	global_load_dwordx4 v[0:3], v136, s[100:101] offset:0
	global_load_dwordx4 v[4:7], v136, s[100:101] offset:1024
	global_load_dwordx4 v[8:11], v136, s[100:101] offset:2048
	global_load_dwordx4 v[12:15], v136, s[100:101] offset:3072
	s_waitcnt vmcnt(16)
; __device__ __forceinline__ void row_phase(const Params& P, int glayer, int layer, int xsrc, bool hasY, int gate_idx, const float* gpost,
;                           int xdst, bool doH, const float* gpre, int sh_idx, int nrows) {
;     ...
;         const int mi = row < N_X ? (row >> 13) : 4;
;         const float* modp = P.mod + (long)(layer * 5 + mi) * 6144;
;     ...
;         if (doH) {
;           float ss = 0.f;
; #pragma unroll
;           for (int i = 0; i < 4; ++i) ss += xv[i].x * xv[i].x + xv[i].y * xv[i].y + xv[i].z * xv[i].z + xv[i].w * xv[i].w;
;           ss = wave_sum(ss);
;           const float rstd = __builtin_amdgcn_rsqf(ss * (1.f / 1024.f) + EPSF);
;           u16* h = P.hy + (long)row * 1024;
; #pragma unroll
;           for (int i = 0; i < 4; ++i) {
;             const int col = (i * 64 + lane) * 4;
;             const float4 g = *reinterpret_cast<const float4*>(gpre + col);
;             const float4 sh = *reinterpret_cast<const float4*>(modp + sh_idx * 1024 + col);
;             const float4 sc = *reinterpret_cast<const float4*>(modp + (sh_idx + 1) * 1024 + col);
;             const unsigned h0 = f2bf(xv[i].x * rstd * g.x * (1.f + sc.x) + sh.x);
;             const unsigned h1 = f2bf(xv[i].y * rstd * g.y * (1.f + sc.y) + sh.y);
;             const unsigned h2 = f2bf(xv[i].z * rstd * g.z * (1.f + sc.z) + sh.z);
;             const unsigned h3 = f2bf(xv[i].w * rstd * g.w * (1.f + sc.w) + sh.w);
;             *reinterpret_cast<uint2*>(h + col) = make_uint2(h0 | (h1 << 16), h2 | (h3 << 16));
;           }
	v_mul_f32_e32 v138, v16, v16
	v_mul_f32_e32 v149, v17, v17
	v_mul_f32_e32 v150, v18, v18
	v_mul_f32_e32 v154, v19, v19
	v_fma_f32 v138, v20, v20, v138
	v_fma_f32 v149, v21, v21, v149
	v_fma_f32 v150, v22, v22, v150
	v_fma_f32 v154, v23, v23, v154
	v_fma_f32 v138, v24, v24, v138
	v_fma_f32 v149, v25, v25, v149
	v_fma_f32 v150, v26, v26, v150
	v_fma_f32 v154, v27, v27, v154
	v_fma_f32 v138, v28, v28, v138
	v_fma_f32 v149, v29, v29, v149
	v_fma_f32 v150, v30, v30, v150
	v_fma_f32 v154, v31, v31, v154
	v_add_f32_e32 v138, v138, v149
	v_add_f32_e32 v150, v150, v154
	v_add_f32_e32 v138, v138, v150
	s_nop 1
	v_add_f32_dpp v138, v138, v138 quad_perm:[1,0,3,2] row_mask:0xf bank_mask:0xf
	s_nop 1
	v_add_f32_dpp v138, v138, v138 quad_perm:[2,3,0,1] row_mask:0xf bank_mask:0xf
	s_nop 1
	v_add_f32_dpp v138, v138, v138 row_half_mirror row_mask:0xf bank_mask:0xf
	s_nop 1
	v_add_f32_dpp v138, v138, v138 row_mirror row_mask:0xf bank_mask:0xf
	v_mov_b32_e32 v139, v138
	s_nop 1
	v_permlane16_swap_b32_e32 v138, v139
	v_add_f32_e32 v138, v138, v139
	v_mov_b32_e32 v139, v138
	s_nop 1
	v_permlane32_swap_b32_e32 v138, v139
	v_add_f32_e32 v138, v138, v139
	v_mul_f32_e32 v138, 0x3a800000, v138
	v_add_f32_e32 v138, 0x358637bd, v138
	v_rsq_f32_e32 v140, v138
	s_nop 0
	v_mul_f32_e32 v120, v16, v140
	v_mul_f32_e32 v121, v17, v140
	v_mul_f32_e32 v122, v18, v140
	v_mul_f32_e32 v123, v19, v140
	v_mul_f32_e32 v124, v20, v140
	v_mul_f32_e32 v125, v21, v140
	v_mul_f32_e32 v126, v22, v140
	v_mul_f32_e32 v127, v23, v140
	v_mul_f32_e32 v128, v24, v140
	v_mul_f32_e32 v129, v25, v140
	v_mul_f32_e32 v130, v26, v140
	v_mul_f32_e32 v131, v27, v140
	v_mul_f32_e32 v132, v28, v140
	v_mul_f32_e32 v133, v29, v140
	v_mul_f32_e32 v134, v30, v140
	v_mul_f32_e32 v135, v31, v140
	v_fma_f32 v120, v120, v88, v104
	v_fma_f32 v121, v121, v89, v105
	v_fma_f32 v122, v122, v90, v106
	v_fma_f32 v123, v123, v91, v107
	v_fma_f32 v124, v124, v92, v108
	v_fma_f32 v125, v125, v93, v109
	v_fma_f32 v126, v126, v94, v110
	v_fma_f32 v127, v127, v95, v111
	v_fma_f32 v128, v128, v96, v112
	v_fma_f32 v129, v129, v97, v113
	v_fma_f32 v130, v130, v98, v114
	v_fma_f32 v131, v131, v99, v115
	v_fma_f32 v132, v132, v100, v116
	v_fma_f32 v133, v133, v101, v117
	v_fma_f32 v134, v134, v102, v118
	v_fma_f32 v135, v135, v103, v119
	v_cvt_pk_bf16_f32 v156, v120, v121
	v_cvt_pk_bf16_f32 v157, v122, v123
	v_cvt_pk_bf16_f32 v158, v124, v125
	v_cvt_pk_bf16_f32 v159, v126, v127
	v_cvt_pk_bf16_f32 v160, v128, v129
	v_cvt_pk_bf16_f32 v161, v130, v131
	v_cvt_pk_bf16_f32 v162, v132, v133
	v_cvt_pk_bf16_f32 v163, v134, v135
	s_lshl_b32 vcc_lo, s19, 11
	s_add_u32 vcc_lo, vcc_lo, 0x2800000
	s_add_u32 s100, s14, vcc_lo
	s_addc_u32 s101, s15, 0
	global_store_dwordx2 v137, v[156:157], s[100:101] offset:0
	global_store_dwordx2 v137, v[158:159], s[100:101] offset:512
	global_store_dwordx2 v137, v[160:161], s[100:101] offset:1024
	global_store_dwordx2 v137, v[162:163], s[100:101] offset:1536
	s_lshl_b32 vcc_lo, s19, 12
	s_add_u32 vcc_lo, vcc_lo, 0x6800000
	s_add_u32 s100, s12, vcc_lo
	s_addc_u32 s101, s13, 0
	global_load_dwordx4 v[16:19], v136, s[100:101] offset:0
	global_load_dwordx4 v[20:23], v136, s[100:101] offset:1024
	global_load_dwordx4 v[24:27], v136, s[100:101] offset:2048
	global_load_dwordx4 v[28:31], v136, s[100:101] offset:3072
	s_waitcnt vmcnt(16)
	v_mul_f32_e32 v138, v32, v32
	v_mul_f32_e32 v149, v33, v33
	v_mul_f32_e32 v150, v34, v34
	v_mul_f32_e32 v154, v35, v35
	v_fma_f32 v138, v36, v36, v138
	v_fma_f32 v149, v37, v37, v149
	v_fma_f32 v150, v38, v38, v150
	v_fma_f32 v154, v39, v39, v154
	v_fma_f32 v138, v40, v40, v138
	v_fma_f32 v149, v41, v41, v149
	v_fma_f32 v150, v42, v42, v150
	v_fma_f32 v154, v43, v43, v154
	v_fma_f32 v138, v44, v44, v138
	v_fma_f32 v149, v45, v45, v149
	v_fma_f32 v150, v46, v46, v150
	v_fma_f32 v154, v47, v47, v154
	v_add_f32_e32 v138, v138, v149
	v_add_f32_e32 v150, v150, v154
	v_add_f32_e32 v138, v138, v150
	s_nop 1
	v_add_f32_dpp v138, v138, v138 quad_perm:[1,0,3,2] row_mask:0xf bank_mask:0xf
	s_nop 1
	v_add_f32_dpp v138, v138, v138 quad_perm:[2,3,0,1] row_mask:0xf bank_mask:0xf
	s_nop 1
	v_add_f32_dpp v138, v138, v138 row_half_mirror row_mask:0xf bank_mask:0xf
	s_nop 1
	v_add_f32_dpp v138, v138, v138 row_mirror row_mask:0xf bank_mask:0xf
	v_mov_b32_e32 v139, v138
	s_nop 1
	v_permlane16_swap_b32_e32 v138, v139
	v_add_f32_e32 v138, v138, v139
	v_mov_b32_e32 v139, v138
	s_nop 1
	v_permlane32_swap_b32_e32 v138, v139
	v_add_f32_e32 v138, v138, v139
	v_mul_f32_e32 v138, 0x3a800000, v138
	v_add_f32_e32 v138, 0x358637bd, v138
	v_rsq_f32_e32 v140, v138
	s_nop 0
	v_mul_f32_e32 v120, v32, v140
	v_mul_f32_e32 v121, v33, v140
	v_mul_f32_e32 v122, v34, v140
	v_mul_f32_e32 v123, v35, v140
	v_mul_f32_e32 v124, v36, v140
	v_mul_f32_e32 v125, v37, v140
	v_mul_f32_e32 v126, v38, v140
	v_mul_f32_e32 v127, v39, v140
	v_mul_f32_e32 v128, v40, v140
	v_mul_f32_e32 v129, v41, v140
	v_mul_f32_e32 v130, v42, v140
	v_mul_f32_e32 v131, v43, v140
	v_mul_f32_e32 v132, v44, v140
	v_mul_f32_e32 v133, v45, v140
	v_mul_f32_e32 v134, v46, v140
	v_mul_f32_e32 v135, v47, v140
	v_fma_f32 v120, v120, v88, v104
	v_fma_f32 v121, v121, v89, v105
	v_fma_f32 v122, v122, v90, v106
	v_fma_f32 v123, v123, v91, v107
	v_fma_f32 v124, v124, v92, v108
	v_fma_f32 v125, v125, v93, v109
	v_fma_f32 v126, v126, v94, v110
	v_fma_f32 v127, v127, v95, v111
	v_fma_f32 v128, v128, v96, v112
	v_fma_f32 v129, v129, v97, v113
	v_fma_f32 v130, v130, v98, v114
	v_fma_f32 v131, v131, v99, v115
	v_fma_f32 v132, v132, v100, v116
	v_fma_f32 v133, v133, v101, v117
	v_fma_f32 v134, v134, v102, v118
	v_fma_f32 v135, v135, v103, v119
	v_cvt_pk_bf16_f32 v156, v120, v121
	v_cvt_pk_bf16_f32 v157, v122, v123
	v_cvt_pk_bf16_f32 v158, v124, v125
	v_cvt_pk_bf16_f32 v159, v126, v127
	v_cvt_pk_bf16_f32 v160, v128, v129
	v_cvt_pk_bf16_f32 v161, v130, v131
	v_cvt_pk_bf16_f32 v162, v132, v133
	v_cvt_pk_bf16_f32 v163, v134, v135
	s_lshl_b32 vcc_lo, s19, 11
	s_add_u32 vcc_lo, vcc_lo, 0x2c00000
	s_add_u32 s100, s14, vcc_lo
	s_addc_u32 s101, s15, 0
	global_store_dwordx2 v137, v[156:157], s[100:101] offset:0
	global_store_dwordx2 v137, v[158:159], s[100:101] offset:512
	global_store_dwordx2 v137, v[160:161], s[100:101] offset:1024
	global_store_dwordx2 v137, v[162:163], s[100:101] offset:1536
	s_add_u32 s100, s20, 0x12000
	s_addc_u32 s101, s21, 0
	global_load_dwordx4 v[104:107], v136, s[100:101] offset:0
	global_load_dwordx4 v[108:111], v136, s[100:101] offset:1024
	global_load_dwordx4 v[112:115], v136, s[100:101] offset:2048
	global_load_dwordx4 v[116:119], v136, s[100:101] offset:3072
	s_add_u32 s100, s100, 0x1000
	s_addc_u32 s101, s101, 0
	global_load_dwordx4 v[32:35], v136, s[100:101] offset:0
	global_load_dwordx4 v[36:39], v136, s[100:101] offset:1024
	global_load_dwordx4 v[40:43], v136, s[100:101] offset:2048
	global_load_dwordx4 v[44:47], v136, s[100:101] offset:3072
	s_load_dwordx2 s[98:99], s[4:5], 0x30
	s_waitcnt lgkmcnt(0)
; __device__ __forceinline__ void row_phase(const Params& P, int glayer, int layer, int xsrc, bool hasY, int gate_idx, const float* gpost,
;                           int xdst, bool doH, const float* gpre, int sh_idx, int nrows) {
;     ...
;         const int mi = row < N_X ? (row >> 13) : 4;
;         const float* modp = P.mod + (long)(layer * 5 + mi) * 6144;
;     ...
;         if (doH) {
;           float ss = 0.f;
; #pragma unroll
;           for (int i = 0; i < 4; ++i) ss += xv[i].x * xv[i].x + xv[i].y * xv[i].y + xv[i].z * xv[i].z + xv[i].w * xv[i].w;
;           ss = wave_sum(ss);
;           const float rstd = __builtin_amdgcn_rsqf(ss * (1.f / 1024.f) + EPSF);
;           u16* h = P.hy + (long)row * 1024;
; #pragma unroll
;           for (int i = 0; i < 4; ++i) {
;             const int col = (i * 64 + lane) * 4;
;             const float4 g = *reinterpret_cast<const float4*>(gpre + col);
;             const float4 sh = *reinterpret_cast<const float4*>(modp + sh_idx * 1024 + col);
;             const float4 sc = *reinterpret_cast<const float4*>(modp + (sh_idx + 1) * 1024 + col);
;             const unsigned h0 = f2bf(xv[i].x * rstd * g.x * (1.f + sc.x) + sh.x);
;             const unsigned h1 = f2bf(xv[i].y * rstd * g.y * (1.f + sc.y) + sh.y);
;             const unsigned h2 = f2bf(xv[i].z * rstd * g.z * (1.f + sc.z) + sh.z);
;             const unsigned h3 = f2bf(xv[i].w * rstd * g.w * (1.f + sc.w) + sh.w);
;             *reinterpret_cast<uint2*>(h + col) = make_uint2(h0 | (h1 << 16), h2 | (h3 << 16));
;           }
	global_load_dwordx4 v[88:91], v136, s[98:99] offset:0
	global_load_dwordx4 v[92:95], v136, s[98:99] offset:1024
	global_load_dwordx4 v[96:99], v136, s[98:99] offset:2048
	global_load_dwordx4 v[100:103], v136, s[98:99] offset:3072
	s_waitcnt vmcnt(0)
	v_fma_f32 v88, v88, v32, v88
	v_fma_f32 v89, v89, v33, v89
	v_fma_f32 v90, v90, v34, v90
	v_fma_f32 v91, v91, v35, v91
	v_fma_f32 v92, v92, v36, v92
	v_fma_f32 v93, v93, v37, v93
	v_fma_f32 v94, v94, v38, v94
	v_fma_f32 v95, v95, v39, v95
	v_fma_f32 v96, v96, v40, v96
	v_fma_f32 v97, v97, v41, v97
	v_fma_f32 v98, v98, v42, v98
	v_fma_f32 v99, v99, v43, v99
	v_fma_f32 v100, v100, v44, v100
	v_fma_f32 v101, v101, v45, v101
	v_fma_f32 v102, v102, v46, v102
	v_fma_f32 v103, v103, v47, v103
	s_lshl_b32 vcc_lo, s19, 12
	s_add_u32 vcc_lo, vcc_lo, 0x7000000
	s_add_u32 s100, s12, vcc_lo
	s_addc_u32 s101, s13, 0
	global_load_dwordx4 v[32:35], v136, s[100:101] offset:0
	global_load_dwordx4 v[36:39], v136, s[100:101] offset:1024
	global_load_dwordx4 v[40:43], v136, s[100:101] offset:2048
	global_load_dwordx4 v[44:47], v136, s[100:101] offset:3072
	v_mul_f32_e32 v138, v0, v0
	v_mul_f32_e32 v149, v1, v1
	v_mul_f32_e32 v150, v2, v2
	v_mul_f32_e32 v154, v3, v3
	v_fma_f32 v138, v4, v4, v138
	v_fma_f32 v149, v5, v5, v149
	v_fma_f32 v150, v6, v6, v150
	v_fma_f32 v154, v7, v7, v154
	v_fma_f32 v138, v8, v8, v138
	v_fma_f32 v149, v9, v9, v149
	v_fma_f32 v150, v10, v10, v150
	v_fma_f32 v154, v11, v11, v154
	v_fma_f32 v138, v12, v12, v138
	v_fma_f32 v149, v13, v13, v149
	v_fma_f32 v150, v14, v14, v150
	v_fma_f32 v154, v15, v15, v154
	v_add_f32_e32 v138, v138, v149
	v_add_f32_e32 v150, v150, v154
	v_add_f32_e32 v138, v138, v150
	s_nop 1
	v_add_f32_dpp v138, v138, v138 quad_perm:[1,0,3,2] row_mask:0xf bank_mask:0xf
	s_nop 1
	v_add_f32_dpp v138, v138, v138 quad_perm:[2,3,0,1] row_mask:0xf bank_mask:0xf
	s_nop 1
	v_add_f32_dpp v138, v138, v138 row_half_mirror row_mask:0xf bank_mask:0xf
	s_nop 1
	v_add_f32_dpp v138, v138, v138 row_mirror row_mask:0xf bank_mask:0xf
	v_mov_b32_e32 v139, v138
	s_nop 1
	v_permlane16_swap_b32_e32 v138, v139
	v_add_f32_e32 v138, v138, v139
	v_mov_b32_e32 v139, v138
	s_nop 1
	v_permlane32_swap_b32_e32 v138, v139
	v_add_f32_e32 v138, v138, v139
	v_mul_f32_e32 v138, 0x3a800000, v138
	v_add_f32_e32 v138, 0x358637bd, v138
	v_rsq_f32_e32 v140, v138
	s_nop 0
	v_mul_f32_e32 v120, v0, v140
	v_mul_f32_e32 v121, v1, v140
	v_mul_f32_e32 v122, v2, v140
	v_mul_f32_e32 v123, v3, v140
	v_mul_f32_e32 v124, v4, v140
	v_mul_f32_e32 v125, v5, v140
	v_mul_f32_e32 v126, v6, v140
	v_mul_f32_e32 v127, v7, v140
	v_mul_f32_e32 v128, v8, v140
	v_mul_f32_e32 v129, v9, v140
	v_mul_f32_e32 v130, v10, v140
	v_mul_f32_e32 v131, v11, v140
	v_mul_f32_e32 v132, v12, v140
	v_mul_f32_e32 v133, v13, v140
	v_mul_f32_e32 v134, v14, v140
	v_mul_f32_e32 v135, v15, v140
	v_fma_f32 v120, v120, v88, v104
	v_fma_f32 v121, v121, v89, v105
	v_fma_f32 v122, v122, v90, v106
	v_fma_f32 v123, v123, v91, v107
	v_fma_f32 v124, v124, v92, v108
	v_fma_f32 v125, v125, v93, v109
	v_fma_f32 v126, v126, v94, v110
	v_fma_f32 v127, v127, v95, v111
	v_fma_f32 v128, v128, v96, v112
	v_fma_f32 v129, v129, v97, v113
	v_fma_f32 v130, v130, v98, v114
	v_fma_f32 v131, v131, v99, v115
	v_fma_f32 v132, v132, v100, v116
	v_fma_f32 v133, v133, v101, v117
	v_fma_f32 v134, v134, v102, v118
	v_fma_f32 v135, v135, v103, v119
	v_cvt_pk_bf16_f32 v156, v120, v121
	v_cvt_pk_bf16_f32 v157, v122, v123
	v_cvt_pk_bf16_f32 v158, v124, v125
	v_cvt_pk_bf16_f32 v159, v126, v127
	v_cvt_pk_bf16_f32 v160, v128, v129
	v_cvt_pk_bf16_f32 v161, v130, v131
	v_cvt_pk_bf16_f32 v162, v132, v133
	v_cvt_pk_bf16_f32 v163, v134, v135
	s_lshl_b32 vcc_lo, s19, 11
	s_add_u32 vcc_lo, vcc_lo, 0x3000000
	s_add_u32 s100, s14, vcc_lo
	s_addc_u32 s101, s15, 0
	global_store_dwordx2 v137, v[156:157], s[100:101] offset:0
	global_store_dwordx2 v137, v[158:159], s[100:101] offset:512
	global_store_dwordx2 v137, v[160:161], s[100:101] offset:1024
	global_store_dwordx2 v137, v[162:163], s[100:101] offset:1536
	s_lshl_b32 vcc_lo, s19, 12
	s_add_u32 vcc_lo, vcc_lo, 0x7800000
	s_add_u32 s100, s12, vcc_lo
	s_addc_u32 s101, s13, 0
	global_load_dwordx4 v[0:3], v136, s[100:101] offset:0
	global_load_dwordx4 v[4:7], v136, s[100:101] offset:1024
	global_load_dwordx4 v[8:11], v136, s[100:101] offset:2048
	global_load_dwordx4 v[12:15], v136, s[100:101] offset:3072
	v_mul_f32_e32 v138, v16, v16
	v_mul_f32_e32 v149, v17, v17
	v_mul_f32_e32 v150, v18, v18
	v_mul_f32_e32 v154, v19, v19
	v_fma_f32 v138, v20, v20, v138
	v_fma_f32 v149, v21, v21, v149
	v_fma_f32 v150, v22, v22, v150
	v_fma_f32 v154, v23, v23, v154
	v_fma_f32 v138, v24, v24, v138
	v_fma_f32 v149, v25, v25, v149
	v_fma_f32 v150, v26, v26, v150
	v_fma_f32 v154, v27, v27, v154
	v_fma_f32 v138, v28, v28, v138
	v_fma_f32 v149, v29, v29, v149
	v_fma_f32 v150, v30, v30, v150
	v_fma_f32 v154, v31, v31, v154
	v_add_f32_e32 v138, v138, v149
	v_add_f32_e32 v150, v150, v154
	v_add_f32_e32 v138, v138, v150
	s_nop 1
	v_add_f32_dpp v138, v138, v138 quad_perm:[1,0,3,2] row_mask:0xf bank_mask:0xf
	s_nop 1
	v_add_f32_dpp v138, v138, v138 quad_perm:[2,3,0,1] row_mask:0xf bank_mask:0xf
	s_nop 1
	v_add_f32_dpp v138, v138, v138 row_half_mirror row_mask:0xf bank_mask:0xf
	s_nop 1
	v_add_f32_dpp v138, v138, v138 row_mirror row_mask:0xf bank_mask:0xf
	v_mov_b32_e32 v139, v138
	s_nop 1
	v_permlane16_swap_b32_e32 v138, v139
	v_add_f32_e32 v138, v138, v139
	v_mov_b32_e32 v139, v138
	s_nop 1
	v_permlane32_swap_b32_e32 v138, v139
	v_add_f32_e32 v138, v138, v139
	v_mul_f32_e32 v138, 0x3a800000, v138
	v_add_f32_e32 v138, 0x358637bd, v138
	v_rsq_f32_e32 v140, v138
	s_nop 0
	v_mul_f32_e32 v120, v16, v140
; __device__ __forceinline__ void row_phase(const Params& P, int glayer, int layer, int xsrc, bool hasY, int gate_idx, const float* gpost,
;                           int xdst, bool doH, const float* gpre, int sh_idx, int nrows) {
;     ...
;         if (doH) {
;           float ss = 0.f;
; #pragma unroll
;           for (int i = 0; i < 4; ++i) ss += xv[i].x * xv[i].x + xv[i].y * xv[i].y + xv[i].z * xv[i].z + xv[i].w * xv[i].w;
;           ss = wave_sum(ss);
;           const float rstd = __builtin_amdgcn_rsqf(ss * (1.f / 1024.f) + EPSF);
;           u16* h = P.hy + (long)row * 1024;
; #pragma unroll
;           for (int i = 0; i < 4; ++i) {
;             const int col = (i * 64 + lane) * 4;
;             const float4 g = *reinterpret_cast<const float4*>(gpre + col);
;             const float4 sh = *reinterpret_cast<const float4*>(modp + sh_idx * 1024 + col);
;             const float4 sc = *reinterpret_cast<const float4*>(modp + (sh_idx + 1) * 1024 + col);
;             const unsigned h0 = f2bf(xv[i].x * rstd * g.x * (1.f + sc.x) + sh.x);
;             const unsigned h1 = f2bf(xv[i].y * rstd * g.y * (1.f + sc.y) + sh.y);
;             const unsigned h2 = f2bf(xv[i].z * rstd * g.z * (1.f + sc.z) + sh.z);
;             const unsigned h3 = f2bf(xv[i].w * rstd * g.w * (1.f + sc.w) + sh.w);
;             *reinterpret_cast<uint2*>(h + col) = make_uint2(h0 | (h1 << 16), h2 | (h3 << 16));
;           }
	v_mul_f32_e32 v121, v17, v140
	v_mul_f32_e32 v122, v18, v140
	v_mul_f32_e32 v123, v19, v140
	v_mul_f32_e32 v124, v20, v140
	v_mul_f32_e32 v125, v21, v140
	v_mul_f32_e32 v126, v22, v140
	v_mul_f32_e32 v127, v23, v140
	v_mul_f32_e32 v128, v24, v140
	v_mul_f32_e32 v129, v25, v140
	v_mul_f32_e32 v130, v26, v140
	v_mul_f32_e32 v131, v27, v140
	v_mul_f32_e32 v132, v28, v140
	v_mul_f32_e32 v133, v29, v140
	v_mul_f32_e32 v134, v30, v140
	v_mul_f32_e32 v135, v31, v140
	v_fma_f32 v120, v120, v88, v104
	v_fma_f32 v121, v121, v89, v105
	v_fma_f32 v122, v122, v90, v106
	v_fma_f32 v123, v123, v91, v107
	v_fma_f32 v124, v124, v92, v108
	v_fma_f32 v125, v125, v93, v109
	v_fma_f32 v126, v126, v94, v110
	v_fma_f32 v127, v127, v95, v111
	v_fma_f32 v128, v128, v96, v112
	v_fma_f32 v129, v129, v97, v113
	v_fma_f32 v130, v130, v98, v114
	v_fma_f32 v131, v131, v99, v115
	v_fma_f32 v132, v132, v100, v116
	v_fma_f32 v133, v133, v101, v117
	v_fma_f32 v134, v134, v102, v118
	v_fma_f32 v135, v135, v103, v119
	v_cvt_pk_bf16_f32 v156, v120, v121
	v_cvt_pk_bf16_f32 v157, v122, v123
	v_cvt_pk_bf16_f32 v158, v124, v125
	v_cvt_pk_bf16_f32 v159, v126, v127
	v_cvt_pk_bf16_f32 v160, v128, v129
	v_cvt_pk_bf16_f32 v161, v130, v131
	v_cvt_pk_bf16_f32 v162, v132, v133
	v_cvt_pk_bf16_f32 v163, v134, v135
	s_lshl_b32 vcc_lo, s19, 11
	s_add_u32 vcc_lo, vcc_lo, 0x3400000
	s_add_u32 s100, s14, vcc_lo
	s_addc_u32 s101, s15, 0
	global_store_dwordx2 v137, v[156:157], s[100:101] offset:0
	global_store_dwordx2 v137, v[158:159], s[100:101] offset:512
	global_store_dwordx2 v137, v[160:161], s[100:101] offset:1024
	global_store_dwordx2 v137, v[162:163], s[100:101] offset:1536
	s_waitcnt vmcnt(12)
	v_mul_f32_e32 v138, v32, v32
	v_mul_f32_e32 v149, v33, v33
	v_mul_f32_e32 v150, v34, v34
	v_mul_f32_e32 v154, v35, v35
	v_fma_f32 v138, v36, v36, v138
	v_fma_f32 v149, v37, v37, v149
	v_fma_f32 v150, v38, v38, v150
	v_fma_f32 v154, v39, v39, v154
	v_fma_f32 v138, v40, v40, v138
	v_fma_f32 v149, v41, v41, v149
	v_fma_f32 v150, v42, v42, v150
	v_fma_f32 v154, v43, v43, v154
	v_fma_f32 v138, v44, v44, v138
	v_fma_f32 v149, v45, v45, v149
	v_fma_f32 v150, v46, v46, v150
	v_fma_f32 v154, v47, v47, v154
	v_add_f32_e32 v138, v138, v149
	v_add_f32_e32 v150, v150, v154
	v_add_f32_e32 v138, v138, v150
	s_nop 1
	v_add_f32_dpp v138, v138, v138 quad_perm:[1,0,3,2] row_mask:0xf bank_mask:0xf
	s_nop 1
	v_add_f32_dpp v138, v138, v138 quad_perm:[2,3,0,1] row_mask:0xf bank_mask:0xf
	s_nop 1
	v_add_f32_dpp v138, v138, v138 row_half_mirror row_mask:0xf bank_mask:0xf
	s_nop 1
	v_add_f32_dpp v138, v138, v138 row_mirror row_mask:0xf bank_mask:0xf
	v_mov_b32_e32 v139, v138
	s_nop 1
	v_permlane16_swap_b32_e32 v138, v139
	v_add_f32_e32 v138, v138, v139
	v_mov_b32_e32 v139, v138
	s_nop 1
	v_permlane32_swap_b32_e32 v138, v139
	v_add_f32_e32 v138, v138, v139
	v_mul_f32_e32 v138, 0x3a800000, v138
	v_add_f32_e32 v138, 0x358637bd, v138
	v_rsq_f32_e32 v140, v138
	s_nop 0
	v_mul_f32_e32 v120, v32, v140
	v_mul_f32_e32 v121, v33, v140
	v_mul_f32_e32 v122, v34, v140
	v_mul_f32_e32 v123, v35, v140
	v_mul_f32_e32 v124, v36, v140
	v_mul_f32_e32 v125, v37, v140
	v_mul_f32_e32 v126, v38, v140
	v_mul_f32_e32 v127, v39, v140
	v_mul_f32_e32 v128, v40, v140
	v_mul_f32_e32 v129, v41, v140
	v_mul_f32_e32 v130, v42, v140
	v_mul_f32_e32 v131, v43, v140
	v_mul_f32_e32 v132, v44, v140
	v_mul_f32_e32 v133, v45, v140
	v_mul_f32_e32 v134, v46, v140
	v_mul_f32_e32 v135, v47, v140
	v_fma_f32 v120, v120, v88, v104
	v_fma_f32 v121, v121, v89, v105
	v_fma_f32 v122, v122, v90, v106
	v_fma_f32 v123, v123, v91, v107
	v_fma_f32 v124, v124, v92, v108
	v_fma_f32 v125, v125, v93, v109
	v_fma_f32 v126, v126, v94, v110
	v_fma_f32 v127, v127, v95, v111
	v_fma_f32 v128, v128, v96, v112
	v_fma_f32 v129, v129, v97, v113
	v_fma_f32 v130, v130, v98, v114
	v_fma_f32 v131, v131, v99, v115
	v_fma_f32 v132, v132, v100, v116
	v_fma_f32 v133, v133, v101, v117
	v_fma_f32 v134, v134, v102, v118
	v_fma_f32 v135, v135, v103, v119
	v_cvt_pk_bf16_f32 v156, v120, v121
	v_cvt_pk_bf16_f32 v157, v122, v123
	v_cvt_pk_bf16_f32 v158, v124, v125
	v_cvt_pk_bf16_f32 v159, v126, v127
	v_cvt_pk_bf16_f32 v160, v128, v129
	v_cvt_pk_bf16_f32 v161, v130, v131
	v_cvt_pk_bf16_f32 v162, v132, v133
	v_cvt_pk_bf16_f32 v163, v134, v135
	s_lshl_b32 vcc_lo, s19, 11
	s_add_u32 vcc_lo, vcc_lo, 0x3800000
	s_add_u32 s100, s14, vcc_lo
	s_addc_u32 s101, s15, 0
	global_store_dwordx2 v137, v[156:157], s[100:101] offset:0
	global_store_dwordx2 v137, v[158:159], s[100:101] offset:512
	global_store_dwordx2 v137, v[160:161], s[100:101] offset:1024
	global_store_dwordx2 v137, v[162:163], s[100:101] offset:1536
	s_waitcnt vmcnt(8)
; __device__ __forceinline__ void row_phase(const Params& P, int glayer, int layer, int xsrc, bool hasY, int gate_idx, const float* gpost,
;                           int xdst, bool doH, const float* gpre, int sh_idx, int nrows) {
;     ...
;   for (int rb = blockIdx.x * 8 + wid; rb < nrows; rb += 4 * stride) {
;     uint4 xr[4][4];
;     uint2 yy[4][4];
; #pragma unroll
;     for (int u = 0; u < 4; ++u) {
;       const int R = rb + u * stride;
;       if (R < nrows) {
;     ...
;         if (doH) {
;           float ss = 0.f;
; #pragma unroll
;           for (int i = 0; i < 4; ++i) ss += xv[i].x * xv[i].x + xv[i].y * xv[i].y + xv[i].z * xv[i].z + xv[i].w * xv[i].w;
;           ss = wave_sum(ss);
;           const float rstd = __builtin_amdgcn_rsqf(ss * (1.f / 1024.f) + EPSF);
;           u16* h = P.hy + (long)row * 1024;
; #pragma unroll
;           for (int i = 0; i < 4; ++i) {
;             const int col = (i * 64 + lane) * 4;
;             const float4 g = *reinterpret_cast<const float4*>(gpre + col);
;             const float4 sh = *reinterpret_cast<const float4*>(modp + sh_idx * 1024 + col);
;             const float4 sc = *reinterpret_cast<const float4*>(modp + (sh_idx + 1) * 1024 + col);
;             const unsigned h0 = f2bf(xv[i].x * rstd * g.x * (1.f + sc.x) + sh.x);
;             const unsigned h1 = f2bf(xv[i].y * rstd * g.y * (1.f + sc.y) + sh.y);
;             const unsigned h2 = f2bf(xv[i].z * rstd * g.z * (1.f + sc.z) + sh.z);
;             const unsigned h3 = f2bf(xv[i].w * rstd * g.w * (1.f + sc.w) + sh.w);
;             *reinterpret_cast<uint2*>(h + col) = make_uint2(h0 | (h1 << 16), h2 | (h3 << 16));
;           }
	v_mul_f32_e32 v138, v0, v0
	v_mul_f32_e32 v149, v1, v1
	v_mul_f32_e32 v150, v2, v2
	v_mul_f32_e32 v154, v3, v3
	v_fma_f32 v138, v4, v4, v138
	v_fma_f32 v149, v5, v5, v149
	v_fma_f32 v150, v6, v6, v150
	v_fma_f32 v154, v7, v7, v154
	v_fma_f32 v138, v8, v8, v138
	v_fma_f32 v149, v9, v9, v149
	v_fma_f32 v150, v10, v10, v150
	v_fma_f32 v154, v11, v11, v154
	v_fma_f32 v138, v12, v12, v138
	v_fma_f32 v149, v13, v13, v149
	v_fma_f32 v150, v14, v14, v150
	v_fma_f32 v154, v15, v15, v154
	v_add_f32_e32 v138, v138, v149
	v_add_f32_e32 v150, v150, v154
	v_add_f32_e32 v138, v138, v150
	s_nop 1
	v_add_f32_dpp v138, v138, v138 quad_perm:[1,0,3,2] row_mask:0xf bank_mask:0xf
	s_nop 1
	v_add_f32_dpp v138, v138, v138 quad_perm:[2,3,0,1] row_mask:0xf bank_mask:0xf
	s_nop 1
	v_add_f32_dpp v138, v138, v138 row_half_mirror row_mask:0xf bank_mask:0xf
	s_nop 1
	v_add_f32_dpp v138, v138, v138 row_mirror row_mask:0xf bank_mask:0xf
	v_mov_b32_e32 v139, v138
	s_nop 1
	v_permlane16_swap_b32_e32 v138, v139
	v_add_f32_e32 v138, v138, v139
	v_mov_b32_e32 v139, v138
	s_nop 1
	v_permlane32_swap_b32_e32 v138, v139
	v_add_f32_e32 v138, v138, v139
	v_mul_f32_e32 v138, 0x3a800000, v138
	v_add_f32_e32 v138, 0x358637bd, v138
	v_rsq_f32_e32 v140, v138
	s_nop 0
	v_mul_f32_e32 v120, v0, v140
	v_mul_f32_e32 v121, v1, v140
	v_mul_f32_e32 v122, v2, v140
	v_mul_f32_e32 v123, v3, v140
	v_mul_f32_e32 v124, v4, v140
	v_mul_f32_e32 v125, v5, v140
	v_mul_f32_e32 v126, v6, v140
	v_mul_f32_e32 v127, v7, v140
	v_mul_f32_e32 v128, v8, v140
	v_mul_f32_e32 v129, v9, v140
	v_mul_f32_e32 v130, v10, v140
	v_mul_f32_e32 v131, v11, v140
	v_mul_f32_e32 v132, v12, v140
	v_mul_f32_e32 v133, v13, v140
	v_mul_f32_e32 v134, v14, v140
	v_mul_f32_e32 v135, v15, v140
	v_fma_f32 v120, v120, v88, v104
	v_fma_f32 v121, v121, v89, v105
	v_fma_f32 v122, v122, v90, v106
	v_fma_f32 v123, v123, v91, v107
	v_fma_f32 v124, v124, v92, v108
	v_fma_f32 v125, v125, v93, v109
	v_fma_f32 v126, v126, v94, v110
	v_fma_f32 v127, v127, v95, v111
	v_fma_f32 v128, v128, v96, v112
	v_fma_f32 v129, v129, v97, v113
	v_fma_f32 v130, v130, v98, v114
	v_fma_f32 v131, v131, v99, v115
	v_fma_f32 v132, v132, v100, v116
	v_fma_f32 v133, v133, v101, v117
	v_fma_f32 v134, v134, v102, v118
	v_fma_f32 v135, v135, v103, v119
	v_cvt_pk_bf16_f32 v156, v120, v121
	v_cvt_pk_bf16_f32 v157, v122, v123
	v_cvt_pk_bf16_f32 v158, v124, v125
	v_cvt_pk_bf16_f32 v159, v126, v127
	v_cvt_pk_bf16_f32 v160, v128, v129
	v_cvt_pk_bf16_f32 v161, v130, v131
	v_cvt_pk_bf16_f32 v162, v132, v133
	v_cvt_pk_bf16_f32 v163, v134, v135
	s_lshl_b32 vcc_lo, s19, 11
	s_add_u32 vcc_lo, vcc_lo, 0x3c00000
	s_add_u32 s100, s14, vcc_lo
	s_addc_u32 s101, s15, 0
	global_store_dwordx2 v137, v[156:157], s[100:101] offset:0
	global_store_dwordx2 v137, v[158:159], s[100:101] offset:512
	global_store_dwordx2 v137, v[160:161], s[100:101] offset:1024
	global_store_dwordx2 v137, v[162:163], s[100:101] offset:1536
	s_waitcnt vmcnt(0)
	s_cmp_lt_u32 s19, 0x400
	s_cbranch_scc0 .Lmy_r1_done
; __device__ __forceinline__ void row_phase(const Params& P, int glayer, int layer, int xsrc, bool hasY, int gate_idx, const float* gpost,
;                           int xdst, bool doH, const float* gpre, int sh_idx, int nrows) {
;     ...
;           const float* xin_;
;           if (xsrc == 0) xin_ = R < N_X ? P.x + (long)R * 1024 : P.ctx + (long)(R - N_X) * 1024;
;           else           xin_ = P.xc + (long)(R - N_X) * 1024;
; #pragma unroll
;           for (int i = 0; i < 4; ++i) xr[u][i] = *reinterpret_cast<const uint4*>(xin_ + (i * 64 + lane) * 4);
;     ...
;         if (doH) {
;           float ss = 0.f;
; #pragma unroll
;           for (int i = 0; i < 4; ++i) ss += xv[i].x * xv[i].x + xv[i].y * xv[i].y + xv[i].z * xv[i].z + xv[i].w * xv[i].w;
;           ss = wave_sum(ss);
;           const float rstd = __builtin_amdgcn_rsqf(ss * (1.f / 1024.f) + EPSF);
;           u16* h = P.hy + (long)row * 1024;
; #pragma unroll
;           for (int i = 0; i < 4; ++i) {
;             const int col = (i * 64 + lane) * 4;
;             const float4 g = *reinterpret_cast<const float4*>(gpre + col);
;             const float4 sh = *reinterpret_cast<const float4*>(modp + sh_idx * 1024 + col);
;             const float4 sc = *reinterpret_cast<const float4*>(modp + (sh_idx + 1) * 1024 + col);
;             const unsigned h0 = f2bf(xv[i].x * rstd * g.x * (1.f + sc.x) + sh.x);
;             const unsigned h1 = f2bf(xv[i].y * rstd * g.y * (1.f + sc.y) + sh.y);
;             const unsigned h2 = f2bf(xv[i].z * rstd * g.z * (1.f + sc.z) + sh.z);
;             const unsigned h3 = f2bf(xv[i].w * rstd * g.w * (1.f + sc.w) + sh.w);
;             *reinterpret_cast<uint2*>(h + col) = make_uint2(h0 | (h1 << 16), h2 | (h3 << 16));
;           }
	s_load_dwordx2 s[12:13], s[4:5], 0x10
	s_waitcnt lgkmcnt(0)
	s_add_u32 s100, s20, 0x18000
	s_addc_u32 s101, s21, 0
	global_load_dwordx4 v[104:107], v136, s[100:101] offset:0
	global_load_dwordx4 v[108:111], v136, s[100:101] offset:1024
	global_load_dwordx4 v[112:115], v136, s[100:101] offset:2048
	global_load_dwordx4 v[116:119], v136, s[100:101] offset:3072
	s_add_u32 s100, s100, 0x1000
	s_addc_u32 s101, s101, 0
	global_load_dwordx4 v[16:19], v136, s[100:101] offset:0
	global_load_dwordx4 v[20:23], v136, s[100:101] offset:1024
	global_load_dwordx4 v[24:27], v136, s[100:101] offset:2048
	global_load_dwordx4 v[28:31], v136, s[100:101] offset:3072
	s_load_dwordx2 s[98:99], s[4:5], 0x30
	s_waitcnt lgkmcnt(0)
	global_load_dwordx4 v[88:91], v136, s[98:99] offset:0
	global_load_dwordx4 v[92:95], v136, s[98:99] offset:1024
	global_load_dwordx4 v[96:99], v136, s[98:99] offset:2048
	global_load_dwordx4 v[100:103], v136, s[98:99] offset:3072
	s_waitcnt vmcnt(0)
	v_fma_f32 v88, v88, v16, v88
	v_fma_f32 v89, v89, v17, v89
	v_fma_f32 v90, v90, v18, v90
	v_fma_f32 v91, v91, v19, v91
	v_fma_f32 v92, v92, v20, v92
	v_fma_f32 v93, v93, v21, v93
	v_fma_f32 v94, v94, v22, v94
	v_fma_f32 v95, v95, v23, v95
	v_fma_f32 v96, v96, v24, v96
	v_fma_f32 v97, v97, v25, v97
	v_fma_f32 v98, v98, v26, v98
	v_fma_f32 v99, v99, v27, v99
	v_fma_f32 v100, v100, v28, v100
	v_fma_f32 v101, v101, v29, v101
	v_fma_f32 v102, v102, v30, v102
	v_fma_f32 v103, v103, v31, v103
	s_lshl_b32 vcc_lo, s19, 12
	s_add_u32 s100, s12, vcc_lo
	s_addc_u32 s101, s13, 0
	global_load_dwordx4 v[0:3], v136, s[100:101] offset:0
	global_load_dwordx4 v[4:7], v136, s[100:101] offset:1024
	global_load_dwordx4 v[8:11], v136, s[100:101] offset:2048
	global_load_dwordx4 v[12:15], v136, s[100:101] offset:3072
	s_waitcnt vmcnt(0)
	v_mul_f32_e32 v138, v0, v0
	v_mul_f32_e32 v149, v1, v1
	v_mul_f32_e32 v150, v2, v2
	v_mul_f32_e32 v154, v3, v3
	v_fma_f32 v138, v4, v4, v138
	v_fma_f32 v149, v5, v5, v149
	v_fma_f32 v150, v6, v6, v150
	v_fma_f32 v154, v7, v7, v154
	v_fma_f32 v138, v8, v8, v138
	v_fma_f32 v149, v9, v9, v149
	v_fma_f32 v150, v10, v10, v150
	v_fma_f32 v154, v11, v11, v154
	v_fma_f32 v138, v12, v12, v138
	v_fma_f32 v149, v13, v13, v149
	v_fma_f32 v150, v14, v14, v150
	v_fma_f32 v154, v15, v15, v154
	v_add_f32_e32 v138, v138, v149
	v_add_f32_e32 v150, v150, v154
	v_add_f32_e32 v138, v138, v150
	s_nop 1
	v_add_f32_dpp v138, v138, v138 quad_perm:[1,0,3,2] row_mask:0xf bank_mask:0xf
	s_nop 1
	v_add_f32_dpp v138, v138, v138 quad_perm:[2,3,0,1] row_mask:0xf bank_mask:0xf
	s_nop 1
	v_add_f32_dpp v138, v138, v138 row_half_mirror row_mask:0xf bank_mask:0xf
	s_nop 1
	v_add_f32_dpp v138, v138, v138 row_mirror row_mask:0xf bank_mask:0xf
	v_mov_b32_e32 v139, v138
	s_nop 1
	v_permlane16_swap_b32_e32 v138, v139
	v_add_f32_e32 v138, v138, v139
	v_mov_b32_e32 v139, v138
	s_nop 1
	v_permlane32_swap_b32_e32 v138, v139
	v_add_f32_e32 v138, v138, v139
	v_mul_f32_e32 v138, 0x3a800000, v138
	v_add_f32_e32 v138, 0x358637bd, v138
	v_rsq_f32_e32 v140, v138
	s_nop 0
	v_mul_f32_e32 v120, v0, v140
	v_mul_f32_e32 v121, v1, v140
	v_mul_f32_e32 v122, v2, v140
	v_mul_f32_e32 v123, v3, v140
	v_mul_f32_e32 v124, v4, v140
	v_mul_f32_e32 v125, v5, v140
	v_mul_f32_e32 v126, v6, v140
	v_mul_f32_e32 v127, v7, v140
	v_mul_f32_e32 v128, v8, v140
	v_mul_f32_e32 v129, v9, v140
	v_mul_f32_e32 v130, v10, v140
	v_mul_f32_e32 v131, v11, v140
	v_mul_f32_e32 v132, v12, v140
	v_mul_f32_e32 v133, v13, v140
	v_mul_f32_e32 v134, v14, v140
	v_mul_f32_e32 v135, v15, v140
	v_fma_f32 v120, v120, v88, v104
	v_fma_f32 v121, v121, v89, v105
	v_fma_f32 v122, v122, v90, v106
	v_fma_f32 v123, v123, v91, v107
	v_fma_f32 v124, v124, v92, v108
	v_fma_f32 v125, v125, v93, v109
	v_fma_f32 v126, v126, v94, v110
	v_fma_f32 v127, v127, v95, v111
	v_fma_f32 v128, v128, v96, v112
	v_fma_f32 v129, v129, v97, v113
	v_fma_f32 v130, v130, v98, v114
	v_fma_f32 v131, v131, v99, v115
	v_fma_f32 v132, v132, v100, v116
	v_fma_f32 v133, v133, v101, v117
	v_fma_f32 v134, v134, v102, v118
	v_fma_f32 v135, v135, v103, v119
	v_cvt_pk_bf16_f32 v156, v120, v121
	v_cvt_pk_bf16_f32 v157, v122, v123
	v_cvt_pk_bf16_f32 v158, v124, v125
	v_cvt_pk_bf16_f32 v159, v126, v127
	v_cvt_pk_bf16_f32 v160, v128, v129
	v_cvt_pk_bf16_f32 v161, v130, v131
	v_cvt_pk_bf16_f32 v162, v132, v133
	v_cvt_pk_bf16_f32 v163, v134, v135
	s_lshl_b32 vcc_lo, s19, 11
	s_add_u32 vcc_lo, vcc_lo, 0x4000000
	s_add_u32 s100, s14, vcc_lo
	s_addc_u32 s101, s15, 0
	global_store_dwordx2 v137, v[156:157], s[100:101] offset:0
	global_store_dwordx2 v137, v[158:159], s[100:101] offset:512
	global_store_dwordx2 v137, v[160:161], s[100:101] offset:1024
	global_store_dwordx2 v137, v[162:163], s[100:101] offset:1536
.Lmy_r1_done:
	s_branch .LBB0_109

; __device__ __forceinline__ float bf2f(u16 h) { return __uint_as_float(((unsigned)h) << 16); }
; __device__ __forceinline__ void lru_tile(const Params& P, int chunk, int head, int pass, char* smem_raw) {
;     ...
;     const float w0 = P.conv_w[gch], w1 = P.conv_w[512 + gch], w2 = P.conv_w[1024 + gch], w3 = P.conv_w[1536 + gch];
;     const float cb = P.conv_b[gch];
;     const u16* zu = P.zq + gch;
;     const int r = row0 + q * 32;
;     float uv[35];
; #pragma unroll
;     for (int i = 0; i < 35; ++i) {
;       const int rr = r - 2 + i;
;       uv[i] = (rr >= seq_lo && rr < seq_hi) ? bf2f(zu[(long)rr * 1536]) : 0.f;
;     ...
;       *reinterpret_cast<uint4*>(&sm_w[rowi * LDSS + kg * 8]) = ldg16(P.wg + ((long)(d * 8 + head) * 128 + rowi) * 64 + kg * 8);
;     }
;     float ba[4], bi[4], c8[4];
; #pragma unroll
;     for (int tc = 0; tc < 4; ++tc) {
;       const int cidx = d * 512 + head * 64 + 16 * tc + (lane & 15);
;       ba[tc] = P.b_a[cidx] * -1.4426950408889634f; bi[tc] = P.b_i[cidx] * -1.4426950408889634f;
;       const float nl = -P.lam[cidx];
.Lmy_lrua_fl:
	s_cmp_eq_u32 s57, 0
	s_cselect_b64 s[0:1], s[84:85], 0
	s_cmp_eq_u32 s57, s60
	s_cselect_b64 s[4:5], s[86:87], 0
	v_cndmask_b32_e64 v202, 1.0, 0, s[0:1]
	v_cndmask_b32_e64 v203, 1.0, 0, s[4:5]
	v_mov_b32_e32 v255, 0x1800
	v_cndmask_b32_e64 v150, 0, v255, s[0:1]
	v_lshlrev_b32_e32 v136, 1, v150
	v_add_u32_e32 v136, v134, v136
	v_add_u32_e32 v150, v134, v150
	v_cndmask_b32_e64 v151, 0, v255, s[4:5]
	v_sub_u32_e32 v151, v134, v151
	s_lshl_b32 s61, s71, 7
	s_mul_i32 s0, s61, 0xc00
	s_lshl_b32 s1, s56, 1
	s_add_u32 s0, s0, s1
	s_add_u32 s4, s10, s0
	s_addc_u32 s5, s11, 0
	s_sub_u32 s4, s4, 0x1800
	s_subb_u32 s5, s5, 0
	global_load_ushort v90, v136, s[4:5]
	s_add_u32 s4, s4, 0xc00
	s_addc_u32 s5, s5, 0
	global_load_ushort v91, v150, s[4:5]
	s_add_u32 s4, s4, 0xc00
	s_addc_u32 s5, s5, 0
	global_load_ushort v92, v134, s[4:5]
	s_add_u32 s4, s4, 0xc00
	s_addc_u32 s5, s5, 0
	global_load_ushort v93, v134, s[4:5]
	s_add_u32 s4, s4, 0xc00
	s_addc_u32 s5, s5, 0
	global_load_ushort v94, v134, s[4:5]
	s_add_u32 s4, s4, 0xc00
	s_addc_u32 s5, s5, 0
	global_load_ushort v95, v134, s[4:5]
	s_add_u32 s4, s4, 0xc00
	s_addc_u32 s5, s5, 0
	global_load_ushort v96, v134, s[4:5]
	s_add_u32 s4, s4, 0xc00
	s_addc_u32 s5, s5, 0
	global_load_ushort v97, v134, s[4:5]
	s_add_u32 s4, s4, 0xc00
	s_addc_u32 s5, s5, 0
	global_load_ushort v98, v134, s[4:5]
	s_add_u32 s4, s4, 0xc00
	s_addc_u32 s5, s5, 0
	global_load_ushort v99, v134, s[4:5]
	s_add_u32 s4, s4, 0xc00
	s_addc_u32 s5, s5, 0
	global_load_ushort v100, v134, s[4:5]
	s_add_u32 s4, s4, 0xc00
	s_addc_u32 s5, s5, 0
	global_load_ushort v101, v134, s[4:5]
	s_add_u32 s4, s4, 0xc00
	s_addc_u32 s5, s5, 0
	global_load_ushort v102, v134, s[4:5]
	s_add_u32 s4, s4, 0xc00
	s_addc_u32 s5, s5, 0
	global_load_ushort v103, v134, s[4:5]
	s_add_u32 s4, s4, 0xc00
	s_addc_u32 s5, s5, 0
	global_load_ushort v104, v134, s[4:5]
	s_add_u32 s4, s4, 0xc00
	s_addc_u32 s5, s5, 0
	global_load_ushort v105, v134, s[4:5]
	s_add_u32 s4, s4, 0xc00
	s_addc_u32 s5, s5, 0
	global_load_ushort v106, v134, s[4:5]
	s_add_u32 s4, s4, 0xc00
	s_addc_u32 s5, s5, 0
	global_load_ushort v107, v134, s[4:5]
	s_add_u32 s4, s4, 0xc00
	s_addc_u32 s5, s5, 0
	global_load_ushort v108, v134, s[4:5]
	s_add_u32 s4, s4, 0xc00
	s_addc_u32 s5, s5, 0
	global_load_ushort v109, v134, s[4:5]
	s_add_u32 s4, s4, 0xc00
	s_addc_u32 s5, s5, 0
	global_load_ushort v110, v134, s[4:5]
	s_add_u32 s4, s4, 0xc00
	s_addc_u32 s5, s5, 0
	global_load_ushort v111, v134, s[4:5]
	s_add_u32 s4, s4, 0xc00
	s_addc_u32 s5, s5, 0
	global_load_ushort v112, v134, s[4:5]
	s_add_u32 s4, s4, 0xc00
	s_addc_u32 s5, s5, 0
	global_load_ushort v113, v134, s[4:5]
	s_add_u32 s4, s4, 0xc00
	s_addc_u32 s5, s5, 0
	global_load_ushort v114, v134, s[4:5]
	s_add_u32 s4, s4, 0xc00
	s_addc_u32 s5, s5, 0
	global_load_ushort v115, v134, s[4:5]
	s_add_u32 s4, s4, 0xc00
	s_addc_u32 s5, s5, 0
	global_load_ushort v116, v134, s[4:5]
	s_add_u32 s4, s4, 0xc00
	s_addc_u32 s5, s5, 0
	global_load_ushort v117, v134, s[4:5]
	s_add_u32 s4, s4, 0xc00
	s_addc_u32 s5, s5, 0
	global_load_ushort v118, v134, s[4:5]
	s_add_u32 s4, s4, 0xc00
	s_addc_u32 s5, s5, 0
	global_load_ushort v119, v134, s[4:5]
	s_add_u32 s4, s4, 0xc00
	s_addc_u32 s5, s5, 0
	global_load_ushort v120, v134, s[4:5]
	s_add_u32 s4, s4, 0xc00
	s_addc_u32 s5, s5, 0
	global_load_ushort v121, v134, s[4:5]
	s_add_u32 s4, s4, 0xc00
	s_addc_u32 s5, s5, 0
	global_load_ushort v122, v134, s[4:5]
	s_add_u32 s4, s4, 0xc00
	s_addc_u32 s5, s5, 0
	global_load_ushort v123, v134, s[4:5]
	s_add_u32 s4, s4, 0xc00
	s_addc_u32 s5, s5, 0
	global_load_ushort v124, v151, s[4:5]
	v_bfe_u32 v255, v152, 6, 2
	v_and_b32_e32 v253, 15, v152
	v_lshl_add_u32 v255, v255, 4, v253
	v_add_u32_e32 v255, s56, v255
	v_lshlrev_b32_e32 v255, 2, v255
	global_load_dword v65, v255, s[24:25]
	global_load_dword v67, v255, s[24:25] offset:2048
	s_add_u32 s0, s24, 0x1000
	s_addc_u32 s1, s25, 0
	global_load_dword v68, v255, s[0:1]
	global_load_dword v70, v255, s[0:1] offset:2048
	global_load_dword v73, v255, s[26:27]
	s_lshl_b32 s0, s56, 8
	s_add_u32 s0, s0, 0x0
	s_add_u32 s4, s20, s0
	s_addc_u32 s5, s21, 0
	global_load_dwordx4 v[238:241], v251, s[4:5]
	global_load_dwordx4 v[242:245], v251, s[4:5] offset:64
	s_add_u32 s4, s4, 0x2000
	s_addc_u32 s5, s5, 0
	global_load_dwordx4 v[246:249], v251, s[4:5]
	global_load_dwordx4 v[194:197], v251, s[4:5] offset:64
	v_bfe_u32 v255, v152, 6, 2
	v_and_b32_e32 v253, 15, v152
	v_lshl_add_u32 v255, v255, 4, v253
	v_add_u32_e32 v255, s56, v255
	v_lshlrev_b32_e32 v255, 2, v255
	s_add_u32 s0, s28, 0x0
	s_addc_u32 s1, s29, 0
	global_load_dword v75, v255, s[0:1]
	s_add_u32 s0, s30, 0x0
	s_addc_u32 s1, s31, 0
	global_load_dword v84, v255, s[0:1]
	s_add_u32 s0, s36, 0x0
	s_addc_u32 s1, s37, 0
	global_load_dword v85, v255, s[0:1]
	s_barrier
; __device__ __forceinline__ float bf2f(u16 h) { return __uint_as_float(((unsigned)h) << 16); }
; __device__ __forceinline__ void lru_tile(const Params& P, int chunk, int head, int pass, char* smem_raw) {
;     ...
;     for (int i = 0; i < 35; ++i) {
;       const int rr = r - 2 + i;
;       uv[i] = (rr >= seq_lo && rr < seq_hi) ? bf2f(zu[(long)rr * 1536]) : 0.f;
;     }
;     __syncthreads();
; #pragma unroll
;     for (int i = 0; i < 32; ++i) {
;       const float v = cb + uv[i] * w0 + uv[i + 1] * w1 + uv[i + 2] * w2 + uv[i + 3] * w3;
;       sm_uc[(q * 32 + i) * LDSS + ch] = f2bf(v);
	s_waitcnt vmcnt(0)
	v_lshlrev_b32_e32 v90, 16, v90
	v_lshlrev_b32_e32 v91, 16, v91
	v_lshlrev_b32_e32 v92, 16, v92
	v_lshlrev_b32_e32 v93, 16, v93
	v_lshlrev_b32_e32 v94, 16, v94
	v_lshlrev_b32_e32 v95, 16, v95
	v_lshlrev_b32_e32 v96, 16, v96
	v_lshlrev_b32_e32 v97, 16, v97
	v_lshlrev_b32_e32 v98, 16, v98
	v_lshlrev_b32_e32 v99, 16, v99
	v_lshlrev_b32_e32 v100, 16, v100
	v_lshlrev_b32_e32 v101, 16, v101
	v_lshlrev_b32_e32 v102, 16, v102
	v_lshlrev_b32_e32 v103, 16, v103
	v_lshlrev_b32_e32 v104, 16, v104
	v_lshlrev_b32_e32 v105, 16, v105
	v_lshlrev_b32_e32 v106, 16, v106
	v_lshlrev_b32_e32 v107, 16, v107
	v_lshlrev_b32_e32 v108, 16, v108
	v_lshlrev_b32_e32 v109, 16, v109
	v_lshlrev_b32_e32 v110, 16, v110
	v_lshlrev_b32_e32 v111, 16, v111
	v_lshlrev_b32_e32 v112, 16, v112
	v_lshlrev_b32_e32 v113, 16, v113
	v_lshlrev_b32_e32 v114, 16, v114
	v_lshlrev_b32_e32 v115, 16, v115
	v_lshlrev_b32_e32 v116, 16, v116
	v_lshlrev_b32_e32 v117, 16, v117
	v_lshlrev_b32_e32 v118, 16, v118
	v_lshlrev_b32_e32 v119, 16, v119
	v_lshlrev_b32_e32 v120, 16, v120
	v_lshlrev_b32_e32 v121, 16, v121
	v_lshlrev_b32_e32 v122, 16, v122
	v_lshlrev_b32_e32 v123, 16, v123
	v_lshlrev_b32_e32 v124, 16, v124
	v_mul_f32_e32 v90, v90, v202
	v_mul_f32_e32 v91, v91, v202
	v_mul_f32_e32 v124, v124, v203
	v_fma_f32 v162, v90, v65, v73
	v_fma_f32 v162, v91, v67, v162
	v_fma_f32 v162, v92, v68, v162
	v_fma_f32 v162, v93, v70, v162
	v_fma_f32 v163, v91, v65, v73
	v_fma_f32 v163, v92, v67, v163
	v_fma_f32 v163, v93, v68, v163
	v_fma_f32 v163, v94, v70, v163
	v_fma_f32 v164, v92, v65, v73
	v_fma_f32 v164, v93, v67, v164
	v_fma_f32 v164, v94, v68, v164
	v_fma_f32 v164, v95, v70, v164
	v_fma_f32 v165, v93, v65, v73
	v_fma_f32 v165, v94, v67, v165
	v_fma_f32 v165, v95, v68, v165
	v_fma_f32 v165, v96, v70, v165
	v_fma_f32 v166, v94, v65, v73
	v_fma_f32 v166, v95, v67, v166
	v_fma_f32 v166, v96, v68, v166
	v_fma_f32 v166, v97, v70, v166
	v_fma_f32 v167, v95, v65, v73
	v_fma_f32 v167, v96, v67, v167
	v_fma_f32 v167, v97, v68, v167
	v_fma_f32 v167, v98, v70, v167
	v_fma_f32 v168, v96, v65, v73
	v_fma_f32 v168, v97, v67, v168
	v_fma_f32 v168, v98, v68, v168
	v_fma_f32 v168, v99, v70, v168
	v_fma_f32 v169, v97, v65, v73
	v_fma_f32 v169, v98, v67, v169
	v_fma_f32 v169, v99, v68, v169
	v_fma_f32 v169, v100, v70, v169
	v_fma_f32 v170, v98, v65, v73
	v_fma_f32 v170, v99, v67, v170
	v_fma_f32 v170, v100, v68, v170
	v_fma_f32 v170, v101, v70, v170
	v_fma_f32 v171, v99, v65, v73
	v_fma_f32 v171, v100, v67, v171
	v_fma_f32 v171, v101, v68, v171
	v_fma_f32 v171, v102, v70, v171
	v_fma_f32 v172, v100, v65, v73
	v_fma_f32 v172, v101, v67, v172
	v_fma_f32 v172, v102, v68, v172
	v_fma_f32 v172, v103, v70, v172
	v_fma_f32 v173, v101, v65, v73
	v_fma_f32 v173, v102, v67, v173
	v_fma_f32 v173, v103, v68, v173
	v_fma_f32 v173, v104, v70, v173
	v_fma_f32 v174, v102, v65, v73
	v_fma_f32 v174, v103, v67, v174
	v_fma_f32 v174, v104, v68, v174
	v_fma_f32 v174, v105, v70, v174
	v_fma_f32 v175, v103, v65, v73
	v_fma_f32 v175, v104, v67, v175
	v_fma_f32 v175, v105, v68, v175
	v_fma_f32 v175, v106, v70, v175
	v_fma_f32 v176, v104, v65, v73
	v_fma_f32 v176, v105, v67, v176
	v_fma_f32 v176, v106, v68, v176
	v_fma_f32 v176, v107, v70, v176
	v_fma_f32 v177, v105, v65, v73
	v_fma_f32 v177, v106, v67, v177
	v_fma_f32 v177, v107, v68, v177
	v_fma_f32 v177, v108, v70, v177
	v_fma_f32 v178, v106, v65, v73
	v_fma_f32 v178, v107, v67, v178
	v_fma_f32 v178, v108, v68, v178
	v_fma_f32 v178, v109, v70, v178
	v_fma_f32 v179, v107, v65, v73
	v_fma_f32 v179, v108, v67, v179
	v_fma_f32 v179, v109, v68, v179
	v_fma_f32 v179, v110, v70, v179
	v_fma_f32 v180, v108, v65, v73
	v_fma_f32 v180, v109, v67, v180
	v_fma_f32 v180, v110, v68, v180
	v_fma_f32 v180, v111, v70, v180
	v_fma_f32 v181, v109, v65, v73
	v_fma_f32 v181, v110, v67, v181
	v_fma_f32 v181, v111, v68, v181
	v_fma_f32 v181, v112, v70, v181
	v_fma_f32 v182, v110, v65, v73
	v_fma_f32 v182, v111, v67, v182
	v_fma_f32 v182, v112, v68, v182
	v_fma_f32 v182, v113, v70, v182
	v_fma_f32 v183, v111, v65, v73
	v_fma_f32 v183, v112, v67, v183
	v_fma_f32 v183, v113, v68, v183
	v_fma_f32 v183, v114, v70, v183
	v_fma_f32 v184, v112, v65, v73
	v_fma_f32 v184, v113, v67, v184
	v_fma_f32 v184, v114, v68, v184
	v_fma_f32 v184, v115, v70, v184
	v_fma_f32 v185, v113, v65, v73
	v_fma_f32 v185, v114, v67, v185
	v_fma_f32 v185, v115, v68, v185
	v_fma_f32 v185, v116, v70, v185
	v_fma_f32 v186, v114, v65, v73
	v_fma_f32 v186, v115, v67, v186
	v_fma_f32 v186, v116, v68, v186
	v_fma_f32 v186, v117, v70, v186
	v_fma_f32 v187, v115, v65, v73
	v_fma_f32 v187, v116, v67, v187
	v_fma_f32 v187, v117, v68, v187
	v_fma_f32 v187, v118, v70, v187
	v_fma_f32 v188, v116, v65, v73
	v_fma_f32 v188, v117, v67, v188
	v_fma_f32 v188, v118, v68, v188
	v_fma_f32 v188, v119, v70, v188
	v_fma_f32 v189, v117, v65, v73
	v_fma_f32 v189, v118, v67, v189
	v_fma_f32 v189, v119, v68, v189
	v_fma_f32 v189, v120, v70, v189
	v_fma_f32 v190, v118, v65, v73
	v_fma_f32 v190, v119, v67, v190
	v_fma_f32 v190, v120, v68, v190
	v_fma_f32 v190, v121, v70, v190
	v_fma_f32 v191, v119, v65, v73
	v_fma_f32 v191, v120, v67, v191
	v_fma_f32 v191, v121, v68, v191
	v_fma_f32 v191, v122, v70, v191
	v_fma_f32 v192, v120, v65, v73
	v_fma_f32 v192, v121, v67, v192
	v_fma_f32 v192, v122, v68, v192
	v_fma_f32 v192, v123, v70, v192
	v_fma_f32 v193, v121, v65, v73
	v_fma_f32 v193, v122, v67, v193
	v_fma_f32 v193, v123, v68, v193
	v_fma_f32 v193, v124, v70, v193
	v_cvt_pk_bf16_f32 v162, v162, v162
	v_cvt_pk_bf16_f32 v163, v163, v163
	v_cvt_pk_bf16_f32 v164, v164, v164
	v_cvt_pk_bf16_f32 v165, v165, v165
	v_cvt_pk_bf16_f32 v166, v166, v166
	v_cvt_pk_bf16_f32 v167, v167, v167
; __device__ __forceinline__ void lru_tile(const Params& P, int chunk, int head, int pass, char* smem_raw) {
;     ...
;       sm_uc[(q * 32 + i) * LDSS + ch] = f2bf(v);
;     ...
; #pragma unroll
;       for (int s = 0; s < 2; ++s) {
;         const bf16x8 af = *reinterpret_cast<const bf16x8*>(&sm_uc[(sb * 64 + wid * 16 + (lane & 15)) * LDSS + s * 32 + (lane >> 4) * 8]);
; #pragma unroll
;         for (int t = 0; t < 8; ++t) {
;           const bf16x8 bfr = *reinterpret_cast<const bf16x8*>(&sm_w[(t * 16 + (lane & 15)) * LDSS + s * 32 + (lane >> 4) * 8]);
;           acc[t] = __builtin_amdgcn_mfma_f32_16x16x32_bf16(af, bfr, acc[t], 0, 0, 0);
;         }
;       }
	v_cvt_pk_bf16_f32 v168, v168, v168
	v_cvt_pk_bf16_f32 v169, v169, v169
	v_cvt_pk_bf16_f32 v170, v170, v170
	v_cvt_pk_bf16_f32 v171, v171, v171
	v_cvt_pk_bf16_f32 v172, v172, v172
	v_cvt_pk_bf16_f32 v173, v173, v173
	v_cvt_pk_bf16_f32 v174, v174, v174
	v_cvt_pk_bf16_f32 v175, v175, v175
	v_cvt_pk_bf16_f32 v176, v176, v176
	v_cvt_pk_bf16_f32 v177, v177, v177
	v_cvt_pk_bf16_f32 v178, v178, v178
	v_cvt_pk_bf16_f32 v179, v179, v179
	v_cvt_pk_bf16_f32 v180, v180, v180
	v_cvt_pk_bf16_f32 v181, v181, v181
	v_cvt_pk_bf16_f32 v182, v182, v182
	v_cvt_pk_bf16_f32 v183, v183, v183
	v_cvt_pk_bf16_f32 v184, v184, v184
	v_cvt_pk_bf16_f32 v185, v185, v185
	v_cvt_pk_bf16_f32 v186, v186, v186
	v_cvt_pk_bf16_f32 v187, v187, v187
	v_cvt_pk_bf16_f32 v188, v188, v188
	v_cvt_pk_bf16_f32 v189, v189, v189
	v_cvt_pk_bf16_f32 v190, v190, v190
	v_cvt_pk_bf16_f32 v191, v191, v191
	v_cvt_pk_bf16_f32 v192, v192, v192
	v_cvt_pk_bf16_f32 v193, v193, v193
	ds_write_b16 v89, v162 offset:0
	ds_write_b16 v89, v163 offset:128
	ds_write_b16 v130, v164 offset:256
	ds_write_b16 v130, v165 offset:384
	ds_write_b16 v89, v166 offset:512
	ds_write_b16 v89, v167 offset:640
	ds_write_b16 v130, v168 offset:768
	ds_write_b16 v130, v169 offset:896
	ds_write_b16 v89, v170 offset:1024
	ds_write_b16 v89, v171 offset:1152
	ds_write_b16 v130, v172 offset:1280
	ds_write_b16 v130, v173 offset:1408
	ds_write_b16 v89, v174 offset:1536
	ds_write_b16 v89, v175 offset:1664
	ds_write_b16 v130, v176 offset:1792
	ds_write_b16 v130, v177 offset:1920
	ds_write_b16 v89, v178 offset:2048
	ds_write_b16 v89, v179 offset:2176
	ds_write_b16 v130, v180 offset:2304
	ds_write_b16 v130, v181 offset:2432
	ds_write_b16 v89, v182 offset:2560
	ds_write_b16 v89, v183 offset:2688
	ds_write_b16 v130, v184 offset:2816
	ds_write_b16 v130, v185 offset:2944
	ds_write_b16 v89, v186 offset:3072
	ds_write_b16 v89, v187 offset:3200
	ds_write_b16 v130, v188 offset:3328
	ds_write_b16 v130, v189 offset:3456
	ds_write_b16 v89, v190 offset:3584
	ds_write_b16 v89, v191 offset:3712
	ds_write_b16 v130, v192 offset:3840
	ds_write_b16 v130, v193 offset:3968
	v_lshlrev_b32_e32 v162, 16, v162
	v_lshlrev_b32_e32 v163, 16, v163
	v_lshlrev_b32_e32 v164, 16, v164
	v_lshlrev_b32_e32 v165, 16, v165
	v_lshlrev_b32_e32 v166, 16, v166
	v_lshlrev_b32_e32 v167, 16, v167
	v_lshlrev_b32_e32 v168, 16, v168
	v_lshlrev_b32_e32 v169, 16, v169
	v_lshlrev_b32_e32 v170, 16, v170
	v_lshlrev_b32_e32 v171, 16, v171
	v_lshlrev_b32_e32 v172, 16, v172
	v_lshlrev_b32_e32 v173, 16, v173
	v_lshlrev_b32_e32 v174, 16, v174
	v_lshlrev_b32_e32 v175, 16, v175
	v_lshlrev_b32_e32 v176, 16, v176
	v_lshlrev_b32_e32 v177, 16, v177
	v_lshlrev_b32_e32 v178, 16, v178
	v_lshlrev_b32_e32 v179, 16, v179
	v_lshlrev_b32_e32 v180, 16, v180
	v_lshlrev_b32_e32 v181, 16, v181
	v_lshlrev_b32_e32 v182, 16, v182
	v_lshlrev_b32_e32 v183, 16, v183
	v_lshlrev_b32_e32 v184, 16, v184
	v_lshlrev_b32_e32 v185, 16, v185
	v_lshlrev_b32_e32 v186, 16, v186
	v_lshlrev_b32_e32 v187, 16, v187
	v_lshlrev_b32_e32 v188, 16, v188
	v_lshlrev_b32_e32 v189, 16, v189
	v_lshlrev_b32_e32 v190, 16, v190
	v_lshlrev_b32_e32 v191, 16, v191
	v_lshlrev_b32_e32 v192, 16, v192
	v_lshlrev_b32_e32 v193, 16, v193
	s_waitcnt lgkmcnt(0)
	s_barrier
	ds_read_b128 v[76:79], v131 offset:0
	ds_read_b128 v[80:83], v133 offset:0
	ds_read_b128 v[122:125], v131 offset:512
	ds_read_b128 v[126:129], v133 offset:512
	s_waitcnt lgkmcnt(3)
	v_mfma_f32_16x16x32_bf16 v[0:3], v[76:79], v[238:241], 0
	v_mfma_f32_16x16x32_bf16 v[90:93], v[76:79], v[246:249], 0
	ds_read_b128 v[76:79], v131 offset:1024
	s_waitcnt lgkmcnt(3)
	v_mfma_f32_16x16x32_bf16 v[0:3], v[80:83], v[242:245], v[0:3]
	v_mfma_f32_16x16x32_bf16 v[90:93], v[80:83], v[194:197], v[90:93]
	ds_read_b128 v[80:83], v133 offset:1024
	s_waitcnt lgkmcnt(3)
	v_mfma_f32_16x16x32_bf16 v[4:7], v[122:125], v[238:241], 0
	v_mfma_f32_16x16x32_bf16 v[94:97], v[122:125], v[246:249], 0
	ds_read_b128 v[122:125], v131 offset:1536
	s_waitcnt lgkmcnt(3)
	v_mfma_f32_16x16x32_bf16 v[4:7], v[126:129], v[242:245], v[4:7]
	v_mfma_f32_16x16x32_bf16 v[94:97], v[126:129], v[194:197], v[94:97]
	ds_read_b128 v[126:129], v133 offset:1536
	s_waitcnt lgkmcnt(3)
	v_mfma_f32_16x16x32_bf16 v[8:11], v[76:79], v[238:241], 0
	v_mfma_f32_16x16x32_bf16 v[98:101], v[76:79], v[246:249], 0
	ds_read_b128 v[76:79], v131 offset:2048
	s_waitcnt lgkmcnt(3)
	v_mfma_f32_16x16x32_bf16 v[8:11], v[80:83], v[242:245], v[8:11]
	v_mfma_f32_16x16x32_bf16 v[98:101], v[80:83], v[194:197], v[98:101]
	ds_read_b128 v[80:83], v133 offset:2048
	s_waitcnt lgkmcnt(3)
	v_mfma_f32_16x16x32_bf16 v[12:15], v[122:125], v[238:241], 0
	v_mfma_f32_16x16x32_bf16 v[102:105], v[122:125], v[246:249], 0
	ds_read_b128 v[122:125], v131 offset:2560
	s_waitcnt lgkmcnt(3)
	v_mfma_f32_16x16x32_bf16 v[12:15], v[126:129], v[242:245], v[12:15]
	v_mfma_f32_16x16x32_bf16 v[102:105], v[126:129], v[194:197], v[102:105]
	ds_read_b128 v[126:129], v133 offset:2560
	s_waitcnt lgkmcnt(3)
	v_mfma_f32_16x16x32_bf16 v[16:19], v[76:79], v[238:241], 0
	v_mfma_f32_16x16x32_bf16 v[106:109], v[76:79], v[246:249], 0
	ds_read_b128 v[76:79], v131 offset:3072
	s_waitcnt lgkmcnt(3)
	v_mfma_f32_16x16x32_bf16 v[16:19], v[80:83], v[242:245], v[16:19]
	v_mfma_f32_16x16x32_bf16 v[106:109], v[80:83], v[194:197], v[106:109]
	ds_read_b128 v[80:83], v133 offset:3072
	s_waitcnt lgkmcnt(3)
	v_mfma_f32_16x16x32_bf16 v[20:23], v[122:125], v[238:241], 0
	v_mfma_f32_16x16x32_bf16 v[110:113], v[122:125], v[246:249], 0
	ds_read_b128 v[122:125], v131 offset:3584
	s_waitcnt lgkmcnt(3)
	v_mfma_f32_16x16x32_bf16 v[20:23], v[126:129], v[242:245], v[20:23]
	v_mfma_f32_16x16x32_bf16 v[110:113], v[126:129], v[194:197], v[110:113]
	ds_read_b128 v[126:129], v133 offset:3584
	s_waitcnt lgkmcnt(3)
; __device__ __forceinline__ float bf2f(u16 h) { return __uint_as_float(((unsigned)h) << 16); }
; __device__ __forceinline__ void lru_tile(const Params& P, int chunk, int head, int pass, char* smem_raw) {
;     ...
;       *reinterpret_cast<uint4*>(&sm_w[rowi * LDSS + kg * 8]) = ldg16(P.wg + ((long)(d * 8 + head) * 128 + rowi) * 64 + kg * 8);
;     }
;     float ba[4], bi[4], c8[4];
; #pragma unroll
;     for (int tc = 0; tc < 4; ++tc) {
;       const int cidx = d * 512 + head * 64 + 16 * tc + (lane & 15);
;       ba[tc] = P.b_a[cidx] * -1.4426950408889634f; bi[tc] = P.b_i[cidx] * -1.4426950408889634f;
;       const float nl = -P.lam[cidx];
;       const float e_ = __expf(nl);
;       const float sp = (nl > 20.f) ? nl
;                      : (e_ < 0.03f ? e_ * (1.f - e_ * (0.5f - e_ * (0.33333334f - 0.25f * e_))) : __logf(1.f + e_));
;       c8[tc] = 8.f * 1.4426950408889634f * sp;
;     ...
;           const float r = __builtin_amdgcn_rcpf(1.f + __builtin_amdgcn_exp2f(acc[tc][reg] + ba[tc]));
;           const float ii = __builtin_amdgcn_rcpf(1.f + __builtin_amdgcn_exp2f(acc[tc + 4][reg] + bi[tc]));
;           const float la = -c8[tc] * r;
;           const float a = __builtin_amdgcn_exp2f(la);
;           const float ucv = bf2f(sm_uc[(sb * 64 + tl) * LDSS + c]);
;           const float bt = __builtin_amdgcn_sqrtf(fmaxf(1.f - a * a, 0.f)) * (ii * ucv);
	v_mfma_f32_16x16x32_bf16 v[24:27], v[76:79], v[238:241], 0
	v_mfma_f32_16x16x32_bf16 v[114:117], v[76:79], v[246:249], 0
	s_waitcnt lgkmcnt(2)
	v_mfma_f32_16x16x32_bf16 v[24:27], v[80:83], v[242:245], v[24:27]
	v_mfma_f32_16x16x32_bf16 v[114:117], v[80:83], v[194:197], v[114:117]
	s_waitcnt lgkmcnt(1)
	v_mfma_f32_16x16x32_bf16 v[28:31], v[122:125], v[238:241], 0
	v_mfma_f32_16x16x32_bf16 v[118:121], v[122:125], v[246:249], 0
	s_waitcnt lgkmcnt(0)
	v_mfma_f32_16x16x32_bf16 v[28:31], v[126:129], v[242:245], v[28:31]
	v_mfma_f32_16x16x32_bf16 v[118:121], v[126:129], v[194:197], v[118:121]
	s_lshl_b32 s0, s56, 8
	s_add_u32 s0, s0, 0x20000
	s_add_u32 s4, s20, s0
	s_addc_u32 s5, s21, 0
	global_load_dwordx4 v[238:241], v251, s[4:5]
	global_load_dwordx4 v[242:245], v251, s[4:5] offset:64
	s_add_u32 s4, s4, 0x2000
	s_addc_u32 s5, s5, 0
	global_load_dwordx4 v[246:249], v251, s[4:5]
	global_load_dwordx4 v[194:197], v251, s[4:5] offset:64
	v_bfe_u32 v255, v152, 6, 2
	v_and_b32_e32 v253, 15, v152
	v_lshl_add_u32 v255, v255, 4, v253
	v_add_u32_e32 v255, s56, v255
	v_lshlrev_b32_e32 v255, 2, v255
	s_add_u32 s0, s28, 0x800
	s_addc_u32 s1, s29, 0
	global_load_dword v68, v255, s[0:1]
	s_add_u32 s0, s30, 0x800
	s_addc_u32 s1, s31, 0
	global_load_dword v70, v255, s[0:1]
	s_add_u32 s0, s36, 0x800
	s_addc_u32 s1, s37, 0
	global_load_dword v73, v255, s[0:1]
	v_mul_f32_e32 v75, 0xbfb8aa3b, v75
	v_mul_f32_e32 v84, 0xbfb8aa3b, v84
	v_sub_f32_e32 v138, 0, v85
	v_mul_f32_e32 v139, 0x3fb8aa3b, v138
	v_exp_f32_e32 v139, v139
	v_mul_f32_e32 v140, 0xbe800000, v139
	v_add_f32_e32 v140, 0x3eaaaaab, v140
	v_fma_f32 v140, -v139, v140, 0.5
	v_fma_f32 v140, -v139, v140, 1.0
	v_mul_f32_e32 v140, v139, v140
	v_add_f32_e32 v141, 1.0, v139
	v_log_f32_e32 v141, v141
	v_mov_b32_e32 v255, 0x3cf5c28f
	v_mul_f32_e32 v141, 0x3f317218, v141
	v_cmp_gt_f32_e32 vcc, v255, v139
	s_nop 1
	v_cndmask_b32_e32 v140, v141, v140, vcc
	v_mov_b32_e32 v255, 0x41a00000
	v_cmp_lt_f32_e32 vcc, v255, v138
	s_nop 1
	v_cndmask_b32_e32 v140, v140, v138, vcc
	v_mul_f32_e32 v85, 0xc138aa3b, v140
	s_nop 7
	v_add_f32_e32 v0, v0, v75
	v_add_f32_e32 v1, v1, v75
	v_add_f32_e32 v2, v2, v75
	v_add_f32_e32 v3, v3, v75
	v_add_f32_e32 v90, v90, v84
	v_add_f32_e32 v91, v91, v84
	v_add_f32_e32 v92, v92, v84
	v_add_f32_e32 v93, v93, v84
	v_exp_f32_e32 v0, v0
	v_exp_f32_e32 v1, v1
	v_exp_f32_e32 v2, v2
	v_exp_f32_e32 v3, v3
	v_exp_f32_e32 v90, v90
	v_exp_f32_e32 v91, v91
	v_exp_f32_e32 v92, v92
	v_exp_f32_e32 v93, v93
	v_add_f32_e32 v0, 1.0, v0
	v_add_f32_e32 v1, 1.0, v1
	v_add_f32_e32 v2, 1.0, v2
	v_add_f32_e32 v3, 1.0, v3
	v_add_f32_e32 v90, 1.0, v90
	v_add_f32_e32 v91, 1.0, v91
	v_add_f32_e32 v92, 1.0, v92
	v_add_f32_e32 v93, 1.0, v93
	v_rcp_f32_e32 v0, v0
	v_rcp_f32_e32 v1, v1
	v_rcp_f32_e32 v2, v2
	v_rcp_f32_e32 v3, v3
	v_rcp_f32_e32 v90, v90
	v_rcp_f32_e32 v91, v91
	v_rcp_f32_e32 v92, v92
	v_rcp_f32_e32 v93, v93
	v_mul_f32_e32 v0, v85, v0
	v_mul_f32_e32 v1, v85, v1
	v_mul_f32_e32 v2, v85, v2
	v_mul_f32_e32 v3, v85, v3
	v_mul_f32_e32 v90, v90, v162
	v_mul_f32_e32 v91, v91, v163
	v_mul_f32_e32 v92, v92, v164
	v_mul_f32_e32 v93, v93, v165
	v_exp_f32_e32 v0, v0
	v_exp_f32_e32 v1, v1
	v_exp_f32_e32 v2, v2
	v_exp_f32_e32 v3, v3
	s_nop 0
	v_fma_f32 v138, -v0, v0, 1.0
	v_fma_f32 v139, -v1, v1, 1.0
	v_fma_f32 v140, -v2, v2, 1.0
	v_fma_f32 v141, -v3, v3, 1.0
	v_max_f32_e32 v138, 0, v138
	v_max_f32_e32 v139, 0, v139
	v_max_f32_e32 v140, 0, v140
	v_max_f32_e32 v141, 0, v141
	v_sqrt_f32_e32 v138, v138
	v_sqrt_f32_e32 v139, v139
	v_sqrt_f32_e32 v140, v140
	v_sqrt_f32_e32 v141, v141
	s_nop 0
	v_mul_f32_e32 v90, v138, v90
	v_mul_f32_e32 v91, v139, v91
	v_mul_f32_e32 v92, v140, v92
	v_mul_f32_e32 v93, v141, v93
	v_add_f32_e32 v4, v4, v75
	v_add_f32_e32 v5, v5, v75
	v_add_f32_e32 v6, v6, v75
	v_add_f32_e32 v7, v7, v75
	v_add_f32_e32 v94, v94, v84
	v_add_f32_e32 v95, v95, v84
	v_add_f32_e32 v96, v96, v84
	v_add_f32_e32 v97, v97, v84
	v_exp_f32_e32 v4, v4
	v_exp_f32_e32 v5, v5
	v_exp_f32_e32 v6, v6
	v_exp_f32_e32 v7, v7
	v_exp_f32_e32 v94, v94
	v_exp_f32_e32 v95, v95
	v_exp_f32_e32 v96, v96
	v_exp_f32_e32 v97, v97
	v_add_f32_e32 v4, 1.0, v4
	v_add_f32_e32 v5, 1.0, v5
	v_add_f32_e32 v6, 1.0, v6
	v_add_f32_e32 v7, 1.0, v7
	v_add_f32_e32 v94, 1.0, v94
	v_add_f32_e32 v95, 1.0, v95
	v_add_f32_e32 v96, 1.0, v96
	v_add_f32_e32 v97, 1.0, v97
	v_rcp_f32_e32 v4, v4
	v_rcp_f32_e32 v5, v5
	v_rcp_f32_e32 v6, v6
	v_rcp_f32_e32 v7, v7
	v_rcp_f32_e32 v94, v94
	v_rcp_f32_e32 v95, v95
	v_rcp_f32_e32 v96, v96
	v_rcp_f32_e32 v97, v97
	v_mul_f32_e32 v4, v85, v4
	v_mul_f32_e32 v5, v85, v5
	v_mul_f32_e32 v6, v85, v6
	v_mul_f32_e32 v7, v85, v7
	v_mul_f32_e32 v94, v94, v166
	v_mul_f32_e32 v95, v95, v167
	v_mul_f32_e32 v96, v96, v168
	v_mul_f32_e32 v97, v97, v169
	v_exp_f32_e32 v4, v4
	v_exp_f32_e32 v5, v5
	v_exp_f32_e32 v6, v6
	v_exp_f32_e32 v7, v7
	s_nop 0
	v_fma_f32 v138, -v4, v4, 1.0
	v_fma_f32 v139, -v5, v5, 1.0
	v_fma_f32 v140, -v6, v6, 1.0
	v_fma_f32 v141, -v7, v7, 1.0
	v_max_f32_e32 v138, 0, v138
	v_max_f32_e32 v139, 0, v139
	v_max_f32_e32 v140, 0, v140
	v_max_f32_e32 v141, 0, v141
	v_sqrt_f32_e32 v138, v138
	v_sqrt_f32_e32 v139, v139
	v_sqrt_f32_e32 v140, v140
	v_sqrt_f32_e32 v141, v141
	s_nop 0
	v_mul_f32_e32 v94, v138, v94
	v_mul_f32_e32 v95, v139, v95
	v_mul_f32_e32 v96, v140, v96
	v_mul_f32_e32 v97, v141, v97
	v_add_f32_e32 v8, v8, v75
	v_add_f32_e32 v9, v9, v75
	v_add_f32_e32 v10, v10, v75
	v_add_f32_e32 v11, v11, v75
	v_add_f32_e32 v98, v98, v84
	v_add_f32_e32 v99, v99, v84
	v_add_f32_e32 v100, v100, v84
	v_add_f32_e32 v101, v101, v84
	v_exp_f32_e32 v8, v8
	v_exp_f32_e32 v9, v9
	v_exp_f32_e32 v10, v10
	v_exp_f32_e32 v11, v11
	v_exp_f32_e32 v98, v98
; __device__ __forceinline__ float bf2f(u16 h) { return __uint_as_float(((unsigned)h) << 16); }
; __device__ __forceinline__ void lru_tile(const Params& P, int chunk, int head, int pass, char* smem_raw) {
;     ...
;           const float r = __builtin_amdgcn_rcpf(1.f + __builtin_amdgcn_exp2f(acc[tc][reg] + ba[tc]));
;           const float ii = __builtin_amdgcn_rcpf(1.f + __builtin_amdgcn_exp2f(acc[tc + 4][reg] + bi[tc]));
;           const float la = -c8[tc] * r;
;           const float a = __builtin_amdgcn_exp2f(la);
;           const float ucv = bf2f(sm_uc[(sb * 64 + tl) * LDSS + c]);
;           const float bt = __builtin_amdgcn_sqrtf(fmaxf(1.f - a * a, 0.f)) * (ii * ucv);
	v_exp_f32_e32 v99, v99
	v_exp_f32_e32 v100, v100
	v_exp_f32_e32 v101, v101
	v_add_f32_e32 v8, 1.0, v8
	v_add_f32_e32 v9, 1.0, v9
	v_add_f32_e32 v10, 1.0, v10
	v_add_f32_e32 v11, 1.0, v11
	v_add_f32_e32 v98, 1.0, v98
	v_add_f32_e32 v99, 1.0, v99
	v_add_f32_e32 v100, 1.0, v100
	v_add_f32_e32 v101, 1.0, v101
	v_rcp_f32_e32 v8, v8
	v_rcp_f32_e32 v9, v9
	v_rcp_f32_e32 v10, v10
	v_rcp_f32_e32 v11, v11
	v_rcp_f32_e32 v98, v98
	v_rcp_f32_e32 v99, v99
	v_rcp_f32_e32 v100, v100
	v_rcp_f32_e32 v101, v101
	v_mul_f32_e32 v8, v85, v8
	v_mul_f32_e32 v9, v85, v9
	v_mul_f32_e32 v10, v85, v10
	v_mul_f32_e32 v11, v85, v11
	v_mul_f32_e32 v98, v98, v170
	v_mul_f32_e32 v99, v99, v171
	v_mul_f32_e32 v100, v100, v172
	v_mul_f32_e32 v101, v101, v173
	v_exp_f32_e32 v8, v8
	v_exp_f32_e32 v9, v9
	v_exp_f32_e32 v10, v10
	v_exp_f32_e32 v11, v11
	s_nop 0
	v_fma_f32 v138, -v8, v8, 1.0
	v_fma_f32 v139, -v9, v9, 1.0
	v_fma_f32 v140, -v10, v10, 1.0
	v_fma_f32 v141, -v11, v11, 1.0
	v_max_f32_e32 v138, 0, v138
	v_max_f32_e32 v139, 0, v139
	v_max_f32_e32 v140, 0, v140
	v_max_f32_e32 v141, 0, v141
	v_sqrt_f32_e32 v138, v138
	v_sqrt_f32_e32 v139, v139
	v_sqrt_f32_e32 v140, v140
	v_sqrt_f32_e32 v141, v141
	s_nop 0
	v_mul_f32_e32 v98, v138, v98
	v_mul_f32_e32 v99, v139, v99
	v_mul_f32_e32 v100, v140, v100
	v_mul_f32_e32 v101, v141, v101
	v_add_f32_e32 v12, v12, v75
	v_add_f32_e32 v13, v13, v75
	v_add_f32_e32 v14, v14, v75
	v_add_f32_e32 v15, v15, v75
	v_add_f32_e32 v102, v102, v84
	v_add_f32_e32 v103, v103, v84
	v_add_f32_e32 v104, v104, v84
	v_add_f32_e32 v105, v105, v84
	v_exp_f32_e32 v12, v12
	v_exp_f32_e32 v13, v13
	v_exp_f32_e32 v14, v14
	v_exp_f32_e32 v15, v15
	v_exp_f32_e32 v102, v102
	v_exp_f32_e32 v103, v103
	v_exp_f32_e32 v104, v104
	v_exp_f32_e32 v105, v105
	v_add_f32_e32 v12, 1.0, v12
	v_add_f32_e32 v13, 1.0, v13
	v_add_f32_e32 v14, 1.0, v14
	v_add_f32_e32 v15, 1.0, v15
	v_add_f32_e32 v102, 1.0, v102
	v_add_f32_e32 v103, 1.0, v103
	v_add_f32_e32 v104, 1.0, v104
	v_add_f32_e32 v105, 1.0, v105
	v_rcp_f32_e32 v12, v12
	v_rcp_f32_e32 v13, v13
	v_rcp_f32_e32 v14, v14
	v_rcp_f32_e32 v15, v15
	v_rcp_f32_e32 v102, v102
	v_rcp_f32_e32 v103, v103
	v_rcp_f32_e32 v104, v104
	v_rcp_f32_e32 v105, v105
	v_mul_f32_e32 v12, v85, v12
	v_mul_f32_e32 v13, v85, v13
	v_mul_f32_e32 v14, v85, v14
	v_mul_f32_e32 v15, v85, v15
	v_mul_f32_e32 v102, v102, v174
	v_mul_f32_e32 v103, v103, v175
	v_mul_f32_e32 v104, v104, v176
	v_mul_f32_e32 v105, v105, v177
	v_exp_f32_e32 v12, v12
	v_exp_f32_e32 v13, v13
	v_exp_f32_e32 v14, v14
	v_exp_f32_e32 v15, v15
	s_nop 0
	v_fma_f32 v138, -v12, v12, 1.0
	v_fma_f32 v139, -v13, v13, 1.0
	v_fma_f32 v140, -v14, v14, 1.0
	v_fma_f32 v141, -v15, v15, 1.0
	v_max_f32_e32 v138, 0, v138
	v_max_f32_e32 v139, 0, v139
	v_max_f32_e32 v140, 0, v140
	v_max_f32_e32 v141, 0, v141
	v_sqrt_f32_e32 v138, v138
	v_sqrt_f32_e32 v139, v139
	v_sqrt_f32_e32 v140, v140
	v_sqrt_f32_e32 v141, v141
	s_nop 0
	v_mul_f32_e32 v102, v138, v102
	v_mul_f32_e32 v103, v139, v103
	v_mul_f32_e32 v104, v140, v104
	v_mul_f32_e32 v105, v141, v105
	v_add_f32_e32 v16, v16, v75
	v_add_f32_e32 v17, v17, v75
	v_add_f32_e32 v18, v18, v75
	v_add_f32_e32 v19, v19, v75
	v_add_f32_e32 v106, v106, v84
	v_add_f32_e32 v107, v107, v84
	v_add_f32_e32 v108, v108, v84
	v_add_f32_e32 v109, v109, v84
	v_exp_f32_e32 v16, v16
	v_exp_f32_e32 v17, v17
	v_exp_f32_e32 v18, v18
	v_exp_f32_e32 v19, v19
	v_exp_f32_e32 v106, v106
	v_exp_f32_e32 v107, v107
	v_exp_f32_e32 v108, v108
	v_exp_f32_e32 v109, v109
	v_add_f32_e32 v16, 1.0, v16
	v_add_f32_e32 v17, 1.0, v17
	v_add_f32_e32 v18, 1.0, v18
	v_add_f32_e32 v19, 1.0, v19
	v_add_f32_e32 v106, 1.0, v106
	v_add_f32_e32 v107, 1.0, v107
	v_add_f32_e32 v108, 1.0, v108
	v_add_f32_e32 v109, 1.0, v109
	v_rcp_f32_e32 v16, v16
	v_rcp_f32_e32 v17, v17
	v_rcp_f32_e32 v18, v18
	v_rcp_f32_e32 v19, v19
	v_rcp_f32_e32 v106, v106
	v_rcp_f32_e32 v107, v107
	v_rcp_f32_e32 v108, v108
	v_rcp_f32_e32 v109, v109
	v_mul_f32_e32 v16, v85, v16
	v_mul_f32_e32 v17, v85, v17
	v_mul_f32_e32 v18, v85, v18
	v_mul_f32_e32 v19, v85, v19
	v_mul_f32_e32 v106, v106, v178
	v_mul_f32_e32 v107, v107, v179
	v_mul_f32_e32 v108, v108, v180
	v_mul_f32_e32 v109, v109, v181
	v_exp_f32_e32 v16, v16
	v_exp_f32_e32 v17, v17
	v_exp_f32_e32 v18, v18
	v_exp_f32_e32 v19, v19
	s_nop 0
	v_fma_f32 v138, -v16, v16, 1.0
	v_fma_f32 v139, -v17, v17, 1.0
	v_fma_f32 v140, -v18, v18, 1.0
	v_fma_f32 v141, -v19, v19, 1.0
	v_max_f32_e32 v138, 0, v138
	v_max_f32_e32 v139, 0, v139
	v_max_f32_e32 v140, 0, v140
	v_max_f32_e32 v141, 0, v141
	v_sqrt_f32_e32 v138, v138
	v_sqrt_f32_e32 v139, v139
	v_sqrt_f32_e32 v140, v140
	v_sqrt_f32_e32 v141, v141
	s_nop 0
	v_mul_f32_e32 v106, v138, v106
	v_mul_f32_e32 v107, v139, v107
	v_mul_f32_e32 v108, v140, v108
	v_mul_f32_e32 v109, v141, v109
	v_add_f32_e32 v20, v20, v75
	v_add_f32_e32 v21, v21, v75
	v_add_f32_e32 v22, v22, v75
	v_add_f32_e32 v23, v23, v75
	v_add_f32_e32 v110, v110, v84
	v_add_f32_e32 v111, v111, v84
	v_add_f32_e32 v112, v112, v84
	v_add_f32_e32 v113, v113, v84
	v_exp_f32_e32 v20, v20
	v_exp_f32_e32 v21, v21
	v_exp_f32_e32 v22, v22
	v_exp_f32_e32 v23, v23
	v_exp_f32_e32 v110, v110
	v_exp_f32_e32 v111, v111
	v_exp_f32_e32 v112, v112
	v_exp_f32_e32 v113, v113
	v_add_f32_e32 v20, 1.0, v20
	v_add_f32_e32 v21, 1.0, v21
	v_add_f32_e32 v22, 1.0, v22
	v_add_f32_e32 v23, 1.0, v23
	v_add_f32_e32 v110, 1.0, v110
	v_add_f32_e32 v111, 1.0, v111
	v_add_f32_e32 v112, 1.0, v112
	v_add_f32_e32 v113, 1.0, v113
	v_rcp_f32_e32 v20, v20
	v_rcp_f32_e32 v21, v21
	v_rcp_f32_e32 v22, v22
	v_rcp_f32_e32 v23, v23
	v_rcp_f32_e32 v110, v110
	v_rcp_f32_e32 v111, v111
	v_rcp_f32_e32 v112, v112
	v_rcp_f32_e32 v113, v113
; __device__ __forceinline__ float bf2f(u16 h) { return __uint_as_float(((unsigned)h) << 16); }
; __device__ __forceinline__ void lru_tile(const Params& P, int chunk, int head, int pass, char* smem_raw) {
;     ...
;           const float r = __builtin_amdgcn_rcpf(1.f + __builtin_amdgcn_exp2f(acc[tc][reg] + ba[tc]));
;           const float ii = __builtin_amdgcn_rcpf(1.f + __builtin_amdgcn_exp2f(acc[tc + 4][reg] + bi[tc]));
;           const float la = -c8[tc] * r;
;           const float a = __builtin_amdgcn_exp2f(la);
;           const float ucv = bf2f(sm_uc[(sb * 64 + tl) * LDSS + c]);
;           const float bt = __builtin_amdgcn_sqrtf(fmaxf(1.f - a * a, 0.f)) * (ii * ucv);
;           sm_a[tl * 64 + c] = a;
;           sm_b[tl * 64 + c] = bt;
;         }
;       __syncthreads();
;       const int pos = (d == 0) ? q : 3 - q;
;       {
;         float Pp = 1.f, H = 0.f;
; #pragma unroll 4
;         for (int i = 0; i < 16; ++i) {
;           const int tl = (d == 0) ? (q * 16 + i) : (q * 16 + 15 - i);
;           const float a = sm_a[tl * 64 + ch], b = sm_b[tl * 64 + ch];
;           H = a * H + b; Pp *= a;
	v_mul_f32_e32 v20, v85, v20
	v_mul_f32_e32 v21, v85, v21
	v_mul_f32_e32 v22, v85, v22
	v_mul_f32_e32 v23, v85, v23
	v_mul_f32_e32 v110, v110, v182
	v_mul_f32_e32 v111, v111, v183
	v_mul_f32_e32 v112, v112, v184
	v_mul_f32_e32 v113, v113, v185
	v_exp_f32_e32 v20, v20
	v_exp_f32_e32 v21, v21
	v_exp_f32_e32 v22, v22
	v_exp_f32_e32 v23, v23
	s_nop 0
	v_fma_f32 v138, -v20, v20, 1.0
	v_fma_f32 v139, -v21, v21, 1.0
	v_fma_f32 v140, -v22, v22, 1.0
	v_fma_f32 v141, -v23, v23, 1.0
	v_max_f32_e32 v138, 0, v138
	v_max_f32_e32 v139, 0, v139
	v_max_f32_e32 v140, 0, v140
	v_max_f32_e32 v141, 0, v141
	v_sqrt_f32_e32 v138, v138
	v_sqrt_f32_e32 v139, v139
	v_sqrt_f32_e32 v140, v140
	v_sqrt_f32_e32 v141, v141
	s_nop 0
	v_mul_f32_e32 v110, v138, v110
	v_mul_f32_e32 v111, v139, v111
	v_mul_f32_e32 v112, v140, v112
	v_mul_f32_e32 v113, v141, v113
	v_add_f32_e32 v24, v24, v75
	v_add_f32_e32 v25, v25, v75
	v_add_f32_e32 v26, v26, v75
	v_add_f32_e32 v27, v27, v75
	v_add_f32_e32 v114, v114, v84
	v_add_f32_e32 v115, v115, v84
	v_add_f32_e32 v116, v116, v84
	v_add_f32_e32 v117, v117, v84
	v_exp_f32_e32 v24, v24
	v_exp_f32_e32 v25, v25
	v_exp_f32_e32 v26, v26
	v_exp_f32_e32 v27, v27
	v_exp_f32_e32 v114, v114
	v_exp_f32_e32 v115, v115
	v_exp_f32_e32 v116, v116
	v_exp_f32_e32 v117, v117
	v_add_f32_e32 v24, 1.0, v24
	v_add_f32_e32 v25, 1.0, v25
	v_add_f32_e32 v26, 1.0, v26
	v_add_f32_e32 v27, 1.0, v27
	v_add_f32_e32 v114, 1.0, v114
	v_add_f32_e32 v115, 1.0, v115
	v_add_f32_e32 v116, 1.0, v116
	v_add_f32_e32 v117, 1.0, v117
	v_rcp_f32_e32 v24, v24
	v_rcp_f32_e32 v25, v25
	v_rcp_f32_e32 v26, v26
	v_rcp_f32_e32 v27, v27
	v_rcp_f32_e32 v114, v114
	v_rcp_f32_e32 v115, v115
	v_rcp_f32_e32 v116, v116
	v_rcp_f32_e32 v117, v117
	v_mul_f32_e32 v24, v85, v24
	v_mul_f32_e32 v25, v85, v25
	v_mul_f32_e32 v26, v85, v26
	v_mul_f32_e32 v27, v85, v27
	v_mul_f32_e32 v114, v114, v186
	v_mul_f32_e32 v115, v115, v187
	v_mul_f32_e32 v116, v116, v188
	v_mul_f32_e32 v117, v117, v189
	v_exp_f32_e32 v24, v24
	v_exp_f32_e32 v25, v25
	v_exp_f32_e32 v26, v26
	v_exp_f32_e32 v27, v27
	s_nop 0
	v_fma_f32 v138, -v24, v24, 1.0
	v_fma_f32 v139, -v25, v25, 1.0
	v_fma_f32 v140, -v26, v26, 1.0
	v_fma_f32 v141, -v27, v27, 1.0
	v_max_f32_e32 v138, 0, v138
	v_max_f32_e32 v139, 0, v139
	v_max_f32_e32 v140, 0, v140
	v_max_f32_e32 v141, 0, v141
	v_sqrt_f32_e32 v138, v138
	v_sqrt_f32_e32 v139, v139
	v_sqrt_f32_e32 v140, v140
	v_sqrt_f32_e32 v141, v141
	s_nop 0
	v_mul_f32_e32 v114, v138, v114
	v_mul_f32_e32 v115, v139, v115
	v_mul_f32_e32 v116, v140, v116
	v_mul_f32_e32 v117, v141, v117
	v_add_f32_e32 v28, v28, v75
	v_add_f32_e32 v29, v29, v75
	v_add_f32_e32 v30, v30, v75
	v_add_f32_e32 v31, v31, v75
	v_add_f32_e32 v118, v118, v84
	v_add_f32_e32 v119, v119, v84
	v_add_f32_e32 v120, v120, v84
	v_add_f32_e32 v121, v121, v84
	v_exp_f32_e32 v28, v28
	v_exp_f32_e32 v29, v29
	v_exp_f32_e32 v30, v30
	v_exp_f32_e32 v31, v31
	v_exp_f32_e32 v118, v118
	v_exp_f32_e32 v119, v119
	v_exp_f32_e32 v120, v120
	v_exp_f32_e32 v121, v121
	v_add_f32_e32 v28, 1.0, v28
	v_add_f32_e32 v29, 1.0, v29
	v_add_f32_e32 v30, 1.0, v30
	v_add_f32_e32 v31, 1.0, v31
	v_add_f32_e32 v118, 1.0, v118
	v_add_f32_e32 v119, 1.0, v119
	v_add_f32_e32 v120, 1.0, v120
	v_add_f32_e32 v121, 1.0, v121
	v_rcp_f32_e32 v28, v28
	v_rcp_f32_e32 v29, v29
	v_rcp_f32_e32 v30, v30
	v_rcp_f32_e32 v31, v31
	v_rcp_f32_e32 v118, v118
	v_rcp_f32_e32 v119, v119
	v_rcp_f32_e32 v120, v120
	v_rcp_f32_e32 v121, v121
	v_mul_f32_e32 v28, v85, v28
	v_mul_f32_e32 v29, v85, v29
	v_mul_f32_e32 v30, v85, v30
	v_mul_f32_e32 v31, v85, v31
	v_mul_f32_e32 v118, v118, v190
	v_mul_f32_e32 v119, v119, v191
	v_mul_f32_e32 v120, v120, v192
	v_mul_f32_e32 v121, v121, v193
	v_exp_f32_e32 v28, v28
	v_exp_f32_e32 v29, v29
	v_exp_f32_e32 v30, v30
	v_exp_f32_e32 v31, v31
	s_nop 0
	v_fma_f32 v138, -v28, v28, 1.0
	v_fma_f32 v139, -v29, v29, 1.0
	v_fma_f32 v140, -v30, v30, 1.0
	v_fma_f32 v141, -v31, v31, 1.0
	v_max_f32_e32 v138, 0, v138
	v_max_f32_e32 v139, 0, v139
	v_max_f32_e32 v140, 0, v140
	v_max_f32_e32 v141, 0, v141
	v_sqrt_f32_e32 v138, v138
	v_sqrt_f32_e32 v139, v139
	v_sqrt_f32_e32 v140, v140
	v_sqrt_f32_e32 v141, v141
	s_nop 0
	v_mul_f32_e32 v118, v138, v118
	v_mul_f32_e32 v119, v139, v119
	v_mul_f32_e32 v120, v140, v120
	v_mul_f32_e32 v121, v141, v121
	v_mov_b32_e32 v253, v0
	v_mov_b32_e32 v254, v90
	v_fma_f32 v254, v1, v254, v91
	v_mul_f32_e32 v253, v253, v1
	v_fma_f32 v254, v2, v254, v92
	v_mul_f32_e32 v253, v253, v2
	v_fma_f32 v254, v3, v254, v93
	v_mul_f32_e32 v253, v253, v3
	v_fma_f32 v254, v4, v254, v94
	v_mul_f32_e32 v253, v253, v4
	v_fma_f32 v254, v5, v254, v95
	v_mul_f32_e32 v253, v253, v5
	v_fma_f32 v254, v6, v254, v96
	v_mul_f32_e32 v253, v253, v6
	v_fma_f32 v254, v7, v254, v97
	v_mul_f32_e32 v253, v253, v7
	v_fma_f32 v254, v8, v254, v98
	v_mul_f32_e32 v253, v253, v8
	v_fma_f32 v254, v9, v254, v99
	v_mul_f32_e32 v253, v253, v9
	v_fma_f32 v254, v10, v254, v100
	v_mul_f32_e32 v253, v253, v10
	v_fma_f32 v254, v11, v254, v101
	v_mul_f32_e32 v253, v253, v11
	v_fma_f32 v254, v12, v254, v102
	v_mul_f32_e32 v253, v253, v12
	v_fma_f32 v254, v13, v254, v103
	v_mul_f32_e32 v253, v253, v13
	v_fma_f32 v254, v14, v254, v104
	v_mul_f32_e32 v253, v253, v14
	v_fma_f32 v254, v15, v254, v105
	v_mul_f32_e32 v253, v253, v15
	v_fma_f32 v254, v16, v254, v106
	v_mul_f32_e32 v253, v253, v16
	v_fma_f32 v254, v17, v254, v107
	v_mul_f32_e32 v253, v253, v17
	v_fma_f32 v254, v18, v254, v108
	v_mul_f32_e32 v253, v253, v18
	v_fma_f32 v254, v19, v254, v109
	v_mul_f32_e32 v253, v253, v19
	v_fma_f32 v254, v20, v254, v110
	v_mul_f32_e32 v253, v253, v20
	v_fma_f32 v254, v21, v254, v111
	v_mul_f32_e32 v253, v253, v21
; __device__ __forceinline__ void lru_tile(const Params& P, int chunk, int head, int pass, char* smem_raw) {
;     ...
; #pragma unroll
;       for (int s = 0; s < 2; ++s) {
;         const bf16x8 af = *reinterpret_cast<const bf16x8*>(&sm_uc[(sb * 64 + wid * 16 + (lane & 15)) * LDSS + s * 32 + (lane >> 4) * 8]);
; #pragma unroll
;         for (int t = 0; t < 8; ++t) {
;           const bf16x8 bfr = *reinterpret_cast<const bf16x8*>(&sm_w[(t * 16 + (lane & 15)) * LDSS + s * 32 + (lane >> 4) * 8]);
;           acc[t] = __builtin_amdgcn_mfma_f32_16x16x32_bf16(af, bfr, acc[t], 0, 0, 0);
;         }
;       }
;     ...
;       const float2 p0 = sm_ph[ch], p1 = sm_ph[64 + ch], p2 = sm_ph[128 + ch], p3 = sm_ph[192 + ch];
;       if (pass == 2) {
;         float hin = cB;
;         if (pos > 0) hin = p0.x * hin + p0.y;
;         if (pos > 1) hin = p1.x * hin + p1.y;
;         if (pos > 2) hin = p2.x * hin + p2.y;
;         float h = hin;
;         float hfp[16], gp[16];
;         if (d == 1) {
; #pragma unroll
;           for (int i = 0; i < 16; ++i) {
;             const long rowp = row0 + sb * 64 + q * 16 + 15 - i;
;             hfp[i] = hfbuf[rowp * 512 + gch];
;             gp[i] = bf2f(P.zq[rowp * 1536 + 512 + gch]);
;           }
;         }
; #pragma unroll
;         for (int i = 0; i < 16; ++i) {
;           const int tl = (d == 0) ? (q * 16 + i) : (q * 16 + 15 - i);
;           const float a = sm_a[tl * 64 + ch], b = sm_b[tl * 64 + ch];
;           h = a * h + b;
;           const long row = row0 + sb * 64 + tl;
;           if (d == 0) {
;             hfw[row * 512 + gch] = h;
;           } else {
;             const float hfv = hfp[i];
;             const float g = gp[i];
;             const float tz = 0.7978845608028654f * (g + 0.044715f * g * g * g);
;             const float th = 1.f - 2.f * __builtin_amdgcn_rcpf(1.f + __expf(2.f * tz));
;             const float ge = 0.5f * g * (1.f + th);
;             P.cat[row * 1024 + gch] = f2bf((hfv + h) * ge);
;           }
;         }
;       }
;       cB = p0.x * cB + p0.y; cA *= p0.x;
;       cB = p1.x * cB + p1.y; cA *= p1.x;
;       cB = p2.x * cB + p2.y; cA *= p2.x;
;       cB = p3.x * cB + p3.y; cA *= p3.x;
;       __syncthreads();
;     }
;     if (pass == 1 && q == 0) P.summ[((long)d * 264 + chunk) * 512 + gch] = make_float2(cA, cB);
	v_fma_f32 v254, v22, v254, v112
	v_mul_f32_e32 v253, v253, v22
	v_fma_f32 v254, v23, v254, v113
	v_mul_f32_e32 v253, v253, v23
	v_fma_f32 v254, v24, v254, v114
	v_mul_f32_e32 v253, v253, v24
	v_fma_f32 v254, v25, v254, v115
	v_mul_f32_e32 v253, v253, v25
	v_fma_f32 v254, v26, v254, v116
	v_mul_f32_e32 v253, v253, v26
	v_fma_f32 v254, v27, v254, v117
	v_mul_f32_e32 v253, v253, v27
	v_fma_f32 v254, v28, v254, v118
	v_mul_f32_e32 v253, v253, v28
	v_fma_f32 v254, v29, v254, v119
	v_mul_f32_e32 v253, v253, v29
	v_fma_f32 v254, v30, v254, v120
	v_mul_f32_e32 v253, v253, v30
	v_fma_f32 v254, v31, v254, v121
	v_mul_f32_e32 v253, v253, v31
	v_mov_b32_e32 v138, v253
	v_mov_b32_e32 v139, v253
	s_nop 1
	v_permlane16_swap_b32_e32 v138, v139
	v_mov_b32_e32 v140, v138
	v_mov_b32_e32 v141, v139
	s_nop 1
	v_permlane32_swap_b32_e32 v138, v140
	v_permlane32_swap_b32_e32 v139, v141
	v_mov_b32_e32 v198, v254
	v_mov_b32_e32 v199, v254
	s_nop 1
	v_permlane16_swap_b32_e32 v198, v199
	v_mov_b32_e32 v200, v198
	v_mov_b32_e32 v201, v199
	s_nop 1
	v_permlane32_swap_b32_e32 v198, v200
	v_permlane32_swap_b32_e32 v199, v201
	v_mov_b32_e32 v136, 0
	v_fma_f32 v150, v138, v136, v198
	v_fma_f32 v151, v139, v150, v199
	v_fma_f32 v202, v140, v151, v200
	v_fma_f32 v254, v141, v202, v201
	v_mul_f32_e32 v253, v138, v139
	v_mul_f32_e32 v253, v253, v140
	v_mul_f32_e32 v200, v253, v141
	v_mov_b32_e32 v201, v254
	s_add_u32 s0, s71, 0
	s_lshl_b32 s0, s0, 12
	s_lshl_b32 s1, s56, 3
	s_add_u32 s0, s0, s1
	s_add_u32 s4, s18, s0
	s_addc_u32 s5, s19, 0
	global_store_dwordx2 v250, v[200:201], s[4:5]
	ds_read_b128 v[76:79], v131 offset:0
	ds_read_b128 v[80:83], v133 offset:0
	ds_read_b128 v[122:125], v131 offset:512
	ds_read_b128 v[126:129], v133 offset:512
	s_waitcnt vmcnt(0)
	s_waitcnt lgkmcnt(3)
	v_mfma_f32_16x16x32_bf16 v[0:3], v[76:79], v[238:241], 0
	v_mfma_f32_16x16x32_bf16 v[90:93], v[76:79], v[246:249], 0
	ds_read_b128 v[76:79], v131 offset:1024
	s_waitcnt lgkmcnt(3)
	v_mfma_f32_16x16x32_bf16 v[0:3], v[80:83], v[242:245], v[0:3]
	v_mfma_f32_16x16x32_bf16 v[90:93], v[80:83], v[194:197], v[90:93]
	ds_read_b128 v[80:83], v133 offset:1024
	s_waitcnt lgkmcnt(3)
	v_mfma_f32_16x16x32_bf16 v[4:7], v[122:125], v[238:241], 0
	v_mfma_f32_16x16x32_bf16 v[94:97], v[122:125], v[246:249], 0
	ds_read_b128 v[122:125], v131 offset:1536
	s_waitcnt lgkmcnt(3)
	v_mfma_f32_16x16x32_bf16 v[4:7], v[126:129], v[242:245], v[4:7]
	v_mfma_f32_16x16x32_bf16 v[94:97], v[126:129], v[194:197], v[94:97]
	ds_read_b128 v[126:129], v133 offset:1536
	s_waitcnt lgkmcnt(3)
	v_mfma_f32_16x16x32_bf16 v[8:11], v[76:79], v[238:241], 0
	v_mfma_f32_16x16x32_bf16 v[98:101], v[76:79], v[246:249], 0
	ds_read_b128 v[76:79], v131 offset:2048
	s_waitcnt lgkmcnt(3)
	v_mfma_f32_16x16x32_bf16 v[8:11], v[80:83], v[242:245], v[8:11]
	v_mfma_f32_16x16x32_bf16 v[98:101], v[80:83], v[194:197], v[98:101]
	ds_read_b128 v[80:83], v133 offset:2048
	s_waitcnt lgkmcnt(3)
	v_mfma_f32_16x16x32_bf16 v[12:15], v[122:125], v[238:241], 0
	v_mfma_f32_16x16x32_bf16 v[102:105], v[122:125], v[246:249], 0
	ds_read_b128 v[122:125], v131 offset:2560
	s_waitcnt lgkmcnt(3)
	v_mfma_f32_16x16x32_bf16 v[12:15], v[126:129], v[242:245], v[12:15]
	v_mfma_f32_16x16x32_bf16 v[102:105], v[126:129], v[194:197], v[102:105]
	ds_read_b128 v[126:129], v133 offset:2560
	s_waitcnt lgkmcnt(3)
	v_mfma_f32_16x16x32_bf16 v[16:19], v[76:79], v[238:241], 0
	v_mfma_f32_16x16x32_bf16 v[106:109], v[76:79], v[246:249], 0
	ds_read_b128 v[76:79], v131 offset:3072
	s_waitcnt lgkmcnt(3)
	v_mfma_f32_16x16x32_bf16 v[16:19], v[80:83], v[242:245], v[16:19]
	v_mfma_f32_16x16x32_bf16 v[106:109], v[80:83], v[194:197], v[106:109]
	ds_read_b128 v[80:83], v133 offset:3072
	s_waitcnt lgkmcnt(3)
	v_mfma_f32_16x16x32_bf16 v[20:23], v[122:125], v[238:241], 0
	v_mfma_f32_16x16x32_bf16 v[110:113], v[122:125], v[246:249], 0
	ds_read_b128 v[122:125], v131 offset:3584
	s_waitcnt lgkmcnt(3)
	v_mfma_f32_16x16x32_bf16 v[20:23], v[126:129], v[242:245], v[20:23]
	v_mfma_f32_16x16x32_bf16 v[110:113], v[126:129], v[194:197], v[110:113]
	ds_read_b128 v[126:129], v133 offset:3584
	s_waitcnt lgkmcnt(3)
	v_mfma_f32_16x16x32_bf16 v[24:27], v[76:79], v[238:241], 0
	v_mfma_f32_16x16x32_bf16 v[114:117], v[76:79], v[246:249], 0
	s_waitcnt lgkmcnt(2)
	v_mfma_f32_16x16x32_bf16 v[24:27], v[80:83], v[242:245], v[24:27]
	v_mfma_f32_16x16x32_bf16 v[114:117], v[80:83], v[194:197], v[114:117]
	s_waitcnt lgkmcnt(1)
	v_mfma_f32_16x16x32_bf16 v[28:31], v[122:125], v[238:241], 0
	v_mfma_f32_16x16x32_bf16 v[118:121], v[122:125], v[246:249], 0
	s_waitcnt lgkmcnt(0)
; __device__ __forceinline__ float bf2f(u16 h) { return __uint_as_float(((unsigned)h) << 16); }
; __device__ __forceinline__ void lru_tile(const Params& P, int chunk, int head, int pass, char* smem_raw) {
;     ...
;       ba[tc] = P.b_a[cidx] * -1.4426950408889634f; bi[tc] = P.b_i[cidx] * -1.4426950408889634f;
;       const float nl = -P.lam[cidx];
;       const float e_ = __expf(nl);
;       const float sp = (nl > 20.f) ? nl
;                      : (e_ < 0.03f ? e_ * (1.f - e_ * (0.5f - e_ * (0.33333334f - 0.25f * e_))) : __logf(1.f + e_));
;       c8[tc] = 8.f * 1.4426950408889634f * sp;
;     }
;     __syncthreads();
;     float cA = 1.f, cB = (pass == 2) ? sm_init[d * 64 + ch] : 0.f;
;     for (int sbi = 0; sbi < 2; ++sbi) {
;       const int sb = (d == 0) ? sbi : 1 - sbi;
;       f32x4 acc[8];
; #pragma unroll
;       for (int t = 0; t < 8; ++t) acc[t] = f32x4{0.f, 0.f, 0.f, 0.f};
; #pragma unroll
;       for (int s = 0; s < 2; ++s) {
;         const bf16x8 af = *reinterpret_cast<const bf16x8*>(&sm_uc[(sb * 64 + wid * 16 + (lane & 15)) * LDSS + s * 32 + (lane >> 4) * 8]);
; #pragma unroll
;         for (int t = 0; t < 8; ++t) {
;           const bf16x8 bfr = *reinterpret_cast<const bf16x8*>(&sm_w[(t * 16 + (lane & 15)) * LDSS + s * 32 + (lane >> 4) * 8]);
;           acc[t] = __builtin_amdgcn_mfma_f32_16x16x32_bf16(af, bfr, acc[t], 0, 0, 0);
;         }
;       }
; #pragma unroll
;       for (int tc = 0; tc < 4; ++tc)
; #pragma unroll
;         for (int reg = 0; reg < 4; ++reg) {
;           const int tl = wid * 16 + (lane >> 4) * 4 + reg;
;           const int c = 16 * tc + (lane & 15);
;           const float r = __builtin_amdgcn_rcpf(1.f + __builtin_amdgcn_exp2f(acc[tc][reg] + ba[tc]));
;           const float ii = __builtin_amdgcn_rcpf(1.f + __builtin_amdgcn_exp2f(acc[tc + 4][reg] + bi[tc]));
;           const float la = -c8[tc] * r;
;           const float a = __builtin_amdgcn_exp2f(la);
;           const float ucv = bf2f(sm_uc[(sb * 64 + tl) * LDSS + c]);
;           const float bt = __builtin_amdgcn_sqrtf(fmaxf(1.f - a * a, 0.f)) * (ii * ucv);
;           sm_a[tl * 64 + c] = a;
;           sm_b[tl * 64 + c] = bt;
;         }
	v_mfma_f32_16x16x32_bf16 v[28:31], v[126:129], v[242:245], v[28:31]
	v_mfma_f32_16x16x32_bf16 v[118:121], v[126:129], v[194:197], v[118:121]
	v_mul_f32_e32 v68, 0xbfb8aa3b, v68
	v_mul_f32_e32 v70, 0xbfb8aa3b, v70
	v_sub_f32_e32 v138, 0, v73
	v_mul_f32_e32 v139, 0x3fb8aa3b, v138
	v_exp_f32_e32 v139, v139
	v_mul_f32_e32 v140, 0xbe800000, v139
	v_add_f32_e32 v140, 0x3eaaaaab, v140
	v_fma_f32 v140, -v139, v140, 0.5
	v_fma_f32 v140, -v139, v140, 1.0
	v_mul_f32_e32 v140, v139, v140
	v_add_f32_e32 v141, 1.0, v139
	v_log_f32_e32 v141, v141
	v_mov_b32_e32 v255, 0x3cf5c28f
	v_mul_f32_e32 v141, 0x3f317218, v141
	v_cmp_gt_f32_e32 vcc, v255, v139
	s_nop 1
	v_cndmask_b32_e32 v140, v141, v140, vcc
	v_mov_b32_e32 v255, 0x41a00000
	v_cmp_lt_f32_e32 vcc, v255, v138
	s_nop 1
	v_cndmask_b32_e32 v140, v140, v138, vcc
	v_mul_f32_e32 v73, 0xc138aa3b, v140
	s_nop 7
	v_add_f32_e32 v0, v0, v68
	v_add_f32_e32 v1, v1, v68
	v_add_f32_e32 v2, v2, v68
	v_add_f32_e32 v3, v3, v68
	v_add_f32_e32 v90, v90, v70
	v_add_f32_e32 v91, v91, v70
	v_add_f32_e32 v92, v92, v70
	v_add_f32_e32 v93, v93, v70
	v_exp_f32_e32 v0, v0
	v_exp_f32_e32 v1, v1
	v_exp_f32_e32 v2, v2
	v_exp_f32_e32 v3, v3
	v_exp_f32_e32 v90, v90
	v_exp_f32_e32 v91, v91
	v_exp_f32_e32 v92, v92
	v_exp_f32_e32 v93, v93
	v_add_f32_e32 v0, 1.0, v0
	v_add_f32_e32 v1, 1.0, v1
	v_add_f32_e32 v2, 1.0, v2
	v_add_f32_e32 v3, 1.0, v3
	v_add_f32_e32 v90, 1.0, v90
	v_add_f32_e32 v91, 1.0, v91
	v_add_f32_e32 v92, 1.0, v92
	v_add_f32_e32 v93, 1.0, v93
	v_rcp_f32_e32 v0, v0
	v_rcp_f32_e32 v1, v1
	v_rcp_f32_e32 v2, v2
	v_rcp_f32_e32 v3, v3
	v_rcp_f32_e32 v90, v90
	v_rcp_f32_e32 v91, v91
	v_rcp_f32_e32 v92, v92
	v_rcp_f32_e32 v93, v93
	v_mul_f32_e32 v0, v73, v0
	v_mul_f32_e32 v1, v73, v1
	v_mul_f32_e32 v2, v73, v2
	v_mul_f32_e32 v3, v73, v3
	v_mul_f32_e32 v90, v90, v162
	v_mul_f32_e32 v91, v91, v163
	v_mul_f32_e32 v92, v92, v164
	v_mul_f32_e32 v93, v93, v165
	v_exp_f32_e32 v0, v0
	v_exp_f32_e32 v1, v1
	v_exp_f32_e32 v2, v2
	v_exp_f32_e32 v3, v3
	s_nop 0
	v_fma_f32 v138, -v0, v0, 1.0
	v_fma_f32 v139, -v1, v1, 1.0
	v_fma_f32 v140, -v2, v2, 1.0
	v_fma_f32 v141, -v3, v3, 1.0
	v_max_f32_e32 v138, 0, v138
	v_max_f32_e32 v139, 0, v139
	v_max_f32_e32 v140, 0, v140
	v_max_f32_e32 v141, 0, v141
	v_sqrt_f32_e32 v138, v138
	v_sqrt_f32_e32 v139, v139
	v_sqrt_f32_e32 v140, v140
	v_sqrt_f32_e32 v141, v141
	s_nop 0
	v_mul_f32_e32 v90, v138, v90
	v_mul_f32_e32 v91, v139, v91
	v_mul_f32_e32 v92, v140, v92
	v_mul_f32_e32 v93, v141, v93
	v_add_f32_e32 v4, v4, v68
	v_add_f32_e32 v5, v5, v68
	v_add_f32_e32 v6, v6, v68
	v_add_f32_e32 v7, v7, v68
	v_add_f32_e32 v94, v94, v70
	v_add_f32_e32 v95, v95, v70
	v_add_f32_e32 v96, v96, v70
	v_add_f32_e32 v97, v97, v70
	v_exp_f32_e32 v4, v4
	v_exp_f32_e32 v5, v5
	v_exp_f32_e32 v6, v6
	v_exp_f32_e32 v7, v7
	v_exp_f32_e32 v94, v94
	v_exp_f32_e32 v95, v95
	v_exp_f32_e32 v96, v96
	v_exp_f32_e32 v97, v97
	v_add_f32_e32 v4, 1.0, v4
	v_add_f32_e32 v5, 1.0, v5
	v_add_f32_e32 v6, 1.0, v6
	v_add_f32_e32 v7, 1.0, v7
	v_add_f32_e32 v94, 1.0, v94
	v_add_f32_e32 v95, 1.0, v95
	v_add_f32_e32 v96, 1.0, v96
	v_add_f32_e32 v97, 1.0, v97
	v_rcp_f32_e32 v4, v4
	v_rcp_f32_e32 v5, v5
	v_rcp_f32_e32 v6, v6
	v_rcp_f32_e32 v7, v7
	v_rcp_f32_e32 v94, v94
	v_rcp_f32_e32 v95, v95
	v_rcp_f32_e32 v96, v96
	v_rcp_f32_e32 v97, v97
	v_mul_f32_e32 v4, v73, v4
	v_mul_f32_e32 v5, v73, v5
	v_mul_f32_e32 v6, v73, v6
	v_mul_f32_e32 v7, v73, v7
	v_mul_f32_e32 v94, v94, v166
	v_mul_f32_e32 v95, v95, v167
	v_mul_f32_e32 v96, v96, v168
	v_mul_f32_e32 v97, v97, v169
	v_exp_f32_e32 v4, v4
	v_exp_f32_e32 v5, v5
	v_exp_f32_e32 v6, v6
	v_exp_f32_e32 v7, v7
	s_nop 0
	v_fma_f32 v138, -v4, v4, 1.0
	v_fma_f32 v139, -v5, v5, 1.0
	v_fma_f32 v140, -v6, v6, 1.0
	v_fma_f32 v141, -v7, v7, 1.0
	v_max_f32_e32 v138, 0, v138
	v_max_f32_e32 v139, 0, v139
	v_max_f32_e32 v140, 0, v140
	v_max_f32_e32 v141, 0, v141
	v_sqrt_f32_e32 v138, v138
	v_sqrt_f32_e32 v139, v139
	v_sqrt_f32_e32 v140, v140
	v_sqrt_f32_e32 v141, v141
	s_nop 0
	v_mul_f32_e32 v94, v138, v94
	v_mul_f32_e32 v95, v139, v95
	v_mul_f32_e32 v96, v140, v96
	v_mul_f32_e32 v97, v141, v97
	v_add_f32_e32 v8, v8, v68
	v_add_f32_e32 v9, v9, v68
	v_add_f32_e32 v10, v10, v68
	v_add_f32_e32 v11, v11, v68
	v_add_f32_e32 v98, v98, v70
	v_add_f32_e32 v99, v99, v70
	v_add_f32_e32 v100, v100, v70
	v_add_f32_e32 v101, v101, v70
	v_exp_f32_e32 v8, v8
	v_exp_f32_e32 v9, v9
	v_exp_f32_e32 v10, v10
	v_exp_f32_e32 v11, v11
	v_exp_f32_e32 v98, v98
	v_exp_f32_e32 v99, v99
	v_exp_f32_e32 v100, v100
	v_exp_f32_e32 v101, v101
	v_add_f32_e32 v8, 1.0, v8
	v_add_f32_e32 v9, 1.0, v9
	v_add_f32_e32 v10, 1.0, v10
	v_add_f32_e32 v11, 1.0, v11
	v_add_f32_e32 v98, 1.0, v98
	v_add_f32_e32 v99, 1.0, v99
	v_add_f32_e32 v100, 1.0, v100
	v_add_f32_e32 v101, 1.0, v101
	v_rcp_f32_e32 v8, v8
	v_rcp_f32_e32 v9, v9
	v_rcp_f32_e32 v10, v10
	v_rcp_f32_e32 v11, v11
	v_rcp_f32_e32 v98, v98
	v_rcp_f32_e32 v99, v99
	v_rcp_f32_e32 v100, v100
	v_rcp_f32_e32 v101, v101
	v_mul_f32_e32 v8, v73, v8
	v_mul_f32_e32 v9, v73, v9
	v_mul_f32_e32 v10, v73, v10
	v_mul_f32_e32 v11, v73, v11
	v_mul_f32_e32 v98, v98, v170
	v_mul_f32_e32 v99, v99, v171
	v_mul_f32_e32 v100, v100, v172
	v_mul_f32_e32 v101, v101, v173
	v_exp_f32_e32 v8, v8
	v_exp_f32_e32 v9, v9
	v_exp_f32_e32 v10, v10
	v_exp_f32_e32 v11, v11
	s_nop 0
	v_fma_f32 v138, -v8, v8, 1.0
	v_fma_f32 v139, -v9, v9, 1.0
	v_fma_f32 v140, -v10, v10, 1.0
	v_fma_f32 v141, -v11, v11, 1.0
	v_max_f32_e32 v138, 0, v138
	v_max_f32_e32 v139, 0, v139
	v_max_f32_e32 v140, 0, v140
	v_max_f32_e32 v141, 0, v141
	v_sqrt_f32_e32 v138, v138
	v_sqrt_f32_e32 v139, v139
	v_sqrt_f32_e32 v140, v140
	v_sqrt_f32_e32 v141, v141
	s_nop 0
; __device__ __forceinline__ float bf2f(u16 h) { return __uint_as_float(((unsigned)h) << 16); }
; __device__ __forceinline__ void lru_tile(const Params& P, int chunk, int head, int pass, char* smem_raw) {
;     ...
;       for (int tc = 0; tc < 4; ++tc)
; #pragma unroll
;         for (int reg = 0; reg < 4; ++reg) {
;           const int tl = wid * 16 + (lane >> 4) * 4 + reg;
;           const int c = 16 * tc + (lane & 15);
;           const float r = __builtin_amdgcn_rcpf(1.f + __builtin_amdgcn_exp2f(acc[tc][reg] + ba[tc]));
;           const float ii = __builtin_amdgcn_rcpf(1.f + __builtin_amdgcn_exp2f(acc[tc + 4][reg] + bi[tc]));
;           const float la = -c8[tc] * r;
;           const float a = __builtin_amdgcn_exp2f(la);
;           const float ucv = bf2f(sm_uc[(sb * 64 + tl) * LDSS + c]);
;           const float bt = __builtin_amdgcn_sqrtf(fmaxf(1.f - a * a, 0.f)) * (ii * ucv);
;           sm_a[tl * 64 + c] = a;
;           sm_b[tl * 64 + c] = bt;
;         }
	v_mul_f32_e32 v98, v138, v98
	v_mul_f32_e32 v99, v139, v99
	v_mul_f32_e32 v100, v140, v100
	v_mul_f32_e32 v101, v141, v101
	v_add_f32_e32 v12, v12, v68
	v_add_f32_e32 v13, v13, v68
	v_add_f32_e32 v14, v14, v68
	v_add_f32_e32 v15, v15, v68
	v_add_f32_e32 v102, v102, v70
	v_add_f32_e32 v103, v103, v70
	v_add_f32_e32 v104, v104, v70
	v_add_f32_e32 v105, v105, v70
	v_exp_f32_e32 v12, v12
	v_exp_f32_e32 v13, v13
	v_exp_f32_e32 v14, v14
	v_exp_f32_e32 v15, v15
	v_exp_f32_e32 v102, v102
	v_exp_f32_e32 v103, v103
	v_exp_f32_e32 v104, v104
	v_exp_f32_e32 v105, v105
	v_add_f32_e32 v12, 1.0, v12
	v_add_f32_e32 v13, 1.0, v13
	v_add_f32_e32 v14, 1.0, v14
	v_add_f32_e32 v15, 1.0, v15
	v_add_f32_e32 v102, 1.0, v102
	v_add_f32_e32 v103, 1.0, v103
	v_add_f32_e32 v104, 1.0, v104
	v_add_f32_e32 v105, 1.0, v105
	v_rcp_f32_e32 v12, v12
	v_rcp_f32_e32 v13, v13
	v_rcp_f32_e32 v14, v14
	v_rcp_f32_e32 v15, v15
	v_rcp_f32_e32 v102, v102
	v_rcp_f32_e32 v103, v103
	v_rcp_f32_e32 v104, v104
	v_rcp_f32_e32 v105, v105
	v_mul_f32_e32 v12, v73, v12
	v_mul_f32_e32 v13, v73, v13
	v_mul_f32_e32 v14, v73, v14
	v_mul_f32_e32 v15, v73, v15
	v_mul_f32_e32 v102, v102, v174
	v_mul_f32_e32 v103, v103, v175
	v_mul_f32_e32 v104, v104, v176
	v_mul_f32_e32 v105, v105, v177
	v_exp_f32_e32 v12, v12
	v_exp_f32_e32 v13, v13
	v_exp_f32_e32 v14, v14
	v_exp_f32_e32 v15, v15
	s_nop 0
	v_fma_f32 v138, -v12, v12, 1.0
	v_fma_f32 v139, -v13, v13, 1.0
	v_fma_f32 v140, -v14, v14, 1.0
	v_fma_f32 v141, -v15, v15, 1.0
	v_max_f32_e32 v138, 0, v138
	v_max_f32_e32 v139, 0, v139
	v_max_f32_e32 v140, 0, v140
	v_max_f32_e32 v141, 0, v141
	v_sqrt_f32_e32 v138, v138
	v_sqrt_f32_e32 v139, v139
	v_sqrt_f32_e32 v140, v140
	v_sqrt_f32_e32 v141, v141
	s_nop 0
	v_mul_f32_e32 v102, v138, v102
	v_mul_f32_e32 v103, v139, v103
	v_mul_f32_e32 v104, v140, v104
	v_mul_f32_e32 v105, v141, v105
	v_add_f32_e32 v16, v16, v68
	v_add_f32_e32 v17, v17, v68
	v_add_f32_e32 v18, v18, v68
	v_add_f32_e32 v19, v19, v68
	v_add_f32_e32 v106, v106, v70
	v_add_f32_e32 v107, v107, v70
	v_add_f32_e32 v108, v108, v70
	v_add_f32_e32 v109, v109, v70
	v_exp_f32_e32 v16, v16
	v_exp_f32_e32 v17, v17
	v_exp_f32_e32 v18, v18
	v_exp_f32_e32 v19, v19
	v_exp_f32_e32 v106, v106
	v_exp_f32_e32 v107, v107
	v_exp_f32_e32 v108, v108
	v_exp_f32_e32 v109, v109
	v_add_f32_e32 v16, 1.0, v16
	v_add_f32_e32 v17, 1.0, v17
	v_add_f32_e32 v18, 1.0, v18
	v_add_f32_e32 v19, 1.0, v19
	v_add_f32_e32 v106, 1.0, v106
	v_add_f32_e32 v107, 1.0, v107
	v_add_f32_e32 v108, 1.0, v108
	v_add_f32_e32 v109, 1.0, v109
	v_rcp_f32_e32 v16, v16
	v_rcp_f32_e32 v17, v17
	v_rcp_f32_e32 v18, v18
	v_rcp_f32_e32 v19, v19
	v_rcp_f32_e32 v106, v106
	v_rcp_f32_e32 v107, v107
	v_rcp_f32_e32 v108, v108
	v_rcp_f32_e32 v109, v109
	v_mul_f32_e32 v16, v73, v16
	v_mul_f32_e32 v17, v73, v17
	v_mul_f32_e32 v18, v73, v18
	v_mul_f32_e32 v19, v73, v19
	v_mul_f32_e32 v106, v106, v178
	v_mul_f32_e32 v107, v107, v179
	v_mul_f32_e32 v108, v108, v180
	v_mul_f32_e32 v109, v109, v181
	v_exp_f32_e32 v16, v16
	v_exp_f32_e32 v17, v17
	v_exp_f32_e32 v18, v18
	v_exp_f32_e32 v19, v19
	s_nop 0
	v_fma_f32 v138, -v16, v16, 1.0
	v_fma_f32 v139, -v17, v17, 1.0
	v_fma_f32 v140, -v18, v18, 1.0
	v_fma_f32 v141, -v19, v19, 1.0
	v_max_f32_e32 v138, 0, v138
	v_max_f32_e32 v139, 0, v139
	v_max_f32_e32 v140, 0, v140
	v_max_f32_e32 v141, 0, v141
	v_sqrt_f32_e32 v138, v138
	v_sqrt_f32_e32 v139, v139
	v_sqrt_f32_e32 v140, v140
	v_sqrt_f32_e32 v141, v141
	s_nop 0
	v_mul_f32_e32 v106, v138, v106
	v_mul_f32_e32 v107, v139, v107
	v_mul_f32_e32 v108, v140, v108
	v_mul_f32_e32 v109, v141, v109
	v_add_f32_e32 v20, v20, v68
	v_add_f32_e32 v21, v21, v68
	v_add_f32_e32 v22, v22, v68
	v_add_f32_e32 v23, v23, v68
	v_add_f32_e32 v110, v110, v70
	v_add_f32_e32 v111, v111, v70
	v_add_f32_e32 v112, v112, v70
	v_add_f32_e32 v113, v113, v70
	v_exp_f32_e32 v20, v20
	v_exp_f32_e32 v21, v21
	v_exp_f32_e32 v22, v22
	v_exp_f32_e32 v23, v23
	v_exp_f32_e32 v110, v110
	v_exp_f32_e32 v111, v111
	v_exp_f32_e32 v112, v112
	v_exp_f32_e32 v113, v113
	v_add_f32_e32 v20, 1.0, v20
	v_add_f32_e32 v21, 1.0, v21
	v_add_f32_e32 v22, 1.0, v22
	v_add_f32_e32 v23, 1.0, v23
	v_add_f32_e32 v110, 1.0, v110
	v_add_f32_e32 v111, 1.0, v111
	v_add_f32_e32 v112, 1.0, v112
	v_add_f32_e32 v113, 1.0, v113
	v_rcp_f32_e32 v20, v20
	v_rcp_f32_e32 v21, v21
	v_rcp_f32_e32 v22, v22
	v_rcp_f32_e32 v23, v23
	v_rcp_f32_e32 v110, v110
	v_rcp_f32_e32 v111, v111
	v_rcp_f32_e32 v112, v112
	v_rcp_f32_e32 v113, v113
	v_mul_f32_e32 v20, v73, v20
	v_mul_f32_e32 v21, v73, v21
	v_mul_f32_e32 v22, v73, v22
	v_mul_f32_e32 v23, v73, v23
	v_mul_f32_e32 v110, v110, v182
	v_mul_f32_e32 v111, v111, v183
	v_mul_f32_e32 v112, v112, v184
	v_mul_f32_e32 v113, v113, v185
	v_exp_f32_e32 v20, v20
	v_exp_f32_e32 v21, v21
	v_exp_f32_e32 v22, v22
	v_exp_f32_e32 v23, v23
	s_nop 0
	v_fma_f32 v138, -v20, v20, 1.0
	v_fma_f32 v139, -v21, v21, 1.0
	v_fma_f32 v140, -v22, v22, 1.0
	v_fma_f32 v141, -v23, v23, 1.0
	v_max_f32_e32 v138, 0, v138
	v_max_f32_e32 v139, 0, v139
	v_max_f32_e32 v140, 0, v140
	v_max_f32_e32 v141, 0, v141
	v_sqrt_f32_e32 v138, v138
	v_sqrt_f32_e32 v139, v139
	v_sqrt_f32_e32 v140, v140
	v_sqrt_f32_e32 v141, v141
	s_nop 0
	v_mul_f32_e32 v110, v138, v110
	v_mul_f32_e32 v111, v139, v111
	v_mul_f32_e32 v112, v140, v112
	v_mul_f32_e32 v113, v141, v113
	v_add_f32_e32 v24, v24, v68
	v_add_f32_e32 v25, v25, v68
	v_add_f32_e32 v26, v26, v68
	v_add_f32_e32 v27, v27, v68
	v_add_f32_e32 v114, v114, v70
	v_add_f32_e32 v115, v115, v70
	v_add_f32_e32 v116, v116, v70
	v_add_f32_e32 v117, v117, v70
	v_exp_f32_e32 v24, v24
	v_exp_f32_e32 v25, v25
	v_exp_f32_e32 v26, v26
	v_exp_f32_e32 v27, v27
	v_exp_f32_e32 v114, v114
; __device__ __forceinline__ float bf2f(u16 h) { return __uint_as_float(((unsigned)h) << 16); }
; __device__ __forceinline__ void lru_tile(const Params& P, int chunk, int head, int pass, char* smem_raw) {
;     ...
;       for (int tc = 0; tc < 4; ++tc)
; #pragma unroll
;         for (int reg = 0; reg < 4; ++reg) {
;           const int tl = wid * 16 + (lane >> 4) * 4 + reg;
;           const int c = 16 * tc + (lane & 15);
;           const float r = __builtin_amdgcn_rcpf(1.f + __builtin_amdgcn_exp2f(acc[tc][reg] + ba[tc]));
;           const float ii = __builtin_amdgcn_rcpf(1.f + __builtin_amdgcn_exp2f(acc[tc + 4][reg] + bi[tc]));
;           const float la = -c8[tc] * r;
;           const float a = __builtin_amdgcn_exp2f(la);
;           const float ucv = bf2f(sm_uc[(sb * 64 + tl) * LDSS + c]);
;           const float bt = __builtin_amdgcn_sqrtf(fmaxf(1.f - a * a, 0.f)) * (ii * ucv);
;           sm_a[tl * 64 + c] = a;
;           sm_b[tl * 64 + c] = bt;
;         }
;       __syncthreads();
;       const int pos = (d == 0) ? q : 3 - q;
;       {
;         float Pp = 1.f, H = 0.f;
; #pragma unroll 4
;         for (int i = 0; i < 16; ++i) {
;           const int tl = (d == 0) ? (q * 16 + i) : (q * 16 + 15 - i);
;           const float a = sm_a[tl * 64 + ch], b = sm_b[tl * 64 + ch];
;           H = a * H + b; Pp *= a;
;         }
;         sm_ph[pos * 64 + ch] = make_float2(Pp, H);
;     ...
;       cB = p0.x * cB + p0.y; cA *= p0.x;
;       cB = p1.x * cB + p1.y; cA *= p1.x;
;       cB = p2.x * cB + p2.y; cA *= p2.x;
;       cB = p3.x * cB + p3.y; cA *= p3.x;
;       __syncthreads();
;     }
;     if (pass == 1 && q == 0) P.summ[((long)d * 264 + chunk) * 512 + gch] = make_float2(cA, cB);
	v_exp_f32_e32 v115, v115
	v_exp_f32_e32 v116, v116
	v_exp_f32_e32 v117, v117
	v_add_f32_e32 v24, 1.0, v24
	v_add_f32_e32 v25, 1.0, v25
	v_add_f32_e32 v26, 1.0, v26
	v_add_f32_e32 v27, 1.0, v27
	v_add_f32_e32 v114, 1.0, v114
	v_add_f32_e32 v115, 1.0, v115
	v_add_f32_e32 v116, 1.0, v116
	v_add_f32_e32 v117, 1.0, v117
	v_rcp_f32_e32 v24, v24
	v_rcp_f32_e32 v25, v25
	v_rcp_f32_e32 v26, v26
	v_rcp_f32_e32 v27, v27
	v_rcp_f32_e32 v114, v114
	v_rcp_f32_e32 v115, v115
	v_rcp_f32_e32 v116, v116
	v_rcp_f32_e32 v117, v117
	v_mul_f32_e32 v24, v73, v24
	v_mul_f32_e32 v25, v73, v25
	v_mul_f32_e32 v26, v73, v26
	v_mul_f32_e32 v27, v73, v27
	v_mul_f32_e32 v114, v114, v186
	v_mul_f32_e32 v115, v115, v187
	v_mul_f32_e32 v116, v116, v188
	v_mul_f32_e32 v117, v117, v189
	v_exp_f32_e32 v24, v24
	v_exp_f32_e32 v25, v25
	v_exp_f32_e32 v26, v26
	v_exp_f32_e32 v27, v27
	s_nop 0
	v_fma_f32 v138, -v24, v24, 1.0
	v_fma_f32 v139, -v25, v25, 1.0
	v_fma_f32 v140, -v26, v26, 1.0
	v_fma_f32 v141, -v27, v27, 1.0
	v_max_f32_e32 v138, 0, v138
	v_max_f32_e32 v139, 0, v139
	v_max_f32_e32 v140, 0, v140
	v_max_f32_e32 v141, 0, v141
	v_sqrt_f32_e32 v138, v138
	v_sqrt_f32_e32 v139, v139
	v_sqrt_f32_e32 v140, v140
	v_sqrt_f32_e32 v141, v141
	s_nop 0
	v_mul_f32_e32 v114, v138, v114
	v_mul_f32_e32 v115, v139, v115
	v_mul_f32_e32 v116, v140, v116
	v_mul_f32_e32 v117, v141, v117
	v_add_f32_e32 v28, v28, v68
	v_add_f32_e32 v29, v29, v68
	v_add_f32_e32 v30, v30, v68
	v_add_f32_e32 v31, v31, v68
	v_add_f32_e32 v118, v118, v70
	v_add_f32_e32 v119, v119, v70
	v_add_f32_e32 v120, v120, v70
	v_add_f32_e32 v121, v121, v70
	v_exp_f32_e32 v28, v28
	v_exp_f32_e32 v29, v29
	v_exp_f32_e32 v30, v30
	v_exp_f32_e32 v31, v31
	v_exp_f32_e32 v118, v118
	v_exp_f32_e32 v119, v119
	v_exp_f32_e32 v120, v120
	v_exp_f32_e32 v121, v121
	v_add_f32_e32 v28, 1.0, v28
	v_add_f32_e32 v29, 1.0, v29
	v_add_f32_e32 v30, 1.0, v30
	v_add_f32_e32 v31, 1.0, v31
	v_add_f32_e32 v118, 1.0, v118
	v_add_f32_e32 v119, 1.0, v119
	v_add_f32_e32 v120, 1.0, v120
	v_add_f32_e32 v121, 1.0, v121
	v_rcp_f32_e32 v28, v28
	v_rcp_f32_e32 v29, v29
	v_rcp_f32_e32 v30, v30
	v_rcp_f32_e32 v31, v31
	v_rcp_f32_e32 v118, v118
	v_rcp_f32_e32 v119, v119
	v_rcp_f32_e32 v120, v120
	v_rcp_f32_e32 v121, v121
	v_mul_f32_e32 v28, v73, v28
	v_mul_f32_e32 v29, v73, v29
	v_mul_f32_e32 v30, v73, v30
	v_mul_f32_e32 v31, v73, v31
	v_mul_f32_e32 v118, v118, v190
	v_mul_f32_e32 v119, v119, v191
	v_mul_f32_e32 v120, v120, v192
	v_mul_f32_e32 v121, v121, v193
	v_exp_f32_e32 v28, v28
	v_exp_f32_e32 v29, v29
	v_exp_f32_e32 v30, v30
	v_exp_f32_e32 v31, v31
	s_nop 0
	v_fma_f32 v138, -v28, v28, 1.0
	v_fma_f32 v139, -v29, v29, 1.0
	v_fma_f32 v140, -v30, v30, 1.0
	v_fma_f32 v141, -v31, v31, 1.0
	v_max_f32_e32 v138, 0, v138
	v_max_f32_e32 v139, 0, v139
	v_max_f32_e32 v140, 0, v140
	v_max_f32_e32 v141, 0, v141
	v_sqrt_f32_e32 v138, v138
	v_sqrt_f32_e32 v139, v139
	v_sqrt_f32_e32 v140, v140
	v_sqrt_f32_e32 v141, v141
	s_nop 0
	v_mul_f32_e32 v118, v138, v118
	v_mul_f32_e32 v119, v139, v119
	v_mul_f32_e32 v120, v140, v120
	v_mul_f32_e32 v121, v141, v121
	v_mov_b32_e32 v253, v31
	v_mov_b32_e32 v254, v121
	v_fma_f32 v254, v30, v254, v120
	v_mul_f32_e32 v253, v253, v30
	v_fma_f32 v254, v29, v254, v119
	v_mul_f32_e32 v253, v253, v29
	v_fma_f32 v254, v28, v254, v118
	v_mul_f32_e32 v253, v253, v28
	v_fma_f32 v254, v27, v254, v117
	v_mul_f32_e32 v253, v253, v27
	v_fma_f32 v254, v26, v254, v116
	v_mul_f32_e32 v253, v253, v26
	v_fma_f32 v254, v25, v254, v115
	v_mul_f32_e32 v253, v253, v25
	v_fma_f32 v254, v24, v254, v114
	v_mul_f32_e32 v253, v253, v24
	v_fma_f32 v254, v23, v254, v113
	v_mul_f32_e32 v253, v253, v23
	v_fma_f32 v254, v22, v254, v112
	v_mul_f32_e32 v253, v253, v22
	v_fma_f32 v254, v21, v254, v111
	v_mul_f32_e32 v253, v253, v21
	v_fma_f32 v254, v20, v254, v110
	v_mul_f32_e32 v253, v253, v20
	v_fma_f32 v254, v19, v254, v109
	v_mul_f32_e32 v253, v253, v19
	v_fma_f32 v254, v18, v254, v108
	v_mul_f32_e32 v253, v253, v18
	v_fma_f32 v254, v17, v254, v107
	v_mul_f32_e32 v253, v253, v17
	v_fma_f32 v254, v16, v254, v106
	v_mul_f32_e32 v253, v253, v16
	v_fma_f32 v254, v15, v254, v105
	v_mul_f32_e32 v253, v253, v15
	v_fma_f32 v254, v14, v254, v104
	v_mul_f32_e32 v253, v253, v14
	v_fma_f32 v254, v13, v254, v103
	v_mul_f32_e32 v253, v253, v13
	v_fma_f32 v254, v12, v254, v102
	v_mul_f32_e32 v253, v253, v12
	v_fma_f32 v254, v11, v254, v101
	v_mul_f32_e32 v253, v253, v11
	v_fma_f32 v254, v10, v254, v100
	v_mul_f32_e32 v253, v253, v10
	v_fma_f32 v254, v9, v254, v99
	v_mul_f32_e32 v253, v253, v9
	v_fma_f32 v254, v8, v254, v98
	v_mul_f32_e32 v253, v253, v8
	v_fma_f32 v254, v7, v254, v97
	v_mul_f32_e32 v253, v253, v7
	v_fma_f32 v254, v6, v254, v96
	v_mul_f32_e32 v253, v253, v6
	v_fma_f32 v254, v5, v254, v95
	v_mul_f32_e32 v253, v253, v5
	v_fma_f32 v254, v4, v254, v94
	v_mul_f32_e32 v253, v253, v4
	v_fma_f32 v254, v3, v254, v93
	v_mul_f32_e32 v253, v253, v3
	v_fma_f32 v254, v2, v254, v92
	v_mul_f32_e32 v253, v253, v2
	v_fma_f32 v254, v1, v254, v91
	v_mul_f32_e32 v253, v253, v1
	v_fma_f32 v254, v0, v254, v90
	v_mul_f32_e32 v253, v253, v0
	v_mov_b32_e32 v138, v253
	v_mov_b32_e32 v139, v253
	s_nop 1
	v_permlane16_swap_b32_e32 v138, v139
	v_mov_b32_e32 v140, v138
	v_mov_b32_e32 v141, v139
	s_nop 1
	v_permlane32_swap_b32_e32 v138, v140
	v_permlane32_swap_b32_e32 v139, v141
	v_mov_b32_e32 v198, v254
	v_mov_b32_e32 v199, v254
	s_nop 1
	v_permlane16_swap_b32_e32 v198, v199
	v_mov_b32_e32 v200, v198
	v_mov_b32_e32 v201, v199
	s_nop 1
	v_permlane32_swap_b32_e32 v198, v200
	v_permlane32_swap_b32_e32 v199, v201
	v_mov_b32_e32 v202, 0
	v_fma_f32 v151, v141, v202, v201
	v_fma_f32 v150, v140, v151, v200
	v_fma_f32 v136, v139, v150, v199
	v_fma_f32 v254, v138, v136, v198
	v_mul_f32_e32 v253, v138, v139
	v_mul_f32_e32 v253, v253, v140
	v_mul_f32_e32 v200, v253, v141
	v_mov_b32_e32 v201, v254
	s_add_u32 s0, s71, 264
	s_lshl_b32 s0, s0, 12
	s_lshl_b32 s1, s56, 3
	s_add_u32 s0, s0, s1
	s_add_u32 s4, s18, s0
	s_addc_u32 s5, s19, 0
	global_store_dwordx2 v250, v[200:201], s[4:5]
	s_add_u32 s69, s69, 1
	s_cmp_lt_u32 s69, s70
	s_cbranch_scc1 .Lmy_lrua_tile
	s_waitcnt lgkmcnt(0)
	s_barrier

; __device__ __forceinline__ float bf2f(u16 h) { return __uint_as_float(((unsigned)h) << 16); }
; __device__ __forceinline__ void lru_tile(const Params& P, int chunk, int head, int pass, char* smem_raw) {
;     ...
;     const float w0 = P.conv_w[gch], w1 = P.conv_w[512 + gch], w2 = P.conv_w[1024 + gch], w3 = P.conv_w[1536 + gch];
;     const float cb = P.conv_b[gch];
;     const u16* zu = P.zq + gch;
;     const int r = row0 + q * 32;
;     float uv[35];
; #pragma unroll
;     for (int i = 0; i < 35; ++i) {
;       const int rr = r - 2 + i;
;       uv[i] = (rr >= seq_lo && rr < seq_hi) ? bf2f(zu[(long)rr * 1536]) : 0.f;
;     }
;     ...
;     for (int i = 0; i < 4; ++i) {
;       const int idx = tid + 256 * i, rowi = idx >> 3, kg = idx & 7;
;       *reinterpret_cast<uint4*>(&sm_w[rowi * LDSS + kg * 8]) = ldg16(P.wg + ((long)(d * 8 + head) * 128 + rowi) * 64 + kg * 8);
;     }
;     float ba[4], bi[4], c8[4];
; #pragma unroll
;     for (int tc = 0; tc < 4; ++tc) {
;       const int cidx = d * 512 + head * 64 + 16 * tc + (lane & 15);
;       ba[tc] = P.b_a[cidx] * -1.4426950408889634f; bi[tc] = P.b_i[cidx] * -1.4426950408889634f;
;       const float nl = -P.lam[cidx];
;       const float e_ = __expf(nl);
;       const float sp = (nl > 20.f) ? nl
;                      : (e_ < 0.03f ? e_ * (1.f - e_ * (0.5f - e_ * (0.33333334f - 0.25f * e_))) : __logf(1.f + e_));
;       c8[tc] = 8.f * 1.4426950408889634f * sp;
.Lmy_lrub_fl:
	s_cmp_eq_u32 s57, 0
	s_cselect_b64 s[0:1], s[84:85], 0
	s_cmp_eq_u32 s57, s60
	s_cselect_b64 s[4:5], s[86:87], 0
	v_cndmask_b32_e64 v202, 1.0, 0, s[0:1]
	v_cndmask_b32_e64 v203, 1.0, 0, s[4:5]
	v_mov_b32_e32 v255, 0x1800
	v_cndmask_b32_e64 v150, 0, v255, s[0:1]
	v_lshlrev_b32_e32 v136, 1, v150
	v_add_u32_e32 v136, v134, v136
	v_add_u32_e32 v150, v134, v150
	v_cndmask_b32_e64 v151, 0, v255, s[4:5]
	v_sub_u32_e32 v151, v134, v151
	s_lshl_b32 s61, s71, 7
	s_mul_i32 s0, s61, 0xc00
	s_lshl_b32 s1, s56, 1
	s_add_u32 s0, s0, s1
	s_add_u32 s4, s10, s0
	s_addc_u32 s5, s11, 0
	s_sub_u32 s4, s4, 0x1800
	s_subb_u32 s5, s5, 0
	global_load_ushort v90, v136, s[4:5]
	s_add_u32 s4, s4, 0xc00
	s_addc_u32 s5, s5, 0
	global_load_ushort v91, v150, s[4:5]
	s_add_u32 s4, s4, 0xc00
	s_addc_u32 s5, s5, 0
	global_load_ushort v92, v134, s[4:5]
	s_add_u32 s4, s4, 0xc00
	s_addc_u32 s5, s5, 0
	global_load_ushort v93, v134, s[4:5]
	s_add_u32 s4, s4, 0xc00
	s_addc_u32 s5, s5, 0
	global_load_ushort v94, v134, s[4:5]
	s_add_u32 s4, s4, 0xc00
	s_addc_u32 s5, s5, 0
	global_load_ushort v95, v134, s[4:5]
	s_add_u32 s4, s4, 0xc00
	s_addc_u32 s5, s5, 0
	global_load_ushort v96, v134, s[4:5]
	s_add_u32 s4, s4, 0xc00
	s_addc_u32 s5, s5, 0
	global_load_ushort v97, v134, s[4:5]
	s_add_u32 s4, s4, 0xc00
	s_addc_u32 s5, s5, 0
	global_load_ushort v98, v134, s[4:5]
	s_add_u32 s4, s4, 0xc00
	s_addc_u32 s5, s5, 0
	global_load_ushort v99, v134, s[4:5]
	s_add_u32 s4, s4, 0xc00
	s_addc_u32 s5, s5, 0
	global_load_ushort v100, v134, s[4:5]
	s_add_u32 s4, s4, 0xc00
	s_addc_u32 s5, s5, 0
	global_load_ushort v101, v134, s[4:5]
	s_add_u32 s4, s4, 0xc00
	s_addc_u32 s5, s5, 0
	global_load_ushort v102, v134, s[4:5]
	s_add_u32 s4, s4, 0xc00
	s_addc_u32 s5, s5, 0
	global_load_ushort v103, v134, s[4:5]
	s_add_u32 s4, s4, 0xc00
	s_addc_u32 s5, s5, 0
	global_load_ushort v104, v134, s[4:5]
	s_add_u32 s4, s4, 0xc00
	s_addc_u32 s5, s5, 0
	global_load_ushort v105, v134, s[4:5]
	s_add_u32 s4, s4, 0xc00
	s_addc_u32 s5, s5, 0
	global_load_ushort v106, v134, s[4:5]
	s_add_u32 s4, s4, 0xc00
	s_addc_u32 s5, s5, 0
	global_load_ushort v107, v134, s[4:5]
	s_add_u32 s4, s4, 0xc00
	s_addc_u32 s5, s5, 0
	global_load_ushort v108, v134, s[4:5]
	s_add_u32 s4, s4, 0xc00
	s_addc_u32 s5, s5, 0
	global_load_ushort v109, v134, s[4:5]
	s_add_u32 s4, s4, 0xc00
	s_addc_u32 s5, s5, 0
	global_load_ushort v110, v134, s[4:5]
	s_add_u32 s4, s4, 0xc00
	s_addc_u32 s5, s5, 0
	global_load_ushort v111, v134, s[4:5]
	s_add_u32 s4, s4, 0xc00
	s_addc_u32 s5, s5, 0
	global_load_ushort v112, v134, s[4:5]
	s_add_u32 s4, s4, 0xc00
	s_addc_u32 s5, s5, 0
	global_load_ushort v113, v134, s[4:5]
	s_add_u32 s4, s4, 0xc00
	s_addc_u32 s5, s5, 0
	global_load_ushort v114, v134, s[4:5]
	s_add_u32 s4, s4, 0xc00
	s_addc_u32 s5, s5, 0
	global_load_ushort v115, v134, s[4:5]
	s_add_u32 s4, s4, 0xc00
	s_addc_u32 s5, s5, 0
	global_load_ushort v116, v134, s[4:5]
	s_add_u32 s4, s4, 0xc00
	s_addc_u32 s5, s5, 0
	global_load_ushort v117, v134, s[4:5]
	s_add_u32 s4, s4, 0xc00
	s_addc_u32 s5, s5, 0
	global_load_ushort v118, v134, s[4:5]
	s_add_u32 s4, s4, 0xc00
	s_addc_u32 s5, s5, 0
	global_load_ushort v119, v134, s[4:5]
	s_add_u32 s4, s4, 0xc00
	s_addc_u32 s5, s5, 0
	global_load_ushort v120, v134, s[4:5]
	s_add_u32 s4, s4, 0xc00
	s_addc_u32 s5, s5, 0
	global_load_ushort v121, v134, s[4:5]
	s_add_u32 s4, s4, 0xc00
	s_addc_u32 s5, s5, 0
	global_load_ushort v122, v134, s[4:5]
	s_add_u32 s4, s4, 0xc00
	s_addc_u32 s5, s5, 0
	global_load_ushort v123, v134, s[4:5]
	s_add_u32 s4, s4, 0xc00
	s_addc_u32 s5, s5, 0
	global_load_ushort v124, v151, s[4:5]
	v_bfe_u32 v255, v152, 6, 2
	v_and_b32_e32 v253, 15, v152
	v_lshl_add_u32 v255, v255, 4, v253
	v_add_u32_e32 v255, s56, v255
	v_lshlrev_b32_e32 v255, 2, v255
	global_load_dword v65, v255, s[24:25]
	global_load_dword v67, v255, s[24:25] offset:2048
	s_add_u32 s0, s24, 0x1000
	s_addc_u32 s1, s25, 0
	global_load_dword v68, v255, s[0:1]
	global_load_dword v70, v255, s[0:1] offset:2048
	global_load_dword v73, v255, s[26:27]
	s_lshl_b32 s0, s56, 8
	s_add_u32 s0, s0, 0x0
	s_add_u32 s4, s20, s0
	s_addc_u32 s5, s21, 0
	global_load_dwordx4 v[238:241], v251, s[4:5]
	global_load_dwordx4 v[242:245], v251, s[4:5] offset:64
	s_add_u32 s4, s4, 0x2000
	s_addc_u32 s5, s5, 0
	global_load_dwordx4 v[246:249], v251, s[4:5]
	global_load_dwordx4 v[194:197], v251, s[4:5] offset:64
	v_bfe_u32 v255, v152, 6, 2
	v_and_b32_e32 v253, 15, v152
	v_lshl_add_u32 v255, v255, 4, v253
	v_add_u32_e32 v255, s56, v255
	v_lshlrev_b32_e32 v255, 2, v255
	s_add_u32 s0, s28, 0x0
	s_addc_u32 s1, s29, 0
	global_load_dword v75, v255, s[0:1]
	s_add_u32 s0, s30, 0x0
	s_addc_u32 s1, s31, 0
	global_load_dword v84, v255, s[0:1]
	s_add_u32 s0, s36, 0x0
	s_addc_u32 s1, s37, 0
	global_load_dword v85, v255, s[0:1]
	s_barrier
; __device__ __forceinline__ float bf2f(u16 h) { return __uint_as_float(((unsigned)h) << 16); }
; __device__ __forceinline__ void lru_tile(const Params& P, int chunk, int head, int pass, char* smem_raw) {
;     ...
;     float uv[35];
; #pragma unroll
;     for (int i = 0; i < 35; ++i) {
;       const int rr = r - 2 + i;
;       uv[i] = (rr >= seq_lo && rr < seq_hi) ? bf2f(zu[(long)rr * 1536]) : 0.f;
;     }
;     __syncthreads();
; #pragma unroll
;     for (int i = 0; i < 32; ++i) {
;       const float v = cb + uv[i] * w0 + uv[i + 1] * w1 + uv[i + 2] * w2 + uv[i + 3] * w3;
;       sm_uc[(q * 32 + i) * LDSS + ch] = f2bf(v);
	s_waitcnt vmcnt(0)
	v_lshlrev_b32_e32 v90, 16, v90
	v_lshlrev_b32_e32 v91, 16, v91
	v_lshlrev_b32_e32 v92, 16, v92
	v_lshlrev_b32_e32 v93, 16, v93
	v_lshlrev_b32_e32 v94, 16, v94
	v_lshlrev_b32_e32 v95, 16, v95
	v_lshlrev_b32_e32 v96, 16, v96
	v_lshlrev_b32_e32 v97, 16, v97
	v_lshlrev_b32_e32 v98, 16, v98
	v_lshlrev_b32_e32 v99, 16, v99
	v_lshlrev_b32_e32 v100, 16, v100
	v_lshlrev_b32_e32 v101, 16, v101
	v_lshlrev_b32_e32 v102, 16, v102
	v_lshlrev_b32_e32 v103, 16, v103
	v_lshlrev_b32_e32 v104, 16, v104
	v_lshlrev_b32_e32 v105, 16, v105
	v_lshlrev_b32_e32 v106, 16, v106
	v_lshlrev_b32_e32 v107, 16, v107
	v_lshlrev_b32_e32 v108, 16, v108
	v_lshlrev_b32_e32 v109, 16, v109
	v_lshlrev_b32_e32 v110, 16, v110
	v_lshlrev_b32_e32 v111, 16, v111
	v_lshlrev_b32_e32 v112, 16, v112
	v_lshlrev_b32_e32 v113, 16, v113
	v_lshlrev_b32_e32 v114, 16, v114
	v_lshlrev_b32_e32 v115, 16, v115
	v_lshlrev_b32_e32 v116, 16, v116
	v_lshlrev_b32_e32 v117, 16, v117
	v_lshlrev_b32_e32 v118, 16, v118
	v_lshlrev_b32_e32 v119, 16, v119
	v_lshlrev_b32_e32 v120, 16, v120
	v_lshlrev_b32_e32 v121, 16, v121
	v_lshlrev_b32_e32 v122, 16, v122
	v_lshlrev_b32_e32 v123, 16, v123
	v_lshlrev_b32_e32 v124, 16, v124
	v_mul_f32_e32 v90, v90, v202
	v_mul_f32_e32 v91, v91, v202
	v_mul_f32_e32 v124, v124, v203
	v_fma_f32 v162, v90, v65, v73
	v_fma_f32 v162, v91, v67, v162
	v_fma_f32 v162, v92, v68, v162
	v_fma_f32 v162, v93, v70, v162
	v_fma_f32 v163, v91, v65, v73
	v_fma_f32 v163, v92, v67, v163
	v_fma_f32 v163, v93, v68, v163
	v_fma_f32 v163, v94, v70, v163
	v_fma_f32 v164, v92, v65, v73
	v_fma_f32 v164, v93, v67, v164
	v_fma_f32 v164, v94, v68, v164
	v_fma_f32 v164, v95, v70, v164
	v_fma_f32 v165, v93, v65, v73
	v_fma_f32 v165, v94, v67, v165
	v_fma_f32 v165, v95, v68, v165
	v_fma_f32 v165, v96, v70, v165
	v_fma_f32 v166, v94, v65, v73
	v_fma_f32 v166, v95, v67, v166
	v_fma_f32 v166, v96, v68, v166
	v_fma_f32 v166, v97, v70, v166
	v_fma_f32 v167, v95, v65, v73
	v_fma_f32 v167, v96, v67, v167
	v_fma_f32 v167, v97, v68, v167
	v_fma_f32 v167, v98, v70, v167
	v_fma_f32 v168, v96, v65, v73
	v_fma_f32 v168, v97, v67, v168
	v_fma_f32 v168, v98, v68, v168
	v_fma_f32 v168, v99, v70, v168
	v_fma_f32 v169, v97, v65, v73
	v_fma_f32 v169, v98, v67, v169
	v_fma_f32 v169, v99, v68, v169
	v_fma_f32 v169, v100, v70, v169
	v_fma_f32 v170, v98, v65, v73
	v_fma_f32 v170, v99, v67, v170
	v_fma_f32 v170, v100, v68, v170
	v_fma_f32 v170, v101, v70, v170
	v_fma_f32 v171, v99, v65, v73
	v_fma_f32 v171, v100, v67, v171
	v_fma_f32 v171, v101, v68, v171
	v_fma_f32 v171, v102, v70, v171
	v_fma_f32 v172, v100, v65, v73
	v_fma_f32 v172, v101, v67, v172
	v_fma_f32 v172, v102, v68, v172
	v_fma_f32 v172, v103, v70, v172
	v_fma_f32 v173, v101, v65, v73
	v_fma_f32 v173, v102, v67, v173
	v_fma_f32 v173, v103, v68, v173
	v_fma_f32 v173, v104, v70, v173
	v_fma_f32 v174, v102, v65, v73
	v_fma_f32 v174, v103, v67, v174
	v_fma_f32 v174, v104, v68, v174
	v_fma_f32 v174, v105, v70, v174
	v_fma_f32 v175, v103, v65, v73
	v_fma_f32 v175, v104, v67, v175
	v_fma_f32 v175, v105, v68, v175
	v_fma_f32 v175, v106, v70, v175
	v_fma_f32 v176, v104, v65, v73
	v_fma_f32 v176, v105, v67, v176
	v_fma_f32 v176, v106, v68, v176
	v_fma_f32 v176, v107, v70, v176
	v_fma_f32 v177, v105, v65, v73
	v_fma_f32 v177, v106, v67, v177
	v_fma_f32 v177, v107, v68, v177
	v_fma_f32 v177, v108, v70, v177
	v_fma_f32 v178, v106, v65, v73
	v_fma_f32 v178, v107, v67, v178
	v_fma_f32 v178, v108, v68, v178
	v_fma_f32 v178, v109, v70, v178
	v_fma_f32 v179, v107, v65, v73
	v_fma_f32 v179, v108, v67, v179
	v_fma_f32 v179, v109, v68, v179
	v_fma_f32 v179, v110, v70, v179
	v_fma_f32 v180, v108, v65, v73
	v_fma_f32 v180, v109, v67, v180
	v_fma_f32 v180, v110, v68, v180
	v_fma_f32 v180, v111, v70, v180
	v_fma_f32 v181, v109, v65, v73
	v_fma_f32 v181, v110, v67, v181
	v_fma_f32 v181, v111, v68, v181
	v_fma_f32 v181, v112, v70, v181
	v_fma_f32 v182, v110, v65, v73
	v_fma_f32 v182, v111, v67, v182
	v_fma_f32 v182, v112, v68, v182
	v_fma_f32 v182, v113, v70, v182
	v_fma_f32 v183, v111, v65, v73
	v_fma_f32 v183, v112, v67, v183
	v_fma_f32 v183, v113, v68, v183
	v_fma_f32 v183, v114, v70, v183
	v_fma_f32 v184, v112, v65, v73
	v_fma_f32 v184, v113, v67, v184
	v_fma_f32 v184, v114, v68, v184
	v_fma_f32 v184, v115, v70, v184
	v_fma_f32 v185, v113, v65, v73
	v_fma_f32 v185, v114, v67, v185
	v_fma_f32 v185, v115, v68, v185
	v_fma_f32 v185, v116, v70, v185
	v_fma_f32 v186, v114, v65, v73
	v_fma_f32 v186, v115, v67, v186
	v_fma_f32 v186, v116, v68, v186
	v_fma_f32 v186, v117, v70, v186
	v_fma_f32 v187, v115, v65, v73
	v_fma_f32 v187, v116, v67, v187
	v_fma_f32 v187, v117, v68, v187
	v_fma_f32 v187, v118, v70, v187
	v_fma_f32 v188, v116, v65, v73
	v_fma_f32 v188, v117, v67, v188
	v_fma_f32 v188, v118, v68, v188
	v_fma_f32 v188, v119, v70, v188
	v_fma_f32 v189, v117, v65, v73
	v_fma_f32 v189, v118, v67, v189
	v_fma_f32 v189, v119, v68, v189
	v_fma_f32 v189, v120, v70, v189
	v_fma_f32 v190, v118, v65, v73
	v_fma_f32 v190, v119, v67, v190
	v_fma_f32 v190, v120, v68, v190
	v_fma_f32 v190, v121, v70, v190
	v_fma_f32 v191, v119, v65, v73
	v_fma_f32 v191, v120, v67, v191
	v_fma_f32 v191, v121, v68, v191
	v_fma_f32 v191, v122, v70, v191
	v_fma_f32 v192, v120, v65, v73
	v_fma_f32 v192, v121, v67, v192
	v_fma_f32 v192, v122, v68, v192
	v_fma_f32 v192, v123, v70, v192
	v_fma_f32 v193, v121, v65, v73
	v_fma_f32 v193, v122, v67, v193
	v_fma_f32 v193, v123, v68, v193
	v_fma_f32 v193, v124, v70, v193
	v_cvt_pk_bf16_f32 v162, v162, v162
	v_cvt_pk_bf16_f32 v163, v163, v163
	v_cvt_pk_bf16_f32 v164, v164, v164
	v_cvt_pk_bf16_f32 v165, v165, v165
	v_cvt_pk_bf16_f32 v166, v166, v166
	v_cvt_pk_bf16_f32 v167, v167, v167
; __device__ __forceinline__ void lru_tile(const Params& P, int chunk, int head, int pass, char* smem_raw) {
;     ...
;     for (int i = 0; i < 32; ++i) {
;       const float v = cb + uv[i] * w0 + uv[i + 1] * w1 + uv[i + 2] * w2 + uv[i + 3] * w3;
;       sm_uc[(q * 32 + i) * LDSS + ch] = f2bf(v);
;     }
;   }
;   if (pass == 2 && tid < 128) {
;     const int d = tid >> 6;
;     float h = 0.f;
;     const float2* S = P.summ + (long)d * 264 * 512 + gch;
;     if (chunk < 256) {
;       const int b = chunk >> 6, j = chunk & 63;
;       if (d == 0) {
;         float2 s = S[(long)(256 + 2 * b) * 512]; h = s.x * h + s.y;
;         s = S[(long)(256 + 2 * b + 1) * 512]; h = s.x * h + s.y;
	v_cvt_pk_bf16_f32 v168, v168, v168
	v_cvt_pk_bf16_f32 v169, v169, v169
	v_cvt_pk_bf16_f32 v170, v170, v170
	v_cvt_pk_bf16_f32 v171, v171, v171
	v_cvt_pk_bf16_f32 v172, v172, v172
	v_cvt_pk_bf16_f32 v173, v173, v173
	v_cvt_pk_bf16_f32 v174, v174, v174
	v_cvt_pk_bf16_f32 v175, v175, v175
	v_cvt_pk_bf16_f32 v176, v176, v176
	v_cvt_pk_bf16_f32 v177, v177, v177
	v_cvt_pk_bf16_f32 v178, v178, v178
	v_cvt_pk_bf16_f32 v179, v179, v179
	v_cvt_pk_bf16_f32 v180, v180, v180
	v_cvt_pk_bf16_f32 v181, v181, v181
	v_cvt_pk_bf16_f32 v182, v182, v182
	v_cvt_pk_bf16_f32 v183, v183, v183
	v_cvt_pk_bf16_f32 v184, v184, v184
	v_cvt_pk_bf16_f32 v185, v185, v185
	v_cvt_pk_bf16_f32 v186, v186, v186
	v_cvt_pk_bf16_f32 v187, v187, v187
	v_cvt_pk_bf16_f32 v188, v188, v188
	v_cvt_pk_bf16_f32 v189, v189, v189
	v_cvt_pk_bf16_f32 v190, v190, v190
	v_cvt_pk_bf16_f32 v191, v191, v191
	v_cvt_pk_bf16_f32 v192, v192, v192
	v_cvt_pk_bf16_f32 v193, v193, v193
	ds_write_b16 v89, v162 offset:0
	ds_write_b16 v89, v163 offset:128
	ds_write_b16 v130, v164 offset:256
	ds_write_b16 v130, v165 offset:384
	ds_write_b16 v89, v166 offset:512
	ds_write_b16 v89, v167 offset:640
	ds_write_b16 v130, v168 offset:768
	ds_write_b16 v130, v169 offset:896
	ds_write_b16 v89, v170 offset:1024
	ds_write_b16 v89, v171 offset:1152
	ds_write_b16 v130, v172 offset:1280
	ds_write_b16 v130, v173 offset:1408
	ds_write_b16 v89, v174 offset:1536
	ds_write_b16 v89, v175 offset:1664
	ds_write_b16 v130, v176 offset:1792
	ds_write_b16 v130, v177 offset:1920
	ds_write_b16 v89, v178 offset:2048
	ds_write_b16 v89, v179 offset:2176
	ds_write_b16 v130, v180 offset:2304
	ds_write_b16 v130, v181 offset:2432
	ds_write_b16 v89, v182 offset:2560
	ds_write_b16 v89, v183 offset:2688
	ds_write_b16 v130, v184 offset:2816
	ds_write_b16 v130, v185 offset:2944
	ds_write_b16 v89, v186 offset:3072
	ds_write_b16 v89, v187 offset:3200
	ds_write_b16 v130, v188 offset:3328
	ds_write_b16 v130, v189 offset:3456
	ds_write_b16 v89, v190 offset:3584
	ds_write_b16 v89, v191 offset:3712
	ds_write_b16 v130, v192 offset:3840
	ds_write_b16 v130, v193 offset:3968
	v_lshlrev_b32_e32 v162, 16, v162
	v_lshlrev_b32_e32 v163, 16, v163
	v_lshlrev_b32_e32 v164, 16, v164
	v_lshlrev_b32_e32 v165, 16, v165
	v_lshlrev_b32_e32 v166, 16, v166
	v_lshlrev_b32_e32 v167, 16, v167
	v_lshlrev_b32_e32 v168, 16, v168
	v_lshlrev_b32_e32 v169, 16, v169
	v_lshlrev_b32_e32 v170, 16, v170
	v_lshlrev_b32_e32 v171, 16, v171
	v_lshlrev_b32_e32 v172, 16, v172
	v_lshlrev_b32_e32 v173, 16, v173
	v_lshlrev_b32_e32 v174, 16, v174
	v_lshlrev_b32_e32 v175, 16, v175
	v_lshlrev_b32_e32 v176, 16, v176
	v_lshlrev_b32_e32 v177, 16, v177
	v_lshlrev_b32_e32 v178, 16, v178
	v_lshlrev_b32_e32 v179, 16, v179
	v_lshlrev_b32_e32 v180, 16, v180
	v_lshlrev_b32_e32 v181, 16, v181
	v_lshlrev_b32_e32 v182, 16, v182
	v_lshlrev_b32_e32 v183, 16, v183
	v_lshlrev_b32_e32 v184, 16, v184
	v_lshlrev_b32_e32 v185, 16, v185
	v_lshlrev_b32_e32 v186, 16, v186
	v_lshlrev_b32_e32 v187, 16, v187
	v_lshlrev_b32_e32 v188, 16, v188
	v_lshlrev_b32_e32 v189, 16, v189
	v_lshlrev_b32_e32 v190, 16, v190
	v_lshlrev_b32_e32 v191, 16, v191
	v_lshlrev_b32_e32 v192, 16, v192
	v_lshlrev_b32_e32 v193, 16, v193
	s_waitcnt lgkmcnt(0)
	s_barrier
	v_mov_b32_e32 v65, 0
	s_lshl_b32 s0, s56, 3
	s_add_u32 s0, s0, 0x0
	s_add_u32 s4, s18, s0
	s_addc_u32 s5, s19, 0
	s_cmp_lt_u32 s71, 256
	s_cbranch_scc0 .Lmy_lrub_lb0_ctx
; __device__ __forceinline__ void lru_tile(const Params& P, int chunk, int head, int pass, char* smem_raw) {
;     ...
;       const int b = chunk >> 6, j = chunk & 63;
;       if (d == 0) {
;         float2 s = S[(long)(256 + 2 * b) * 512]; h = s.x * h + s.y;
;         s = S[(long)(256 + 2 * b + 1) * 512]; h = s.x * h + s.y;
;         int i = 0;
;         for (; i + 8 <= j; i += 8) {
;           float2 sv[8];
; #pragma unroll
;           for (int u = 0; u < 8; ++u) sv[u] = S[(long)(b * 64 + i + u) * 512];
; #pragma unroll
;           for (int u = 0; u < 8; ++u) h = sv[u].x * h + sv[u].y;
;         }
;         for (; i < j; ++i) { s = S[(long)(b * 64 + i) * 512]; h = s.x * h + s.y; }
	s_lshr_b32 s0, s71, 6
	s_lshl_b32 s1, s0, 1
	s_add_u32 s1, s1, 256
	s_add_u32 s60, s1, 0
	s_lshl_b32 s60, s60, 12
	s_add_u32 s60, s4, s60
	s_addc_u32 s61, s5, 0
	global_load_dwordx2 v[0:1], v250, s[60:61]
	s_add_u32 s60, s1, 1
	s_lshl_b32 s60, s60, 12
	s_add_u32 s60, s4, s60
	s_addc_u32 s61, s5, 0
	global_load_dwordx2 v[2:3], v250, s[60:61]
	s_lshl_b32 s0, s0, 6
	v_bfe_u32 v150, v152, 4, 2
	s_mov_b32 s1, s57
	v_lshl_add_u32 v136, v150, 16, v250
	s_lshl_b32 s60, s0, 12
	v_lshlrev_b32_e32 v150, 4, v150
	v_sub_u32_e32 v150, s1, v150
	s_add_u32 s60, s4, s60
	s_addc_u32 s61, s5, 0
	global_load_dwordx2 v[4:5], v136, s[60:61]
	s_add_u32 s60, s60, 0x1000
	s_addc_u32 s61, s61, 0
	global_load_dwordx2 v[6:7], v136, s[60:61]
	s_add_u32 s60, s60, 0x1000
	s_addc_u32 s61, s61, 0
	global_load_dwordx2 v[8:9], v136, s[60:61]
	s_add_u32 s60, s60, 0x1000
	s_addc_u32 s61, s61, 0
	global_load_dwordx2 v[10:11], v136, s[60:61]
	s_add_u32 s60, s60, 0x1000
	s_addc_u32 s61, s61, 0
	global_load_dwordx2 v[12:13], v136, s[60:61]
	s_add_u32 s60, s60, 0x1000
	s_addc_u32 s61, s61, 0
	global_load_dwordx2 v[14:15], v136, s[60:61]
	s_add_u32 s60, s60, 0x1000
	s_addc_u32 s61, s61, 0
	global_load_dwordx2 v[16:17], v136, s[60:61]
	s_add_u32 s60, s60, 0x1000
	s_addc_u32 s61, s61, 0
	global_load_dwordx2 v[18:19], v136, s[60:61]
	s_add_u32 s60, s60, 0x1000
	s_addc_u32 s61, s61, 0
	global_load_dwordx2 v[20:21], v136, s[60:61]
	s_add_u32 s60, s60, 0x1000
	s_addc_u32 s61, s61, 0
	global_load_dwordx2 v[22:23], v136, s[60:61]
	s_add_u32 s60, s60, 0x1000
	s_addc_u32 s61, s61, 0
	global_load_dwordx2 v[24:25], v136, s[60:61]
	s_add_u32 s60, s60, 0x1000
	s_addc_u32 s61, s61, 0
	global_load_dwordx2 v[26:27], v136, s[60:61]
	s_add_u32 s60, s60, 0x1000
	s_addc_u32 s61, s61, 0
	global_load_dwordx2 v[28:29], v136, s[60:61]
	s_add_u32 s60, s60, 0x1000
	s_addc_u32 s61, s61, 0
	global_load_dwordx2 v[30:31], v136, s[60:61]
	s_add_u32 s60, s60, 0x1000
	s_addc_u32 s61, s61, 0
	global_load_dwordx2 v[32:33], v136, s[60:61]
	s_add_u32 s60, s60, 0x1000
	s_addc_u32 s61, s61, 0
	global_load_dwordx2 v[34:35], v136, s[60:61]
	s_waitcnt vmcnt(16)
	v_fma_f32 v65, v0, v65, v1
	v_fma_f32 v65, v2, v65, v3
	v_mov_b32_e32 v253, 1.0
	v_mov_b32_e32 v254, 0
	s_waitcnt vmcnt(0)
	v_cmp_lt_i32_e32 vcc, 0, v150
	s_nop 1
	v_cndmask_b32_e32 v4, 1.0, v4, vcc
	v_cndmask_b32_e32 v5, 0, v5, vcc
	v_fma_f32 v254, v4, v254, v5
	v_mul_f32_e32 v253, v253, v4
	v_cmp_lt_i32_e32 vcc, 1, v150
	s_nop 1
	v_cndmask_b32_e32 v6, 1.0, v6, vcc
	v_cndmask_b32_e32 v7, 0, v7, vcc
	v_fma_f32 v254, v6, v254, v7
	v_mul_f32_e32 v253, v253, v6
	v_cmp_lt_i32_e32 vcc, 2, v150
	s_nop 1
	v_cndmask_b32_e32 v8, 1.0, v8, vcc
	v_cndmask_b32_e32 v9, 0, v9, vcc
	v_fma_f32 v254, v8, v254, v9
	v_mul_f32_e32 v253, v253, v8
	v_cmp_lt_i32_e32 vcc, 3, v150
	s_nop 1
	v_cndmask_b32_e32 v10, 1.0, v10, vcc
	v_cndmask_b32_e32 v11, 0, v11, vcc
	v_fma_f32 v254, v10, v254, v11
	v_mul_f32_e32 v253, v253, v10
	v_cmp_lt_i32_e32 vcc, 4, v150
	s_nop 1
	v_cndmask_b32_e32 v12, 1.0, v12, vcc
	v_cndmask_b32_e32 v13, 0, v13, vcc
	v_fma_f32 v254, v12, v254, v13
	v_mul_f32_e32 v253, v253, v12
	v_cmp_lt_i32_e32 vcc, 5, v150
	s_nop 1
	v_cndmask_b32_e32 v14, 1.0, v14, vcc
	v_cndmask_b32_e32 v15, 0, v15, vcc
	v_fma_f32 v254, v14, v254, v15
	v_mul_f32_e32 v253, v253, v14
	v_cmp_lt_i32_e32 vcc, 6, v150
	s_nop 1
	v_cndmask_b32_e32 v16, 1.0, v16, vcc
	v_cndmask_b32_e32 v17, 0, v17, vcc
	v_fma_f32 v254, v16, v254, v17
	v_mul_f32_e32 v253, v253, v16
	v_cmp_lt_i32_e32 vcc, 7, v150
	s_nop 1
	v_cndmask_b32_e32 v18, 1.0, v18, vcc
	v_cndmask_b32_e32 v19, 0, v19, vcc
	v_fma_f32 v254, v18, v254, v19
	v_mul_f32_e32 v253, v253, v18
	v_cmp_lt_i32_e32 vcc, 8, v150
	s_nop 1
	v_cndmask_b32_e32 v20, 1.0, v20, vcc
	v_cndmask_b32_e32 v21, 0, v21, vcc
	v_fma_f32 v254, v20, v254, v21
	v_mul_f32_e32 v253, v253, v20
	v_cmp_lt_i32_e32 vcc, 9, v150
	s_nop 1
	v_cndmask_b32_e32 v22, 1.0, v22, vcc
	v_cndmask_b32_e32 v23, 0, v23, vcc
	v_fma_f32 v254, v22, v254, v23
	v_mul_f32_e32 v253, v253, v22
	v_cmp_lt_i32_e32 vcc, 10, v150
	s_nop 1
	v_cndmask_b32_e32 v24, 1.0, v24, vcc
	v_cndmask_b32_e32 v25, 0, v25, vcc
	v_fma_f32 v254, v24, v254, v25
	v_mul_f32_e32 v253, v253, v24
	v_cmp_lt_i32_e32 vcc, 11, v150
	s_nop 1
	v_cndmask_b32_e32 v26, 1.0, v26, vcc
	v_cndmask_b32_e32 v27, 0, v27, vcc
	v_fma_f32 v254, v26, v254, v27
	v_mul_f32_e32 v253, v253, v26
	v_cmp_lt_i32_e32 vcc, 12, v150
	s_nop 1
	v_cndmask_b32_e32 v28, 1.0, v28, vcc
	v_cndmask_b32_e32 v29, 0, v29, vcc
	v_fma_f32 v254, v28, v254, v29
	v_mul_f32_e32 v253, v253, v28
	v_cmp_lt_i32_e32 vcc, 13, v150
	s_nop 1
	v_cndmask_b32_e32 v30, 1.0, v30, vcc
	v_cndmask_b32_e32 v31, 0, v31, vcc
	v_fma_f32 v254, v30, v254, v31
	v_mul_f32_e32 v253, v253, v30
	v_cmp_lt_i32_e32 vcc, 14, v150
	s_nop 1
	v_cndmask_b32_e32 v32, 1.0, v32, vcc
	v_cndmask_b32_e32 v33, 0, v33, vcc
	v_fma_f32 v254, v32, v254, v33
	v_mul_f32_e32 v253, v253, v32
	v_cmp_lt_i32_e32 vcc, 15, v150
	s_nop 1
	v_cndmask_b32_e32 v34, 1.0, v34, vcc
	v_cndmask_b32_e32 v35, 0, v35, vcc
	v_fma_f32 v254, v34, v254, v35
	v_mul_f32_e32 v253, v253, v34
	v_mov_b32_e32 v138, v253
	v_mov_b32_e32 v139, v253
	s_nop 1
	v_permlane16_swap_b32_e32 v138, v139
	v_mov_b32_e32 v140, v138
	v_mov_b32_e32 v141, v139
	s_nop 1
	v_permlane32_swap_b32_e32 v138, v140
	v_permlane32_swap_b32_e32 v139, v141
	v_mov_b32_e32 v198, v254
	v_mov_b32_e32 v199, v254
	s_nop 1
	v_permlane16_swap_b32_e32 v198, v199
	v_mov_b32_e32 v200, v198
	v_mov_b32_e32 v201, v199
	s_nop 1
	v_permlane32_swap_b32_e32 v198, v200
	v_permlane32_swap_b32_e32 v199, v201
	v_fma_f32 v65, v138, v65, v198
	v_fma_f32 v65, v139, v65, v199
	v_fma_f32 v65, v140, v65, v200
	v_fma_f32 v65, v141, v65, v201
	s_branch .Lmy_lrub_lb0_done

; __device__ __forceinline__ void lru_tile(const Params& P, int chunk, int head, int pass, char* smem_raw) {
;     ...
;       } else {
;         float2 s = S[(long)(256 + 2 * b + 1) * 512]; h = s.x * h + s.y;
;         s = S[(long)(256 + 2 * b) * 512]; h = s.x * h + s.y;
;         int i = 63;
;         for (; i - 8 >= j; i -= 8) {
;           float2 sv[8];
; #pragma unroll
;           for (int u = 0; u < 8; ++u) sv[u] = S[(long)(b * 64 + i - u) * 512];
; #pragma unroll
;           for (int u = 0; u < 8; ++u) h = sv[u].x * h + sv[u].y;
;         }
;         for (; i > j; --i) { s = S[(long)(b * 64 + i) * 512]; h = s.x * h + s.y; }
;       }
.Lmy_lrub_lb0_done:
	v_mov_b32_e32 v67, 0
	s_lshl_b32 s0, s56, 3
	s_add_u32 s0, s0, 0x108000
	s_add_u32 s4, s18, s0
	s_addc_u32 s5, s19, 0
	s_cmp_lt_u32 s71, 256
	s_cbranch_scc0 .Lmy_lrub_lb1_ctx
	s_lshr_b32 s0, s71, 6
	s_lshl_b32 s1, s0, 1
	s_add_u32 s1, s1, 256
	s_add_u32 s60, s1, 1
	s_lshl_b32 s60, s60, 12
	s_add_u32 s60, s4, s60
	s_addc_u32 s61, s5, 0
	global_load_dwordx2 v[0:1], v250, s[60:61]
	s_add_u32 s60, s1, 0
	s_lshl_b32 s60, s60, 12
	s_add_u32 s60, s4, s60
	s_addc_u32 s61, s5, 0
	global_load_dwordx2 v[2:3], v250, s[60:61]
	s_lshl_b32 s0, s0, 6
	v_bfe_u32 v150, v152, 4, 2
	s_sub_u32 s1, 63, s57
	v_sub_u32_e32 v136, 3, v150
	v_lshl_add_u32 v136, v136, 16, v250
	s_add_u32 s60, s0, 15
	s_lshl_b32 s60, s60, 12
	v_lshlrev_b32_e32 v150, 4, v150
	v_sub_u32_e32 v150, s1, v150
	s_add_u32 s60, s4, s60
	s_addc_u32 s61, s5, 0
	global_load_dwordx2 v[4:5], v136, s[60:61]
	s_sub_u32 s60, s60, 0x1000
	s_subb_u32 s61, s61, 0
	global_load_dwordx2 v[6:7], v136, s[60:61]
	s_sub_u32 s60, s60, 0x1000
	s_subb_u32 s61, s61, 0
	global_load_dwordx2 v[8:9], v136, s[60:61]
	s_sub_u32 s60, s60, 0x1000
	s_subb_u32 s61, s61, 0
	global_load_dwordx2 v[10:11], v136, s[60:61]
	s_sub_u32 s60, s60, 0x1000
	s_subb_u32 s61, s61, 0
	global_load_dwordx2 v[12:13], v136, s[60:61]
	s_sub_u32 s60, s60, 0x1000
	s_subb_u32 s61, s61, 0
	global_load_dwordx2 v[14:15], v136, s[60:61]
	s_sub_u32 s60, s60, 0x1000
	s_subb_u32 s61, s61, 0
	global_load_dwordx2 v[16:17], v136, s[60:61]
	s_sub_u32 s60, s60, 0x1000
	s_subb_u32 s61, s61, 0
	global_load_dwordx2 v[18:19], v136, s[60:61]
	s_sub_u32 s60, s60, 0x1000
	s_subb_u32 s61, s61, 0
	global_load_dwordx2 v[20:21], v136, s[60:61]
	s_sub_u32 s60, s60, 0x1000
	s_subb_u32 s61, s61, 0
	global_load_dwordx2 v[22:23], v136, s[60:61]
	s_sub_u32 s60, s60, 0x1000
	s_subb_u32 s61, s61, 0
	global_load_dwordx2 v[24:25], v136, s[60:61]
	s_sub_u32 s60, s60, 0x1000
	s_subb_u32 s61, s61, 0
	global_load_dwordx2 v[26:27], v136, s[60:61]
	s_sub_u32 s60, s60, 0x1000
	s_subb_u32 s61, s61, 0
	global_load_dwordx2 v[28:29], v136, s[60:61]
	s_sub_u32 s60, s60, 0x1000
	s_subb_u32 s61, s61, 0
	global_load_dwordx2 v[30:31], v136, s[60:61]
	s_sub_u32 s60, s60, 0x1000
	s_subb_u32 s61, s61, 0
	global_load_dwordx2 v[32:33], v136, s[60:61]
	s_sub_u32 s60, s60, 0x1000
	s_subb_u32 s61, s61, 0
	global_load_dwordx2 v[34:35], v136, s[60:61]
	s_waitcnt vmcnt(16)
	v_fma_f32 v67, v0, v67, v1
	v_fma_f32 v67, v2, v67, v3
	v_mov_b32_e32 v253, 1.0
	v_mov_b32_e32 v254, 0
	s_waitcnt vmcnt(0)
	v_cmp_lt_i32_e32 vcc, 0, v150
	s_nop 1
	v_cndmask_b32_e32 v4, 1.0, v4, vcc
	v_cndmask_b32_e32 v5, 0, v5, vcc
	v_fma_f32 v254, v4, v254, v5
	v_mul_f32_e32 v253, v253, v4
	v_cmp_lt_i32_e32 vcc, 1, v150
	s_nop 1
	v_cndmask_b32_e32 v6, 1.0, v6, vcc
	v_cndmask_b32_e32 v7, 0, v7, vcc
	v_fma_f32 v254, v6, v254, v7
	v_mul_f32_e32 v253, v253, v6
	v_cmp_lt_i32_e32 vcc, 2, v150
	s_nop 1
	v_cndmask_b32_e32 v8, 1.0, v8, vcc
	v_cndmask_b32_e32 v9, 0, v9, vcc
	v_fma_f32 v254, v8, v254, v9
	v_mul_f32_e32 v253, v253, v8
	v_cmp_lt_i32_e32 vcc, 3, v150
	s_nop 1
	v_cndmask_b32_e32 v10, 1.0, v10, vcc
	v_cndmask_b32_e32 v11, 0, v11, vcc
	v_fma_f32 v254, v10, v254, v11
	v_mul_f32_e32 v253, v253, v10
	v_cmp_lt_i32_e32 vcc, 4, v150
	s_nop 1
	v_cndmask_b32_e32 v12, 1.0, v12, vcc
	v_cndmask_b32_e32 v13, 0, v13, vcc
	v_fma_f32 v254, v12, v254, v13
	v_mul_f32_e32 v253, v253, v12
	v_cmp_lt_i32_e32 vcc, 5, v150
	s_nop 1
	v_cndmask_b32_e32 v14, 1.0, v14, vcc
	v_cndmask_b32_e32 v15, 0, v15, vcc
	v_fma_f32 v254, v14, v254, v15
	v_mul_f32_e32 v253, v253, v14
	v_cmp_lt_i32_e32 vcc, 6, v150
	s_nop 1
	v_cndmask_b32_e32 v16, 1.0, v16, vcc
	v_cndmask_b32_e32 v17, 0, v17, vcc
	v_fma_f32 v254, v16, v254, v17
	v_mul_f32_e32 v253, v253, v16
	v_cmp_lt_i32_e32 vcc, 7, v150
	s_nop 1
	v_cndmask_b32_e32 v18, 1.0, v18, vcc
	v_cndmask_b32_e32 v19, 0, v19, vcc
	v_fma_f32 v254, v18, v254, v19
	v_mul_f32_e32 v253, v253, v18
	v_cmp_lt_i32_e32 vcc, 8, v150
	s_nop 1
	v_cndmask_b32_e32 v20, 1.0, v20, vcc
	v_cndmask_b32_e32 v21, 0, v21, vcc
	v_fma_f32 v254, v20, v254, v21
	v_mul_f32_e32 v253, v253, v20
	v_cmp_lt_i32_e32 vcc, 9, v150
	s_nop 1
	v_cndmask_b32_e32 v22, 1.0, v22, vcc
	v_cndmask_b32_e32 v23, 0, v23, vcc
	v_fma_f32 v254, v22, v254, v23
	v_mul_f32_e32 v253, v253, v22
	v_cmp_lt_i32_e32 vcc, 10, v150
	s_nop 1
	v_cndmask_b32_e32 v24, 1.0, v24, vcc
	v_cndmask_b32_e32 v25, 0, v25, vcc
	v_fma_f32 v254, v24, v254, v25
	v_mul_f32_e32 v253, v253, v24
	v_cmp_lt_i32_e32 vcc, 11, v150
	s_nop 1
	v_cndmask_b32_e32 v26, 1.0, v26, vcc
	v_cndmask_b32_e32 v27, 0, v27, vcc
	v_fma_f32 v254, v26, v254, v27
	v_mul_f32_e32 v253, v253, v26
	v_cmp_lt_i32_e32 vcc, 12, v150
	s_nop 1
	v_cndmask_b32_e32 v28, 1.0, v28, vcc
	v_cndmask_b32_e32 v29, 0, v29, vcc
	v_fma_f32 v254, v28, v254, v29
	v_mul_f32_e32 v253, v253, v28
	v_cmp_lt_i32_e32 vcc, 13, v150
	s_nop 1
	v_cndmask_b32_e32 v30, 1.0, v30, vcc
	v_cndmask_b32_e32 v31, 0, v31, vcc
	v_fma_f32 v254, v30, v254, v31
	v_mul_f32_e32 v253, v253, v30
	v_cmp_lt_i32_e32 vcc, 14, v150
	s_nop 1
	v_cndmask_b32_e32 v32, 1.0, v32, vcc
	v_cndmask_b32_e32 v33, 0, v33, vcc
	v_fma_f32 v254, v32, v254, v33
	v_mul_f32_e32 v253, v253, v32
	v_cmp_lt_i32_e32 vcc, 15, v150
	s_nop 1
	v_cndmask_b32_e32 v34, 1.0, v34, vcc
	v_cndmask_b32_e32 v35, 0, v35, vcc
	v_fma_f32 v254, v34, v254, v35
	v_mul_f32_e32 v253, v253, v34
	v_mov_b32_e32 v138, v253
	v_mov_b32_e32 v139, v253
	s_nop 1
	v_permlane16_swap_b32_e32 v138, v139
	v_mov_b32_e32 v140, v138
	v_mov_b32_e32 v141, v139
	s_nop 1
	v_permlane32_swap_b32_e32 v138, v140
	v_permlane32_swap_b32_e32 v139, v141
	v_mov_b32_e32 v198, v254
	v_mov_b32_e32 v199, v254
	s_nop 1
	v_permlane16_swap_b32_e32 v198, v199
	v_mov_b32_e32 v200, v198
	v_mov_b32_e32 v201, v199
	s_nop 1
	v_permlane32_swap_b32_e32 v198, v200
	v_permlane32_swap_b32_e32 v199, v201
	v_fma_f32 v67, v138, v67, v198
	v_fma_f32 v67, v139, v67, v199
	v_fma_f32 v67, v140, v67, v200
	v_fma_f32 v67, v141, v67, v201
	s_branch .Lmy_lrub_lb1_done

; __device__ __forceinline__ float bf2f(u16 h) { return __uint_as_float(((unsigned)h) << 16); }
; __device__ __forceinline__ void lru_tile(const Params& P, int chunk, int head, int pass, char* smem_raw) {
;     ...
;       *reinterpret_cast<uint4*>(&sm_w[rowi * LDSS + kg * 8]) = ldg16(P.wg + ((long)(d * 8 + head) * 128 + rowi) * 64 + kg * 8);
;     }
;     float ba[4], bi[4], c8[4];
; #pragma unroll
;     for (int tc = 0; tc < 4; ++tc) {
;       const int cidx = d * 512 + head * 64 + 16 * tc + (lane & 15);
;       ba[tc] = P.b_a[cidx] * -1.4426950408889634f; bi[tc] = P.b_i[cidx] * -1.4426950408889634f;
;       const float nl = -P.lam[cidx];
;       const float e_ = __expf(nl);
;       const float sp = (nl > 20.f) ? nl
;                      : (e_ < 0.03f ? e_ * (1.f - e_ * (0.5f - e_ * (0.33333334f - 0.25f * e_))) : __logf(1.f + e_));
;       c8[tc] = 8.f * 1.4426950408889634f * sp;
;     }
;     __syncthreads();
;     float cA = 1.f, cB = (pass == 2) ? sm_init[d * 64 + ch] : 0.f;
;     for (int sbi = 0; sbi < 2; ++sbi) {
;       const int sb = (d == 0) ? sbi : 1 - sbi;
;       f32x4 acc[8];
; #pragma unroll
;       for (int t = 0; t < 8; ++t) acc[t] = f32x4{0.f, 0.f, 0.f, 0.f};
; #pragma unroll
;       for (int s = 0; s < 2; ++s) {
;         const bf16x8 af = *reinterpret_cast<const bf16x8*>(&sm_uc[(sb * 64 + wid * 16 + (lane & 15)) * LDSS + s * 32 + (lane >> 4) * 8]);
; #pragma unroll
;         for (int t = 0; t < 8; ++t) {
;           const bf16x8 bfr = *reinterpret_cast<const bf16x8*>(&sm_w[(t * 16 + (lane & 15)) * LDSS + s * 32 + (lane >> 4) * 8]);
;           acc[t] = __builtin_amdgcn_mfma_f32_16x16x32_bf16(af, bfr, acc[t], 0, 0, 0);
;         }
;       }
; #pragma unroll
;       for (int tc = 0; tc < 4; ++tc)
; #pragma unroll
;         for (int reg = 0; reg < 4; ++reg) {
;           const int tl = wid * 16 + (lane >> 4) * 4 + reg;
;           const int c = 16 * tc + (lane & 15);
;           const float r = __builtin_amdgcn_rcpf(1.f + __builtin_amdgcn_exp2f(acc[tc][reg] + ba[tc]));
;           const float ii = __builtin_amdgcn_rcpf(1.f + __builtin_amdgcn_exp2f(acc[tc + 4][reg] + bi[tc]));
;           const float la = -c8[tc] * r;
;           const float a = __builtin_amdgcn_exp2f(la);
;           const float ucv = bf2f(sm_uc[(sb * 64 + tl) * LDSS + c]);
;           const float bt = __builtin_amdgcn_sqrtf(fmaxf(1.f - a * a, 0.f)) * (ii * ucv);
.Lmy_lrub_lb1_done:
	ds_read_b128 v[76:79], v131 offset:0
	ds_read_b128 v[80:83], v133 offset:0
	ds_read_b128 v[122:125], v131 offset:512
	ds_read_b128 v[126:129], v133 offset:512
	s_waitcnt lgkmcnt(3)
	v_mfma_f32_16x16x32_bf16 v[0:3], v[76:79], v[238:241], 0
	v_mfma_f32_16x16x32_bf16 v[90:93], v[76:79], v[246:249], 0
	ds_read_b128 v[76:79], v131 offset:1024
	s_waitcnt lgkmcnt(3)
	v_mfma_f32_16x16x32_bf16 v[0:3], v[80:83], v[242:245], v[0:3]
	v_mfma_f32_16x16x32_bf16 v[90:93], v[80:83], v[194:197], v[90:93]
	ds_read_b128 v[80:83], v133 offset:1024
	s_waitcnt lgkmcnt(3)
	v_mfma_f32_16x16x32_bf16 v[4:7], v[122:125], v[238:241], 0
	v_mfma_f32_16x16x32_bf16 v[94:97], v[122:125], v[246:249], 0
	ds_read_b128 v[122:125], v131 offset:1536
	s_waitcnt lgkmcnt(3)
	v_mfma_f32_16x16x32_bf16 v[4:7], v[126:129], v[242:245], v[4:7]
	v_mfma_f32_16x16x32_bf16 v[94:97], v[126:129], v[194:197], v[94:97]
	ds_read_b128 v[126:129], v133 offset:1536
	s_waitcnt lgkmcnt(3)
	v_mfma_f32_16x16x32_bf16 v[8:11], v[76:79], v[238:241], 0
	v_mfma_f32_16x16x32_bf16 v[98:101], v[76:79], v[246:249], 0
	ds_read_b128 v[76:79], v131 offset:2048
	s_waitcnt lgkmcnt(3)
	v_mfma_f32_16x16x32_bf16 v[8:11], v[80:83], v[242:245], v[8:11]
	v_mfma_f32_16x16x32_bf16 v[98:101], v[80:83], v[194:197], v[98:101]
	ds_read_b128 v[80:83], v133 offset:2048
	s_waitcnt lgkmcnt(3)
	v_mfma_f32_16x16x32_bf16 v[12:15], v[122:125], v[238:241], 0
	v_mfma_f32_16x16x32_bf16 v[102:105], v[122:125], v[246:249], 0
	ds_read_b128 v[122:125], v131 offset:2560
	s_waitcnt lgkmcnt(3)
	v_mfma_f32_16x16x32_bf16 v[12:15], v[126:129], v[242:245], v[12:15]
	v_mfma_f32_16x16x32_bf16 v[102:105], v[126:129], v[194:197], v[102:105]
	ds_read_b128 v[126:129], v133 offset:2560
	s_waitcnt lgkmcnt(3)
	v_mfma_f32_16x16x32_bf16 v[16:19], v[76:79], v[238:241], 0
	v_mfma_f32_16x16x32_bf16 v[106:109], v[76:79], v[246:249], 0
	ds_read_b128 v[76:79], v131 offset:3072
	s_waitcnt lgkmcnt(3)
	v_mfma_f32_16x16x32_bf16 v[16:19], v[80:83], v[242:245], v[16:19]
	v_mfma_f32_16x16x32_bf16 v[106:109], v[80:83], v[194:197], v[106:109]
	ds_read_b128 v[80:83], v133 offset:3072
	s_waitcnt lgkmcnt(3)
	v_mfma_f32_16x16x32_bf16 v[20:23], v[122:125], v[238:241], 0
	v_mfma_f32_16x16x32_bf16 v[110:113], v[122:125], v[246:249], 0
	ds_read_b128 v[122:125], v131 offset:3584
	s_waitcnt lgkmcnt(3)
	v_mfma_f32_16x16x32_bf16 v[20:23], v[126:129], v[242:245], v[20:23]
	v_mfma_f32_16x16x32_bf16 v[110:113], v[126:129], v[194:197], v[110:113]
	ds_read_b128 v[126:129], v133 offset:3584
	s_waitcnt lgkmcnt(3)
	v_mfma_f32_16x16x32_bf16 v[24:27], v[76:79], v[238:241], 0
	v_mfma_f32_16x16x32_bf16 v[114:117], v[76:79], v[246:249], 0
	s_waitcnt lgkmcnt(2)
	v_mfma_f32_16x16x32_bf16 v[24:27], v[80:83], v[242:245], v[24:27]
	v_mfma_f32_16x16x32_bf16 v[114:117], v[80:83], v[194:197], v[114:117]
	s_waitcnt lgkmcnt(1)
	v_mfma_f32_16x16x32_bf16 v[28:31], v[122:125], v[238:241], 0
	v_mfma_f32_16x16x32_bf16 v[118:121], v[122:125], v[246:249], 0
	s_waitcnt lgkmcnt(0)
	v_mfma_f32_16x16x32_bf16 v[28:31], v[126:129], v[242:245], v[28:31]
	v_mfma_f32_16x16x32_bf16 v[118:121], v[126:129], v[194:197], v[118:121]
	s_lshl_b32 s0, s56, 8
	s_add_u32 s0, s0, 0x20000
	s_add_u32 s4, s20, s0
	s_addc_u32 s5, s21, 0
	global_load_dwordx4 v[238:241], v251, s[4:5]
	global_load_dwordx4 v[242:245], v251, s[4:5] offset:64
	s_add_u32 s4, s4, 0x2000
	s_addc_u32 s5, s5, 0
	global_load_dwordx4 v[246:249], v251, s[4:5]
	global_load_dwordx4 v[194:197], v251, s[4:5] offset:64
	v_bfe_u32 v255, v152, 6, 2
	v_and_b32_e32 v253, 15, v152
	v_lshl_add_u32 v255, v255, 4, v253
	v_add_u32_e32 v255, s56, v255
	v_lshlrev_b32_e32 v255, 2, v255
	s_add_u32 s0, s28, 0x800
	s_addc_u32 s1, s29, 0
	global_load_dword v68, v255, s[0:1]
	s_add_u32 s0, s30, 0x800
	s_addc_u32 s1, s31, 0
	global_load_dword v70, v255, s[0:1]
	s_add_u32 s0, s36, 0x800
	s_addc_u32 s1, s37, 0
	global_load_dword v73, v255, s[0:1]
	v_mul_f32_e32 v75, 0xbfb8aa3b, v75
	v_mul_f32_e32 v84, 0xbfb8aa3b, v84
	v_sub_f32_e32 v138, 0, v85
	v_mul_f32_e32 v139, 0x3fb8aa3b, v138
	v_exp_f32_e32 v139, v139
	v_mul_f32_e32 v140, 0xbe800000, v139
	v_add_f32_e32 v140, 0x3eaaaaab, v140
	v_fma_f32 v140, -v139, v140, 0.5
	v_fma_f32 v140, -v139, v140, 1.0
	v_mul_f32_e32 v140, v139, v140
	v_add_f32_e32 v141, 1.0, v139
	v_log_f32_e32 v141, v141
	v_mov_b32_e32 v255, 0x3cf5c28f
	v_mul_f32_e32 v141, 0x3f317218, v141
	v_cmp_gt_f32_e32 vcc, v255, v139
	s_nop 1
	v_cndmask_b32_e32 v140, v141, v140, vcc
	v_mov_b32_e32 v255, 0x41a00000
	v_cmp_lt_f32_e32 vcc, v255, v138
	s_nop 1
	v_cndmask_b32_e32 v140, v140, v138, vcc
	v_mul_f32_e32 v85, 0xc138aa3b, v140
	s_nop 7
	v_add_f32_e32 v0, v0, v75
	v_add_f32_e32 v1, v1, v75
	v_add_f32_e32 v2, v2, v75
	v_add_f32_e32 v3, v3, v75
	v_add_f32_e32 v90, v90, v84
	v_add_f32_e32 v91, v91, v84
	v_add_f32_e32 v92, v92, v84
	v_add_f32_e32 v93, v93, v84
	v_exp_f32_e32 v0, v0
	v_exp_f32_e32 v1, v1
	v_exp_f32_e32 v2, v2
	v_exp_f32_e32 v3, v3
	v_exp_f32_e32 v90, v90
	v_exp_f32_e32 v91, v91
	v_exp_f32_e32 v92, v92
	v_exp_f32_e32 v93, v93
	v_add_f32_e32 v0, 1.0, v0
	v_add_f32_e32 v1, 1.0, v1
	v_add_f32_e32 v2, 1.0, v2
	v_add_f32_e32 v3, 1.0, v3
	v_add_f32_e32 v90, 1.0, v90
	v_add_f32_e32 v91, 1.0, v91
	v_add_f32_e32 v92, 1.0, v92
	v_add_f32_e32 v93, 1.0, v93
	v_rcp_f32_e32 v0, v0
	v_rcp_f32_e32 v1, v1
	v_rcp_f32_e32 v2, v2
	v_rcp_f32_e32 v3, v3
	v_rcp_f32_e32 v90, v90
	v_rcp_f32_e32 v91, v91
	v_rcp_f32_e32 v92, v92
	v_rcp_f32_e32 v93, v93
	v_mul_f32_e32 v0, v85, v0
	v_mul_f32_e32 v1, v85, v1
	v_mul_f32_e32 v2, v85, v2
	v_mul_f32_e32 v3, v85, v3
	v_mul_f32_e32 v90, v90, v162
	v_mul_f32_e32 v91, v91, v163
	v_mul_f32_e32 v92, v92, v164
	v_mul_f32_e32 v93, v93, v165
; __device__ __forceinline__ float bf2f(u16 h) { return __uint_as_float(((unsigned)h) << 16); }
; __device__ __forceinline__ void lru_tile(const Params& P, int chunk, int head, int pass, char* smem_raw) {
;     ...
;       for (int tc = 0; tc < 4; ++tc)
; #pragma unroll
;         for (int reg = 0; reg < 4; ++reg) {
;           const int tl = wid * 16 + (lane >> 4) * 4 + reg;
;           const int c = 16 * tc + (lane & 15);
;           const float r = __builtin_amdgcn_rcpf(1.f + __builtin_amdgcn_exp2f(acc[tc][reg] + ba[tc]));
;           const float ii = __builtin_amdgcn_rcpf(1.f + __builtin_amdgcn_exp2f(acc[tc + 4][reg] + bi[tc]));
;           const float la = -c8[tc] * r;
;           const float a = __builtin_amdgcn_exp2f(la);
;           const float ucv = bf2f(sm_uc[(sb * 64 + tl) * LDSS + c]);
;           const float bt = __builtin_amdgcn_sqrtf(fmaxf(1.f - a * a, 0.f)) * (ii * ucv);
;           sm_a[tl * 64 + c] = a;
;           sm_b[tl * 64 + c] = bt;
;         }
	v_exp_f32_e32 v0, v0
	v_exp_f32_e32 v1, v1
	v_exp_f32_e32 v2, v2
	v_exp_f32_e32 v3, v3
	s_nop 0
	v_fma_f32 v138, -v0, v0, 1.0
	v_fma_f32 v139, -v1, v1, 1.0
	v_fma_f32 v140, -v2, v2, 1.0
	v_fma_f32 v141, -v3, v3, 1.0
	v_max_f32_e32 v138, 0, v138
	v_max_f32_e32 v139, 0, v139
	v_max_f32_e32 v140, 0, v140
	v_max_f32_e32 v141, 0, v141
	v_sqrt_f32_e32 v138, v138
	v_sqrt_f32_e32 v139, v139
	v_sqrt_f32_e32 v140, v140
	v_sqrt_f32_e32 v141, v141
	s_nop 0
	v_mul_f32_e32 v90, v138, v90
	v_mul_f32_e32 v91, v139, v91
	v_mul_f32_e32 v92, v140, v92
	v_mul_f32_e32 v93, v141, v93
	v_add_f32_e32 v4, v4, v75
	v_add_f32_e32 v5, v5, v75
	v_add_f32_e32 v6, v6, v75
	v_add_f32_e32 v7, v7, v75
	v_add_f32_e32 v94, v94, v84
	v_add_f32_e32 v95, v95, v84
	v_add_f32_e32 v96, v96, v84
	v_add_f32_e32 v97, v97, v84
	v_exp_f32_e32 v4, v4
	v_exp_f32_e32 v5, v5
	v_exp_f32_e32 v6, v6
	v_exp_f32_e32 v7, v7
	v_exp_f32_e32 v94, v94
	v_exp_f32_e32 v95, v95
	v_exp_f32_e32 v96, v96
	v_exp_f32_e32 v97, v97
	v_add_f32_e32 v4, 1.0, v4
	v_add_f32_e32 v5, 1.0, v5
	v_add_f32_e32 v6, 1.0, v6
	v_add_f32_e32 v7, 1.0, v7
	v_add_f32_e32 v94, 1.0, v94
	v_add_f32_e32 v95, 1.0, v95
	v_add_f32_e32 v96, 1.0, v96
	v_add_f32_e32 v97, 1.0, v97
	v_rcp_f32_e32 v4, v4
	v_rcp_f32_e32 v5, v5
	v_rcp_f32_e32 v6, v6
	v_rcp_f32_e32 v7, v7
	v_rcp_f32_e32 v94, v94
	v_rcp_f32_e32 v95, v95
	v_rcp_f32_e32 v96, v96
	v_rcp_f32_e32 v97, v97
	v_mul_f32_e32 v4, v85, v4
	v_mul_f32_e32 v5, v85, v5
	v_mul_f32_e32 v6, v85, v6
	v_mul_f32_e32 v7, v85, v7
	v_mul_f32_e32 v94, v94, v166
	v_mul_f32_e32 v95, v95, v167
	v_mul_f32_e32 v96, v96, v168
	v_mul_f32_e32 v97, v97, v169
	v_exp_f32_e32 v4, v4
	v_exp_f32_e32 v5, v5
	v_exp_f32_e32 v6, v6
	v_exp_f32_e32 v7, v7
	s_nop 0
	v_fma_f32 v138, -v4, v4, 1.0
	v_fma_f32 v139, -v5, v5, 1.0
	v_fma_f32 v140, -v6, v6, 1.0
	v_fma_f32 v141, -v7, v7, 1.0
	v_max_f32_e32 v138, 0, v138
	v_max_f32_e32 v139, 0, v139
	v_max_f32_e32 v140, 0, v140
	v_max_f32_e32 v141, 0, v141
	v_sqrt_f32_e32 v138, v138
	v_sqrt_f32_e32 v139, v139
	v_sqrt_f32_e32 v140, v140
	v_sqrt_f32_e32 v141, v141
	s_nop 0
	v_mul_f32_e32 v94, v138, v94
	v_mul_f32_e32 v95, v139, v95
	v_mul_f32_e32 v96, v140, v96
	v_mul_f32_e32 v97, v141, v97
	v_add_f32_e32 v8, v8, v75
	v_add_f32_e32 v9, v9, v75
	v_add_f32_e32 v10, v10, v75
	v_add_f32_e32 v11, v11, v75
	v_add_f32_e32 v98, v98, v84
	v_add_f32_e32 v99, v99, v84
	v_add_f32_e32 v100, v100, v84
	v_add_f32_e32 v101, v101, v84
	v_exp_f32_e32 v8, v8
	v_exp_f32_e32 v9, v9
	v_exp_f32_e32 v10, v10
	v_exp_f32_e32 v11, v11
	v_exp_f32_e32 v98, v98
	v_exp_f32_e32 v99, v99
	v_exp_f32_e32 v100, v100
	v_exp_f32_e32 v101, v101
	v_add_f32_e32 v8, 1.0, v8
	v_add_f32_e32 v9, 1.0, v9
	v_add_f32_e32 v10, 1.0, v10
	v_add_f32_e32 v11, 1.0, v11
	v_add_f32_e32 v98, 1.0, v98
	v_add_f32_e32 v99, 1.0, v99
	v_add_f32_e32 v100, 1.0, v100
	v_add_f32_e32 v101, 1.0, v101
	v_rcp_f32_e32 v8, v8
	v_rcp_f32_e32 v9, v9
	v_rcp_f32_e32 v10, v10
	v_rcp_f32_e32 v11, v11
	v_rcp_f32_e32 v98, v98
	v_rcp_f32_e32 v99, v99
	v_rcp_f32_e32 v100, v100
	v_rcp_f32_e32 v101, v101
	v_mul_f32_e32 v8, v85, v8
	v_mul_f32_e32 v9, v85, v9
	v_mul_f32_e32 v10, v85, v10
	v_mul_f32_e32 v11, v85, v11
	v_mul_f32_e32 v98, v98, v170
	v_mul_f32_e32 v99, v99, v171
	v_mul_f32_e32 v100, v100, v172
	v_mul_f32_e32 v101, v101, v173
	v_exp_f32_e32 v8, v8
	v_exp_f32_e32 v9, v9
	v_exp_f32_e32 v10, v10
	v_exp_f32_e32 v11, v11
	s_nop 0
	v_fma_f32 v138, -v8, v8, 1.0
	v_fma_f32 v139, -v9, v9, 1.0
	v_fma_f32 v140, -v10, v10, 1.0
	v_fma_f32 v141, -v11, v11, 1.0
	v_max_f32_e32 v138, 0, v138
	v_max_f32_e32 v139, 0, v139
	v_max_f32_e32 v140, 0, v140
	v_max_f32_e32 v141, 0, v141
	v_sqrt_f32_e32 v138, v138
	v_sqrt_f32_e32 v139, v139
	v_sqrt_f32_e32 v140, v140
	v_sqrt_f32_e32 v141, v141
	s_nop 0
	v_mul_f32_e32 v98, v138, v98
	v_mul_f32_e32 v99, v139, v99
	v_mul_f32_e32 v100, v140, v100
	v_mul_f32_e32 v101, v141, v101
	v_add_f32_e32 v12, v12, v75
	v_add_f32_e32 v13, v13, v75
	v_add_f32_e32 v14, v14, v75
	v_add_f32_e32 v15, v15, v75
	v_add_f32_e32 v102, v102, v84
	v_add_f32_e32 v103, v103, v84
	v_add_f32_e32 v104, v104, v84
	v_add_f32_e32 v105, v105, v84
	v_exp_f32_e32 v12, v12
	v_exp_f32_e32 v13, v13
	v_exp_f32_e32 v14, v14
	v_exp_f32_e32 v15, v15
	v_exp_f32_e32 v102, v102
	v_exp_f32_e32 v103, v103
	v_exp_f32_e32 v104, v104
	v_exp_f32_e32 v105, v105
	v_add_f32_e32 v12, 1.0, v12
	v_add_f32_e32 v13, 1.0, v13
	v_add_f32_e32 v14, 1.0, v14
	v_add_f32_e32 v15, 1.0, v15
	v_add_f32_e32 v102, 1.0, v102
	v_add_f32_e32 v103, 1.0, v103
	v_add_f32_e32 v104, 1.0, v104
	v_add_f32_e32 v105, 1.0, v105
	v_rcp_f32_e32 v12, v12
	v_rcp_f32_e32 v13, v13
	v_rcp_f32_e32 v14, v14
	v_rcp_f32_e32 v15, v15
	v_rcp_f32_e32 v102, v102
	v_rcp_f32_e32 v103, v103
	v_rcp_f32_e32 v104, v104
	v_rcp_f32_e32 v105, v105
	v_mul_f32_e32 v12, v85, v12
	v_mul_f32_e32 v13, v85, v13
	v_mul_f32_e32 v14, v85, v14
	v_mul_f32_e32 v15, v85, v15
	v_mul_f32_e32 v102, v102, v174
	v_mul_f32_e32 v103, v103, v175
	v_mul_f32_e32 v104, v104, v176
	v_mul_f32_e32 v105, v105, v177
	v_exp_f32_e32 v12, v12
	v_exp_f32_e32 v13, v13
	v_exp_f32_e32 v14, v14
	v_exp_f32_e32 v15, v15
	s_nop 0
	v_fma_f32 v138, -v12, v12, 1.0
	v_fma_f32 v139, -v13, v13, 1.0
	v_fma_f32 v140, -v14, v14, 1.0
	v_fma_f32 v141, -v15, v15, 1.0
	v_max_f32_e32 v138, 0, v138
	v_max_f32_e32 v139, 0, v139
	v_max_f32_e32 v140, 0, v140
	v_max_f32_e32 v141, 0, v141
	v_sqrt_f32_e32 v138, v138
	v_sqrt_f32_e32 v139, v139
	v_sqrt_f32_e32 v140, v140
	v_sqrt_f32_e32 v141, v141
	s_nop 0
	v_mul_f32_e32 v102, v138, v102
	v_mul_f32_e32 v103, v139, v103
	v_mul_f32_e32 v104, v140, v104
	v_mul_f32_e32 v105, v141, v105
	v_add_f32_e32 v16, v16, v75
	v_add_f32_e32 v17, v17, v75
; __device__ __forceinline__ float bf2f(u16 h) { return __uint_as_float(((unsigned)h) << 16); }
; __device__ __forceinline__ void lru_tile(const Params& P, int chunk, int head, int pass, char* smem_raw) {
;     ...
;       for (int tc = 0; tc < 4; ++tc)
; #pragma unroll
;         for (int reg = 0; reg < 4; ++reg) {
;           const int tl = wid * 16 + (lane >> 4) * 4 + reg;
;           const int c = 16 * tc + (lane & 15);
;           const float r = __builtin_amdgcn_rcpf(1.f + __builtin_amdgcn_exp2f(acc[tc][reg] + ba[tc]));
;           const float ii = __builtin_amdgcn_rcpf(1.f + __builtin_amdgcn_exp2f(acc[tc + 4][reg] + bi[tc]));
;           const float la = -c8[tc] * r;
;           const float a = __builtin_amdgcn_exp2f(la);
;           const float ucv = bf2f(sm_uc[(sb * 64 + tl) * LDSS + c]);
;           const float bt = __builtin_amdgcn_sqrtf(fmaxf(1.f - a * a, 0.f)) * (ii * ucv);
;           sm_a[tl * 64 + c] = a;
;           sm_b[tl * 64 + c] = bt;
;         }
	v_add_f32_e32 v18, v18, v75
	v_add_f32_e32 v19, v19, v75
	v_add_f32_e32 v106, v106, v84
	v_add_f32_e32 v107, v107, v84
	v_add_f32_e32 v108, v108, v84
	v_add_f32_e32 v109, v109, v84
	v_exp_f32_e32 v16, v16
	v_exp_f32_e32 v17, v17
	v_exp_f32_e32 v18, v18
	v_exp_f32_e32 v19, v19
	v_exp_f32_e32 v106, v106
	v_exp_f32_e32 v107, v107
	v_exp_f32_e32 v108, v108
	v_exp_f32_e32 v109, v109
	v_add_f32_e32 v16, 1.0, v16
	v_add_f32_e32 v17, 1.0, v17
	v_add_f32_e32 v18, 1.0, v18
	v_add_f32_e32 v19, 1.0, v19
	v_add_f32_e32 v106, 1.0, v106
	v_add_f32_e32 v107, 1.0, v107
	v_add_f32_e32 v108, 1.0, v108
	v_add_f32_e32 v109, 1.0, v109
	v_rcp_f32_e32 v16, v16
	v_rcp_f32_e32 v17, v17
	v_rcp_f32_e32 v18, v18
	v_rcp_f32_e32 v19, v19
	v_rcp_f32_e32 v106, v106
	v_rcp_f32_e32 v107, v107
	v_rcp_f32_e32 v108, v108
	v_rcp_f32_e32 v109, v109
	v_mul_f32_e32 v16, v85, v16
	v_mul_f32_e32 v17, v85, v17
	v_mul_f32_e32 v18, v85, v18
	v_mul_f32_e32 v19, v85, v19
	v_mul_f32_e32 v106, v106, v178
	v_mul_f32_e32 v107, v107, v179
	v_mul_f32_e32 v108, v108, v180
	v_mul_f32_e32 v109, v109, v181
	v_exp_f32_e32 v16, v16
	v_exp_f32_e32 v17, v17
	v_exp_f32_e32 v18, v18
	v_exp_f32_e32 v19, v19
	s_nop 0
	v_fma_f32 v138, -v16, v16, 1.0
	v_fma_f32 v139, -v17, v17, 1.0
	v_fma_f32 v140, -v18, v18, 1.0
	v_fma_f32 v141, -v19, v19, 1.0
	v_max_f32_e32 v138, 0, v138
	v_max_f32_e32 v139, 0, v139
	v_max_f32_e32 v140, 0, v140
	v_max_f32_e32 v141, 0, v141
	v_sqrt_f32_e32 v138, v138
	v_sqrt_f32_e32 v139, v139
	v_sqrt_f32_e32 v140, v140
	v_sqrt_f32_e32 v141, v141
	s_nop 0
	v_mul_f32_e32 v106, v138, v106
	v_mul_f32_e32 v107, v139, v107
	v_mul_f32_e32 v108, v140, v108
	v_mul_f32_e32 v109, v141, v109
	v_add_f32_e32 v20, v20, v75
	v_add_f32_e32 v21, v21, v75
	v_add_f32_e32 v22, v22, v75
	v_add_f32_e32 v23, v23, v75
	v_add_f32_e32 v110, v110, v84
	v_add_f32_e32 v111, v111, v84
	v_add_f32_e32 v112, v112, v84
	v_add_f32_e32 v113, v113, v84
	v_exp_f32_e32 v20, v20
	v_exp_f32_e32 v21, v21
	v_exp_f32_e32 v22, v22
	v_exp_f32_e32 v23, v23
	v_exp_f32_e32 v110, v110
	v_exp_f32_e32 v111, v111
	v_exp_f32_e32 v112, v112
	v_exp_f32_e32 v113, v113
	v_add_f32_e32 v20, 1.0, v20
	v_add_f32_e32 v21, 1.0, v21
	v_add_f32_e32 v22, 1.0, v22
	v_add_f32_e32 v23, 1.0, v23
	v_add_f32_e32 v110, 1.0, v110
	v_add_f32_e32 v111, 1.0, v111
	v_add_f32_e32 v112, 1.0, v112
	v_add_f32_e32 v113, 1.0, v113
	v_rcp_f32_e32 v20, v20
	v_rcp_f32_e32 v21, v21
	v_rcp_f32_e32 v22, v22
	v_rcp_f32_e32 v23, v23
	v_rcp_f32_e32 v110, v110
	v_rcp_f32_e32 v111, v111
	v_rcp_f32_e32 v112, v112
	v_rcp_f32_e32 v113, v113
	v_mul_f32_e32 v20, v85, v20
	v_mul_f32_e32 v21, v85, v21
	v_mul_f32_e32 v22, v85, v22
	v_mul_f32_e32 v23, v85, v23
	v_mul_f32_e32 v110, v110, v182
	v_mul_f32_e32 v111, v111, v183
	v_mul_f32_e32 v112, v112, v184
	v_mul_f32_e32 v113, v113, v185
	v_exp_f32_e32 v20, v20
	v_exp_f32_e32 v21, v21
	v_exp_f32_e32 v22, v22
	v_exp_f32_e32 v23, v23
	s_nop 0
	v_fma_f32 v138, -v20, v20, 1.0
	v_fma_f32 v139, -v21, v21, 1.0
	v_fma_f32 v140, -v22, v22, 1.0
	v_fma_f32 v141, -v23, v23, 1.0
	v_max_f32_e32 v138, 0, v138
	v_max_f32_e32 v139, 0, v139
	v_max_f32_e32 v140, 0, v140
	v_max_f32_e32 v141, 0, v141
	v_sqrt_f32_e32 v138, v138
	v_sqrt_f32_e32 v139, v139
	v_sqrt_f32_e32 v140, v140
	v_sqrt_f32_e32 v141, v141
	s_nop 0
	v_mul_f32_e32 v110, v138, v110
	v_mul_f32_e32 v111, v139, v111
	v_mul_f32_e32 v112, v140, v112
	v_mul_f32_e32 v113, v141, v113
	v_add_f32_e32 v24, v24, v75
	v_add_f32_e32 v25, v25, v75
	v_add_f32_e32 v26, v26, v75
	v_add_f32_e32 v27, v27, v75
	v_add_f32_e32 v114, v114, v84
	v_add_f32_e32 v115, v115, v84
	v_add_f32_e32 v116, v116, v84
	v_add_f32_e32 v117, v117, v84
	v_exp_f32_e32 v24, v24
	v_exp_f32_e32 v25, v25
	v_exp_f32_e32 v26, v26
	v_exp_f32_e32 v27, v27
	v_exp_f32_e32 v114, v114
	v_exp_f32_e32 v115, v115
	v_exp_f32_e32 v116, v116
	v_exp_f32_e32 v117, v117
	v_add_f32_e32 v24, 1.0, v24
	v_add_f32_e32 v25, 1.0, v25
	v_add_f32_e32 v26, 1.0, v26
	v_add_f32_e32 v27, 1.0, v27
	v_add_f32_e32 v114, 1.0, v114
	v_add_f32_e32 v115, 1.0, v115
	v_add_f32_e32 v116, 1.0, v116
	v_add_f32_e32 v117, 1.0, v117
	v_rcp_f32_e32 v24, v24
	v_rcp_f32_e32 v25, v25
	v_rcp_f32_e32 v26, v26
	v_rcp_f32_e32 v27, v27
	v_rcp_f32_e32 v114, v114
	v_rcp_f32_e32 v115, v115
	v_rcp_f32_e32 v116, v116
	v_rcp_f32_e32 v117, v117
	v_mul_f32_e32 v24, v85, v24
	v_mul_f32_e32 v25, v85, v25
	v_mul_f32_e32 v26, v85, v26
	v_mul_f32_e32 v27, v85, v27
	v_mul_f32_e32 v114, v114, v186
	v_mul_f32_e32 v115, v115, v187
	v_mul_f32_e32 v116, v116, v188
	v_mul_f32_e32 v117, v117, v189
	v_exp_f32_e32 v24, v24
	v_exp_f32_e32 v25, v25
	v_exp_f32_e32 v26, v26
	v_exp_f32_e32 v27, v27
	s_nop 0
	v_fma_f32 v138, -v24, v24, 1.0
	v_fma_f32 v139, -v25, v25, 1.0
	v_fma_f32 v140, -v26, v26, 1.0
	v_fma_f32 v141, -v27, v27, 1.0
	v_max_f32_e32 v138, 0, v138
	v_max_f32_e32 v139, 0, v139
	v_max_f32_e32 v140, 0, v140
	v_max_f32_e32 v141, 0, v141
	v_sqrt_f32_e32 v138, v138
	v_sqrt_f32_e32 v139, v139
	v_sqrt_f32_e32 v140, v140
	v_sqrt_f32_e32 v141, v141
	s_nop 0
	v_mul_f32_e32 v114, v138, v114
	v_mul_f32_e32 v115, v139, v115
	v_mul_f32_e32 v116, v140, v116
	v_mul_f32_e32 v117, v141, v117
	v_add_f32_e32 v28, v28, v75
	v_add_f32_e32 v29, v29, v75
	v_add_f32_e32 v30, v30, v75
	v_add_f32_e32 v31, v31, v75
	v_add_f32_e32 v118, v118, v84
	v_add_f32_e32 v119, v119, v84
	v_add_f32_e32 v120, v120, v84
	v_add_f32_e32 v121, v121, v84
	v_exp_f32_e32 v28, v28
	v_exp_f32_e32 v29, v29
	v_exp_f32_e32 v30, v30
	v_exp_f32_e32 v31, v31
	v_exp_f32_e32 v118, v118
	v_exp_f32_e32 v119, v119
	v_exp_f32_e32 v120, v120
	v_exp_f32_e32 v121, v121
	v_add_f32_e32 v28, 1.0, v28
	v_add_f32_e32 v29, 1.0, v29
	v_add_f32_e32 v30, 1.0, v30
	v_add_f32_e32 v31, 1.0, v31
; __device__ __forceinline__ void lru_tile(const Params& P, int chunk, int head, int pass, char* smem_raw) {
;     ...
;       for (int tc = 0; tc < 4; ++tc)
; #pragma unroll
;         for (int reg = 0; reg < 4; ++reg) {
;           const int tl = wid * 16 + (lane >> 4) * 4 + reg;
;           const int c = 16 * tc + (lane & 15);
;           const float r = __builtin_amdgcn_rcpf(1.f + __builtin_amdgcn_exp2f(acc[tc][reg] + ba[tc]));
;           const float ii = __builtin_amdgcn_rcpf(1.f + __builtin_amdgcn_exp2f(acc[tc + 4][reg] + bi[tc]));
;           const float la = -c8[tc] * r;
;           const float a = __builtin_amdgcn_exp2f(la);
;           const float ucv = bf2f(sm_uc[(sb * 64 + tl) * LDSS + c]);
;           const float bt = __builtin_amdgcn_sqrtf(fmaxf(1.f - a * a, 0.f)) * (ii * ucv);
;           sm_a[tl * 64 + c] = a;
;           sm_b[tl * 64 + c] = bt;
;         }
;       __syncthreads();
;       const int pos = (d == 0) ? q : 3 - q;
;       {
;         float Pp = 1.f, H = 0.f;
; #pragma unroll 4
;         for (int i = 0; i < 16; ++i) {
;           const int tl = (d == 0) ? (q * 16 + i) : (q * 16 + 15 - i);
;           const float a = sm_a[tl * 64 + ch], b = sm_b[tl * 64 + ch];
;           H = a * H + b; Pp *= a;
;         }
;         sm_ph[pos * 64 + ch] = make_float2(Pp, H);
;       }
;       __syncthreads();
;       const float2 p0 = sm_ph[ch], p1 = sm_ph[64 + ch], p2 = sm_ph[128 + ch], p3 = sm_ph[192 + ch];
;       if (pass == 2) {
;         float hin = cB;
;         if (pos > 0) hin = p0.x * hin + p0.y;
;         if (pos > 1) hin = p1.x * hin + p1.y;
;         if (pos > 2) hin = p2.x * hin + p2.y;
;         float h = hin;
;         float hfp[16], gp[16];
;         if (d == 1) {
; #pragma unroll
;           for (int i = 0; i < 16; ++i) {
;             const long rowp = row0 + sb * 64 + q * 16 + 15 - i;
;             hfp[i] = hfbuf[rowp * 512 + gch];
;             gp[i] = bf2f(P.zq[rowp * 1536 + 512 + gch]);
;           }
;         }
; #pragma unroll
;         for (int i = 0; i < 16; ++i) {
;           const int tl = (d == 0) ? (q * 16 + i) : (q * 16 + 15 - i);
;           const float a = sm_a[tl * 64 + ch], b = sm_b[tl * 64 + ch];
;           h = a * h + b;
;           const long row = row0 + sb * 64 + tl;
;           if (d == 0) {
;             hfw[row * 512 + gch] = h;
	v_add_f32_e32 v118, 1.0, v118
	v_add_f32_e32 v119, 1.0, v119
	v_add_f32_e32 v120, 1.0, v120
	v_add_f32_e32 v121, 1.0, v121
	v_rcp_f32_e32 v28, v28
	v_rcp_f32_e32 v29, v29
	v_rcp_f32_e32 v30, v30
	v_rcp_f32_e32 v31, v31
	v_rcp_f32_e32 v118, v118
	v_rcp_f32_e32 v119, v119
	v_rcp_f32_e32 v120, v120
	v_rcp_f32_e32 v121, v121
	v_mul_f32_e32 v28, v85, v28
	v_mul_f32_e32 v29, v85, v29
	v_mul_f32_e32 v30, v85, v30
	v_mul_f32_e32 v31, v85, v31
	v_mul_f32_e32 v118, v118, v190
	v_mul_f32_e32 v119, v119, v191
	v_mul_f32_e32 v120, v120, v192
	v_mul_f32_e32 v121, v121, v193
	v_exp_f32_e32 v28, v28
	v_exp_f32_e32 v29, v29
	v_exp_f32_e32 v30, v30
	v_exp_f32_e32 v31, v31
	s_nop 0
	v_fma_f32 v138, -v28, v28, 1.0
	v_fma_f32 v139, -v29, v29, 1.0
	v_fma_f32 v140, -v30, v30, 1.0
	v_fma_f32 v141, -v31, v31, 1.0
	v_max_f32_e32 v138, 0, v138
	v_max_f32_e32 v139, 0, v139
	v_max_f32_e32 v140, 0, v140
	v_max_f32_e32 v141, 0, v141
	v_sqrt_f32_e32 v138, v138
	v_sqrt_f32_e32 v139, v139
	v_sqrt_f32_e32 v140, v140
	v_sqrt_f32_e32 v141, v141
	s_nop 0
	v_mul_f32_e32 v118, v138, v118
	v_mul_f32_e32 v119, v139, v119
	v_mul_f32_e32 v120, v140, v120
	v_mul_f32_e32 v121, v141, v121
	v_mov_b32_e32 v253, v0
	v_mov_b32_e32 v254, v90
	v_fma_f32 v254, v1, v254, v91
	v_mul_f32_e32 v253, v253, v1
	v_fma_f32 v254, v2, v254, v92
	v_mul_f32_e32 v253, v253, v2
	v_fma_f32 v254, v3, v254, v93
	v_mul_f32_e32 v253, v253, v3
	v_fma_f32 v254, v4, v254, v94
	v_mul_f32_e32 v253, v253, v4
	v_fma_f32 v254, v5, v254, v95
	v_mul_f32_e32 v253, v253, v5
	v_fma_f32 v254, v6, v254, v96
	v_mul_f32_e32 v253, v253, v6
	v_fma_f32 v254, v7, v254, v97
	v_mul_f32_e32 v253, v253, v7
	v_fma_f32 v254, v8, v254, v98
	v_mul_f32_e32 v253, v253, v8
	v_fma_f32 v254, v9, v254, v99
	v_mul_f32_e32 v253, v253, v9
	v_fma_f32 v254, v10, v254, v100
	v_mul_f32_e32 v253, v253, v10
	v_fma_f32 v254, v11, v254, v101
	v_mul_f32_e32 v253, v253, v11
	v_fma_f32 v254, v12, v254, v102
	v_mul_f32_e32 v253, v253, v12
	v_fma_f32 v254, v13, v254, v103
	v_mul_f32_e32 v253, v253, v13
	v_fma_f32 v254, v14, v254, v104
	v_mul_f32_e32 v253, v253, v14
	v_fma_f32 v254, v15, v254, v105
	v_mul_f32_e32 v253, v253, v15
	v_fma_f32 v254, v16, v254, v106
	v_mul_f32_e32 v253, v253, v16
	v_fma_f32 v254, v17, v254, v107
	v_mul_f32_e32 v253, v253, v17
	v_fma_f32 v254, v18, v254, v108
	v_mul_f32_e32 v253, v253, v18
	v_fma_f32 v254, v19, v254, v109
	v_mul_f32_e32 v253, v253, v19
	v_fma_f32 v254, v20, v254, v110
	v_mul_f32_e32 v253, v253, v20
	v_fma_f32 v254, v21, v254, v111
	v_mul_f32_e32 v253, v253, v21
	v_fma_f32 v254, v22, v254, v112
	v_mul_f32_e32 v253, v253, v22
	v_fma_f32 v254, v23, v254, v113
	v_mul_f32_e32 v253, v253, v23
	v_fma_f32 v254, v24, v254, v114
	v_mul_f32_e32 v253, v253, v24
	v_fma_f32 v254, v25, v254, v115
	v_mul_f32_e32 v253, v253, v25
	v_fma_f32 v254, v26, v254, v116
	v_mul_f32_e32 v253, v253, v26
	v_fma_f32 v254, v27, v254, v117
	v_mul_f32_e32 v253, v253, v27
	v_fma_f32 v254, v28, v254, v118
	v_mul_f32_e32 v253, v253, v28
	v_fma_f32 v254, v29, v254, v119
	v_mul_f32_e32 v253, v253, v29
	v_fma_f32 v254, v30, v254, v120
	v_mul_f32_e32 v253, v253, v30
	v_fma_f32 v254, v31, v254, v121
	v_mul_f32_e32 v253, v253, v31
	v_mov_b32_e32 v138, v253
	v_mov_b32_e32 v139, v253
	s_nop 1
	v_permlane16_swap_b32_e32 v138, v139
	v_mov_b32_e32 v140, v138
	v_mov_b32_e32 v141, v139
	s_nop 1
	v_permlane32_swap_b32_e32 v138, v140
	v_permlane32_swap_b32_e32 v139, v141
	v_mov_b32_e32 v198, v254
	v_mov_b32_e32 v199, v254
	s_nop 1
	v_permlane16_swap_b32_e32 v198, v199
	v_mov_b32_e32 v200, v198
	v_mov_b32_e32 v201, v199
	s_nop 1
	v_permlane32_swap_b32_e32 v198, v200
	v_permlane32_swap_b32_e32 v199, v201
	v_mov_b32_e32 v136, v65
	v_fma_f32 v150, v138, v136, v198
	v_fma_f32 v151, v139, v150, v199
	v_fma_f32 v202, v140, v151, v200
	v_mov_b32_e32 v254, v136
	v_cndmask_b32_e64 v254, v254, v150, s[72:73]
	v_cndmask_b32_e64 v254, v254, v151, s[74:75]
	v_cndmask_b32_e64 v254, v254, v202, s[76:77]
	v_fma_f32 v205, v0, v254, v90
	v_fma_f32 v206, v1, v205, v91
	v_fma_f32 v207, v2, v206, v92
	v_fma_f32 v208, v3, v207, v93
	v_fma_f32 v209, v4, v208, v94
	v_fma_f32 v210, v5, v209, v95
	v_fma_f32 v211, v6, v210, v96
	v_fma_f32 v212, v7, v211, v97
	v_fma_f32 v213, v8, v212, v98
	v_fma_f32 v214, v9, v213, v99
	v_fma_f32 v215, v10, v214, v100
	v_fma_f32 v216, v11, v215, v101
	v_fma_f32 v217, v12, v216, v102
	v_fma_f32 v218, v13, v217, v103
	v_fma_f32 v219, v14, v218, v104
	v_fma_f32 v220, v15, v219, v105
	v_fma_f32 v221, v16, v220, v106
	v_fma_f32 v222, v17, v221, v107
	v_fma_f32 v223, v18, v222, v108
	v_fma_f32 v224, v19, v223, v109
	v_fma_f32 v225, v20, v224, v110
	v_fma_f32 v226, v21, v225, v111
	v_fma_f32 v227, v22, v226, v112
	v_fma_f32 v228, v23, v227, v113
	v_fma_f32 v229, v24, v228, v114
	v_fma_f32 v230, v25, v229, v115
	v_fma_f32 v231, v26, v230, v116
	v_fma_f32 v232, v27, v231, v117
	v_fma_f32 v233, v28, v232, v118
	v_fma_f32 v234, v29, v233, v119
	v_fma_f32 v235, v30, v234, v120
	v_fma_f32 v236, v31, v235, v121
	ds_read_b128 v[76:79], v131 offset:0
	ds_read_b128 v[80:83], v133 offset:0
	ds_read_b128 v[122:125], v131 offset:512
	ds_read_b128 v[126:129], v133 offset:512
	s_waitcnt vmcnt(0)
	s_waitcnt lgkmcnt(3)
	v_mfma_f32_16x16x32_bf16 v[0:3], v[76:79], v[238:241], 0
	v_mfma_f32_16x16x32_bf16 v[90:93], v[76:79], v[246:249], 0
	ds_read_b128 v[76:79], v131 offset:1024
	s_waitcnt lgkmcnt(3)
	v_mfma_f32_16x16x32_bf16 v[0:3], v[80:83], v[242:245], v[0:3]
	v_mfma_f32_16x16x32_bf16 v[90:93], v[80:83], v[194:197], v[90:93]
	ds_read_b128 v[80:83], v133 offset:1024
	s_waitcnt lgkmcnt(3)
	v_mfma_f32_16x16x32_bf16 v[4:7], v[122:125], v[238:241], 0
	v_mfma_f32_16x16x32_bf16 v[94:97], v[122:125], v[246:249], 0
	ds_read_b128 v[122:125], v131 offset:1536
	s_waitcnt lgkmcnt(3)
; __device__ __forceinline__ float bf2f(u16 h) { return __uint_as_float(((unsigned)h) << 16); }
; __device__ __forceinline__ void lru_tile(const Params& P, int chunk, int head, int pass, char* smem_raw) {
;     ...
; #pragma unroll
;       for (int s = 0; s < 2; ++s) {
;         const bf16x8 af = *reinterpret_cast<const bf16x8*>(&sm_uc[(sb * 64 + wid * 16 + (lane & 15)) * LDSS + s * 32 + (lane >> 4) * 8]);
; #pragma unroll
;         for (int t = 0; t < 8; ++t) {
;           const bf16x8 bfr = *reinterpret_cast<const bf16x8*>(&sm_w[(t * 16 + (lane & 15)) * LDSS + s * 32 + (lane >> 4) * 8]);
;           acc[t] = __builtin_amdgcn_mfma_f32_16x16x32_bf16(af, bfr, acc[t], 0, 0, 0);
;         }
;       }
; #pragma unroll
;       for (int tc = 0; tc < 4; ++tc)
; #pragma unroll
;         for (int reg = 0; reg < 4; ++reg) {
;           const int tl = wid * 16 + (lane >> 4) * 4 + reg;
;           const int c = 16 * tc + (lane & 15);
;           const float r = __builtin_amdgcn_rcpf(1.f + __builtin_amdgcn_exp2f(acc[tc][reg] + ba[tc]));
;           const float ii = __builtin_amdgcn_rcpf(1.f + __builtin_amdgcn_exp2f(acc[tc + 4][reg] + bi[tc]));
;           const float la = -c8[tc] * r;
;           const float a = __builtin_amdgcn_exp2f(la);
;           const float ucv = bf2f(sm_uc[(sb * 64 + tl) * LDSS + c]);
;           const float bt = __builtin_amdgcn_sqrtf(fmaxf(1.f - a * a, 0.f)) * (ii * ucv);
;           sm_a[tl * 64 + c] = a;
;           sm_b[tl * 64 + c] = bt;
;         }
	v_mfma_f32_16x16x32_bf16 v[4:7], v[126:129], v[242:245], v[4:7]
	v_mfma_f32_16x16x32_bf16 v[94:97], v[126:129], v[194:197], v[94:97]
	ds_read_b128 v[126:129], v133 offset:1536
	s_waitcnt lgkmcnt(3)
	v_mfma_f32_16x16x32_bf16 v[8:11], v[76:79], v[238:241], 0
	v_mfma_f32_16x16x32_bf16 v[98:101], v[76:79], v[246:249], 0
	ds_read_b128 v[76:79], v131 offset:2048
	s_waitcnt lgkmcnt(3)
	v_mfma_f32_16x16x32_bf16 v[8:11], v[80:83], v[242:245], v[8:11]
	v_mfma_f32_16x16x32_bf16 v[98:101], v[80:83], v[194:197], v[98:101]
	ds_read_b128 v[80:83], v133 offset:2048
	s_waitcnt lgkmcnt(3)
	v_mfma_f32_16x16x32_bf16 v[12:15], v[122:125], v[238:241], 0
	v_mfma_f32_16x16x32_bf16 v[102:105], v[122:125], v[246:249], 0
	ds_read_b128 v[122:125], v131 offset:2560
	s_waitcnt lgkmcnt(3)
	v_mfma_f32_16x16x32_bf16 v[12:15], v[126:129], v[242:245], v[12:15]
	v_mfma_f32_16x16x32_bf16 v[102:105], v[126:129], v[194:197], v[102:105]
	ds_read_b128 v[126:129], v133 offset:2560
	s_waitcnt lgkmcnt(3)
	v_mfma_f32_16x16x32_bf16 v[16:19], v[76:79], v[238:241], 0
	v_mfma_f32_16x16x32_bf16 v[106:109], v[76:79], v[246:249], 0
	ds_read_b128 v[76:79], v131 offset:3072
	s_waitcnt lgkmcnt(3)
	v_mfma_f32_16x16x32_bf16 v[16:19], v[80:83], v[242:245], v[16:19]
	v_mfma_f32_16x16x32_bf16 v[106:109], v[80:83], v[194:197], v[106:109]
	ds_read_b128 v[80:83], v133 offset:3072
	s_waitcnt lgkmcnt(3)
	v_mfma_f32_16x16x32_bf16 v[20:23], v[122:125], v[238:241], 0
	v_mfma_f32_16x16x32_bf16 v[110:113], v[122:125], v[246:249], 0
	ds_read_b128 v[122:125], v131 offset:3584
	s_waitcnt lgkmcnt(3)
	v_mfma_f32_16x16x32_bf16 v[20:23], v[126:129], v[242:245], v[20:23]
	v_mfma_f32_16x16x32_bf16 v[110:113], v[126:129], v[194:197], v[110:113]
	ds_read_b128 v[126:129], v133 offset:3584
	s_waitcnt lgkmcnt(3)
	v_mfma_f32_16x16x32_bf16 v[24:27], v[76:79], v[238:241], 0
	v_mfma_f32_16x16x32_bf16 v[114:117], v[76:79], v[246:249], 0
	s_waitcnt lgkmcnt(2)
	v_mfma_f32_16x16x32_bf16 v[24:27], v[80:83], v[242:245], v[24:27]
	v_mfma_f32_16x16x32_bf16 v[114:117], v[80:83], v[194:197], v[114:117]
	s_waitcnt lgkmcnt(1)
	v_mfma_f32_16x16x32_bf16 v[28:31], v[122:125], v[238:241], 0
	v_mfma_f32_16x16x32_bf16 v[118:121], v[122:125], v[246:249], 0
	s_waitcnt lgkmcnt(0)
	v_mfma_f32_16x16x32_bf16 v[28:31], v[126:129], v[242:245], v[28:31]
	v_mfma_f32_16x16x32_bf16 v[118:121], v[126:129], v[194:197], v[118:121]
	v_mul_f32_e32 v68, 0xbfb8aa3b, v68
	v_mul_f32_e32 v70, 0xbfb8aa3b, v70
	v_sub_f32_e32 v138, 0, v73
	v_mul_f32_e32 v139, 0x3fb8aa3b, v138
	v_exp_f32_e32 v139, v139
	v_mul_f32_e32 v140, 0xbe800000, v139
	v_add_f32_e32 v140, 0x3eaaaaab, v140
	v_fma_f32 v140, -v139, v140, 0.5
	v_fma_f32 v140, -v139, v140, 1.0
	v_mul_f32_e32 v140, v139, v140
	v_add_f32_e32 v141, 1.0, v139
	v_log_f32_e32 v141, v141
	v_mov_b32_e32 v255, 0x3cf5c28f
	v_mul_f32_e32 v141, 0x3f317218, v141
	v_cmp_gt_f32_e32 vcc, v255, v139
	s_nop 1
	v_cndmask_b32_e32 v140, v141, v140, vcc
	v_mov_b32_e32 v255, 0x41a00000
	v_cmp_lt_f32_e32 vcc, v255, v138
	s_nop 1
	v_cndmask_b32_e32 v140, v140, v138, vcc
	v_mul_f32_e32 v73, 0xc138aa3b, v140
	s_nop 7
	v_add_f32_e32 v0, v0, v68
	v_add_f32_e32 v1, v1, v68
	v_add_f32_e32 v2, v2, v68
	v_add_f32_e32 v3, v3, v68
	v_add_f32_e32 v90, v90, v70
	v_add_f32_e32 v91, v91, v70
	v_add_f32_e32 v92, v92, v70
	v_add_f32_e32 v93, v93, v70
	v_exp_f32_e32 v0, v0
	v_exp_f32_e32 v1, v1
	v_exp_f32_e32 v2, v2
	v_exp_f32_e32 v3, v3
	v_exp_f32_e32 v90, v90
	v_exp_f32_e32 v91, v91
	v_exp_f32_e32 v92, v92
	v_exp_f32_e32 v93, v93
	v_add_f32_e32 v0, 1.0, v0
	v_add_f32_e32 v1, 1.0, v1
	v_add_f32_e32 v2, 1.0, v2
	v_add_f32_e32 v3, 1.0, v3
	v_add_f32_e32 v90, 1.0, v90
	v_add_f32_e32 v91, 1.0, v91
	v_add_f32_e32 v92, 1.0, v92
	v_add_f32_e32 v93, 1.0, v93
	v_rcp_f32_e32 v0, v0
	v_rcp_f32_e32 v1, v1
	v_rcp_f32_e32 v2, v2
	v_rcp_f32_e32 v3, v3
	v_rcp_f32_e32 v90, v90
	v_rcp_f32_e32 v91, v91
	v_rcp_f32_e32 v92, v92
	v_rcp_f32_e32 v93, v93
	v_mul_f32_e32 v0, v73, v0
	v_mul_f32_e32 v1, v73, v1
	v_mul_f32_e32 v2, v73, v2
	v_mul_f32_e32 v3, v73, v3
	v_mul_f32_e32 v90, v90, v162
	v_mul_f32_e32 v91, v91, v163
	v_mul_f32_e32 v92, v92, v164
	v_mul_f32_e32 v93, v93, v165
	v_exp_f32_e32 v0, v0
	v_exp_f32_e32 v1, v1
	v_exp_f32_e32 v2, v2
	v_exp_f32_e32 v3, v3
	s_nop 0
	v_fma_f32 v138, -v0, v0, 1.0
	v_fma_f32 v139, -v1, v1, 1.0
	v_fma_f32 v140, -v2, v2, 1.0
	v_fma_f32 v141, -v3, v3, 1.0
	v_max_f32_e32 v138, 0, v138
	v_max_f32_e32 v139, 0, v139
	v_max_f32_e32 v140, 0, v140
	v_max_f32_e32 v141, 0, v141
	v_sqrt_f32_e32 v138, v138
	v_sqrt_f32_e32 v139, v139
	v_sqrt_f32_e32 v140, v140
	v_sqrt_f32_e32 v141, v141
	s_nop 0
	v_mul_f32_e32 v90, v138, v90
	v_mul_f32_e32 v91, v139, v91
	v_mul_f32_e32 v92, v140, v92
	v_mul_f32_e32 v93, v141, v93
	v_add_f32_e32 v4, v4, v68
	v_add_f32_e32 v5, v5, v68
	v_add_f32_e32 v6, v6, v68
	v_add_f32_e32 v7, v7, v68
	v_add_f32_e32 v94, v94, v70
	v_add_f32_e32 v95, v95, v70
	v_add_f32_e32 v96, v96, v70
	v_add_f32_e32 v97, v97, v70
	v_exp_f32_e32 v4, v4
	v_exp_f32_e32 v5, v5
	v_exp_f32_e32 v6, v6
	v_exp_f32_e32 v7, v7
	v_exp_f32_e32 v94, v94
	v_exp_f32_e32 v95, v95
	v_exp_f32_e32 v96, v96
	v_exp_f32_e32 v97, v97
	v_add_f32_e32 v4, 1.0, v4
	v_add_f32_e32 v5, 1.0, v5
	v_add_f32_e32 v6, 1.0, v6
	v_add_f32_e32 v7, 1.0, v7
	v_add_f32_e32 v94, 1.0, v94
	v_add_f32_e32 v95, 1.0, v95
	v_add_f32_e32 v96, 1.0, v96
	v_add_f32_e32 v97, 1.0, v97
	v_rcp_f32_e32 v4, v4
	v_rcp_f32_e32 v5, v5
	v_rcp_f32_e32 v6, v6
	v_rcp_f32_e32 v7, v7
	v_rcp_f32_e32 v94, v94
	v_rcp_f32_e32 v95, v95
	v_rcp_f32_e32 v96, v96
	v_rcp_f32_e32 v97, v97
	v_mul_f32_e32 v4, v73, v4
	v_mul_f32_e32 v5, v73, v5
	v_mul_f32_e32 v6, v73, v6
	v_mul_f32_e32 v7, v73, v7
	v_mul_f32_e32 v94, v94, v166
; __device__ __forceinline__ float bf2f(u16 h) { return __uint_as_float(((unsigned)h) << 16); }
; __device__ __forceinline__ void lru_tile(const Params& P, int chunk, int head, int pass, char* smem_raw) {
;     ...
;       for (int tc = 0; tc < 4; ++tc)
; #pragma unroll
;         for (int reg = 0; reg < 4; ++reg) {
;           const int tl = wid * 16 + (lane >> 4) * 4 + reg;
;           const int c = 16 * tc + (lane & 15);
;           const float r = __builtin_amdgcn_rcpf(1.f + __builtin_amdgcn_exp2f(acc[tc][reg] + ba[tc]));
;           const float ii = __builtin_amdgcn_rcpf(1.f + __builtin_amdgcn_exp2f(acc[tc + 4][reg] + bi[tc]));
;           const float la = -c8[tc] * r;
;           const float a = __builtin_amdgcn_exp2f(la);
;           const float ucv = bf2f(sm_uc[(sb * 64 + tl) * LDSS + c]);
;           const float bt = __builtin_amdgcn_sqrtf(fmaxf(1.f - a * a, 0.f)) * (ii * ucv);
;           sm_a[tl * 64 + c] = a;
;           sm_b[tl * 64 + c] = bt;
;         }
	v_mul_f32_e32 v95, v95, v167
	v_mul_f32_e32 v96, v96, v168
	v_mul_f32_e32 v97, v97, v169
	v_exp_f32_e32 v4, v4
	v_exp_f32_e32 v5, v5
	v_exp_f32_e32 v6, v6
	v_exp_f32_e32 v7, v7
	s_nop 0
	v_fma_f32 v138, -v4, v4, 1.0
	v_fma_f32 v139, -v5, v5, 1.0
	v_fma_f32 v140, -v6, v6, 1.0
	v_fma_f32 v141, -v7, v7, 1.0
	v_max_f32_e32 v138, 0, v138
	v_max_f32_e32 v139, 0, v139
	v_max_f32_e32 v140, 0, v140
	v_max_f32_e32 v141, 0, v141
	v_sqrt_f32_e32 v138, v138
	v_sqrt_f32_e32 v139, v139
	v_sqrt_f32_e32 v140, v140
	v_sqrt_f32_e32 v141, v141
	s_nop 0
	v_mul_f32_e32 v94, v138, v94
	v_mul_f32_e32 v95, v139, v95
	v_mul_f32_e32 v96, v140, v96
	v_mul_f32_e32 v97, v141, v97
	v_add_f32_e32 v8, v8, v68
	v_add_f32_e32 v9, v9, v68
	v_add_f32_e32 v10, v10, v68
	v_add_f32_e32 v11, v11, v68
	v_add_f32_e32 v98, v98, v70
	v_add_f32_e32 v99, v99, v70
	v_add_f32_e32 v100, v100, v70
	v_add_f32_e32 v101, v101, v70
	v_exp_f32_e32 v8, v8
	v_exp_f32_e32 v9, v9
	v_exp_f32_e32 v10, v10
	v_exp_f32_e32 v11, v11
	v_exp_f32_e32 v98, v98
	v_exp_f32_e32 v99, v99
	v_exp_f32_e32 v100, v100
	v_exp_f32_e32 v101, v101
	v_add_f32_e32 v8, 1.0, v8
	v_add_f32_e32 v9, 1.0, v9
	v_add_f32_e32 v10, 1.0, v10
	v_add_f32_e32 v11, 1.0, v11
	v_add_f32_e32 v98, 1.0, v98
	v_add_f32_e32 v99, 1.0, v99
	v_add_f32_e32 v100, 1.0, v100
	v_add_f32_e32 v101, 1.0, v101
	v_rcp_f32_e32 v8, v8
	v_rcp_f32_e32 v9, v9
	v_rcp_f32_e32 v10, v10
	v_rcp_f32_e32 v11, v11
	v_rcp_f32_e32 v98, v98
	v_rcp_f32_e32 v99, v99
	v_rcp_f32_e32 v100, v100
	v_rcp_f32_e32 v101, v101
	v_mul_f32_e32 v8, v73, v8
	v_mul_f32_e32 v9, v73, v9
	v_mul_f32_e32 v10, v73, v10
	v_mul_f32_e32 v11, v73, v11
	v_mul_f32_e32 v98, v98, v170
	v_mul_f32_e32 v99, v99, v171
	v_mul_f32_e32 v100, v100, v172
	v_mul_f32_e32 v101, v101, v173
	v_exp_f32_e32 v8, v8
	v_exp_f32_e32 v9, v9
	v_exp_f32_e32 v10, v10
	v_exp_f32_e32 v11, v11
	s_nop 0
	v_fma_f32 v138, -v8, v8, 1.0
	v_fma_f32 v139, -v9, v9, 1.0
	v_fma_f32 v140, -v10, v10, 1.0
	v_fma_f32 v141, -v11, v11, 1.0
	v_max_f32_e32 v138, 0, v138
	v_max_f32_e32 v139, 0, v139
	v_max_f32_e32 v140, 0, v140
	v_max_f32_e32 v141, 0, v141
	v_sqrt_f32_e32 v138, v138
	v_sqrt_f32_e32 v139, v139
	v_sqrt_f32_e32 v140, v140
	v_sqrt_f32_e32 v141, v141
	s_nop 0
	v_mul_f32_e32 v98, v138, v98
	v_mul_f32_e32 v99, v139, v99
	v_mul_f32_e32 v100, v140, v100
	v_mul_f32_e32 v101, v141, v101
	v_add_f32_e32 v12, v12, v68
	v_add_f32_e32 v13, v13, v68
	v_add_f32_e32 v14, v14, v68
	v_add_f32_e32 v15, v15, v68
	v_add_f32_e32 v102, v102, v70
	v_add_f32_e32 v103, v103, v70
	v_add_f32_e32 v104, v104, v70
	v_add_f32_e32 v105, v105, v70
	v_exp_f32_e32 v12, v12
	v_exp_f32_e32 v13, v13
	v_exp_f32_e32 v14, v14
	v_exp_f32_e32 v15, v15
	v_exp_f32_e32 v102, v102
	v_exp_f32_e32 v103, v103
	v_exp_f32_e32 v104, v104
	v_exp_f32_e32 v105, v105
	v_add_f32_e32 v12, 1.0, v12
	v_add_f32_e32 v13, 1.0, v13
	v_add_f32_e32 v14, 1.0, v14
	v_add_f32_e32 v15, 1.0, v15
	v_add_f32_e32 v102, 1.0, v102
	v_add_f32_e32 v103, 1.0, v103
	v_add_f32_e32 v104, 1.0, v104
	v_add_f32_e32 v105, 1.0, v105
	v_rcp_f32_e32 v12, v12
	v_rcp_f32_e32 v13, v13
	v_rcp_f32_e32 v14, v14
	v_rcp_f32_e32 v15, v15
	v_rcp_f32_e32 v102, v102
	v_rcp_f32_e32 v103, v103
	v_rcp_f32_e32 v104, v104
	v_rcp_f32_e32 v105, v105
	v_mul_f32_e32 v12, v73, v12
	v_mul_f32_e32 v13, v73, v13
	v_mul_f32_e32 v14, v73, v14
	v_mul_f32_e32 v15, v73, v15
	v_mul_f32_e32 v102, v102, v174
	v_mul_f32_e32 v103, v103, v175
	v_mul_f32_e32 v104, v104, v176
	v_mul_f32_e32 v105, v105, v177
	v_exp_f32_e32 v12, v12
	v_exp_f32_e32 v13, v13
	v_exp_f32_e32 v14, v14
	v_exp_f32_e32 v15, v15
	s_nop 0
	v_fma_f32 v138, -v12, v12, 1.0
	v_fma_f32 v139, -v13, v13, 1.0
	v_fma_f32 v140, -v14, v14, 1.0
	v_fma_f32 v141, -v15, v15, 1.0
	v_max_f32_e32 v138, 0, v138
	v_max_f32_e32 v139, 0, v139
	v_max_f32_e32 v140, 0, v140
	v_max_f32_e32 v141, 0, v141
	v_sqrt_f32_e32 v138, v138
	v_sqrt_f32_e32 v139, v139
	v_sqrt_f32_e32 v140, v140
	v_sqrt_f32_e32 v141, v141
	s_nop 0
	v_mul_f32_e32 v102, v138, v102
	v_mul_f32_e32 v103, v139, v103
	v_mul_f32_e32 v104, v140, v104
	v_mul_f32_e32 v105, v141, v105
	v_add_f32_e32 v16, v16, v68
	v_add_f32_e32 v17, v17, v68
	v_add_f32_e32 v18, v18, v68
	v_add_f32_e32 v19, v19, v68
	v_add_f32_e32 v106, v106, v70
	v_add_f32_e32 v107, v107, v70
	v_add_f32_e32 v108, v108, v70
	v_add_f32_e32 v109, v109, v70
	v_exp_f32_e32 v16, v16
	v_exp_f32_e32 v17, v17
	v_exp_f32_e32 v18, v18
	v_exp_f32_e32 v19, v19
	v_exp_f32_e32 v106, v106
	v_exp_f32_e32 v107, v107
	v_exp_f32_e32 v108, v108
	v_exp_f32_e32 v109, v109
	v_add_f32_e32 v16, 1.0, v16
	v_add_f32_e32 v17, 1.0, v17
	v_add_f32_e32 v18, 1.0, v18
	v_add_f32_e32 v19, 1.0, v19
	v_add_f32_e32 v106, 1.0, v106
	v_add_f32_e32 v107, 1.0, v107
	v_add_f32_e32 v108, 1.0, v108
	v_add_f32_e32 v109, 1.0, v109
	v_rcp_f32_e32 v16, v16
	v_rcp_f32_e32 v17, v17
	v_rcp_f32_e32 v18, v18
	v_rcp_f32_e32 v19, v19
	v_rcp_f32_e32 v106, v106
	v_rcp_f32_e32 v107, v107
	v_rcp_f32_e32 v108, v108
	v_rcp_f32_e32 v109, v109
	v_mul_f32_e32 v16, v73, v16
	v_mul_f32_e32 v17, v73, v17
	v_mul_f32_e32 v18, v73, v18
	v_mul_f32_e32 v19, v73, v19
	v_mul_f32_e32 v106, v106, v178
	v_mul_f32_e32 v107, v107, v179
	v_mul_f32_e32 v108, v108, v180
	v_mul_f32_e32 v109, v109, v181
	v_exp_f32_e32 v16, v16
	v_exp_f32_e32 v17, v17
	v_exp_f32_e32 v18, v18
	v_exp_f32_e32 v19, v19
	s_nop 0
	v_fma_f32 v138, -v16, v16, 1.0
	v_fma_f32 v139, -v17, v17, 1.0
	v_fma_f32 v140, -v18, v18, 1.0
	v_fma_f32 v141, -v19, v19, 1.0
	v_max_f32_e32 v138, 0, v138
	v_max_f32_e32 v139, 0, v139
	v_max_f32_e32 v140, 0, v140
	v_max_f32_e32 v141, 0, v141
	v_sqrt_f32_e32 v138, v138
	v_sqrt_f32_e32 v139, v139
	v_sqrt_f32_e32 v140, v140
	v_sqrt_f32_e32 v141, v141
	s_nop 0
; __device__ __forceinline__ float bf2f(u16 h) { return __uint_as_float(((unsigned)h) << 16); }
; __device__ __forceinline__ void lru_tile(const Params& P, int chunk, int head, int pass, char* smem_raw) {
;     ...
;       for (int tc = 0; tc < 4; ++tc)
; #pragma unroll
;         for (int reg = 0; reg < 4; ++reg) {
;           const int tl = wid * 16 + (lane >> 4) * 4 + reg;
;           const int c = 16 * tc + (lane & 15);
;           const float r = __builtin_amdgcn_rcpf(1.f + __builtin_amdgcn_exp2f(acc[tc][reg] + ba[tc]));
;           const float ii = __builtin_amdgcn_rcpf(1.f + __builtin_amdgcn_exp2f(acc[tc + 4][reg] + bi[tc]));
;           const float la = -c8[tc] * r;
;           const float a = __builtin_amdgcn_exp2f(la);
;           const float ucv = bf2f(sm_uc[(sb * 64 + tl) * LDSS + c]);
;           const float bt = __builtin_amdgcn_sqrtf(fmaxf(1.f - a * a, 0.f)) * (ii * ucv);
;           sm_a[tl * 64 + c] = a;
;           sm_b[tl * 64 + c] = bt;
;         }
;       __syncthreads();
;       const int pos = (d == 0) ? q : 3 - q;
;       {
;         float Pp = 1.f, H = 0.f;
; #pragma unroll 4
;         for (int i = 0; i < 16; ++i) {
;           const int tl = (d == 0) ? (q * 16 + i) : (q * 16 + 15 - i);
;           const float a = sm_a[tl * 64 + ch], b = sm_b[tl * 64 + ch];
;           H = a * H + b; Pp *= a;
;         }
;         sm_ph[pos * 64 + ch] = make_float2(Pp, H);
;       }
;       __syncthreads();
;       const float2 p0 = sm_ph[ch], p1 = sm_ph[64 + ch], p2 = sm_ph[128 + ch], p3 = sm_ph[192 + ch];
;       if (pass == 2) {
;         float hin = cB;
;         if (pos > 0) hin = p0.x * hin + p0.y;
;         if (pos > 1) hin = p1.x * hin + p1.y;
;         if (pos > 2) hin = p2.x * hin + p2.y;
;         float h = hin;
;         float hfp[16], gp[16];
;         if (d == 1) {
; #pragma unroll
;           for (int i = 0; i < 16; ++i) {
;             const long rowp = row0 + sb * 64 + q * 16 + 15 - i;
;             hfp[i] = hfbuf[rowp * 512 + gch];
;             gp[i] = bf2f(P.zq[rowp * 1536 + 512 + gch]);
;           }
	v_mul_f32_e32 v106, v138, v106
	v_mul_f32_e32 v107, v139, v107
	v_mul_f32_e32 v108, v140, v108
	v_mul_f32_e32 v109, v141, v109
	v_add_f32_e32 v20, v20, v68
	v_add_f32_e32 v21, v21, v68
	v_add_f32_e32 v22, v22, v68
	v_add_f32_e32 v23, v23, v68
	v_add_f32_e32 v110, v110, v70
	v_add_f32_e32 v111, v111, v70
	v_add_f32_e32 v112, v112, v70
	v_add_f32_e32 v113, v113, v70
	v_exp_f32_e32 v20, v20
	v_exp_f32_e32 v21, v21
	v_exp_f32_e32 v22, v22
	v_exp_f32_e32 v23, v23
	v_exp_f32_e32 v110, v110
	v_exp_f32_e32 v111, v111
	v_exp_f32_e32 v112, v112
	v_exp_f32_e32 v113, v113
	v_add_f32_e32 v20, 1.0, v20
	v_add_f32_e32 v21, 1.0, v21
	v_add_f32_e32 v22, 1.0, v22
	v_add_f32_e32 v23, 1.0, v23
	v_add_f32_e32 v110, 1.0, v110
	v_add_f32_e32 v111, 1.0, v111
	v_add_f32_e32 v112, 1.0, v112
	v_add_f32_e32 v113, 1.0, v113
	v_rcp_f32_e32 v20, v20
	v_rcp_f32_e32 v21, v21
	v_rcp_f32_e32 v22, v22
	v_rcp_f32_e32 v23, v23
	v_rcp_f32_e32 v110, v110
	v_rcp_f32_e32 v111, v111
	v_rcp_f32_e32 v112, v112
	v_rcp_f32_e32 v113, v113
	v_mul_f32_e32 v20, v73, v20
	v_mul_f32_e32 v21, v73, v21
	v_mul_f32_e32 v22, v73, v22
	v_mul_f32_e32 v23, v73, v23
	v_mul_f32_e32 v110, v110, v182
	v_mul_f32_e32 v111, v111, v183
	v_mul_f32_e32 v112, v112, v184
	v_mul_f32_e32 v113, v113, v185
	v_exp_f32_e32 v20, v20
	v_exp_f32_e32 v21, v21
	v_exp_f32_e32 v22, v22
	v_exp_f32_e32 v23, v23
	s_nop 0
	v_fma_f32 v138, -v20, v20, 1.0
	v_fma_f32 v139, -v21, v21, 1.0
	v_fma_f32 v140, -v22, v22, 1.0
	v_fma_f32 v141, -v23, v23, 1.0
	v_max_f32_e32 v138, 0, v138
	v_max_f32_e32 v139, 0, v139
	v_max_f32_e32 v140, 0, v140
	v_max_f32_e32 v141, 0, v141
	v_sqrt_f32_e32 v138, v138
	v_sqrt_f32_e32 v139, v139
	v_sqrt_f32_e32 v140, v140
	v_sqrt_f32_e32 v141, v141
	s_nop 0
	v_mul_f32_e32 v110, v138, v110
	v_mul_f32_e32 v111, v139, v111
	v_mul_f32_e32 v112, v140, v112
	v_mul_f32_e32 v113, v141, v113
	v_add_f32_e32 v24, v24, v68
	v_add_f32_e32 v25, v25, v68
	v_add_f32_e32 v26, v26, v68
	v_add_f32_e32 v27, v27, v68
	v_add_f32_e32 v114, v114, v70
	v_add_f32_e32 v115, v115, v70
	v_add_f32_e32 v116, v116, v70
	v_add_f32_e32 v117, v117, v70
	v_exp_f32_e32 v24, v24
	v_exp_f32_e32 v25, v25
	v_exp_f32_e32 v26, v26
	v_exp_f32_e32 v27, v27
	v_exp_f32_e32 v114, v114
	v_exp_f32_e32 v115, v115
	v_exp_f32_e32 v116, v116
	v_exp_f32_e32 v117, v117
	v_add_f32_e32 v24, 1.0, v24
	v_add_f32_e32 v25, 1.0, v25
	v_add_f32_e32 v26, 1.0, v26
	v_add_f32_e32 v27, 1.0, v27
	v_add_f32_e32 v114, 1.0, v114
	v_add_f32_e32 v115, 1.0, v115
	v_add_f32_e32 v116, 1.0, v116
	v_add_f32_e32 v117, 1.0, v117
	v_rcp_f32_e32 v24, v24
	v_rcp_f32_e32 v25, v25
	v_rcp_f32_e32 v26, v26
	v_rcp_f32_e32 v27, v27
	v_rcp_f32_e32 v114, v114
	v_rcp_f32_e32 v115, v115
	v_rcp_f32_e32 v116, v116
	v_rcp_f32_e32 v117, v117
	v_mul_f32_e32 v24, v73, v24
	v_mul_f32_e32 v25, v73, v25
	v_mul_f32_e32 v26, v73, v26
	v_mul_f32_e32 v27, v73, v27
	v_mul_f32_e32 v114, v114, v186
	v_mul_f32_e32 v115, v115, v187
	v_mul_f32_e32 v116, v116, v188
	v_mul_f32_e32 v117, v117, v189
	v_exp_f32_e32 v24, v24
	v_exp_f32_e32 v25, v25
	v_exp_f32_e32 v26, v26
	v_exp_f32_e32 v27, v27
	s_nop 0
	v_fma_f32 v138, -v24, v24, 1.0
	v_fma_f32 v139, -v25, v25, 1.0
	v_fma_f32 v140, -v26, v26, 1.0
	v_fma_f32 v141, -v27, v27, 1.0
	v_max_f32_e32 v138, 0, v138
	v_max_f32_e32 v139, 0, v139
	v_max_f32_e32 v140, 0, v140
	v_max_f32_e32 v141, 0, v141
	v_sqrt_f32_e32 v138, v138
	v_sqrt_f32_e32 v139, v139
	v_sqrt_f32_e32 v140, v140
	v_sqrt_f32_e32 v141, v141
	s_nop 0
	v_mul_f32_e32 v114, v138, v114
	v_mul_f32_e32 v115, v139, v115
	v_mul_f32_e32 v116, v140, v116
	v_mul_f32_e32 v117, v141, v117
	v_add_f32_e32 v28, v28, v68
	v_add_f32_e32 v29, v29, v68
	v_add_f32_e32 v30, v30, v68
	v_add_f32_e32 v31, v31, v68
	v_add_f32_e32 v118, v118, v70
	v_add_f32_e32 v119, v119, v70
	v_add_f32_e32 v120, v120, v70
	v_add_f32_e32 v121, v121, v70
	v_exp_f32_e32 v28, v28
	v_exp_f32_e32 v29, v29
	v_exp_f32_e32 v30, v30
	v_exp_f32_e32 v31, v31
	v_exp_f32_e32 v118, v118
	v_exp_f32_e32 v119, v119
	v_exp_f32_e32 v120, v120
	v_exp_f32_e32 v121, v121
	v_add_f32_e32 v28, 1.0, v28
	v_add_f32_e32 v29, 1.0, v29
	v_add_f32_e32 v30, 1.0, v30
	v_add_f32_e32 v31, 1.0, v31
	v_add_f32_e32 v118, 1.0, v118
	v_add_f32_e32 v119, 1.0, v119
	v_add_f32_e32 v120, 1.0, v120
	v_add_f32_e32 v121, 1.0, v121
	v_rcp_f32_e32 v28, v28
	v_rcp_f32_e32 v29, v29
	v_rcp_f32_e32 v30, v30
	v_rcp_f32_e32 v31, v31
	v_rcp_f32_e32 v118, v118
	v_rcp_f32_e32 v119, v119
	v_rcp_f32_e32 v120, v120
	v_rcp_f32_e32 v121, v121
	v_mul_f32_e32 v28, v73, v28
	v_mul_f32_e32 v29, v73, v29
	v_mul_f32_e32 v30, v73, v30
	v_mul_f32_e32 v31, v73, v31
	v_mul_f32_e32 v118, v118, v190
	v_mul_f32_e32 v119, v119, v191
	v_mul_f32_e32 v120, v120, v192
	v_mul_f32_e32 v121, v121, v193
	v_exp_f32_e32 v28, v28
	v_exp_f32_e32 v29, v29
	v_exp_f32_e32 v30, v30
	v_exp_f32_e32 v31, v31
	s_nop 0
	v_fma_f32 v138, -v28, v28, 1.0
	v_fma_f32 v139, -v29, v29, 1.0
	v_fma_f32 v140, -v30, v30, 1.0
	v_fma_f32 v141, -v31, v31, 1.0
	v_max_f32_e32 v138, 0, v138
	v_max_f32_e32 v139, 0, v139
	v_max_f32_e32 v140, 0, v140
	v_max_f32_e32 v141, 0, v141
	v_sqrt_f32_e32 v138, v138
	v_sqrt_f32_e32 v139, v139
	v_sqrt_f32_e32 v140, v140
	v_sqrt_f32_e32 v141, v141
	s_nop 0
	v_mul_f32_e32 v118, v138, v118
	v_mul_f32_e32 v119, v139, v119
	v_mul_f32_e32 v120, v140, v120
	v_mul_f32_e32 v121, v141, v121
	s_mul_i32 s0, s71, 0x60000
	s_lshl_b32 s1, s56, 1
	s_add_u32 s0, s0, s1
	s_add_u32 s0, s0, 0x400
	s_add_u32 s4, s10, s0
	s_addc_u32 s5, s11, 0
	global_load_ushort v162, v134, s[4:5]
	s_add_u32 s4, s4, 0xc00
	s_addc_u32 s5, s5, 0
	global_load_ushort v163, v134, s[4:5]
	s_add_u32 s4, s4, 0xc00
	s_addc_u32 s5, s5, 0
	global_load_ushort v164, v134, s[4:5]
; __device__ __forceinline__ float bf2f(u16 h) { return __uint_as_float(((unsigned)h) << 16); }
; __device__ __forceinline__ void lru_tile(const Params& P, int chunk, int head, int pass, char* smem_raw) {
;     ...
;         float Pp = 1.f, H = 0.f;
; #pragma unroll 4
;         for (int i = 0; i < 16; ++i) {
;           const int tl = (d == 0) ? (q * 16 + i) : (q * 16 + 15 - i);
;           const float a = sm_a[tl * 64 + ch], b = sm_b[tl * 64 + ch];
;           H = a * H + b; Pp *= a;
;         }
;         sm_ph[pos * 64 + ch] = make_float2(Pp, H);
;       }
;       __syncthreads();
;       const float2 p0 = sm_ph[ch], p1 = sm_ph[64 + ch], p2 = sm_ph[128 + ch], p3 = sm_ph[192 + ch];
;       if (pass == 2) {
;         float hin = cB;
;         if (pos > 0) hin = p0.x * hin + p0.y;
;         if (pos > 1) hin = p1.x * hin + p1.y;
;         if (pos > 2) hin = p2.x * hin + p2.y;
;         float h = hin;
;         float hfp[16], gp[16];
;         if (d == 1) {
; #pragma unroll
;           for (int i = 0; i < 16; ++i) {
;             const long rowp = row0 + sb * 64 + q * 16 + 15 - i;
;             hfp[i] = hfbuf[rowp * 512 + gch];
;             gp[i] = bf2f(P.zq[rowp * 1536 + 512 + gch]);
;           }
;         }
; #pragma unroll
;         for (int i = 0; i < 16; ++i) {
;           const int tl = (d == 0) ? (q * 16 + i) : (q * 16 + 15 - i);
;           const float a = sm_a[tl * 64 + ch], b = sm_b[tl * 64 + ch];
;           h = a * h + b;
	s_add_u32 s4, s4, 0xc00
	s_addc_u32 s5, s5, 0
	global_load_ushort v165, v134, s[4:5]
	s_add_u32 s4, s4, 0xc00
	s_addc_u32 s5, s5, 0
	global_load_ushort v166, v134, s[4:5]
	s_add_u32 s4, s4, 0xc00
	s_addc_u32 s5, s5, 0
	global_load_ushort v167, v134, s[4:5]
	s_add_u32 s4, s4, 0xc00
	s_addc_u32 s5, s5, 0
	global_load_ushort v168, v134, s[4:5]
	s_add_u32 s4, s4, 0xc00
	s_addc_u32 s5, s5, 0
	global_load_ushort v169, v134, s[4:5]
	s_add_u32 s4, s4, 0xc00
	s_addc_u32 s5, s5, 0
	global_load_ushort v170, v134, s[4:5]
	s_add_u32 s4, s4, 0xc00
	s_addc_u32 s5, s5, 0
	global_load_ushort v171, v134, s[4:5]
	s_add_u32 s4, s4, 0xc00
	s_addc_u32 s5, s5, 0
	global_load_ushort v172, v134, s[4:5]
	s_add_u32 s4, s4, 0xc00
	s_addc_u32 s5, s5, 0
	global_load_ushort v173, v134, s[4:5]
	s_add_u32 s4, s4, 0xc00
	s_addc_u32 s5, s5, 0
	global_load_ushort v174, v134, s[4:5]
	s_add_u32 s4, s4, 0xc00
	s_addc_u32 s5, s5, 0
	global_load_ushort v175, v134, s[4:5]
	s_add_u32 s4, s4, 0xc00
	s_addc_u32 s5, s5, 0
	global_load_ushort v176, v134, s[4:5]
	s_add_u32 s4, s4, 0xc00
	s_addc_u32 s5, s5, 0
	global_load_ushort v177, v134, s[4:5]
	s_add_u32 s4, s4, 0xc00
	s_addc_u32 s5, s5, 0
	global_load_ushort v178, v134, s[4:5]
	s_add_u32 s4, s4, 0xc00
	s_addc_u32 s5, s5, 0
	global_load_ushort v179, v134, s[4:5]
	s_add_u32 s4, s4, 0xc00
	s_addc_u32 s5, s5, 0
	global_load_ushort v180, v134, s[4:5]
	s_add_u32 s4, s4, 0xc00
	s_addc_u32 s5, s5, 0
	global_load_ushort v181, v134, s[4:5]
	s_add_u32 s4, s4, 0xc00
	s_addc_u32 s5, s5, 0
	global_load_ushort v182, v134, s[4:5]
	s_add_u32 s4, s4, 0xc00
	s_addc_u32 s5, s5, 0
	global_load_ushort v183, v134, s[4:5]
	s_add_u32 s4, s4, 0xc00
	s_addc_u32 s5, s5, 0
	global_load_ushort v184, v134, s[4:5]
	s_add_u32 s4, s4, 0xc00
	s_addc_u32 s5, s5, 0
	global_load_ushort v185, v134, s[4:5]
	s_add_u32 s4, s4, 0xc00
	s_addc_u32 s5, s5, 0
	global_load_ushort v186, v134, s[4:5]
	s_add_u32 s4, s4, 0xc00
	s_addc_u32 s5, s5, 0
	global_load_ushort v187, v134, s[4:5]
	s_add_u32 s4, s4, 0xc00
	s_addc_u32 s5, s5, 0
	global_load_ushort v188, v134, s[4:5]
	s_add_u32 s4, s4, 0xc00
	s_addc_u32 s5, s5, 0
	global_load_ushort v189, v134, s[4:5]
	s_add_u32 s4, s4, 0xc00
	s_addc_u32 s5, s5, 0
	global_load_ushort v190, v134, s[4:5]
	s_add_u32 s4, s4, 0xc00
	s_addc_u32 s5, s5, 0
	global_load_ushort v191, v134, s[4:5]
	s_add_u32 s4, s4, 0xc00
	s_addc_u32 s5, s5, 0
	global_load_ushort v192, v134, s[4:5]
	s_add_u32 s4, s4, 0xc00
	s_addc_u32 s5, s5, 0
	global_load_ushort v193, v134, s[4:5]
	v_mov_b32_e32 v253, v31
	v_mov_b32_e32 v254, v121
	v_fma_f32 v254, v30, v254, v120
	v_mul_f32_e32 v253, v253, v30
	v_fma_f32 v254, v29, v254, v119
	v_mul_f32_e32 v253, v253, v29
	v_fma_f32 v254, v28, v254, v118
	v_mul_f32_e32 v253, v253, v28
	v_fma_f32 v254, v27, v254, v117
	v_mul_f32_e32 v253, v253, v27
	v_fma_f32 v254, v26, v254, v116
	v_mul_f32_e32 v253, v253, v26
	v_fma_f32 v254, v25, v254, v115
	v_mul_f32_e32 v253, v253, v25
	v_fma_f32 v254, v24, v254, v114
	v_mul_f32_e32 v253, v253, v24
	v_fma_f32 v254, v23, v254, v113
	v_mul_f32_e32 v253, v253, v23
	v_fma_f32 v254, v22, v254, v112
	v_mul_f32_e32 v253, v253, v22
	v_fma_f32 v254, v21, v254, v111
	v_mul_f32_e32 v253, v253, v21
	v_fma_f32 v254, v20, v254, v110
	v_mul_f32_e32 v253, v253, v20
	v_fma_f32 v254, v19, v254, v109
	v_mul_f32_e32 v253, v253, v19
	v_fma_f32 v254, v18, v254, v108
	v_mul_f32_e32 v253, v253, v18
	v_fma_f32 v254, v17, v254, v107
	v_mul_f32_e32 v253, v253, v17
	v_fma_f32 v254, v16, v254, v106
	v_mul_f32_e32 v253, v253, v16
	v_fma_f32 v254, v15, v254, v105
	v_mul_f32_e32 v253, v253, v15
	v_fma_f32 v254, v14, v254, v104
	v_mul_f32_e32 v253, v253, v14
	v_fma_f32 v254, v13, v254, v103
	v_mul_f32_e32 v253, v253, v13
	v_fma_f32 v254, v12, v254, v102
	v_mul_f32_e32 v253, v253, v12
	v_fma_f32 v254, v11, v254, v101
	v_mul_f32_e32 v253, v253, v11
	v_fma_f32 v254, v10, v254, v100
	v_mul_f32_e32 v253, v253, v10
	v_fma_f32 v254, v9, v254, v99
	v_mul_f32_e32 v253, v253, v9
	v_fma_f32 v254, v8, v254, v98
	v_mul_f32_e32 v253, v253, v8
	v_fma_f32 v254, v7, v254, v97
	v_mul_f32_e32 v253, v253, v7
	v_fma_f32 v254, v6, v254, v96
	v_mul_f32_e32 v253, v253, v6
	v_fma_f32 v254, v5, v254, v95
	v_mul_f32_e32 v253, v253, v5
	v_fma_f32 v254, v4, v254, v94
	v_mul_f32_e32 v253, v253, v4
	v_fma_f32 v254, v3, v254, v93
	v_mul_f32_e32 v253, v253, v3
	v_fma_f32 v254, v2, v254, v92
	v_mul_f32_e32 v253, v253, v2
	v_fma_f32 v254, v1, v254, v91
	v_mul_f32_e32 v253, v253, v1
	v_fma_f32 v254, v0, v254, v90
	v_mul_f32_e32 v253, v253, v0
	v_mov_b32_e32 v138, v253
	v_mov_b32_e32 v139, v253
	s_nop 1
	v_permlane16_swap_b32_e32 v138, v139
	v_mov_b32_e32 v140, v138
	v_mov_b32_e32 v141, v139
	s_nop 1
	v_permlane32_swap_b32_e32 v138, v140
	v_permlane32_swap_b32_e32 v139, v141
	v_mov_b32_e32 v198, v254
	v_mov_b32_e32 v199, v254
	s_nop 1
	v_permlane16_swap_b32_e32 v198, v199
	v_mov_b32_e32 v200, v198
	v_mov_b32_e32 v201, v199
	s_nop 1
	v_permlane32_swap_b32_e32 v198, v200
	v_permlane32_swap_b32_e32 v199, v201
	v_mov_b32_e32 v202, v67
	v_fma_f32 v151, v141, v202, v201
	v_fma_f32 v150, v140, v151, v200
	v_fma_f32 v136, v139, v150, v199
	v_mov_b32_e32 v254, v202
	v_cndmask_b32_e64 v254, v254, v151, s[78:79]
	v_cndmask_b32_e64 v254, v254, v150, s[80:81]
	v_cndmask_b32_e64 v254, v254, v136, s[82:83]
	v_fma_f32 v121, v31, v254, v121
	v_fma_f32 v120, v30, v121, v120
	v_fma_f32 v119, v29, v120, v119
	v_fma_f32 v118, v28, v119, v118
	v_fma_f32 v117, v27, v118, v117
	v_fma_f32 v116, v26, v117, v116
	v_fma_f32 v115, v25, v116, v115
	v_fma_f32 v114, v24, v115, v114
	v_fma_f32 v113, v23, v114, v113
	v_fma_f32 v112, v22, v113, v112
	v_fma_f32 v111, v21, v112, v111
	v_fma_f32 v110, v20, v111, v110
	v_fma_f32 v109, v19, v110, v109
	v_fma_f32 v108, v18, v109, v108
	v_fma_f32 v107, v17, v108, v107
	v_fma_f32 v106, v16, v107, v106
	v_fma_f32 v105, v15, v106, v105
	v_fma_f32 v104, v14, v105, v104
	v_fma_f32 v103, v13, v104, v103
	v_fma_f32 v102, v12, v103, v102
	v_fma_f32 v101, v11, v102, v101
	v_fma_f32 v100, v10, v101, v100
	v_fma_f32 v99, v9, v100, v99
	v_fma_f32 v98, v8, v99, v98
	v_fma_f32 v97, v7, v98, v97
	v_fma_f32 v96, v6, v97, v96
	v_fma_f32 v95, v5, v96, v95
	v_fma_f32 v94, v4, v95, v94
	v_fma_f32 v93, v3, v94, v93
	v_fma_f32 v92, v2, v93, v92
	v_fma_f32 v91, v1, v92, v91
	v_fma_f32 v90, v0, v91, v90
	s_waitcnt vmcnt(0)
; __device__ __forceinline__ void lru_tile(const Params& P, int chunk, int head, int pass, char* smem_raw) {
;     ...
;           } else {
;             const float hfv = hfp[i];
;             const float g = gp[i];
;             const float tz = 0.7978845608028654f * (g + 0.044715f * g * g * g);
;             const float th = 1.f - 2.f * __builtin_amdgcn_rcpf(1.f + __expf(2.f * tz));
;             const float ge = 0.5f * g * (1.f + th);
;             P.cat[row * 1024 + gch] = f2bf((hfv + h) * ge);
	v_lshlrev_b32_e32 v162, 16, v162
	v_lshlrev_b32_e32 v163, 16, v163
	v_lshlrev_b32_e32 v164, 16, v164
	v_lshlrev_b32_e32 v165, 16, v165
	v_lshlrev_b32_e32 v166, 16, v166
	v_lshlrev_b32_e32 v167, 16, v167
	v_lshlrev_b32_e32 v168, 16, v168
	v_lshlrev_b32_e32 v169, 16, v169
	v_lshlrev_b32_e32 v170, 16, v170
	v_lshlrev_b32_e32 v171, 16, v171
	v_lshlrev_b32_e32 v172, 16, v172
	v_lshlrev_b32_e32 v173, 16, v173
	v_lshlrev_b32_e32 v174, 16, v174
	v_lshlrev_b32_e32 v175, 16, v175
	v_lshlrev_b32_e32 v176, 16, v176
	v_lshlrev_b32_e32 v177, 16, v177
	v_lshlrev_b32_e32 v178, 16, v178
	v_lshlrev_b32_e32 v179, 16, v179
	v_lshlrev_b32_e32 v180, 16, v180
	v_lshlrev_b32_e32 v181, 16, v181
	v_lshlrev_b32_e32 v182, 16, v182
	v_lshlrev_b32_e32 v183, 16, v183
	v_lshlrev_b32_e32 v184, 16, v184
	v_lshlrev_b32_e32 v185, 16, v185
	v_lshlrev_b32_e32 v186, 16, v186
	v_lshlrev_b32_e32 v187, 16, v187
	v_lshlrev_b32_e32 v188, 16, v188
	v_lshlrev_b32_e32 v189, 16, v189
	v_lshlrev_b32_e32 v190, 16, v190
	v_lshlrev_b32_e32 v191, 16, v191
	v_lshlrev_b32_e32 v192, 16, v192
	v_lshlrev_b32_e32 v193, 16, v193
	v_mov_b32_e32 v202, 0x3d372713
	v_mul_f32_e32 v138, v162, v162
	v_mul_f32_e32 v139, v163, v163
	v_mul_f32_e32 v140, v164, v164
	v_mul_f32_e32 v141, v165, v165
	v_mul_f32_e32 v138, v138, v162
	v_mul_f32_e32 v139, v139, v163
	v_mul_f32_e32 v140, v140, v164
	v_mul_f32_e32 v141, v141, v165
	v_fma_f32 v138, v202, v138, v162
	v_fma_f32 v139, v202, v139, v163
	v_fma_f32 v140, v202, v140, v164
	v_fma_f32 v141, v202, v141, v165
	v_mul_f32_e32 v138, 0x40135761, v138
	v_mul_f32_e32 v139, 0x40135761, v139
	v_mul_f32_e32 v140, 0x40135761, v140
	v_mul_f32_e32 v141, 0x40135761, v141
	v_exp_f32_e32 v138, v138
	v_exp_f32_e32 v139, v139
	v_exp_f32_e32 v140, v140
	v_exp_f32_e32 v141, v141
	s_nop 0
	v_add_f32_e32 v138, 1.0, v138
	v_add_f32_e32 v139, 1.0, v139
	v_add_f32_e32 v140, 1.0, v140
	v_add_f32_e32 v141, 1.0, v141
	v_rcp_f32_e32 v138, v138
	v_rcp_f32_e32 v139, v139
	v_rcp_f32_e32 v140, v140
	v_rcp_f32_e32 v141, v141
	s_nop 0
	v_fma_f32 v138, -2.0, v138, 1.0
	v_fma_f32 v139, -2.0, v139, 1.0
	v_fma_f32 v140, -2.0, v140, 1.0
	v_fma_f32 v141, -2.0, v141, 1.0
	v_add_f32_e32 v138, 1.0, v138
	v_add_f32_e32 v139, 1.0, v139
	v_add_f32_e32 v140, 1.0, v140
	v_add_f32_e32 v141, 1.0, v141
	v_mul_f32_e32 v162, 0.5, v162
	v_mul_f32_e32 v163, 0.5, v163
	v_mul_f32_e32 v164, 0.5, v164
	v_mul_f32_e32 v165, 0.5, v165
	v_mul_f32_e32 v162, v162, v138
	v_mul_f32_e32 v163, v163, v139
	v_mul_f32_e32 v164, v164, v140
	v_mul_f32_e32 v165, v165, v141
	v_add_f32_e32 v90, v205, v90
	v_add_f32_e32 v91, v206, v91
	v_add_f32_e32 v92, v207, v92
	v_add_f32_e32 v93, v208, v93
	v_mul_f32_e32 v90, v90, v162
	v_mul_f32_e32 v91, v91, v163
	v_mul_f32_e32 v92, v92, v164
	v_mul_f32_e32 v93, v93, v165
	v_cvt_pk_bf16_f32 v90, v90, v90
	v_cvt_pk_bf16_f32 v91, v91, v91
	v_cvt_pk_bf16_f32 v92, v92, v92
	v_cvt_pk_bf16_f32 v93, v93, v93
	v_mul_f32_e32 v138, v166, v166
	v_mul_f32_e32 v139, v167, v167
	v_mul_f32_e32 v140, v168, v168
	v_mul_f32_e32 v141, v169, v169
	v_mul_f32_e32 v138, v138, v166
	v_mul_f32_e32 v139, v139, v167
	v_mul_f32_e32 v140, v140, v168
	v_mul_f32_e32 v141, v141, v169
	v_fma_f32 v138, v202, v138, v166
	v_fma_f32 v139, v202, v139, v167
	v_fma_f32 v140, v202, v140, v168
	v_fma_f32 v141, v202, v141, v169
	v_mul_f32_e32 v138, 0x40135761, v138
	v_mul_f32_e32 v139, 0x40135761, v139
	v_mul_f32_e32 v140, 0x40135761, v140
	v_mul_f32_e32 v141, 0x40135761, v141
	v_exp_f32_e32 v138, v138
	v_exp_f32_e32 v139, v139
	v_exp_f32_e32 v140, v140
	v_exp_f32_e32 v141, v141
	s_nop 0
	v_add_f32_e32 v138, 1.0, v138
	v_add_f32_e32 v139, 1.0, v139
	v_add_f32_e32 v140, 1.0, v140
	v_add_f32_e32 v141, 1.0, v141
	v_rcp_f32_e32 v138, v138
	v_rcp_f32_e32 v139, v139
	v_rcp_f32_e32 v140, v140
	v_rcp_f32_e32 v141, v141
	s_nop 0
	v_fma_f32 v138, -2.0, v138, 1.0
	v_fma_f32 v139, -2.0, v139, 1.0
	v_fma_f32 v140, -2.0, v140, 1.0
	v_fma_f32 v141, -2.0, v141, 1.0
	v_add_f32_e32 v138, 1.0, v138
	v_add_f32_e32 v139, 1.0, v139
	v_add_f32_e32 v140, 1.0, v140
	v_add_f32_e32 v141, 1.0, v141
	v_mul_f32_e32 v166, 0.5, v166
	v_mul_f32_e32 v167, 0.5, v167
	v_mul_f32_e32 v168, 0.5, v168
	v_mul_f32_e32 v169, 0.5, v169
	v_mul_f32_e32 v166, v166, v138
	v_mul_f32_e32 v167, v167, v139
	v_mul_f32_e32 v168, v168, v140
	v_mul_f32_e32 v169, v169, v141
	v_add_f32_e32 v94, v209, v94
	v_add_f32_e32 v95, v210, v95
	v_add_f32_e32 v96, v211, v96
	v_add_f32_e32 v97, v212, v97
	v_mul_f32_e32 v94, v94, v166
	v_mul_f32_e32 v95, v95, v167
	v_mul_f32_e32 v96, v96, v168
	v_mul_f32_e32 v97, v97, v169
	v_cvt_pk_bf16_f32 v94, v94, v94
	v_cvt_pk_bf16_f32 v95, v95, v95
	v_cvt_pk_bf16_f32 v96, v96, v96
	v_cvt_pk_bf16_f32 v97, v97, v97
	v_mul_f32_e32 v138, v170, v170
	v_mul_f32_e32 v139, v171, v171
	v_mul_f32_e32 v140, v172, v172
	v_mul_f32_e32 v141, v173, v173
	v_mul_f32_e32 v138, v138, v170
	v_mul_f32_e32 v139, v139, v171
	v_mul_f32_e32 v140, v140, v172
	v_mul_f32_e32 v141, v141, v173
	v_fma_f32 v138, v202, v138, v170
	v_fma_f32 v139, v202, v139, v171
	v_fma_f32 v140, v202, v140, v172
	v_fma_f32 v141, v202, v141, v173
	v_mul_f32_e32 v138, 0x40135761, v138
	v_mul_f32_e32 v139, 0x40135761, v139
	v_mul_f32_e32 v140, 0x40135761, v140
	v_mul_f32_e32 v141, 0x40135761, v141
	v_exp_f32_e32 v138, v138
	v_exp_f32_e32 v139, v139
	v_exp_f32_e32 v140, v140
	v_exp_f32_e32 v141, v141
	s_nop 0
	v_add_f32_e32 v138, 1.0, v138
	v_add_f32_e32 v139, 1.0, v139
	v_add_f32_e32 v140, 1.0, v140
	v_add_f32_e32 v141, 1.0, v141
	v_rcp_f32_e32 v138, v138
	v_rcp_f32_e32 v139, v139
	v_rcp_f32_e32 v140, v140
	v_rcp_f32_e32 v141, v141
	s_nop 0
	v_fma_f32 v138, -2.0, v138, 1.0
	v_fma_f32 v139, -2.0, v139, 1.0
; __device__ __forceinline__ void lru_tile(const Params& P, int chunk, int head, int pass, char* smem_raw) {
;     ...
;           } else {
;             const float hfv = hfp[i];
;             const float g = gp[i];
;             const float tz = 0.7978845608028654f * (g + 0.044715f * g * g * g);
;             const float th = 1.f - 2.f * __builtin_amdgcn_rcpf(1.f + __expf(2.f * tz));
;             const float ge = 0.5f * g * (1.f + th);
;             P.cat[row * 1024 + gch] = f2bf((hfv + h) * ge);
	v_fma_f32 v140, -2.0, v140, 1.0
	v_fma_f32 v141, -2.0, v141, 1.0
	v_add_f32_e32 v138, 1.0, v138
	v_add_f32_e32 v139, 1.0, v139
	v_add_f32_e32 v140, 1.0, v140
	v_add_f32_e32 v141, 1.0, v141
	v_mul_f32_e32 v170, 0.5, v170
	v_mul_f32_e32 v171, 0.5, v171
	v_mul_f32_e32 v172, 0.5, v172
	v_mul_f32_e32 v173, 0.5, v173
	v_mul_f32_e32 v170, v170, v138
	v_mul_f32_e32 v171, v171, v139
	v_mul_f32_e32 v172, v172, v140
	v_mul_f32_e32 v173, v173, v141
	v_add_f32_e32 v98, v213, v98
	v_add_f32_e32 v99, v214, v99
	v_add_f32_e32 v100, v215, v100
	v_add_f32_e32 v101, v216, v101
	v_mul_f32_e32 v98, v98, v170
	v_mul_f32_e32 v99, v99, v171
	v_mul_f32_e32 v100, v100, v172
	v_mul_f32_e32 v101, v101, v173
	v_cvt_pk_bf16_f32 v98, v98, v98
	v_cvt_pk_bf16_f32 v99, v99, v99
	v_cvt_pk_bf16_f32 v100, v100, v100
	v_cvt_pk_bf16_f32 v101, v101, v101
	v_mul_f32_e32 v138, v174, v174
	v_mul_f32_e32 v139, v175, v175
	v_mul_f32_e32 v140, v176, v176
	v_mul_f32_e32 v141, v177, v177
	v_mul_f32_e32 v138, v138, v174
	v_mul_f32_e32 v139, v139, v175
	v_mul_f32_e32 v140, v140, v176
	v_mul_f32_e32 v141, v141, v177
	v_fma_f32 v138, v202, v138, v174
	v_fma_f32 v139, v202, v139, v175
	v_fma_f32 v140, v202, v140, v176
	v_fma_f32 v141, v202, v141, v177
	v_mul_f32_e32 v138, 0x40135761, v138
	v_mul_f32_e32 v139, 0x40135761, v139
	v_mul_f32_e32 v140, 0x40135761, v140
	v_mul_f32_e32 v141, 0x40135761, v141
	v_exp_f32_e32 v138, v138
	v_exp_f32_e32 v139, v139
	v_exp_f32_e32 v140, v140
	v_exp_f32_e32 v141, v141
	s_nop 0
	v_add_f32_e32 v138, 1.0, v138
	v_add_f32_e32 v139, 1.0, v139
	v_add_f32_e32 v140, 1.0, v140
	v_add_f32_e32 v141, 1.0, v141
	v_rcp_f32_e32 v138, v138
	v_rcp_f32_e32 v139, v139
	v_rcp_f32_e32 v140, v140
	v_rcp_f32_e32 v141, v141
	s_nop 0
	v_fma_f32 v138, -2.0, v138, 1.0
	v_fma_f32 v139, -2.0, v139, 1.0
	v_fma_f32 v140, -2.0, v140, 1.0
	v_fma_f32 v141, -2.0, v141, 1.0
	v_add_f32_e32 v138, 1.0, v138
	v_add_f32_e32 v139, 1.0, v139
	v_add_f32_e32 v140, 1.0, v140
	v_add_f32_e32 v141, 1.0, v141
	v_mul_f32_e32 v174, 0.5, v174
	v_mul_f32_e32 v175, 0.5, v175
	v_mul_f32_e32 v176, 0.5, v176
	v_mul_f32_e32 v177, 0.5, v177
	v_mul_f32_e32 v174, v174, v138
	v_mul_f32_e32 v175, v175, v139
	v_mul_f32_e32 v176, v176, v140
	v_mul_f32_e32 v177, v177, v141
	v_add_f32_e32 v102, v217, v102
	v_add_f32_e32 v103, v218, v103
	v_add_f32_e32 v104, v219, v104
	v_add_f32_e32 v105, v220, v105
	v_mul_f32_e32 v102, v102, v174
	v_mul_f32_e32 v103, v103, v175
	v_mul_f32_e32 v104, v104, v176
	v_mul_f32_e32 v105, v105, v177
	v_cvt_pk_bf16_f32 v102, v102, v102
	v_cvt_pk_bf16_f32 v103, v103, v103
	v_cvt_pk_bf16_f32 v104, v104, v104
	v_cvt_pk_bf16_f32 v105, v105, v105
	v_mul_f32_e32 v138, v178, v178
	v_mul_f32_e32 v139, v179, v179
	v_mul_f32_e32 v140, v180, v180
	v_mul_f32_e32 v141, v181, v181
	v_mul_f32_e32 v138, v138, v178
	v_mul_f32_e32 v139, v139, v179
	v_mul_f32_e32 v140, v140, v180
	v_mul_f32_e32 v141, v141, v181
	v_fma_f32 v138, v202, v138, v178
	v_fma_f32 v139, v202, v139, v179
	v_fma_f32 v140, v202, v140, v180
	v_fma_f32 v141, v202, v141, v181
	v_mul_f32_e32 v138, 0x40135761, v138
	v_mul_f32_e32 v139, 0x40135761, v139
	v_mul_f32_e32 v140, 0x40135761, v140
	v_mul_f32_e32 v141, 0x40135761, v141
	v_exp_f32_e32 v138, v138
	v_exp_f32_e32 v139, v139
	v_exp_f32_e32 v140, v140
	v_exp_f32_e32 v141, v141
	s_nop 0
	v_add_f32_e32 v138, 1.0, v138
	v_add_f32_e32 v139, 1.0, v139
	v_add_f32_e32 v140, 1.0, v140
	v_add_f32_e32 v141, 1.0, v141
	v_rcp_f32_e32 v138, v138
	v_rcp_f32_e32 v139, v139
	v_rcp_f32_e32 v140, v140
	v_rcp_f32_e32 v141, v141
	s_nop 0
	v_fma_f32 v138, -2.0, v138, 1.0
	v_fma_f32 v139, -2.0, v139, 1.0
	v_fma_f32 v140, -2.0, v140, 1.0
	v_fma_f32 v141, -2.0, v141, 1.0
	v_add_f32_e32 v138, 1.0, v138
	v_add_f32_e32 v139, 1.0, v139
	v_add_f32_e32 v140, 1.0, v140
	v_add_f32_e32 v141, 1.0, v141
	v_mul_f32_e32 v178, 0.5, v178
	v_mul_f32_e32 v179, 0.5, v179
	v_mul_f32_e32 v180, 0.5, v180
	v_mul_f32_e32 v181, 0.5, v181
	v_mul_f32_e32 v178, v178, v138
	v_mul_f32_e32 v179, v179, v139
	v_mul_f32_e32 v180, v180, v140
	v_mul_f32_e32 v181, v181, v141
	v_add_f32_e32 v106, v221, v106
	v_add_f32_e32 v107, v222, v107
	v_add_f32_e32 v108, v223, v108
	v_add_f32_e32 v109, v224, v109
	v_mul_f32_e32 v106, v106, v178
	v_mul_f32_e32 v107, v107, v179
	v_mul_f32_e32 v108, v108, v180
	v_mul_f32_e32 v109, v109, v181
	v_cvt_pk_bf16_f32 v106, v106, v106
	v_cvt_pk_bf16_f32 v107, v107, v107
	v_cvt_pk_bf16_f32 v108, v108, v108
	v_cvt_pk_bf16_f32 v109, v109, v109
	v_mul_f32_e32 v138, v182, v182
	v_mul_f32_e32 v139, v183, v183
	v_mul_f32_e32 v140, v184, v184
	v_mul_f32_e32 v141, v185, v185
	v_mul_f32_e32 v138, v138, v182
	v_mul_f32_e32 v139, v139, v183
	v_mul_f32_e32 v140, v140, v184
	v_mul_f32_e32 v141, v141, v185
	v_fma_f32 v138, v202, v138, v182
	v_fma_f32 v139, v202, v139, v183
	v_fma_f32 v140, v202, v140, v184
	v_fma_f32 v141, v202, v141, v185
	v_mul_f32_e32 v138, 0x40135761, v138
	v_mul_f32_e32 v139, 0x40135761, v139
	v_mul_f32_e32 v140, 0x40135761, v140
	v_mul_f32_e32 v141, 0x40135761, v141
	v_exp_f32_e32 v138, v138
	v_exp_f32_e32 v139, v139
	v_exp_f32_e32 v140, v140
	v_exp_f32_e32 v141, v141
	s_nop 0
	v_add_f32_e32 v138, 1.0, v138
	v_add_f32_e32 v139, 1.0, v139
	v_add_f32_e32 v140, 1.0, v140
	v_add_f32_e32 v141, 1.0, v141
	v_rcp_f32_e32 v138, v138
	v_rcp_f32_e32 v139, v139
	v_rcp_f32_e32 v140, v140
	v_rcp_f32_e32 v141, v141
	s_nop 0
	v_fma_f32 v138, -2.0, v138, 1.0
	v_fma_f32 v139, -2.0, v139, 1.0
	v_fma_f32 v140, -2.0, v140, 1.0
	v_fma_f32 v141, -2.0, v141, 1.0
	v_add_f32_e32 v138, 1.0, v138
	v_add_f32_e32 v139, 1.0, v139
	v_add_f32_e32 v140, 1.0, v140
	v_add_f32_e32 v141, 1.0, v141
	v_mul_f32_e32 v182, 0.5, v182
	v_mul_f32_e32 v183, 0.5, v183
; __device__ __forceinline__ void lru_tile(const Params& P, int chunk, int head, int pass, char* smem_raw) {
;     ...
;           } else {
;             const float hfv = hfp[i];
;             const float g = gp[i];
;             const float tz = 0.7978845608028654f * (g + 0.044715f * g * g * g);
;             const float th = 1.f - 2.f * __builtin_amdgcn_rcpf(1.f + __expf(2.f * tz));
;             const float ge = 0.5f * g * (1.f + th);
;             P.cat[row * 1024 + gch] = f2bf((hfv + h) * ge);
	v_mul_f32_e32 v184, 0.5, v184
	v_mul_f32_e32 v185, 0.5, v185
	v_mul_f32_e32 v182, v182, v138
	v_mul_f32_e32 v183, v183, v139
	v_mul_f32_e32 v184, v184, v140
	v_mul_f32_e32 v185, v185, v141
	v_add_f32_e32 v110, v225, v110
	v_add_f32_e32 v111, v226, v111
	v_add_f32_e32 v112, v227, v112
	v_add_f32_e32 v113, v228, v113
	v_mul_f32_e32 v110, v110, v182
	v_mul_f32_e32 v111, v111, v183
	v_mul_f32_e32 v112, v112, v184
	v_mul_f32_e32 v113, v113, v185
	v_cvt_pk_bf16_f32 v110, v110, v110
	v_cvt_pk_bf16_f32 v111, v111, v111
	v_cvt_pk_bf16_f32 v112, v112, v112
	v_cvt_pk_bf16_f32 v113, v113, v113
	v_mul_f32_e32 v138, v186, v186
	v_mul_f32_e32 v139, v187, v187
	v_mul_f32_e32 v140, v188, v188
	v_mul_f32_e32 v141, v189, v189
	v_mul_f32_e32 v138, v138, v186
	v_mul_f32_e32 v139, v139, v187
	v_mul_f32_e32 v140, v140, v188
	v_mul_f32_e32 v141, v141, v189
	v_fma_f32 v138, v202, v138, v186
	v_fma_f32 v139, v202, v139, v187
	v_fma_f32 v140, v202, v140, v188
	v_fma_f32 v141, v202, v141, v189
	v_mul_f32_e32 v138, 0x40135761, v138
	v_mul_f32_e32 v139, 0x40135761, v139
	v_mul_f32_e32 v140, 0x40135761, v140
	v_mul_f32_e32 v141, 0x40135761, v141
	v_exp_f32_e32 v138, v138
	v_exp_f32_e32 v139, v139
	v_exp_f32_e32 v140, v140
	v_exp_f32_e32 v141, v141
	s_nop 0
	v_add_f32_e32 v138, 1.0, v138
	v_add_f32_e32 v139, 1.0, v139
	v_add_f32_e32 v140, 1.0, v140
	v_add_f32_e32 v141, 1.0, v141
	v_rcp_f32_e32 v138, v138
	v_rcp_f32_e32 v139, v139
	v_rcp_f32_e32 v140, v140
	v_rcp_f32_e32 v141, v141
	s_nop 0
	v_fma_f32 v138, -2.0, v138, 1.0
	v_fma_f32 v139, -2.0, v139, 1.0
	v_fma_f32 v140, -2.0, v140, 1.0
	v_fma_f32 v141, -2.0, v141, 1.0
	v_add_f32_e32 v138, 1.0, v138
	v_add_f32_e32 v139, 1.0, v139
	v_add_f32_e32 v140, 1.0, v140
	v_add_f32_e32 v141, 1.0, v141
	v_mul_f32_e32 v186, 0.5, v186
	v_mul_f32_e32 v187, 0.5, v187
	v_mul_f32_e32 v188, 0.5, v188
	v_mul_f32_e32 v189, 0.5, v189
	v_mul_f32_e32 v186, v186, v138
	v_mul_f32_e32 v187, v187, v139
	v_mul_f32_e32 v188, v188, v140
	v_mul_f32_e32 v189, v189, v141
	v_add_f32_e32 v114, v229, v114
	v_add_f32_e32 v115, v230, v115
	v_add_f32_e32 v116, v231, v116
	v_add_f32_e32 v117, v232, v117
	v_mul_f32_e32 v114, v114, v186
	v_mul_f32_e32 v115, v115, v187
	v_mul_f32_e32 v116, v116, v188
	v_mul_f32_e32 v117, v117, v189
	v_cvt_pk_bf16_f32 v114, v114, v114
	v_cvt_pk_bf16_f32 v115, v115, v115
	v_cvt_pk_bf16_f32 v116, v116, v116
	v_cvt_pk_bf16_f32 v117, v117, v117
	v_mul_f32_e32 v138, v190, v190
	v_mul_f32_e32 v139, v191, v191
	v_mul_f32_e32 v140, v192, v192
	v_mul_f32_e32 v141, v193, v193
	v_mul_f32_e32 v138, v138, v190
	v_mul_f32_e32 v139, v139, v191
	v_mul_f32_e32 v140, v140, v192
	v_mul_f32_e32 v141, v141, v193
	v_fma_f32 v138, v202, v138, v190
	v_fma_f32 v139, v202, v139, v191
	v_fma_f32 v140, v202, v140, v192
	v_fma_f32 v141, v202, v141, v193
	v_mul_f32_e32 v138, 0x40135761, v138
	v_mul_f32_e32 v139, 0x40135761, v139
	v_mul_f32_e32 v140, 0x40135761, v140
	v_mul_f32_e32 v141, 0x40135761, v141
	v_exp_f32_e32 v138, v138
	v_exp_f32_e32 v139, v139
	v_exp_f32_e32 v140, v140
	v_exp_f32_e32 v141, v141
	s_nop 0
	v_add_f32_e32 v138, 1.0, v138
	v_add_f32_e32 v139, 1.0, v139
	v_add_f32_e32 v140, 1.0, v140
	v_add_f32_e32 v141, 1.0, v141
	v_rcp_f32_e32 v138, v138
	v_rcp_f32_e32 v139, v139
	v_rcp_f32_e32 v140, v140
	v_rcp_f32_e32 v141, v141
	s_nop 0
	v_fma_f32 v138, -2.0, v138, 1.0
	v_fma_f32 v139, -2.0, v139, 1.0
	v_fma_f32 v140, -2.0, v140, 1.0
	v_fma_f32 v141, -2.0, v141, 1.0
	v_add_f32_e32 v138, 1.0, v138
	v_add_f32_e32 v139, 1.0, v139
	v_add_f32_e32 v140, 1.0, v140
	v_add_f32_e32 v141, 1.0, v141
	v_mul_f32_e32 v190, 0.5, v190
; __device__ __forceinline__ void lru_tile(const Params& P, int chunk, int head, int pass, char* smem_raw) {
;     ...
;           } else {
;             const float hfv = hfp[i];
;             const float g = gp[i];
;             const float tz = 0.7978845608028654f * (g + 0.044715f * g * g * g);
;             const float th = 1.f - 2.f * __builtin_amdgcn_rcpf(1.f + __expf(2.f * tz));
;             const float ge = 0.5f * g * (1.f + th);
;             P.cat[row * 1024 + gch] = f2bf((hfv + h) * ge);
;           }
;         }
;       }
;       cB = p0.x * cB + p0.y; cA *= p0.x;
;       cB = p1.x * cB + p1.y; cA *= p1.x;
;       cB = p2.x * cB + p2.y; cA *= p2.x;
;       cB = p3.x * cB + p3.y; cA *= p3.x;
;       __syncthreads();
;     }
;     if (pass == 1 && q == 0) P.summ[((long)d * 264 + chunk) * 512 + gch] = make_float2(cA, cB);
	v_mul_f32_e32 v191, 0.5, v191
	v_mul_f32_e32 v192, 0.5, v192
	v_mul_f32_e32 v193, 0.5, v193
	v_mul_f32_e32 v190, v190, v138
	v_mul_f32_e32 v191, v191, v139
	v_mul_f32_e32 v192, v192, v140
	v_mul_f32_e32 v193, v193, v141
	v_add_f32_e32 v118, v233, v118
	v_add_f32_e32 v119, v234, v119
	v_add_f32_e32 v120, v235, v120
	v_add_f32_e32 v121, v236, v121
	v_mul_f32_e32 v118, v118, v190
	v_mul_f32_e32 v119, v119, v191
	v_mul_f32_e32 v120, v120, v192
	v_mul_f32_e32 v121, v121, v193
	v_cvt_pk_bf16_f32 v118, v118, v118
	v_cvt_pk_bf16_f32 v119, v119, v119
	v_cvt_pk_bf16_f32 v120, v120, v120
	v_cvt_pk_bf16_f32 v121, v121, v121
	s_lshl_b32 s0, s71, 18
	s_lshl_b32 s1, s56, 1
	s_add_u32 s0, s0, s1
	s_add_u32 s4, s12, s0
	s_addc_u32 s5, s13, 0
	global_store_short v237, v90, s[4:5]
	s_add_u32 s4, s4, 0x800
	s_addc_u32 s5, s5, 0
	global_store_short v237, v91, s[4:5]
	s_add_u32 s4, s4, 0x800
	s_addc_u32 s5, s5, 0
	global_store_short v237, v92, s[4:5]
	s_add_u32 s4, s4, 0x800
	s_addc_u32 s5, s5, 0
	global_store_short v237, v93, s[4:5]
	s_add_u32 s4, s4, 0x800
	s_addc_u32 s5, s5, 0
	global_store_short v237, v94, s[4:5]
	s_add_u32 s4, s4, 0x800
	s_addc_u32 s5, s5, 0
	global_store_short v237, v95, s[4:5]
	s_add_u32 s4, s4, 0x800
	s_addc_u32 s5, s5, 0
	global_store_short v237, v96, s[4:5]
	s_add_u32 s4, s4, 0x800
	s_addc_u32 s5, s5, 0
	global_store_short v237, v97, s[4:5]
	s_add_u32 s4, s4, 0x800
	s_addc_u32 s5, s5, 0
	global_store_short v237, v98, s[4:5]
	s_add_u32 s4, s4, 0x800
	s_addc_u32 s5, s5, 0
	global_store_short v237, v99, s[4:5]
	s_add_u32 s4, s4, 0x800
	s_addc_u32 s5, s5, 0
	global_store_short v237, v100, s[4:5]
	s_add_u32 s4, s4, 0x800
	s_addc_u32 s5, s5, 0
	global_store_short v237, v101, s[4:5]
	s_add_u32 s4, s4, 0x800
	s_addc_u32 s5, s5, 0
	global_store_short v237, v102, s[4:5]
	s_add_u32 s4, s4, 0x800
	s_addc_u32 s5, s5, 0
	global_store_short v237, v103, s[4:5]
	s_add_u32 s4, s4, 0x800
	s_addc_u32 s5, s5, 0
	global_store_short v237, v104, s[4:5]
	s_add_u32 s4, s4, 0x800
	s_addc_u32 s5, s5, 0
	global_store_short v237, v105, s[4:5]
	s_add_u32 s4, s4, 0x800
	s_addc_u32 s5, s5, 0
	global_store_short v237, v106, s[4:5]
	s_add_u32 s4, s4, 0x800
	s_addc_u32 s5, s5, 0
	global_store_short v237, v107, s[4:5]
	s_add_u32 s4, s4, 0x800
	s_addc_u32 s5, s5, 0
	global_store_short v237, v108, s[4:5]
	s_add_u32 s4, s4, 0x800
	s_addc_u32 s5, s5, 0
	global_store_short v237, v109, s[4:5]
	s_add_u32 s4, s4, 0x800
	s_addc_u32 s5, s5, 0
	global_store_short v237, v110, s[4:5]
	s_add_u32 s4, s4, 0x800
	s_addc_u32 s5, s5, 0
	global_store_short v237, v111, s[4:5]
	s_add_u32 s4, s4, 0x800
	s_addc_u32 s5, s5, 0
	global_store_short v237, v112, s[4:5]
	s_add_u32 s4, s4, 0x800
	s_addc_u32 s5, s5, 0
	global_store_short v237, v113, s[4:5]
	s_add_u32 s4, s4, 0x800
	s_addc_u32 s5, s5, 0
	global_store_short v237, v114, s[4:5]
	s_add_u32 s4, s4, 0x800
	s_addc_u32 s5, s5, 0
	global_store_short v237, v115, s[4:5]
	s_add_u32 s4, s4, 0x800
	s_addc_u32 s5, s5, 0
	global_store_short v237, v116, s[4:5]
	s_add_u32 s4, s4, 0x800
	s_addc_u32 s5, s5, 0
	global_store_short v237, v117, s[4:5]
	s_add_u32 s4, s4, 0x800
	s_addc_u32 s5, s5, 0
	global_store_short v237, v118, s[4:5]
	s_add_u32 s4, s4, 0x800
	s_addc_u32 s5, s5, 0
	global_store_short v237, v119, s[4:5]
	s_add_u32 s4, s4, 0x800
	s_addc_u32 s5, s5, 0
	global_store_short v237, v120, s[4:5]
	s_add_u32 s4, s4, 0x800
	s_addc_u32 s5, s5, 0
	global_store_short v237, v121, s[4:5]
	s_add_u32 s69, s69, 1
	s_cmp_lt_u32 s69, s70
	s_cbranch_scc1 .Lmy_lrub_tile
	s_waitcnt lgkmcnt(0)
	s_barrier
	s_branch .LBB0_680

; __device__ __forceinline__ void row_phase(const Params& P, int glayer, int layer, int xsrc, bool hasY, int gate_idx, const float* gpost,
;                           int xdst, bool doH, const float* gpre, int sh_idx, int nrows) {
;     ...
;   for (int rb = blockIdx.x * 8 + wid; rb < nrows; rb += 4 * stride) {
;     uint4 xr[4][4];
;     uint2 yy[4][4];
; #pragma unroll
;     for (int u = 0; u < 4; ++u) {
;       const int R = rb + u * stride;
;       if (R < nrows) {
;         if (xsrc != 0 && R < N_X) {
;           const u16* xs_ = ((xsrc == 1) ? resA : P.zf) + (long)R * 1024;
; #pragma unroll
;           for (int i = 0; i < 4; ++i) {
;             const uint2 t2 = *reinterpret_cast<const uint2*>(xs_ + (i * 64 + lane) * 4);
;             xr[u][i].x = t2.x; xr[u][i].y = t2.y;
;           }
;         } else {
;           const float* xin_;
;           if (xsrc == 0) xin_ = R < N_X ? P.x + (long)R * 1024 : P.ctx + (long)(R - N_X) * 1024;
;           else           xin_ = P.xc + (long)(R - N_X) * 1024;
; #pragma unroll
;           for (int i = 0; i < 4; ++i) xr[u][i] = *reinterpret_cast<const uint4*>(xin_ + (i * 64 + lane) * 4);
;         }
;         if (hasY) {
;           const u16* y_ = P.hy + (long)R * 1024;
; #pragma unroll
;           for (int i = 0; i < 4; ++i) yy[u][i] = *reinterpret_cast<const uint2*>(y_ + (i * 64 + lane) * 4);
;         }
;       }
;     }
;     ...
;           const float rstd = __builtin_amdgcn_rsqf(ss * (1.f / 1024.f) + EPSF);
; #pragma unroll
;           for (int i = 0; i < 4; ++i) {
;             const int col = (i * 64 + lane) * 4;
;             const float4 gt = *reinterpret_cast<const float4*>(modg + gate_idx * 1024 + col);
;             const float4 gp = *reinterpret_cast<const float4*>(gpost + col);
;             xv[i].x += gt.x * (yv[i].x * rstd * gp.x); xv[i].y += gt.y * (yv[i].y * rstd * gp.y);
;             xv[i].z += gt.z * (yv[i].z * rstd * gp.z); xv[i].w += gt.w * (yv[i].w * rstd * gp.w);
;           }
;         }
;         if (xdst == 3 || (xdst == 1 && row >= N_X)) {
;           float* xout = (xdst == 3) ? P.out + (long)row * 1024 : P.xc + (long)(row - N_X) * 1024;
; #pragma unroll
;           for (int i = 0; i < 4; ++i) *reinterpret_cast<float4*>(xout + (i * 64 + lane) * 4) = xv[i];
;         } else if (xdst != 0) {
;           u16* xo = ((xdst == 1) ? resA : P.zf) + (long)row * 1024;
; #pragma unroll
.LBB0_921:
	s_cmp_gt_i32 s34, 7
	s_cselect_b64 s[0:1], -1, 0
	s_cmp_lt_i32 s35, 8
	s_cselect_b64 s[4:5], -1, 0
	s_or_b64 s[0:1], s[0:1], s[4:5]
	s_and_b64 vcc, exec, s[0:1]
	s_cbranch_vccnz .LBB0_1007
	v_lshl_add_u32 v64, s2, 3, v204
	s_mov_b32 s3, 0x8400
	v_mov_b32_e32 v0, v153
	v_cmp_gt_i32_e32 vcc, s3, v64
	s_and_saveexec_b64 s[8:9], vcc
	s_cbranch_execz .LBB0_953
	v_readlane_b32 s4, v252, 0
	v_readlane_b32 s5, v252, 1
	v_readfirstlane_b32 s19, v204
	s_nop 3
	s_sub_u32 s4, s4, 0x170
	s_subb_u32 s5, s5, 0
	s_load_dwordx2 s[12:13], s[4:5], 0x0
	s_load_dwordx2 s[14:15], s[4:5], 0x140
	s_load_dwordx2 s[16:17], s[4:5], 0xc8
	s_load_dwordx2 s[20:21], s[4:5], 0x100
	s_lshl_b32 s98, s2, 3
	s_add_u32 s19, s98, s19
	v_and_b32_e32 v136, 63, v152
	v_lshlrev_b32_e32 v137, 3, v136
	v_lshlrev_b32_e32 v136, 4, v136
	s_waitcnt lgkmcnt(0)
	s_lshl_b32 vcc_lo, s19, 12
	s_add_u32 s100, s12, vcc_lo
	s_addc_u32 s101, s13, 0
	global_load_dwordx4 v[0:3], v136, s[100:101] offset:0
	global_load_dwordx4 v[4:7], v136, s[100:101] offset:1024
	global_load_dwordx4 v[8:11], v136, s[100:101] offset:2048
	global_load_dwordx4 v[12:15], v136, s[100:101] offset:3072
	s_lshl_b32 vcc_lo, s19, 11
	s_add_u32 s100, s14, vcc_lo
	s_addc_u32 s101, s15, 0
	global_load_dwordx2 v[48:49], v137, s[100:101] offset:0
	global_load_dwordx2 v[50:51], v137, s[100:101] offset:512
	global_load_dwordx2 v[52:53], v137, s[100:101] offset:1024
	global_load_dwordx2 v[54:55], v137, s[100:101] offset:1536
	s_lshl_b32 vcc_lo, s19, 12
	s_add_u32 vcc_lo, vcc_lo, 0x800000
	s_add_u32 s100, s12, vcc_lo
	s_addc_u32 s101, s13, 0
	global_load_dwordx4 v[16:19], v136, s[100:101] offset:0
	global_load_dwordx4 v[20:23], v136, s[100:101] offset:1024
	global_load_dwordx4 v[24:27], v136, s[100:101] offset:2048
	global_load_dwordx4 v[28:31], v136, s[100:101] offset:3072
	s_lshl_b32 vcc_lo, s19, 11
	s_add_u32 vcc_lo, vcc_lo, 0x400000
	s_add_u32 s100, s14, vcc_lo
	s_addc_u32 s101, s15, 0
	global_load_dwordx2 v[56:57], v137, s[100:101] offset:0
	global_load_dwordx2 v[58:59], v137, s[100:101] offset:512
	global_load_dwordx2 v[60:61], v137, s[100:101] offset:1024
	global_load_dwordx2 v[62:63], v137, s[100:101] offset:1536
	s_add_u32 s100, s20, 0x2000
	s_addc_u32 s101, s21, 0
	global_load_dwordx4 v[72:75], v136, s[100:101] offset:0
	global_load_dwordx4 v[76:79], v136, s[100:101] offset:1024
	global_load_dwordx4 v[80:83], v136, s[100:101] offset:2048
	global_load_dwordx4 v[84:87], v136, s[100:101] offset:3072
	s_load_dwordx2 s[98:99], s[4:5], 0x38
	s_waitcnt lgkmcnt(0)
	global_load_dwordx4 v[120:123], v136, s[98:99] offset:0
	global_load_dwordx4 v[124:127], v136, s[98:99] offset:1024
	global_load_dwordx4 v[128:131], v136, s[98:99] offset:2048
	global_load_dwordx4 v[132:135], v136, s[98:99] offset:3072
	s_add_u32 s100, s20, 0x3000
	s_addc_u32 s101, s21, 0
	global_load_dwordx4 v[104:107], v136, s[100:101] offset:0
	global_load_dwordx4 v[108:111], v136, s[100:101] offset:1024
	global_load_dwordx4 v[112:115], v136, s[100:101] offset:2048
	global_load_dwordx4 v[116:119], v136, s[100:101] offset:3072
	s_add_u32 s100, s100, 0x1000
	s_addc_u32 s101, s101, 0
	global_load_dwordx4 v[32:35], v136, s[100:101] offset:0
	global_load_dwordx4 v[36:39], v136, s[100:101] offset:1024
	global_load_dwordx4 v[40:43], v136, s[100:101] offset:2048
	global_load_dwordx4 v[44:47], v136, s[100:101] offset:3072
	s_load_dwordx2 s[98:99], s[4:5], 0x40
	s_waitcnt lgkmcnt(0)
	global_load_dwordx4 v[88:91], v136, s[98:99] offset:0
	global_load_dwordx4 v[92:95], v136, s[98:99] offset:1024
	global_load_dwordx4 v[96:99], v136, s[98:99] offset:2048
	global_load_dwordx4 v[100:103], v136, s[98:99] offset:3072
	s_waitcnt vmcnt(0)
	v_mul_f32_e32 v72, v72, v120
	v_mul_f32_e32 v73, v73, v121
	v_mul_f32_e32 v74, v74, v122
	v_mul_f32_e32 v75, v75, v123
	v_mul_f32_e32 v76, v76, v124
	v_mul_f32_e32 v77, v77, v125
	v_mul_f32_e32 v78, v78, v126
	v_mul_f32_e32 v79, v79, v127
	v_mul_f32_e32 v80, v80, v128
	v_mul_f32_e32 v81, v81, v129
	v_mul_f32_e32 v82, v82, v130
	v_mul_f32_e32 v83, v83, v131
	v_mul_f32_e32 v84, v84, v132
	v_mul_f32_e32 v85, v85, v133
	v_mul_f32_e32 v86, v86, v134
	v_mul_f32_e32 v87, v87, v135
	v_fma_f32 v88, v88, v32, v88
	v_fma_f32 v89, v89, v33, v89
	v_fma_f32 v90, v90, v34, v90
	v_fma_f32 v91, v91, v35, v91
	v_fma_f32 v92, v92, v36, v92
	v_fma_f32 v93, v93, v37, v93
	v_fma_f32 v94, v94, v38, v94
	v_fma_f32 v95, v95, v39, v95
	v_fma_f32 v96, v96, v40, v96
	v_fma_f32 v97, v97, v41, v97
	v_fma_f32 v98, v98, v42, v98
	v_fma_f32 v99, v99, v43, v99
	v_fma_f32 v100, v100, v44, v100
	v_fma_f32 v101, v101, v45, v101
	v_fma_f32 v102, v102, v46, v102
	v_fma_f32 v103, v103, v47, v103
	s_lshl_b32 vcc_lo, s19, 12
	s_add_u32 vcc_lo, vcc_lo, 0x1000000
	s_add_u32 s100, s12, vcc_lo
	s_addc_u32 s101, s13, 0
	global_load_dwordx4 v[32:35], v136, s[100:101] offset:0
	global_load_dwordx4 v[36:39], v136, s[100:101] offset:1024
	global_load_dwordx4 v[40:43], v136, s[100:101] offset:2048
	global_load_dwordx4 v[44:47], v136, s[100:101] offset:3072
	s_lshl_b32 vcc_lo, s19, 11
	s_add_u32 vcc_lo, vcc_lo, 0x800000
	s_add_u32 s100, s14, vcc_lo
	s_addc_u32 s101, s15, 0
	global_load_dwordx2 v[64:65], v137, s[100:101] offset:0
	global_load_dwordx2 v[66:67], v137, s[100:101] offset:512
	global_load_dwordx2 v[68:69], v137, s[100:101] offset:1024
	global_load_dwordx2 v[70:71], v137, s[100:101] offset:1536
	v_lshlrev_b32_e32 v120, 16, v48
	v_and_b32_e32 v121, 0xffff0000, v48
	v_lshlrev_b32_e32 v122, 16, v49
	v_and_b32_e32 v123, 0xffff0000, v49
	v_lshlrev_b32_e32 v124, 16, v50
	v_and_b32_e32 v125, 0xffff0000, v50
	v_lshlrev_b32_e32 v126, 16, v51
	v_and_b32_e32 v127, 0xffff0000, v51
; __device__ __forceinline__ void row_phase(const Params& P, int glayer, int layer, int xsrc, bool hasY, int gate_idx, const float* gpost,
;                           int xdst, bool doH, const float* gpre, int sh_idx, int nrows) {
;     ...
;         if (hasY) {
;           float4 yv[4];
;           float ss = 0.f;
; #pragma unroll
;           for (int i = 0; i < 4; ++i) {
;             const uint2 raw = yy[u][i];
;             yv[i].x = bf2f((u16)(raw.x & 0xffff)); yv[i].y = bf2f((u16)(raw.x >> 16));
;             yv[i].z = bf2f((u16)(raw.y & 0xffff)); yv[i].w = bf2f((u16)(raw.y >> 16));
;             ss += yv[i].x * yv[i].x + yv[i].y * yv[i].y + yv[i].z * yv[i].z + yv[i].w * yv[i].w;
;           }
;           ss = wave_sum(ss);
;           const float rstd = __builtin_amdgcn_rsqf(ss * (1.f / 1024.f) + EPSF);
; #pragma unroll
;           for (int i = 0; i < 4; ++i) {
;             const int col = (i * 64 + lane) * 4;
;             const float4 gt = *reinterpret_cast<const float4*>(modg + gate_idx * 1024 + col);
;             const float4 gp = *reinterpret_cast<const float4*>(gpost + col);
;             xv[i].x += gt.x * (yv[i].x * rstd * gp.x); xv[i].y += gt.y * (yv[i].y * rstd * gp.y);
;             xv[i].z += gt.z * (yv[i].z * rstd * gp.z); xv[i].w += gt.w * (yv[i].w * rstd * gp.w);
;           }
;         }
;         if (xdst == 3 || (xdst == 1 && row >= N_X)) {
;           float* xout = (xdst == 3) ? P.out + (long)row * 1024 : P.xc + (long)(row - N_X) * 1024;
; #pragma unroll
;           for (int i = 0; i < 4; ++i) *reinterpret_cast<float4*>(xout + (i * 64 + lane) * 4) = xv[i];
;         } else if (xdst != 0) {
;           u16* xo = ((xdst == 1) ? resA : P.zf) + (long)row * 1024;
; #pragma unroll
;           for (int i = 0; i < 4; ++i) {
;             const unsigned b0 = f2bf(xv[i].x), b1 = f2bf(xv[i].y), b2 = f2bf(xv[i].z), b3 = f2bf(xv[i].w);
;             *reinterpret_cast<uint2*>(xo + (i * 64 + lane) * 4) = make_uint2(b0 | (b1 << 16), b2 | (b3 << 16));
;           }
;         }
;         if (doH) {
;           float ss = 0.f;
; #pragma unroll
;           for (int i = 0; i < 4; ++i) ss += xv[i].x * xv[i].x + xv[i].y * xv[i].y + xv[i].z * xv[i].z + xv[i].w * xv[i].w;
;           ss = wave_sum(ss);
;           const float rstd = __builtin_amdgcn_rsqf(ss * (1.f / 1024.f) + EPSF);
;           u16* h = P.hy + (long)row * 1024;
; #pragma unroll
	v_lshlrev_b32_e32 v128, 16, v52
	v_and_b32_e32 v129, 0xffff0000, v52
	v_lshlrev_b32_e32 v130, 16, v53
	v_and_b32_e32 v131, 0xffff0000, v53
	v_lshlrev_b32_e32 v132, 16, v54
	v_and_b32_e32 v133, 0xffff0000, v54
	v_lshlrev_b32_e32 v134, 16, v55
	v_and_b32_e32 v135, 0xffff0000, v55
	v_mul_f32_e32 v138, v120, v120
	v_mul_f32_e32 v149, v121, v121
	v_mul_f32_e32 v150, v122, v122
	v_mul_f32_e32 v154, v123, v123
	v_fma_f32 v138, v124, v124, v138
	v_fma_f32 v149, v125, v125, v149
	v_fma_f32 v150, v126, v126, v150
	v_fma_f32 v154, v127, v127, v154
	v_fma_f32 v138, v128, v128, v138
	v_fma_f32 v149, v129, v129, v149
	v_fma_f32 v150, v130, v130, v150
	v_fma_f32 v154, v131, v131, v154
	v_fma_f32 v138, v132, v132, v138
	v_fma_f32 v149, v133, v133, v149
	v_fma_f32 v150, v134, v134, v150
	v_fma_f32 v154, v135, v135, v154
	v_add_f32_e32 v138, v138, v149
	v_add_f32_e32 v150, v150, v154
	v_add_f32_e32 v138, v138, v150
	s_nop 1
	v_add_f32_dpp v138, v138, v138 quad_perm:[1,0,3,2] row_mask:0xf bank_mask:0xf
	s_nop 1
	v_add_f32_dpp v138, v138, v138 quad_perm:[2,3,0,1] row_mask:0xf bank_mask:0xf
	s_nop 1
	v_add_f32_dpp v138, v138, v138 row_half_mirror row_mask:0xf bank_mask:0xf
	s_nop 1
	v_add_f32_dpp v138, v138, v138 row_mirror row_mask:0xf bank_mask:0xf
	v_mov_b32_e32 v139, v138
	s_nop 1
	v_permlane16_swap_b32_e32 v138, v139
	v_add_f32_e32 v138, v138, v139
	v_mov_b32_e32 v139, v138
	s_nop 1
	v_permlane32_swap_b32_e32 v138, v139
	v_add_f32_e32 v138, v138, v139
	v_mul_f32_e32 v138, 0x3a800000, v138
	v_add_f32_e32 v138, 0x358637bd, v138
	v_rsq_f32_e32 v140, v138
	s_nop 0
	v_mul_f32_e32 v120, v120, v140
	v_mul_f32_e32 v121, v121, v140
	v_mul_f32_e32 v122, v122, v140
	v_mul_f32_e32 v123, v123, v140
	v_mul_f32_e32 v124, v124, v140
	v_mul_f32_e32 v125, v125, v140
	v_mul_f32_e32 v126, v126, v140
	v_mul_f32_e32 v127, v127, v140
	v_mul_f32_e32 v128, v128, v140
	v_mul_f32_e32 v129, v129, v140
	v_mul_f32_e32 v130, v130, v140
	v_mul_f32_e32 v131, v131, v140
	v_mul_f32_e32 v132, v132, v140
	v_mul_f32_e32 v133, v133, v140
	v_mul_f32_e32 v134, v134, v140
	v_mul_f32_e32 v135, v135, v140
	v_fma_f32 v0, v120, v72, v0
	v_fma_f32 v1, v121, v73, v1
	v_fma_f32 v2, v122, v74, v2
	v_fma_f32 v3, v123, v75, v3
	v_fma_f32 v4, v124, v76, v4
	v_fma_f32 v5, v125, v77, v5
	v_fma_f32 v6, v126, v78, v6
	v_fma_f32 v7, v127, v79, v7
	v_fma_f32 v8, v128, v80, v8
	v_fma_f32 v9, v129, v81, v9
	v_fma_f32 v10, v130, v82, v10
	v_fma_f32 v11, v131, v83, v11
	v_fma_f32 v12, v132, v84, v12
	v_fma_f32 v13, v133, v85, v13
	v_fma_f32 v14, v134, v86, v14
	v_fma_f32 v15, v135, v87, v15
	v_cvt_pk_bf16_f32 v156, v0, v1
	v_cvt_pk_bf16_f32 v157, v2, v3
	v_cvt_pk_bf16_f32 v158, v4, v5
	v_cvt_pk_bf16_f32 v159, v6, v7
	v_cvt_pk_bf16_f32 v160, v8, v9
	v_cvt_pk_bf16_f32 v161, v10, v11
	v_cvt_pk_bf16_f32 v162, v12, v13
	v_cvt_pk_bf16_f32 v163, v14, v15
	s_lshl_b32 vcc_lo, s19, 11
	s_add_u32 s100, s16, vcc_lo
	s_addc_u32 s101, s17, 0
	global_store_dwordx2 v137, v[156:157], s[100:101] offset:0
	global_store_dwordx2 v137, v[158:159], s[100:101] offset:512
	global_store_dwordx2 v137, v[160:161], s[100:101] offset:1024
	global_store_dwordx2 v137, v[162:163], s[100:101] offset:1536
	v_mul_f32_e32 v138, v0, v0
	v_mul_f32_e32 v149, v1, v1
	v_mul_f32_e32 v150, v2, v2
	v_mul_f32_e32 v154, v3, v3
	v_fma_f32 v138, v4, v4, v138
	v_fma_f32 v149, v5, v5, v149
	v_fma_f32 v150, v6, v6, v150
	v_fma_f32 v154, v7, v7, v154
	v_fma_f32 v138, v8, v8, v138
	v_fma_f32 v149, v9, v9, v149
	v_fma_f32 v150, v10, v10, v150
	v_fma_f32 v154, v11, v11, v154
	v_fma_f32 v138, v12, v12, v138
	v_fma_f32 v149, v13, v13, v149
	v_fma_f32 v150, v14, v14, v150
	v_fma_f32 v154, v15, v15, v154
	v_add_f32_e32 v138, v138, v149
	v_add_f32_e32 v150, v150, v154
	v_add_f32_e32 v138, v138, v150
	s_nop 1
	v_add_f32_dpp v138, v138, v138 quad_perm:[1,0,3,2] row_mask:0xf bank_mask:0xf
	s_nop 1
	v_add_f32_dpp v138, v138, v138 quad_perm:[2,3,0,1] row_mask:0xf bank_mask:0xf
	s_nop 1
	v_add_f32_dpp v138, v138, v138 row_half_mirror row_mask:0xf bank_mask:0xf
	s_nop 1
	v_add_f32_dpp v138, v138, v138 row_mirror row_mask:0xf bank_mask:0xf
	v_mov_b32_e32 v139, v138
	s_nop 1
	v_permlane16_swap_b32_e32 v138, v139
	v_add_f32_e32 v138, v138, v139
	v_mov_b32_e32 v139, v138
	s_nop 1
	v_permlane32_swap_b32_e32 v138, v139
	v_add_f32_e32 v138, v138, v139
	v_mul_f32_e32 v138, 0x3a800000, v138
	v_add_f32_e32 v138, 0x358637bd, v138
	v_rsq_f32_e32 v140, v138
	s_nop 0
	v_mul_f32_e32 v120, v0, v140
	v_mul_f32_e32 v121, v1, v140
	v_mul_f32_e32 v122, v2, v140
	v_mul_f32_e32 v123, v3, v140
	v_mul_f32_e32 v124, v4, v140
	v_mul_f32_e32 v125, v5, v140
	v_mul_f32_e32 v126, v6, v140
	v_mul_f32_e32 v127, v7, v140
	v_mul_f32_e32 v128, v8, v140
	v_mul_f32_e32 v129, v9, v140
	v_mul_f32_e32 v130, v10, v140
	v_mul_f32_e32 v131, v11, v140
	v_mul_f32_e32 v132, v12, v140
	v_mul_f32_e32 v133, v13, v140
	v_mul_f32_e32 v134, v14, v140
	v_mul_f32_e32 v135, v15, v140
	v_fma_f32 v120, v120, v88, v104
	v_fma_f32 v121, v121, v89, v105
	v_fma_f32 v122, v122, v90, v106
	v_fma_f32 v123, v123, v91, v107
	v_fma_f32 v124, v124, v92, v108
	v_fma_f32 v125, v125, v93, v109
	v_fma_f32 v126, v126, v94, v110
	v_fma_f32 v127, v127, v95, v111
	v_fma_f32 v128, v128, v96, v112
	v_fma_f32 v129, v129, v97, v113
	v_fma_f32 v130, v130, v98, v114
	v_fma_f32 v131, v131, v99, v115
	v_fma_f32 v132, v132, v100, v116
	v_fma_f32 v133, v133, v101, v117
	v_fma_f32 v134, v134, v102, v118
	v_fma_f32 v135, v135, v103, v119
	v_cvt_pk_bf16_f32 v156, v120, v121
	v_cvt_pk_bf16_f32 v157, v122, v123
	v_cvt_pk_bf16_f32 v158, v124, v125
	v_cvt_pk_bf16_f32 v159, v126, v127
	v_cvt_pk_bf16_f32 v160, v128, v129
	v_cvt_pk_bf16_f32 v161, v130, v131
; __device__ __forceinline__ void row_phase(const Params& P, int glayer, int layer, int xsrc, bool hasY, int gate_idx, const float* gpost,
;                           int xdst, bool doH, const float* gpre, int sh_idx, int nrows) {
;     ...
;         if (hasY) {
;           float4 yv[4];
;           float ss = 0.f;
; #pragma unroll
;           for (int i = 0; i < 4; ++i) {
;             const uint2 raw = yy[u][i];
;             yv[i].x = bf2f((u16)(raw.x & 0xffff)); yv[i].y = bf2f((u16)(raw.x >> 16));
;             yv[i].z = bf2f((u16)(raw.y & 0xffff)); yv[i].w = bf2f((u16)(raw.y >> 16));
;             ss += yv[i].x * yv[i].x + yv[i].y * yv[i].y + yv[i].z * yv[i].z + yv[i].w * yv[i].w;
;           }
;           ss = wave_sum(ss);
;           const float rstd = __builtin_amdgcn_rsqf(ss * (1.f / 1024.f) + EPSF);
; #pragma unroll
;           for (int i = 0; i < 4; ++i) {
;             const int col = (i * 64 + lane) * 4;
;             const float4 gt = *reinterpret_cast<const float4*>(modg + gate_idx * 1024 + col);
;             const float4 gp = *reinterpret_cast<const float4*>(gpost + col);
;             xv[i].x += gt.x * (yv[i].x * rstd * gp.x); xv[i].y += gt.y * (yv[i].y * rstd * gp.y);
;             xv[i].z += gt.z * (yv[i].z * rstd * gp.z); xv[i].w += gt.w * (yv[i].w * rstd * gp.w);
;           }
;         }
;         if (xdst == 3 || (xdst == 1 && row >= N_X)) {
;           float* xout = (xdst == 3) ? P.out + (long)row * 1024 : P.xc + (long)(row - N_X) * 1024;
; #pragma unroll
;           for (int i = 0; i < 4; ++i) *reinterpret_cast<float4*>(xout + (i * 64 + lane) * 4) = xv[i];
;         } else if (xdst != 0) {
;           u16* xo = ((xdst == 1) ? resA : P.zf) + (long)row * 1024;
; #pragma unroll
;           for (int i = 0; i < 4; ++i) {
;             const unsigned b0 = f2bf(xv[i].x), b1 = f2bf(xv[i].y), b2 = f2bf(xv[i].z), b3 = f2bf(xv[i].w);
;             *reinterpret_cast<uint2*>(xo + (i * 64 + lane) * 4) = make_uint2(b0 | (b1 << 16), b2 | (b3 << 16));
;           }
;         }
;         if (doH) {
;           float ss = 0.f;
; #pragma unroll
;           for (int i = 0; i < 4; ++i) ss += xv[i].x * xv[i].x + xv[i].y * xv[i].y + xv[i].z * xv[i].z + xv[i].w * xv[i].w;
;           ss = wave_sum(ss);
;           const float rstd = __builtin_amdgcn_rsqf(ss * (1.f / 1024.f) + EPSF);
;           u16* h = P.hy + (long)row * 1024;
; #pragma unroll
	v_cvt_pk_bf16_f32 v162, v132, v133
	v_cvt_pk_bf16_f32 v163, v134, v135
	s_lshl_b32 vcc_lo, s19, 11
	s_add_u32 s100, s14, vcc_lo
	s_addc_u32 s101, s15, 0
	global_store_dwordx2 v137, v[156:157], s[100:101] offset:0
	global_store_dwordx2 v137, v[158:159], s[100:101] offset:512
	global_store_dwordx2 v137, v[160:161], s[100:101] offset:1024
	global_store_dwordx2 v137, v[162:163], s[100:101] offset:1536
	s_lshl_b32 vcc_lo, s19, 12
	s_add_u32 vcc_lo, vcc_lo, 0x1800000
	s_add_u32 s100, s12, vcc_lo
	s_addc_u32 s101, s13, 0
	global_load_dwordx4 v[0:3], v136, s[100:101] offset:0
	global_load_dwordx4 v[4:7], v136, s[100:101] offset:1024
	global_load_dwordx4 v[8:11], v136, s[100:101] offset:2048
	global_load_dwordx4 v[12:15], v136, s[100:101] offset:3072
	s_lshl_b32 vcc_lo, s19, 11
	s_add_u32 vcc_lo, vcc_lo, 0xc00000
	s_add_u32 s100, s14, vcc_lo
	s_addc_u32 s101, s15, 0
	global_load_dwordx2 v[48:49], v137, s[100:101] offset:0
	global_load_dwordx2 v[50:51], v137, s[100:101] offset:512
	global_load_dwordx2 v[52:53], v137, s[100:101] offset:1024
	global_load_dwordx2 v[54:55], v137, s[100:101] offset:1536
	v_lshlrev_b32_e32 v120, 16, v56
	v_and_b32_e32 v121, 0xffff0000, v56
	v_lshlrev_b32_e32 v122, 16, v57
	v_and_b32_e32 v123, 0xffff0000, v57
	v_lshlrev_b32_e32 v124, 16, v58
	v_and_b32_e32 v125, 0xffff0000, v58
	v_lshlrev_b32_e32 v126, 16, v59
	v_and_b32_e32 v127, 0xffff0000, v59
	v_lshlrev_b32_e32 v128, 16, v60
	v_and_b32_e32 v129, 0xffff0000, v60
	v_lshlrev_b32_e32 v130, 16, v61
	v_and_b32_e32 v131, 0xffff0000, v61
	v_lshlrev_b32_e32 v132, 16, v62
	v_and_b32_e32 v133, 0xffff0000, v62
	v_lshlrev_b32_e32 v134, 16, v63
	v_and_b32_e32 v135, 0xffff0000, v63
	v_mul_f32_e32 v138, v120, v120
	v_mul_f32_e32 v149, v121, v121
	v_mul_f32_e32 v150, v122, v122
	v_mul_f32_e32 v154, v123, v123
	v_fma_f32 v138, v124, v124, v138
	v_fma_f32 v149, v125, v125, v149
	v_fma_f32 v150, v126, v126, v150
	v_fma_f32 v154, v127, v127, v154
	v_fma_f32 v138, v128, v128, v138
	v_fma_f32 v149, v129, v129, v149
	v_fma_f32 v150, v130, v130, v150
	v_fma_f32 v154, v131, v131, v154
	v_fma_f32 v138, v132, v132, v138
	v_fma_f32 v149, v133, v133, v149
	v_fma_f32 v150, v134, v134, v150
	v_fma_f32 v154, v135, v135, v154
	v_add_f32_e32 v138, v138, v149
	v_add_f32_e32 v150, v150, v154
	v_add_f32_e32 v138, v138, v150
	s_nop 1
	v_add_f32_dpp v138, v138, v138 quad_perm:[1,0,3,2] row_mask:0xf bank_mask:0xf
	s_nop 1
	v_add_f32_dpp v138, v138, v138 quad_perm:[2,3,0,1] row_mask:0xf bank_mask:0xf
	s_nop 1
	v_add_f32_dpp v138, v138, v138 row_half_mirror row_mask:0xf bank_mask:0xf
	s_nop 1
	v_add_f32_dpp v138, v138, v138 row_mirror row_mask:0xf bank_mask:0xf
	v_mov_b32_e32 v139, v138
	s_nop 1
	v_permlane16_swap_b32_e32 v138, v139
	v_add_f32_e32 v138, v138, v139
	v_mov_b32_e32 v139, v138
	s_nop 1
	v_permlane32_swap_b32_e32 v138, v139
	v_add_f32_e32 v138, v138, v139
	v_mul_f32_e32 v138, 0x3a800000, v138
	v_add_f32_e32 v138, 0x358637bd, v138
	v_rsq_f32_e32 v140, v138
	s_nop 0
	v_mul_f32_e32 v120, v120, v140
	v_mul_f32_e32 v121, v121, v140
	v_mul_f32_e32 v122, v122, v140
	v_mul_f32_e32 v123, v123, v140
	v_mul_f32_e32 v124, v124, v140
	v_mul_f32_e32 v125, v125, v140
	v_mul_f32_e32 v126, v126, v140
	v_mul_f32_e32 v127, v127, v140
	v_mul_f32_e32 v128, v128, v140
	v_mul_f32_e32 v129, v129, v140
	v_mul_f32_e32 v130, v130, v140
	v_mul_f32_e32 v131, v131, v140
	v_mul_f32_e32 v132, v132, v140
	v_mul_f32_e32 v133, v133, v140
	v_mul_f32_e32 v134, v134, v140
	v_mul_f32_e32 v135, v135, v140
	v_fma_f32 v16, v120, v72, v16
	v_fma_f32 v17, v121, v73, v17
	v_fma_f32 v18, v122, v74, v18
	v_fma_f32 v19, v123, v75, v19
	v_fma_f32 v20, v124, v76, v20
	v_fma_f32 v21, v125, v77, v21
	v_fma_f32 v22, v126, v78, v22
	v_fma_f32 v23, v127, v79, v23
	v_fma_f32 v24, v128, v80, v24
	v_fma_f32 v25, v129, v81, v25
	v_fma_f32 v26, v130, v82, v26
	v_fma_f32 v27, v131, v83, v27
	v_fma_f32 v28, v132, v84, v28
	v_fma_f32 v29, v133, v85, v29
	v_fma_f32 v30, v134, v86, v30
	v_fma_f32 v31, v135, v87, v31
	v_cvt_pk_bf16_f32 v156, v16, v17
	v_cvt_pk_bf16_f32 v157, v18, v19
	v_cvt_pk_bf16_f32 v158, v20, v21
	v_cvt_pk_bf16_f32 v159, v22, v23
	v_cvt_pk_bf16_f32 v160, v24, v25
	v_cvt_pk_bf16_f32 v161, v26, v27
	v_cvt_pk_bf16_f32 v162, v28, v29
	v_cvt_pk_bf16_f32 v163, v30, v31
	s_lshl_b32 vcc_lo, s19, 11
	s_add_u32 vcc_lo, vcc_lo, 0x400000
	s_add_u32 s100, s16, vcc_lo
	s_addc_u32 s101, s17, 0
	global_store_dwordx2 v137, v[156:157], s[100:101] offset:0
	global_store_dwordx2 v137, v[158:159], s[100:101] offset:512
	global_store_dwordx2 v137, v[160:161], s[100:101] offset:1024
	global_store_dwordx2 v137, v[162:163], s[100:101] offset:1536
	v_mul_f32_e32 v138, v16, v16
	v_mul_f32_e32 v149, v17, v17
	v_mul_f32_e32 v150, v18, v18
	v_mul_f32_e32 v154, v19, v19
	v_fma_f32 v138, v20, v20, v138
	v_fma_f32 v149, v21, v21, v149
	v_fma_f32 v150, v22, v22, v150
	v_fma_f32 v154, v23, v23, v154
	v_fma_f32 v138, v24, v24, v138
	v_fma_f32 v149, v25, v25, v149
	v_fma_f32 v150, v26, v26, v150
	v_fma_f32 v154, v27, v27, v154
	v_fma_f32 v138, v28, v28, v138
	v_fma_f32 v149, v29, v29, v149
	v_fma_f32 v150, v30, v30, v150
	v_fma_f32 v154, v31, v31, v154
	v_add_f32_e32 v138, v138, v149
	v_add_f32_e32 v150, v150, v154
	v_add_f32_e32 v138, v138, v150
	s_nop 1
	v_add_f32_dpp v138, v138, v138 quad_perm:[1,0,3,2] row_mask:0xf bank_mask:0xf
	s_nop 1
	v_add_f32_dpp v138, v138, v138 quad_perm:[2,3,0,1] row_mask:0xf bank_mask:0xf
	s_nop 1
	v_add_f32_dpp v138, v138, v138 row_half_mirror row_mask:0xf bank_mask:0xf
	s_nop 1
	v_add_f32_dpp v138, v138, v138 row_mirror row_mask:0xf bank_mask:0xf
	v_mov_b32_e32 v139, v138
	s_nop 1
	v_permlane16_swap_b32_e32 v138, v139
	v_add_f32_e32 v138, v138, v139
; __device__ __forceinline__ void row_phase(const Params& P, int glayer, int layer, int xsrc, bool hasY, int gate_idx, const float* gpost,
;                           int xdst, bool doH, const float* gpre, int sh_idx, int nrows) {
;     ...
;         if (hasY) {
;           float4 yv[4];
;           float ss = 0.f;
; #pragma unroll
;           for (int i = 0; i < 4; ++i) {
;             const uint2 raw = yy[u][i];
;             yv[i].x = bf2f((u16)(raw.x & 0xffff)); yv[i].y = bf2f((u16)(raw.x >> 16));
;             yv[i].z = bf2f((u16)(raw.y & 0xffff)); yv[i].w = bf2f((u16)(raw.y >> 16));
;             ss += yv[i].x * yv[i].x + yv[i].y * yv[i].y + yv[i].z * yv[i].z + yv[i].w * yv[i].w;
;           }
;           ss = wave_sum(ss);
;           const float rstd = __builtin_amdgcn_rsqf(ss * (1.f / 1024.f) + EPSF);
; #pragma unroll
;           for (int i = 0; i < 4; ++i) {
;             const int col = (i * 64 + lane) * 4;
;             const float4 gt = *reinterpret_cast<const float4*>(modg + gate_idx * 1024 + col);
;             const float4 gp = *reinterpret_cast<const float4*>(gpost + col);
;             xv[i].x += gt.x * (yv[i].x * rstd * gp.x); xv[i].y += gt.y * (yv[i].y * rstd * gp.y);
;             xv[i].z += gt.z * (yv[i].z * rstd * gp.z); xv[i].w += gt.w * (yv[i].w * rstd * gp.w);
;           }
;         }
;         if (xdst == 3 || (xdst == 1 && row >= N_X)) {
;           float* xout = (xdst == 3) ? P.out + (long)row * 1024 : P.xc + (long)(row - N_X) * 1024;
; #pragma unroll
;           for (int i = 0; i < 4; ++i) *reinterpret_cast<float4*>(xout + (i * 64 + lane) * 4) = xv[i];
;         } else if (xdst != 0) {
;           u16* xo = ((xdst == 1) ? resA : P.zf) + (long)row * 1024;
; #pragma unroll
;           for (int i = 0; i < 4; ++i) {
;             const unsigned b0 = f2bf(xv[i].x), b1 = f2bf(xv[i].y), b2 = f2bf(xv[i].z), b3 = f2bf(xv[i].w);
;             *reinterpret_cast<uint2*>(xo + (i * 64 + lane) * 4) = make_uint2(b0 | (b1 << 16), b2 | (b3 << 16));
;           }
;         }
;         if (doH) {
;           float ss = 0.f;
; #pragma unroll
;           for (int i = 0; i < 4; ++i) ss += xv[i].x * xv[i].x + xv[i].y * xv[i].y + xv[i].z * xv[i].z + xv[i].w * xv[i].w;
;           ss = wave_sum(ss);
;           const float rstd = __builtin_amdgcn_rsqf(ss * (1.f / 1024.f) + EPSF);
;           u16* h = P.hy + (long)row * 1024;
; #pragma unroll
	v_mov_b32_e32 v139, v138
	s_nop 1
	v_permlane32_swap_b32_e32 v138, v139
	v_add_f32_e32 v138, v138, v139
	v_mul_f32_e32 v138, 0x3a800000, v138
	v_add_f32_e32 v138, 0x358637bd, v138
	v_rsq_f32_e32 v140, v138
	s_nop 0
	v_mul_f32_e32 v120, v16, v140
	v_mul_f32_e32 v121, v17, v140
	v_mul_f32_e32 v122, v18, v140
	v_mul_f32_e32 v123, v19, v140
	v_mul_f32_e32 v124, v20, v140
	v_mul_f32_e32 v125, v21, v140
	v_mul_f32_e32 v126, v22, v140
	v_mul_f32_e32 v127, v23, v140
	v_mul_f32_e32 v128, v24, v140
	v_mul_f32_e32 v129, v25, v140
	v_mul_f32_e32 v130, v26, v140
	v_mul_f32_e32 v131, v27, v140
	v_mul_f32_e32 v132, v28, v140
	v_mul_f32_e32 v133, v29, v140
	v_mul_f32_e32 v134, v30, v140
	v_mul_f32_e32 v135, v31, v140
	v_fma_f32 v120, v120, v88, v104
	v_fma_f32 v121, v121, v89, v105
	v_fma_f32 v122, v122, v90, v106
	v_fma_f32 v123, v123, v91, v107
	v_fma_f32 v124, v124, v92, v108
	v_fma_f32 v125, v125, v93, v109
	v_fma_f32 v126, v126, v94, v110
	v_fma_f32 v127, v127, v95, v111
	v_fma_f32 v128, v128, v96, v112
	v_fma_f32 v129, v129, v97, v113
	v_fma_f32 v130, v130, v98, v114
	v_fma_f32 v131, v131, v99, v115
	v_fma_f32 v132, v132, v100, v116
	v_fma_f32 v133, v133, v101, v117
	v_fma_f32 v134, v134, v102, v118
	v_fma_f32 v135, v135, v103, v119
	v_cvt_pk_bf16_f32 v156, v120, v121
	v_cvt_pk_bf16_f32 v157, v122, v123
	v_cvt_pk_bf16_f32 v158, v124, v125
	v_cvt_pk_bf16_f32 v159, v126, v127
	v_cvt_pk_bf16_f32 v160, v128, v129
	v_cvt_pk_bf16_f32 v161, v130, v131
	v_cvt_pk_bf16_f32 v162, v132, v133
	v_cvt_pk_bf16_f32 v163, v134, v135
	s_lshl_b32 vcc_lo, s19, 11
	s_add_u32 vcc_lo, vcc_lo, 0x400000
	s_add_u32 s100, s14, vcc_lo
	s_addc_u32 s101, s15, 0
	global_store_dwordx2 v137, v[156:157], s[100:101] offset:0
	global_store_dwordx2 v137, v[158:159], s[100:101] offset:512
	global_store_dwordx2 v137, v[160:161], s[100:101] offset:1024
	global_store_dwordx2 v137, v[162:163], s[100:101] offset:1536
	s_lshl_b32 vcc_lo, s19, 12
	s_add_u32 vcc_lo, vcc_lo, 0x2000000
	s_add_u32 s100, s12, vcc_lo
	s_addc_u32 s101, s13, 0
	global_load_dwordx4 v[16:19], v136, s[100:101] offset:0
	global_load_dwordx4 v[20:23], v136, s[100:101] offset:1024
	global_load_dwordx4 v[24:27], v136, s[100:101] offset:2048
	global_load_dwordx4 v[28:31], v136, s[100:101] offset:3072
	s_lshl_b32 vcc_lo, s19, 11
	s_add_u32 vcc_lo, vcc_lo, 0x1000000
	s_add_u32 s100, s14, vcc_lo
	s_addc_u32 s101, s15, 0
	global_load_dwordx2 v[56:57], v137, s[100:101] offset:0
	global_load_dwordx2 v[58:59], v137, s[100:101] offset:512
	global_load_dwordx2 v[60:61], v137, s[100:101] offset:1024
	global_load_dwordx2 v[62:63], v137, s[100:101] offset:1536
	s_waitcnt vmcnt(32)
	v_lshlrev_b32_e32 v120, 16, v64
	v_and_b32_e32 v121, 0xffff0000, v64
	v_lshlrev_b32_e32 v122, 16, v65
	v_and_b32_e32 v123, 0xffff0000, v65
	v_lshlrev_b32_e32 v124, 16, v66
	v_and_b32_e32 v125, 0xffff0000, v66
	v_lshlrev_b32_e32 v126, 16, v67
	v_and_b32_e32 v127, 0xffff0000, v67
	v_lshlrev_b32_e32 v128, 16, v68
	v_and_b32_e32 v129, 0xffff0000, v68
	v_lshlrev_b32_e32 v130, 16, v69
	v_and_b32_e32 v131, 0xffff0000, v69
	v_lshlrev_b32_e32 v132, 16, v70
	v_and_b32_e32 v133, 0xffff0000, v70
	v_lshlrev_b32_e32 v134, 16, v71
	v_and_b32_e32 v135, 0xffff0000, v71
	v_mul_f32_e32 v138, v120, v120
	v_mul_f32_e32 v149, v121, v121
	v_mul_f32_e32 v150, v122, v122
	v_mul_f32_e32 v154, v123, v123
	v_fma_f32 v138, v124, v124, v138
	v_fma_f32 v149, v125, v125, v149
	v_fma_f32 v150, v126, v126, v150
	v_fma_f32 v154, v127, v127, v154
	v_fma_f32 v138, v128, v128, v138
	v_fma_f32 v149, v129, v129, v149
	v_fma_f32 v150, v130, v130, v150
	v_fma_f32 v154, v131, v131, v154
	v_fma_f32 v138, v132, v132, v138
	v_fma_f32 v149, v133, v133, v149
	v_fma_f32 v150, v134, v134, v150
	v_fma_f32 v154, v135, v135, v154
	v_add_f32_e32 v138, v138, v149
	v_add_f32_e32 v150, v150, v154
	v_add_f32_e32 v138, v138, v150
	s_nop 1
	v_add_f32_dpp v138, v138, v138 quad_perm:[1,0,3,2] row_mask:0xf bank_mask:0xf
	s_nop 1
	v_add_f32_dpp v138, v138, v138 quad_perm:[2,3,0,1] row_mask:0xf bank_mask:0xf
	s_nop 1
	v_add_f32_dpp v138, v138, v138 row_half_mirror row_mask:0xf bank_mask:0xf
	s_nop 1
	v_add_f32_dpp v138, v138, v138 row_mirror row_mask:0xf bank_mask:0xf
	v_mov_b32_e32 v139, v138
	s_nop 1
	v_permlane16_swap_b32_e32 v138, v139
	v_add_f32_e32 v138, v138, v139
	v_mov_b32_e32 v139, v138
	s_nop 1
	v_permlane32_swap_b32_e32 v138, v139
	v_add_f32_e32 v138, v138, v139
	v_mul_f32_e32 v138, 0x3a800000, v138
	v_add_f32_e32 v138, 0x358637bd, v138
	v_rsq_f32_e32 v140, v138
	s_nop 0
	v_mul_f32_e32 v120, v120, v140
	v_mul_f32_e32 v121, v121, v140
	v_mul_f32_e32 v122, v122, v140
	v_mul_f32_e32 v123, v123, v140
	v_mul_f32_e32 v124, v124, v140
	v_mul_f32_e32 v125, v125, v140
	v_mul_f32_e32 v126, v126, v140
	v_mul_f32_e32 v127, v127, v140
	v_mul_f32_e32 v128, v128, v140
	v_mul_f32_e32 v129, v129, v140
	v_mul_f32_e32 v130, v130, v140
	v_mul_f32_e32 v131, v131, v140
	v_mul_f32_e32 v132, v132, v140
	v_mul_f32_e32 v133, v133, v140
	v_mul_f32_e32 v134, v134, v140
	v_mul_f32_e32 v135, v135, v140
	v_fma_f32 v32, v120, v72, v32
	v_fma_f32 v33, v121, v73, v33
	v_fma_f32 v34, v122, v74, v34
	v_fma_f32 v35, v123, v75, v35
	v_fma_f32 v36, v124, v76, v36
	v_fma_f32 v37, v125, v77, v37
	v_fma_f32 v38, v126, v78, v38
	v_fma_f32 v39, v127, v79, v39
	v_fma_f32 v40, v128, v80, v40
	v_fma_f32 v41, v129, v81, v41
	v_fma_f32 v42, v130, v82, v42
	v_fma_f32 v43, v131, v83, v43
	v_fma_f32 v44, v132, v84, v44
	v_fma_f32 v45, v133, v85, v45
	v_fma_f32 v46, v134, v86, v46
	v_fma_f32 v47, v135, v87, v47
	v_cvt_pk_bf16_f32 v156, v32, v33
	v_cvt_pk_bf16_f32 v157, v34, v35
	v_cvt_pk_bf16_f32 v158, v36, v37
	v_cvt_pk_bf16_f32 v159, v38, v39
; __device__ __forceinline__ void row_phase(const Params& P, int glayer, int layer, int xsrc, bool hasY, int gate_idx, const float* gpost,
;                           int xdst, bool doH, const float* gpre, int sh_idx, int nrows) {
;     ...
;         if (hasY) {
;           float4 yv[4];
;           float ss = 0.f;
; #pragma unroll
;           for (int i = 0; i < 4; ++i) {
;             const uint2 raw = yy[u][i];
;             yv[i].x = bf2f((u16)(raw.x & 0xffff)); yv[i].y = bf2f((u16)(raw.x >> 16));
;             yv[i].z = bf2f((u16)(raw.y & 0xffff)); yv[i].w = bf2f((u16)(raw.y >> 16));
;             ss += yv[i].x * yv[i].x + yv[i].y * yv[i].y + yv[i].z * yv[i].z + yv[i].w * yv[i].w;
;           }
;           ss = wave_sum(ss);
;           const float rstd = __builtin_amdgcn_rsqf(ss * (1.f / 1024.f) + EPSF);
; #pragma unroll
;           for (int i = 0; i < 4; ++i) {
;             const int col = (i * 64 + lane) * 4;
;             const float4 gt = *reinterpret_cast<const float4*>(modg + gate_idx * 1024 + col);
;             const float4 gp = *reinterpret_cast<const float4*>(gpost + col);
;             xv[i].x += gt.x * (yv[i].x * rstd * gp.x); xv[i].y += gt.y * (yv[i].y * rstd * gp.y);
;             xv[i].z += gt.z * (yv[i].z * rstd * gp.z); xv[i].w += gt.w * (yv[i].w * rstd * gp.w);
;           }
;         }
;         if (xdst == 3 || (xdst == 1 && row >= N_X)) {
;           float* xout = (xdst == 3) ? P.out + (long)row * 1024 : P.xc + (long)(row - N_X) * 1024;
; #pragma unroll
;           for (int i = 0; i < 4; ++i) *reinterpret_cast<float4*>(xout + (i * 64 + lane) * 4) = xv[i];
;         } else if (xdst != 0) {
;           u16* xo = ((xdst == 1) ? resA : P.zf) + (long)row * 1024;
; #pragma unroll
;           for (int i = 0; i < 4; ++i) {
;             const unsigned b0 = f2bf(xv[i].x), b1 = f2bf(xv[i].y), b2 = f2bf(xv[i].z), b3 = f2bf(xv[i].w);
;             *reinterpret_cast<uint2*>(xo + (i * 64 + lane) * 4) = make_uint2(b0 | (b1 << 16), b2 | (b3 << 16));
;           }
;         }
;         if (doH) {
;           float ss = 0.f;
; #pragma unroll
;           for (int i = 0; i < 4; ++i) ss += xv[i].x * xv[i].x + xv[i].y * xv[i].y + xv[i].z * xv[i].z + xv[i].w * xv[i].w;
;           ss = wave_sum(ss);
;           const float rstd = __builtin_amdgcn_rsqf(ss * (1.f / 1024.f) + EPSF);
;           u16* h = P.hy + (long)row * 1024;
; #pragma unroll
	v_cvt_pk_bf16_f32 v160, v40, v41
	v_cvt_pk_bf16_f32 v161, v42, v43
	v_cvt_pk_bf16_f32 v162, v44, v45
	v_cvt_pk_bf16_f32 v163, v46, v47
	s_lshl_b32 vcc_lo, s19, 11
	s_add_u32 vcc_lo, vcc_lo, 0x800000
	s_add_u32 s100, s16, vcc_lo
	s_addc_u32 s101, s17, 0
	global_store_dwordx2 v137, v[156:157], s[100:101] offset:0
	global_store_dwordx2 v137, v[158:159], s[100:101] offset:512
	global_store_dwordx2 v137, v[160:161], s[100:101] offset:1024
	global_store_dwordx2 v137, v[162:163], s[100:101] offset:1536
	v_mul_f32_e32 v138, v32, v32
	v_mul_f32_e32 v149, v33, v33
	v_mul_f32_e32 v150, v34, v34
	v_mul_f32_e32 v154, v35, v35
	v_fma_f32 v138, v36, v36, v138
	v_fma_f32 v149, v37, v37, v149
	v_fma_f32 v150, v38, v38, v150
	v_fma_f32 v154, v39, v39, v154
	v_fma_f32 v138, v40, v40, v138
	v_fma_f32 v149, v41, v41, v149
	v_fma_f32 v150, v42, v42, v150
	v_fma_f32 v154, v43, v43, v154
	v_fma_f32 v138, v44, v44, v138
	v_fma_f32 v149, v45, v45, v149
	v_fma_f32 v150, v46, v46, v150
	v_fma_f32 v154, v47, v47, v154
	v_add_f32_e32 v138, v138, v149
	v_add_f32_e32 v150, v150, v154
	v_add_f32_e32 v138, v138, v150
	s_nop 1
	v_add_f32_dpp v138, v138, v138 quad_perm:[1,0,3,2] row_mask:0xf bank_mask:0xf
	s_nop 1
	v_add_f32_dpp v138, v138, v138 quad_perm:[2,3,0,1] row_mask:0xf bank_mask:0xf
	s_nop 1
	v_add_f32_dpp v138, v138, v138 row_half_mirror row_mask:0xf bank_mask:0xf
	s_nop 1
	v_add_f32_dpp v138, v138, v138 row_mirror row_mask:0xf bank_mask:0xf
	v_mov_b32_e32 v139, v138
	s_nop 1
	v_permlane16_swap_b32_e32 v138, v139
	v_add_f32_e32 v138, v138, v139
	v_mov_b32_e32 v139, v138
	s_nop 1
	v_permlane32_swap_b32_e32 v138, v139
	v_add_f32_e32 v138, v138, v139
	v_mul_f32_e32 v138, 0x3a800000, v138
	v_add_f32_e32 v138, 0x358637bd, v138
	v_rsq_f32_e32 v140, v138
	s_nop 0
	v_mul_f32_e32 v120, v32, v140
	v_mul_f32_e32 v121, v33, v140
	v_mul_f32_e32 v122, v34, v140
	v_mul_f32_e32 v123, v35, v140
	v_mul_f32_e32 v124, v36, v140
	v_mul_f32_e32 v125, v37, v140
	v_mul_f32_e32 v126, v38, v140
	v_mul_f32_e32 v127, v39, v140
	v_mul_f32_e32 v128, v40, v140
	v_mul_f32_e32 v129, v41, v140
	v_mul_f32_e32 v130, v42, v140
	v_mul_f32_e32 v131, v43, v140
	v_mul_f32_e32 v132, v44, v140
	v_mul_f32_e32 v133, v45, v140
	v_mul_f32_e32 v134, v46, v140
	v_mul_f32_e32 v135, v47, v140
	v_fma_f32 v120, v120, v88, v104
	v_fma_f32 v121, v121, v89, v105
	v_fma_f32 v122, v122, v90, v106
	v_fma_f32 v123, v123, v91, v107
	v_fma_f32 v124, v124, v92, v108
	v_fma_f32 v125, v125, v93, v109
	v_fma_f32 v126, v126, v94, v110
	v_fma_f32 v127, v127, v95, v111
	v_fma_f32 v128, v128, v96, v112
	v_fma_f32 v129, v129, v97, v113
	v_fma_f32 v130, v130, v98, v114
	v_fma_f32 v131, v131, v99, v115
	v_fma_f32 v132, v132, v100, v116
	v_fma_f32 v133, v133, v101, v117
	v_fma_f32 v134, v134, v102, v118
	v_fma_f32 v135, v135, v103, v119
	v_cvt_pk_bf16_f32 v156, v120, v121
	v_cvt_pk_bf16_f32 v157, v122, v123
	v_cvt_pk_bf16_f32 v158, v124, v125
	v_cvt_pk_bf16_f32 v159, v126, v127
	v_cvt_pk_bf16_f32 v160, v128, v129
	v_cvt_pk_bf16_f32 v161, v130, v131
	v_cvt_pk_bf16_f32 v162, v132, v133
	v_cvt_pk_bf16_f32 v163, v134, v135
	s_lshl_b32 vcc_lo, s19, 11
	s_add_u32 vcc_lo, vcc_lo, 0x800000
	s_add_u32 s100, s14, vcc_lo
	s_addc_u32 s101, s15, 0
	global_store_dwordx2 v137, v[156:157], s[100:101] offset:0
	global_store_dwordx2 v137, v[158:159], s[100:101] offset:512
	global_store_dwordx2 v137, v[160:161], s[100:101] offset:1024
	global_store_dwordx2 v137, v[162:163], s[100:101] offset:1536
	s_lshl_b32 vcc_lo, s19, 12
	s_add_u32 vcc_lo, vcc_lo, 0x2800000
	s_add_u32 s100, s12, vcc_lo
	s_addc_u32 s101, s13, 0
	global_load_dwordx4 v[32:35], v136, s[100:101] offset:0
	global_load_dwordx4 v[36:39], v136, s[100:101] offset:1024
	global_load_dwordx4 v[40:43], v136, s[100:101] offset:2048
	global_load_dwordx4 v[44:47], v136, s[100:101] offset:3072
	s_lshl_b32 vcc_lo, s19, 11
	s_add_u32 vcc_lo, vcc_lo, 0x1400000
	s_add_u32 s100, s14, vcc_lo
	s_addc_u32 s101, s15, 0
	global_load_dwordx2 v[64:65], v137, s[100:101] offset:0
	global_load_dwordx2 v[66:67], v137, s[100:101] offset:512
	global_load_dwordx2 v[68:69], v137, s[100:101] offset:1024
	global_load_dwordx2 v[70:71], v137, s[100:101] offset:1536
	s_waitcnt vmcnt(32)
	v_lshlrev_b32_e32 v120, 16, v48
	v_and_b32_e32 v121, 0xffff0000, v48
	v_lshlrev_b32_e32 v122, 16, v49
	v_and_b32_e32 v123, 0xffff0000, v49
	v_lshlrev_b32_e32 v124, 16, v50
	v_and_b32_e32 v125, 0xffff0000, v50
	v_lshlrev_b32_e32 v126, 16, v51
	v_and_b32_e32 v127, 0xffff0000, v51
	v_lshlrev_b32_e32 v128, 16, v52
	v_and_b32_e32 v129, 0xffff0000, v52
	v_lshlrev_b32_e32 v130, 16, v53
	v_and_b32_e32 v131, 0xffff0000, v53
	v_lshlrev_b32_e32 v132, 16, v54
	v_and_b32_e32 v133, 0xffff0000, v54
	v_lshlrev_b32_e32 v134, 16, v55
	v_and_b32_e32 v135, 0xffff0000, v55
	v_mul_f32_e32 v138, v120, v120
	v_mul_f32_e32 v149, v121, v121
	v_mul_f32_e32 v150, v122, v122
	v_mul_f32_e32 v154, v123, v123
	v_fma_f32 v138, v124, v124, v138
	v_fma_f32 v149, v125, v125, v149
	v_fma_f32 v150, v126, v126, v150
	v_fma_f32 v154, v127, v127, v154
	v_fma_f32 v138, v128, v128, v138
	v_fma_f32 v149, v129, v129, v149
	v_fma_f32 v150, v130, v130, v150
	v_fma_f32 v154, v131, v131, v154
	v_fma_f32 v138, v132, v132, v138
	v_fma_f32 v149, v133, v133, v149
	v_fma_f32 v150, v134, v134, v150
	v_fma_f32 v154, v135, v135, v154
	v_add_f32_e32 v138, v138, v149
	v_add_f32_e32 v150, v150, v154
	v_add_f32_e32 v138, v138, v150
	s_nop 1
	v_add_f32_dpp v138, v138, v138 quad_perm:[1,0,3,2] row_mask:0xf bank_mask:0xf
	s_nop 1
	v_add_f32_dpp v138, v138, v138 quad_perm:[2,3,0,1] row_mask:0xf bank_mask:0xf
	s_nop 1
	v_add_f32_dpp v138, v138, v138 row_half_mirror row_mask:0xf bank_mask:0xf
	s_nop 1
; __device__ __forceinline__ void row_phase(const Params& P, int glayer, int layer, int xsrc, bool hasY, int gate_idx, const float* gpost,
;                           int xdst, bool doH, const float* gpre, int sh_idx, int nrows) {
;     ...
;         if (hasY) {
;           float4 yv[4];
;           float ss = 0.f;
; #pragma unroll
;           for (int i = 0; i < 4; ++i) {
;             const uint2 raw = yy[u][i];
;             yv[i].x = bf2f((u16)(raw.x & 0xffff)); yv[i].y = bf2f((u16)(raw.x >> 16));
;             yv[i].z = bf2f((u16)(raw.y & 0xffff)); yv[i].w = bf2f((u16)(raw.y >> 16));
;             ss += yv[i].x * yv[i].x + yv[i].y * yv[i].y + yv[i].z * yv[i].z + yv[i].w * yv[i].w;
;           }
;           ss = wave_sum(ss);
;           const float rstd = __builtin_amdgcn_rsqf(ss * (1.f / 1024.f) + EPSF);
; #pragma unroll
;           for (int i = 0; i < 4; ++i) {
;             const int col = (i * 64 + lane) * 4;
;             const float4 gt = *reinterpret_cast<const float4*>(modg + gate_idx * 1024 + col);
;             const float4 gp = *reinterpret_cast<const float4*>(gpost + col);
;             xv[i].x += gt.x * (yv[i].x * rstd * gp.x); xv[i].y += gt.y * (yv[i].y * rstd * gp.y);
;             xv[i].z += gt.z * (yv[i].z * rstd * gp.z); xv[i].w += gt.w * (yv[i].w * rstd * gp.w);
;           }
;         }
;         if (xdst == 3 || (xdst == 1 && row >= N_X)) {
;           float* xout = (xdst == 3) ? P.out + (long)row * 1024 : P.xc + (long)(row - N_X) * 1024;
; #pragma unroll
;           for (int i = 0; i < 4; ++i) *reinterpret_cast<float4*>(xout + (i * 64 + lane) * 4) = xv[i];
;         } else if (xdst != 0) {
;           u16* xo = ((xdst == 1) ? resA : P.zf) + (long)row * 1024;
; #pragma unroll
;           for (int i = 0; i < 4; ++i) {
;             const unsigned b0 = f2bf(xv[i].x), b1 = f2bf(xv[i].y), b2 = f2bf(xv[i].z), b3 = f2bf(xv[i].w);
;             *reinterpret_cast<uint2*>(xo + (i * 64 + lane) * 4) = make_uint2(b0 | (b1 << 16), b2 | (b3 << 16));
;           }
;         }
;         if (doH) {
;           float ss = 0.f;
; #pragma unroll
;           for (int i = 0; i < 4; ++i) ss += xv[i].x * xv[i].x + xv[i].y * xv[i].y + xv[i].z * xv[i].z + xv[i].w * xv[i].w;
;           ss = wave_sum(ss);
;           const float rstd = __builtin_amdgcn_rsqf(ss * (1.f / 1024.f) + EPSF);
;           u16* h = P.hy + (long)row * 1024;
; #pragma unroll
	v_add_f32_dpp v138, v138, v138 row_mirror row_mask:0xf bank_mask:0xf
	v_mov_b32_e32 v139, v138
	s_nop 1
	v_permlane16_swap_b32_e32 v138, v139
	v_add_f32_e32 v138, v138, v139
	v_mov_b32_e32 v139, v138
	s_nop 1
	v_permlane32_swap_b32_e32 v138, v139
	v_add_f32_e32 v138, v138, v139
	v_mul_f32_e32 v138, 0x3a800000, v138
	v_add_f32_e32 v138, 0x358637bd, v138
	v_rsq_f32_e32 v140, v138
	s_nop 0
	v_mul_f32_e32 v120, v120, v140
	v_mul_f32_e32 v121, v121, v140
	v_mul_f32_e32 v122, v122, v140
	v_mul_f32_e32 v123, v123, v140
	v_mul_f32_e32 v124, v124, v140
	v_mul_f32_e32 v125, v125, v140
	v_mul_f32_e32 v126, v126, v140
	v_mul_f32_e32 v127, v127, v140
	v_mul_f32_e32 v128, v128, v140
	v_mul_f32_e32 v129, v129, v140
	v_mul_f32_e32 v130, v130, v140
	v_mul_f32_e32 v131, v131, v140
	v_mul_f32_e32 v132, v132, v140
	v_mul_f32_e32 v133, v133, v140
	v_mul_f32_e32 v134, v134, v140
	v_mul_f32_e32 v135, v135, v140
	v_fma_f32 v0, v120, v72, v0
	v_fma_f32 v1, v121, v73, v1
	v_fma_f32 v2, v122, v74, v2
	v_fma_f32 v3, v123, v75, v3
	v_fma_f32 v4, v124, v76, v4
	v_fma_f32 v5, v125, v77, v5
	v_fma_f32 v6, v126, v78, v6
	v_fma_f32 v7, v127, v79, v7
	v_fma_f32 v8, v128, v80, v8
	v_fma_f32 v9, v129, v81, v9
	v_fma_f32 v10, v130, v82, v10
	v_fma_f32 v11, v131, v83, v11
	v_fma_f32 v12, v132, v84, v12
	v_fma_f32 v13, v133, v85, v13
	v_fma_f32 v14, v134, v86, v14
	v_fma_f32 v15, v135, v87, v15
	v_cvt_pk_bf16_f32 v156, v0, v1
	v_cvt_pk_bf16_f32 v157, v2, v3
	v_cvt_pk_bf16_f32 v158, v4, v5
	v_cvt_pk_bf16_f32 v159, v6, v7
	v_cvt_pk_bf16_f32 v160, v8, v9
	v_cvt_pk_bf16_f32 v161, v10, v11
	v_cvt_pk_bf16_f32 v162, v12, v13
	v_cvt_pk_bf16_f32 v163, v14, v15
	s_lshl_b32 vcc_lo, s19, 11
	s_add_u32 vcc_lo, vcc_lo, 0xc00000
	s_add_u32 s100, s16, vcc_lo
	s_addc_u32 s101, s17, 0
	global_store_dwordx2 v137, v[156:157], s[100:101] offset:0
	global_store_dwordx2 v137, v[158:159], s[100:101] offset:512
	global_store_dwordx2 v137, v[160:161], s[100:101] offset:1024
	global_store_dwordx2 v137, v[162:163], s[100:101] offset:1536
	v_mul_f32_e32 v138, v0, v0
	v_mul_f32_e32 v149, v1, v1
	v_mul_f32_e32 v150, v2, v2
	v_mul_f32_e32 v154, v3, v3
	v_fma_f32 v138, v4, v4, v138
	v_fma_f32 v149, v5, v5, v149
	v_fma_f32 v150, v6, v6, v150
	v_fma_f32 v154, v7, v7, v154
	v_fma_f32 v138, v8, v8, v138
	v_fma_f32 v149, v9, v9, v149
	v_fma_f32 v150, v10, v10, v150
	v_fma_f32 v154, v11, v11, v154
	v_fma_f32 v138, v12, v12, v138
	v_fma_f32 v149, v13, v13, v149
	v_fma_f32 v150, v14, v14, v150
	v_fma_f32 v154, v15, v15, v154
	v_add_f32_e32 v138, v138, v149
	v_add_f32_e32 v150, v150, v154
	v_add_f32_e32 v138, v138, v150
	s_nop 1
	v_add_f32_dpp v138, v138, v138 quad_perm:[1,0,3,2] row_mask:0xf bank_mask:0xf
	s_nop 1
	v_add_f32_dpp v138, v138, v138 quad_perm:[2,3,0,1] row_mask:0xf bank_mask:0xf
	s_nop 1
	v_add_f32_dpp v138, v138, v138 row_half_mirror row_mask:0xf bank_mask:0xf
	s_nop 1
	v_add_f32_dpp v138, v138, v138 row_mirror row_mask:0xf bank_mask:0xf
	v_mov_b32_e32 v139, v138
	s_nop 1
	v_permlane16_swap_b32_e32 v138, v139
	v_add_f32_e32 v138, v138, v139
	v_mov_b32_e32 v139, v138
	s_nop 1
	v_permlane32_swap_b32_e32 v138, v139
	v_add_f32_e32 v138, v138, v139
	v_mul_f32_e32 v138, 0x3a800000, v138
	v_add_f32_e32 v138, 0x358637bd, v138
	v_rsq_f32_e32 v140, v138
	s_nop 0
	v_mul_f32_e32 v120, v0, v140
	v_mul_f32_e32 v121, v1, v140
	v_mul_f32_e32 v122, v2, v140
	v_mul_f32_e32 v123, v3, v140
	v_mul_f32_e32 v124, v4, v140
	v_mul_f32_e32 v125, v5, v140
	v_mul_f32_e32 v126, v6, v140
	v_mul_f32_e32 v127, v7, v140
	v_mul_f32_e32 v128, v8, v140
	v_mul_f32_e32 v129, v9, v140
	v_mul_f32_e32 v130, v10, v140
	v_mul_f32_e32 v131, v11, v140
	v_mul_f32_e32 v132, v12, v140
	v_mul_f32_e32 v133, v13, v140
	v_mul_f32_e32 v134, v14, v140
	v_mul_f32_e32 v135, v15, v140
	v_fma_f32 v120, v120, v88, v104
	v_fma_f32 v121, v121, v89, v105
	v_fma_f32 v122, v122, v90, v106
	v_fma_f32 v123, v123, v91, v107
	v_fma_f32 v124, v124, v92, v108
	v_fma_f32 v125, v125, v93, v109
	v_fma_f32 v126, v126, v94, v110
	v_fma_f32 v127, v127, v95, v111
	v_fma_f32 v128, v128, v96, v112
	v_fma_f32 v129, v129, v97, v113
	v_fma_f32 v130, v130, v98, v114
	v_fma_f32 v131, v131, v99, v115
	v_fma_f32 v132, v132, v100, v116
	v_fma_f32 v133, v133, v101, v117
	v_fma_f32 v134, v134, v102, v118
	v_fma_f32 v135, v135, v103, v119
	v_cvt_pk_bf16_f32 v156, v120, v121
	v_cvt_pk_bf16_f32 v157, v122, v123
	v_cvt_pk_bf16_f32 v158, v124, v125
	v_cvt_pk_bf16_f32 v159, v126, v127
	v_cvt_pk_bf16_f32 v160, v128, v129
	v_cvt_pk_bf16_f32 v161, v130, v131
	v_cvt_pk_bf16_f32 v162, v132, v133
	v_cvt_pk_bf16_f32 v163, v134, v135
	s_lshl_b32 vcc_lo, s19, 11
	s_add_u32 vcc_lo, vcc_lo, 0xc00000
	s_add_u32 s100, s14, vcc_lo
	s_addc_u32 s101, s15, 0
	global_store_dwordx2 v137, v[156:157], s[100:101] offset:0
	global_store_dwordx2 v137, v[158:159], s[100:101] offset:512
	global_store_dwordx2 v137, v[160:161], s[100:101] offset:1024
	global_store_dwordx2 v137, v[162:163], s[100:101] offset:1536
	s_add_u32 s100, s20, 0x8000
	s_addc_u32 s101, s21, 0
	global_load_dwordx4 v[72:75], v136, s[100:101] offset:0
	global_load_dwordx4 v[76:79], v136, s[100:101] offset:1024
	global_load_dwordx4 v[80:83], v136, s[100:101] offset:2048
	global_load_dwordx4 v[84:87], v136, s[100:101] offset:3072
	s_load_dwordx2 s[98:99], s[4:5], 0x38
	s_waitcnt lgkmcnt(0)
; __device__ __forceinline__ void row_phase(const Params& P, int glayer, int layer, int xsrc, bool hasY, int gate_idx, const float* gpost,
;                           int xdst, bool doH, const float* gpre, int sh_idx, int nrows) {
;     ...
;         if (hasY) {
;           float4 yv[4];
;           float ss = 0.f;
; #pragma unroll
;           for (int i = 0; i < 4; ++i) {
;             const uint2 raw = yy[u][i];
;             yv[i].x = bf2f((u16)(raw.x & 0xffff)); yv[i].y = bf2f((u16)(raw.x >> 16));
;             yv[i].z = bf2f((u16)(raw.y & 0xffff)); yv[i].w = bf2f((u16)(raw.y >> 16));
;             ss += yv[i].x * yv[i].x + yv[i].y * yv[i].y + yv[i].z * yv[i].z + yv[i].w * yv[i].w;
;           }
;           ss = wave_sum(ss);
;           const float rstd = __builtin_amdgcn_rsqf(ss * (1.f / 1024.f) + EPSF);
; #pragma unroll
;           for (int i = 0; i < 4; ++i) {
;             const int col = (i * 64 + lane) * 4;
;             const float4 gt = *reinterpret_cast<const float4*>(modg + gate_idx * 1024 + col);
;             const float4 gp = *reinterpret_cast<const float4*>(gpost + col);
;             xv[i].x += gt.x * (yv[i].x * rstd * gp.x); xv[i].y += gt.y * (yv[i].y * rstd * gp.y);
;             xv[i].z += gt.z * (yv[i].z * rstd * gp.z); xv[i].w += gt.w * (yv[i].w * rstd * gp.w);
;           }
;         }
;         if (xdst == 3 || (xdst == 1 && row >= N_X)) {
;           float* xout = (xdst == 3) ? P.out + (long)row * 1024 : P.xc + (long)(row - N_X) * 1024;
; #pragma unroll
;           for (int i = 0; i < 4; ++i) *reinterpret_cast<float4*>(xout + (i * 64 + lane) * 4) = xv[i];
;         } else if (xdst != 0) {
;           u16* xo = ((xdst == 1) ? resA : P.zf) + (long)row * 1024;
; #pragma unroll
;           for (int i = 0; i < 4; ++i) {
;             const unsigned b0 = f2bf(xv[i].x), b1 = f2bf(xv[i].y), b2 = f2bf(xv[i].z), b3 = f2bf(xv[i].w);
;             *reinterpret_cast<uint2*>(xo + (i * 64 + lane) * 4) = make_uint2(b0 | (b1 << 16), b2 | (b3 << 16));
;           }
;         }
;         if (doH) {
;           float ss = 0.f;
; #pragma unroll
;           for (int i = 0; i < 4; ++i) ss += xv[i].x * xv[i].x + xv[i].y * xv[i].y + xv[i].z * xv[i].z + xv[i].w * xv[i].w;
;           ss = wave_sum(ss);
;           const float rstd = __builtin_amdgcn_rsqf(ss * (1.f / 1024.f) + EPSF);
;           u16* h = P.hy + (long)row * 1024;
; #pragma unroll
	global_load_dwordx4 v[120:123], v136, s[98:99] offset:0
	global_load_dwordx4 v[124:127], v136, s[98:99] offset:1024
	global_load_dwordx4 v[128:131], v136, s[98:99] offset:2048
	global_load_dwordx4 v[132:135], v136, s[98:99] offset:3072
	s_add_u32 s100, s20, 0x9000
	s_addc_u32 s101, s21, 0
	global_load_dwordx4 v[104:107], v136, s[100:101] offset:0
	global_load_dwordx4 v[108:111], v136, s[100:101] offset:1024
	global_load_dwordx4 v[112:115], v136, s[100:101] offset:2048
	global_load_dwordx4 v[116:119], v136, s[100:101] offset:3072
	s_add_u32 s100, s100, 0x1000
	s_addc_u32 s101, s101, 0
	global_load_dwordx4 v[0:3], v136, s[100:101] offset:0
	global_load_dwordx4 v[4:7], v136, s[100:101] offset:1024
	global_load_dwordx4 v[8:11], v136, s[100:101] offset:2048
	global_load_dwordx4 v[12:15], v136, s[100:101] offset:3072
	s_load_dwordx2 s[98:99], s[4:5], 0x40
	s_waitcnt lgkmcnt(0)
	global_load_dwordx4 v[88:91], v136, s[98:99] offset:0
	global_load_dwordx4 v[92:95], v136, s[98:99] offset:1024
	global_load_dwordx4 v[96:99], v136, s[98:99] offset:2048
	global_load_dwordx4 v[100:103], v136, s[98:99] offset:3072
	s_waitcnt vmcnt(0)
	v_mul_f32_e32 v72, v72, v120
	v_mul_f32_e32 v73, v73, v121
	v_mul_f32_e32 v74, v74, v122
	v_mul_f32_e32 v75, v75, v123
	v_mul_f32_e32 v76, v76, v124
	v_mul_f32_e32 v77, v77, v125
	v_mul_f32_e32 v78, v78, v126
	v_mul_f32_e32 v79, v79, v127
	v_mul_f32_e32 v80, v80, v128
	v_mul_f32_e32 v81, v81, v129
	v_mul_f32_e32 v82, v82, v130
	v_mul_f32_e32 v83, v83, v131
	v_mul_f32_e32 v84, v84, v132
	v_mul_f32_e32 v85, v85, v133
	v_mul_f32_e32 v86, v86, v134
	v_mul_f32_e32 v87, v87, v135
	v_fma_f32 v88, v88, v0, v88
	v_fma_f32 v89, v89, v1, v89
	v_fma_f32 v90, v90, v2, v90
	v_fma_f32 v91, v91, v3, v91
	v_fma_f32 v92, v92, v4, v92
	v_fma_f32 v93, v93, v5, v93
	v_fma_f32 v94, v94, v6, v94
	v_fma_f32 v95, v95, v7, v95
	v_fma_f32 v96, v96, v8, v96
	v_fma_f32 v97, v97, v9, v97
	v_fma_f32 v98, v98, v10, v98
	v_fma_f32 v99, v99, v11, v99
	v_fma_f32 v100, v100, v12, v100
	v_fma_f32 v101, v101, v13, v101
	v_fma_f32 v102, v102, v14, v102
	v_fma_f32 v103, v103, v15, v103
	s_lshl_b32 vcc_lo, s19, 12
	s_add_u32 vcc_lo, vcc_lo, 0x3000000
	s_add_u32 s100, s12, vcc_lo
	s_addc_u32 s101, s13, 0
	global_load_dwordx4 v[0:3], v136, s[100:101] offset:0
	global_load_dwordx4 v[4:7], v136, s[100:101] offset:1024
	global_load_dwordx4 v[8:11], v136, s[100:101] offset:2048
	global_load_dwordx4 v[12:15], v136, s[100:101] offset:3072
	s_lshl_b32 vcc_lo, s19, 11
	s_add_u32 vcc_lo, vcc_lo, 0x1800000
	s_add_u32 s100, s14, vcc_lo
	s_addc_u32 s101, s15, 0
	global_load_dwordx2 v[48:49], v137, s[100:101] offset:0
	global_load_dwordx2 v[50:51], v137, s[100:101] offset:512
	global_load_dwordx2 v[52:53], v137, s[100:101] offset:1024
	global_load_dwordx2 v[54:55], v137, s[100:101] offset:1536
	v_lshlrev_b32_e32 v120, 16, v56
	v_and_b32_e32 v121, 0xffff0000, v56
	v_lshlrev_b32_e32 v122, 16, v57
	v_and_b32_e32 v123, 0xffff0000, v57
	v_lshlrev_b32_e32 v124, 16, v58
	v_and_b32_e32 v125, 0xffff0000, v58
	v_lshlrev_b32_e32 v126, 16, v59
	v_and_b32_e32 v127, 0xffff0000, v59
	v_lshlrev_b32_e32 v128, 16, v60
	v_and_b32_e32 v129, 0xffff0000, v60
	v_lshlrev_b32_e32 v130, 16, v61
	v_and_b32_e32 v131, 0xffff0000, v61
	v_lshlrev_b32_e32 v132, 16, v62
	v_and_b32_e32 v133, 0xffff0000, v62
	v_lshlrev_b32_e32 v134, 16, v63
	v_and_b32_e32 v135, 0xffff0000, v63
	v_mul_f32_e32 v138, v120, v120
	v_mul_f32_e32 v149, v121, v121
	v_mul_f32_e32 v150, v122, v122
	v_mul_f32_e32 v154, v123, v123
	v_fma_f32 v138, v124, v124, v138
	v_fma_f32 v149, v125, v125, v149
	v_fma_f32 v150, v126, v126, v150
	v_fma_f32 v154, v127, v127, v154
	v_fma_f32 v138, v128, v128, v138
	v_fma_f32 v149, v129, v129, v149
	v_fma_f32 v150, v130, v130, v150
	v_fma_f32 v154, v131, v131, v154
	v_fma_f32 v138, v132, v132, v138
	v_fma_f32 v149, v133, v133, v149
	v_fma_f32 v150, v134, v134, v150
	v_fma_f32 v154, v135, v135, v154
	v_add_f32_e32 v138, v138, v149
	v_add_f32_e32 v150, v150, v154
	v_add_f32_e32 v138, v138, v150
	s_nop 1
	v_add_f32_dpp v138, v138, v138 quad_perm:[1,0,3,2] row_mask:0xf bank_mask:0xf
	s_nop 1
	v_add_f32_dpp v138, v138, v138 quad_perm:[2,3,0,1] row_mask:0xf bank_mask:0xf
	s_nop 1
	v_add_f32_dpp v138, v138, v138 row_half_mirror row_mask:0xf bank_mask:0xf
	s_nop 1
	v_add_f32_dpp v138, v138, v138 row_mirror row_mask:0xf bank_mask:0xf
	v_mov_b32_e32 v139, v138
	s_nop 1
	v_permlane16_swap_b32_e32 v138, v139
	v_add_f32_e32 v138, v138, v139
	v_mov_b32_e32 v139, v138
	s_nop 1
	v_permlane32_swap_b32_e32 v138, v139
	v_add_f32_e32 v138, v138, v139
	v_mul_f32_e32 v138, 0x3a800000, v138
	v_add_f32_e32 v138, 0x358637bd, v138
	v_rsq_f32_e32 v140, v138
	s_nop 0
	v_mul_f32_e32 v120, v120, v140
	v_mul_f32_e32 v121, v121, v140
	v_mul_f32_e32 v122, v122, v140
	v_mul_f32_e32 v123, v123, v140
	v_mul_f32_e32 v124, v124, v140
	v_mul_f32_e32 v125, v125, v140
	v_mul_f32_e32 v126, v126, v140
	v_mul_f32_e32 v127, v127, v140
	v_mul_f32_e32 v128, v128, v140
	v_mul_f32_e32 v129, v129, v140
	v_mul_f32_e32 v130, v130, v140
	v_mul_f32_e32 v131, v131, v140
	v_mul_f32_e32 v132, v132, v140
	v_mul_f32_e32 v133, v133, v140
	v_mul_f32_e32 v134, v134, v140
	v_mul_f32_e32 v135, v135, v140
	v_fma_f32 v16, v120, v72, v16
	v_fma_f32 v17, v121, v73, v17
	v_fma_f32 v18, v122, v74, v18
	v_fma_f32 v19, v123, v75, v19
	v_fma_f32 v20, v124, v76, v20
	v_fma_f32 v21, v125, v77, v21
	v_fma_f32 v22, v126, v78, v22
	v_fma_f32 v23, v127, v79, v23
	v_fma_f32 v24, v128, v80, v24
	v_fma_f32 v25, v129, v81, v25
	v_fma_f32 v26, v130, v82, v26
	v_fma_f32 v27, v131, v83, v27
	v_fma_f32 v28, v132, v84, v28
	v_fma_f32 v29, v133, v85, v29
	v_fma_f32 v30, v134, v86, v30
; __device__ __forceinline__ void row_phase(const Params& P, int glayer, int layer, int xsrc, bool hasY, int gate_idx, const float* gpost,
;                           int xdst, bool doH, const float* gpre, int sh_idx, int nrows) {
;     ...
;         if (hasY) {
;           float4 yv[4];
;           float ss = 0.f;
; #pragma unroll
;           for (int i = 0; i < 4; ++i) {
;             const uint2 raw = yy[u][i];
;             yv[i].x = bf2f((u16)(raw.x & 0xffff)); yv[i].y = bf2f((u16)(raw.x >> 16));
;             yv[i].z = bf2f((u16)(raw.y & 0xffff)); yv[i].w = bf2f((u16)(raw.y >> 16));
;             ss += yv[i].x * yv[i].x + yv[i].y * yv[i].y + yv[i].z * yv[i].z + yv[i].w * yv[i].w;
;           }
;           ss = wave_sum(ss);
;           const float rstd = __builtin_amdgcn_rsqf(ss * (1.f / 1024.f) + EPSF);
; #pragma unroll
;           for (int i = 0; i < 4; ++i) {
;             const int col = (i * 64 + lane) * 4;
;             const float4 gt = *reinterpret_cast<const float4*>(modg + gate_idx * 1024 + col);
;             const float4 gp = *reinterpret_cast<const float4*>(gpost + col);
;             xv[i].x += gt.x * (yv[i].x * rstd * gp.x); xv[i].y += gt.y * (yv[i].y * rstd * gp.y);
;             xv[i].z += gt.z * (yv[i].z * rstd * gp.z); xv[i].w += gt.w * (yv[i].w * rstd * gp.w);
;           }
;         }
;         if (xdst == 3 || (xdst == 1 && row >= N_X)) {
;           float* xout = (xdst == 3) ? P.out + (long)row * 1024 : P.xc + (long)(row - N_X) * 1024;
; #pragma unroll
;           for (int i = 0; i < 4; ++i) *reinterpret_cast<float4*>(xout + (i * 64 + lane) * 4) = xv[i];
;         } else if (xdst != 0) {
;           u16* xo = ((xdst == 1) ? resA : P.zf) + (long)row * 1024;
; #pragma unroll
;           for (int i = 0; i < 4; ++i) {
;             const unsigned b0 = f2bf(xv[i].x), b1 = f2bf(xv[i].y), b2 = f2bf(xv[i].z), b3 = f2bf(xv[i].w);
;             *reinterpret_cast<uint2*>(xo + (i * 64 + lane) * 4) = make_uint2(b0 | (b1 << 16), b2 | (b3 << 16));
;           }
;         }
;         if (doH) {
;           float ss = 0.f;
; #pragma unroll
;           for (int i = 0; i < 4; ++i) ss += xv[i].x * xv[i].x + xv[i].y * xv[i].y + xv[i].z * xv[i].z + xv[i].w * xv[i].w;
;           ss = wave_sum(ss);
;           const float rstd = __builtin_amdgcn_rsqf(ss * (1.f / 1024.f) + EPSF);
;           u16* h = P.hy + (long)row * 1024;
; #pragma unroll
	v_fma_f32 v31, v135, v87, v31
	v_cvt_pk_bf16_f32 v156, v16, v17
	v_cvt_pk_bf16_f32 v157, v18, v19
	v_cvt_pk_bf16_f32 v158, v20, v21
	v_cvt_pk_bf16_f32 v159, v22, v23
	v_cvt_pk_bf16_f32 v160, v24, v25
	v_cvt_pk_bf16_f32 v161, v26, v27
	v_cvt_pk_bf16_f32 v162, v28, v29
	v_cvt_pk_bf16_f32 v163, v30, v31
	s_lshl_b32 vcc_lo, s19, 11
	s_add_u32 vcc_lo, vcc_lo, 0x1000000
	s_add_u32 s100, s16, vcc_lo
	s_addc_u32 s101, s17, 0
	global_store_dwordx2 v137, v[156:157], s[100:101] offset:0
	global_store_dwordx2 v137, v[158:159], s[100:101] offset:512
	global_store_dwordx2 v137, v[160:161], s[100:101] offset:1024
	global_store_dwordx2 v137, v[162:163], s[100:101] offset:1536
	v_mul_f32_e32 v138, v16, v16
	v_mul_f32_e32 v149, v17, v17
	v_mul_f32_e32 v150, v18, v18
	v_mul_f32_e32 v154, v19, v19
	v_fma_f32 v138, v20, v20, v138
	v_fma_f32 v149, v21, v21, v149
	v_fma_f32 v150, v22, v22, v150
	v_fma_f32 v154, v23, v23, v154
	v_fma_f32 v138, v24, v24, v138
	v_fma_f32 v149, v25, v25, v149
	v_fma_f32 v150, v26, v26, v150
	v_fma_f32 v154, v27, v27, v154
	v_fma_f32 v138, v28, v28, v138
	v_fma_f32 v149, v29, v29, v149
	v_fma_f32 v150, v30, v30, v150
	v_fma_f32 v154, v31, v31, v154
	v_add_f32_e32 v138, v138, v149
	v_add_f32_e32 v150, v150, v154
	v_add_f32_e32 v138, v138, v150
	s_nop 1
	v_add_f32_dpp v138, v138, v138 quad_perm:[1,0,3,2] row_mask:0xf bank_mask:0xf
	s_nop 1
	v_add_f32_dpp v138, v138, v138 quad_perm:[2,3,0,1] row_mask:0xf bank_mask:0xf
	s_nop 1
	v_add_f32_dpp v138, v138, v138 row_half_mirror row_mask:0xf bank_mask:0xf
	s_nop 1
	v_add_f32_dpp v138, v138, v138 row_mirror row_mask:0xf bank_mask:0xf
	v_mov_b32_e32 v139, v138
	s_nop 1
	v_permlane16_swap_b32_e32 v138, v139
	v_add_f32_e32 v138, v138, v139
	v_mov_b32_e32 v139, v138
	s_nop 1
	v_permlane32_swap_b32_e32 v138, v139
	v_add_f32_e32 v138, v138, v139
	v_mul_f32_e32 v138, 0x3a800000, v138
	v_add_f32_e32 v138, 0x358637bd, v138
	v_rsq_f32_e32 v140, v138
	s_nop 0
	v_mul_f32_e32 v120, v16, v140
	v_mul_f32_e32 v121, v17, v140
	v_mul_f32_e32 v122, v18, v140
	v_mul_f32_e32 v123, v19, v140
	v_mul_f32_e32 v124, v20, v140
	v_mul_f32_e32 v125, v21, v140
	v_mul_f32_e32 v126, v22, v140
	v_mul_f32_e32 v127, v23, v140
	v_mul_f32_e32 v128, v24, v140
	v_mul_f32_e32 v129, v25, v140
	v_mul_f32_e32 v130, v26, v140
	v_mul_f32_e32 v131, v27, v140
	v_mul_f32_e32 v132, v28, v140
	v_mul_f32_e32 v133, v29, v140
	v_mul_f32_e32 v134, v30, v140
	v_mul_f32_e32 v135, v31, v140
	v_fma_f32 v120, v120, v88, v104
	v_fma_f32 v121, v121, v89, v105
	v_fma_f32 v122, v122, v90, v106
	v_fma_f32 v123, v123, v91, v107
	v_fma_f32 v124, v124, v92, v108
	v_fma_f32 v125, v125, v93, v109
	v_fma_f32 v126, v126, v94, v110
	v_fma_f32 v127, v127, v95, v111
	v_fma_f32 v128, v128, v96, v112
	v_fma_f32 v129, v129, v97, v113
	v_fma_f32 v130, v130, v98, v114
	v_fma_f32 v131, v131, v99, v115
	v_fma_f32 v132, v132, v100, v116
	v_fma_f32 v133, v133, v101, v117
	v_fma_f32 v134, v134, v102, v118
	v_fma_f32 v135, v135, v103, v119
	v_cvt_pk_bf16_f32 v156, v120, v121
	v_cvt_pk_bf16_f32 v157, v122, v123
	v_cvt_pk_bf16_f32 v158, v124, v125
	v_cvt_pk_bf16_f32 v159, v126, v127
	v_cvt_pk_bf16_f32 v160, v128, v129
	v_cvt_pk_bf16_f32 v161, v130, v131
	v_cvt_pk_bf16_f32 v162, v132, v133
	v_cvt_pk_bf16_f32 v163, v134, v135
	s_lshl_b32 vcc_lo, s19, 11
	s_add_u32 vcc_lo, vcc_lo, 0x1000000
	s_add_u32 s100, s14, vcc_lo
	s_addc_u32 s101, s15, 0
	global_store_dwordx2 v137, v[156:157], s[100:101] offset:0
	global_store_dwordx2 v137, v[158:159], s[100:101] offset:512
	global_store_dwordx2 v137, v[160:161], s[100:101] offset:1024
	global_store_dwordx2 v137, v[162:163], s[100:101] offset:1536
	s_lshl_b32 vcc_lo, s19, 12
	s_add_u32 vcc_lo, vcc_lo, 0x3800000
	s_add_u32 s100, s12, vcc_lo
	s_addc_u32 s101, s13, 0
	global_load_dwordx4 v[16:19], v136, s[100:101] offset:0
	global_load_dwordx4 v[20:23], v136, s[100:101] offset:1024
	global_load_dwordx4 v[24:27], v136, s[100:101] offset:2048
	global_load_dwordx4 v[28:31], v136, s[100:101] offset:3072
	s_lshl_b32 vcc_lo, s19, 11
	s_add_u32 vcc_lo, vcc_lo, 0x1c00000
	s_add_u32 s100, s14, vcc_lo
	s_addc_u32 s101, s15, 0
	global_load_dwordx2 v[56:57], v137, s[100:101] offset:0
	global_load_dwordx2 v[58:59], v137, s[100:101] offset:512
	global_load_dwordx2 v[60:61], v137, s[100:101] offset:1024
	global_load_dwordx2 v[62:63], v137, s[100:101] offset:1536
	v_lshlrev_b32_e32 v120, 16, v64
	v_and_b32_e32 v121, 0xffff0000, v64
	v_lshlrev_b32_e32 v122, 16, v65
	v_and_b32_e32 v123, 0xffff0000, v65
	v_lshlrev_b32_e32 v124, 16, v66
	v_and_b32_e32 v125, 0xffff0000, v66
	v_lshlrev_b32_e32 v126, 16, v67
	v_and_b32_e32 v127, 0xffff0000, v67
	v_lshlrev_b32_e32 v128, 16, v68
	v_and_b32_e32 v129, 0xffff0000, v68
	v_lshlrev_b32_e32 v130, 16, v69
	v_and_b32_e32 v131, 0xffff0000, v69
	v_lshlrev_b32_e32 v132, 16, v70
	v_and_b32_e32 v133, 0xffff0000, v70
	v_lshlrev_b32_e32 v134, 16, v71
	v_and_b32_e32 v135, 0xffff0000, v71
	v_mul_f32_e32 v138, v120, v120
	v_mul_f32_e32 v149, v121, v121
	v_mul_f32_e32 v150, v122, v122
	v_mul_f32_e32 v154, v123, v123
	v_fma_f32 v138, v124, v124, v138
	v_fma_f32 v149, v125, v125, v149
	v_fma_f32 v150, v126, v126, v150
	v_fma_f32 v154, v127, v127, v154
	v_fma_f32 v138, v128, v128, v138
	v_fma_f32 v149, v129, v129, v149
	v_fma_f32 v150, v130, v130, v150
	v_fma_f32 v154, v131, v131, v154
	v_fma_f32 v138, v132, v132, v138
	v_fma_f32 v149, v133, v133, v149
	v_fma_f32 v150, v134, v134, v150
	v_fma_f32 v154, v135, v135, v154
	v_add_f32_e32 v138, v138, v149
	v_add_f32_e32 v150, v150, v154
	v_add_f32_e32 v138, v138, v150
	s_nop 1
	v_add_f32_dpp v138, v138, v138 quad_perm:[1,0,3,2] row_mask:0xf bank_mask:0xf
	s_nop 1
; __device__ __forceinline__ void row_phase(const Params& P, int glayer, int layer, int xsrc, bool hasY, int gate_idx, const float* gpost,
;                           int xdst, bool doH, const float* gpre, int sh_idx, int nrows) {
;     ...
;         if (hasY) {
;           float4 yv[4];
;           float ss = 0.f;
; #pragma unroll
;           for (int i = 0; i < 4; ++i) {
;             const uint2 raw = yy[u][i];
;             yv[i].x = bf2f((u16)(raw.x & 0xffff)); yv[i].y = bf2f((u16)(raw.x >> 16));
;             yv[i].z = bf2f((u16)(raw.y & 0xffff)); yv[i].w = bf2f((u16)(raw.y >> 16));
;             ss += yv[i].x * yv[i].x + yv[i].y * yv[i].y + yv[i].z * yv[i].z + yv[i].w * yv[i].w;
;           }
;           ss = wave_sum(ss);
;           const float rstd = __builtin_amdgcn_rsqf(ss * (1.f / 1024.f) + EPSF);
; #pragma unroll
;           for (int i = 0; i < 4; ++i) {
;             const int col = (i * 64 + lane) * 4;
;             const float4 gt = *reinterpret_cast<const float4*>(modg + gate_idx * 1024 + col);
;             const float4 gp = *reinterpret_cast<const float4*>(gpost + col);
;             xv[i].x += gt.x * (yv[i].x * rstd * gp.x); xv[i].y += gt.y * (yv[i].y * rstd * gp.y);
;             xv[i].z += gt.z * (yv[i].z * rstd * gp.z); xv[i].w += gt.w * (yv[i].w * rstd * gp.w);
;           }
;         }
;         if (xdst == 3 || (xdst == 1 && row >= N_X)) {
;           float* xout = (xdst == 3) ? P.out + (long)row * 1024 : P.xc + (long)(row - N_X) * 1024;
; #pragma unroll
;           for (int i = 0; i < 4; ++i) *reinterpret_cast<float4*>(xout + (i * 64 + lane) * 4) = xv[i];
;         } else if (xdst != 0) {
;           u16* xo = ((xdst == 1) ? resA : P.zf) + (long)row * 1024;
; #pragma unroll
;           for (int i = 0; i < 4; ++i) {
;             const unsigned b0 = f2bf(xv[i].x), b1 = f2bf(xv[i].y), b2 = f2bf(xv[i].z), b3 = f2bf(xv[i].w);
;             *reinterpret_cast<uint2*>(xo + (i * 64 + lane) * 4) = make_uint2(b0 | (b1 << 16), b2 | (b3 << 16));
;           }
;         }
;         if (doH) {
;           float ss = 0.f;
; #pragma unroll
;           for (int i = 0; i < 4; ++i) ss += xv[i].x * xv[i].x + xv[i].y * xv[i].y + xv[i].z * xv[i].z + xv[i].w * xv[i].w;
;           ss = wave_sum(ss);
;           const float rstd = __builtin_amdgcn_rsqf(ss * (1.f / 1024.f) + EPSF);
;           u16* h = P.hy + (long)row * 1024;
; #pragma unroll
	v_add_f32_dpp v138, v138, v138 quad_perm:[2,3,0,1] row_mask:0xf bank_mask:0xf
	s_nop 1
	v_add_f32_dpp v138, v138, v138 row_half_mirror row_mask:0xf bank_mask:0xf
	s_nop 1
	v_add_f32_dpp v138, v138, v138 row_mirror row_mask:0xf bank_mask:0xf
	v_mov_b32_e32 v139, v138
	s_nop 1
	v_permlane16_swap_b32_e32 v138, v139
	v_add_f32_e32 v138, v138, v139
	v_mov_b32_e32 v139, v138
	s_nop 1
	v_permlane32_swap_b32_e32 v138, v139
	v_add_f32_e32 v138, v138, v139
	v_mul_f32_e32 v138, 0x3a800000, v138
	v_add_f32_e32 v138, 0x358637bd, v138
	v_rsq_f32_e32 v140, v138
	s_nop 0
	v_mul_f32_e32 v120, v120, v140
	v_mul_f32_e32 v121, v121, v140
	v_mul_f32_e32 v122, v122, v140
	v_mul_f32_e32 v123, v123, v140
	v_mul_f32_e32 v124, v124, v140
	v_mul_f32_e32 v125, v125, v140
	v_mul_f32_e32 v126, v126, v140
	v_mul_f32_e32 v127, v127, v140
	v_mul_f32_e32 v128, v128, v140
	v_mul_f32_e32 v129, v129, v140
	v_mul_f32_e32 v130, v130, v140
	v_mul_f32_e32 v131, v131, v140
	v_mul_f32_e32 v132, v132, v140
	v_mul_f32_e32 v133, v133, v140
	v_mul_f32_e32 v134, v134, v140
	v_mul_f32_e32 v135, v135, v140
	v_fma_f32 v32, v120, v72, v32
	v_fma_f32 v33, v121, v73, v33
	v_fma_f32 v34, v122, v74, v34
	v_fma_f32 v35, v123, v75, v35
	v_fma_f32 v36, v124, v76, v36
	v_fma_f32 v37, v125, v77, v37
	v_fma_f32 v38, v126, v78, v38
	v_fma_f32 v39, v127, v79, v39
	v_fma_f32 v40, v128, v80, v40
	v_fma_f32 v41, v129, v81, v41
	v_fma_f32 v42, v130, v82, v42
	v_fma_f32 v43, v131, v83, v43
	v_fma_f32 v44, v132, v84, v44
	v_fma_f32 v45, v133, v85, v45
	v_fma_f32 v46, v134, v86, v46
	v_fma_f32 v47, v135, v87, v47
	v_cvt_pk_bf16_f32 v156, v32, v33
	v_cvt_pk_bf16_f32 v157, v34, v35
	v_cvt_pk_bf16_f32 v158, v36, v37
	v_cvt_pk_bf16_f32 v159, v38, v39
	v_cvt_pk_bf16_f32 v160, v40, v41
	v_cvt_pk_bf16_f32 v161, v42, v43
	v_cvt_pk_bf16_f32 v162, v44, v45
	v_cvt_pk_bf16_f32 v163, v46, v47
	s_lshl_b32 vcc_lo, s19, 11
	s_add_u32 vcc_lo, vcc_lo, 0x1400000
	s_add_u32 s100, s16, vcc_lo
	s_addc_u32 s101, s17, 0
	global_store_dwordx2 v137, v[156:157], s[100:101] offset:0
	global_store_dwordx2 v137, v[158:159], s[100:101] offset:512
	global_store_dwordx2 v137, v[160:161], s[100:101] offset:1024
	global_store_dwordx2 v137, v[162:163], s[100:101] offset:1536
	v_mul_f32_e32 v138, v32, v32
	v_mul_f32_e32 v149, v33, v33
	v_mul_f32_e32 v150, v34, v34
	v_mul_f32_e32 v154, v35, v35
	v_fma_f32 v138, v36, v36, v138
	v_fma_f32 v149, v37, v37, v149
	v_fma_f32 v150, v38, v38, v150
	v_fma_f32 v154, v39, v39, v154
	v_fma_f32 v138, v40, v40, v138
	v_fma_f32 v149, v41, v41, v149
	v_fma_f32 v150, v42, v42, v150
	v_fma_f32 v154, v43, v43, v154
	v_fma_f32 v138, v44, v44, v138
	v_fma_f32 v149, v45, v45, v149
	v_fma_f32 v150, v46, v46, v150
	v_fma_f32 v154, v47, v47, v154
	v_add_f32_e32 v138, v138, v149
	v_add_f32_e32 v150, v150, v154
	v_add_f32_e32 v138, v138, v150
	s_nop 1
	v_add_f32_dpp v138, v138, v138 quad_perm:[1,0,3,2] row_mask:0xf bank_mask:0xf
	s_nop 1
	v_add_f32_dpp v138, v138, v138 quad_perm:[2,3,0,1] row_mask:0xf bank_mask:0xf
	s_nop 1
	v_add_f32_dpp v138, v138, v138 row_half_mirror row_mask:0xf bank_mask:0xf
	s_nop 1
	v_add_f32_dpp v138, v138, v138 row_mirror row_mask:0xf bank_mask:0xf
	v_mov_b32_e32 v139, v138
	s_nop 1
	v_permlane16_swap_b32_e32 v138, v139
	v_add_f32_e32 v138, v138, v139
	v_mov_b32_e32 v139, v138
	s_nop 1
	v_permlane32_swap_b32_e32 v138, v139
	v_add_f32_e32 v138, v138, v139
	v_mul_f32_e32 v138, 0x3a800000, v138
	v_add_f32_e32 v138, 0x358637bd, v138
	v_rsq_f32_e32 v140, v138
	s_nop 0
	v_mul_f32_e32 v120, v32, v140
	v_mul_f32_e32 v121, v33, v140
	v_mul_f32_e32 v122, v34, v140
	v_mul_f32_e32 v123, v35, v140
	v_mul_f32_e32 v124, v36, v140
	v_mul_f32_e32 v125, v37, v140
	v_mul_f32_e32 v126, v38, v140
	v_mul_f32_e32 v127, v39, v140
	v_mul_f32_e32 v128, v40, v140
	v_mul_f32_e32 v129, v41, v140
	v_mul_f32_e32 v130, v42, v140
	v_mul_f32_e32 v131, v43, v140
	v_mul_f32_e32 v132, v44, v140
	v_mul_f32_e32 v133, v45, v140
	v_mul_f32_e32 v134, v46, v140
	v_mul_f32_e32 v135, v47, v140
	v_fma_f32 v120, v120, v88, v104
	v_fma_f32 v121, v121, v89, v105
	v_fma_f32 v122, v122, v90, v106
	v_fma_f32 v123, v123, v91, v107
	v_fma_f32 v124, v124, v92, v108
	v_fma_f32 v125, v125, v93, v109
	v_fma_f32 v126, v126, v94, v110
	v_fma_f32 v127, v127, v95, v111
	v_fma_f32 v128, v128, v96, v112
	v_fma_f32 v129, v129, v97, v113
	v_fma_f32 v130, v130, v98, v114
	v_fma_f32 v131, v131, v99, v115
	v_fma_f32 v132, v132, v100, v116
	v_fma_f32 v133, v133, v101, v117
	v_fma_f32 v134, v134, v102, v118
	v_fma_f32 v135, v135, v103, v119
	v_cvt_pk_bf16_f32 v156, v120, v121
	v_cvt_pk_bf16_f32 v157, v122, v123
	v_cvt_pk_bf16_f32 v158, v124, v125
	v_cvt_pk_bf16_f32 v159, v126, v127
	v_cvt_pk_bf16_f32 v160, v128, v129
	v_cvt_pk_bf16_f32 v161, v130, v131
	v_cvt_pk_bf16_f32 v162, v132, v133
	v_cvt_pk_bf16_f32 v163, v134, v135
	s_lshl_b32 vcc_lo, s19, 11
	s_add_u32 vcc_lo, vcc_lo, 0x1400000
	s_add_u32 s100, s14, vcc_lo
	s_addc_u32 s101, s15, 0
	global_store_dwordx2 v137, v[156:157], s[100:101] offset:0
	global_store_dwordx2 v137, v[158:159], s[100:101] offset:512
	global_store_dwordx2 v137, v[160:161], s[100:101] offset:1024
	global_store_dwordx2 v137, v[162:163], s[100:101] offset:1536
	s_lshl_b32 vcc_lo, s19, 12
	s_add_u32 vcc_lo, vcc_lo, 0x4000000
	s_add_u32 s100, s12, vcc_lo
	s_addc_u32 s101, s13, 0
	global_load_dwordx4 v[32:35], v136, s[100:101] offset:0
	global_load_dwordx4 v[36:39], v136, s[100:101] offset:1024
	global_load_dwordx4 v[40:43], v136, s[100:101] offset:2048
	global_load_dwordx4 v[44:47], v136, s[100:101] offset:3072
	s_lshl_b32 vcc_lo, s19, 11
	s_add_u32 vcc_lo, vcc_lo, 0x2000000
	s_add_u32 s100, s14, vcc_lo
	s_addc_u32 s101, s15, 0
	global_load_dwordx2 v[64:65], v137, s[100:101] offset:0
	global_load_dwordx2 v[66:67], v137, s[100:101] offset:512
	global_load_dwordx2 v[68:69], v137, s[100:101] offset:1024
	global_load_dwordx2 v[70:71], v137, s[100:101] offset:1536
	s_waitcnt vmcnt(32)
; __device__ __forceinline__ void row_phase(const Params& P, int glayer, int layer, int xsrc, bool hasY, int gate_idx, const float* gpost,
;                           int xdst, bool doH, const float* gpre, int sh_idx, int nrows) {
;     ...
;         if (hasY) {
;           float4 yv[4];
;           float ss = 0.f;
; #pragma unroll
;           for (int i = 0; i < 4; ++i) {
;             const uint2 raw = yy[u][i];
;             yv[i].x = bf2f((u16)(raw.x & 0xffff)); yv[i].y = bf2f((u16)(raw.x >> 16));
;             yv[i].z = bf2f((u16)(raw.y & 0xffff)); yv[i].w = bf2f((u16)(raw.y >> 16));
;             ss += yv[i].x * yv[i].x + yv[i].y * yv[i].y + yv[i].z * yv[i].z + yv[i].w * yv[i].w;
;           }
;           ss = wave_sum(ss);
;           const float rstd = __builtin_amdgcn_rsqf(ss * (1.f / 1024.f) + EPSF);
; #pragma unroll
;           for (int i = 0; i < 4; ++i) {
;             const int col = (i * 64 + lane) * 4;
;             const float4 gt = *reinterpret_cast<const float4*>(modg + gate_idx * 1024 + col);
;             const float4 gp = *reinterpret_cast<const float4*>(gpost + col);
;             xv[i].x += gt.x * (yv[i].x * rstd * gp.x); xv[i].y += gt.y * (yv[i].y * rstd * gp.y);
;             xv[i].z += gt.z * (yv[i].z * rstd * gp.z); xv[i].w += gt.w * (yv[i].w * rstd * gp.w);
;           }
;         }
;         if (xdst == 3 || (xdst == 1 && row >= N_X)) {
;           float* xout = (xdst == 3) ? P.out + (long)row * 1024 : P.xc + (long)(row - N_X) * 1024;
; #pragma unroll
;           for (int i = 0; i < 4; ++i) *reinterpret_cast<float4*>(xout + (i * 64 + lane) * 4) = xv[i];
;         } else if (xdst != 0) {
;           u16* xo = ((xdst == 1) ? resA : P.zf) + (long)row * 1024;
; #pragma unroll
;           for (int i = 0; i < 4; ++i) {
;             const unsigned b0 = f2bf(xv[i].x), b1 = f2bf(xv[i].y), b2 = f2bf(xv[i].z), b3 = f2bf(xv[i].w);
;             *reinterpret_cast<uint2*>(xo + (i * 64 + lane) * 4) = make_uint2(b0 | (b1 << 16), b2 | (b3 << 16));
;           }
;         }
;         if (doH) {
;           float ss = 0.f;
; #pragma unroll
;           for (int i = 0; i < 4; ++i) ss += xv[i].x * xv[i].x + xv[i].y * xv[i].y + xv[i].z * xv[i].z + xv[i].w * xv[i].w;
;           ss = wave_sum(ss);
;           const float rstd = __builtin_amdgcn_rsqf(ss * (1.f / 1024.f) + EPSF);
;           u16* h = P.hy + (long)row * 1024;
; #pragma unroll
	v_lshlrev_b32_e32 v120, 16, v48
	v_and_b32_e32 v121, 0xffff0000, v48
	v_lshlrev_b32_e32 v122, 16, v49
	v_and_b32_e32 v123, 0xffff0000, v49
	v_lshlrev_b32_e32 v124, 16, v50
	v_and_b32_e32 v125, 0xffff0000, v50
	v_lshlrev_b32_e32 v126, 16, v51
	v_and_b32_e32 v127, 0xffff0000, v51
	v_lshlrev_b32_e32 v128, 16, v52
	v_and_b32_e32 v129, 0xffff0000, v52
	v_lshlrev_b32_e32 v130, 16, v53
	v_and_b32_e32 v131, 0xffff0000, v53
	v_lshlrev_b32_e32 v132, 16, v54
	v_and_b32_e32 v133, 0xffff0000, v54
	v_lshlrev_b32_e32 v134, 16, v55
	v_and_b32_e32 v135, 0xffff0000, v55
	v_mul_f32_e32 v138, v120, v120
	v_mul_f32_e32 v149, v121, v121
	v_mul_f32_e32 v150, v122, v122
	v_mul_f32_e32 v154, v123, v123
	v_fma_f32 v138, v124, v124, v138
	v_fma_f32 v149, v125, v125, v149
	v_fma_f32 v150, v126, v126, v150
	v_fma_f32 v154, v127, v127, v154
	v_fma_f32 v138, v128, v128, v138
	v_fma_f32 v149, v129, v129, v149
	v_fma_f32 v150, v130, v130, v150
	v_fma_f32 v154, v131, v131, v154
	v_fma_f32 v138, v132, v132, v138
	v_fma_f32 v149, v133, v133, v149
	v_fma_f32 v150, v134, v134, v150
	v_fma_f32 v154, v135, v135, v154
	v_add_f32_e32 v138, v138, v149
	v_add_f32_e32 v150, v150, v154
	v_add_f32_e32 v138, v138, v150
	s_nop 1
	v_add_f32_dpp v138, v138, v138 quad_perm:[1,0,3,2] row_mask:0xf bank_mask:0xf
	s_nop 1
	v_add_f32_dpp v138, v138, v138 quad_perm:[2,3,0,1] row_mask:0xf bank_mask:0xf
	s_nop 1
	v_add_f32_dpp v138, v138, v138 row_half_mirror row_mask:0xf bank_mask:0xf
	s_nop 1
	v_add_f32_dpp v138, v138, v138 row_mirror row_mask:0xf bank_mask:0xf
	v_mov_b32_e32 v139, v138
	s_nop 1
	v_permlane16_swap_b32_e32 v138, v139
	v_add_f32_e32 v138, v138, v139
	v_mov_b32_e32 v139, v138
	s_nop 1
	v_permlane32_swap_b32_e32 v138, v139
	v_add_f32_e32 v138, v138, v139
	v_mul_f32_e32 v138, 0x3a800000, v138
	v_add_f32_e32 v138, 0x358637bd, v138
	v_rsq_f32_e32 v140, v138
	s_nop 0
	v_mul_f32_e32 v120, v120, v140
	v_mul_f32_e32 v121, v121, v140
	v_mul_f32_e32 v122, v122, v140
	v_mul_f32_e32 v123, v123, v140
	v_mul_f32_e32 v124, v124, v140
	v_mul_f32_e32 v125, v125, v140
	v_mul_f32_e32 v126, v126, v140
	v_mul_f32_e32 v127, v127, v140
	v_mul_f32_e32 v128, v128, v140
	v_mul_f32_e32 v129, v129, v140
	v_mul_f32_e32 v130, v130, v140
	v_mul_f32_e32 v131, v131, v140
	v_mul_f32_e32 v132, v132, v140
	v_mul_f32_e32 v133, v133, v140
	v_mul_f32_e32 v134, v134, v140
	v_mul_f32_e32 v135, v135, v140
	v_fma_f32 v0, v120, v72, v0
	v_fma_f32 v1, v121, v73, v1
	v_fma_f32 v2, v122, v74, v2
	v_fma_f32 v3, v123, v75, v3
	v_fma_f32 v4, v124, v76, v4
	v_fma_f32 v5, v125, v77, v5
	v_fma_f32 v6, v126, v78, v6
	v_fma_f32 v7, v127, v79, v7
	v_fma_f32 v8, v128, v80, v8
	v_fma_f32 v9, v129, v81, v9
	v_fma_f32 v10, v130, v82, v10
	v_fma_f32 v11, v131, v83, v11
	v_fma_f32 v12, v132, v84, v12
	v_fma_f32 v13, v133, v85, v13
	v_fma_f32 v14, v134, v86, v14
	v_fma_f32 v15, v135, v87, v15
	v_cvt_pk_bf16_f32 v156, v0, v1
	v_cvt_pk_bf16_f32 v157, v2, v3
	v_cvt_pk_bf16_f32 v158, v4, v5
	v_cvt_pk_bf16_f32 v159, v6, v7
	v_cvt_pk_bf16_f32 v160, v8, v9
	v_cvt_pk_bf16_f32 v161, v10, v11
	v_cvt_pk_bf16_f32 v162, v12, v13
	v_cvt_pk_bf16_f32 v163, v14, v15
	s_lshl_b32 vcc_lo, s19, 11
	s_add_u32 vcc_lo, vcc_lo, 0x1800000
	s_add_u32 s100, s16, vcc_lo
	s_addc_u32 s101, s17, 0
	global_store_dwordx2 v137, v[156:157], s[100:101] offset:0
	global_store_dwordx2 v137, v[158:159], s[100:101] offset:512
	global_store_dwordx2 v137, v[160:161], s[100:101] offset:1024
	global_store_dwordx2 v137, v[162:163], s[100:101] offset:1536
	v_mul_f32_e32 v138, v0, v0
	v_mul_f32_e32 v149, v1, v1
	v_mul_f32_e32 v150, v2, v2
	v_mul_f32_e32 v154, v3, v3
	v_fma_f32 v138, v4, v4, v138
	v_fma_f32 v149, v5, v5, v149
	v_fma_f32 v150, v6, v6, v150
	v_fma_f32 v154, v7, v7, v154
	v_fma_f32 v138, v8, v8, v138
	v_fma_f32 v149, v9, v9, v149
	v_fma_f32 v150, v10, v10, v150
	v_fma_f32 v154, v11, v11, v154
	v_fma_f32 v138, v12, v12, v138
	v_fma_f32 v149, v13, v13, v149
	v_fma_f32 v150, v14, v14, v150
	v_fma_f32 v154, v15, v15, v154
	v_add_f32_e32 v138, v138, v149
	v_add_f32_e32 v150, v150, v154
	v_add_f32_e32 v138, v138, v150
	s_nop 1
	v_add_f32_dpp v138, v138, v138 quad_perm:[1,0,3,2] row_mask:0xf bank_mask:0xf
	s_nop 1
	v_add_f32_dpp v138, v138, v138 quad_perm:[2,3,0,1] row_mask:0xf bank_mask:0xf
	s_nop 1
	v_add_f32_dpp v138, v138, v138 row_half_mirror row_mask:0xf bank_mask:0xf
	s_nop 1
	v_add_f32_dpp v138, v138, v138 row_mirror row_mask:0xf bank_mask:0xf
	v_mov_b32_e32 v139, v138
	s_nop 1
	v_permlane16_swap_b32_e32 v138, v139
	v_add_f32_e32 v138, v138, v139
	v_mov_b32_e32 v139, v138
	s_nop 1
	v_permlane32_swap_b32_e32 v138, v139
	v_add_f32_e32 v138, v138, v139
	v_mul_f32_e32 v138, 0x3a800000, v138
	v_add_f32_e32 v138, 0x358637bd, v138
	v_rsq_f32_e32 v140, v138
	s_nop 0
	v_mul_f32_e32 v120, v0, v140
	v_mul_f32_e32 v121, v1, v140
	v_mul_f32_e32 v122, v2, v140
	v_mul_f32_e32 v123, v3, v140
	v_mul_f32_e32 v124, v4, v140
	v_mul_f32_e32 v125, v5, v140
	v_mul_f32_e32 v126, v6, v140
	v_mul_f32_e32 v127, v7, v140
	v_mul_f32_e32 v128, v8, v140
	v_mul_f32_e32 v129, v9, v140
	v_mul_f32_e32 v130, v10, v140
	v_mul_f32_e32 v131, v11, v140
	v_mul_f32_e32 v132, v12, v140
	v_mul_f32_e32 v133, v13, v140
	v_mul_f32_e32 v134, v14, v140
	v_mul_f32_e32 v135, v15, v140
	v_fma_f32 v120, v120, v88, v104
	v_fma_f32 v121, v121, v89, v105
	v_fma_f32 v122, v122, v90, v106
	v_fma_f32 v123, v123, v91, v107
	v_fma_f32 v124, v124, v92, v108
	v_fma_f32 v125, v125, v93, v109
	v_fma_f32 v126, v126, v94, v110
	v_fma_f32 v127, v127, v95, v111
	v_fma_f32 v128, v128, v96, v112
	v_fma_f32 v129, v129, v97, v113
	v_fma_f32 v130, v130, v98, v114
	v_fma_f32 v131, v131, v99, v115
	v_fma_f32 v132, v132, v100, v116
; __device__ __forceinline__ void row_phase(const Params& P, int glayer, int layer, int xsrc, bool hasY, int gate_idx, const float* gpost,
;                           int xdst, bool doH, const float* gpre, int sh_idx, int nrows) {
;     ...
;         if (hasY) {
;           float4 yv[4];
;           float ss = 0.f;
; #pragma unroll
;           for (int i = 0; i < 4; ++i) {
;             const uint2 raw = yy[u][i];
;             yv[i].x = bf2f((u16)(raw.x & 0xffff)); yv[i].y = bf2f((u16)(raw.x >> 16));
;             yv[i].z = bf2f((u16)(raw.y & 0xffff)); yv[i].w = bf2f((u16)(raw.y >> 16));
;             ss += yv[i].x * yv[i].x + yv[i].y * yv[i].y + yv[i].z * yv[i].z + yv[i].w * yv[i].w;
;           }
;           ss = wave_sum(ss);
;           const float rstd = __builtin_amdgcn_rsqf(ss * (1.f / 1024.f) + EPSF);
; #pragma unroll
;           for (int i = 0; i < 4; ++i) {
;             const int col = (i * 64 + lane) * 4;
;             const float4 gt = *reinterpret_cast<const float4*>(modg + gate_idx * 1024 + col);
;             const float4 gp = *reinterpret_cast<const float4*>(gpost + col);
;             xv[i].x += gt.x * (yv[i].x * rstd * gp.x); xv[i].y += gt.y * (yv[i].y * rstd * gp.y);
;             xv[i].z += gt.z * (yv[i].z * rstd * gp.z); xv[i].w += gt.w * (yv[i].w * rstd * gp.w);
;           }
;         }
;         if (xdst == 3 || (xdst == 1 && row >= N_X)) {
;           float* xout = (xdst == 3) ? P.out + (long)row * 1024 : P.xc + (long)(row - N_X) * 1024;
; #pragma unroll
;           for (int i = 0; i < 4; ++i) *reinterpret_cast<float4*>(xout + (i * 64 + lane) * 4) = xv[i];
;         } else if (xdst != 0) {
;           u16* xo = ((xdst == 1) ? resA : P.zf) + (long)row * 1024;
; #pragma unroll
;           for (int i = 0; i < 4; ++i) {
;             const unsigned b0 = f2bf(xv[i].x), b1 = f2bf(xv[i].y), b2 = f2bf(xv[i].z), b3 = f2bf(xv[i].w);
;             *reinterpret_cast<uint2*>(xo + (i * 64 + lane) * 4) = make_uint2(b0 | (b1 << 16), b2 | (b3 << 16));
;           }
;         }
;         if (doH) {
;           float ss = 0.f;
; #pragma unroll
;           for (int i = 0; i < 4; ++i) ss += xv[i].x * xv[i].x + xv[i].y * xv[i].y + xv[i].z * xv[i].z + xv[i].w * xv[i].w;
;           ss = wave_sum(ss);
;           const float rstd = __builtin_amdgcn_rsqf(ss * (1.f / 1024.f) + EPSF);
;           u16* h = P.hy + (long)row * 1024;
; #pragma unroll
	v_fma_f32 v133, v133, v101, v117
	v_fma_f32 v134, v134, v102, v118
	v_fma_f32 v135, v135, v103, v119
	v_cvt_pk_bf16_f32 v156, v120, v121
	v_cvt_pk_bf16_f32 v157, v122, v123
	v_cvt_pk_bf16_f32 v158, v124, v125
	v_cvt_pk_bf16_f32 v159, v126, v127
	v_cvt_pk_bf16_f32 v160, v128, v129
	v_cvt_pk_bf16_f32 v161, v130, v131
	v_cvt_pk_bf16_f32 v162, v132, v133
	v_cvt_pk_bf16_f32 v163, v134, v135
	s_lshl_b32 vcc_lo, s19, 11
	s_add_u32 vcc_lo, vcc_lo, 0x1800000
	s_add_u32 s100, s14, vcc_lo
	s_addc_u32 s101, s15, 0
	global_store_dwordx2 v137, v[156:157], s[100:101] offset:0
	global_store_dwordx2 v137, v[158:159], s[100:101] offset:512
	global_store_dwordx2 v137, v[160:161], s[100:101] offset:1024
	global_store_dwordx2 v137, v[162:163], s[100:101] offset:1536
	s_lshl_b32 vcc_lo, s19, 12
	s_add_u32 vcc_lo, vcc_lo, 0x4800000
	s_add_u32 s100, s12, vcc_lo
	s_addc_u32 s101, s13, 0
	global_load_dwordx4 v[0:3], v136, s[100:101] offset:0
	global_load_dwordx4 v[4:7], v136, s[100:101] offset:1024
	global_load_dwordx4 v[8:11], v136, s[100:101] offset:2048
	global_load_dwordx4 v[12:15], v136, s[100:101] offset:3072
	s_lshl_b32 vcc_lo, s19, 11
	s_add_u32 vcc_lo, vcc_lo, 0x2400000
	s_add_u32 s100, s14, vcc_lo
	s_addc_u32 s101, s15, 0
	global_load_dwordx2 v[48:49], v137, s[100:101] offset:0
	global_load_dwordx2 v[50:51], v137, s[100:101] offset:512
	global_load_dwordx2 v[52:53], v137, s[100:101] offset:1024
	global_load_dwordx2 v[54:55], v137, s[100:101] offset:1536
	s_waitcnt vmcnt(32)
	v_lshlrev_b32_e32 v120, 16, v56
	v_and_b32_e32 v121, 0xffff0000, v56
	v_lshlrev_b32_e32 v122, 16, v57
	v_and_b32_e32 v123, 0xffff0000, v57
	v_lshlrev_b32_e32 v124, 16, v58
	v_and_b32_e32 v125, 0xffff0000, v58
	v_lshlrev_b32_e32 v126, 16, v59
	v_and_b32_e32 v127, 0xffff0000, v59
	v_lshlrev_b32_e32 v128, 16, v60
	v_and_b32_e32 v129, 0xffff0000, v60
	v_lshlrev_b32_e32 v130, 16, v61
	v_and_b32_e32 v131, 0xffff0000, v61
	v_lshlrev_b32_e32 v132, 16, v62
	v_and_b32_e32 v133, 0xffff0000, v62
	v_lshlrev_b32_e32 v134, 16, v63
	v_and_b32_e32 v135, 0xffff0000, v63
	v_mul_f32_e32 v138, v120, v120
	v_mul_f32_e32 v149, v121, v121
	v_mul_f32_e32 v150, v122, v122
	v_mul_f32_e32 v154, v123, v123
	v_fma_f32 v138, v124, v124, v138
	v_fma_f32 v149, v125, v125, v149
	v_fma_f32 v150, v126, v126, v150
	v_fma_f32 v154, v127, v127, v154
	v_fma_f32 v138, v128, v128, v138
	v_fma_f32 v149, v129, v129, v149
	v_fma_f32 v150, v130, v130, v150
	v_fma_f32 v154, v131, v131, v154
	v_fma_f32 v138, v132, v132, v138
	v_fma_f32 v149, v133, v133, v149
	v_fma_f32 v150, v134, v134, v150
	v_fma_f32 v154, v135, v135, v154
	v_add_f32_e32 v138, v138, v149
	v_add_f32_e32 v150, v150, v154
	v_add_f32_e32 v138, v138, v150
	s_nop 1
	v_add_f32_dpp v138, v138, v138 quad_perm:[1,0,3,2] row_mask:0xf bank_mask:0xf
	s_nop 1
	v_add_f32_dpp v138, v138, v138 quad_perm:[2,3,0,1] row_mask:0xf bank_mask:0xf
	s_nop 1
	v_add_f32_dpp v138, v138, v138 row_half_mirror row_mask:0xf bank_mask:0xf
	s_nop 1
	v_add_f32_dpp v138, v138, v138 row_mirror row_mask:0xf bank_mask:0xf
	v_mov_b32_e32 v139, v138
	s_nop 1
	v_permlane16_swap_b32_e32 v138, v139
	v_add_f32_e32 v138, v138, v139
	v_mov_b32_e32 v139, v138
	s_nop 1
	v_permlane32_swap_b32_e32 v138, v139
	v_add_f32_e32 v138, v138, v139
	v_mul_f32_e32 v138, 0x3a800000, v138
	v_add_f32_e32 v138, 0x358637bd, v138
	v_rsq_f32_e32 v140, v138
	s_nop 0
	v_mul_f32_e32 v120, v120, v140
	v_mul_f32_e32 v121, v121, v140
	v_mul_f32_e32 v122, v122, v140
	v_mul_f32_e32 v123, v123, v140
	v_mul_f32_e32 v124, v124, v140
	v_mul_f32_e32 v125, v125, v140
	v_mul_f32_e32 v126, v126, v140
	v_mul_f32_e32 v127, v127, v140
	v_mul_f32_e32 v128, v128, v140
	v_mul_f32_e32 v129, v129, v140
	v_mul_f32_e32 v130, v130, v140
	v_mul_f32_e32 v131, v131, v140
	v_mul_f32_e32 v132, v132, v140
	v_mul_f32_e32 v133, v133, v140
	v_mul_f32_e32 v134, v134, v140
	v_mul_f32_e32 v135, v135, v140
	v_fma_f32 v16, v120, v72, v16
	v_fma_f32 v17, v121, v73, v17
	v_fma_f32 v18, v122, v74, v18
	v_fma_f32 v19, v123, v75, v19
	v_fma_f32 v20, v124, v76, v20
	v_fma_f32 v21, v125, v77, v21
	v_fma_f32 v22, v126, v78, v22
	v_fma_f32 v23, v127, v79, v23
	v_fma_f32 v24, v128, v80, v24
	v_fma_f32 v25, v129, v81, v25
	v_fma_f32 v26, v130, v82, v26
	v_fma_f32 v27, v131, v83, v27
	v_fma_f32 v28, v132, v84, v28
	v_fma_f32 v29, v133, v85, v29
	v_fma_f32 v30, v134, v86, v30
	v_fma_f32 v31, v135, v87, v31
	v_cvt_pk_bf16_f32 v156, v16, v17
	v_cvt_pk_bf16_f32 v157, v18, v19
	v_cvt_pk_bf16_f32 v158, v20, v21
	v_cvt_pk_bf16_f32 v159, v22, v23
	v_cvt_pk_bf16_f32 v160, v24, v25
	v_cvt_pk_bf16_f32 v161, v26, v27
	v_cvt_pk_bf16_f32 v162, v28, v29
	v_cvt_pk_bf16_f32 v163, v30, v31
	s_lshl_b32 vcc_lo, s19, 11
	s_add_u32 vcc_lo, vcc_lo, 0x1c00000
	s_add_u32 s100, s16, vcc_lo
	s_addc_u32 s101, s17, 0
	global_store_dwordx2 v137, v[156:157], s[100:101] offset:0
	global_store_dwordx2 v137, v[158:159], s[100:101] offset:512
	global_store_dwordx2 v137, v[160:161], s[100:101] offset:1024
	global_store_dwordx2 v137, v[162:163], s[100:101] offset:1536
	v_mul_f32_e32 v138, v16, v16
	v_mul_f32_e32 v149, v17, v17
	v_mul_f32_e32 v150, v18, v18
	v_mul_f32_e32 v154, v19, v19
	v_fma_f32 v138, v20, v20, v138
	v_fma_f32 v149, v21, v21, v149
	v_fma_f32 v150, v22, v22, v150
	v_fma_f32 v154, v23, v23, v154
	v_fma_f32 v138, v24, v24, v138
	v_fma_f32 v149, v25, v25, v149
	v_fma_f32 v150, v26, v26, v150
	v_fma_f32 v154, v27, v27, v154
	v_fma_f32 v138, v28, v28, v138
	v_fma_f32 v149, v29, v29, v149
	v_fma_f32 v150, v30, v30, v150
	v_fma_f32 v154, v31, v31, v154
	v_add_f32_e32 v138, v138, v149
	v_add_f32_e32 v150, v150, v154
	v_add_f32_e32 v138, v138, v150
	s_nop 1
	v_add_f32_dpp v138, v138, v138 quad_perm:[1,0,3,2] row_mask:0xf bank_mask:0xf
; __device__ __forceinline__ void row_phase(const Params& P, int glayer, int layer, int xsrc, bool hasY, int gate_idx, const float* gpost,
;                           int xdst, bool doH, const float* gpre, int sh_idx, int nrows) {
;     ...
;         if (hasY) {
;           float4 yv[4];
;           float ss = 0.f;
; #pragma unroll
;           for (int i = 0; i < 4; ++i) {
;             const uint2 raw = yy[u][i];
;             yv[i].x = bf2f((u16)(raw.x & 0xffff)); yv[i].y = bf2f((u16)(raw.x >> 16));
;             yv[i].z = bf2f((u16)(raw.y & 0xffff)); yv[i].w = bf2f((u16)(raw.y >> 16));
;             ss += yv[i].x * yv[i].x + yv[i].y * yv[i].y + yv[i].z * yv[i].z + yv[i].w * yv[i].w;
;           }
;           ss = wave_sum(ss);
;           const float rstd = __builtin_amdgcn_rsqf(ss * (1.f / 1024.f) + EPSF);
; #pragma unroll
;           for (int i = 0; i < 4; ++i) {
;             const int col = (i * 64 + lane) * 4;
;             const float4 gt = *reinterpret_cast<const float4*>(modg + gate_idx * 1024 + col);
;             const float4 gp = *reinterpret_cast<const float4*>(gpost + col);
;             xv[i].x += gt.x * (yv[i].x * rstd * gp.x); xv[i].y += gt.y * (yv[i].y * rstd * gp.y);
;             xv[i].z += gt.z * (yv[i].z * rstd * gp.z); xv[i].w += gt.w * (yv[i].w * rstd * gp.w);
;           }
;         }
;         if (xdst == 3 || (xdst == 1 && row >= N_X)) {
;           float* xout = (xdst == 3) ? P.out + (long)row * 1024 : P.xc + (long)(row - N_X) * 1024;
; #pragma unroll
;           for (int i = 0; i < 4; ++i) *reinterpret_cast<float4*>(xout + (i * 64 + lane) * 4) = xv[i];
;         } else if (xdst != 0) {
;           u16* xo = ((xdst == 1) ? resA : P.zf) + (long)row * 1024;
; #pragma unroll
;           for (int i = 0; i < 4; ++i) {
;             const unsigned b0 = f2bf(xv[i].x), b1 = f2bf(xv[i].y), b2 = f2bf(xv[i].z), b3 = f2bf(xv[i].w);
;             *reinterpret_cast<uint2*>(xo + (i * 64 + lane) * 4) = make_uint2(b0 | (b1 << 16), b2 | (b3 << 16));
;           }
;         }
;         if (doH) {
;           float ss = 0.f;
; #pragma unroll
;           for (int i = 0; i < 4; ++i) ss += xv[i].x * xv[i].x + xv[i].y * xv[i].y + xv[i].z * xv[i].z + xv[i].w * xv[i].w;
;           ss = wave_sum(ss);
;           const float rstd = __builtin_amdgcn_rsqf(ss * (1.f / 1024.f) + EPSF);
;           u16* h = P.hy + (long)row * 1024;
; #pragma unroll
	s_nop 1
	v_add_f32_dpp v138, v138, v138 quad_perm:[2,3,0,1] row_mask:0xf bank_mask:0xf
	s_nop 1
	v_add_f32_dpp v138, v138, v138 row_half_mirror row_mask:0xf bank_mask:0xf
	s_nop 1
	v_add_f32_dpp v138, v138, v138 row_mirror row_mask:0xf bank_mask:0xf
	v_mov_b32_e32 v139, v138
	s_nop 1
	v_permlane16_swap_b32_e32 v138, v139
	v_add_f32_e32 v138, v138, v139
	v_mov_b32_e32 v139, v138
	s_nop 1
	v_permlane32_swap_b32_e32 v138, v139
	v_add_f32_e32 v138, v138, v139
	v_mul_f32_e32 v138, 0x3a800000, v138
	v_add_f32_e32 v138, 0x358637bd, v138
	v_rsq_f32_e32 v140, v138
	s_nop 0
	v_mul_f32_e32 v120, v16, v140
	v_mul_f32_e32 v121, v17, v140
	v_mul_f32_e32 v122, v18, v140
	v_mul_f32_e32 v123, v19, v140
	v_mul_f32_e32 v124, v20, v140
	v_mul_f32_e32 v125, v21, v140
	v_mul_f32_e32 v126, v22, v140
	v_mul_f32_e32 v127, v23, v140
	v_mul_f32_e32 v128, v24, v140
	v_mul_f32_e32 v129, v25, v140
	v_mul_f32_e32 v130, v26, v140
	v_mul_f32_e32 v131, v27, v140
	v_mul_f32_e32 v132, v28, v140
	v_mul_f32_e32 v133, v29, v140
	v_mul_f32_e32 v134, v30, v140
	v_mul_f32_e32 v135, v31, v140
	v_fma_f32 v120, v120, v88, v104
	v_fma_f32 v121, v121, v89, v105
	v_fma_f32 v122, v122, v90, v106
	v_fma_f32 v123, v123, v91, v107
	v_fma_f32 v124, v124, v92, v108
	v_fma_f32 v125, v125, v93, v109
	v_fma_f32 v126, v126, v94, v110
	v_fma_f32 v127, v127, v95, v111
	v_fma_f32 v128, v128, v96, v112
	v_fma_f32 v129, v129, v97, v113
	v_fma_f32 v130, v130, v98, v114
	v_fma_f32 v131, v131, v99, v115
	v_fma_f32 v132, v132, v100, v116
	v_fma_f32 v133, v133, v101, v117
	v_fma_f32 v134, v134, v102, v118
	v_fma_f32 v135, v135, v103, v119
	v_cvt_pk_bf16_f32 v156, v120, v121
	v_cvt_pk_bf16_f32 v157, v122, v123
	v_cvt_pk_bf16_f32 v158, v124, v125
	v_cvt_pk_bf16_f32 v159, v126, v127
	v_cvt_pk_bf16_f32 v160, v128, v129
	v_cvt_pk_bf16_f32 v161, v130, v131
	v_cvt_pk_bf16_f32 v162, v132, v133
	v_cvt_pk_bf16_f32 v163, v134, v135
	s_lshl_b32 vcc_lo, s19, 11
	s_add_u32 vcc_lo, vcc_lo, 0x1c00000
	s_add_u32 s100, s14, vcc_lo
	s_addc_u32 s101, s15, 0
	global_store_dwordx2 v137, v[156:157], s[100:101] offset:0
	global_store_dwordx2 v137, v[158:159], s[100:101] offset:512
	global_store_dwordx2 v137, v[160:161], s[100:101] offset:1024
	global_store_dwordx2 v137, v[162:163], s[100:101] offset:1536
	s_add_u32 s100, s20, 0xe000
	s_addc_u32 s101, s21, 0
	global_load_dwordx4 v[72:75], v136, s[100:101] offset:0
	global_load_dwordx4 v[76:79], v136, s[100:101] offset:1024
	global_load_dwordx4 v[80:83], v136, s[100:101] offset:2048
	global_load_dwordx4 v[84:87], v136, s[100:101] offset:3072
	s_load_dwordx2 s[98:99], s[4:5], 0x38
	s_waitcnt lgkmcnt(0)
	global_load_dwordx4 v[120:123], v136, s[98:99] offset:0
	global_load_dwordx4 v[124:127], v136, s[98:99] offset:1024
	global_load_dwordx4 v[128:131], v136, s[98:99] offset:2048
	global_load_dwordx4 v[132:135], v136, s[98:99] offset:3072
	s_add_u32 s100, s20, 0xf000
	s_addc_u32 s101, s21, 0
	global_load_dwordx4 v[104:107], v136, s[100:101] offset:0
	global_load_dwordx4 v[108:111], v136, s[100:101] offset:1024
	global_load_dwordx4 v[112:115], v136, s[100:101] offset:2048
	global_load_dwordx4 v[116:119], v136, s[100:101] offset:3072
	s_add_u32 s100, s100, 0x1000
	s_addc_u32 s101, s101, 0
	global_load_dwordx4 v[16:19], v136, s[100:101] offset:0
	global_load_dwordx4 v[20:23], v136, s[100:101] offset:1024
	global_load_dwordx4 v[24:27], v136, s[100:101] offset:2048
	global_load_dwordx4 v[28:31], v136, s[100:101] offset:3072
	s_load_dwordx2 s[98:99], s[4:5], 0x40
	s_waitcnt lgkmcnt(0)
	global_load_dwordx4 v[88:91], v136, s[98:99] offset:0
	global_load_dwordx4 v[92:95], v136, s[98:99] offset:1024
	global_load_dwordx4 v[96:99], v136, s[98:99] offset:2048
	global_load_dwordx4 v[100:103], v136, s[98:99] offset:3072
	s_waitcnt vmcnt(0)
	v_mul_f32_e32 v72, v72, v120
	v_mul_f32_e32 v73, v73, v121
	v_mul_f32_e32 v74, v74, v122
	v_mul_f32_e32 v75, v75, v123
	v_mul_f32_e32 v76, v76, v124
	v_mul_f32_e32 v77, v77, v125
	v_mul_f32_e32 v78, v78, v126
	v_mul_f32_e32 v79, v79, v127
	v_mul_f32_e32 v80, v80, v128
	v_mul_f32_e32 v81, v81, v129
	v_mul_f32_e32 v82, v82, v130
	v_mul_f32_e32 v83, v83, v131
	v_mul_f32_e32 v84, v84, v132
	v_mul_f32_e32 v85, v85, v133
	v_mul_f32_e32 v86, v86, v134
	v_mul_f32_e32 v87, v87, v135
	v_fma_f32 v88, v88, v16, v88
	v_fma_f32 v89, v89, v17, v89
	v_fma_f32 v90, v90, v18, v90
	v_fma_f32 v91, v91, v19, v91
	v_fma_f32 v92, v92, v20, v92
	v_fma_f32 v93, v93, v21, v93
	v_fma_f32 v94, v94, v22, v94
	v_fma_f32 v95, v95, v23, v95
	v_fma_f32 v96, v96, v24, v96
	v_fma_f32 v97, v97, v25, v97
	v_fma_f32 v98, v98, v26, v98
	v_fma_f32 v99, v99, v27, v99
	v_fma_f32 v100, v100, v28, v100
	v_fma_f32 v101, v101, v29, v101
	v_fma_f32 v102, v102, v30, v102
	v_fma_f32 v103, v103, v31, v103
	s_lshl_b32 vcc_lo, s19, 12
	s_add_u32 vcc_lo, vcc_lo, 0x5000000
	s_add_u32 s100, s12, vcc_lo
	s_addc_u32 s101, s13, 0
	global_load_dwordx4 v[16:19], v136, s[100:101] offset:0
	global_load_dwordx4 v[20:23], v136, s[100:101] offset:1024
	global_load_dwordx4 v[24:27], v136, s[100:101] offset:2048
	global_load_dwordx4 v[28:31], v136, s[100:101] offset:3072
	s_lshl_b32 vcc_lo, s19, 11
	s_add_u32 vcc_lo, vcc_lo, 0x2800000
	s_add_u32 s100, s14, vcc_lo
	s_addc_u32 s101, s15, 0
	global_load_dwordx2 v[56:57], v137, s[100:101] offset:0
	global_load_dwordx2 v[58:59], v137, s[100:101] offset:512
	global_load_dwordx2 v[60:61], v137, s[100:101] offset:1024
	global_load_dwordx2 v[62:63], v137, s[100:101] offset:1536
	v_lshlrev_b32_e32 v120, 16, v64
	v_and_b32_e32 v121, 0xffff0000, v64
	v_lshlrev_b32_e32 v122, 16, v65
	v_and_b32_e32 v123, 0xffff0000, v65
	v_lshlrev_b32_e32 v124, 16, v66
	v_and_b32_e32 v125, 0xffff0000, v66
; __device__ __forceinline__ void row_phase(const Params& P, int glayer, int layer, int xsrc, bool hasY, int gate_idx, const float* gpost,
;                           int xdst, bool doH, const float* gpre, int sh_idx, int nrows) {
;     ...
;         if (hasY) {
;           float4 yv[4];
;           float ss = 0.f;
; #pragma unroll
;           for (int i = 0; i < 4; ++i) {
;             const uint2 raw = yy[u][i];
;             yv[i].x = bf2f((u16)(raw.x & 0xffff)); yv[i].y = bf2f((u16)(raw.x >> 16));
;             yv[i].z = bf2f((u16)(raw.y & 0xffff)); yv[i].w = bf2f((u16)(raw.y >> 16));
;             ss += yv[i].x * yv[i].x + yv[i].y * yv[i].y + yv[i].z * yv[i].z + yv[i].w * yv[i].w;
;           }
;           ss = wave_sum(ss);
;           const float rstd = __builtin_amdgcn_rsqf(ss * (1.f / 1024.f) + EPSF);
; #pragma unroll
;           for (int i = 0; i < 4; ++i) {
;             const int col = (i * 64 + lane) * 4;
;             const float4 gt = *reinterpret_cast<const float4*>(modg + gate_idx * 1024 + col);
;             const float4 gp = *reinterpret_cast<const float4*>(gpost + col);
;             xv[i].x += gt.x * (yv[i].x * rstd * gp.x); xv[i].y += gt.y * (yv[i].y * rstd * gp.y);
;             xv[i].z += gt.z * (yv[i].z * rstd * gp.z); xv[i].w += gt.w * (yv[i].w * rstd * gp.w);
;           }
;         }
;         if (xdst == 3 || (xdst == 1 && row >= N_X)) {
;           float* xout = (xdst == 3) ? P.out + (long)row * 1024 : P.xc + (long)(row - N_X) * 1024;
; #pragma unroll
;           for (int i = 0; i < 4; ++i) *reinterpret_cast<float4*>(xout + (i * 64 + lane) * 4) = xv[i];
;         } else if (xdst != 0) {
;           u16* xo = ((xdst == 1) ? resA : P.zf) + (long)row * 1024;
; #pragma unroll
;           for (int i = 0; i < 4; ++i) {
;             const unsigned b0 = f2bf(xv[i].x), b1 = f2bf(xv[i].y), b2 = f2bf(xv[i].z), b3 = f2bf(xv[i].w);
;             *reinterpret_cast<uint2*>(xo + (i * 64 + lane) * 4) = make_uint2(b0 | (b1 << 16), b2 | (b3 << 16));
;           }
;         }
;         if (doH) {
;           float ss = 0.f;
; #pragma unroll
;           for (int i = 0; i < 4; ++i) ss += xv[i].x * xv[i].x + xv[i].y * xv[i].y + xv[i].z * xv[i].z + xv[i].w * xv[i].w;
;           ss = wave_sum(ss);
;           const float rstd = __builtin_amdgcn_rsqf(ss * (1.f / 1024.f) + EPSF);
;           u16* h = P.hy + (long)row * 1024;
; #pragma unroll
	v_lshlrev_b32_e32 v126, 16, v67
	v_and_b32_e32 v127, 0xffff0000, v67
	v_lshlrev_b32_e32 v128, 16, v68
	v_and_b32_e32 v129, 0xffff0000, v68
	v_lshlrev_b32_e32 v130, 16, v69
	v_and_b32_e32 v131, 0xffff0000, v69
	v_lshlrev_b32_e32 v132, 16, v70
	v_and_b32_e32 v133, 0xffff0000, v70
	v_lshlrev_b32_e32 v134, 16, v71
	v_and_b32_e32 v135, 0xffff0000, v71
	v_mul_f32_e32 v138, v120, v120
	v_mul_f32_e32 v149, v121, v121
	v_mul_f32_e32 v150, v122, v122
	v_mul_f32_e32 v154, v123, v123
	v_fma_f32 v138, v124, v124, v138
	v_fma_f32 v149, v125, v125, v149
	v_fma_f32 v150, v126, v126, v150
	v_fma_f32 v154, v127, v127, v154
	v_fma_f32 v138, v128, v128, v138
	v_fma_f32 v149, v129, v129, v149
	v_fma_f32 v150, v130, v130, v150
	v_fma_f32 v154, v131, v131, v154
	v_fma_f32 v138, v132, v132, v138
	v_fma_f32 v149, v133, v133, v149
	v_fma_f32 v150, v134, v134, v150
	v_fma_f32 v154, v135, v135, v154
	v_add_f32_e32 v138, v138, v149
	v_add_f32_e32 v150, v150, v154
	v_add_f32_e32 v138, v138, v150
	s_nop 1
	v_add_f32_dpp v138, v138, v138 quad_perm:[1,0,3,2] row_mask:0xf bank_mask:0xf
	s_nop 1
	v_add_f32_dpp v138, v138, v138 quad_perm:[2,3,0,1] row_mask:0xf bank_mask:0xf
	s_nop 1
	v_add_f32_dpp v138, v138, v138 row_half_mirror row_mask:0xf bank_mask:0xf
	s_nop 1
	v_add_f32_dpp v138, v138, v138 row_mirror row_mask:0xf bank_mask:0xf
	v_mov_b32_e32 v139, v138
	s_nop 1
	v_permlane16_swap_b32_e32 v138, v139
	v_add_f32_e32 v138, v138, v139
	v_mov_b32_e32 v139, v138
	s_nop 1
	v_permlane32_swap_b32_e32 v138, v139
	v_add_f32_e32 v138, v138, v139
	v_mul_f32_e32 v138, 0x3a800000, v138
	v_add_f32_e32 v138, 0x358637bd, v138
	v_rsq_f32_e32 v140, v138
	s_nop 0
	v_mul_f32_e32 v120, v120, v140
	v_mul_f32_e32 v121, v121, v140
	v_mul_f32_e32 v122, v122, v140
	v_mul_f32_e32 v123, v123, v140
	v_mul_f32_e32 v124, v124, v140
	v_mul_f32_e32 v125, v125, v140
	v_mul_f32_e32 v126, v126, v140
	v_mul_f32_e32 v127, v127, v140
	v_mul_f32_e32 v128, v128, v140
	v_mul_f32_e32 v129, v129, v140
	v_mul_f32_e32 v130, v130, v140
	v_mul_f32_e32 v131, v131, v140
	v_mul_f32_e32 v132, v132, v140
	v_mul_f32_e32 v133, v133, v140
	v_mul_f32_e32 v134, v134, v140
	v_mul_f32_e32 v135, v135, v140
	v_fma_f32 v32, v120, v72, v32
	v_fma_f32 v33, v121, v73, v33
	v_fma_f32 v34, v122, v74, v34
	v_fma_f32 v35, v123, v75, v35
	v_fma_f32 v36, v124, v76, v36
	v_fma_f32 v37, v125, v77, v37
	v_fma_f32 v38, v126, v78, v38
	v_fma_f32 v39, v127, v79, v39
	v_fma_f32 v40, v128, v80, v40
	v_fma_f32 v41, v129, v81, v41
	v_fma_f32 v42, v130, v82, v42
	v_fma_f32 v43, v131, v83, v43
	v_fma_f32 v44, v132, v84, v44
	v_fma_f32 v45, v133, v85, v45
	v_fma_f32 v46, v134, v86, v46
	v_fma_f32 v47, v135, v87, v47
	v_cvt_pk_bf16_f32 v156, v32, v33
	v_cvt_pk_bf16_f32 v157, v34, v35
	v_cvt_pk_bf16_f32 v158, v36, v37
	v_cvt_pk_bf16_f32 v159, v38, v39
	v_cvt_pk_bf16_f32 v160, v40, v41
	v_cvt_pk_bf16_f32 v161, v42, v43
	v_cvt_pk_bf16_f32 v162, v44, v45
	v_cvt_pk_bf16_f32 v163, v46, v47
	s_lshl_b32 vcc_lo, s19, 11
	s_add_u32 vcc_lo, vcc_lo, 0x2000000
	s_add_u32 s100, s16, vcc_lo
	s_addc_u32 s101, s17, 0
	global_store_dwordx2 v137, v[156:157], s[100:101] offset:0
	global_store_dwordx2 v137, v[158:159], s[100:101] offset:512
	global_store_dwordx2 v137, v[160:161], s[100:101] offset:1024
	global_store_dwordx2 v137, v[162:163], s[100:101] offset:1536
	v_mul_f32_e32 v138, v32, v32
	v_mul_f32_e32 v149, v33, v33
	v_mul_f32_e32 v150, v34, v34
	v_mul_f32_e32 v154, v35, v35
	v_fma_f32 v138, v36, v36, v138
	v_fma_f32 v149, v37, v37, v149
	v_fma_f32 v150, v38, v38, v150
	v_fma_f32 v154, v39, v39, v154
	v_fma_f32 v138, v40, v40, v138
	v_fma_f32 v149, v41, v41, v149
	v_fma_f32 v150, v42, v42, v150
	v_fma_f32 v154, v43, v43, v154
	v_fma_f32 v138, v44, v44, v138
	v_fma_f32 v149, v45, v45, v149
	v_fma_f32 v150, v46, v46, v150
	v_fma_f32 v154, v47, v47, v154
	v_add_f32_e32 v138, v138, v149
	v_add_f32_e32 v150, v150, v154
	v_add_f32_e32 v138, v138, v150
	s_nop 1
	v_add_f32_dpp v138, v138, v138 quad_perm:[1,0,3,2] row_mask:0xf bank_mask:0xf
	s_nop 1
	v_add_f32_dpp v138, v138, v138 quad_perm:[2,3,0,1] row_mask:0xf bank_mask:0xf
	s_nop 1
	v_add_f32_dpp v138, v138, v138 row_half_mirror row_mask:0xf bank_mask:0xf
	s_nop 1
	v_add_f32_dpp v138, v138, v138 row_mirror row_mask:0xf bank_mask:0xf
	v_mov_b32_e32 v139, v138
	s_nop 1
	v_permlane16_swap_b32_e32 v138, v139
	v_add_f32_e32 v138, v138, v139
	v_mov_b32_e32 v139, v138
	s_nop 1
	v_permlane32_swap_b32_e32 v138, v139
	v_add_f32_e32 v138, v138, v139
	v_mul_f32_e32 v138, 0x3a800000, v138
	v_add_f32_e32 v138, 0x358637bd, v138
	v_rsq_f32_e32 v140, v138
	s_nop 0
	v_mul_f32_e32 v120, v32, v140
	v_mul_f32_e32 v121, v33, v140
	v_mul_f32_e32 v122, v34, v140
	v_mul_f32_e32 v123, v35, v140
	v_mul_f32_e32 v124, v36, v140
	v_mul_f32_e32 v125, v37, v140
	v_mul_f32_e32 v126, v38, v140
	v_mul_f32_e32 v127, v39, v140
	v_mul_f32_e32 v128, v40, v140
	v_mul_f32_e32 v129, v41, v140
	v_mul_f32_e32 v130, v42, v140
	v_mul_f32_e32 v131, v43, v140
	v_mul_f32_e32 v132, v44, v140
	v_mul_f32_e32 v133, v45, v140
	v_mul_f32_e32 v134, v46, v140
	v_mul_f32_e32 v135, v47, v140
	v_fma_f32 v120, v120, v88, v104
	v_fma_f32 v121, v121, v89, v105
	v_fma_f32 v122, v122, v90, v106
	v_fma_f32 v123, v123, v91, v107
	v_fma_f32 v124, v124, v92, v108
	v_fma_f32 v125, v125, v93, v109
	v_fma_f32 v126, v126, v94, v110
	v_fma_f32 v127, v127, v95, v111
	v_fma_f32 v128, v128, v96, v112
	v_fma_f32 v129, v129, v97, v113
	v_fma_f32 v130, v130, v98, v114
	v_fma_f32 v131, v131, v99, v115
	v_fma_f32 v132, v132, v100, v116
	v_fma_f32 v133, v133, v101, v117
	v_fma_f32 v134, v134, v102, v118
	v_fma_f32 v135, v135, v103, v119
	v_cvt_pk_bf16_f32 v156, v120, v121
	v_cvt_pk_bf16_f32 v157, v122, v123
; __device__ __forceinline__ void row_phase(const Params& P, int glayer, int layer, int xsrc, bool hasY, int gate_idx, const float* gpost,
;                           int xdst, bool doH, const float* gpre, int sh_idx, int nrows) {
;     ...
;         if (hasY) {
;           float4 yv[4];
;           float ss = 0.f;
; #pragma unroll
;           for (int i = 0; i < 4; ++i) {
;             const uint2 raw = yy[u][i];
;             yv[i].x = bf2f((u16)(raw.x & 0xffff)); yv[i].y = bf2f((u16)(raw.x >> 16));
;             yv[i].z = bf2f((u16)(raw.y & 0xffff)); yv[i].w = bf2f((u16)(raw.y >> 16));
;             ss += yv[i].x * yv[i].x + yv[i].y * yv[i].y + yv[i].z * yv[i].z + yv[i].w * yv[i].w;
;           }
;           ss = wave_sum(ss);
;           const float rstd = __builtin_amdgcn_rsqf(ss * (1.f / 1024.f) + EPSF);
; #pragma unroll
;           for (int i = 0; i < 4; ++i) {
;             const int col = (i * 64 + lane) * 4;
;             const float4 gt = *reinterpret_cast<const float4*>(modg + gate_idx * 1024 + col);
;             const float4 gp = *reinterpret_cast<const float4*>(gpost + col);
;             xv[i].x += gt.x * (yv[i].x * rstd * gp.x); xv[i].y += gt.y * (yv[i].y * rstd * gp.y);
;             xv[i].z += gt.z * (yv[i].z * rstd * gp.z); xv[i].w += gt.w * (yv[i].w * rstd * gp.w);
;           }
;         }
;         if (xdst == 3 || (xdst == 1 && row >= N_X)) {
;           float* xout = (xdst == 3) ? P.out + (long)row * 1024 : P.xc + (long)(row - N_X) * 1024;
; #pragma unroll
;           for (int i = 0; i < 4; ++i) *reinterpret_cast<float4*>(xout + (i * 64 + lane) * 4) = xv[i];
;         } else if (xdst != 0) {
;           u16* xo = ((xdst == 1) ? resA : P.zf) + (long)row * 1024;
; #pragma unroll
;           for (int i = 0; i < 4; ++i) {
;             const unsigned b0 = f2bf(xv[i].x), b1 = f2bf(xv[i].y), b2 = f2bf(xv[i].z), b3 = f2bf(xv[i].w);
;             *reinterpret_cast<uint2*>(xo + (i * 64 + lane) * 4) = make_uint2(b0 | (b1 << 16), b2 | (b3 << 16));
;           }
;         }
;         if (doH) {
;           float ss = 0.f;
; #pragma unroll
;           for (int i = 0; i < 4; ++i) ss += xv[i].x * xv[i].x + xv[i].y * xv[i].y + xv[i].z * xv[i].z + xv[i].w * xv[i].w;
;           ss = wave_sum(ss);
;           const float rstd = __builtin_amdgcn_rsqf(ss * (1.f / 1024.f) + EPSF);
;           u16* h = P.hy + (long)row * 1024;
; #pragma unroll
	v_cvt_pk_bf16_f32 v158, v124, v125
	v_cvt_pk_bf16_f32 v159, v126, v127
	v_cvt_pk_bf16_f32 v160, v128, v129
	v_cvt_pk_bf16_f32 v161, v130, v131
	v_cvt_pk_bf16_f32 v162, v132, v133
	v_cvt_pk_bf16_f32 v163, v134, v135
	s_lshl_b32 vcc_lo, s19, 11
	s_add_u32 vcc_lo, vcc_lo, 0x2000000
	s_add_u32 s100, s14, vcc_lo
	s_addc_u32 s101, s15, 0
	global_store_dwordx2 v137, v[156:157], s[100:101] offset:0
	global_store_dwordx2 v137, v[158:159], s[100:101] offset:512
	global_store_dwordx2 v137, v[160:161], s[100:101] offset:1024
	global_store_dwordx2 v137, v[162:163], s[100:101] offset:1536
	s_lshl_b32 vcc_lo, s19, 12
	s_add_u32 vcc_lo, vcc_lo, 0x5800000
	s_add_u32 s100, s12, vcc_lo
	s_addc_u32 s101, s13, 0
	global_load_dwordx4 v[32:35], v136, s[100:101] offset:0
	global_load_dwordx4 v[36:39], v136, s[100:101] offset:1024
	global_load_dwordx4 v[40:43], v136, s[100:101] offset:2048
	global_load_dwordx4 v[44:47], v136, s[100:101] offset:3072
	s_lshl_b32 vcc_lo, s19, 11
	s_add_u32 vcc_lo, vcc_lo, 0x2c00000
	s_add_u32 s100, s14, vcc_lo
	s_addc_u32 s101, s15, 0
	global_load_dwordx2 v[64:65], v137, s[100:101] offset:0
	global_load_dwordx2 v[66:67], v137, s[100:101] offset:512
	global_load_dwordx2 v[68:69], v137, s[100:101] offset:1024
	global_load_dwordx2 v[70:71], v137, s[100:101] offset:1536
	v_lshlrev_b32_e32 v120, 16, v48
	v_and_b32_e32 v121, 0xffff0000, v48
	v_lshlrev_b32_e32 v122, 16, v49
	v_and_b32_e32 v123, 0xffff0000, v49
	v_lshlrev_b32_e32 v124, 16, v50
	v_and_b32_e32 v125, 0xffff0000, v50
	v_lshlrev_b32_e32 v126, 16, v51
	v_and_b32_e32 v127, 0xffff0000, v51
	v_lshlrev_b32_e32 v128, 16, v52
	v_and_b32_e32 v129, 0xffff0000, v52
	v_lshlrev_b32_e32 v130, 16, v53
	v_and_b32_e32 v131, 0xffff0000, v53
	v_lshlrev_b32_e32 v132, 16, v54
	v_and_b32_e32 v133, 0xffff0000, v54
	v_lshlrev_b32_e32 v134, 16, v55
	v_and_b32_e32 v135, 0xffff0000, v55
	v_mul_f32_e32 v138, v120, v120
	v_mul_f32_e32 v149, v121, v121
	v_mul_f32_e32 v150, v122, v122
	v_mul_f32_e32 v154, v123, v123
	v_fma_f32 v138, v124, v124, v138
	v_fma_f32 v149, v125, v125, v149
	v_fma_f32 v150, v126, v126, v150
	v_fma_f32 v154, v127, v127, v154
	v_fma_f32 v138, v128, v128, v138
	v_fma_f32 v149, v129, v129, v149
	v_fma_f32 v150, v130, v130, v150
	v_fma_f32 v154, v131, v131, v154
	v_fma_f32 v138, v132, v132, v138
	v_fma_f32 v149, v133, v133, v149
	v_fma_f32 v150, v134, v134, v150
	v_fma_f32 v154, v135, v135, v154
	v_add_f32_e32 v138, v138, v149
	v_add_f32_e32 v150, v150, v154
	v_add_f32_e32 v138, v138, v150
	s_nop 1
	v_add_f32_dpp v138, v138, v138 quad_perm:[1,0,3,2] row_mask:0xf bank_mask:0xf
	s_nop 1
	v_add_f32_dpp v138, v138, v138 quad_perm:[2,3,0,1] row_mask:0xf bank_mask:0xf
	s_nop 1
	v_add_f32_dpp v138, v138, v138 row_half_mirror row_mask:0xf bank_mask:0xf
	s_nop 1
	v_add_f32_dpp v138, v138, v138 row_mirror row_mask:0xf bank_mask:0xf
	v_mov_b32_e32 v139, v138
	s_nop 1
	v_permlane16_swap_b32_e32 v138, v139
	v_add_f32_e32 v138, v138, v139
	v_mov_b32_e32 v139, v138
	s_nop 1
	v_permlane32_swap_b32_e32 v138, v139
	v_add_f32_e32 v138, v138, v139
	v_mul_f32_e32 v138, 0x3a800000, v138
	v_add_f32_e32 v138, 0x358637bd, v138
	v_rsq_f32_e32 v140, v138
	s_nop 0
	v_mul_f32_e32 v120, v120, v140
	v_mul_f32_e32 v121, v121, v140
	v_mul_f32_e32 v122, v122, v140
	v_mul_f32_e32 v123, v123, v140
	v_mul_f32_e32 v124, v124, v140
	v_mul_f32_e32 v125, v125, v140
	v_mul_f32_e32 v126, v126, v140
	v_mul_f32_e32 v127, v127, v140
	v_mul_f32_e32 v128, v128, v140
	v_mul_f32_e32 v129, v129, v140
	v_mul_f32_e32 v130, v130, v140
	v_mul_f32_e32 v131, v131, v140
	v_mul_f32_e32 v132, v132, v140
	v_mul_f32_e32 v133, v133, v140
	v_mul_f32_e32 v134, v134, v140
	v_mul_f32_e32 v135, v135, v140
	v_fma_f32 v0, v120, v72, v0
	v_fma_f32 v1, v121, v73, v1
	v_fma_f32 v2, v122, v74, v2
	v_fma_f32 v3, v123, v75, v3
	v_fma_f32 v4, v124, v76, v4
	v_fma_f32 v5, v125, v77, v5
	v_fma_f32 v6, v126, v78, v6
	v_fma_f32 v7, v127, v79, v7
	v_fma_f32 v8, v128, v80, v8
	v_fma_f32 v9, v129, v81, v9
	v_fma_f32 v10, v130, v82, v10
	v_fma_f32 v11, v131, v83, v11
	v_fma_f32 v12, v132, v84, v12
	v_fma_f32 v13, v133, v85, v13
	v_fma_f32 v14, v134, v86, v14
	v_fma_f32 v15, v135, v87, v15
	v_cvt_pk_bf16_f32 v156, v0, v1
	v_cvt_pk_bf16_f32 v157, v2, v3
	v_cvt_pk_bf16_f32 v158, v4, v5
	v_cvt_pk_bf16_f32 v159, v6, v7
	v_cvt_pk_bf16_f32 v160, v8, v9
	v_cvt_pk_bf16_f32 v161, v10, v11
	v_cvt_pk_bf16_f32 v162, v12, v13
	v_cvt_pk_bf16_f32 v163, v14, v15
	s_lshl_b32 vcc_lo, s19, 11
	s_add_u32 vcc_lo, vcc_lo, 0x2400000
	s_add_u32 s100, s16, vcc_lo
	s_addc_u32 s101, s17, 0
	global_store_dwordx2 v137, v[156:157], s[100:101] offset:0
	global_store_dwordx2 v137, v[158:159], s[100:101] offset:512
	global_store_dwordx2 v137, v[160:161], s[100:101] offset:1024
	global_store_dwordx2 v137, v[162:163], s[100:101] offset:1536
	v_mul_f32_e32 v138, v0, v0
	v_mul_f32_e32 v149, v1, v1
	v_mul_f32_e32 v150, v2, v2
	v_mul_f32_e32 v154, v3, v3
	v_fma_f32 v138, v4, v4, v138
	v_fma_f32 v149, v5, v5, v149
	v_fma_f32 v150, v6, v6, v150
	v_fma_f32 v154, v7, v7, v154
	v_fma_f32 v138, v8, v8, v138
	v_fma_f32 v149, v9, v9, v149
	v_fma_f32 v150, v10, v10, v150
	v_fma_f32 v154, v11, v11, v154
	v_fma_f32 v138, v12, v12, v138
	v_fma_f32 v149, v13, v13, v149
	v_fma_f32 v150, v14, v14, v150
	v_fma_f32 v154, v15, v15, v154
	v_add_f32_e32 v138, v138, v149
	v_add_f32_e32 v150, v150, v154
	v_add_f32_e32 v138, v138, v150
	s_nop 1
	v_add_f32_dpp v138, v138, v138 quad_perm:[1,0,3,2] row_mask:0xf bank_mask:0xf
	s_nop 1
	v_add_f32_dpp v138, v138, v138 quad_perm:[2,3,0,1] row_mask:0xf bank_mask:0xf
	s_nop 1
	v_add_f32_dpp v138, v138, v138 row_half_mirror row_mask:0xf bank_mask:0xf
	s_nop 1
; __device__ __forceinline__ void row_phase(const Params& P, int glayer, int layer, int xsrc, bool hasY, int gate_idx, const float* gpost,
;                           int xdst, bool doH, const float* gpre, int sh_idx, int nrows) {
;     ...
;         if (hasY) {
;           float4 yv[4];
;           float ss = 0.f;
; #pragma unroll
;           for (int i = 0; i < 4; ++i) {
;             const uint2 raw = yy[u][i];
;             yv[i].x = bf2f((u16)(raw.x & 0xffff)); yv[i].y = bf2f((u16)(raw.x >> 16));
;             yv[i].z = bf2f((u16)(raw.y & 0xffff)); yv[i].w = bf2f((u16)(raw.y >> 16));
;             ss += yv[i].x * yv[i].x + yv[i].y * yv[i].y + yv[i].z * yv[i].z + yv[i].w * yv[i].w;
;           }
;           ss = wave_sum(ss);
;           const float rstd = __builtin_amdgcn_rsqf(ss * (1.f / 1024.f) + EPSF);
; #pragma unroll
;           for (int i = 0; i < 4; ++i) {
;             const int col = (i * 64 + lane) * 4;
;             const float4 gt = *reinterpret_cast<const float4*>(modg + gate_idx * 1024 + col);
;             const float4 gp = *reinterpret_cast<const float4*>(gpost + col);
;             xv[i].x += gt.x * (yv[i].x * rstd * gp.x); xv[i].y += gt.y * (yv[i].y * rstd * gp.y);
;             xv[i].z += gt.z * (yv[i].z * rstd * gp.z); xv[i].w += gt.w * (yv[i].w * rstd * gp.w);
;           }
;         }
;         if (xdst == 3 || (xdst == 1 && row >= N_X)) {
;           float* xout = (xdst == 3) ? P.out + (long)row * 1024 : P.xc + (long)(row - N_X) * 1024;
; #pragma unroll
;           for (int i = 0; i < 4; ++i) *reinterpret_cast<float4*>(xout + (i * 64 + lane) * 4) = xv[i];
;         } else if (xdst != 0) {
;           u16* xo = ((xdst == 1) ? resA : P.zf) + (long)row * 1024;
; #pragma unroll
;           for (int i = 0; i < 4; ++i) {
;             const unsigned b0 = f2bf(xv[i].x), b1 = f2bf(xv[i].y), b2 = f2bf(xv[i].z), b3 = f2bf(xv[i].w);
;             *reinterpret_cast<uint2*>(xo + (i * 64 + lane) * 4) = make_uint2(b0 | (b1 << 16), b2 | (b3 << 16));
;           }
;         }
;         if (doH) {
;           float ss = 0.f;
; #pragma unroll
;           for (int i = 0; i < 4; ++i) ss += xv[i].x * xv[i].x + xv[i].y * xv[i].y + xv[i].z * xv[i].z + xv[i].w * xv[i].w;
;           ss = wave_sum(ss);
;           const float rstd = __builtin_amdgcn_rsqf(ss * (1.f / 1024.f) + EPSF);
;           u16* h = P.hy + (long)row * 1024;
; #pragma unroll
	v_add_f32_dpp v138, v138, v138 row_mirror row_mask:0xf bank_mask:0xf
	v_mov_b32_e32 v139, v138
	s_nop 1
	v_permlane16_swap_b32_e32 v138, v139
	v_add_f32_e32 v138, v138, v139
	v_mov_b32_e32 v139, v138
	s_nop 1
	v_permlane32_swap_b32_e32 v138, v139
	v_add_f32_e32 v138, v138, v139
	v_mul_f32_e32 v138, 0x3a800000, v138
	v_add_f32_e32 v138, 0x358637bd, v138
	v_rsq_f32_e32 v140, v138
	s_nop 0
	v_mul_f32_e32 v120, v0, v140
	v_mul_f32_e32 v121, v1, v140
	v_mul_f32_e32 v122, v2, v140
	v_mul_f32_e32 v123, v3, v140
	v_mul_f32_e32 v124, v4, v140
	v_mul_f32_e32 v125, v5, v140
	v_mul_f32_e32 v126, v6, v140
	v_mul_f32_e32 v127, v7, v140
	v_mul_f32_e32 v128, v8, v140
	v_mul_f32_e32 v129, v9, v140
	v_mul_f32_e32 v130, v10, v140
	v_mul_f32_e32 v131, v11, v140
	v_mul_f32_e32 v132, v12, v140
	v_mul_f32_e32 v133, v13, v140
	v_mul_f32_e32 v134, v14, v140
	v_mul_f32_e32 v135, v15, v140
	v_fma_f32 v120, v120, v88, v104
	v_fma_f32 v121, v121, v89, v105
	v_fma_f32 v122, v122, v90, v106
	v_fma_f32 v123, v123, v91, v107
	v_fma_f32 v124, v124, v92, v108
	v_fma_f32 v125, v125, v93, v109
	v_fma_f32 v126, v126, v94, v110
	v_fma_f32 v127, v127, v95, v111
	v_fma_f32 v128, v128, v96, v112
	v_fma_f32 v129, v129, v97, v113
	v_fma_f32 v130, v130, v98, v114
	v_fma_f32 v131, v131, v99, v115
	v_fma_f32 v132, v132, v100, v116
	v_fma_f32 v133, v133, v101, v117
	v_fma_f32 v134, v134, v102, v118
	v_fma_f32 v135, v135, v103, v119
	v_cvt_pk_bf16_f32 v156, v120, v121
	v_cvt_pk_bf16_f32 v157, v122, v123
	v_cvt_pk_bf16_f32 v158, v124, v125
	v_cvt_pk_bf16_f32 v159, v126, v127
	v_cvt_pk_bf16_f32 v160, v128, v129
	v_cvt_pk_bf16_f32 v161, v130, v131
	v_cvt_pk_bf16_f32 v162, v132, v133
	v_cvt_pk_bf16_f32 v163, v134, v135
	s_lshl_b32 vcc_lo, s19, 11
	s_add_u32 vcc_lo, vcc_lo, 0x2400000
	s_add_u32 s100, s14, vcc_lo
	s_addc_u32 s101, s15, 0
	global_store_dwordx2 v137, v[156:157], s[100:101] offset:0
	global_store_dwordx2 v137, v[158:159], s[100:101] offset:512
	global_store_dwordx2 v137, v[160:161], s[100:101] offset:1024
	global_store_dwordx2 v137, v[162:163], s[100:101] offset:1536
	s_lshl_b32 vcc_lo, s19, 12
	s_add_u32 vcc_lo, vcc_lo, 0x6000000
	s_add_u32 s100, s12, vcc_lo
	s_addc_u32 s101, s13, 0
	global_load_dwordx4 v[0:3], v136, s[100:101] offset:0
	global_load_dwordx4 v[4:7], v136, s[100:101] offset:1024
	global_load_dwordx4 v[8:11], v136, s[100:101] offset:2048
	global_load_dwordx4 v[12:15], v136, s[100:101] offset:3072
	s_lshl_b32 vcc_lo, s19, 11
	s_add_u32 vcc_lo, vcc_lo, 0x3000000
	s_add_u32 s100, s14, vcc_lo
	s_addc_u32 s101, s15, 0
	global_load_dwordx2 v[48:49], v137, s[100:101] offset:0
	global_load_dwordx2 v[50:51], v137, s[100:101] offset:512
	global_load_dwordx2 v[52:53], v137, s[100:101] offset:1024
	global_load_dwordx2 v[54:55], v137, s[100:101] offset:1536
	s_waitcnt vmcnt(32)
	v_lshlrev_b32_e32 v120, 16, v56
	v_and_b32_e32 v121, 0xffff0000, v56
	v_lshlrev_b32_e32 v122, 16, v57
	v_and_b32_e32 v123, 0xffff0000, v57
	v_lshlrev_b32_e32 v124, 16, v58
	v_and_b32_e32 v125, 0xffff0000, v58
	v_lshlrev_b32_e32 v126, 16, v59
	v_and_b32_e32 v127, 0xffff0000, v59
	v_lshlrev_b32_e32 v128, 16, v60
	v_and_b32_e32 v129, 0xffff0000, v60
	v_lshlrev_b32_e32 v130, 16, v61
	v_and_b32_e32 v131, 0xffff0000, v61
	v_lshlrev_b32_e32 v132, 16, v62
	v_and_b32_e32 v133, 0xffff0000, v62
	v_lshlrev_b32_e32 v134, 16, v63
	v_and_b32_e32 v135, 0xffff0000, v63
	v_mul_f32_e32 v138, v120, v120
	v_mul_f32_e32 v149, v121, v121
	v_mul_f32_e32 v150, v122, v122
	v_mul_f32_e32 v154, v123, v123
	v_fma_f32 v138, v124, v124, v138
	v_fma_f32 v149, v125, v125, v149
	v_fma_f32 v150, v126, v126, v150
	v_fma_f32 v154, v127, v127, v154
	v_fma_f32 v138, v128, v128, v138
	v_fma_f32 v149, v129, v129, v149
	v_fma_f32 v150, v130, v130, v150
	v_fma_f32 v154, v131, v131, v154
	v_fma_f32 v138, v132, v132, v138
	v_fma_f32 v149, v133, v133, v149
	v_fma_f32 v150, v134, v134, v150
	v_fma_f32 v154, v135, v135, v154
	v_add_f32_e32 v138, v138, v149
	v_add_f32_e32 v150, v150, v154
	v_add_f32_e32 v138, v138, v150
	s_nop 1
	v_add_f32_dpp v138, v138, v138 quad_perm:[1,0,3,2] row_mask:0xf bank_mask:0xf
	s_nop 1
	v_add_f32_dpp v138, v138, v138 quad_perm:[2,3,0,1] row_mask:0xf bank_mask:0xf
	s_nop 1
	v_add_f32_dpp v138, v138, v138 row_half_mirror row_mask:0xf bank_mask:0xf
	s_nop 1
	v_add_f32_dpp v138, v138, v138 row_mirror row_mask:0xf bank_mask:0xf
	v_mov_b32_e32 v139, v138
	s_nop 1
	v_permlane16_swap_b32_e32 v138, v139
	v_add_f32_e32 v138, v138, v139
	v_mov_b32_e32 v139, v138
	s_nop 1
	v_permlane32_swap_b32_e32 v138, v139
	v_add_f32_e32 v138, v138, v139
	v_mul_f32_e32 v138, 0x3a800000, v138
	v_add_f32_e32 v138, 0x358637bd, v138
	v_rsq_f32_e32 v140, v138
	s_nop 0
	v_mul_f32_e32 v120, v120, v140
	v_mul_f32_e32 v121, v121, v140
	v_mul_f32_e32 v122, v122, v140
	v_mul_f32_e32 v123, v123, v140
	v_mul_f32_e32 v124, v124, v140
	v_mul_f32_e32 v125, v125, v140
	v_mul_f32_e32 v126, v126, v140
	v_mul_f32_e32 v127, v127, v140
	v_mul_f32_e32 v128, v128, v140
	v_mul_f32_e32 v129, v129, v140
	v_mul_f32_e32 v130, v130, v140
	v_mul_f32_e32 v131, v131, v140
	v_mul_f32_e32 v132, v132, v140
	v_mul_f32_e32 v133, v133, v140
	v_mul_f32_e32 v134, v134, v140
	v_mul_f32_e32 v135, v135, v140
	v_fma_f32 v16, v120, v72, v16
	v_fma_f32 v17, v121, v73, v17
	v_fma_f32 v18, v122, v74, v18
	v_fma_f32 v19, v123, v75, v19
	v_fma_f32 v20, v124, v76, v20
	v_fma_f32 v21, v125, v77, v21
	v_fma_f32 v22, v126, v78, v22
	v_fma_f32 v23, v127, v79, v23
	v_fma_f32 v24, v128, v80, v24
	v_fma_f32 v25, v129, v81, v25
	v_fma_f32 v26, v130, v82, v26
	v_fma_f32 v27, v131, v83, v27
	v_fma_f32 v28, v132, v84, v28
	v_fma_f32 v29, v133, v85, v29
	v_fma_f32 v30, v134, v86, v30
	v_fma_f32 v31, v135, v87, v31
; __device__ __forceinline__ void row_phase(const Params& P, int glayer, int layer, int xsrc, bool hasY, int gate_idx, const float* gpost,
;                           int xdst, bool doH, const float* gpre, int sh_idx, int nrows) {
;     ...
;         if (hasY) {
;           float4 yv[4];
;           float ss = 0.f;
; #pragma unroll
;           for (int i = 0; i < 4; ++i) {
;             const uint2 raw = yy[u][i];
;             yv[i].x = bf2f((u16)(raw.x & 0xffff)); yv[i].y = bf2f((u16)(raw.x >> 16));
;             yv[i].z = bf2f((u16)(raw.y & 0xffff)); yv[i].w = bf2f((u16)(raw.y >> 16));
;             ss += yv[i].x * yv[i].x + yv[i].y * yv[i].y + yv[i].z * yv[i].z + yv[i].w * yv[i].w;
;           }
;           ss = wave_sum(ss);
;           const float rstd = __builtin_amdgcn_rsqf(ss * (1.f / 1024.f) + EPSF);
; #pragma unroll
;           for (int i = 0; i < 4; ++i) {
;             const int col = (i * 64 + lane) * 4;
;             const float4 gt = *reinterpret_cast<const float4*>(modg + gate_idx * 1024 + col);
;             const float4 gp = *reinterpret_cast<const float4*>(gpost + col);
;             xv[i].x += gt.x * (yv[i].x * rstd * gp.x); xv[i].y += gt.y * (yv[i].y * rstd * gp.y);
;             xv[i].z += gt.z * (yv[i].z * rstd * gp.z); xv[i].w += gt.w * (yv[i].w * rstd * gp.w);
;           }
;         }
;         if (xdst == 3 || (xdst == 1 && row >= N_X)) {
;           float* xout = (xdst == 3) ? P.out + (long)row * 1024 : P.xc + (long)(row - N_X) * 1024;
; #pragma unroll
;           for (int i = 0; i < 4; ++i) *reinterpret_cast<float4*>(xout + (i * 64 + lane) * 4) = xv[i];
;         } else if (xdst != 0) {
;           u16* xo = ((xdst == 1) ? resA : P.zf) + (long)row * 1024;
; #pragma unroll
;           for (int i = 0; i < 4; ++i) {
;             const unsigned b0 = f2bf(xv[i].x), b1 = f2bf(xv[i].y), b2 = f2bf(xv[i].z), b3 = f2bf(xv[i].w);
;             *reinterpret_cast<uint2*>(xo + (i * 64 + lane) * 4) = make_uint2(b0 | (b1 << 16), b2 | (b3 << 16));
;           }
;         }
;         if (doH) {
;           float ss = 0.f;
; #pragma unroll
;           for (int i = 0; i < 4; ++i) ss += xv[i].x * xv[i].x + xv[i].y * xv[i].y + xv[i].z * xv[i].z + xv[i].w * xv[i].w;
;           ss = wave_sum(ss);
;           const float rstd = __builtin_amdgcn_rsqf(ss * (1.f / 1024.f) + EPSF);
;           u16* h = P.hy + (long)row * 1024;
; #pragma unroll
	v_cvt_pk_bf16_f32 v156, v16, v17
	v_cvt_pk_bf16_f32 v157, v18, v19
	v_cvt_pk_bf16_f32 v158, v20, v21
	v_cvt_pk_bf16_f32 v159, v22, v23
	v_cvt_pk_bf16_f32 v160, v24, v25
	v_cvt_pk_bf16_f32 v161, v26, v27
	v_cvt_pk_bf16_f32 v162, v28, v29
	v_cvt_pk_bf16_f32 v163, v30, v31
	s_lshl_b32 vcc_lo, s19, 11
	s_add_u32 vcc_lo, vcc_lo, 0x2800000
	s_add_u32 s100, s16, vcc_lo
	s_addc_u32 s101, s17, 0
	global_store_dwordx2 v137, v[156:157], s[100:101] offset:0
	global_store_dwordx2 v137, v[158:159], s[100:101] offset:512
	global_store_dwordx2 v137, v[160:161], s[100:101] offset:1024
	global_store_dwordx2 v137, v[162:163], s[100:101] offset:1536
	v_mul_f32_e32 v138, v16, v16
	v_mul_f32_e32 v149, v17, v17
	v_mul_f32_e32 v150, v18, v18
	v_mul_f32_e32 v154, v19, v19
	v_fma_f32 v138, v20, v20, v138
	v_fma_f32 v149, v21, v21, v149
	v_fma_f32 v150, v22, v22, v150
	v_fma_f32 v154, v23, v23, v154
	v_fma_f32 v138, v24, v24, v138
	v_fma_f32 v149, v25, v25, v149
	v_fma_f32 v150, v26, v26, v150
	v_fma_f32 v154, v27, v27, v154
	v_fma_f32 v138, v28, v28, v138
	v_fma_f32 v149, v29, v29, v149
	v_fma_f32 v150, v30, v30, v150
	v_fma_f32 v154, v31, v31, v154
	v_add_f32_e32 v138, v138, v149
	v_add_f32_e32 v150, v150, v154
	v_add_f32_e32 v138, v138, v150
	s_nop 1
	v_add_f32_dpp v138, v138, v138 quad_perm:[1,0,3,2] row_mask:0xf bank_mask:0xf
	s_nop 1
	v_add_f32_dpp v138, v138, v138 quad_perm:[2,3,0,1] row_mask:0xf bank_mask:0xf
	s_nop 1
	v_add_f32_dpp v138, v138, v138 row_half_mirror row_mask:0xf bank_mask:0xf
	s_nop 1
	v_add_f32_dpp v138, v138, v138 row_mirror row_mask:0xf bank_mask:0xf
	v_mov_b32_e32 v139, v138
	s_nop 1
	v_permlane16_swap_b32_e32 v138, v139
	v_add_f32_e32 v138, v138, v139
	v_mov_b32_e32 v139, v138
	s_nop 1
	v_permlane32_swap_b32_e32 v138, v139
	v_add_f32_e32 v138, v138, v139
	v_mul_f32_e32 v138, 0x3a800000, v138
	v_add_f32_e32 v138, 0x358637bd, v138
	v_rsq_f32_e32 v140, v138
	s_nop 0
	v_mul_f32_e32 v120, v16, v140
	v_mul_f32_e32 v121, v17, v140
	v_mul_f32_e32 v122, v18, v140
	v_mul_f32_e32 v123, v19, v140
	v_mul_f32_e32 v124, v20, v140
	v_mul_f32_e32 v125, v21, v140
	v_mul_f32_e32 v126, v22, v140
	v_mul_f32_e32 v127, v23, v140
	v_mul_f32_e32 v128, v24, v140
	v_mul_f32_e32 v129, v25, v140
	v_mul_f32_e32 v130, v26, v140
	v_mul_f32_e32 v131, v27, v140
	v_mul_f32_e32 v132, v28, v140
	v_mul_f32_e32 v133, v29, v140
	v_mul_f32_e32 v134, v30, v140
	v_mul_f32_e32 v135, v31, v140
	v_fma_f32 v120, v120, v88, v104
	v_fma_f32 v121, v121, v89, v105
	v_fma_f32 v122, v122, v90, v106
	v_fma_f32 v123, v123, v91, v107
	v_fma_f32 v124, v124, v92, v108
	v_fma_f32 v125, v125, v93, v109
	v_fma_f32 v126, v126, v94, v110
	v_fma_f32 v127, v127, v95, v111
	v_fma_f32 v128, v128, v96, v112
	v_fma_f32 v129, v129, v97, v113
	v_fma_f32 v130, v130, v98, v114
	v_fma_f32 v131, v131, v99, v115
	v_fma_f32 v132, v132, v100, v116
	v_fma_f32 v133, v133, v101, v117
	v_fma_f32 v134, v134, v102, v118
	v_fma_f32 v135, v135, v103, v119
	v_cvt_pk_bf16_f32 v156, v120, v121
	v_cvt_pk_bf16_f32 v157, v122, v123
	v_cvt_pk_bf16_f32 v158, v124, v125
	v_cvt_pk_bf16_f32 v159, v126, v127
	v_cvt_pk_bf16_f32 v160, v128, v129
	v_cvt_pk_bf16_f32 v161, v130, v131
	v_cvt_pk_bf16_f32 v162, v132, v133
	v_cvt_pk_bf16_f32 v163, v134, v135
	s_lshl_b32 vcc_lo, s19, 11
	s_add_u32 vcc_lo, vcc_lo, 0x2800000
	s_add_u32 s100, s14, vcc_lo
	s_addc_u32 s101, s15, 0
	global_store_dwordx2 v137, v[156:157], s[100:101] offset:0
	global_store_dwordx2 v137, v[158:159], s[100:101] offset:512
	global_store_dwordx2 v137, v[160:161], s[100:101] offset:1024
	global_store_dwordx2 v137, v[162:163], s[100:101] offset:1536
	s_lshl_b32 vcc_lo, s19, 12
	s_add_u32 vcc_lo, vcc_lo, 0x6800000
	s_add_u32 s100, s12, vcc_lo
	s_addc_u32 s101, s13, 0
	global_load_dwordx4 v[16:19], v136, s[100:101] offset:0
	global_load_dwordx4 v[20:23], v136, s[100:101] offset:1024
	global_load_dwordx4 v[24:27], v136, s[100:101] offset:2048
	global_load_dwordx4 v[28:31], v136, s[100:101] offset:3072
	s_lshl_b32 vcc_lo, s19, 11
	s_add_u32 vcc_lo, vcc_lo, 0x3400000
	s_add_u32 s100, s14, vcc_lo
	s_addc_u32 s101, s15, 0
	global_load_dwordx2 v[56:57], v137, s[100:101] offset:0
	global_load_dwordx2 v[58:59], v137, s[100:101] offset:512
	global_load_dwordx2 v[60:61], v137, s[100:101] offset:1024
	global_load_dwordx2 v[62:63], v137, s[100:101] offset:1536
	s_waitcnt vmcnt(32)
; __device__ __forceinline__ void row_phase(const Params& P, int glayer, int layer, int xsrc, bool hasY, int gate_idx, const float* gpost,
;                           int xdst, bool doH, const float* gpre, int sh_idx, int nrows) {
;     ...
;         if (hasY) {
;           float4 yv[4];
;           float ss = 0.f;
; #pragma unroll
;           for (int i = 0; i < 4; ++i) {
;             const uint2 raw = yy[u][i];
;             yv[i].x = bf2f((u16)(raw.x & 0xffff)); yv[i].y = bf2f((u16)(raw.x >> 16));
;             yv[i].z = bf2f((u16)(raw.y & 0xffff)); yv[i].w = bf2f((u16)(raw.y >> 16));
;             ss += yv[i].x * yv[i].x + yv[i].y * yv[i].y + yv[i].z * yv[i].z + yv[i].w * yv[i].w;
;           }
;           ss = wave_sum(ss);
;           const float rstd = __builtin_amdgcn_rsqf(ss * (1.f / 1024.f) + EPSF);
; #pragma unroll
;           for (int i = 0; i < 4; ++i) {
;             const int col = (i * 64 + lane) * 4;
;             const float4 gt = *reinterpret_cast<const float4*>(modg + gate_idx * 1024 + col);
;             const float4 gp = *reinterpret_cast<const float4*>(gpost + col);
;             xv[i].x += gt.x * (yv[i].x * rstd * gp.x); xv[i].y += gt.y * (yv[i].y * rstd * gp.y);
;             xv[i].z += gt.z * (yv[i].z * rstd * gp.z); xv[i].w += gt.w * (yv[i].w * rstd * gp.w);
;           }
;         }
;         if (xdst == 3 || (xdst == 1 && row >= N_X)) {
;           float* xout = (xdst == 3) ? P.out + (long)row * 1024 : P.xc + (long)(row - N_X) * 1024;
; #pragma unroll
;           for (int i = 0; i < 4; ++i) *reinterpret_cast<float4*>(xout + (i * 64 + lane) * 4) = xv[i];
;         } else if (xdst != 0) {
;           u16* xo = ((xdst == 1) ? resA : P.zf) + (long)row * 1024;
; #pragma unroll
;           for (int i = 0; i < 4; ++i) {
;             const unsigned b0 = f2bf(xv[i].x), b1 = f2bf(xv[i].y), b2 = f2bf(xv[i].z), b3 = f2bf(xv[i].w);
;             *reinterpret_cast<uint2*>(xo + (i * 64 + lane) * 4) = make_uint2(b0 | (b1 << 16), b2 | (b3 << 16));
;           }
;         }
;         if (doH) {
;           float ss = 0.f;
; #pragma unroll
;           for (int i = 0; i < 4; ++i) ss += xv[i].x * xv[i].x + xv[i].y * xv[i].y + xv[i].z * xv[i].z + xv[i].w * xv[i].w;
;           ss = wave_sum(ss);
;           const float rstd = __builtin_amdgcn_rsqf(ss * (1.f / 1024.f) + EPSF);
;           u16* h = P.hy + (long)row * 1024;
; #pragma unroll
	v_lshlrev_b32_e32 v120, 16, v64
	v_and_b32_e32 v121, 0xffff0000, v64
	v_lshlrev_b32_e32 v122, 16, v65
	v_and_b32_e32 v123, 0xffff0000, v65
	v_lshlrev_b32_e32 v124, 16, v66
	v_and_b32_e32 v125, 0xffff0000, v66
	v_lshlrev_b32_e32 v126, 16, v67
	v_and_b32_e32 v127, 0xffff0000, v67
	v_lshlrev_b32_e32 v128, 16, v68
	v_and_b32_e32 v129, 0xffff0000, v68
	v_lshlrev_b32_e32 v130, 16, v69
	v_and_b32_e32 v131, 0xffff0000, v69
	v_lshlrev_b32_e32 v132, 16, v70
	v_and_b32_e32 v133, 0xffff0000, v70
	v_lshlrev_b32_e32 v134, 16, v71
	v_and_b32_e32 v135, 0xffff0000, v71
	v_mul_f32_e32 v138, v120, v120
	v_mul_f32_e32 v149, v121, v121
	v_mul_f32_e32 v150, v122, v122
	v_mul_f32_e32 v154, v123, v123
	v_fma_f32 v138, v124, v124, v138
	v_fma_f32 v149, v125, v125, v149
	v_fma_f32 v150, v126, v126, v150
	v_fma_f32 v154, v127, v127, v154
	v_fma_f32 v138, v128, v128, v138
	v_fma_f32 v149, v129, v129, v149
	v_fma_f32 v150, v130, v130, v150
	v_fma_f32 v154, v131, v131, v154
	v_fma_f32 v138, v132, v132, v138
	v_fma_f32 v149, v133, v133, v149
	v_fma_f32 v150, v134, v134, v150
	v_fma_f32 v154, v135, v135, v154
	v_add_f32_e32 v138, v138, v149
	v_add_f32_e32 v150, v150, v154
	v_add_f32_e32 v138, v138, v150
	s_nop 1
	v_add_f32_dpp v138, v138, v138 quad_perm:[1,0,3,2] row_mask:0xf bank_mask:0xf
	s_nop 1
	v_add_f32_dpp v138, v138, v138 quad_perm:[2,3,0,1] row_mask:0xf bank_mask:0xf
	s_nop 1
	v_add_f32_dpp v138, v138, v138 row_half_mirror row_mask:0xf bank_mask:0xf
	s_nop 1
	v_add_f32_dpp v138, v138, v138 row_mirror row_mask:0xf bank_mask:0xf
	v_mov_b32_e32 v139, v138
	s_nop 1
	v_permlane16_swap_b32_e32 v138, v139
	v_add_f32_e32 v138, v138, v139
	v_mov_b32_e32 v139, v138
	s_nop 1
	v_permlane32_swap_b32_e32 v138, v139
	v_add_f32_e32 v138, v138, v139
	v_mul_f32_e32 v138, 0x3a800000, v138
	v_add_f32_e32 v138, 0x358637bd, v138
	v_rsq_f32_e32 v140, v138
	s_nop 0
	v_mul_f32_e32 v120, v120, v140
	v_mul_f32_e32 v121, v121, v140
	v_mul_f32_e32 v122, v122, v140
	v_mul_f32_e32 v123, v123, v140
	v_mul_f32_e32 v124, v124, v140
	v_mul_f32_e32 v125, v125, v140
	v_mul_f32_e32 v126, v126, v140
	v_mul_f32_e32 v127, v127, v140
	v_mul_f32_e32 v128, v128, v140
	v_mul_f32_e32 v129, v129, v140
	v_mul_f32_e32 v130, v130, v140
	v_mul_f32_e32 v131, v131, v140
	v_mul_f32_e32 v132, v132, v140
	v_mul_f32_e32 v133, v133, v140
	v_mul_f32_e32 v134, v134, v140
	v_mul_f32_e32 v135, v135, v140
	v_fma_f32 v32, v120, v72, v32
	v_fma_f32 v33, v121, v73, v33
	v_fma_f32 v34, v122, v74, v34
	v_fma_f32 v35, v123, v75, v35
	v_fma_f32 v36, v124, v76, v36
	v_fma_f32 v37, v125, v77, v37
	v_fma_f32 v38, v126, v78, v38
	v_fma_f32 v39, v127, v79, v39
	v_fma_f32 v40, v128, v80, v40
	v_fma_f32 v41, v129, v81, v41
	v_fma_f32 v42, v130, v82, v42
	v_fma_f32 v43, v131, v83, v43
	v_fma_f32 v44, v132, v84, v44
	v_fma_f32 v45, v133, v85, v45
	v_fma_f32 v46, v134, v86, v46
	v_fma_f32 v47, v135, v87, v47
	v_cvt_pk_bf16_f32 v156, v32, v33
	v_cvt_pk_bf16_f32 v157, v34, v35
	v_cvt_pk_bf16_f32 v158, v36, v37
	v_cvt_pk_bf16_f32 v159, v38, v39
	v_cvt_pk_bf16_f32 v160, v40, v41
	v_cvt_pk_bf16_f32 v161, v42, v43
	v_cvt_pk_bf16_f32 v162, v44, v45
	v_cvt_pk_bf16_f32 v163, v46, v47
	s_lshl_b32 vcc_lo, s19, 11
	s_add_u32 vcc_lo, vcc_lo, 0x2c00000
	s_add_u32 s100, s16, vcc_lo
	s_addc_u32 s101, s17, 0
	global_store_dwordx2 v137, v[156:157], s[100:101] offset:0
	global_store_dwordx2 v137, v[158:159], s[100:101] offset:512
	global_store_dwordx2 v137, v[160:161], s[100:101] offset:1024
	global_store_dwordx2 v137, v[162:163], s[100:101] offset:1536
	v_mul_f32_e32 v138, v32, v32
	v_mul_f32_e32 v149, v33, v33
	v_mul_f32_e32 v150, v34, v34
	v_mul_f32_e32 v154, v35, v35
	v_fma_f32 v138, v36, v36, v138
	v_fma_f32 v149, v37, v37, v149
	v_fma_f32 v150, v38, v38, v150
	v_fma_f32 v154, v39, v39, v154
	v_fma_f32 v138, v40, v40, v138
	v_fma_f32 v149, v41, v41, v149
	v_fma_f32 v150, v42, v42, v150
	v_fma_f32 v154, v43, v43, v154
	v_fma_f32 v138, v44, v44, v138
	v_fma_f32 v149, v45, v45, v149
	v_fma_f32 v150, v46, v46, v150
	v_fma_f32 v154, v47, v47, v154
	v_add_f32_e32 v138, v138, v149
	v_add_f32_e32 v150, v150, v154
	v_add_f32_e32 v138, v138, v150
	s_nop 1
	v_add_f32_dpp v138, v138, v138 quad_perm:[1,0,3,2] row_mask:0xf bank_mask:0xf
	s_nop 1
	v_add_f32_dpp v138, v138, v138 quad_perm:[2,3,0,1] row_mask:0xf bank_mask:0xf
	s_nop 1
	v_add_f32_dpp v138, v138, v138 row_half_mirror row_mask:0xf bank_mask:0xf
	s_nop 1
	v_add_f32_dpp v138, v138, v138 row_mirror row_mask:0xf bank_mask:0xf
	v_mov_b32_e32 v139, v138
	s_nop 1
	v_permlane16_swap_b32_e32 v138, v139
	v_add_f32_e32 v138, v138, v139
	v_mov_b32_e32 v139, v138
	s_nop 1
	v_permlane32_swap_b32_e32 v138, v139
	v_add_f32_e32 v138, v138, v139
	v_mul_f32_e32 v138, 0x3a800000, v138
	v_add_f32_e32 v138, 0x358637bd, v138
	v_rsq_f32_e32 v140, v138
	s_nop 0
	v_mul_f32_e32 v120, v32, v140
	v_mul_f32_e32 v121, v33, v140
	v_mul_f32_e32 v122, v34, v140
	v_mul_f32_e32 v123, v35, v140
	v_mul_f32_e32 v124, v36, v140
	v_mul_f32_e32 v125, v37, v140
	v_mul_f32_e32 v126, v38, v140
	v_mul_f32_e32 v127, v39, v140
	v_mul_f32_e32 v128, v40, v140
	v_mul_f32_e32 v129, v41, v140
	v_mul_f32_e32 v130, v42, v140
	v_mul_f32_e32 v131, v43, v140
	v_mul_f32_e32 v132, v44, v140
	v_mul_f32_e32 v133, v45, v140
	v_mul_f32_e32 v134, v46, v140
	v_mul_f32_e32 v135, v47, v140
	v_fma_f32 v120, v120, v88, v104
	v_fma_f32 v121, v121, v89, v105
	v_fma_f32 v122, v122, v90, v106
	v_fma_f32 v123, v123, v91, v107
	v_fma_f32 v124, v124, v92, v108
	v_fma_f32 v125, v125, v93, v109
	v_fma_f32 v126, v126, v94, v110
	v_fma_f32 v127, v127, v95, v111
	v_fma_f32 v128, v128, v96, v112
	v_fma_f32 v129, v129, v97, v113
	v_fma_f32 v130, v130, v98, v114
	v_fma_f32 v131, v131, v99, v115
	v_fma_f32 v132, v132, v100, v116
	v_fma_f32 v133, v133, v101, v117
	v_fma_f32 v134, v134, v102, v118
	v_fma_f32 v135, v135, v103, v119
	v_cvt_pk_bf16_f32 v156, v120, v121
	v_cvt_pk_bf16_f32 v157, v122, v123
	v_cvt_pk_bf16_f32 v158, v124, v125
	v_cvt_pk_bf16_f32 v159, v126, v127
	v_cvt_pk_bf16_f32 v160, v128, v129
	v_cvt_pk_bf16_f32 v161, v130, v131
	v_cvt_pk_bf16_f32 v162, v132, v133
	v_cvt_pk_bf16_f32 v163, v134, v135
	s_lshl_b32 vcc_lo, s19, 11
	s_add_u32 vcc_lo, vcc_lo, 0x2c00000
	s_add_u32 s100, s14, vcc_lo
	s_addc_u32 s101, s15, 0
	global_store_dwordx2 v137, v[156:157], s[100:101] offset:0
	global_store_dwordx2 v137, v[158:159], s[100:101] offset:512
	global_store_dwordx2 v137, v[160:161], s[100:101] offset:1024
	global_store_dwordx2 v137, v[162:163], s[100:101] offset:1536
	s_add_u32 s100, s20, 0x14000
	s_addc_u32 s101, s21, 0
	global_load_dwordx4 v[72:75], v136, s[100:101] offset:0
	global_load_dwordx4 v[76:79], v136, s[100:101] offset:1024
	global_load_dwordx4 v[80:83], v136, s[100:101] offset:2048
	global_load_dwordx4 v[84:87], v136, s[100:101] offset:3072
	s_load_dwordx2 s[98:99], s[4:5], 0x38
	s_waitcnt lgkmcnt(0)
; __device__ __forceinline__ void row_phase(const Params& P, int glayer, int layer, int xsrc, bool hasY, int gate_idx, const float* gpost,
;                           int xdst, bool doH, const float* gpre, int sh_idx, int nrows) {
;     ...
;         if (hasY) {
;           float4 yv[4];
;           float ss = 0.f;
; #pragma unroll
;           for (int i = 0; i < 4; ++i) {
;             const uint2 raw = yy[u][i];
;             yv[i].x = bf2f((u16)(raw.x & 0xffff)); yv[i].y = bf2f((u16)(raw.x >> 16));
;             yv[i].z = bf2f((u16)(raw.y & 0xffff)); yv[i].w = bf2f((u16)(raw.y >> 16));
;             ss += yv[i].x * yv[i].x + yv[i].y * yv[i].y + yv[i].z * yv[i].z + yv[i].w * yv[i].w;
;           }
;           ss = wave_sum(ss);
;           const float rstd = __builtin_amdgcn_rsqf(ss * (1.f / 1024.f) + EPSF);
; #pragma unroll
;           for (int i = 0; i < 4; ++i) {
;             const int col = (i * 64 + lane) * 4;
;             const float4 gt = *reinterpret_cast<const float4*>(modg + gate_idx * 1024 + col);
;             const float4 gp = *reinterpret_cast<const float4*>(gpost + col);
;             xv[i].x += gt.x * (yv[i].x * rstd * gp.x); xv[i].y += gt.y * (yv[i].y * rstd * gp.y);
;             xv[i].z += gt.z * (yv[i].z * rstd * gp.z); xv[i].w += gt.w * (yv[i].w * rstd * gp.w);
;           }
;         }
;         if (xdst == 3 || (xdst == 1 && row >= N_X)) {
;           float* xout = (xdst == 3) ? P.out + (long)row * 1024 : P.xc + (long)(row - N_X) * 1024;
; #pragma unroll
;           for (int i = 0; i < 4; ++i) *reinterpret_cast<float4*>(xout + (i * 64 + lane) * 4) = xv[i];
;         } else if (xdst != 0) {
;           u16* xo = ((xdst == 1) ? resA : P.zf) + (long)row * 1024;
; #pragma unroll
;           for (int i = 0; i < 4; ++i) {
;             const unsigned b0 = f2bf(xv[i].x), b1 = f2bf(xv[i].y), b2 = f2bf(xv[i].z), b3 = f2bf(xv[i].w);
;             *reinterpret_cast<uint2*>(xo + (i * 64 + lane) * 4) = make_uint2(b0 | (b1 << 16), b2 | (b3 << 16));
;           }
;         }
;         if (doH) {
;           float ss = 0.f;
; #pragma unroll
;           for (int i = 0; i < 4; ++i) ss += xv[i].x * xv[i].x + xv[i].y * xv[i].y + xv[i].z * xv[i].z + xv[i].w * xv[i].w;
;           ss = wave_sum(ss);
;           const float rstd = __builtin_amdgcn_rsqf(ss * (1.f / 1024.f) + EPSF);
;           u16* h = P.hy + (long)row * 1024;
; #pragma unroll
	global_load_dwordx4 v[120:123], v136, s[98:99] offset:0
	global_load_dwordx4 v[124:127], v136, s[98:99] offset:1024
	global_load_dwordx4 v[128:131], v136, s[98:99] offset:2048
	global_load_dwordx4 v[132:135], v136, s[98:99] offset:3072
	s_add_u32 s100, s20, 0x15000
	s_addc_u32 s101, s21, 0
	global_load_dwordx4 v[104:107], v136, s[100:101] offset:0
	global_load_dwordx4 v[108:111], v136, s[100:101] offset:1024
	global_load_dwordx4 v[112:115], v136, s[100:101] offset:2048
	global_load_dwordx4 v[116:119], v136, s[100:101] offset:3072
	s_add_u32 s100, s100, 0x1000
	s_addc_u32 s101, s101, 0
	global_load_dwordx4 v[32:35], v136, s[100:101] offset:0
	global_load_dwordx4 v[36:39], v136, s[100:101] offset:1024
	global_load_dwordx4 v[40:43], v136, s[100:101] offset:2048
	global_load_dwordx4 v[44:47], v136, s[100:101] offset:3072
	s_load_dwordx2 s[98:99], s[4:5], 0x40
	s_waitcnt lgkmcnt(0)
	global_load_dwordx4 v[88:91], v136, s[98:99] offset:0
	global_load_dwordx4 v[92:95], v136, s[98:99] offset:1024
	global_load_dwordx4 v[96:99], v136, s[98:99] offset:2048
	global_load_dwordx4 v[100:103], v136, s[98:99] offset:3072
	s_waitcnt vmcnt(0)
	v_mul_f32_e32 v72, v72, v120
	v_mul_f32_e32 v73, v73, v121
	v_mul_f32_e32 v74, v74, v122
	v_mul_f32_e32 v75, v75, v123
	v_mul_f32_e32 v76, v76, v124
	v_mul_f32_e32 v77, v77, v125
	v_mul_f32_e32 v78, v78, v126
	v_mul_f32_e32 v79, v79, v127
	v_mul_f32_e32 v80, v80, v128
	v_mul_f32_e32 v81, v81, v129
	v_mul_f32_e32 v82, v82, v130
	v_mul_f32_e32 v83, v83, v131
	v_mul_f32_e32 v84, v84, v132
	v_mul_f32_e32 v85, v85, v133
	v_mul_f32_e32 v86, v86, v134
	v_mul_f32_e32 v87, v87, v135
	v_fma_f32 v88, v88, v32, v88
	v_fma_f32 v89, v89, v33, v89
	v_fma_f32 v90, v90, v34, v90
	v_fma_f32 v91, v91, v35, v91
	v_fma_f32 v92, v92, v36, v92
	v_fma_f32 v93, v93, v37, v93
	v_fma_f32 v94, v94, v38, v94
	v_fma_f32 v95, v95, v39, v95
	v_fma_f32 v96, v96, v40, v96
	v_fma_f32 v97, v97, v41, v97
	v_fma_f32 v98, v98, v42, v98
	v_fma_f32 v99, v99, v43, v99
	v_fma_f32 v100, v100, v44, v100
	v_fma_f32 v101, v101, v45, v101
	v_fma_f32 v102, v102, v46, v102
	v_fma_f32 v103, v103, v47, v103
	s_lshl_b32 vcc_lo, s19, 12
	s_add_u32 vcc_lo, vcc_lo, 0x7000000
	s_add_u32 s100, s12, vcc_lo
	s_addc_u32 s101, s13, 0
	global_load_dwordx4 v[32:35], v136, s[100:101] offset:0
	global_load_dwordx4 v[36:39], v136, s[100:101] offset:1024
	global_load_dwordx4 v[40:43], v136, s[100:101] offset:2048
	global_load_dwordx4 v[44:47], v136, s[100:101] offset:3072
	s_lshl_b32 vcc_lo, s19, 11
	s_add_u32 vcc_lo, vcc_lo, 0x3800000
	s_add_u32 s100, s14, vcc_lo
	s_addc_u32 s101, s15, 0
	global_load_dwordx2 v[64:65], v137, s[100:101] offset:0
	global_load_dwordx2 v[66:67], v137, s[100:101] offset:512
	global_load_dwordx2 v[68:69], v137, s[100:101] offset:1024
	global_load_dwordx2 v[70:71], v137, s[100:101] offset:1536
	v_lshlrev_b32_e32 v120, 16, v48
	v_and_b32_e32 v121, 0xffff0000, v48
	v_lshlrev_b32_e32 v122, 16, v49
	v_and_b32_e32 v123, 0xffff0000, v49
	v_lshlrev_b32_e32 v124, 16, v50
	v_and_b32_e32 v125, 0xffff0000, v50
	v_lshlrev_b32_e32 v126, 16, v51
	v_and_b32_e32 v127, 0xffff0000, v51
	v_lshlrev_b32_e32 v128, 16, v52
	v_and_b32_e32 v129, 0xffff0000, v52
	v_lshlrev_b32_e32 v130, 16, v53
	v_and_b32_e32 v131, 0xffff0000, v53
	v_lshlrev_b32_e32 v132, 16, v54
	v_and_b32_e32 v133, 0xffff0000, v54
	v_lshlrev_b32_e32 v134, 16, v55
	v_and_b32_e32 v135, 0xffff0000, v55
	v_mul_f32_e32 v138, v120, v120
	v_mul_f32_e32 v149, v121, v121
	v_mul_f32_e32 v150, v122, v122
	v_mul_f32_e32 v154, v123, v123
	v_fma_f32 v138, v124, v124, v138
	v_fma_f32 v149, v125, v125, v149
	v_fma_f32 v150, v126, v126, v150
	v_fma_f32 v154, v127, v127, v154
	v_fma_f32 v138, v128, v128, v138
	v_fma_f32 v149, v129, v129, v149
	v_fma_f32 v150, v130, v130, v150
	v_fma_f32 v154, v131, v131, v154
	v_fma_f32 v138, v132, v132, v138
	v_fma_f32 v149, v133, v133, v149
	v_fma_f32 v150, v134, v134, v150
	v_fma_f32 v154, v135, v135, v154
	v_add_f32_e32 v138, v138, v149
	v_add_f32_e32 v150, v150, v154
	v_add_f32_e32 v138, v138, v150
	s_nop 1
	v_add_f32_dpp v138, v138, v138 quad_perm:[1,0,3,2] row_mask:0xf bank_mask:0xf
	s_nop 1
	v_add_f32_dpp v138, v138, v138 quad_perm:[2,3,0,1] row_mask:0xf bank_mask:0xf
	s_nop 1
	v_add_f32_dpp v138, v138, v138 row_half_mirror row_mask:0xf bank_mask:0xf
	s_nop 1
	v_add_f32_dpp v138, v138, v138 row_mirror row_mask:0xf bank_mask:0xf
	v_mov_b32_e32 v139, v138
	s_nop 1
	v_permlane16_swap_b32_e32 v138, v139
	v_add_f32_e32 v138, v138, v139
	v_mov_b32_e32 v139, v138
	s_nop 1
	v_permlane32_swap_b32_e32 v138, v139
	v_add_f32_e32 v138, v138, v139
	v_mul_f32_e32 v138, 0x3a800000, v138
	v_add_f32_e32 v138, 0x358637bd, v138
	v_rsq_f32_e32 v140, v138
	s_nop 0
	v_mul_f32_e32 v120, v120, v140
	v_mul_f32_e32 v121, v121, v140
	v_mul_f32_e32 v122, v122, v140
	v_mul_f32_e32 v123, v123, v140
	v_mul_f32_e32 v124, v124, v140
	v_mul_f32_e32 v125, v125, v140
	v_mul_f32_e32 v126, v126, v140
	v_mul_f32_e32 v127, v127, v140
	v_mul_f32_e32 v128, v128, v140
	v_mul_f32_e32 v129, v129, v140
	v_mul_f32_e32 v130, v130, v140
	v_mul_f32_e32 v131, v131, v140
	v_mul_f32_e32 v132, v132, v140
	v_mul_f32_e32 v133, v133, v140
	v_mul_f32_e32 v134, v134, v140
	v_mul_f32_e32 v135, v135, v140
	v_fma_f32 v0, v120, v72, v0
	v_fma_f32 v1, v121, v73, v1
	v_fma_f32 v2, v122, v74, v2
	v_fma_f32 v3, v123, v75, v3
	v_fma_f32 v4, v124, v76, v4
	v_fma_f32 v5, v125, v77, v5
	v_fma_f32 v6, v126, v78, v6
	v_fma_f32 v7, v127, v79, v7
	v_fma_f32 v8, v128, v80, v8
	v_fma_f32 v9, v129, v81, v9
	v_fma_f32 v10, v130, v82, v10
	v_fma_f32 v11, v131, v83, v11
	v_fma_f32 v12, v132, v84, v12
	v_fma_f32 v13, v133, v85, v13
	v_fma_f32 v14, v134, v86, v14
; __device__ __forceinline__ void row_phase(const Params& P, int glayer, int layer, int xsrc, bool hasY, int gate_idx, const float* gpost,
;                           int xdst, bool doH, const float* gpre, int sh_idx, int nrows) {
;     ...
;         if (hasY) {
;           float4 yv[4];
;           float ss = 0.f;
; #pragma unroll
;           for (int i = 0; i < 4; ++i) {
;             const uint2 raw = yy[u][i];
;             yv[i].x = bf2f((u16)(raw.x & 0xffff)); yv[i].y = bf2f((u16)(raw.x >> 16));
;             yv[i].z = bf2f((u16)(raw.y & 0xffff)); yv[i].w = bf2f((u16)(raw.y >> 16));
;             ss += yv[i].x * yv[i].x + yv[i].y * yv[i].y + yv[i].z * yv[i].z + yv[i].w * yv[i].w;
;           }
;           ss = wave_sum(ss);
;           const float rstd = __builtin_amdgcn_rsqf(ss * (1.f / 1024.f) + EPSF);
; #pragma unroll
;           for (int i = 0; i < 4; ++i) {
;             const int col = (i * 64 + lane) * 4;
;             const float4 gt = *reinterpret_cast<const float4*>(modg + gate_idx * 1024 + col);
;             const float4 gp = *reinterpret_cast<const float4*>(gpost + col);
;             xv[i].x += gt.x * (yv[i].x * rstd * gp.x); xv[i].y += gt.y * (yv[i].y * rstd * gp.y);
;             xv[i].z += gt.z * (yv[i].z * rstd * gp.z); xv[i].w += gt.w * (yv[i].w * rstd * gp.w);
;           }
;         }
;         if (xdst == 3 || (xdst == 1 && row >= N_X)) {
;           float* xout = (xdst == 3) ? P.out + (long)row * 1024 : P.xc + (long)(row - N_X) * 1024;
; #pragma unroll
;           for (int i = 0; i < 4; ++i) *reinterpret_cast<float4*>(xout + (i * 64 + lane) * 4) = xv[i];
;         } else if (xdst != 0) {
;           u16* xo = ((xdst == 1) ? resA : P.zf) + (long)row * 1024;
; #pragma unroll
;           for (int i = 0; i < 4; ++i) {
;             const unsigned b0 = f2bf(xv[i].x), b1 = f2bf(xv[i].y), b2 = f2bf(xv[i].z), b3 = f2bf(xv[i].w);
;             *reinterpret_cast<uint2*>(xo + (i * 64 + lane) * 4) = make_uint2(b0 | (b1 << 16), b2 | (b3 << 16));
;           }
;         }
;         if (doH) {
;           float ss = 0.f;
; #pragma unroll
;           for (int i = 0; i < 4; ++i) ss += xv[i].x * xv[i].x + xv[i].y * xv[i].y + xv[i].z * xv[i].z + xv[i].w * xv[i].w;
;           ss = wave_sum(ss);
;           const float rstd = __builtin_amdgcn_rsqf(ss * (1.f / 1024.f) + EPSF);
;           u16* h = P.hy + (long)row * 1024;
; #pragma unroll
	v_fma_f32 v15, v135, v87, v15
	v_cvt_pk_bf16_f32 v156, v0, v1
	v_cvt_pk_bf16_f32 v157, v2, v3
	v_cvt_pk_bf16_f32 v158, v4, v5
	v_cvt_pk_bf16_f32 v159, v6, v7
	v_cvt_pk_bf16_f32 v160, v8, v9
	v_cvt_pk_bf16_f32 v161, v10, v11
	v_cvt_pk_bf16_f32 v162, v12, v13
	v_cvt_pk_bf16_f32 v163, v14, v15
	s_lshl_b32 vcc_lo, s19, 11
	s_add_u32 vcc_lo, vcc_lo, 0x3000000
	s_add_u32 s100, s16, vcc_lo
	s_addc_u32 s101, s17, 0
	global_store_dwordx2 v137, v[156:157], s[100:101] offset:0
	global_store_dwordx2 v137, v[158:159], s[100:101] offset:512
	global_store_dwordx2 v137, v[160:161], s[100:101] offset:1024
	global_store_dwordx2 v137, v[162:163], s[100:101] offset:1536
	v_mul_f32_e32 v138, v0, v0
	v_mul_f32_e32 v149, v1, v1
	v_mul_f32_e32 v150, v2, v2
	v_mul_f32_e32 v154, v3, v3
	v_fma_f32 v138, v4, v4, v138
	v_fma_f32 v149, v5, v5, v149
	v_fma_f32 v150, v6, v6, v150
	v_fma_f32 v154, v7, v7, v154
	v_fma_f32 v138, v8, v8, v138
	v_fma_f32 v149, v9, v9, v149
	v_fma_f32 v150, v10, v10, v150
	v_fma_f32 v154, v11, v11, v154
	v_fma_f32 v138, v12, v12, v138
	v_fma_f32 v149, v13, v13, v149
	v_fma_f32 v150, v14, v14, v150
	v_fma_f32 v154, v15, v15, v154
	v_add_f32_e32 v138, v138, v149
	v_add_f32_e32 v150, v150, v154
	v_add_f32_e32 v138, v138, v150
	s_nop 1
	v_add_f32_dpp v138, v138, v138 quad_perm:[1,0,3,2] row_mask:0xf bank_mask:0xf
	s_nop 1
	v_add_f32_dpp v138, v138, v138 quad_perm:[2,3,0,1] row_mask:0xf bank_mask:0xf
	s_nop 1
	v_add_f32_dpp v138, v138, v138 row_half_mirror row_mask:0xf bank_mask:0xf
	s_nop 1
	v_add_f32_dpp v138, v138, v138 row_mirror row_mask:0xf bank_mask:0xf
	v_mov_b32_e32 v139, v138
	s_nop 1
	v_permlane16_swap_b32_e32 v138, v139
	v_add_f32_e32 v138, v138, v139
	v_mov_b32_e32 v139, v138
	s_nop 1
	v_permlane32_swap_b32_e32 v138, v139
	v_add_f32_e32 v138, v138, v139
	v_mul_f32_e32 v138, 0x3a800000, v138
	v_add_f32_e32 v138, 0x358637bd, v138
	v_rsq_f32_e32 v140, v138
	s_nop 0
	v_mul_f32_e32 v120, v0, v140
	v_mul_f32_e32 v121, v1, v140
	v_mul_f32_e32 v122, v2, v140
	v_mul_f32_e32 v123, v3, v140
	v_mul_f32_e32 v124, v4, v140
	v_mul_f32_e32 v125, v5, v140
	v_mul_f32_e32 v126, v6, v140
	v_mul_f32_e32 v127, v7, v140
	v_mul_f32_e32 v128, v8, v140
	v_mul_f32_e32 v129, v9, v140
	v_mul_f32_e32 v130, v10, v140
	v_mul_f32_e32 v131, v11, v140
	v_mul_f32_e32 v132, v12, v140
	v_mul_f32_e32 v133, v13, v140
	v_mul_f32_e32 v134, v14, v140
	v_mul_f32_e32 v135, v15, v140
	v_fma_f32 v120, v120, v88, v104
	v_fma_f32 v121, v121, v89, v105
	v_fma_f32 v122, v122, v90, v106
	v_fma_f32 v123, v123, v91, v107
	v_fma_f32 v124, v124, v92, v108
	v_fma_f32 v125, v125, v93, v109
	v_fma_f32 v126, v126, v94, v110
	v_fma_f32 v127, v127, v95, v111
	v_fma_f32 v128, v128, v96, v112
	v_fma_f32 v129, v129, v97, v113
	v_fma_f32 v130, v130, v98, v114
	v_fma_f32 v131, v131, v99, v115
	v_fma_f32 v132, v132, v100, v116
	v_fma_f32 v133, v133, v101, v117
	v_fma_f32 v134, v134, v102, v118
	v_fma_f32 v135, v135, v103, v119
	v_cvt_pk_bf16_f32 v156, v120, v121
	v_cvt_pk_bf16_f32 v157, v122, v123
	v_cvt_pk_bf16_f32 v158, v124, v125
	v_cvt_pk_bf16_f32 v159, v126, v127
	v_cvt_pk_bf16_f32 v160, v128, v129
	v_cvt_pk_bf16_f32 v161, v130, v131
	v_cvt_pk_bf16_f32 v162, v132, v133
	v_cvt_pk_bf16_f32 v163, v134, v135
	s_lshl_b32 vcc_lo, s19, 11
	s_add_u32 vcc_lo, vcc_lo, 0x3000000
	s_add_u32 s100, s14, vcc_lo
	s_addc_u32 s101, s15, 0
	global_store_dwordx2 v137, v[156:157], s[100:101] offset:0
	global_store_dwordx2 v137, v[158:159], s[100:101] offset:512
	global_store_dwordx2 v137, v[160:161], s[100:101] offset:1024
	global_store_dwordx2 v137, v[162:163], s[100:101] offset:1536
	s_lshl_b32 vcc_lo, s19, 12
	s_add_u32 vcc_lo, vcc_lo, 0x7800000
	s_add_u32 s100, s12, vcc_lo
	s_addc_u32 s101, s13, 0
	global_load_dwordx4 v[0:3], v136, s[100:101] offset:0
	global_load_dwordx4 v[4:7], v136, s[100:101] offset:1024
	global_load_dwordx4 v[8:11], v136, s[100:101] offset:2048
	global_load_dwordx4 v[12:15], v136, s[100:101] offset:3072
	s_lshl_b32 vcc_lo, s19, 11
	s_add_u32 vcc_lo, vcc_lo, 0x3c00000
	s_add_u32 s100, s14, vcc_lo
	s_addc_u32 s101, s15, 0
	global_load_dwordx2 v[48:49], v137, s[100:101] offset:0
	global_load_dwordx2 v[50:51], v137, s[100:101] offset:512
	global_load_dwordx2 v[52:53], v137, s[100:101] offset:1024
	global_load_dwordx2 v[54:55], v137, s[100:101] offset:1536
	v_lshlrev_b32_e32 v120, 16, v56
	v_and_b32_e32 v121, 0xffff0000, v56
	v_lshlrev_b32_e32 v122, 16, v57
	v_and_b32_e32 v123, 0xffff0000, v57
	v_lshlrev_b32_e32 v124, 16, v58
	v_and_b32_e32 v125, 0xffff0000, v58
	v_lshlrev_b32_e32 v126, 16, v59
	v_and_b32_e32 v127, 0xffff0000, v59
	v_lshlrev_b32_e32 v128, 16, v60
	v_and_b32_e32 v129, 0xffff0000, v60
	v_lshlrev_b32_e32 v130, 16, v61
	v_and_b32_e32 v131, 0xffff0000, v61
	v_lshlrev_b32_e32 v132, 16, v62
	v_and_b32_e32 v133, 0xffff0000, v62
	v_lshlrev_b32_e32 v134, 16, v63
	v_and_b32_e32 v135, 0xffff0000, v63
	v_mul_f32_e32 v138, v120, v120
	v_mul_f32_e32 v149, v121, v121
	v_mul_f32_e32 v150, v122, v122
	v_mul_f32_e32 v154, v123, v123
	v_fma_f32 v138, v124, v124, v138
	v_fma_f32 v149, v125, v125, v149
	v_fma_f32 v150, v126, v126, v150
	v_fma_f32 v154, v127, v127, v154
	v_fma_f32 v138, v128, v128, v138
	v_fma_f32 v149, v129, v129, v149
	v_fma_f32 v150, v130, v130, v150
	v_fma_f32 v154, v131, v131, v154
	v_fma_f32 v138, v132, v132, v138
	v_fma_f32 v149, v133, v133, v149
	v_fma_f32 v150, v134, v134, v150
	v_fma_f32 v154, v135, v135, v154
	v_add_f32_e32 v138, v138, v149
	v_add_f32_e32 v150, v150, v154
	v_add_f32_e32 v138, v138, v150
	s_nop 1
	v_add_f32_dpp v138, v138, v138 quad_perm:[1,0,3,2] row_mask:0xf bank_mask:0xf
	s_nop 1
	v_add_f32_dpp v138, v138, v138 quad_perm:[2,3,0,1] row_mask:0xf bank_mask:0xf
; __device__ __forceinline__ void row_phase(const Params& P, int glayer, int layer, int xsrc, bool hasY, int gate_idx, const float* gpost,
;                           int xdst, bool doH, const float* gpre, int sh_idx, int nrows) {
;     ...
;         if (hasY) {
;           float4 yv[4];
;           float ss = 0.f;
; #pragma unroll
;           for (int i = 0; i < 4; ++i) {
;             const uint2 raw = yy[u][i];
;             yv[i].x = bf2f((u16)(raw.x & 0xffff)); yv[i].y = bf2f((u16)(raw.x >> 16));
;             yv[i].z = bf2f((u16)(raw.y & 0xffff)); yv[i].w = bf2f((u16)(raw.y >> 16));
;             ss += yv[i].x * yv[i].x + yv[i].y * yv[i].y + yv[i].z * yv[i].z + yv[i].w * yv[i].w;
;           }
;           ss = wave_sum(ss);
;           const float rstd = __builtin_amdgcn_rsqf(ss * (1.f / 1024.f) + EPSF);
; #pragma unroll
;           for (int i = 0; i < 4; ++i) {
;             const int col = (i * 64 + lane) * 4;
;             const float4 gt = *reinterpret_cast<const float4*>(modg + gate_idx * 1024 + col);
;             const float4 gp = *reinterpret_cast<const float4*>(gpost + col);
;             xv[i].x += gt.x * (yv[i].x * rstd * gp.x); xv[i].y += gt.y * (yv[i].y * rstd * gp.y);
;             xv[i].z += gt.z * (yv[i].z * rstd * gp.z); xv[i].w += gt.w * (yv[i].w * rstd * gp.w);
;           }
;         }
;         if (xdst == 3 || (xdst == 1 && row >= N_X)) {
;           float* xout = (xdst == 3) ? P.out + (long)row * 1024 : P.xc + (long)(row - N_X) * 1024;
; #pragma unroll
;           for (int i = 0; i < 4; ++i) *reinterpret_cast<float4*>(xout + (i * 64 + lane) * 4) = xv[i];
;         } else if (xdst != 0) {
;           u16* xo = ((xdst == 1) ? resA : P.zf) + (long)row * 1024;
; #pragma unroll
;           for (int i = 0; i < 4; ++i) {
;             const unsigned b0 = f2bf(xv[i].x), b1 = f2bf(xv[i].y), b2 = f2bf(xv[i].z), b3 = f2bf(xv[i].w);
;             *reinterpret_cast<uint2*>(xo + (i * 64 + lane) * 4) = make_uint2(b0 | (b1 << 16), b2 | (b3 << 16));
;           }
;         }
;         if (doH) {
;           float ss = 0.f;
; #pragma unroll
;           for (int i = 0; i < 4; ++i) ss += xv[i].x * xv[i].x + xv[i].y * xv[i].y + xv[i].z * xv[i].z + xv[i].w * xv[i].w;
;           ss = wave_sum(ss);
;           const float rstd = __builtin_amdgcn_rsqf(ss * (1.f / 1024.f) + EPSF);
;           u16* h = P.hy + (long)row * 1024;
; #pragma unroll
	s_nop 1
	v_add_f32_dpp v138, v138, v138 row_half_mirror row_mask:0xf bank_mask:0xf
	s_nop 1
	v_add_f32_dpp v138, v138, v138 row_mirror row_mask:0xf bank_mask:0xf
	v_mov_b32_e32 v139, v138
	s_nop 1
	v_permlane16_swap_b32_e32 v138, v139
	v_add_f32_e32 v138, v138, v139
	v_mov_b32_e32 v139, v138
	s_nop 1
	v_permlane32_swap_b32_e32 v138, v139
	v_add_f32_e32 v138, v138, v139
	v_mul_f32_e32 v138, 0x3a800000, v138
	v_add_f32_e32 v138, 0x358637bd, v138
	v_rsq_f32_e32 v140, v138
	s_nop 0
	v_mul_f32_e32 v120, v120, v140
	v_mul_f32_e32 v121, v121, v140
	v_mul_f32_e32 v122, v122, v140
	v_mul_f32_e32 v123, v123, v140
	v_mul_f32_e32 v124, v124, v140
	v_mul_f32_e32 v125, v125, v140
	v_mul_f32_e32 v126, v126, v140
	v_mul_f32_e32 v127, v127, v140
	v_mul_f32_e32 v128, v128, v140
	v_mul_f32_e32 v129, v129, v140
	v_mul_f32_e32 v130, v130, v140
	v_mul_f32_e32 v131, v131, v140
	v_mul_f32_e32 v132, v132, v140
	v_mul_f32_e32 v133, v133, v140
	v_mul_f32_e32 v134, v134, v140
	v_mul_f32_e32 v135, v135, v140
	v_fma_f32 v16, v120, v72, v16
	v_fma_f32 v17, v121, v73, v17
	v_fma_f32 v18, v122, v74, v18
	v_fma_f32 v19, v123, v75, v19
	v_fma_f32 v20, v124, v76, v20
	v_fma_f32 v21, v125, v77, v21
	v_fma_f32 v22, v126, v78, v22
	v_fma_f32 v23, v127, v79, v23
	v_fma_f32 v24, v128, v80, v24
	v_fma_f32 v25, v129, v81, v25
	v_fma_f32 v26, v130, v82, v26
	v_fma_f32 v27, v131, v83, v27
	v_fma_f32 v28, v132, v84, v28
	v_fma_f32 v29, v133, v85, v29
	v_fma_f32 v30, v134, v86, v30
	v_fma_f32 v31, v135, v87, v31
	v_cvt_pk_bf16_f32 v156, v16, v17
	v_cvt_pk_bf16_f32 v157, v18, v19
	v_cvt_pk_bf16_f32 v158, v20, v21
	v_cvt_pk_bf16_f32 v159, v22, v23
	v_cvt_pk_bf16_f32 v160, v24, v25
	v_cvt_pk_bf16_f32 v161, v26, v27
	v_cvt_pk_bf16_f32 v162, v28, v29
	v_cvt_pk_bf16_f32 v163, v30, v31
	s_lshl_b32 vcc_lo, s19, 11
	s_add_u32 vcc_lo, vcc_lo, 0x3400000
	s_add_u32 s100, s16, vcc_lo
	s_addc_u32 s101, s17, 0
	global_store_dwordx2 v137, v[156:157], s[100:101] offset:0
	global_store_dwordx2 v137, v[158:159], s[100:101] offset:512
	global_store_dwordx2 v137, v[160:161], s[100:101] offset:1024
	global_store_dwordx2 v137, v[162:163], s[100:101] offset:1536
	v_mul_f32_e32 v138, v16, v16
	v_mul_f32_e32 v149, v17, v17
	v_mul_f32_e32 v150, v18, v18
	v_mul_f32_e32 v154, v19, v19
	v_fma_f32 v138, v20, v20, v138
	v_fma_f32 v149, v21, v21, v149
	v_fma_f32 v150, v22, v22, v150
	v_fma_f32 v154, v23, v23, v154
	v_fma_f32 v138, v24, v24, v138
	v_fma_f32 v149, v25, v25, v149
	v_fma_f32 v150, v26, v26, v150
	v_fma_f32 v154, v27, v27, v154
	v_fma_f32 v138, v28, v28, v138
	v_fma_f32 v149, v29, v29, v149
	v_fma_f32 v150, v30, v30, v150
	v_fma_f32 v154, v31, v31, v154
	v_add_f32_e32 v138, v138, v149
	v_add_f32_e32 v150, v150, v154
	v_add_f32_e32 v138, v138, v150
	s_nop 1
	v_add_f32_dpp v138, v138, v138 quad_perm:[1,0,3,2] row_mask:0xf bank_mask:0xf
	s_nop 1
	v_add_f32_dpp v138, v138, v138 quad_perm:[2,3,0,1] row_mask:0xf bank_mask:0xf
	s_nop 1
	v_add_f32_dpp v138, v138, v138 row_half_mirror row_mask:0xf bank_mask:0xf
	s_nop 1
	v_add_f32_dpp v138, v138, v138 row_mirror row_mask:0xf bank_mask:0xf
	v_mov_b32_e32 v139, v138
	s_nop 1
	v_permlane16_swap_b32_e32 v138, v139
	v_add_f32_e32 v138, v138, v139
	v_mov_b32_e32 v139, v138
	s_nop 1
	v_permlane32_swap_b32_e32 v138, v139
	v_add_f32_e32 v138, v138, v139
	v_mul_f32_e32 v138, 0x3a800000, v138
	v_add_f32_e32 v138, 0x358637bd, v138
	v_rsq_f32_e32 v140, v138
	s_nop 0
	v_mul_f32_e32 v120, v16, v140
	v_mul_f32_e32 v121, v17, v140
	v_mul_f32_e32 v122, v18, v140
	v_mul_f32_e32 v123, v19, v140
	v_mul_f32_e32 v124, v20, v140
	v_mul_f32_e32 v125, v21, v140
	v_mul_f32_e32 v126, v22, v140
	v_mul_f32_e32 v127, v23, v140
	v_mul_f32_e32 v128, v24, v140
	v_mul_f32_e32 v129, v25, v140
	v_mul_f32_e32 v130, v26, v140
	v_mul_f32_e32 v131, v27, v140
	v_mul_f32_e32 v132, v28, v140
	v_mul_f32_e32 v133, v29, v140
	v_mul_f32_e32 v134, v30, v140
	v_mul_f32_e32 v135, v31, v140
	v_fma_f32 v120, v120, v88, v104
	v_fma_f32 v121, v121, v89, v105
	v_fma_f32 v122, v122, v90, v106
	v_fma_f32 v123, v123, v91, v107
	v_fma_f32 v124, v124, v92, v108
	v_fma_f32 v125, v125, v93, v109
	v_fma_f32 v126, v126, v94, v110
	v_fma_f32 v127, v127, v95, v111
	v_fma_f32 v128, v128, v96, v112
	v_fma_f32 v129, v129, v97, v113
	v_fma_f32 v130, v130, v98, v114
	v_fma_f32 v131, v131, v99, v115
	v_fma_f32 v132, v132, v100, v116
	v_fma_f32 v133, v133, v101, v117
	v_fma_f32 v134, v134, v102, v118
	v_fma_f32 v135, v135, v103, v119
	v_cvt_pk_bf16_f32 v156, v120, v121
	v_cvt_pk_bf16_f32 v157, v122, v123
	v_cvt_pk_bf16_f32 v158, v124, v125
	v_cvt_pk_bf16_f32 v159, v126, v127
	v_cvt_pk_bf16_f32 v160, v128, v129
	v_cvt_pk_bf16_f32 v161, v130, v131
	v_cvt_pk_bf16_f32 v162, v132, v133
	v_cvt_pk_bf16_f32 v163, v134, v135
	s_lshl_b32 vcc_lo, s19, 11
	s_add_u32 vcc_lo, vcc_lo, 0x3400000
	s_add_u32 s100, s14, vcc_lo
	s_addc_u32 s101, s15, 0
	global_store_dwordx2 v137, v[156:157], s[100:101] offset:0
	global_store_dwordx2 v137, v[158:159], s[100:101] offset:512
	global_store_dwordx2 v137, v[160:161], s[100:101] offset:1024
	global_store_dwordx2 v137, v[162:163], s[100:101] offset:1536
	s_waitcnt vmcnt(24)
; __device__ __forceinline__ void row_phase(const Params& P, int glayer, int layer, int xsrc, bool hasY, int gate_idx, const float* gpost,
;                           int xdst, bool doH, const float* gpre, int sh_idx, int nrows) {
;     ...
;         if (hasY) {
;           float4 yv[4];
;           float ss = 0.f;
; #pragma unroll
;           for (int i = 0; i < 4; ++i) {
;             const uint2 raw = yy[u][i];
;             yv[i].x = bf2f((u16)(raw.x & 0xffff)); yv[i].y = bf2f((u16)(raw.x >> 16));
;             yv[i].z = bf2f((u16)(raw.y & 0xffff)); yv[i].w = bf2f((u16)(raw.y >> 16));
;             ss += yv[i].x * yv[i].x + yv[i].y * yv[i].y + yv[i].z * yv[i].z + yv[i].w * yv[i].w;
;           }
;           ss = wave_sum(ss);
;           const float rstd = __builtin_amdgcn_rsqf(ss * (1.f / 1024.f) + EPSF);
; #pragma unroll
;           for (int i = 0; i < 4; ++i) {
;             const int col = (i * 64 + lane) * 4;
;             const float4 gt = *reinterpret_cast<const float4*>(modg + gate_idx * 1024 + col);
;             const float4 gp = *reinterpret_cast<const float4*>(gpost + col);
;             xv[i].x += gt.x * (yv[i].x * rstd * gp.x); xv[i].y += gt.y * (yv[i].y * rstd * gp.y);
;             xv[i].z += gt.z * (yv[i].z * rstd * gp.z); xv[i].w += gt.w * (yv[i].w * rstd * gp.w);
;           }
;         }
;         if (xdst == 3 || (xdst == 1 && row >= N_X)) {
;           float* xout = (xdst == 3) ? P.out + (long)row * 1024 : P.xc + (long)(row - N_X) * 1024;
; #pragma unroll
;           for (int i = 0; i < 4; ++i) *reinterpret_cast<float4*>(xout + (i * 64 + lane) * 4) = xv[i];
;         } else if (xdst != 0) {
;           u16* xo = ((xdst == 1) ? resA : P.zf) + (long)row * 1024;
; #pragma unroll
;           for (int i = 0; i < 4; ++i) {
;             const unsigned b0 = f2bf(xv[i].x), b1 = f2bf(xv[i].y), b2 = f2bf(xv[i].z), b3 = f2bf(xv[i].w);
;             *reinterpret_cast<uint2*>(xo + (i * 64 + lane) * 4) = make_uint2(b0 | (b1 << 16), b2 | (b3 << 16));
;           }
;         }
;         if (doH) {
;           float ss = 0.f;
; #pragma unroll
;           for (int i = 0; i < 4; ++i) ss += xv[i].x * xv[i].x + xv[i].y * xv[i].y + xv[i].z * xv[i].z + xv[i].w * xv[i].w;
;           ss = wave_sum(ss);
;           const float rstd = __builtin_amdgcn_rsqf(ss * (1.f / 1024.f) + EPSF);
;           u16* h = P.hy + (long)row * 1024;
; #pragma unroll
	v_lshlrev_b32_e32 v120, 16, v64
	v_and_b32_e32 v121, 0xffff0000, v64
	v_lshlrev_b32_e32 v122, 16, v65
	v_and_b32_e32 v123, 0xffff0000, v65
	v_lshlrev_b32_e32 v124, 16, v66
	v_and_b32_e32 v125, 0xffff0000, v66
	v_lshlrev_b32_e32 v126, 16, v67
	v_and_b32_e32 v127, 0xffff0000, v67
	v_lshlrev_b32_e32 v128, 16, v68
	v_and_b32_e32 v129, 0xffff0000, v68
	v_lshlrev_b32_e32 v130, 16, v69
	v_and_b32_e32 v131, 0xffff0000, v69
	v_lshlrev_b32_e32 v132, 16, v70
	v_and_b32_e32 v133, 0xffff0000, v70
	v_lshlrev_b32_e32 v134, 16, v71
	v_and_b32_e32 v135, 0xffff0000, v71
	v_mul_f32_e32 v138, v120, v120
	v_mul_f32_e32 v149, v121, v121
	v_mul_f32_e32 v150, v122, v122
	v_mul_f32_e32 v154, v123, v123
	v_fma_f32 v138, v124, v124, v138
	v_fma_f32 v149, v125, v125, v149
	v_fma_f32 v150, v126, v126, v150
	v_fma_f32 v154, v127, v127, v154
	v_fma_f32 v138, v128, v128, v138
	v_fma_f32 v149, v129, v129, v149
	v_fma_f32 v150, v130, v130, v150
	v_fma_f32 v154, v131, v131, v154
	v_fma_f32 v138, v132, v132, v138
	v_fma_f32 v149, v133, v133, v149
	v_fma_f32 v150, v134, v134, v150
	v_fma_f32 v154, v135, v135, v154
	v_add_f32_e32 v138, v138, v149
	v_add_f32_e32 v150, v150, v154
	v_add_f32_e32 v138, v138, v150
	s_nop 1
	v_add_f32_dpp v138, v138, v138 quad_perm:[1,0,3,2] row_mask:0xf bank_mask:0xf
	s_nop 1
	v_add_f32_dpp v138, v138, v138 quad_perm:[2,3,0,1] row_mask:0xf bank_mask:0xf
	s_nop 1
	v_add_f32_dpp v138, v138, v138 row_half_mirror row_mask:0xf bank_mask:0xf
	s_nop 1
	v_add_f32_dpp v138, v138, v138 row_mirror row_mask:0xf bank_mask:0xf
	v_mov_b32_e32 v139, v138
	s_nop 1
	v_permlane16_swap_b32_e32 v138, v139
	v_add_f32_e32 v138, v138, v139
	v_mov_b32_e32 v139, v138
	s_nop 1
	v_permlane32_swap_b32_e32 v138, v139
	v_add_f32_e32 v138, v138, v139
	v_mul_f32_e32 v138, 0x3a800000, v138
	v_add_f32_e32 v138, 0x358637bd, v138
	v_rsq_f32_e32 v140, v138
	s_nop 0
	v_mul_f32_e32 v120, v120, v140
	v_mul_f32_e32 v121, v121, v140
	v_mul_f32_e32 v122, v122, v140
	v_mul_f32_e32 v123, v123, v140
	v_mul_f32_e32 v124, v124, v140
	v_mul_f32_e32 v125, v125, v140
	v_mul_f32_e32 v126, v126, v140
	v_mul_f32_e32 v127, v127, v140
	v_mul_f32_e32 v128, v128, v140
	v_mul_f32_e32 v129, v129, v140
	v_mul_f32_e32 v130, v130, v140
	v_mul_f32_e32 v131, v131, v140
	v_mul_f32_e32 v132, v132, v140
	v_mul_f32_e32 v133, v133, v140
	v_mul_f32_e32 v134, v134, v140
	v_mul_f32_e32 v135, v135, v140
	v_fma_f32 v32, v120, v72, v32
	v_fma_f32 v33, v121, v73, v33
	v_fma_f32 v34, v122, v74, v34
	v_fma_f32 v35, v123, v75, v35
	v_fma_f32 v36, v124, v76, v36
	v_fma_f32 v37, v125, v77, v37
	v_fma_f32 v38, v126, v78, v38
	v_fma_f32 v39, v127, v79, v39
	v_fma_f32 v40, v128, v80, v40
	v_fma_f32 v41, v129, v81, v41
	v_fma_f32 v42, v130, v82, v42
	v_fma_f32 v43, v131, v83, v43
	v_fma_f32 v44, v132, v84, v44
	v_fma_f32 v45, v133, v85, v45
	v_fma_f32 v46, v134, v86, v46
	v_fma_f32 v47, v135, v87, v47
	v_cvt_pk_bf16_f32 v156, v32, v33
	v_cvt_pk_bf16_f32 v157, v34, v35
	v_cvt_pk_bf16_f32 v158, v36, v37
	v_cvt_pk_bf16_f32 v159, v38, v39
	v_cvt_pk_bf16_f32 v160, v40, v41
	v_cvt_pk_bf16_f32 v161, v42, v43
	v_cvt_pk_bf16_f32 v162, v44, v45
	v_cvt_pk_bf16_f32 v163, v46, v47
	s_lshl_b32 vcc_lo, s19, 11
	s_add_u32 vcc_lo, vcc_lo, 0x3800000
	s_add_u32 s100, s16, vcc_lo
	s_addc_u32 s101, s17, 0
	global_store_dwordx2 v137, v[156:157], s[100:101] offset:0
	global_store_dwordx2 v137, v[158:159], s[100:101] offset:512
	global_store_dwordx2 v137, v[160:161], s[100:101] offset:1024
	global_store_dwordx2 v137, v[162:163], s[100:101] offset:1536
	v_mul_f32_e32 v138, v32, v32
	v_mul_f32_e32 v149, v33, v33
	v_mul_f32_e32 v150, v34, v34
	v_mul_f32_e32 v154, v35, v35
	v_fma_f32 v138, v36, v36, v138
	v_fma_f32 v149, v37, v37, v149
	v_fma_f32 v150, v38, v38, v150
	v_fma_f32 v154, v39, v39, v154
	v_fma_f32 v138, v40, v40, v138
	v_fma_f32 v149, v41, v41, v149
	v_fma_f32 v150, v42, v42, v150
	v_fma_f32 v154, v43, v43, v154
	v_fma_f32 v138, v44, v44, v138
	v_fma_f32 v149, v45, v45, v149
	v_fma_f32 v150, v46, v46, v150
	v_fma_f32 v154, v47, v47, v154
	v_add_f32_e32 v138, v138, v149
	v_add_f32_e32 v150, v150, v154
	v_add_f32_e32 v138, v138, v150
	s_nop 1
	v_add_f32_dpp v138, v138, v138 quad_perm:[1,0,3,2] row_mask:0xf bank_mask:0xf
	s_nop 1
	v_add_f32_dpp v138, v138, v138 quad_perm:[2,3,0,1] row_mask:0xf bank_mask:0xf
	s_nop 1
	v_add_f32_dpp v138, v138, v138 row_half_mirror row_mask:0xf bank_mask:0xf
	s_nop 1
	v_add_f32_dpp v138, v138, v138 row_mirror row_mask:0xf bank_mask:0xf
	v_mov_b32_e32 v139, v138
	s_nop 1
	v_permlane16_swap_b32_e32 v138, v139
	v_add_f32_e32 v138, v138, v139
	v_mov_b32_e32 v139, v138
	s_nop 1
	v_permlane32_swap_b32_e32 v138, v139
	v_add_f32_e32 v138, v138, v139
	v_mul_f32_e32 v138, 0x3a800000, v138
	v_add_f32_e32 v138, 0x358637bd, v138
	v_rsq_f32_e32 v140, v138
	s_nop 0
	v_mul_f32_e32 v120, v32, v140
	v_mul_f32_e32 v121, v33, v140
	v_mul_f32_e32 v122, v34, v140
	v_mul_f32_e32 v123, v35, v140
	v_mul_f32_e32 v124, v36, v140
	v_mul_f32_e32 v125, v37, v140
	v_mul_f32_e32 v126, v38, v140
	v_mul_f32_e32 v127, v39, v140
	v_mul_f32_e32 v128, v40, v140
	v_mul_f32_e32 v129, v41, v140
	v_mul_f32_e32 v130, v42, v140
	v_mul_f32_e32 v131, v43, v140
	v_mul_f32_e32 v132, v44, v140
	v_mul_f32_e32 v133, v45, v140
	v_mul_f32_e32 v134, v46, v140
	v_mul_f32_e32 v135, v47, v140
	v_fma_f32 v120, v120, v88, v104
	v_fma_f32 v121, v121, v89, v105
	v_fma_f32 v122, v122, v90, v106
	v_fma_f32 v123, v123, v91, v107
	v_fma_f32 v124, v124, v92, v108
	v_fma_f32 v125, v125, v93, v109
	v_fma_f32 v126, v126, v94, v110
	v_fma_f32 v127, v127, v95, v111
	v_fma_f32 v128, v128, v96, v112
	v_fma_f32 v129, v129, v97, v113
	v_fma_f32 v130, v130, v98, v114
	v_fma_f32 v131, v131, v99, v115
	v_fma_f32 v132, v132, v100, v116
	v_fma_f32 v133, v133, v101, v117
	v_fma_f32 v134, v134, v102, v118
	v_fma_f32 v135, v135, v103, v119
	v_cvt_pk_bf16_f32 v156, v120, v121
	v_cvt_pk_bf16_f32 v157, v122, v123
	v_cvt_pk_bf16_f32 v158, v124, v125
	v_cvt_pk_bf16_f32 v159, v126, v127
	v_cvt_pk_bf16_f32 v160, v128, v129
	v_cvt_pk_bf16_f32 v161, v130, v131
	v_cvt_pk_bf16_f32 v162, v132, v133
	v_cvt_pk_bf16_f32 v163, v134, v135
	s_lshl_b32 vcc_lo, s19, 11
	s_add_u32 vcc_lo, vcc_lo, 0x3800000
	s_add_u32 s100, s14, vcc_lo
	s_addc_u32 s101, s15, 0
	global_store_dwordx2 v137, v[156:157], s[100:101] offset:0
	global_store_dwordx2 v137, v[158:159], s[100:101] offset:512
	global_store_dwordx2 v137, v[160:161], s[100:101] offset:1024
	global_store_dwordx2 v137, v[162:163], s[100:101] offset:1536
	s_waitcnt vmcnt(16)
; __device__ __forceinline__ void row_phase(const Params& P, int glayer, int layer, int xsrc, bool hasY, int gate_idx, const float* gpost,
;                           int xdst, bool doH, const float* gpre, int sh_idx, int nrows) {
;     ...
;         if (hasY) {
;           float4 yv[4];
;           float ss = 0.f;
; #pragma unroll
;           for (int i = 0; i < 4; ++i) {
;             const uint2 raw = yy[u][i];
;             yv[i].x = bf2f((u16)(raw.x & 0xffff)); yv[i].y = bf2f((u16)(raw.x >> 16));
;             yv[i].z = bf2f((u16)(raw.y & 0xffff)); yv[i].w = bf2f((u16)(raw.y >> 16));
;             ss += yv[i].x * yv[i].x + yv[i].y * yv[i].y + yv[i].z * yv[i].z + yv[i].w * yv[i].w;
;           }
;           ss = wave_sum(ss);
;           const float rstd = __builtin_amdgcn_rsqf(ss * (1.f / 1024.f) + EPSF);
; #pragma unroll
;           for (int i = 0; i < 4; ++i) {
;             const int col = (i * 64 + lane) * 4;
;             const float4 gt = *reinterpret_cast<const float4*>(modg + gate_idx * 1024 + col);
;             const float4 gp = *reinterpret_cast<const float4*>(gpost + col);
;             xv[i].x += gt.x * (yv[i].x * rstd * gp.x); xv[i].y += gt.y * (yv[i].y * rstd * gp.y);
;             xv[i].z += gt.z * (yv[i].z * rstd * gp.z); xv[i].w += gt.w * (yv[i].w * rstd * gp.w);
;           }
;         }
;         if (xdst == 3 || (xdst == 1 && row >= N_X)) {
;           float* xout = (xdst == 3) ? P.out + (long)row * 1024 : P.xc + (long)(row - N_X) * 1024;
; #pragma unroll
;           for (int i = 0; i < 4; ++i) *reinterpret_cast<float4*>(xout + (i * 64 + lane) * 4) = xv[i];
;         } else if (xdst != 0) {
;           u16* xo = ((xdst == 1) ? resA : P.zf) + (long)row * 1024;
; #pragma unroll
;           for (int i = 0; i < 4; ++i) {
;             const unsigned b0 = f2bf(xv[i].x), b1 = f2bf(xv[i].y), b2 = f2bf(xv[i].z), b3 = f2bf(xv[i].w);
;             *reinterpret_cast<uint2*>(xo + (i * 64 + lane) * 4) = make_uint2(b0 | (b1 << 16), b2 | (b3 << 16));
;           }
;         }
;         if (doH) {
;           float ss = 0.f;
; #pragma unroll
;           for (int i = 0; i < 4; ++i) ss += xv[i].x * xv[i].x + xv[i].y * xv[i].y + xv[i].z * xv[i].z + xv[i].w * xv[i].w;
;           ss = wave_sum(ss);
;           const float rstd = __builtin_amdgcn_rsqf(ss * (1.f / 1024.f) + EPSF);
;           u16* h = P.hy + (long)row * 1024;
; #pragma unroll
	v_lshlrev_b32_e32 v120, 16, v48
	v_and_b32_e32 v121, 0xffff0000, v48
	v_lshlrev_b32_e32 v122, 16, v49
	v_and_b32_e32 v123, 0xffff0000, v49
	v_lshlrev_b32_e32 v124, 16, v50
	v_and_b32_e32 v125, 0xffff0000, v50
	v_lshlrev_b32_e32 v126, 16, v51
	v_and_b32_e32 v127, 0xffff0000, v51
	v_lshlrev_b32_e32 v128, 16, v52
	v_and_b32_e32 v129, 0xffff0000, v52
	v_lshlrev_b32_e32 v130, 16, v53
	v_and_b32_e32 v131, 0xffff0000, v53
	v_lshlrev_b32_e32 v132, 16, v54
	v_and_b32_e32 v133, 0xffff0000, v54
	v_lshlrev_b32_e32 v134, 16, v55
	v_and_b32_e32 v135, 0xffff0000, v55
	v_mul_f32_e32 v138, v120, v120
	v_mul_f32_e32 v149, v121, v121
	v_mul_f32_e32 v150, v122, v122
	v_mul_f32_e32 v154, v123, v123
	v_fma_f32 v138, v124, v124, v138
	v_fma_f32 v149, v125, v125, v149
	v_fma_f32 v150, v126, v126, v150
	v_fma_f32 v154, v127, v127, v154
	v_fma_f32 v138, v128, v128, v138
	v_fma_f32 v149, v129, v129, v149
	v_fma_f32 v150, v130, v130, v150
	v_fma_f32 v154, v131, v131, v154
	v_fma_f32 v138, v132, v132, v138
	v_fma_f32 v149, v133, v133, v149
	v_fma_f32 v150, v134, v134, v150
	v_fma_f32 v154, v135, v135, v154
	v_add_f32_e32 v138, v138, v149
	v_add_f32_e32 v150, v150, v154
	v_add_f32_e32 v138, v138, v150
	s_nop 1
	v_add_f32_dpp v138, v138, v138 quad_perm:[1,0,3,2] row_mask:0xf bank_mask:0xf
	s_nop 1
	v_add_f32_dpp v138, v138, v138 quad_perm:[2,3,0,1] row_mask:0xf bank_mask:0xf
	s_nop 1
	v_add_f32_dpp v138, v138, v138 row_half_mirror row_mask:0xf bank_mask:0xf
	s_nop 1
	v_add_f32_dpp v138, v138, v138 row_mirror row_mask:0xf bank_mask:0xf
	v_mov_b32_e32 v139, v138
	s_nop 1
	v_permlane16_swap_b32_e32 v138, v139
	v_add_f32_e32 v138, v138, v139
	v_mov_b32_e32 v139, v138
	s_nop 1
	v_permlane32_swap_b32_e32 v138, v139
	v_add_f32_e32 v138, v138, v139
	v_mul_f32_e32 v138, 0x3a800000, v138
	v_add_f32_e32 v138, 0x358637bd, v138
	v_rsq_f32_e32 v140, v138
	s_nop 0
	v_mul_f32_e32 v120, v120, v140
	v_mul_f32_e32 v121, v121, v140
	v_mul_f32_e32 v122, v122, v140
	v_mul_f32_e32 v123, v123, v140
	v_mul_f32_e32 v124, v124, v140
	v_mul_f32_e32 v125, v125, v140
	v_mul_f32_e32 v126, v126, v140
	v_mul_f32_e32 v127, v127, v140
	v_mul_f32_e32 v128, v128, v140
	v_mul_f32_e32 v129, v129, v140
	v_mul_f32_e32 v130, v130, v140
	v_mul_f32_e32 v131, v131, v140
	v_mul_f32_e32 v132, v132, v140
	v_mul_f32_e32 v133, v133, v140
	v_mul_f32_e32 v134, v134, v140
	v_mul_f32_e32 v135, v135, v140
	v_fma_f32 v0, v120, v72, v0
	v_fma_f32 v1, v121, v73, v1
	v_fma_f32 v2, v122, v74, v2
	v_fma_f32 v3, v123, v75, v3
	v_fma_f32 v4, v124, v76, v4
	v_fma_f32 v5, v125, v77, v5
	v_fma_f32 v6, v126, v78, v6
	v_fma_f32 v7, v127, v79, v7
	v_fma_f32 v8, v128, v80, v8
	v_fma_f32 v9, v129, v81, v9
	v_fma_f32 v10, v130, v82, v10
	v_fma_f32 v11, v131, v83, v11
	v_fma_f32 v12, v132, v84, v12
	v_fma_f32 v13, v133, v85, v13
	v_fma_f32 v14, v134, v86, v14
	v_fma_f32 v15, v135, v87, v15
	v_cvt_pk_bf16_f32 v156, v0, v1
	v_cvt_pk_bf16_f32 v157, v2, v3
	v_cvt_pk_bf16_f32 v158, v4, v5
	v_cvt_pk_bf16_f32 v159, v6, v7
	v_cvt_pk_bf16_f32 v160, v8, v9
	v_cvt_pk_bf16_f32 v161, v10, v11
	v_cvt_pk_bf16_f32 v162, v12, v13
	v_cvt_pk_bf16_f32 v163, v14, v15
	s_lshl_b32 vcc_lo, s19, 11
	s_add_u32 vcc_lo, vcc_lo, 0x3c00000
	s_add_u32 s100, s16, vcc_lo
	s_addc_u32 s101, s17, 0
	global_store_dwordx2 v137, v[156:157], s[100:101] offset:0
	global_store_dwordx2 v137, v[158:159], s[100:101] offset:512
	global_store_dwordx2 v137, v[160:161], s[100:101] offset:1024
	global_store_dwordx2 v137, v[162:163], s[100:101] offset:1536
	v_mul_f32_e32 v138, v0, v0
	v_mul_f32_e32 v149, v1, v1
	v_mul_f32_e32 v150, v2, v2
	v_mul_f32_e32 v154, v3, v3
	v_fma_f32 v138, v4, v4, v138
	v_fma_f32 v149, v5, v5, v149
	v_fma_f32 v150, v6, v6, v150
	v_fma_f32 v154, v7, v7, v154
	v_fma_f32 v138, v8, v8, v138
	v_fma_f32 v149, v9, v9, v149
	v_fma_f32 v150, v10, v10, v150
	v_fma_f32 v154, v11, v11, v154
	v_fma_f32 v138, v12, v12, v138
	v_fma_f32 v149, v13, v13, v149
	v_fma_f32 v150, v14, v14, v150
	v_fma_f32 v154, v15, v15, v154
	v_add_f32_e32 v138, v138, v149
	v_add_f32_e32 v150, v150, v154
	v_add_f32_e32 v138, v138, v150
	s_nop 1
	v_add_f32_dpp v138, v138, v138 quad_perm:[1,0,3,2] row_mask:0xf bank_mask:0xf
	s_nop 1
	v_add_f32_dpp v138, v138, v138 quad_perm:[2,3,0,1] row_mask:0xf bank_mask:0xf
	s_nop 1
	v_add_f32_dpp v138, v138, v138 row_half_mirror row_mask:0xf bank_mask:0xf
	s_nop 1
	v_add_f32_dpp v138, v138, v138 row_mirror row_mask:0xf bank_mask:0xf
	v_mov_b32_e32 v139, v138
	s_nop 1
	v_permlane16_swap_b32_e32 v138, v139
	v_add_f32_e32 v138, v138, v139
	v_mov_b32_e32 v139, v138
	s_nop 1
	v_permlane32_swap_b32_e32 v138, v139
	v_add_f32_e32 v138, v138, v139
	v_mul_f32_e32 v138, 0x3a800000, v138
	v_add_f32_e32 v138, 0x358637bd, v138
	v_rsq_f32_e32 v140, v138
	s_nop 0
	v_mul_f32_e32 v120, v0, v140
	v_mul_f32_e32 v121, v1, v140
	v_mul_f32_e32 v122, v2, v140
	v_mul_f32_e32 v123, v3, v140
	v_mul_f32_e32 v124, v4, v140
	v_mul_f32_e32 v125, v5, v140
	v_mul_f32_e32 v126, v6, v140
	v_mul_f32_e32 v127, v7, v140
	v_mul_f32_e32 v128, v8, v140
	v_mul_f32_e32 v129, v9, v140
	v_mul_f32_e32 v130, v10, v140
	v_mul_f32_e32 v131, v11, v140
	v_mul_f32_e32 v132, v12, v140
	v_mul_f32_e32 v133, v13, v140
	v_mul_f32_e32 v134, v14, v140
	v_mul_f32_e32 v135, v15, v140
	v_fma_f32 v120, v120, v88, v104
	v_fma_f32 v121, v121, v89, v105
	v_fma_f32 v122, v122, v90, v106
	v_fma_f32 v123, v123, v91, v107
	v_fma_f32 v124, v124, v92, v108
	v_fma_f32 v125, v125, v93, v109
	v_fma_f32 v126, v126, v94, v110
	v_fma_f32 v127, v127, v95, v111
	v_fma_f32 v128, v128, v96, v112
	v_fma_f32 v129, v129, v97, v113
	v_fma_f32 v130, v130, v98, v114
	v_fma_f32 v131, v131, v99, v115
	v_fma_f32 v132, v132, v100, v116
	v_fma_f32 v133, v133, v101, v117
	v_fma_f32 v134, v134, v102, v118
	v_fma_f32 v135, v135, v103, v119
	v_cvt_pk_bf16_f32 v156, v120, v121
	v_cvt_pk_bf16_f32 v157, v122, v123
	v_cvt_pk_bf16_f32 v158, v124, v125
	v_cvt_pk_bf16_f32 v159, v126, v127
	v_cvt_pk_bf16_f32 v160, v128, v129
	v_cvt_pk_bf16_f32 v161, v130, v131
	v_cvt_pk_bf16_f32 v162, v132, v133
	v_cvt_pk_bf16_f32 v163, v134, v135
	s_lshl_b32 vcc_lo, s19, 11
	s_add_u32 vcc_lo, vcc_lo, 0x3c00000
	s_add_u32 s100, s14, vcc_lo
	s_addc_u32 s101, s15, 0
	global_store_dwordx2 v137, v[156:157], s[100:101] offset:0
	global_store_dwordx2 v137, v[158:159], s[100:101] offset:512
	global_store_dwordx2 v137, v[160:161], s[100:101] offset:1024
	global_store_dwordx2 v137, v[162:163], s[100:101] offset:1536
	s_waitcnt vmcnt(0)
	s_cmp_lt_u32 s19, 0x400
	s_cbranch_scc0 .Lmy_r7_done
; __device__ __forceinline__ void row_phase(const Params& P, int glayer, int layer, int xsrc, bool hasY, int gate_idx, const float* gpost,
;                           int xdst, bool doH, const float* gpre, int sh_idx, int nrows) {
;     ...
;           const float* xin_;
;           if (xsrc == 0) xin_ = R < N_X ? P.x + (long)R * 1024 : P.ctx + (long)(R - N_X) * 1024;
;           else           xin_ = P.xc + (long)(R - N_X) * 1024;
; #pragma unroll
;           for (int i = 0; i < 4; ++i) xr[u][i] = *reinterpret_cast<const uint4*>(xin_ + (i * 64 + lane) * 4);
;         }
;         if (hasY) {
;           const u16* y_ = P.hy + (long)R * 1024;
; #pragma unroll
;           for (int i = 0; i < 4; ++i) yy[u][i] = *reinterpret_cast<const uint2*>(y_ + (i * 64 + lane) * 4);
;         }
;       }
;     }
; #pragma unroll
;     for (int u = 0; u < 4; ++u) {
;       const int row = rb + u * stride;
;       if (row < nrows) {
;         const int mi = row < N_X ? (row >> 13) : 4;
;         const float* modp = P.mod + (long)(layer * 5 + mi) * 6144;
;         const float* modg = P.mod + (long)(glayer * 5 + mi) * 6144;
;         float4 xv[4];
;         if (xsrc != 0 && row < N_X) {
; #pragma unroll
;           for (int i = 0; i < 4; ++i) {
;             const uint4 raw = xr[u][i];
;             xv[i].x = bf2f((u16)(raw.x & 0xffff)); xv[i].y = bf2f((u16)(raw.x >> 16));
;             xv[i].z = bf2f((u16)(raw.y & 0xffff)); xv[i].w = bf2f((u16)(raw.y >> 16));
;           }
;         } else {
; #pragma unroll
;           for (int i = 0; i < 4; ++i) {
;             xv[i].x = __uint_as_float(xr[u][i].x); xv[i].y = __uint_as_float(xr[u][i].y);
;             xv[i].z = __uint_as_float(xr[u][i].z); xv[i].w = __uint_as_float(xr[u][i].w);
;           }
;         }
;         if (hasY) {
;           float4 yv[4];
;           float ss = 0.f;
; #pragma unroll
;           for (int i = 0; i < 4; ++i) {
;             const uint2 raw = yy[u][i];
;             yv[i].x = bf2f((u16)(raw.x & 0xffff)); yv[i].y = bf2f((u16)(raw.x >> 16));
;             yv[i].z = bf2f((u16)(raw.y & 0xffff)); yv[i].w = bf2f((u16)(raw.y >> 16));
;             ss += yv[i].x * yv[i].x + yv[i].y * yv[i].y + yv[i].z * yv[i].z + yv[i].w * yv[i].w;
;           }
;           ss = wave_sum(ss);
;           const float rstd = __builtin_amdgcn_rsqf(ss * (1.f / 1024.f) + EPSF);
; #pragma unroll
;           for (int i = 0; i < 4; ++i) {
	s_load_dwordx2 s[12:13], s[4:5], 0x10
	s_waitcnt lgkmcnt(0)
	s_add_u32 s100, s20, 0x1a000
	s_addc_u32 s101, s21, 0
	global_load_dwordx4 v[72:75], v136, s[100:101] offset:0
	global_load_dwordx4 v[76:79], v136, s[100:101] offset:1024
	global_load_dwordx4 v[80:83], v136, s[100:101] offset:2048
	global_load_dwordx4 v[84:87], v136, s[100:101] offset:3072
	s_load_dwordx2 s[98:99], s[4:5], 0x38
	s_waitcnt lgkmcnt(0)
	global_load_dwordx4 v[120:123], v136, s[98:99] offset:0
	global_load_dwordx4 v[124:127], v136, s[98:99] offset:1024
	global_load_dwordx4 v[128:131], v136, s[98:99] offset:2048
	global_load_dwordx4 v[132:135], v136, s[98:99] offset:3072
	s_add_u32 s100, s20, 0x1b000
	s_addc_u32 s101, s21, 0
	global_load_dwordx4 v[104:107], v136, s[100:101] offset:0
	global_load_dwordx4 v[108:111], v136, s[100:101] offset:1024
	global_load_dwordx4 v[112:115], v136, s[100:101] offset:2048
	global_load_dwordx4 v[116:119], v136, s[100:101] offset:3072
	s_add_u32 s100, s100, 0x1000
	s_addc_u32 s101, s101, 0
	global_load_dwordx4 v[16:19], v136, s[100:101] offset:0
	global_load_dwordx4 v[20:23], v136, s[100:101] offset:1024
	global_load_dwordx4 v[24:27], v136, s[100:101] offset:2048
	global_load_dwordx4 v[28:31], v136, s[100:101] offset:3072
	s_load_dwordx2 s[98:99], s[4:5], 0x40
	s_waitcnt lgkmcnt(0)
	global_load_dwordx4 v[88:91], v136, s[98:99] offset:0
	global_load_dwordx4 v[92:95], v136, s[98:99] offset:1024
	global_load_dwordx4 v[96:99], v136, s[98:99] offset:2048
	global_load_dwordx4 v[100:103], v136, s[98:99] offset:3072
	s_waitcnt vmcnt(0)
	v_mul_f32_e32 v72, v72, v120
	v_mul_f32_e32 v73, v73, v121
	v_mul_f32_e32 v74, v74, v122
	v_mul_f32_e32 v75, v75, v123
	v_mul_f32_e32 v76, v76, v124
	v_mul_f32_e32 v77, v77, v125
	v_mul_f32_e32 v78, v78, v126
	v_mul_f32_e32 v79, v79, v127
	v_mul_f32_e32 v80, v80, v128
	v_mul_f32_e32 v81, v81, v129
	v_mul_f32_e32 v82, v82, v130
	v_mul_f32_e32 v83, v83, v131
	v_mul_f32_e32 v84, v84, v132
	v_mul_f32_e32 v85, v85, v133
	v_mul_f32_e32 v86, v86, v134
	v_mul_f32_e32 v87, v87, v135
	v_fma_f32 v88, v88, v16, v88
	v_fma_f32 v89, v89, v17, v89
	v_fma_f32 v90, v90, v18, v90
	v_fma_f32 v91, v91, v19, v91
	v_fma_f32 v92, v92, v20, v92
	v_fma_f32 v93, v93, v21, v93
	v_fma_f32 v94, v94, v22, v94
	v_fma_f32 v95, v95, v23, v95
	v_fma_f32 v96, v96, v24, v96
	v_fma_f32 v97, v97, v25, v97
	v_fma_f32 v98, v98, v26, v98
	v_fma_f32 v99, v99, v27, v99
	v_fma_f32 v100, v100, v28, v100
	v_fma_f32 v101, v101, v29, v101
	v_fma_f32 v102, v102, v30, v102
	v_fma_f32 v103, v103, v31, v103
	s_lshl_b32 vcc_lo, s19, 12
	s_add_u32 s100, s12, vcc_lo
	s_addc_u32 s101, s13, 0
	global_load_dwordx4 v[0:3], v136, s[100:101] offset:0
	global_load_dwordx4 v[4:7], v136, s[100:101] offset:1024
	global_load_dwordx4 v[8:11], v136, s[100:101] offset:2048
	global_load_dwordx4 v[12:15], v136, s[100:101] offset:3072
	s_lshl_b32 vcc_lo, s19, 11
	s_add_u32 vcc_lo, vcc_lo, 0x4000000
	s_add_u32 s100, s14, vcc_lo
	s_addc_u32 s101, s15, 0
	global_load_dwordx2 v[48:49], v137, s[100:101] offset:0
	global_load_dwordx2 v[50:51], v137, s[100:101] offset:512
	global_load_dwordx2 v[52:53], v137, s[100:101] offset:1024
	global_load_dwordx2 v[54:55], v137, s[100:101] offset:1536
	s_waitcnt vmcnt(0)
	v_lshlrev_b32_e32 v120, 16, v48
	v_and_b32_e32 v121, 0xffff0000, v48
	v_lshlrev_b32_e32 v122, 16, v49
	v_and_b32_e32 v123, 0xffff0000, v49
	v_lshlrev_b32_e32 v124, 16, v50
	v_and_b32_e32 v125, 0xffff0000, v50
	v_lshlrev_b32_e32 v126, 16, v51
	v_and_b32_e32 v127, 0xffff0000, v51
	v_lshlrev_b32_e32 v128, 16, v52
	v_and_b32_e32 v129, 0xffff0000, v52
	v_lshlrev_b32_e32 v130, 16, v53
	v_and_b32_e32 v131, 0xffff0000, v53
	v_lshlrev_b32_e32 v132, 16, v54
	v_and_b32_e32 v133, 0xffff0000, v54
	v_lshlrev_b32_e32 v134, 16, v55
	v_and_b32_e32 v135, 0xffff0000, v55
	v_mul_f32_e32 v138, v120, v120
	v_mul_f32_e32 v149, v121, v121
	v_mul_f32_e32 v150, v122, v122
	v_mul_f32_e32 v154, v123, v123
	v_fma_f32 v138, v124, v124, v138
	v_fma_f32 v149, v125, v125, v149
	v_fma_f32 v150, v126, v126, v150
	v_fma_f32 v154, v127, v127, v154
	v_fma_f32 v138, v128, v128, v138
	v_fma_f32 v149, v129, v129, v149
	v_fma_f32 v150, v130, v130, v150
	v_fma_f32 v154, v131, v131, v154
	v_fma_f32 v138, v132, v132, v138
	v_fma_f32 v149, v133, v133, v149
	v_fma_f32 v150, v134, v134, v150
	v_fma_f32 v154, v135, v135, v154
	v_add_f32_e32 v138, v138, v149
	v_add_f32_e32 v150, v150, v154
	v_add_f32_e32 v138, v138, v150
	s_nop 1
	v_add_f32_dpp v138, v138, v138 quad_perm:[1,0,3,2] row_mask:0xf bank_mask:0xf
	s_nop 1
	v_add_f32_dpp v138, v138, v138 quad_perm:[2,3,0,1] row_mask:0xf bank_mask:0xf
	s_nop 1
	v_add_f32_dpp v138, v138, v138 row_half_mirror row_mask:0xf bank_mask:0xf
	s_nop 1
	v_add_f32_dpp v138, v138, v138 row_mirror row_mask:0xf bank_mask:0xf
	v_mov_b32_e32 v139, v138
	s_nop 1
	v_permlane16_swap_b32_e32 v138, v139
	v_add_f32_e32 v138, v138, v139
	v_mov_b32_e32 v139, v138
	s_nop 1
	v_permlane32_swap_b32_e32 v138, v139
	v_add_f32_e32 v138, v138, v139
	v_mul_f32_e32 v138, 0x3a800000, v138
	v_add_f32_e32 v138, 0x358637bd, v138
	v_rsq_f32_e32 v140, v138
	s_nop 0
	v_mul_f32_e32 v120, v120, v140
	v_mul_f32_e32 v121, v121, v140
	v_mul_f32_e32 v122, v122, v140
	v_mul_f32_e32 v123, v123, v140
	v_mul_f32_e32 v124, v124, v140
	v_mul_f32_e32 v125, v125, v140
	v_mul_f32_e32 v126, v126, v140
	v_mul_f32_e32 v127, v127, v140
	v_mul_f32_e32 v128, v128, v140
	v_mul_f32_e32 v129, v129, v140
	v_mul_f32_e32 v130, v130, v140
	v_mul_f32_e32 v131, v131, v140
	v_mul_f32_e32 v132, v132, v140
	v_mul_f32_e32 v133, v133, v140
	v_mul_f32_e32 v134, v134, v140
	v_mul_f32_e32 v135, v135, v140
	v_fma_f32 v0, v120, v72, v0
	v_fma_f32 v1, v121, v73, v1
	v_fma_f32 v2, v122, v74, v2
	v_fma_f32 v3, v123, v75, v3
	v_fma_f32 v4, v124, v76, v4
	v_fma_f32 v5, v125, v77, v5
	v_fma_f32 v6, v126, v78, v6
	v_fma_f32 v7, v127, v79, v7
	v_fma_f32 v8, v128, v80, v8
	v_fma_f32 v9, v129, v81, v9
	v_fma_f32 v10, v130, v82, v10
	v_fma_f32 v11, v131, v83, v11
	v_fma_f32 v12, v132, v84, v12
	v_fma_f32 v13, v133, v85, v13
	v_fma_f32 v14, v134, v86, v14
	v_fma_f32 v15, v135, v87, v15
	s_load_dwordx2 s[98:99], s[4:5], 0x138
	s_waitcnt lgkmcnt(0)
; __device__ __forceinline__ void row_phase(const Params& P, int glayer, int layer, int xsrc, bool hasY, int gate_idx, const float* gpost,
;                           int xdst, bool doH, const float* gpre, int sh_idx, int nrows) {
;     ...
;         if (xdst == 3 || (xdst == 1 && row >= N_X)) {
;           float* xout = (xdst == 3) ? P.out + (long)row * 1024 : P.xc + (long)(row - N_X) * 1024;
; #pragma unroll
;           for (int i = 0; i < 4; ++i) *reinterpret_cast<float4*>(xout + (i * 64 + lane) * 4) = xv[i];
;         } else if (xdst != 0) {
;           u16* xo = ((xdst == 1) ? resA : P.zf) + (long)row * 1024;
; #pragma unroll
;           for (int i = 0; i < 4; ++i) {
;             const unsigned b0 = f2bf(xv[i].x), b1 = f2bf(xv[i].y), b2 = f2bf(xv[i].z), b3 = f2bf(xv[i].w);
;             *reinterpret_cast<uint2*>(xo + (i * 64 + lane) * 4) = make_uint2(b0 | (b1 << 16), b2 | (b3 << 16));
;           }
;         }
;         if (doH) {
;           float ss = 0.f;
; #pragma unroll
;           for (int i = 0; i < 4; ++i) ss += xv[i].x * xv[i].x + xv[i].y * xv[i].y + xv[i].z * xv[i].z + xv[i].w * xv[i].w;
;           ss = wave_sum(ss);
;           const float rstd = __builtin_amdgcn_rsqf(ss * (1.f / 1024.f) + EPSF);
;           u16* h = P.hy + (long)row * 1024;
; #pragma unroll
;           for (int i = 0; i < 4; ++i) {
;             const int col = (i * 64 + lane) * 4;
;             const float4 g = *reinterpret_cast<const float4*>(gpre + col);
;             const float4 sh = *reinterpret_cast<const float4*>(modp + sh_idx * 1024 + col);
;             const float4 sc = *reinterpret_cast<const float4*>(modp + (sh_idx + 1) * 1024 + col);
;             const unsigned h0 = f2bf(xv[i].x * rstd * g.x * (1.f + sc.x) + sh.x);
;             const unsigned h1 = f2bf(xv[i].y * rstd * g.y * (1.f + sc.y) + sh.y);
;             const unsigned h2 = f2bf(xv[i].z * rstd * g.z * (1.f + sc.z) + sh.z);
;             const unsigned h3 = f2bf(xv[i].w * rstd * g.w * (1.f + sc.w) + sh.w);
;             *reinterpret_cast<uint2*>(h + col) = make_uint2(h0 | (h1 << 16), h2 | (h3 << 16));
;           }
;         }
	s_lshl_b32 vcc_lo, s19, 12
	s_add_u32 s100, s98, vcc_lo
	s_addc_u32 s101, s99, 0
	global_store_dwordx4 v136, v[0:3], s[100:101] offset:0
	global_store_dwordx4 v136, v[4:7], s[100:101] offset:1024
	global_store_dwordx4 v136, v[8:11], s[100:101] offset:2048
	global_store_dwordx4 v136, v[12:15], s[100:101] offset:3072
	v_mul_f32_e32 v138, v0, v0
	v_mul_f32_e32 v149, v1, v1
	v_mul_f32_e32 v150, v2, v2
	v_mul_f32_e32 v154, v3, v3
	v_fma_f32 v138, v4, v4, v138
	v_fma_f32 v149, v5, v5, v149
	v_fma_f32 v150, v6, v6, v150
	v_fma_f32 v154, v7, v7, v154
	v_fma_f32 v138, v8, v8, v138
	v_fma_f32 v149, v9, v9, v149
	v_fma_f32 v150, v10, v10, v150
	v_fma_f32 v154, v11, v11, v154
	v_fma_f32 v138, v12, v12, v138
	v_fma_f32 v149, v13, v13, v149
	v_fma_f32 v150, v14, v14, v150
	v_fma_f32 v154, v15, v15, v154
	v_add_f32_e32 v138, v138, v149
	v_add_f32_e32 v150, v150, v154
	v_add_f32_e32 v138, v138, v150
	s_nop 1
	v_add_f32_dpp v138, v138, v138 quad_perm:[1,0,3,2] row_mask:0xf bank_mask:0xf
	s_nop 1
	v_add_f32_dpp v138, v138, v138 quad_perm:[2,3,0,1] row_mask:0xf bank_mask:0xf
	s_nop 1
	v_add_f32_dpp v138, v138, v138 row_half_mirror row_mask:0xf bank_mask:0xf
	s_nop 1
	v_add_f32_dpp v138, v138, v138 row_mirror row_mask:0xf bank_mask:0xf
	v_mov_b32_e32 v139, v138
	s_nop 1
	v_permlane16_swap_b32_e32 v138, v139
	v_add_f32_e32 v138, v138, v139
	v_mov_b32_e32 v139, v138
	s_nop 1
	v_permlane32_swap_b32_e32 v138, v139
	v_add_f32_e32 v138, v138, v139
	v_mul_f32_e32 v138, 0x3a800000, v138
	v_add_f32_e32 v138, 0x358637bd, v138
	v_rsq_f32_e32 v140, v138
	s_nop 0
	v_mul_f32_e32 v120, v0, v140
	v_mul_f32_e32 v121, v1, v140
	v_mul_f32_e32 v122, v2, v140
	v_mul_f32_e32 v123, v3, v140
	v_mul_f32_e32 v124, v4, v140
	v_mul_f32_e32 v125, v5, v140
	v_mul_f32_e32 v126, v6, v140
	v_mul_f32_e32 v127, v7, v140
	v_mul_f32_e32 v128, v8, v140
	v_mul_f32_e32 v129, v9, v140
	v_mul_f32_e32 v130, v10, v140
	v_mul_f32_e32 v131, v11, v140
	v_mul_f32_e32 v132, v12, v140
	v_mul_f32_e32 v133, v13, v140
	v_mul_f32_e32 v134, v14, v140
	v_mul_f32_e32 v135, v15, v140
	v_fma_f32 v120, v120, v88, v104
	v_fma_f32 v121, v121, v89, v105
	v_fma_f32 v122, v122, v90, v106
	v_fma_f32 v123, v123, v91, v107
	v_fma_f32 v124, v124, v92, v108
	v_fma_f32 v125, v125, v93, v109
	v_fma_f32 v126, v126, v94, v110
	v_fma_f32 v127, v127, v95, v111
	v_fma_f32 v128, v128, v96, v112
	v_fma_f32 v129, v129, v97, v113
	v_fma_f32 v130, v130, v98, v114
	v_fma_f32 v131, v131, v99, v115
	v_fma_f32 v132, v132, v100, v116
	v_fma_f32 v133, v133, v101, v117
	v_fma_f32 v134, v134, v102, v118
	v_fma_f32 v135, v135, v103, v119
	v_cvt_pk_bf16_f32 v156, v120, v121
	v_cvt_pk_bf16_f32 v157, v122, v123
	v_cvt_pk_bf16_f32 v158, v124, v125
	v_cvt_pk_bf16_f32 v159, v126, v127
	v_cvt_pk_bf16_f32 v160, v128, v129
	v_cvt_pk_bf16_f32 v161, v130, v131
	v_cvt_pk_bf16_f32 v162, v132, v133
	v_cvt_pk_bf16_f32 v163, v134, v135
	s_lshl_b32 vcc_lo, s19, 11
	s_add_u32 vcc_lo, vcc_lo, 0x4000000
	s_add_u32 s100, s14, vcc_lo
	s_addc_u32 s101, s15, 0
	global_store_dwordx2 v137, v[156:157], s[100:101] offset:0
	global_store_dwordx2 v137, v[158:159], s[100:101] offset:512
	global_store_dwordx2 v137, v[160:161], s[100:101] offset:1024
	global_store_dwordx2 v137, v[162:163], s[100:101] offset:1536

; __device__ __forceinline__ void row_phase(const Params& P, int glayer, int layer, int xsrc, bool hasY, int gate_idx, const float* gpost,
;                           int xdst, bool doH, const float* gpre, int sh_idx, int nrows) {
;     ...
; #pragma unroll
;     for (int u = 0; u < 4; ++u) {
;       const int R = rb + u * stride;
;       if (R < nrows) {
;         if (xsrc != 0 && R < N_X) {
;           const u16* xs_ = ((xsrc == 1) ? resA : P.zf) + (long)R * 1024;
; #pragma unroll
;           for (int i = 0; i < 4; ++i) {
;             const uint2 t2 = *reinterpret_cast<const uint2*>(xs_ + (i * 64 + lane) * 4);
;             xr[u][i].x = t2.x; xr[u][i].y = t2.y;
;           }
;         } else {
;           const float* xin_;
;           if (xsrc == 0) xin_ = R < N_X ? P.x + (long)R * 1024 : P.ctx + (long)(R - N_X) * 1024;
;           else           xin_ = P.xc + (long)(R - N_X) * 1024;
; #pragma unroll
;           for (int i = 0; i < 4; ++i) xr[u][i] = *reinterpret_cast<const uint4*>(xin_ + (i * 64 + lane) * 4);
;         }
;         if (hasY) {
;           const u16* y_ = P.hy + (long)R * 1024;
; #pragma unroll
;           for (int i = 0; i < 4; ++i) yy[u][i] = *reinterpret_cast<const uint2*>(y_ + (i * 64 + lane) * 4);
;         }
;     ...
;           for (int i = 0; i < 4; ++i) {
;             const int col = (i * 64 + lane) * 4;
;             const float4 gt = *reinterpret_cast<const float4*>(modg + gate_idx * 1024 + col);
;             const float4 gp = *reinterpret_cast<const float4*>(gpost + col);
;             xv[i].x += gt.x * (yv[i].x * rstd * gp.x); xv[i].y += gt.y * (yv[i].y * rstd * gp.y);
;             xv[i].z += gt.z * (yv[i].z * rstd * gp.z); xv[i].w += gt.w * (yv[i].w * rstd * gp.w);
;           }
;         }
;         if (xdst == 3 || (xdst == 1 && row >= N_X)) {
;           float* xout = (xdst == 3) ? P.out + (long)row * 1024 : P.xc + (long)(row - N_X) * 1024;
; #pragma unroll
;           for (int i = 0; i < 4; ++i) *reinterpret_cast<float4*>(xout + (i * 64 + lane) * 4) = xv[i];
;         } else if (xdst != 0) {
;           u16* xo = ((xdst == 1) ? resA : P.zf) + (long)row * 1024;
; #pragma unroll
;           for (int i = 0; i < 4; ++i) {
;             const unsigned b0 = f2bf(xv[i].x), b1 = f2bf(xv[i].y), b2 = f2bf(xv[i].z), b3 = f2bf(xv[i].w);
.LBB0_1247:
	s_cmp_gt_i32 s34, 10
	s_cselect_b64 s[0:1], -1, 0
	s_cmp_lt_i32 s35, 11
	s_cselect_b64 s[4:5], -1, 0
	s_or_b64 s[0:1], s[0:1], s[4:5]
	s_and_b64 vcc, exec, s[0:1]
	s_cbranch_vccnz .LBB0_1357
	v_lshl_add_u32 v22, s2, 3, v204
	s_mov_b32 s3, 0x8400
	v_mov_b32_e32 v0, v153
	v_cmp_gt_i32_e32 vcc, s3, v22
	s_and_saveexec_b64 s[10:11], vcc
	s_cbranch_execz .LBB0_1303
	v_readlane_b32 s4, v252, 0
	v_readlane_b32 s5, v252, 1
	v_readfirstlane_b32 s19, v204
	s_nop 3
	s_sub_u32 s4, s4, 0x170
	s_subb_u32 s5, s5, 0
	s_load_dwordx2 s[12:13], s[4:5], 0xc8
	s_load_dwordx2 s[14:15], s[4:5], 0x140
	s_load_dwordx2 s[16:17], s[4:5], 0xc8
	s_load_dwordx2 s[20:21], s[4:5], 0x100
	s_lshl_b32 s98, s2, 3
	s_add_u32 s19, s98, s19
	v_and_b32_e32 v136, 63, v152
	v_lshlrev_b32_e32 v137, 3, v136
	v_lshlrev_b32_e32 v136, 4, v136
	s_waitcnt lgkmcnt(0)
	s_lshl_b32 vcc_lo, s19, 11
	s_add_u32 s100, s12, vcc_lo
	s_addc_u32 s101, s13, 0
	global_load_dwordx2 v[8:9], v137, s[100:101] offset:0
	global_load_dwordx2 v[10:11], v137, s[100:101] offset:512
	global_load_dwordx2 v[12:13], v137, s[100:101] offset:1024
	global_load_dwordx2 v[14:15], v137, s[100:101] offset:1536
	s_lshl_b32 vcc_lo, s19, 11
	s_add_u32 s100, s14, vcc_lo
	s_addc_u32 s101, s15, 0
	global_load_dwordx2 v[48:49], v137, s[100:101] offset:0
	global_load_dwordx2 v[50:51], v137, s[100:101] offset:512
	global_load_dwordx2 v[52:53], v137, s[100:101] offset:1024
	global_load_dwordx2 v[54:55], v137, s[100:101] offset:1536
	s_lshl_b32 vcc_lo, s19, 11
	s_add_u32 vcc_lo, vcc_lo, 0x400000
	s_add_u32 s100, s12, vcc_lo
	s_addc_u32 s101, s13, 0
	global_load_dwordx2 v[24:25], v137, s[100:101] offset:0
	global_load_dwordx2 v[26:27], v137, s[100:101] offset:512
	global_load_dwordx2 v[28:29], v137, s[100:101] offset:1024
	global_load_dwordx2 v[30:31], v137, s[100:101] offset:1536
	s_lshl_b32 vcc_lo, s19, 11
	s_add_u32 vcc_lo, vcc_lo, 0x400000
	s_add_u32 s100, s14, vcc_lo
	s_addc_u32 s101, s15, 0
	global_load_dwordx2 v[56:57], v137, s[100:101] offset:0
	global_load_dwordx2 v[58:59], v137, s[100:101] offset:512
	global_load_dwordx2 v[60:61], v137, s[100:101] offset:1024
	global_load_dwordx2 v[62:63], v137, s[100:101] offset:1536
	s_add_u32 s100, s20, 0x5000
	s_addc_u32 s101, s21, 0
	global_load_dwordx4 v[72:75], v136, s[100:101] offset:0
	global_load_dwordx4 v[76:79], v136, s[100:101] offset:1024
	global_load_dwordx4 v[80:83], v136, s[100:101] offset:2048
	global_load_dwordx4 v[84:87], v136, s[100:101] offset:3072
	s_load_dwordx2 s[98:99], s[4:5], 0x48
	s_waitcnt lgkmcnt(0)
	global_load_dwordx4 v[120:123], v136, s[98:99] offset:0
	global_load_dwordx4 v[124:127], v136, s[98:99] offset:1024
	global_load_dwordx4 v[128:131], v136, s[98:99] offset:2048
	global_load_dwordx4 v[132:135], v136, s[98:99] offset:3072
	s_add_u32 s100, s20, 0x1e000
	s_addc_u32 s101, s21, 0
	global_load_dwordx4 v[104:107], v136, s[100:101] offset:0
	global_load_dwordx4 v[108:111], v136, s[100:101] offset:1024
	global_load_dwordx4 v[112:115], v136, s[100:101] offset:2048
	global_load_dwordx4 v[116:119], v136, s[100:101] offset:3072
	s_add_u32 s100, s100, 0x1000
	s_addc_u32 s101, s101, 0
	global_load_dwordx4 v[32:35], v136, s[100:101] offset:0
	global_load_dwordx4 v[36:39], v136, s[100:101] offset:1024
	global_load_dwordx4 v[40:43], v136, s[100:101] offset:2048
	global_load_dwordx4 v[44:47], v136, s[100:101] offset:3072
	s_load_dwordx2 s[98:99], s[4:5], 0x30
	s_waitcnt lgkmcnt(0)
	s_add_u32 s98, s98, 0x1000
	s_addc_u32 s99, s99, 0
	global_load_dwordx4 v[88:91], v136, s[98:99] offset:0
	global_load_dwordx4 v[92:95], v136, s[98:99] offset:1024
	global_load_dwordx4 v[96:99], v136, s[98:99] offset:2048
	global_load_dwordx4 v[100:103], v136, s[98:99] offset:3072
	s_waitcnt vmcnt(0)
	v_mul_f32_e32 v72, v72, v120
	v_mul_f32_e32 v73, v73, v121
	v_mul_f32_e32 v74, v74, v122
	v_mul_f32_e32 v75, v75, v123
	v_mul_f32_e32 v76, v76, v124
	v_mul_f32_e32 v77, v77, v125
	v_mul_f32_e32 v78, v78, v126
	v_mul_f32_e32 v79, v79, v127
	v_mul_f32_e32 v80, v80, v128
	v_mul_f32_e32 v81, v81, v129
	v_mul_f32_e32 v82, v82, v130
	v_mul_f32_e32 v83, v83, v131
	v_mul_f32_e32 v84, v84, v132
	v_mul_f32_e32 v85, v85, v133
	v_mul_f32_e32 v86, v86, v134
	v_mul_f32_e32 v87, v87, v135
	v_fma_f32 v88, v88, v32, v88
	v_fma_f32 v89, v89, v33, v89
	v_fma_f32 v90, v90, v34, v90
	v_fma_f32 v91, v91, v35, v91
	v_fma_f32 v92, v92, v36, v92
	v_fma_f32 v93, v93, v37, v93
	v_fma_f32 v94, v94, v38, v94
	v_fma_f32 v95, v95, v39, v95
	v_fma_f32 v96, v96, v40, v96
	v_fma_f32 v97, v97, v41, v97
	v_fma_f32 v98, v98, v42, v98
	v_fma_f32 v99, v99, v43, v99
	v_fma_f32 v100, v100, v44, v100
	v_fma_f32 v101, v101, v45, v101
	v_fma_f32 v102, v102, v46, v102
	v_fma_f32 v103, v103, v47, v103
	s_lshl_b32 vcc_lo, s19, 11
	s_add_u32 vcc_lo, vcc_lo, 0x800000
	s_add_u32 s100, s12, vcc_lo
	s_addc_u32 s101, s13, 0
	global_load_dwordx2 v[40:41], v137, s[100:101] offset:0
	global_load_dwordx2 v[42:43], v137, s[100:101] offset:512
	global_load_dwordx2 v[44:45], v137, s[100:101] offset:1024
	global_load_dwordx2 v[46:47], v137, s[100:101] offset:1536
	s_lshl_b32 vcc_lo, s19, 11
	s_add_u32 vcc_lo, vcc_lo, 0x800000
	s_add_u32 s100, s14, vcc_lo
	s_addc_u32 s101, s15, 0
	global_load_dwordx2 v[64:65], v137, s[100:101] offset:0
	global_load_dwordx2 v[66:67], v137, s[100:101] offset:512
	global_load_dwordx2 v[68:69], v137, s[100:101] offset:1024
	global_load_dwordx2 v[70:71], v137, s[100:101] offset:1536
	v_lshlrev_b32_e32 v120, 16, v48
	v_and_b32_e32 v121, 0xffff0000, v48
	v_lshlrev_b32_e32 v122, 16, v49
	v_and_b32_e32 v123, 0xffff0000, v49
	v_lshlrev_b32_e32 v124, 16, v50
	v_and_b32_e32 v125, 0xffff0000, v50
	v_lshlrev_b32_e32 v126, 16, v51
; __device__ __forceinline__ void row_phase(const Params& P, int glayer, int layer, int xsrc, bool hasY, int gate_idx, const float* gpost,
;                           int xdst, bool doH, const float* gpre, int sh_idx, int nrows) {
;     ...
;         if (hasY) {
;           float4 yv[4];
;           float ss = 0.f;
; #pragma unroll
;           for (int i = 0; i < 4; ++i) {
;             const uint2 raw = yy[u][i];
;             yv[i].x = bf2f((u16)(raw.x & 0xffff)); yv[i].y = bf2f((u16)(raw.x >> 16));
;             yv[i].z = bf2f((u16)(raw.y & 0xffff)); yv[i].w = bf2f((u16)(raw.y >> 16));
;             ss += yv[i].x * yv[i].x + yv[i].y * yv[i].y + yv[i].z * yv[i].z + yv[i].w * yv[i].w;
;           }
;           ss = wave_sum(ss);
;           const float rstd = __builtin_amdgcn_rsqf(ss * (1.f / 1024.f) + EPSF);
; #pragma unroll
;           for (int i = 0; i < 4; ++i) {
;             const int col = (i * 64 + lane) * 4;
;             const float4 gt = *reinterpret_cast<const float4*>(modg + gate_idx * 1024 + col);
;             const float4 gp = *reinterpret_cast<const float4*>(gpost + col);
;             xv[i].x += gt.x * (yv[i].x * rstd * gp.x); xv[i].y += gt.y * (yv[i].y * rstd * gp.y);
;             xv[i].z += gt.z * (yv[i].z * rstd * gp.z); xv[i].w += gt.w * (yv[i].w * rstd * gp.w);
;           }
;         }
;         if (xdst == 3 || (xdst == 1 && row >= N_X)) {
;           float* xout = (xdst == 3) ? P.out + (long)row * 1024 : P.xc + (long)(row - N_X) * 1024;
; #pragma unroll
;           for (int i = 0; i < 4; ++i) *reinterpret_cast<float4*>(xout + (i * 64 + lane) * 4) = xv[i];
;         } else if (xdst != 0) {
;           u16* xo = ((xdst == 1) ? resA : P.zf) + (long)row * 1024;
; #pragma unroll
;           for (int i = 0; i < 4; ++i) {
;             const unsigned b0 = f2bf(xv[i].x), b1 = f2bf(xv[i].y), b2 = f2bf(xv[i].z), b3 = f2bf(xv[i].w);
;             *reinterpret_cast<uint2*>(xo + (i * 64 + lane) * 4) = make_uint2(b0 | (b1 << 16), b2 | (b3 << 16));
;           }
;         }
;         if (doH) {
;           float ss = 0.f;
; #pragma unroll
;           for (int i = 0; i < 4; ++i) ss += xv[i].x * xv[i].x + xv[i].y * xv[i].y + xv[i].z * xv[i].z + xv[i].w * xv[i].w;
;           ss = wave_sum(ss);
;           const float rstd = __builtin_amdgcn_rsqf(ss * (1.f / 1024.f) + EPSF);
;           u16* h = P.hy + (long)row * 1024;
; #pragma unroll
	v_and_b32_e32 v127, 0xffff0000, v51
	v_lshlrev_b32_e32 v128, 16, v52
	v_and_b32_e32 v129, 0xffff0000, v52
	v_lshlrev_b32_e32 v130, 16, v53
	v_and_b32_e32 v131, 0xffff0000, v53
	v_lshlrev_b32_e32 v132, 16, v54
	v_and_b32_e32 v133, 0xffff0000, v54
	v_lshlrev_b32_e32 v134, 16, v55
	v_and_b32_e32 v135, 0xffff0000, v55
	v_mul_f32_e32 v138, v120, v120
	v_mul_f32_e32 v149, v121, v121
	v_mul_f32_e32 v150, v122, v122
	v_mul_f32_e32 v154, v123, v123
	v_fma_f32 v138, v124, v124, v138
	v_fma_f32 v149, v125, v125, v149
	v_fma_f32 v150, v126, v126, v150
	v_fma_f32 v154, v127, v127, v154
	v_fma_f32 v138, v128, v128, v138
	v_fma_f32 v149, v129, v129, v149
	v_fma_f32 v150, v130, v130, v150
	v_fma_f32 v154, v131, v131, v154
	v_fma_f32 v138, v132, v132, v138
	v_fma_f32 v149, v133, v133, v149
	v_fma_f32 v150, v134, v134, v150
	v_fma_f32 v154, v135, v135, v154
	v_add_f32_e32 v138, v138, v149
	v_add_f32_e32 v150, v150, v154
	v_add_f32_e32 v138, v138, v150
	s_nop 1
	v_add_f32_dpp v138, v138, v138 quad_perm:[1,0,3,2] row_mask:0xf bank_mask:0xf
	s_nop 1
	v_add_f32_dpp v138, v138, v138 quad_perm:[2,3,0,1] row_mask:0xf bank_mask:0xf
	s_nop 1
	v_add_f32_dpp v138, v138, v138 row_half_mirror row_mask:0xf bank_mask:0xf
	s_nop 1
	v_add_f32_dpp v138, v138, v138 row_mirror row_mask:0xf bank_mask:0xf
	v_mov_b32_e32 v139, v138
	s_nop 1
	v_permlane16_swap_b32_e32 v138, v139
	v_add_f32_e32 v138, v138, v139
	v_mov_b32_e32 v139, v138
	s_nop 1
	v_permlane32_swap_b32_e32 v138, v139
	v_add_f32_e32 v138, v138, v139
	v_mul_f32_e32 v138, 0x3a800000, v138
	v_add_f32_e32 v138, 0x358637bd, v138
	v_rsq_f32_e32 v140, v138
	v_lshlrev_b32_e32 v0, 16, v8
	v_and_b32_e32 v1, 0xffff0000, v8
	v_lshlrev_b32_e32 v2, 16, v9
	v_and_b32_e32 v3, 0xffff0000, v9
	v_lshlrev_b32_e32 v4, 16, v10
	v_and_b32_e32 v5, 0xffff0000, v10
	v_lshlrev_b32_e32 v6, 16, v11
	v_and_b32_e32 v7, 0xffff0000, v11
	v_lshlrev_b32_e32 v8, 16, v12
	v_and_b32_e32 v9, 0xffff0000, v12
	v_lshlrev_b32_e32 v10, 16, v13
	v_and_b32_e32 v11, 0xffff0000, v13
	v_lshlrev_b32_e32 v12, 16, v14
	v_and_b32_e32 v13, 0xffff0000, v14
	v_lshlrev_b32_e32 v14, 16, v15
	v_and_b32_e32 v15, 0xffff0000, v15
	s_nop 0
	v_mul_f32_e32 v120, v120, v140
	v_mul_f32_e32 v121, v121, v140
	v_mul_f32_e32 v122, v122, v140
	v_mul_f32_e32 v123, v123, v140
	v_mul_f32_e32 v124, v124, v140
	v_mul_f32_e32 v125, v125, v140
	v_mul_f32_e32 v126, v126, v140
	v_mul_f32_e32 v127, v127, v140
	v_mul_f32_e32 v128, v128, v140
	v_mul_f32_e32 v129, v129, v140
	v_mul_f32_e32 v130, v130, v140
	v_mul_f32_e32 v131, v131, v140
	v_mul_f32_e32 v132, v132, v140
	v_mul_f32_e32 v133, v133, v140
	v_mul_f32_e32 v134, v134, v140
	v_mul_f32_e32 v135, v135, v140
	v_fma_f32 v0, v120, v72, v0
	v_fma_f32 v1, v121, v73, v1
	v_fma_f32 v2, v122, v74, v2
	v_fma_f32 v3, v123, v75, v3
	v_fma_f32 v4, v124, v76, v4
	v_fma_f32 v5, v125, v77, v5
	v_fma_f32 v6, v126, v78, v6
	v_fma_f32 v7, v127, v79, v7
	v_fma_f32 v8, v128, v80, v8
	v_fma_f32 v9, v129, v81, v9
	v_fma_f32 v10, v130, v82, v10
	v_fma_f32 v11, v131, v83, v11
	v_fma_f32 v12, v132, v84, v12
	v_fma_f32 v13, v133, v85, v13
	v_fma_f32 v14, v134, v86, v14
	v_fma_f32 v15, v135, v87, v15
	v_cvt_pk_bf16_f32 v156, v0, v1
	v_cvt_pk_bf16_f32 v157, v2, v3
	v_cvt_pk_bf16_f32 v158, v4, v5
	v_cvt_pk_bf16_f32 v159, v6, v7
	v_cvt_pk_bf16_f32 v160, v8, v9
	v_cvt_pk_bf16_f32 v161, v10, v11
	v_cvt_pk_bf16_f32 v162, v12, v13
	v_cvt_pk_bf16_f32 v163, v14, v15
	s_lshl_b32 vcc_lo, s19, 11
	s_add_u32 s100, s16, vcc_lo
	s_addc_u32 s101, s17, 0
	global_store_dwordx2 v137, v[156:157], s[100:101] offset:0
	global_store_dwordx2 v137, v[158:159], s[100:101] offset:512
	global_store_dwordx2 v137, v[160:161], s[100:101] offset:1024
	global_store_dwordx2 v137, v[162:163], s[100:101] offset:1536
	v_mul_f32_e32 v138, v0, v0
	v_mul_f32_e32 v149, v1, v1
	v_mul_f32_e32 v150, v2, v2
	v_mul_f32_e32 v154, v3, v3
	v_fma_f32 v138, v4, v4, v138
	v_fma_f32 v149, v5, v5, v149
	v_fma_f32 v150, v6, v6, v150
	v_fma_f32 v154, v7, v7, v154
	v_fma_f32 v138, v8, v8, v138
	v_fma_f32 v149, v9, v9, v149
	v_fma_f32 v150, v10, v10, v150
	v_fma_f32 v154, v11, v11, v154
	v_fma_f32 v138, v12, v12, v138
	v_fma_f32 v149, v13, v13, v149
	v_fma_f32 v150, v14, v14, v150
	v_fma_f32 v154, v15, v15, v154
	v_add_f32_e32 v138, v138, v149
	v_add_f32_e32 v150, v150, v154
	v_add_f32_e32 v138, v138, v150
	s_nop 1
	v_add_f32_dpp v138, v138, v138 quad_perm:[1,0,3,2] row_mask:0xf bank_mask:0xf
	s_nop 1
	v_add_f32_dpp v138, v138, v138 quad_perm:[2,3,0,1] row_mask:0xf bank_mask:0xf
	s_nop 1
	v_add_f32_dpp v138, v138, v138 row_half_mirror row_mask:0xf bank_mask:0xf
	s_nop 1
	v_add_f32_dpp v138, v138, v138 row_mirror row_mask:0xf bank_mask:0xf
	v_mov_b32_e32 v139, v138
	s_nop 1
	v_permlane16_swap_b32_e32 v138, v139
	v_add_f32_e32 v138, v138, v139
	v_mov_b32_e32 v139, v138
	s_nop 1
	v_permlane32_swap_b32_e32 v138, v139
	v_add_f32_e32 v138, v138, v139
	v_mul_f32_e32 v138, 0x3a800000, v138
	v_add_f32_e32 v138, 0x358637bd, v138
	v_rsq_f32_e32 v140, v138
	s_nop 0
	v_mul_f32_e32 v120, v0, v140
	v_mul_f32_e32 v121, v1, v140
	v_mul_f32_e32 v122, v2, v140
	v_mul_f32_e32 v123, v3, v140
	v_mul_f32_e32 v124, v4, v140
	v_mul_f32_e32 v125, v5, v140
	v_mul_f32_e32 v126, v6, v140
	v_mul_f32_e32 v127, v7, v140
	v_mul_f32_e32 v128, v8, v140
	v_mul_f32_e32 v129, v9, v140
	v_mul_f32_e32 v130, v10, v140
	v_mul_f32_e32 v131, v11, v140
	v_mul_f32_e32 v132, v12, v140
	v_mul_f32_e32 v133, v13, v140
	v_mul_f32_e32 v134, v14, v140
	v_mul_f32_e32 v135, v15, v140
	v_fma_f32 v120, v120, v88, v104
	v_fma_f32 v121, v121, v89, v105
	v_fma_f32 v122, v122, v90, v106
	v_fma_f32 v123, v123, v91, v107
	v_fma_f32 v124, v124, v92, v108
	v_fma_f32 v125, v125, v93, v109
; __device__ __forceinline__ void row_phase(const Params& P, int glayer, int layer, int xsrc, bool hasY, int gate_idx, const float* gpost,
;                           int xdst, bool doH, const float* gpre, int sh_idx, int nrows) {
;     ...
;         if (hasY) {
;           float4 yv[4];
;           float ss = 0.f;
; #pragma unroll
;           for (int i = 0; i < 4; ++i) {
;             const uint2 raw = yy[u][i];
;             yv[i].x = bf2f((u16)(raw.x & 0xffff)); yv[i].y = bf2f((u16)(raw.x >> 16));
;             yv[i].z = bf2f((u16)(raw.y & 0xffff)); yv[i].w = bf2f((u16)(raw.y >> 16));
;             ss += yv[i].x * yv[i].x + yv[i].y * yv[i].y + yv[i].z * yv[i].z + yv[i].w * yv[i].w;
;           }
;           ss = wave_sum(ss);
;           const float rstd = __builtin_amdgcn_rsqf(ss * (1.f / 1024.f) + EPSF);
; #pragma unroll
;           for (int i = 0; i < 4; ++i) {
;             const int col = (i * 64 + lane) * 4;
;             const float4 gt = *reinterpret_cast<const float4*>(modg + gate_idx * 1024 + col);
;             const float4 gp = *reinterpret_cast<const float4*>(gpost + col);
;             xv[i].x += gt.x * (yv[i].x * rstd * gp.x); xv[i].y += gt.y * (yv[i].y * rstd * gp.y);
;             xv[i].z += gt.z * (yv[i].z * rstd * gp.z); xv[i].w += gt.w * (yv[i].w * rstd * gp.w);
;           }
;         }
;         if (xdst == 3 || (xdst == 1 && row >= N_X)) {
;           float* xout = (xdst == 3) ? P.out + (long)row * 1024 : P.xc + (long)(row - N_X) * 1024;
; #pragma unroll
;           for (int i = 0; i < 4; ++i) *reinterpret_cast<float4*>(xout + (i * 64 + lane) * 4) = xv[i];
;         } else if (xdst != 0) {
;           u16* xo = ((xdst == 1) ? resA : P.zf) + (long)row * 1024;
; #pragma unroll
;           for (int i = 0; i < 4; ++i) {
;             const unsigned b0 = f2bf(xv[i].x), b1 = f2bf(xv[i].y), b2 = f2bf(xv[i].z), b3 = f2bf(xv[i].w);
;             *reinterpret_cast<uint2*>(xo + (i * 64 + lane) * 4) = make_uint2(b0 | (b1 << 16), b2 | (b3 << 16));
;           }
;         }
;         if (doH) {
;           float ss = 0.f;
; #pragma unroll
;           for (int i = 0; i < 4; ++i) ss += xv[i].x * xv[i].x + xv[i].y * xv[i].y + xv[i].z * xv[i].z + xv[i].w * xv[i].w;
;           ss = wave_sum(ss);
;           const float rstd = __builtin_amdgcn_rsqf(ss * (1.f / 1024.f) + EPSF);
;           u16* h = P.hy + (long)row * 1024;
; #pragma unroll
	v_fma_f32 v126, v126, v94, v110
	v_fma_f32 v127, v127, v95, v111
	v_fma_f32 v128, v128, v96, v112
	v_fma_f32 v129, v129, v97, v113
	v_fma_f32 v130, v130, v98, v114
	v_fma_f32 v131, v131, v99, v115
	v_fma_f32 v132, v132, v100, v116
	v_fma_f32 v133, v133, v101, v117
	v_fma_f32 v134, v134, v102, v118
	v_fma_f32 v135, v135, v103, v119
	v_cvt_pk_bf16_f32 v156, v120, v121
	v_cvt_pk_bf16_f32 v157, v122, v123
	v_cvt_pk_bf16_f32 v158, v124, v125
	v_cvt_pk_bf16_f32 v159, v126, v127
	v_cvt_pk_bf16_f32 v160, v128, v129
	v_cvt_pk_bf16_f32 v161, v130, v131
	v_cvt_pk_bf16_f32 v162, v132, v133
	v_cvt_pk_bf16_f32 v163, v134, v135
	s_lshl_b32 vcc_lo, s19, 11
	s_add_u32 s100, s14, vcc_lo
	s_addc_u32 s101, s15, 0
	global_store_dwordx2 v137, v[156:157], s[100:101] offset:0
	global_store_dwordx2 v137, v[158:159], s[100:101] offset:512
	global_store_dwordx2 v137, v[160:161], s[100:101] offset:1024
	global_store_dwordx2 v137, v[162:163], s[100:101] offset:1536
	s_lshl_b32 vcc_lo, s19, 11
	s_add_u32 vcc_lo, vcc_lo, 0xc00000
	s_add_u32 s100, s12, vcc_lo
	s_addc_u32 s101, s13, 0
	global_load_dwordx2 v[8:9], v137, s[100:101] offset:0
	global_load_dwordx2 v[10:11], v137, s[100:101] offset:512
	global_load_dwordx2 v[12:13], v137, s[100:101] offset:1024
	global_load_dwordx2 v[14:15], v137, s[100:101] offset:1536
	s_lshl_b32 vcc_lo, s19, 11
	s_add_u32 vcc_lo, vcc_lo, 0xc00000
	s_add_u32 s100, s14, vcc_lo
	s_addc_u32 s101, s15, 0
	global_load_dwordx2 v[48:49], v137, s[100:101] offset:0
	global_load_dwordx2 v[50:51], v137, s[100:101] offset:512
	global_load_dwordx2 v[52:53], v137, s[100:101] offset:1024
	global_load_dwordx2 v[54:55], v137, s[100:101] offset:1536
	v_lshlrev_b32_e32 v120, 16, v56
	v_and_b32_e32 v121, 0xffff0000, v56
	v_lshlrev_b32_e32 v122, 16, v57
	v_and_b32_e32 v123, 0xffff0000, v57
	v_lshlrev_b32_e32 v124, 16, v58
	v_and_b32_e32 v125, 0xffff0000, v58
	v_lshlrev_b32_e32 v126, 16, v59
	v_and_b32_e32 v127, 0xffff0000, v59
	v_lshlrev_b32_e32 v128, 16, v60
	v_and_b32_e32 v129, 0xffff0000, v60
	v_lshlrev_b32_e32 v130, 16, v61
	v_and_b32_e32 v131, 0xffff0000, v61
	v_lshlrev_b32_e32 v132, 16, v62
	v_and_b32_e32 v133, 0xffff0000, v62
	v_lshlrev_b32_e32 v134, 16, v63
	v_and_b32_e32 v135, 0xffff0000, v63
	v_mul_f32_e32 v138, v120, v120
	v_mul_f32_e32 v149, v121, v121
	v_mul_f32_e32 v150, v122, v122
	v_mul_f32_e32 v154, v123, v123
	v_fma_f32 v138, v124, v124, v138
	v_fma_f32 v149, v125, v125, v149
	v_fma_f32 v150, v126, v126, v150
	v_fma_f32 v154, v127, v127, v154
	v_fma_f32 v138, v128, v128, v138
	v_fma_f32 v149, v129, v129, v149
	v_fma_f32 v150, v130, v130, v150
	v_fma_f32 v154, v131, v131, v154
	v_fma_f32 v138, v132, v132, v138
	v_fma_f32 v149, v133, v133, v149
	v_fma_f32 v150, v134, v134, v150
	v_fma_f32 v154, v135, v135, v154
	v_add_f32_e32 v138, v138, v149
	v_add_f32_e32 v150, v150, v154
	v_add_f32_e32 v138, v138, v150
	s_nop 1
	v_add_f32_dpp v138, v138, v138 quad_perm:[1,0,3,2] row_mask:0xf bank_mask:0xf
	s_nop 1
	v_add_f32_dpp v138, v138, v138 quad_perm:[2,3,0,1] row_mask:0xf bank_mask:0xf
	s_nop 1
	v_add_f32_dpp v138, v138, v138 row_half_mirror row_mask:0xf bank_mask:0xf
	s_nop 1
	v_add_f32_dpp v138, v138, v138 row_mirror row_mask:0xf bank_mask:0xf
	v_mov_b32_e32 v139, v138
	s_nop 1
	v_permlane16_swap_b32_e32 v138, v139
	v_add_f32_e32 v138, v138, v139
	v_mov_b32_e32 v139, v138
	s_nop 1
	v_permlane32_swap_b32_e32 v138, v139
	v_add_f32_e32 v138, v138, v139
	v_mul_f32_e32 v138, 0x3a800000, v138
	v_add_f32_e32 v138, 0x358637bd, v138
	v_rsq_f32_e32 v140, v138
	v_lshlrev_b32_e32 v16, 16, v24
	v_and_b32_e32 v17, 0xffff0000, v24
	v_lshlrev_b32_e32 v18, 16, v25
	v_and_b32_e32 v19, 0xffff0000, v25
	v_lshlrev_b32_e32 v20, 16, v26
	v_and_b32_e32 v21, 0xffff0000, v26
	v_lshlrev_b32_e32 v22, 16, v27
	v_and_b32_e32 v23, 0xffff0000, v27
	v_lshlrev_b32_e32 v24, 16, v28
	v_and_b32_e32 v25, 0xffff0000, v28
	v_lshlrev_b32_e32 v26, 16, v29
	v_and_b32_e32 v27, 0xffff0000, v29
	v_lshlrev_b32_e32 v28, 16, v30
	v_and_b32_e32 v29, 0xffff0000, v30
	v_lshlrev_b32_e32 v30, 16, v31
	v_and_b32_e32 v31, 0xffff0000, v31
	s_nop 0
	v_mul_f32_e32 v120, v120, v140
	v_mul_f32_e32 v121, v121, v140
	v_mul_f32_e32 v122, v122, v140
	v_mul_f32_e32 v123, v123, v140
	v_mul_f32_e32 v124, v124, v140
	v_mul_f32_e32 v125, v125, v140
	v_mul_f32_e32 v126, v126, v140
	v_mul_f32_e32 v127, v127, v140
	v_mul_f32_e32 v128, v128, v140
	v_mul_f32_e32 v129, v129, v140
	v_mul_f32_e32 v130, v130, v140
	v_mul_f32_e32 v131, v131, v140
	v_mul_f32_e32 v132, v132, v140
	v_mul_f32_e32 v133, v133, v140
	v_mul_f32_e32 v134, v134, v140
	v_mul_f32_e32 v135, v135, v140
	v_fma_f32 v16, v120, v72, v16
	v_fma_f32 v17, v121, v73, v17
	v_fma_f32 v18, v122, v74, v18
	v_fma_f32 v19, v123, v75, v19
	v_fma_f32 v20, v124, v76, v20
	v_fma_f32 v21, v125, v77, v21
	v_fma_f32 v22, v126, v78, v22
	v_fma_f32 v23, v127, v79, v23
	v_fma_f32 v24, v128, v80, v24
	v_fma_f32 v25, v129, v81, v25
	v_fma_f32 v26, v130, v82, v26
	v_fma_f32 v27, v131, v83, v27
	v_fma_f32 v28, v132, v84, v28
	v_fma_f32 v29, v133, v85, v29
	v_fma_f32 v30, v134, v86, v30
	v_fma_f32 v31, v135, v87, v31
	v_cvt_pk_bf16_f32 v156, v16, v17
	v_cvt_pk_bf16_f32 v157, v18, v19
	v_cvt_pk_bf16_f32 v158, v20, v21
	v_cvt_pk_bf16_f32 v159, v22, v23
	v_cvt_pk_bf16_f32 v160, v24, v25
	v_cvt_pk_bf16_f32 v161, v26, v27
	v_cvt_pk_bf16_f32 v162, v28, v29
	v_cvt_pk_bf16_f32 v163, v30, v31
	s_lshl_b32 vcc_lo, s19, 11
	s_add_u32 vcc_lo, vcc_lo, 0x400000
	s_add_u32 s100, s16, vcc_lo
	s_addc_u32 s101, s17, 0
	global_store_dwordx2 v137, v[156:157], s[100:101] offset:0
	global_store_dwordx2 v137, v[158:159], s[100:101] offset:512
	global_store_dwordx2 v137, v[160:161], s[100:101] offset:1024
; __device__ __forceinline__ void row_phase(const Params& P, int glayer, int layer, int xsrc, bool hasY, int gate_idx, const float* gpost,
;                           int xdst, bool doH, const float* gpre, int sh_idx, int nrows) {
;     ...
;         if (hasY) {
;           float4 yv[4];
;           float ss = 0.f;
; #pragma unroll
;           for (int i = 0; i < 4; ++i) {
;             const uint2 raw = yy[u][i];
;             yv[i].x = bf2f((u16)(raw.x & 0xffff)); yv[i].y = bf2f((u16)(raw.x >> 16));
;             yv[i].z = bf2f((u16)(raw.y & 0xffff)); yv[i].w = bf2f((u16)(raw.y >> 16));
;             ss += yv[i].x * yv[i].x + yv[i].y * yv[i].y + yv[i].z * yv[i].z + yv[i].w * yv[i].w;
;           }
;           ss = wave_sum(ss);
;           const float rstd = __builtin_amdgcn_rsqf(ss * (1.f / 1024.f) + EPSF);
; #pragma unroll
;           for (int i = 0; i < 4; ++i) {
;             const int col = (i * 64 + lane) * 4;
;             const float4 gt = *reinterpret_cast<const float4*>(modg + gate_idx * 1024 + col);
;             const float4 gp = *reinterpret_cast<const float4*>(gpost + col);
;             xv[i].x += gt.x * (yv[i].x * rstd * gp.x); xv[i].y += gt.y * (yv[i].y * rstd * gp.y);
;             xv[i].z += gt.z * (yv[i].z * rstd * gp.z); xv[i].w += gt.w * (yv[i].w * rstd * gp.w);
;           }
;         }
;         if (xdst == 3 || (xdst == 1 && row >= N_X)) {
;           float* xout = (xdst == 3) ? P.out + (long)row * 1024 : P.xc + (long)(row - N_X) * 1024;
; #pragma unroll
;           for (int i = 0; i < 4; ++i) *reinterpret_cast<float4*>(xout + (i * 64 + lane) * 4) = xv[i];
;         } else if (xdst != 0) {
;           u16* xo = ((xdst == 1) ? resA : P.zf) + (long)row * 1024;
; #pragma unroll
;           for (int i = 0; i < 4; ++i) {
;             const unsigned b0 = f2bf(xv[i].x), b1 = f2bf(xv[i].y), b2 = f2bf(xv[i].z), b3 = f2bf(xv[i].w);
;             *reinterpret_cast<uint2*>(xo + (i * 64 + lane) * 4) = make_uint2(b0 | (b1 << 16), b2 | (b3 << 16));
;           }
;         }
;         if (doH) {
;           float ss = 0.f;
; #pragma unroll
;           for (int i = 0; i < 4; ++i) ss += xv[i].x * xv[i].x + xv[i].y * xv[i].y + xv[i].z * xv[i].z + xv[i].w * xv[i].w;
;           ss = wave_sum(ss);
;           const float rstd = __builtin_amdgcn_rsqf(ss * (1.f / 1024.f) + EPSF);
;           u16* h = P.hy + (long)row * 1024;
; #pragma unroll
	global_store_dwordx2 v137, v[162:163], s[100:101] offset:1536
	v_mul_f32_e32 v138, v16, v16
	v_mul_f32_e32 v149, v17, v17
	v_mul_f32_e32 v150, v18, v18
	v_mul_f32_e32 v154, v19, v19
	v_fma_f32 v138, v20, v20, v138
	v_fma_f32 v149, v21, v21, v149
	v_fma_f32 v150, v22, v22, v150
	v_fma_f32 v154, v23, v23, v154
	v_fma_f32 v138, v24, v24, v138
	v_fma_f32 v149, v25, v25, v149
	v_fma_f32 v150, v26, v26, v150
	v_fma_f32 v154, v27, v27, v154
	v_fma_f32 v138, v28, v28, v138
	v_fma_f32 v149, v29, v29, v149
	v_fma_f32 v150, v30, v30, v150
	v_fma_f32 v154, v31, v31, v154
	v_add_f32_e32 v138, v138, v149
	v_add_f32_e32 v150, v150, v154
	v_add_f32_e32 v138, v138, v150
	s_nop 1
	v_add_f32_dpp v138, v138, v138 quad_perm:[1,0,3,2] row_mask:0xf bank_mask:0xf
	s_nop 1
	v_add_f32_dpp v138, v138, v138 quad_perm:[2,3,0,1] row_mask:0xf bank_mask:0xf
	s_nop 1
	v_add_f32_dpp v138, v138, v138 row_half_mirror row_mask:0xf bank_mask:0xf
	s_nop 1
	v_add_f32_dpp v138, v138, v138 row_mirror row_mask:0xf bank_mask:0xf
	v_mov_b32_e32 v139, v138
	s_nop 1
	v_permlane16_swap_b32_e32 v138, v139
	v_add_f32_e32 v138, v138, v139
	v_mov_b32_e32 v139, v138
	s_nop 1
	v_permlane32_swap_b32_e32 v138, v139
	v_add_f32_e32 v138, v138, v139
	v_mul_f32_e32 v138, 0x3a800000, v138
	v_add_f32_e32 v138, 0x358637bd, v138
	v_rsq_f32_e32 v140, v138
	s_nop 0
	v_mul_f32_e32 v120, v16, v140
	v_mul_f32_e32 v121, v17, v140
	v_mul_f32_e32 v122, v18, v140
	v_mul_f32_e32 v123, v19, v140
	v_mul_f32_e32 v124, v20, v140
	v_mul_f32_e32 v125, v21, v140
	v_mul_f32_e32 v126, v22, v140
	v_mul_f32_e32 v127, v23, v140
	v_mul_f32_e32 v128, v24, v140
	v_mul_f32_e32 v129, v25, v140
	v_mul_f32_e32 v130, v26, v140
	v_mul_f32_e32 v131, v27, v140
	v_mul_f32_e32 v132, v28, v140
	v_mul_f32_e32 v133, v29, v140
	v_mul_f32_e32 v134, v30, v140
	v_mul_f32_e32 v135, v31, v140
	v_fma_f32 v120, v120, v88, v104
	v_fma_f32 v121, v121, v89, v105
	v_fma_f32 v122, v122, v90, v106
	v_fma_f32 v123, v123, v91, v107
	v_fma_f32 v124, v124, v92, v108
	v_fma_f32 v125, v125, v93, v109
	v_fma_f32 v126, v126, v94, v110
	v_fma_f32 v127, v127, v95, v111
	v_fma_f32 v128, v128, v96, v112
	v_fma_f32 v129, v129, v97, v113
	v_fma_f32 v130, v130, v98, v114
	v_fma_f32 v131, v131, v99, v115
	v_fma_f32 v132, v132, v100, v116
	v_fma_f32 v133, v133, v101, v117
	v_fma_f32 v134, v134, v102, v118
	v_fma_f32 v135, v135, v103, v119
	v_cvt_pk_bf16_f32 v156, v120, v121
	v_cvt_pk_bf16_f32 v157, v122, v123
	v_cvt_pk_bf16_f32 v158, v124, v125
	v_cvt_pk_bf16_f32 v159, v126, v127
	v_cvt_pk_bf16_f32 v160, v128, v129
	v_cvt_pk_bf16_f32 v161, v130, v131
	v_cvt_pk_bf16_f32 v162, v132, v133
	v_cvt_pk_bf16_f32 v163, v134, v135
	s_lshl_b32 vcc_lo, s19, 11
	s_add_u32 vcc_lo, vcc_lo, 0x400000
	s_add_u32 s100, s14, vcc_lo
	s_addc_u32 s101, s15, 0
	global_store_dwordx2 v137, v[156:157], s[100:101] offset:0
	global_store_dwordx2 v137, v[158:159], s[100:101] offset:512
	global_store_dwordx2 v137, v[160:161], s[100:101] offset:1024
	global_store_dwordx2 v137, v[162:163], s[100:101] offset:1536
	s_lshl_b32 vcc_lo, s19, 11
	s_add_u32 vcc_lo, vcc_lo, 0x1000000
	s_add_u32 s100, s12, vcc_lo
	s_addc_u32 s101, s13, 0
	global_load_dwordx2 v[24:25], v137, s[100:101] offset:0
	global_load_dwordx2 v[26:27], v137, s[100:101] offset:512
	global_load_dwordx2 v[28:29], v137, s[100:101] offset:1024
	global_load_dwordx2 v[30:31], v137, s[100:101] offset:1536
	s_lshl_b32 vcc_lo, s19, 11
	s_add_u32 vcc_lo, vcc_lo, 0x1000000
	s_add_u32 s100, s14, vcc_lo
	s_addc_u32 s101, s15, 0
	global_load_dwordx2 v[56:57], v137, s[100:101] offset:0
	global_load_dwordx2 v[58:59], v137, s[100:101] offset:512
	global_load_dwordx2 v[60:61], v137, s[100:101] offset:1024
	global_load_dwordx2 v[62:63], v137, s[100:101] offset:1536
	s_waitcnt vmcnt(32)
	v_lshlrev_b32_e32 v120, 16, v64
	v_and_b32_e32 v121, 0xffff0000, v64
	v_lshlrev_b32_e32 v122, 16, v65
	v_and_b32_e32 v123, 0xffff0000, v65
	v_lshlrev_b32_e32 v124, 16, v66
	v_and_b32_e32 v125, 0xffff0000, v66
	v_lshlrev_b32_e32 v126, 16, v67
	v_and_b32_e32 v127, 0xffff0000, v67
	v_lshlrev_b32_e32 v128, 16, v68
	v_and_b32_e32 v129, 0xffff0000, v68
	v_lshlrev_b32_e32 v130, 16, v69
	v_and_b32_e32 v131, 0xffff0000, v69
	v_lshlrev_b32_e32 v132, 16, v70
	v_and_b32_e32 v133, 0xffff0000, v70
	v_lshlrev_b32_e32 v134, 16, v71
	v_and_b32_e32 v135, 0xffff0000, v71
	v_mul_f32_e32 v138, v120, v120
	v_mul_f32_e32 v149, v121, v121
	v_mul_f32_e32 v150, v122, v122
	v_mul_f32_e32 v154, v123, v123
	v_fma_f32 v138, v124, v124, v138
	v_fma_f32 v149, v125, v125, v149
	v_fma_f32 v150, v126, v126, v150
	v_fma_f32 v154, v127, v127, v154
	v_fma_f32 v138, v128, v128, v138
	v_fma_f32 v149, v129, v129, v149
	v_fma_f32 v150, v130, v130, v150
	v_fma_f32 v154, v131, v131, v154
	v_fma_f32 v138, v132, v132, v138
	v_fma_f32 v149, v133, v133, v149
	v_fma_f32 v150, v134, v134, v150
	v_fma_f32 v154, v135, v135, v154
	v_add_f32_e32 v138, v138, v149
	v_add_f32_e32 v150, v150, v154
	v_add_f32_e32 v138, v138, v150
	s_nop 1
	v_add_f32_dpp v138, v138, v138 quad_perm:[1,0,3,2] row_mask:0xf bank_mask:0xf
	s_nop 1
	v_add_f32_dpp v138, v138, v138 quad_perm:[2,3,0,1] row_mask:0xf bank_mask:0xf
	s_nop 1
	v_add_f32_dpp v138, v138, v138 row_half_mirror row_mask:0xf bank_mask:0xf
	s_nop 1
	v_add_f32_dpp v138, v138, v138 row_mirror row_mask:0xf bank_mask:0xf
	v_mov_b32_e32 v139, v138
	s_nop 1
	v_permlane16_swap_b32_e32 v138, v139
	v_add_f32_e32 v138, v138, v139
	v_mov_b32_e32 v139, v138
	s_nop 1
	v_permlane32_swap_b32_e32 v138, v139
	v_add_f32_e32 v138, v138, v139
	v_mul_f32_e32 v138, 0x3a800000, v138
	v_add_f32_e32 v138, 0x358637bd, v138
	v_rsq_f32_e32 v140, v138
	v_lshlrev_b32_e32 v32, 16, v40
	v_and_b32_e32 v33, 0xffff0000, v40
; __device__ __forceinline__ void row_phase(const Params& P, int glayer, int layer, int xsrc, bool hasY, int gate_idx, const float* gpost,
;                           int xdst, bool doH, const float* gpre, int sh_idx, int nrows) {
;     ...
;         if (hasY) {
;           float4 yv[4];
;           float ss = 0.f;
; #pragma unroll
;           for (int i = 0; i < 4; ++i) {
;             const uint2 raw = yy[u][i];
;             yv[i].x = bf2f((u16)(raw.x & 0xffff)); yv[i].y = bf2f((u16)(raw.x >> 16));
;             yv[i].z = bf2f((u16)(raw.y & 0xffff)); yv[i].w = bf2f((u16)(raw.y >> 16));
;             ss += yv[i].x * yv[i].x + yv[i].y * yv[i].y + yv[i].z * yv[i].z + yv[i].w * yv[i].w;
;           }
;           ss = wave_sum(ss);
;           const float rstd = __builtin_amdgcn_rsqf(ss * (1.f / 1024.f) + EPSF);
; #pragma unroll
;           for (int i = 0; i < 4; ++i) {
;             const int col = (i * 64 + lane) * 4;
;             const float4 gt = *reinterpret_cast<const float4*>(modg + gate_idx * 1024 + col);
;             const float4 gp = *reinterpret_cast<const float4*>(gpost + col);
;             xv[i].x += gt.x * (yv[i].x * rstd * gp.x); xv[i].y += gt.y * (yv[i].y * rstd * gp.y);
;             xv[i].z += gt.z * (yv[i].z * rstd * gp.z); xv[i].w += gt.w * (yv[i].w * rstd * gp.w);
;           }
;         }
;         if (xdst == 3 || (xdst == 1 && row >= N_X)) {
;           float* xout = (xdst == 3) ? P.out + (long)row * 1024 : P.xc + (long)(row - N_X) * 1024;
; #pragma unroll
;           for (int i = 0; i < 4; ++i) *reinterpret_cast<float4*>(xout + (i * 64 + lane) * 4) = xv[i];
;         } else if (xdst != 0) {
;           u16* xo = ((xdst == 1) ? resA : P.zf) + (long)row * 1024;
; #pragma unroll
;           for (int i = 0; i < 4; ++i) {
;             const unsigned b0 = f2bf(xv[i].x), b1 = f2bf(xv[i].y), b2 = f2bf(xv[i].z), b3 = f2bf(xv[i].w);
;             *reinterpret_cast<uint2*>(xo + (i * 64 + lane) * 4) = make_uint2(b0 | (b1 << 16), b2 | (b3 << 16));
;           }
;         }
;         if (doH) {
;           float ss = 0.f;
; #pragma unroll
;           for (int i = 0; i < 4; ++i) ss += xv[i].x * xv[i].x + xv[i].y * xv[i].y + xv[i].z * xv[i].z + xv[i].w * xv[i].w;
;           ss = wave_sum(ss);
;           const float rstd = __builtin_amdgcn_rsqf(ss * (1.f / 1024.f) + EPSF);
;           u16* h = P.hy + (long)row * 1024;
; #pragma unroll
	v_lshlrev_b32_e32 v34, 16, v41
	v_and_b32_e32 v35, 0xffff0000, v41
	v_lshlrev_b32_e32 v36, 16, v42
	v_and_b32_e32 v37, 0xffff0000, v42
	v_lshlrev_b32_e32 v38, 16, v43
	v_and_b32_e32 v39, 0xffff0000, v43
	v_lshlrev_b32_e32 v40, 16, v44
	v_and_b32_e32 v41, 0xffff0000, v44
	v_lshlrev_b32_e32 v42, 16, v45
	v_and_b32_e32 v43, 0xffff0000, v45
	v_lshlrev_b32_e32 v44, 16, v46
	v_and_b32_e32 v45, 0xffff0000, v46
	v_lshlrev_b32_e32 v46, 16, v47
	v_and_b32_e32 v47, 0xffff0000, v47
	s_nop 0
	v_mul_f32_e32 v120, v120, v140
	v_mul_f32_e32 v121, v121, v140
	v_mul_f32_e32 v122, v122, v140
	v_mul_f32_e32 v123, v123, v140
	v_mul_f32_e32 v124, v124, v140
	v_mul_f32_e32 v125, v125, v140
	v_mul_f32_e32 v126, v126, v140
	v_mul_f32_e32 v127, v127, v140
	v_mul_f32_e32 v128, v128, v140
	v_mul_f32_e32 v129, v129, v140
	v_mul_f32_e32 v130, v130, v140
	v_mul_f32_e32 v131, v131, v140
	v_mul_f32_e32 v132, v132, v140
	v_mul_f32_e32 v133, v133, v140
	v_mul_f32_e32 v134, v134, v140
	v_mul_f32_e32 v135, v135, v140
	v_fma_f32 v32, v120, v72, v32
	v_fma_f32 v33, v121, v73, v33
	v_fma_f32 v34, v122, v74, v34
	v_fma_f32 v35, v123, v75, v35
	v_fma_f32 v36, v124, v76, v36
	v_fma_f32 v37, v125, v77, v37
	v_fma_f32 v38, v126, v78, v38
	v_fma_f32 v39, v127, v79, v39
	v_fma_f32 v40, v128, v80, v40
	v_fma_f32 v41, v129, v81, v41
	v_fma_f32 v42, v130, v82, v42
	v_fma_f32 v43, v131, v83, v43
	v_fma_f32 v44, v132, v84, v44
	v_fma_f32 v45, v133, v85, v45
	v_fma_f32 v46, v134, v86, v46
	v_fma_f32 v47, v135, v87, v47
	v_cvt_pk_bf16_f32 v156, v32, v33
	v_cvt_pk_bf16_f32 v157, v34, v35
	v_cvt_pk_bf16_f32 v158, v36, v37
	v_cvt_pk_bf16_f32 v159, v38, v39
	v_cvt_pk_bf16_f32 v160, v40, v41
	v_cvt_pk_bf16_f32 v161, v42, v43
	v_cvt_pk_bf16_f32 v162, v44, v45
	v_cvt_pk_bf16_f32 v163, v46, v47
	s_lshl_b32 vcc_lo, s19, 11
	s_add_u32 vcc_lo, vcc_lo, 0x800000
	s_add_u32 s100, s16, vcc_lo
	s_addc_u32 s101, s17, 0
	global_store_dwordx2 v137, v[156:157], s[100:101] offset:0
	global_store_dwordx2 v137, v[158:159], s[100:101] offset:512
	global_store_dwordx2 v137, v[160:161], s[100:101] offset:1024
	global_store_dwordx2 v137, v[162:163], s[100:101] offset:1536
	v_mul_f32_e32 v138, v32, v32
	v_mul_f32_e32 v149, v33, v33
	v_mul_f32_e32 v150, v34, v34
	v_mul_f32_e32 v154, v35, v35
	v_fma_f32 v138, v36, v36, v138
	v_fma_f32 v149, v37, v37, v149
	v_fma_f32 v150, v38, v38, v150
	v_fma_f32 v154, v39, v39, v154
	v_fma_f32 v138, v40, v40, v138
	v_fma_f32 v149, v41, v41, v149
	v_fma_f32 v150, v42, v42, v150
	v_fma_f32 v154, v43, v43, v154
	v_fma_f32 v138, v44, v44, v138
	v_fma_f32 v149, v45, v45, v149
	v_fma_f32 v150, v46, v46, v150
	v_fma_f32 v154, v47, v47, v154
	v_add_f32_e32 v138, v138, v149
	v_add_f32_e32 v150, v150, v154
	v_add_f32_e32 v138, v138, v150
	s_nop 1
	v_add_f32_dpp v138, v138, v138 quad_perm:[1,0,3,2] row_mask:0xf bank_mask:0xf
	s_nop 1
	v_add_f32_dpp v138, v138, v138 quad_perm:[2,3,0,1] row_mask:0xf bank_mask:0xf
	s_nop 1
	v_add_f32_dpp v138, v138, v138 row_half_mirror row_mask:0xf bank_mask:0xf
	s_nop 1
	v_add_f32_dpp v138, v138, v138 row_mirror row_mask:0xf bank_mask:0xf
	v_mov_b32_e32 v139, v138
	s_nop 1
	v_permlane16_swap_b32_e32 v138, v139
	v_add_f32_e32 v138, v138, v139
	v_mov_b32_e32 v139, v138
	s_nop 1
	v_permlane32_swap_b32_e32 v138, v139
	v_add_f32_e32 v138, v138, v139
	v_mul_f32_e32 v138, 0x3a800000, v138
	v_add_f32_e32 v138, 0x358637bd, v138
	v_rsq_f32_e32 v140, v138
	s_nop 0
	v_mul_f32_e32 v120, v32, v140
	v_mul_f32_e32 v121, v33, v140
	v_mul_f32_e32 v122, v34, v140
	v_mul_f32_e32 v123, v35, v140
	v_mul_f32_e32 v124, v36, v140
	v_mul_f32_e32 v125, v37, v140
	v_mul_f32_e32 v126, v38, v140
	v_mul_f32_e32 v127, v39, v140
	v_mul_f32_e32 v128, v40, v140
	v_mul_f32_e32 v129, v41, v140
	v_mul_f32_e32 v130, v42, v140
	v_mul_f32_e32 v131, v43, v140
	v_mul_f32_e32 v132, v44, v140
	v_mul_f32_e32 v133, v45, v140
	v_mul_f32_e32 v134, v46, v140
	v_mul_f32_e32 v135, v47, v140
	v_fma_f32 v120, v120, v88, v104
	v_fma_f32 v121, v121, v89, v105
	v_fma_f32 v122, v122, v90, v106
	v_fma_f32 v123, v123, v91, v107
	v_fma_f32 v124, v124, v92, v108
	v_fma_f32 v125, v125, v93, v109
	v_fma_f32 v126, v126, v94, v110
	v_fma_f32 v127, v127, v95, v111
	v_fma_f32 v128, v128, v96, v112
	v_fma_f32 v129, v129, v97, v113
	v_fma_f32 v130, v130, v98, v114
	v_fma_f32 v131, v131, v99, v115
	v_fma_f32 v132, v132, v100, v116
	v_fma_f32 v133, v133, v101, v117
	v_fma_f32 v134, v134, v102, v118
	v_fma_f32 v135, v135, v103, v119
	v_cvt_pk_bf16_f32 v156, v120, v121
	v_cvt_pk_bf16_f32 v157, v122, v123
	v_cvt_pk_bf16_f32 v158, v124, v125
	v_cvt_pk_bf16_f32 v159, v126, v127
	v_cvt_pk_bf16_f32 v160, v128, v129
	v_cvt_pk_bf16_f32 v161, v130, v131
	v_cvt_pk_bf16_f32 v162, v132, v133
	v_cvt_pk_bf16_f32 v163, v134, v135
	s_lshl_b32 vcc_lo, s19, 11
	s_add_u32 vcc_lo, vcc_lo, 0x800000
	s_add_u32 s100, s14, vcc_lo
	s_addc_u32 s101, s15, 0
	global_store_dwordx2 v137, v[156:157], s[100:101] offset:0
	global_store_dwordx2 v137, v[158:159], s[100:101] offset:512
	global_store_dwordx2 v137, v[160:161], s[100:101] offset:1024
	global_store_dwordx2 v137, v[162:163], s[100:101] offset:1536
	s_lshl_b32 vcc_lo, s19, 11
	s_add_u32 vcc_lo, vcc_lo, 0x1400000
	s_add_u32 s100, s12, vcc_lo
	s_addc_u32 s101, s13, 0
	global_load_dwordx2 v[40:41], v137, s[100:101] offset:0
	global_load_dwordx2 v[42:43], v137, s[100:101] offset:512
	global_load_dwordx2 v[44:45], v137, s[100:101] offset:1024
	global_load_dwordx2 v[46:47], v137, s[100:101] offset:1536
	s_lshl_b32 vcc_lo, s19, 11
	s_add_u32 vcc_lo, vcc_lo, 0x1400000
	s_add_u32 s100, s14, vcc_lo
	s_addc_u32 s101, s15, 0
	global_load_dwordx2 v[64:65], v137, s[100:101] offset:0
	global_load_dwordx2 v[66:67], v137, s[100:101] offset:512
	global_load_dwordx2 v[68:69], v137, s[100:101] offset:1024
	global_load_dwordx2 v[70:71], v137, s[100:101] offset:1536
	s_waitcnt vmcnt(32)
; __device__ __forceinline__ void row_phase(const Params& P, int glayer, int layer, int xsrc, bool hasY, int gate_idx, const float* gpost,
;                           int xdst, bool doH, const float* gpre, int sh_idx, int nrows) {
;     ...
;         if (hasY) {
;           float4 yv[4];
;           float ss = 0.f;
; #pragma unroll
;           for (int i = 0; i < 4; ++i) {
;             const uint2 raw = yy[u][i];
;             yv[i].x = bf2f((u16)(raw.x & 0xffff)); yv[i].y = bf2f((u16)(raw.x >> 16));
;             yv[i].z = bf2f((u16)(raw.y & 0xffff)); yv[i].w = bf2f((u16)(raw.y >> 16));
;             ss += yv[i].x * yv[i].x + yv[i].y * yv[i].y + yv[i].z * yv[i].z + yv[i].w * yv[i].w;
;           }
;           ss = wave_sum(ss);
;           const float rstd = __builtin_amdgcn_rsqf(ss * (1.f / 1024.f) + EPSF);
; #pragma unroll
;           for (int i = 0; i < 4; ++i) {
;             const int col = (i * 64 + lane) * 4;
;             const float4 gt = *reinterpret_cast<const float4*>(modg + gate_idx * 1024 + col);
;             const float4 gp = *reinterpret_cast<const float4*>(gpost + col);
;             xv[i].x += gt.x * (yv[i].x * rstd * gp.x); xv[i].y += gt.y * (yv[i].y * rstd * gp.y);
;             xv[i].z += gt.z * (yv[i].z * rstd * gp.z); xv[i].w += gt.w * (yv[i].w * rstd * gp.w);
;           }
;         }
;         if (xdst == 3 || (xdst == 1 && row >= N_X)) {
;           float* xout = (xdst == 3) ? P.out + (long)row * 1024 : P.xc + (long)(row - N_X) * 1024;
; #pragma unroll
;           for (int i = 0; i < 4; ++i) *reinterpret_cast<float4*>(xout + (i * 64 + lane) * 4) = xv[i];
;         } else if (xdst != 0) {
;           u16* xo = ((xdst == 1) ? resA : P.zf) + (long)row * 1024;
; #pragma unroll
;           for (int i = 0; i < 4; ++i) {
;             const unsigned b0 = f2bf(xv[i].x), b1 = f2bf(xv[i].y), b2 = f2bf(xv[i].z), b3 = f2bf(xv[i].w);
;             *reinterpret_cast<uint2*>(xo + (i * 64 + lane) * 4) = make_uint2(b0 | (b1 << 16), b2 | (b3 << 16));
;           }
;         }
;         if (doH) {
;           float ss = 0.f;
; #pragma unroll
;           for (int i = 0; i < 4; ++i) ss += xv[i].x * xv[i].x + xv[i].y * xv[i].y + xv[i].z * xv[i].z + xv[i].w * xv[i].w;
;           ss = wave_sum(ss);
;           const float rstd = __builtin_amdgcn_rsqf(ss * (1.f / 1024.f) + EPSF);
;           u16* h = P.hy + (long)row * 1024;
; #pragma unroll
	v_lshlrev_b32_e32 v120, 16, v48
	v_and_b32_e32 v121, 0xffff0000, v48
	v_lshlrev_b32_e32 v122, 16, v49
	v_and_b32_e32 v123, 0xffff0000, v49
	v_lshlrev_b32_e32 v124, 16, v50
	v_and_b32_e32 v125, 0xffff0000, v50
	v_lshlrev_b32_e32 v126, 16, v51
	v_and_b32_e32 v127, 0xffff0000, v51
	v_lshlrev_b32_e32 v128, 16, v52
	v_and_b32_e32 v129, 0xffff0000, v52
	v_lshlrev_b32_e32 v130, 16, v53
	v_and_b32_e32 v131, 0xffff0000, v53
	v_lshlrev_b32_e32 v132, 16, v54
	v_and_b32_e32 v133, 0xffff0000, v54
	v_lshlrev_b32_e32 v134, 16, v55
	v_and_b32_e32 v135, 0xffff0000, v55
	v_mul_f32_e32 v138, v120, v120
	v_mul_f32_e32 v149, v121, v121
	v_mul_f32_e32 v150, v122, v122
	v_mul_f32_e32 v154, v123, v123
	v_fma_f32 v138, v124, v124, v138
	v_fma_f32 v149, v125, v125, v149
	v_fma_f32 v150, v126, v126, v150
	v_fma_f32 v154, v127, v127, v154
	v_fma_f32 v138, v128, v128, v138
	v_fma_f32 v149, v129, v129, v149
	v_fma_f32 v150, v130, v130, v150
	v_fma_f32 v154, v131, v131, v154
	v_fma_f32 v138, v132, v132, v138
	v_fma_f32 v149, v133, v133, v149
	v_fma_f32 v150, v134, v134, v150
	v_fma_f32 v154, v135, v135, v154
	v_add_f32_e32 v138, v138, v149
	v_add_f32_e32 v150, v150, v154
	v_add_f32_e32 v138, v138, v150
	s_nop 1
	v_add_f32_dpp v138, v138, v138 quad_perm:[1,0,3,2] row_mask:0xf bank_mask:0xf
	s_nop 1
	v_add_f32_dpp v138, v138, v138 quad_perm:[2,3,0,1] row_mask:0xf bank_mask:0xf
	s_nop 1
	v_add_f32_dpp v138, v138, v138 row_half_mirror row_mask:0xf bank_mask:0xf
	s_nop 1
	v_add_f32_dpp v138, v138, v138 row_mirror row_mask:0xf bank_mask:0xf
	v_mov_b32_e32 v139, v138
	s_nop 1
	v_permlane16_swap_b32_e32 v138, v139
	v_add_f32_e32 v138, v138, v139
	v_mov_b32_e32 v139, v138
	s_nop 1
	v_permlane32_swap_b32_e32 v138, v139
	v_add_f32_e32 v138, v138, v139
	v_mul_f32_e32 v138, 0x3a800000, v138
	v_add_f32_e32 v138, 0x358637bd, v138
	v_rsq_f32_e32 v140, v138
	v_lshlrev_b32_e32 v0, 16, v8
	v_and_b32_e32 v1, 0xffff0000, v8
	v_lshlrev_b32_e32 v2, 16, v9
	v_and_b32_e32 v3, 0xffff0000, v9
	v_lshlrev_b32_e32 v4, 16, v10
	v_and_b32_e32 v5, 0xffff0000, v10
	v_lshlrev_b32_e32 v6, 16, v11
	v_and_b32_e32 v7, 0xffff0000, v11
	v_lshlrev_b32_e32 v8, 16, v12
	v_and_b32_e32 v9, 0xffff0000, v12
	v_lshlrev_b32_e32 v10, 16, v13
	v_and_b32_e32 v11, 0xffff0000, v13
	v_lshlrev_b32_e32 v12, 16, v14
	v_and_b32_e32 v13, 0xffff0000, v14
	v_lshlrev_b32_e32 v14, 16, v15
	v_and_b32_e32 v15, 0xffff0000, v15
	s_nop 0
	v_mul_f32_e32 v120, v120, v140
	v_mul_f32_e32 v121, v121, v140
	v_mul_f32_e32 v122, v122, v140
	v_mul_f32_e32 v123, v123, v140
	v_mul_f32_e32 v124, v124, v140
	v_mul_f32_e32 v125, v125, v140
	v_mul_f32_e32 v126, v126, v140
	v_mul_f32_e32 v127, v127, v140
	v_mul_f32_e32 v128, v128, v140
	v_mul_f32_e32 v129, v129, v140
	v_mul_f32_e32 v130, v130, v140
	v_mul_f32_e32 v131, v131, v140
	v_mul_f32_e32 v132, v132, v140
	v_mul_f32_e32 v133, v133, v140
	v_mul_f32_e32 v134, v134, v140
	v_mul_f32_e32 v135, v135, v140
	v_fma_f32 v0, v120, v72, v0
	v_fma_f32 v1, v121, v73, v1
	v_fma_f32 v2, v122, v74, v2
	v_fma_f32 v3, v123, v75, v3
	v_fma_f32 v4, v124, v76, v4
	v_fma_f32 v5, v125, v77, v5
	v_fma_f32 v6, v126, v78, v6
	v_fma_f32 v7, v127, v79, v7
	v_fma_f32 v8, v128, v80, v8
	v_fma_f32 v9, v129, v81, v9
	v_fma_f32 v10, v130, v82, v10
	v_fma_f32 v11, v131, v83, v11
	v_fma_f32 v12, v132, v84, v12
	v_fma_f32 v13, v133, v85, v13
	v_fma_f32 v14, v134, v86, v14
	v_fma_f32 v15, v135, v87, v15
	v_cvt_pk_bf16_f32 v156, v0, v1
	v_cvt_pk_bf16_f32 v157, v2, v3
	v_cvt_pk_bf16_f32 v158, v4, v5
	v_cvt_pk_bf16_f32 v159, v6, v7
	v_cvt_pk_bf16_f32 v160, v8, v9
	v_cvt_pk_bf16_f32 v161, v10, v11
	v_cvt_pk_bf16_f32 v162, v12, v13
	v_cvt_pk_bf16_f32 v163, v14, v15
	s_lshl_b32 vcc_lo, s19, 11
	s_add_u32 vcc_lo, vcc_lo, 0xc00000
	s_add_u32 s100, s16, vcc_lo
	s_addc_u32 s101, s17, 0
	global_store_dwordx2 v137, v[156:157], s[100:101] offset:0
	global_store_dwordx2 v137, v[158:159], s[100:101] offset:512
	global_store_dwordx2 v137, v[160:161], s[100:101] offset:1024
	global_store_dwordx2 v137, v[162:163], s[100:101] offset:1536
	v_mul_f32_e32 v138, v0, v0
	v_mul_f32_e32 v149, v1, v1
	v_mul_f32_e32 v150, v2, v2
	v_mul_f32_e32 v154, v3, v3
	v_fma_f32 v138, v4, v4, v138
	v_fma_f32 v149, v5, v5, v149
	v_fma_f32 v150, v6, v6, v150
	v_fma_f32 v154, v7, v7, v154
	v_fma_f32 v138, v8, v8, v138
	v_fma_f32 v149, v9, v9, v149
	v_fma_f32 v150, v10, v10, v150
	v_fma_f32 v154, v11, v11, v154
	v_fma_f32 v138, v12, v12, v138
	v_fma_f32 v149, v13, v13, v149
	v_fma_f32 v150, v14, v14, v150
	v_fma_f32 v154, v15, v15, v154
	v_add_f32_e32 v138, v138, v149
	v_add_f32_e32 v150, v150, v154
	v_add_f32_e32 v138, v138, v150
	s_nop 1
	v_add_f32_dpp v138, v138, v138 quad_perm:[1,0,3,2] row_mask:0xf bank_mask:0xf
	s_nop 1
	v_add_f32_dpp v138, v138, v138 quad_perm:[2,3,0,1] row_mask:0xf bank_mask:0xf
	s_nop 1
	v_add_f32_dpp v138, v138, v138 row_half_mirror row_mask:0xf bank_mask:0xf
	s_nop 1
	v_add_f32_dpp v138, v138, v138 row_mirror row_mask:0xf bank_mask:0xf
	v_mov_b32_e32 v139, v138
	s_nop 1
	v_permlane16_swap_b32_e32 v138, v139
	v_add_f32_e32 v138, v138, v139
	v_mov_b32_e32 v139, v138
	s_nop 1
	v_permlane32_swap_b32_e32 v138, v139
	v_add_f32_e32 v138, v138, v139
	v_mul_f32_e32 v138, 0x3a800000, v138
	v_add_f32_e32 v138, 0x358637bd, v138
	v_rsq_f32_e32 v140, v138
	s_nop 0
	v_mul_f32_e32 v120, v0, v140
	v_mul_f32_e32 v121, v1, v140
	v_mul_f32_e32 v122, v2, v140
	v_mul_f32_e32 v123, v3, v140
	v_mul_f32_e32 v124, v4, v140
	v_mul_f32_e32 v125, v5, v140
	v_mul_f32_e32 v126, v6, v140
	v_mul_f32_e32 v127, v7, v140
	v_mul_f32_e32 v128, v8, v140
	v_mul_f32_e32 v129, v9, v140
	v_mul_f32_e32 v130, v10, v140
	v_mul_f32_e32 v131, v11, v140
	v_mul_f32_e32 v132, v12, v140
; __device__ __forceinline__ void row_phase(const Params& P, int glayer, int layer, int xsrc, bool hasY, int gate_idx, const float* gpost,
;                           int xdst, bool doH, const float* gpre, int sh_idx, int nrows) {
;     ...
;         const int mi = row < N_X ? (row >> 13) : 4;
;         const float* modp = P.mod + (long)(layer * 5 + mi) * 6144;
;         const float* modg = P.mod + (long)(glayer * 5 + mi) * 6144;
;     ...
;         if (hasY) {
;           float4 yv[4];
;           float ss = 0.f;
; #pragma unroll
;           for (int i = 0; i < 4; ++i) {
;             const uint2 raw = yy[u][i];
;             yv[i].x = bf2f((u16)(raw.x & 0xffff)); yv[i].y = bf2f((u16)(raw.x >> 16));
;             yv[i].z = bf2f((u16)(raw.y & 0xffff)); yv[i].w = bf2f((u16)(raw.y >> 16));
;             ss += yv[i].x * yv[i].x + yv[i].y * yv[i].y + yv[i].z * yv[i].z + yv[i].w * yv[i].w;
;           }
;           ss = wave_sum(ss);
;           const float rstd = __builtin_amdgcn_rsqf(ss * (1.f / 1024.f) + EPSF);
; #pragma unroll
;           for (int i = 0; i < 4; ++i) {
;             const int col = (i * 64 + lane) * 4;
;             const float4 gt = *reinterpret_cast<const float4*>(modg + gate_idx * 1024 + col);
;             const float4 gp = *reinterpret_cast<const float4*>(gpost + col);
;             xv[i].x += gt.x * (yv[i].x * rstd * gp.x); xv[i].y += gt.y * (yv[i].y * rstd * gp.y);
;             xv[i].z += gt.z * (yv[i].z * rstd * gp.z); xv[i].w += gt.w * (yv[i].w * rstd * gp.w);
;           }
;         }
;         if (xdst == 3 || (xdst == 1 && row >= N_X)) {
;           float* xout = (xdst == 3) ? P.out + (long)row * 1024 : P.xc + (long)(row - N_X) * 1024;
; #pragma unroll
;           for (int i = 0; i < 4; ++i) *reinterpret_cast<float4*>(xout + (i * 64 + lane) * 4) = xv[i];
;         } else if (xdst != 0) {
;           u16* xo = ((xdst == 1) ? resA : P.zf) + (long)row * 1024;
; #pragma unroll
;           for (int i = 0; i < 4; ++i) {
;             const unsigned b0 = f2bf(xv[i].x), b1 = f2bf(xv[i].y), b2 = f2bf(xv[i].z), b3 = f2bf(xv[i].w);
;             *reinterpret_cast<uint2*>(xo + (i * 64 + lane) * 4) = make_uint2(b0 | (b1 << 16), b2 | (b3 << 16));
;           }
;         }
;         if (doH) {
;           float ss = 0.f;
; #pragma unroll
;           for (int i = 0; i < 4; ++i) ss += xv[i].x * xv[i].x + xv[i].y * xv[i].y + xv[i].z * xv[i].z + xv[i].w * xv[i].w;
	v_mul_f32_e32 v133, v13, v140
	v_mul_f32_e32 v134, v14, v140
	v_mul_f32_e32 v135, v15, v140
	v_fma_f32 v120, v120, v88, v104
	v_fma_f32 v121, v121, v89, v105
	v_fma_f32 v122, v122, v90, v106
	v_fma_f32 v123, v123, v91, v107
	v_fma_f32 v124, v124, v92, v108
	v_fma_f32 v125, v125, v93, v109
	v_fma_f32 v126, v126, v94, v110
	v_fma_f32 v127, v127, v95, v111
	v_fma_f32 v128, v128, v96, v112
	v_fma_f32 v129, v129, v97, v113
	v_fma_f32 v130, v130, v98, v114
	v_fma_f32 v131, v131, v99, v115
	v_fma_f32 v132, v132, v100, v116
	v_fma_f32 v133, v133, v101, v117
	v_fma_f32 v134, v134, v102, v118
	v_fma_f32 v135, v135, v103, v119
	v_cvt_pk_bf16_f32 v156, v120, v121
	v_cvt_pk_bf16_f32 v157, v122, v123
	v_cvt_pk_bf16_f32 v158, v124, v125
	v_cvt_pk_bf16_f32 v159, v126, v127
	v_cvt_pk_bf16_f32 v160, v128, v129
	v_cvt_pk_bf16_f32 v161, v130, v131
	v_cvt_pk_bf16_f32 v162, v132, v133
	v_cvt_pk_bf16_f32 v163, v134, v135
	s_lshl_b32 vcc_lo, s19, 11
	s_add_u32 vcc_lo, vcc_lo, 0xc00000
	s_add_u32 s100, s14, vcc_lo
	s_addc_u32 s101, s15, 0
	global_store_dwordx2 v137, v[156:157], s[100:101] offset:0
	global_store_dwordx2 v137, v[158:159], s[100:101] offset:512
	global_store_dwordx2 v137, v[160:161], s[100:101] offset:1024
	global_store_dwordx2 v137, v[162:163], s[100:101] offset:1536
	s_add_u32 s100, s20, 0xb000
	s_addc_u32 s101, s21, 0
	global_load_dwordx4 v[72:75], v136, s[100:101] offset:0
	global_load_dwordx4 v[76:79], v136, s[100:101] offset:1024
	global_load_dwordx4 v[80:83], v136, s[100:101] offset:2048
	global_load_dwordx4 v[84:87], v136, s[100:101] offset:3072
	s_load_dwordx2 s[98:99], s[4:5], 0x48
	s_waitcnt lgkmcnt(0)
	global_load_dwordx4 v[120:123], v136, s[98:99] offset:0
	global_load_dwordx4 v[124:127], v136, s[98:99] offset:1024
	global_load_dwordx4 v[128:131], v136, s[98:99] offset:2048
	global_load_dwordx4 v[132:135], v136, s[98:99] offset:3072
	s_add_u32 s100, s20, 0x24000
	s_addc_u32 s101, s21, 0
	global_load_dwordx4 v[104:107], v136, s[100:101] offset:0
	global_load_dwordx4 v[108:111], v136, s[100:101] offset:1024
	global_load_dwordx4 v[112:115], v136, s[100:101] offset:2048
	global_load_dwordx4 v[116:119], v136, s[100:101] offset:3072
	s_add_u32 s100, s100, 0x1000
	s_addc_u32 s101, s101, 0
	global_load_dwordx4 v[0:3], v136, s[100:101] offset:0
	global_load_dwordx4 v[4:7], v136, s[100:101] offset:1024
	global_load_dwordx4 v[8:11], v136, s[100:101] offset:2048
	global_load_dwordx4 v[12:15], v136, s[100:101] offset:3072
	s_load_dwordx2 s[98:99], s[4:5], 0x30
	s_waitcnt lgkmcnt(0)
	s_add_u32 s98, s98, 0x1000
	s_addc_u32 s99, s99, 0
	global_load_dwordx4 v[88:91], v136, s[98:99] offset:0
	global_load_dwordx4 v[92:95], v136, s[98:99] offset:1024
	global_load_dwordx4 v[96:99], v136, s[98:99] offset:2048
	global_load_dwordx4 v[100:103], v136, s[98:99] offset:3072
	s_waitcnt vmcnt(0)
	v_mul_f32_e32 v72, v72, v120
	v_mul_f32_e32 v73, v73, v121
	v_mul_f32_e32 v74, v74, v122
	v_mul_f32_e32 v75, v75, v123
	v_mul_f32_e32 v76, v76, v124
	v_mul_f32_e32 v77, v77, v125
	v_mul_f32_e32 v78, v78, v126
	v_mul_f32_e32 v79, v79, v127
	v_mul_f32_e32 v80, v80, v128
	v_mul_f32_e32 v81, v81, v129
	v_mul_f32_e32 v82, v82, v130
	v_mul_f32_e32 v83, v83, v131
	v_mul_f32_e32 v84, v84, v132
	v_mul_f32_e32 v85, v85, v133
	v_mul_f32_e32 v86, v86, v134
	v_mul_f32_e32 v87, v87, v135
	v_fma_f32 v88, v88, v0, v88
	v_fma_f32 v89, v89, v1, v89
	v_fma_f32 v90, v90, v2, v90
	v_fma_f32 v91, v91, v3, v91
	v_fma_f32 v92, v92, v4, v92
	v_fma_f32 v93, v93, v5, v93
	v_fma_f32 v94, v94, v6, v94
	v_fma_f32 v95, v95, v7, v95
	v_fma_f32 v96, v96, v8, v96
	v_fma_f32 v97, v97, v9, v97
	v_fma_f32 v98, v98, v10, v98
	v_fma_f32 v99, v99, v11, v99
	v_fma_f32 v100, v100, v12, v100
	v_fma_f32 v101, v101, v13, v101
	v_fma_f32 v102, v102, v14, v102
	v_fma_f32 v103, v103, v15, v103
	s_lshl_b32 vcc_lo, s19, 11
	s_add_u32 vcc_lo, vcc_lo, 0x1800000
	s_add_u32 s100, s12, vcc_lo
	s_addc_u32 s101, s13, 0
	global_load_dwordx2 v[8:9], v137, s[100:101] offset:0
	global_load_dwordx2 v[10:11], v137, s[100:101] offset:512
	global_load_dwordx2 v[12:13], v137, s[100:101] offset:1024
	global_load_dwordx2 v[14:15], v137, s[100:101] offset:1536
	s_lshl_b32 vcc_lo, s19, 11
	s_add_u32 vcc_lo, vcc_lo, 0x1800000
	s_add_u32 s100, s14, vcc_lo
	s_addc_u32 s101, s15, 0
	global_load_dwordx2 v[48:49], v137, s[100:101] offset:0
	global_load_dwordx2 v[50:51], v137, s[100:101] offset:512
	global_load_dwordx2 v[52:53], v137, s[100:101] offset:1024
	global_load_dwordx2 v[54:55], v137, s[100:101] offset:1536
	v_lshlrev_b32_e32 v120, 16, v56
	v_and_b32_e32 v121, 0xffff0000, v56
	v_lshlrev_b32_e32 v122, 16, v57
	v_and_b32_e32 v123, 0xffff0000, v57
	v_lshlrev_b32_e32 v124, 16, v58
	v_and_b32_e32 v125, 0xffff0000, v58
	v_lshlrev_b32_e32 v126, 16, v59
	v_and_b32_e32 v127, 0xffff0000, v59
	v_lshlrev_b32_e32 v128, 16, v60
	v_and_b32_e32 v129, 0xffff0000, v60
	v_lshlrev_b32_e32 v130, 16, v61
	v_and_b32_e32 v131, 0xffff0000, v61
	v_lshlrev_b32_e32 v132, 16, v62
	v_and_b32_e32 v133, 0xffff0000, v62
	v_lshlrev_b32_e32 v134, 16, v63
	v_and_b32_e32 v135, 0xffff0000, v63
	v_mul_f32_e32 v138, v120, v120
	v_mul_f32_e32 v149, v121, v121
	v_mul_f32_e32 v150, v122, v122
	v_mul_f32_e32 v154, v123, v123
	v_fma_f32 v138, v124, v124, v138
	v_fma_f32 v149, v125, v125, v149
	v_fma_f32 v150, v126, v126, v150
	v_fma_f32 v154, v127, v127, v154
	v_fma_f32 v138, v128, v128, v138
	v_fma_f32 v149, v129, v129, v149
	v_fma_f32 v150, v130, v130, v150
	v_fma_f32 v154, v131, v131, v154
	v_fma_f32 v138, v132, v132, v138
	v_fma_f32 v149, v133, v133, v149
	v_fma_f32 v150, v134, v134, v150
	v_fma_f32 v154, v135, v135, v154
	v_add_f32_e32 v138, v138, v149
	v_add_f32_e32 v150, v150, v154
; __device__ __forceinline__ void row_phase(const Params& P, int glayer, int layer, int xsrc, bool hasY, int gate_idx, const float* gpost,
;                           int xdst, bool doH, const float* gpre, int sh_idx, int nrows) {
;     ...
;         if (hasY) {
;           float4 yv[4];
;           float ss = 0.f;
; #pragma unroll
;           for (int i = 0; i < 4; ++i) {
;             const uint2 raw = yy[u][i];
;             yv[i].x = bf2f((u16)(raw.x & 0xffff)); yv[i].y = bf2f((u16)(raw.x >> 16));
;             yv[i].z = bf2f((u16)(raw.y & 0xffff)); yv[i].w = bf2f((u16)(raw.y >> 16));
;             ss += yv[i].x * yv[i].x + yv[i].y * yv[i].y + yv[i].z * yv[i].z + yv[i].w * yv[i].w;
;           }
;           ss = wave_sum(ss);
;           const float rstd = __builtin_amdgcn_rsqf(ss * (1.f / 1024.f) + EPSF);
; #pragma unroll
;           for (int i = 0; i < 4; ++i) {
;             const int col = (i * 64 + lane) * 4;
;             const float4 gt = *reinterpret_cast<const float4*>(modg + gate_idx * 1024 + col);
;             const float4 gp = *reinterpret_cast<const float4*>(gpost + col);
;             xv[i].x += gt.x * (yv[i].x * rstd * gp.x); xv[i].y += gt.y * (yv[i].y * rstd * gp.y);
;             xv[i].z += gt.z * (yv[i].z * rstd * gp.z); xv[i].w += gt.w * (yv[i].w * rstd * gp.w);
;           }
;         }
;         if (xdst == 3 || (xdst == 1 && row >= N_X)) {
;           float* xout = (xdst == 3) ? P.out + (long)row * 1024 : P.xc + (long)(row - N_X) * 1024;
; #pragma unroll
;           for (int i = 0; i < 4; ++i) *reinterpret_cast<float4*>(xout + (i * 64 + lane) * 4) = xv[i];
;         } else if (xdst != 0) {
;           u16* xo = ((xdst == 1) ? resA : P.zf) + (long)row * 1024;
; #pragma unroll
;           for (int i = 0; i < 4; ++i) {
;             const unsigned b0 = f2bf(xv[i].x), b1 = f2bf(xv[i].y), b2 = f2bf(xv[i].z), b3 = f2bf(xv[i].w);
;             *reinterpret_cast<uint2*>(xo + (i * 64 + lane) * 4) = make_uint2(b0 | (b1 << 16), b2 | (b3 << 16));
;           }
;         }
;         if (doH) {
;           float ss = 0.f;
; #pragma unroll
;           for (int i = 0; i < 4; ++i) ss += xv[i].x * xv[i].x + xv[i].y * xv[i].y + xv[i].z * xv[i].z + xv[i].w * xv[i].w;
;           ss = wave_sum(ss);
;           const float rstd = __builtin_amdgcn_rsqf(ss * (1.f / 1024.f) + EPSF);
;           u16* h = P.hy + (long)row * 1024;
; #pragma unroll
	v_add_f32_e32 v138, v138, v150
	s_nop 1
	v_add_f32_dpp v138, v138, v138 quad_perm:[1,0,3,2] row_mask:0xf bank_mask:0xf
	s_nop 1
	v_add_f32_dpp v138, v138, v138 quad_perm:[2,3,0,1] row_mask:0xf bank_mask:0xf
	s_nop 1
	v_add_f32_dpp v138, v138, v138 row_half_mirror row_mask:0xf bank_mask:0xf
	s_nop 1
	v_add_f32_dpp v138, v138, v138 row_mirror row_mask:0xf bank_mask:0xf
	v_mov_b32_e32 v139, v138
	s_nop 1
	v_permlane16_swap_b32_e32 v138, v139
	v_add_f32_e32 v138, v138, v139
	v_mov_b32_e32 v139, v138
	s_nop 1
	v_permlane32_swap_b32_e32 v138, v139
	v_add_f32_e32 v138, v138, v139
	v_mul_f32_e32 v138, 0x3a800000, v138
	v_add_f32_e32 v138, 0x358637bd, v138
	v_rsq_f32_e32 v140, v138
	v_lshlrev_b32_e32 v16, 16, v24
	v_and_b32_e32 v17, 0xffff0000, v24
	v_lshlrev_b32_e32 v18, 16, v25
	v_and_b32_e32 v19, 0xffff0000, v25
	v_lshlrev_b32_e32 v20, 16, v26
	v_and_b32_e32 v21, 0xffff0000, v26
	v_lshlrev_b32_e32 v22, 16, v27
	v_and_b32_e32 v23, 0xffff0000, v27
	v_lshlrev_b32_e32 v24, 16, v28
	v_and_b32_e32 v25, 0xffff0000, v28
	v_lshlrev_b32_e32 v26, 16, v29
	v_and_b32_e32 v27, 0xffff0000, v29
	v_lshlrev_b32_e32 v28, 16, v30
	v_and_b32_e32 v29, 0xffff0000, v30
	v_lshlrev_b32_e32 v30, 16, v31
	v_and_b32_e32 v31, 0xffff0000, v31
	s_nop 0
	v_mul_f32_e32 v120, v120, v140
	v_mul_f32_e32 v121, v121, v140
	v_mul_f32_e32 v122, v122, v140
	v_mul_f32_e32 v123, v123, v140
	v_mul_f32_e32 v124, v124, v140
	v_mul_f32_e32 v125, v125, v140
	v_mul_f32_e32 v126, v126, v140
	v_mul_f32_e32 v127, v127, v140
	v_mul_f32_e32 v128, v128, v140
	v_mul_f32_e32 v129, v129, v140
	v_mul_f32_e32 v130, v130, v140
	v_mul_f32_e32 v131, v131, v140
	v_mul_f32_e32 v132, v132, v140
	v_mul_f32_e32 v133, v133, v140
	v_mul_f32_e32 v134, v134, v140
	v_mul_f32_e32 v135, v135, v140
	v_fma_f32 v16, v120, v72, v16
	v_fma_f32 v17, v121, v73, v17
	v_fma_f32 v18, v122, v74, v18
	v_fma_f32 v19, v123, v75, v19
	v_fma_f32 v20, v124, v76, v20
	v_fma_f32 v21, v125, v77, v21
	v_fma_f32 v22, v126, v78, v22
	v_fma_f32 v23, v127, v79, v23
	v_fma_f32 v24, v128, v80, v24
	v_fma_f32 v25, v129, v81, v25
	v_fma_f32 v26, v130, v82, v26
	v_fma_f32 v27, v131, v83, v27
	v_fma_f32 v28, v132, v84, v28
	v_fma_f32 v29, v133, v85, v29
	v_fma_f32 v30, v134, v86, v30
	v_fma_f32 v31, v135, v87, v31
	v_cvt_pk_bf16_f32 v156, v16, v17
	v_cvt_pk_bf16_f32 v157, v18, v19
	v_cvt_pk_bf16_f32 v158, v20, v21
	v_cvt_pk_bf16_f32 v159, v22, v23
	v_cvt_pk_bf16_f32 v160, v24, v25
	v_cvt_pk_bf16_f32 v161, v26, v27
	v_cvt_pk_bf16_f32 v162, v28, v29
	v_cvt_pk_bf16_f32 v163, v30, v31
	s_lshl_b32 vcc_lo, s19, 11
	s_add_u32 vcc_lo, vcc_lo, 0x1000000
	s_add_u32 s100, s16, vcc_lo
	s_addc_u32 s101, s17, 0
	global_store_dwordx2 v137, v[156:157], s[100:101] offset:0
	global_store_dwordx2 v137, v[158:159], s[100:101] offset:512
	global_store_dwordx2 v137, v[160:161], s[100:101] offset:1024
	global_store_dwordx2 v137, v[162:163], s[100:101] offset:1536
	v_mul_f32_e32 v138, v16, v16
	v_mul_f32_e32 v149, v17, v17
	v_mul_f32_e32 v150, v18, v18
	v_mul_f32_e32 v154, v19, v19
	v_fma_f32 v138, v20, v20, v138
	v_fma_f32 v149, v21, v21, v149
	v_fma_f32 v150, v22, v22, v150
	v_fma_f32 v154, v23, v23, v154
	v_fma_f32 v138, v24, v24, v138
	v_fma_f32 v149, v25, v25, v149
	v_fma_f32 v150, v26, v26, v150
	v_fma_f32 v154, v27, v27, v154
	v_fma_f32 v138, v28, v28, v138
	v_fma_f32 v149, v29, v29, v149
	v_fma_f32 v150, v30, v30, v150
	v_fma_f32 v154, v31, v31, v154
	v_add_f32_e32 v138, v138, v149
	v_add_f32_e32 v150, v150, v154
	v_add_f32_e32 v138, v138, v150
	s_nop 1
	v_add_f32_dpp v138, v138, v138 quad_perm:[1,0,3,2] row_mask:0xf bank_mask:0xf
	s_nop 1
	v_add_f32_dpp v138, v138, v138 quad_perm:[2,3,0,1] row_mask:0xf bank_mask:0xf
	s_nop 1
	v_add_f32_dpp v138, v138, v138 row_half_mirror row_mask:0xf bank_mask:0xf
	s_nop 1
	v_add_f32_dpp v138, v138, v138 row_mirror row_mask:0xf bank_mask:0xf
	v_mov_b32_e32 v139, v138
	s_nop 1
	v_permlane16_swap_b32_e32 v138, v139
	v_add_f32_e32 v138, v138, v139
	v_mov_b32_e32 v139, v138
	s_nop 1
	v_permlane32_swap_b32_e32 v138, v139
	v_add_f32_e32 v138, v138, v139
	v_mul_f32_e32 v138, 0x3a800000, v138
	v_add_f32_e32 v138, 0x358637bd, v138
	v_rsq_f32_e32 v140, v138
	s_nop 0
	v_mul_f32_e32 v120, v16, v140
	v_mul_f32_e32 v121, v17, v140
	v_mul_f32_e32 v122, v18, v140
	v_mul_f32_e32 v123, v19, v140
	v_mul_f32_e32 v124, v20, v140
	v_mul_f32_e32 v125, v21, v140
	v_mul_f32_e32 v126, v22, v140
	v_mul_f32_e32 v127, v23, v140
	v_mul_f32_e32 v128, v24, v140
	v_mul_f32_e32 v129, v25, v140
	v_mul_f32_e32 v130, v26, v140
	v_mul_f32_e32 v131, v27, v140
	v_mul_f32_e32 v132, v28, v140
	v_mul_f32_e32 v133, v29, v140
	v_mul_f32_e32 v134, v30, v140
	v_mul_f32_e32 v135, v31, v140
	v_fma_f32 v120, v120, v88, v104
	v_fma_f32 v121, v121, v89, v105
	v_fma_f32 v122, v122, v90, v106
	v_fma_f32 v123, v123, v91, v107
	v_fma_f32 v124, v124, v92, v108
	v_fma_f32 v125, v125, v93, v109
	v_fma_f32 v126, v126, v94, v110
	v_fma_f32 v127, v127, v95, v111
	v_fma_f32 v128, v128, v96, v112
	v_fma_f32 v129, v129, v97, v113
	v_fma_f32 v130, v130, v98, v114
	v_fma_f32 v131, v131, v99, v115
	v_fma_f32 v132, v132, v100, v116
	v_fma_f32 v133, v133, v101, v117
	v_fma_f32 v134, v134, v102, v118
	v_fma_f32 v135, v135, v103, v119
	v_cvt_pk_bf16_f32 v156, v120, v121
	v_cvt_pk_bf16_f32 v157, v122, v123
	v_cvt_pk_bf16_f32 v158, v124, v125
	v_cvt_pk_bf16_f32 v159, v126, v127
	v_cvt_pk_bf16_f32 v160, v128, v129
	v_cvt_pk_bf16_f32 v161, v130, v131
	v_cvt_pk_bf16_f32 v162, v132, v133
	v_cvt_pk_bf16_f32 v163, v134, v135
	s_lshl_b32 vcc_lo, s19, 11
	s_add_u32 vcc_lo, vcc_lo, 0x1000000
	s_add_u32 s100, s14, vcc_lo
	s_addc_u32 s101, s15, 0
	global_store_dwordx2 v137, v[156:157], s[100:101] offset:0
; __device__ __forceinline__ void row_phase(const Params& P, int glayer, int layer, int xsrc, bool hasY, int gate_idx, const float* gpost,
;                           int xdst, bool doH, const float* gpre, int sh_idx, int nrows) {
;     ...
;         if (hasY) {
;           float4 yv[4];
;           float ss = 0.f;
; #pragma unroll
;           for (int i = 0; i < 4; ++i) {
;             const uint2 raw = yy[u][i];
;             yv[i].x = bf2f((u16)(raw.x & 0xffff)); yv[i].y = bf2f((u16)(raw.x >> 16));
;             yv[i].z = bf2f((u16)(raw.y & 0xffff)); yv[i].w = bf2f((u16)(raw.y >> 16));
;             ss += yv[i].x * yv[i].x + yv[i].y * yv[i].y + yv[i].z * yv[i].z + yv[i].w * yv[i].w;
;           }
;           ss = wave_sum(ss);
;           const float rstd = __builtin_amdgcn_rsqf(ss * (1.f / 1024.f) + EPSF);
; #pragma unroll
;           for (int i = 0; i < 4; ++i) {
;             const int col = (i * 64 + lane) * 4;
;             const float4 gt = *reinterpret_cast<const float4*>(modg + gate_idx * 1024 + col);
;             const float4 gp = *reinterpret_cast<const float4*>(gpost + col);
;             xv[i].x += gt.x * (yv[i].x * rstd * gp.x); xv[i].y += gt.y * (yv[i].y * rstd * gp.y);
;             xv[i].z += gt.z * (yv[i].z * rstd * gp.z); xv[i].w += gt.w * (yv[i].w * rstd * gp.w);
;           }
;         }
;         if (xdst == 3 || (xdst == 1 && row >= N_X)) {
;           float* xout = (xdst == 3) ? P.out + (long)row * 1024 : P.xc + (long)(row - N_X) * 1024;
; #pragma unroll
;           for (int i = 0; i < 4; ++i) *reinterpret_cast<float4*>(xout + (i * 64 + lane) * 4) = xv[i];
;         } else if (xdst != 0) {
;           u16* xo = ((xdst == 1) ? resA : P.zf) + (long)row * 1024;
; #pragma unroll
;           for (int i = 0; i < 4; ++i) {
;             const unsigned b0 = f2bf(xv[i].x), b1 = f2bf(xv[i].y), b2 = f2bf(xv[i].z), b3 = f2bf(xv[i].w);
;             *reinterpret_cast<uint2*>(xo + (i * 64 + lane) * 4) = make_uint2(b0 | (b1 << 16), b2 | (b3 << 16));
;           }
;         }
;         if (doH) {
;           float ss = 0.f;
; #pragma unroll
;           for (int i = 0; i < 4; ++i) ss += xv[i].x * xv[i].x + xv[i].y * xv[i].y + xv[i].z * xv[i].z + xv[i].w * xv[i].w;
;           ss = wave_sum(ss);
;           const float rstd = __builtin_amdgcn_rsqf(ss * (1.f / 1024.f) + EPSF);
;           u16* h = P.hy + (long)row * 1024;
; #pragma unroll
	global_store_dwordx2 v137, v[158:159], s[100:101] offset:512
	global_store_dwordx2 v137, v[160:161], s[100:101] offset:1024
	global_store_dwordx2 v137, v[162:163], s[100:101] offset:1536
	s_lshl_b32 vcc_lo, s19, 11
	s_add_u32 vcc_lo, vcc_lo, 0x1c00000
	s_add_u32 s100, s12, vcc_lo
	s_addc_u32 s101, s13, 0
	global_load_dwordx2 v[24:25], v137, s[100:101] offset:0
	global_load_dwordx2 v[26:27], v137, s[100:101] offset:512
	global_load_dwordx2 v[28:29], v137, s[100:101] offset:1024
	global_load_dwordx2 v[30:31], v137, s[100:101] offset:1536
	s_lshl_b32 vcc_lo, s19, 11
	s_add_u32 vcc_lo, vcc_lo, 0x1c00000
	s_add_u32 s100, s14, vcc_lo
	s_addc_u32 s101, s15, 0
	global_load_dwordx2 v[56:57], v137, s[100:101] offset:0
	global_load_dwordx2 v[58:59], v137, s[100:101] offset:512
	global_load_dwordx2 v[60:61], v137, s[100:101] offset:1024
	global_load_dwordx2 v[62:63], v137, s[100:101] offset:1536
	v_lshlrev_b32_e32 v120, 16, v64
	v_and_b32_e32 v121, 0xffff0000, v64
	v_lshlrev_b32_e32 v122, 16, v65
	v_and_b32_e32 v123, 0xffff0000, v65
	v_lshlrev_b32_e32 v124, 16, v66
	v_and_b32_e32 v125, 0xffff0000, v66
	v_lshlrev_b32_e32 v126, 16, v67
	v_and_b32_e32 v127, 0xffff0000, v67
	v_lshlrev_b32_e32 v128, 16, v68
	v_and_b32_e32 v129, 0xffff0000, v68
	v_lshlrev_b32_e32 v130, 16, v69
	v_and_b32_e32 v131, 0xffff0000, v69
	v_lshlrev_b32_e32 v132, 16, v70
	v_and_b32_e32 v133, 0xffff0000, v70
	v_lshlrev_b32_e32 v134, 16, v71
	v_and_b32_e32 v135, 0xffff0000, v71
	v_mul_f32_e32 v138, v120, v120
	v_mul_f32_e32 v149, v121, v121
	v_mul_f32_e32 v150, v122, v122
	v_mul_f32_e32 v154, v123, v123
	v_fma_f32 v138, v124, v124, v138
	v_fma_f32 v149, v125, v125, v149
	v_fma_f32 v150, v126, v126, v150
	v_fma_f32 v154, v127, v127, v154
	v_fma_f32 v138, v128, v128, v138
	v_fma_f32 v149, v129, v129, v149
	v_fma_f32 v150, v130, v130, v150
	v_fma_f32 v154, v131, v131, v154
	v_fma_f32 v138, v132, v132, v138
	v_fma_f32 v149, v133, v133, v149
	v_fma_f32 v150, v134, v134, v150
	v_fma_f32 v154, v135, v135, v154
	v_add_f32_e32 v138, v138, v149
	v_add_f32_e32 v150, v150, v154
	v_add_f32_e32 v138, v138, v150
	s_nop 1
	v_add_f32_dpp v138, v138, v138 quad_perm:[1,0,3,2] row_mask:0xf bank_mask:0xf
	s_nop 1
	v_add_f32_dpp v138, v138, v138 quad_perm:[2,3,0,1] row_mask:0xf bank_mask:0xf
	s_nop 1
	v_add_f32_dpp v138, v138, v138 row_half_mirror row_mask:0xf bank_mask:0xf
	s_nop 1
	v_add_f32_dpp v138, v138, v138 row_mirror row_mask:0xf bank_mask:0xf
	v_mov_b32_e32 v139, v138
	s_nop 1
	v_permlane16_swap_b32_e32 v138, v139
	v_add_f32_e32 v138, v138, v139
	v_mov_b32_e32 v139, v138
	s_nop 1
	v_permlane32_swap_b32_e32 v138, v139
	v_add_f32_e32 v138, v138, v139
	v_mul_f32_e32 v138, 0x3a800000, v138
	v_add_f32_e32 v138, 0x358637bd, v138
	v_rsq_f32_e32 v140, v138
	v_lshlrev_b32_e32 v32, 16, v40
	v_and_b32_e32 v33, 0xffff0000, v40
	v_lshlrev_b32_e32 v34, 16, v41
	v_and_b32_e32 v35, 0xffff0000, v41
	v_lshlrev_b32_e32 v36, 16, v42
	v_and_b32_e32 v37, 0xffff0000, v42
	v_lshlrev_b32_e32 v38, 16, v43
	v_and_b32_e32 v39, 0xffff0000, v43
	v_lshlrev_b32_e32 v40, 16, v44
	v_and_b32_e32 v41, 0xffff0000, v44
	v_lshlrev_b32_e32 v42, 16, v45
	v_and_b32_e32 v43, 0xffff0000, v45
	v_lshlrev_b32_e32 v44, 16, v46
	v_and_b32_e32 v45, 0xffff0000, v46
	v_lshlrev_b32_e32 v46, 16, v47
	v_and_b32_e32 v47, 0xffff0000, v47
	s_nop 0
	v_mul_f32_e32 v120, v120, v140
	v_mul_f32_e32 v121, v121, v140
	v_mul_f32_e32 v122, v122, v140
	v_mul_f32_e32 v123, v123, v140
	v_mul_f32_e32 v124, v124, v140
	v_mul_f32_e32 v125, v125, v140
	v_mul_f32_e32 v126, v126, v140
	v_mul_f32_e32 v127, v127, v140
	v_mul_f32_e32 v128, v128, v140
	v_mul_f32_e32 v129, v129, v140
	v_mul_f32_e32 v130, v130, v140
	v_mul_f32_e32 v131, v131, v140
	v_mul_f32_e32 v132, v132, v140
	v_mul_f32_e32 v133, v133, v140
	v_mul_f32_e32 v134, v134, v140
	v_mul_f32_e32 v135, v135, v140
	v_fma_f32 v32, v120, v72, v32
	v_fma_f32 v33, v121, v73, v33
	v_fma_f32 v34, v122, v74, v34
	v_fma_f32 v35, v123, v75, v35
	v_fma_f32 v36, v124, v76, v36
	v_fma_f32 v37, v125, v77, v37
	v_fma_f32 v38, v126, v78, v38
	v_fma_f32 v39, v127, v79, v39
	v_fma_f32 v40, v128, v80, v40
	v_fma_f32 v41, v129, v81, v41
	v_fma_f32 v42, v130, v82, v42
	v_fma_f32 v43, v131, v83, v43
	v_fma_f32 v44, v132, v84, v44
	v_fma_f32 v45, v133, v85, v45
	v_fma_f32 v46, v134, v86, v46
	v_fma_f32 v47, v135, v87, v47
	v_cvt_pk_bf16_f32 v156, v32, v33
	v_cvt_pk_bf16_f32 v157, v34, v35
	v_cvt_pk_bf16_f32 v158, v36, v37
	v_cvt_pk_bf16_f32 v159, v38, v39
	v_cvt_pk_bf16_f32 v160, v40, v41
	v_cvt_pk_bf16_f32 v161, v42, v43
	v_cvt_pk_bf16_f32 v162, v44, v45
	v_cvt_pk_bf16_f32 v163, v46, v47
	s_lshl_b32 vcc_lo, s19, 11
	s_add_u32 vcc_lo, vcc_lo, 0x1400000
	s_add_u32 s100, s16, vcc_lo
	s_addc_u32 s101, s17, 0
	global_store_dwordx2 v137, v[156:157], s[100:101] offset:0
	global_store_dwordx2 v137, v[158:159], s[100:101] offset:512
	global_store_dwordx2 v137, v[160:161], s[100:101] offset:1024
	global_store_dwordx2 v137, v[162:163], s[100:101] offset:1536
	v_mul_f32_e32 v138, v32, v32
	v_mul_f32_e32 v149, v33, v33
	v_mul_f32_e32 v150, v34, v34
	v_mul_f32_e32 v154, v35, v35
	v_fma_f32 v138, v36, v36, v138
	v_fma_f32 v149, v37, v37, v149
	v_fma_f32 v150, v38, v38, v150
	v_fma_f32 v154, v39, v39, v154
	v_fma_f32 v138, v40, v40, v138
	v_fma_f32 v149, v41, v41, v149
	v_fma_f32 v150, v42, v42, v150
	v_fma_f32 v154, v43, v43, v154
	v_fma_f32 v138, v44, v44, v138
	v_fma_f32 v149, v45, v45, v149
	v_fma_f32 v150, v46, v46, v150
	v_fma_f32 v154, v47, v47, v154
	v_add_f32_e32 v138, v138, v149
	v_add_f32_e32 v150, v150, v154
	v_add_f32_e32 v138, v138, v150
	s_nop 1
	v_add_f32_dpp v138, v138, v138 quad_perm:[1,0,3,2] row_mask:0xf bank_mask:0xf
	s_nop 1
; __device__ __forceinline__ void row_phase(const Params& P, int glayer, int layer, int xsrc, bool hasY, int gate_idx, const float* gpost,
;                           int xdst, bool doH, const float* gpre, int sh_idx, int nrows) {
;     ...
;         if (hasY) {
;           float4 yv[4];
;           float ss = 0.f;
; #pragma unroll
;           for (int i = 0; i < 4; ++i) {
;             const uint2 raw = yy[u][i];
;             yv[i].x = bf2f((u16)(raw.x & 0xffff)); yv[i].y = bf2f((u16)(raw.x >> 16));
;             yv[i].z = bf2f((u16)(raw.y & 0xffff)); yv[i].w = bf2f((u16)(raw.y >> 16));
;             ss += yv[i].x * yv[i].x + yv[i].y * yv[i].y + yv[i].z * yv[i].z + yv[i].w * yv[i].w;
;           }
;           ss = wave_sum(ss);
;           const float rstd = __builtin_amdgcn_rsqf(ss * (1.f / 1024.f) + EPSF);
; #pragma unroll
;           for (int i = 0; i < 4; ++i) {
;             const int col = (i * 64 + lane) * 4;
;             const float4 gt = *reinterpret_cast<const float4*>(modg + gate_idx * 1024 + col);
;             const float4 gp = *reinterpret_cast<const float4*>(gpost + col);
;             xv[i].x += gt.x * (yv[i].x * rstd * gp.x); xv[i].y += gt.y * (yv[i].y * rstd * gp.y);
;             xv[i].z += gt.z * (yv[i].z * rstd * gp.z); xv[i].w += gt.w * (yv[i].w * rstd * gp.w);
;           }
;         }
;         if (xdst == 3 || (xdst == 1 && row >= N_X)) {
;           float* xout = (xdst == 3) ? P.out + (long)row * 1024 : P.xc + (long)(row - N_X) * 1024;
; #pragma unroll
;           for (int i = 0; i < 4; ++i) *reinterpret_cast<float4*>(xout + (i * 64 + lane) * 4) = xv[i];
;         } else if (xdst != 0) {
;           u16* xo = ((xdst == 1) ? resA : P.zf) + (long)row * 1024;
; #pragma unroll
;           for (int i = 0; i < 4; ++i) {
;             const unsigned b0 = f2bf(xv[i].x), b1 = f2bf(xv[i].y), b2 = f2bf(xv[i].z), b3 = f2bf(xv[i].w);
;             *reinterpret_cast<uint2*>(xo + (i * 64 + lane) * 4) = make_uint2(b0 | (b1 << 16), b2 | (b3 << 16));
;           }
;         }
;         if (doH) {
;           float ss = 0.f;
; #pragma unroll
;           for (int i = 0; i < 4; ++i) ss += xv[i].x * xv[i].x + xv[i].y * xv[i].y + xv[i].z * xv[i].z + xv[i].w * xv[i].w;
;           ss = wave_sum(ss);
;           const float rstd = __builtin_amdgcn_rsqf(ss * (1.f / 1024.f) + EPSF);
;           u16* h = P.hy + (long)row * 1024;
; #pragma unroll
	v_add_f32_dpp v138, v138, v138 quad_perm:[2,3,0,1] row_mask:0xf bank_mask:0xf
	s_nop 1
	v_add_f32_dpp v138, v138, v138 row_half_mirror row_mask:0xf bank_mask:0xf
	s_nop 1
	v_add_f32_dpp v138, v138, v138 row_mirror row_mask:0xf bank_mask:0xf
	v_mov_b32_e32 v139, v138
	s_nop 1
	v_permlane16_swap_b32_e32 v138, v139
	v_add_f32_e32 v138, v138, v139
	v_mov_b32_e32 v139, v138
	s_nop 1
	v_permlane32_swap_b32_e32 v138, v139
	v_add_f32_e32 v138, v138, v139
	v_mul_f32_e32 v138, 0x3a800000, v138
	v_add_f32_e32 v138, 0x358637bd, v138
	v_rsq_f32_e32 v140, v138
	s_nop 0
	v_mul_f32_e32 v120, v32, v140
	v_mul_f32_e32 v121, v33, v140
	v_mul_f32_e32 v122, v34, v140
	v_mul_f32_e32 v123, v35, v140
	v_mul_f32_e32 v124, v36, v140
	v_mul_f32_e32 v125, v37, v140
	v_mul_f32_e32 v126, v38, v140
	v_mul_f32_e32 v127, v39, v140
	v_mul_f32_e32 v128, v40, v140
	v_mul_f32_e32 v129, v41, v140
	v_mul_f32_e32 v130, v42, v140
	v_mul_f32_e32 v131, v43, v140
	v_mul_f32_e32 v132, v44, v140
	v_mul_f32_e32 v133, v45, v140
	v_mul_f32_e32 v134, v46, v140
	v_mul_f32_e32 v135, v47, v140
	v_fma_f32 v120, v120, v88, v104
	v_fma_f32 v121, v121, v89, v105
	v_fma_f32 v122, v122, v90, v106
	v_fma_f32 v123, v123, v91, v107
	v_fma_f32 v124, v124, v92, v108
	v_fma_f32 v125, v125, v93, v109
	v_fma_f32 v126, v126, v94, v110
	v_fma_f32 v127, v127, v95, v111
	v_fma_f32 v128, v128, v96, v112
	v_fma_f32 v129, v129, v97, v113
	v_fma_f32 v130, v130, v98, v114
	v_fma_f32 v131, v131, v99, v115
	v_fma_f32 v132, v132, v100, v116
	v_fma_f32 v133, v133, v101, v117
	v_fma_f32 v134, v134, v102, v118
	v_fma_f32 v135, v135, v103, v119
	v_cvt_pk_bf16_f32 v156, v120, v121
	v_cvt_pk_bf16_f32 v157, v122, v123
	v_cvt_pk_bf16_f32 v158, v124, v125
	v_cvt_pk_bf16_f32 v159, v126, v127
	v_cvt_pk_bf16_f32 v160, v128, v129
	v_cvt_pk_bf16_f32 v161, v130, v131
	v_cvt_pk_bf16_f32 v162, v132, v133
	v_cvt_pk_bf16_f32 v163, v134, v135
	s_lshl_b32 vcc_lo, s19, 11
	s_add_u32 vcc_lo, vcc_lo, 0x1400000
	s_add_u32 s100, s14, vcc_lo
	s_addc_u32 s101, s15, 0
	global_store_dwordx2 v137, v[156:157], s[100:101] offset:0
	global_store_dwordx2 v137, v[158:159], s[100:101] offset:512
	global_store_dwordx2 v137, v[160:161], s[100:101] offset:1024
	global_store_dwordx2 v137, v[162:163], s[100:101] offset:1536
	s_lshl_b32 vcc_lo, s19, 11
	s_add_u32 vcc_lo, vcc_lo, 0x2000000
	s_add_u32 s100, s12, vcc_lo
	s_addc_u32 s101, s13, 0
	global_load_dwordx2 v[40:41], v137, s[100:101] offset:0
	global_load_dwordx2 v[42:43], v137, s[100:101] offset:512
	global_load_dwordx2 v[44:45], v137, s[100:101] offset:1024
	global_load_dwordx2 v[46:47], v137, s[100:101] offset:1536
	s_lshl_b32 vcc_lo, s19, 11
	s_add_u32 vcc_lo, vcc_lo, 0x2000000
	s_add_u32 s100, s14, vcc_lo
	s_addc_u32 s101, s15, 0
	global_load_dwordx2 v[64:65], v137, s[100:101] offset:0
	global_load_dwordx2 v[66:67], v137, s[100:101] offset:512
	global_load_dwordx2 v[68:69], v137, s[100:101] offset:1024
	global_load_dwordx2 v[70:71], v137, s[100:101] offset:1536
	s_waitcnt vmcnt(32)
	v_lshlrev_b32_e32 v120, 16, v48
	v_and_b32_e32 v121, 0xffff0000, v48
	v_lshlrev_b32_e32 v122, 16, v49
	v_and_b32_e32 v123, 0xffff0000, v49
	v_lshlrev_b32_e32 v124, 16, v50
	v_and_b32_e32 v125, 0xffff0000, v50
	v_lshlrev_b32_e32 v126, 16, v51
	v_and_b32_e32 v127, 0xffff0000, v51
	v_lshlrev_b32_e32 v128, 16, v52
	v_and_b32_e32 v129, 0xffff0000, v52
	v_lshlrev_b32_e32 v130, 16, v53
	v_and_b32_e32 v131, 0xffff0000, v53
	v_lshlrev_b32_e32 v132, 16, v54
	v_and_b32_e32 v133, 0xffff0000, v54
	v_lshlrev_b32_e32 v134, 16, v55
	v_and_b32_e32 v135, 0xffff0000, v55
	v_mul_f32_e32 v138, v120, v120
	v_mul_f32_e32 v149, v121, v121
	v_mul_f32_e32 v150, v122, v122
	v_mul_f32_e32 v154, v123, v123
	v_fma_f32 v138, v124, v124, v138
	v_fma_f32 v149, v125, v125, v149
	v_fma_f32 v150, v126, v126, v150
	v_fma_f32 v154, v127, v127, v154
	v_fma_f32 v138, v128, v128, v138
	v_fma_f32 v149, v129, v129, v149
	v_fma_f32 v150, v130, v130, v150
	v_fma_f32 v154, v131, v131, v154
	v_fma_f32 v138, v132, v132, v138
	v_fma_f32 v149, v133, v133, v149
	v_fma_f32 v150, v134, v134, v150
	v_fma_f32 v154, v135, v135, v154
	v_add_f32_e32 v138, v138, v149
	v_add_f32_e32 v150, v150, v154
	v_add_f32_e32 v138, v138, v150
	s_nop 1
	v_add_f32_dpp v138, v138, v138 quad_perm:[1,0,3,2] row_mask:0xf bank_mask:0xf
	s_nop 1
	v_add_f32_dpp v138, v138, v138 quad_perm:[2,3,0,1] row_mask:0xf bank_mask:0xf
	s_nop 1
	v_add_f32_dpp v138, v138, v138 row_half_mirror row_mask:0xf bank_mask:0xf
	s_nop 1
	v_add_f32_dpp v138, v138, v138 row_mirror row_mask:0xf bank_mask:0xf
	v_mov_b32_e32 v139, v138
	s_nop 1
	v_permlane16_swap_b32_e32 v138, v139
	v_add_f32_e32 v138, v138, v139
	v_mov_b32_e32 v139, v138
	s_nop 1
	v_permlane32_swap_b32_e32 v138, v139
	v_add_f32_e32 v138, v138, v139
	v_mul_f32_e32 v138, 0x3a800000, v138
	v_add_f32_e32 v138, 0x358637bd, v138
	v_rsq_f32_e32 v140, v138
	v_lshlrev_b32_e32 v0, 16, v8
	v_and_b32_e32 v1, 0xffff0000, v8
	v_lshlrev_b32_e32 v2, 16, v9
	v_and_b32_e32 v3, 0xffff0000, v9
	v_lshlrev_b32_e32 v4, 16, v10
	v_and_b32_e32 v5, 0xffff0000, v10
	v_lshlrev_b32_e32 v6, 16, v11
	v_and_b32_e32 v7, 0xffff0000, v11
	v_lshlrev_b32_e32 v8, 16, v12
	v_and_b32_e32 v9, 0xffff0000, v12
	v_lshlrev_b32_e32 v10, 16, v13
	v_and_b32_e32 v11, 0xffff0000, v13
	v_lshlrev_b32_e32 v12, 16, v14
	v_and_b32_e32 v13, 0xffff0000, v14
	v_lshlrev_b32_e32 v14, 16, v15
	v_and_b32_e32 v15, 0xffff0000, v15
	s_nop 0
	v_mul_f32_e32 v120, v120, v140
	v_mul_f32_e32 v121, v121, v140
	v_mul_f32_e32 v122, v122, v140
	v_mul_f32_e32 v123, v123, v140
	v_mul_f32_e32 v124, v124, v140
	v_mul_f32_e32 v125, v125, v140
	v_mul_f32_e32 v126, v126, v140
	v_mul_f32_e32 v127, v127, v140
	v_mul_f32_e32 v128, v128, v140
; __device__ __forceinline__ void row_phase(const Params& P, int glayer, int layer, int xsrc, bool hasY, int gate_idx, const float* gpost,
;                           int xdst, bool doH, const float* gpre, int sh_idx, int nrows) {
;     ...
;         if (hasY) {
;           float4 yv[4];
;           float ss = 0.f;
; #pragma unroll
;           for (int i = 0; i < 4; ++i) {
;             const uint2 raw = yy[u][i];
;             yv[i].x = bf2f((u16)(raw.x & 0xffff)); yv[i].y = bf2f((u16)(raw.x >> 16));
;             yv[i].z = bf2f((u16)(raw.y & 0xffff)); yv[i].w = bf2f((u16)(raw.y >> 16));
;             ss += yv[i].x * yv[i].x + yv[i].y * yv[i].y + yv[i].z * yv[i].z + yv[i].w * yv[i].w;
;           }
;           ss = wave_sum(ss);
;           const float rstd = __builtin_amdgcn_rsqf(ss * (1.f / 1024.f) + EPSF);
; #pragma unroll
;           for (int i = 0; i < 4; ++i) {
;             const int col = (i * 64 + lane) * 4;
;             const float4 gt = *reinterpret_cast<const float4*>(modg + gate_idx * 1024 + col);
;             const float4 gp = *reinterpret_cast<const float4*>(gpost + col);
;             xv[i].x += gt.x * (yv[i].x * rstd * gp.x); xv[i].y += gt.y * (yv[i].y * rstd * gp.y);
;             xv[i].z += gt.z * (yv[i].z * rstd * gp.z); xv[i].w += gt.w * (yv[i].w * rstd * gp.w);
;           }
;         }
;         if (xdst == 3 || (xdst == 1 && row >= N_X)) {
;           float* xout = (xdst == 3) ? P.out + (long)row * 1024 : P.xc + (long)(row - N_X) * 1024;
; #pragma unroll
;           for (int i = 0; i < 4; ++i) *reinterpret_cast<float4*>(xout + (i * 64 + lane) * 4) = xv[i];
;         } else if (xdst != 0) {
;           u16* xo = ((xdst == 1) ? resA : P.zf) + (long)row * 1024;
; #pragma unroll
;           for (int i = 0; i < 4; ++i) {
;             const unsigned b0 = f2bf(xv[i].x), b1 = f2bf(xv[i].y), b2 = f2bf(xv[i].z), b3 = f2bf(xv[i].w);
;             *reinterpret_cast<uint2*>(xo + (i * 64 + lane) * 4) = make_uint2(b0 | (b1 << 16), b2 | (b3 << 16));
;           }
;         }
;         if (doH) {
;           float ss = 0.f;
; #pragma unroll
;           for (int i = 0; i < 4; ++i) ss += xv[i].x * xv[i].x + xv[i].y * xv[i].y + xv[i].z * xv[i].z + xv[i].w * xv[i].w;
;           ss = wave_sum(ss);
;           const float rstd = __builtin_amdgcn_rsqf(ss * (1.f / 1024.f) + EPSF);
;           u16* h = P.hy + (long)row * 1024;
; #pragma unroll
	v_mul_f32_e32 v129, v129, v140
	v_mul_f32_e32 v130, v130, v140
	v_mul_f32_e32 v131, v131, v140
	v_mul_f32_e32 v132, v132, v140
	v_mul_f32_e32 v133, v133, v140
	v_mul_f32_e32 v134, v134, v140
	v_mul_f32_e32 v135, v135, v140
	v_fma_f32 v0, v120, v72, v0
	v_fma_f32 v1, v121, v73, v1
	v_fma_f32 v2, v122, v74, v2
	v_fma_f32 v3, v123, v75, v3
	v_fma_f32 v4, v124, v76, v4
	v_fma_f32 v5, v125, v77, v5
	v_fma_f32 v6, v126, v78, v6
	v_fma_f32 v7, v127, v79, v7
	v_fma_f32 v8, v128, v80, v8
	v_fma_f32 v9, v129, v81, v9
	v_fma_f32 v10, v130, v82, v10
	v_fma_f32 v11, v131, v83, v11
	v_fma_f32 v12, v132, v84, v12
	v_fma_f32 v13, v133, v85, v13
	v_fma_f32 v14, v134, v86, v14
	v_fma_f32 v15, v135, v87, v15
	v_cvt_pk_bf16_f32 v156, v0, v1
	v_cvt_pk_bf16_f32 v157, v2, v3
	v_cvt_pk_bf16_f32 v158, v4, v5
	v_cvt_pk_bf16_f32 v159, v6, v7
	v_cvt_pk_bf16_f32 v160, v8, v9
	v_cvt_pk_bf16_f32 v161, v10, v11
	v_cvt_pk_bf16_f32 v162, v12, v13
	v_cvt_pk_bf16_f32 v163, v14, v15
	s_lshl_b32 vcc_lo, s19, 11
	s_add_u32 vcc_lo, vcc_lo, 0x1800000
	s_add_u32 s100, s16, vcc_lo
	s_addc_u32 s101, s17, 0
	global_store_dwordx2 v137, v[156:157], s[100:101] offset:0
	global_store_dwordx2 v137, v[158:159], s[100:101] offset:512
	global_store_dwordx2 v137, v[160:161], s[100:101] offset:1024
	global_store_dwordx2 v137, v[162:163], s[100:101] offset:1536
	v_mul_f32_e32 v138, v0, v0
	v_mul_f32_e32 v149, v1, v1
	v_mul_f32_e32 v150, v2, v2
	v_mul_f32_e32 v154, v3, v3
	v_fma_f32 v138, v4, v4, v138
	v_fma_f32 v149, v5, v5, v149
	v_fma_f32 v150, v6, v6, v150
	v_fma_f32 v154, v7, v7, v154
	v_fma_f32 v138, v8, v8, v138
	v_fma_f32 v149, v9, v9, v149
	v_fma_f32 v150, v10, v10, v150
	v_fma_f32 v154, v11, v11, v154
	v_fma_f32 v138, v12, v12, v138
	v_fma_f32 v149, v13, v13, v149
	v_fma_f32 v150, v14, v14, v150
	v_fma_f32 v154, v15, v15, v154
	v_add_f32_e32 v138, v138, v149
	v_add_f32_e32 v150, v150, v154
	v_add_f32_e32 v138, v138, v150
	s_nop 1
	v_add_f32_dpp v138, v138, v138 quad_perm:[1,0,3,2] row_mask:0xf bank_mask:0xf
	s_nop 1
	v_add_f32_dpp v138, v138, v138 quad_perm:[2,3,0,1] row_mask:0xf bank_mask:0xf
	s_nop 1
	v_add_f32_dpp v138, v138, v138 row_half_mirror row_mask:0xf bank_mask:0xf
	s_nop 1
	v_add_f32_dpp v138, v138, v138 row_mirror row_mask:0xf bank_mask:0xf
	v_mov_b32_e32 v139, v138
	s_nop 1
	v_permlane16_swap_b32_e32 v138, v139
	v_add_f32_e32 v138, v138, v139
	v_mov_b32_e32 v139, v138
	s_nop 1
	v_permlane32_swap_b32_e32 v138, v139
	v_add_f32_e32 v138, v138, v139
	v_mul_f32_e32 v138, 0x3a800000, v138
	v_add_f32_e32 v138, 0x358637bd, v138
	v_rsq_f32_e32 v140, v138
	s_nop 0
	v_mul_f32_e32 v120, v0, v140
	v_mul_f32_e32 v121, v1, v140
	v_mul_f32_e32 v122, v2, v140
	v_mul_f32_e32 v123, v3, v140
	v_mul_f32_e32 v124, v4, v140
	v_mul_f32_e32 v125, v5, v140
	v_mul_f32_e32 v126, v6, v140
	v_mul_f32_e32 v127, v7, v140
	v_mul_f32_e32 v128, v8, v140
	v_mul_f32_e32 v129, v9, v140
	v_mul_f32_e32 v130, v10, v140
	v_mul_f32_e32 v131, v11, v140
	v_mul_f32_e32 v132, v12, v140
	v_mul_f32_e32 v133, v13, v140
	v_mul_f32_e32 v134, v14, v140
	v_mul_f32_e32 v135, v15, v140
	v_fma_f32 v120, v120, v88, v104
	v_fma_f32 v121, v121, v89, v105
	v_fma_f32 v122, v122, v90, v106
	v_fma_f32 v123, v123, v91, v107
	v_fma_f32 v124, v124, v92, v108
	v_fma_f32 v125, v125, v93, v109
	v_fma_f32 v126, v126, v94, v110
	v_fma_f32 v127, v127, v95, v111
	v_fma_f32 v128, v128, v96, v112
	v_fma_f32 v129, v129, v97, v113
	v_fma_f32 v130, v130, v98, v114
	v_fma_f32 v131, v131, v99, v115
	v_fma_f32 v132, v132, v100, v116
	v_fma_f32 v133, v133, v101, v117
	v_fma_f32 v134, v134, v102, v118
	v_fma_f32 v135, v135, v103, v119
	v_cvt_pk_bf16_f32 v156, v120, v121
	v_cvt_pk_bf16_f32 v157, v122, v123
	v_cvt_pk_bf16_f32 v158, v124, v125
	v_cvt_pk_bf16_f32 v159, v126, v127
	v_cvt_pk_bf16_f32 v160, v128, v129
	v_cvt_pk_bf16_f32 v161, v130, v131
	v_cvt_pk_bf16_f32 v162, v132, v133
	v_cvt_pk_bf16_f32 v163, v134, v135
	s_lshl_b32 vcc_lo, s19, 11
	s_add_u32 vcc_lo, vcc_lo, 0x1800000
	s_add_u32 s100, s14, vcc_lo
	s_addc_u32 s101, s15, 0
	global_store_dwordx2 v137, v[156:157], s[100:101] offset:0
	global_store_dwordx2 v137, v[158:159], s[100:101] offset:512
	global_store_dwordx2 v137, v[160:161], s[100:101] offset:1024
	global_store_dwordx2 v137, v[162:163], s[100:101] offset:1536
	s_lshl_b32 vcc_lo, s19, 11
	s_add_u32 vcc_lo, vcc_lo, 0x2400000
	s_add_u32 s100, s12, vcc_lo
	s_addc_u32 s101, s13, 0
	global_load_dwordx2 v[8:9], v137, s[100:101] offset:0
	global_load_dwordx2 v[10:11], v137, s[100:101] offset:512
	global_load_dwordx2 v[12:13], v137, s[100:101] offset:1024
	global_load_dwordx2 v[14:15], v137, s[100:101] offset:1536
	s_lshl_b32 vcc_lo, s19, 11
	s_add_u32 vcc_lo, vcc_lo, 0x2400000
	s_add_u32 s100, s14, vcc_lo
	s_addc_u32 s101, s15, 0
	global_load_dwordx2 v[48:49], v137, s[100:101] offset:0
	global_load_dwordx2 v[50:51], v137, s[100:101] offset:512
	global_load_dwordx2 v[52:53], v137, s[100:101] offset:1024
	global_load_dwordx2 v[54:55], v137, s[100:101] offset:1536
	s_waitcnt vmcnt(32)
; __device__ __forceinline__ void row_phase(const Params& P, int glayer, int layer, int xsrc, bool hasY, int gate_idx, const float* gpost,
;                           int xdst, bool doH, const float* gpre, int sh_idx, int nrows) {
;     ...
;         if (hasY) {
;           float4 yv[4];
;           float ss = 0.f;
; #pragma unroll
;           for (int i = 0; i < 4; ++i) {
;             const uint2 raw = yy[u][i];
;             yv[i].x = bf2f((u16)(raw.x & 0xffff)); yv[i].y = bf2f((u16)(raw.x >> 16));
;             yv[i].z = bf2f((u16)(raw.y & 0xffff)); yv[i].w = bf2f((u16)(raw.y >> 16));
;             ss += yv[i].x * yv[i].x + yv[i].y * yv[i].y + yv[i].z * yv[i].z + yv[i].w * yv[i].w;
;           }
;           ss = wave_sum(ss);
;           const float rstd = __builtin_amdgcn_rsqf(ss * (1.f / 1024.f) + EPSF);
; #pragma unroll
;           for (int i = 0; i < 4; ++i) {
;             const int col = (i * 64 + lane) * 4;
;             const float4 gt = *reinterpret_cast<const float4*>(modg + gate_idx * 1024 + col);
;             const float4 gp = *reinterpret_cast<const float4*>(gpost + col);
;             xv[i].x += gt.x * (yv[i].x * rstd * gp.x); xv[i].y += gt.y * (yv[i].y * rstd * gp.y);
;             xv[i].z += gt.z * (yv[i].z * rstd * gp.z); xv[i].w += gt.w * (yv[i].w * rstd * gp.w);
;           }
;         }
;         if (xdst == 3 || (xdst == 1 && row >= N_X)) {
;           float* xout = (xdst == 3) ? P.out + (long)row * 1024 : P.xc + (long)(row - N_X) * 1024;
; #pragma unroll
;           for (int i = 0; i < 4; ++i) *reinterpret_cast<float4*>(xout + (i * 64 + lane) * 4) = xv[i];
;         } else if (xdst != 0) {
;           u16* xo = ((xdst == 1) ? resA : P.zf) + (long)row * 1024;
; #pragma unroll
;           for (int i = 0; i < 4; ++i) {
;             const unsigned b0 = f2bf(xv[i].x), b1 = f2bf(xv[i].y), b2 = f2bf(xv[i].z), b3 = f2bf(xv[i].w);
;             *reinterpret_cast<uint2*>(xo + (i * 64 + lane) * 4) = make_uint2(b0 | (b1 << 16), b2 | (b3 << 16));
;           }
;         }
;         if (doH) {
;           float ss = 0.f;
; #pragma unroll
;           for (int i = 0; i < 4; ++i) ss += xv[i].x * xv[i].x + xv[i].y * xv[i].y + xv[i].z * xv[i].z + xv[i].w * xv[i].w;
;           ss = wave_sum(ss);
;           const float rstd = __builtin_amdgcn_rsqf(ss * (1.f / 1024.f) + EPSF);
;           u16* h = P.hy + (long)row * 1024;
; #pragma unroll
	v_lshlrev_b32_e32 v120, 16, v56
	v_and_b32_e32 v121, 0xffff0000, v56
	v_lshlrev_b32_e32 v122, 16, v57
	v_and_b32_e32 v123, 0xffff0000, v57
	v_lshlrev_b32_e32 v124, 16, v58
	v_and_b32_e32 v125, 0xffff0000, v58
	v_lshlrev_b32_e32 v126, 16, v59
	v_and_b32_e32 v127, 0xffff0000, v59
	v_lshlrev_b32_e32 v128, 16, v60
	v_and_b32_e32 v129, 0xffff0000, v60
	v_lshlrev_b32_e32 v130, 16, v61
	v_and_b32_e32 v131, 0xffff0000, v61
	v_lshlrev_b32_e32 v132, 16, v62
	v_and_b32_e32 v133, 0xffff0000, v62
	v_lshlrev_b32_e32 v134, 16, v63
	v_and_b32_e32 v135, 0xffff0000, v63
	v_mul_f32_e32 v138, v120, v120
	v_mul_f32_e32 v149, v121, v121
	v_mul_f32_e32 v150, v122, v122
	v_mul_f32_e32 v154, v123, v123
	v_fma_f32 v138, v124, v124, v138
	v_fma_f32 v149, v125, v125, v149
	v_fma_f32 v150, v126, v126, v150
	v_fma_f32 v154, v127, v127, v154
	v_fma_f32 v138, v128, v128, v138
	v_fma_f32 v149, v129, v129, v149
	v_fma_f32 v150, v130, v130, v150
	v_fma_f32 v154, v131, v131, v154
	v_fma_f32 v138, v132, v132, v138
	v_fma_f32 v149, v133, v133, v149
	v_fma_f32 v150, v134, v134, v150
	v_fma_f32 v154, v135, v135, v154
	v_add_f32_e32 v138, v138, v149
	v_add_f32_e32 v150, v150, v154
	v_add_f32_e32 v138, v138, v150
	s_nop 1
	v_add_f32_dpp v138, v138, v138 quad_perm:[1,0,3,2] row_mask:0xf bank_mask:0xf
	s_nop 1
	v_add_f32_dpp v138, v138, v138 quad_perm:[2,3,0,1] row_mask:0xf bank_mask:0xf
	s_nop 1
	v_add_f32_dpp v138, v138, v138 row_half_mirror row_mask:0xf bank_mask:0xf
	s_nop 1
	v_add_f32_dpp v138, v138, v138 row_mirror row_mask:0xf bank_mask:0xf
	v_mov_b32_e32 v139, v138
	s_nop 1
	v_permlane16_swap_b32_e32 v138, v139
	v_add_f32_e32 v138, v138, v139
	v_mov_b32_e32 v139, v138
	s_nop 1
	v_permlane32_swap_b32_e32 v138, v139
	v_add_f32_e32 v138, v138, v139
	v_mul_f32_e32 v138, 0x3a800000, v138
	v_add_f32_e32 v138, 0x358637bd, v138
	v_rsq_f32_e32 v140, v138
	v_lshlrev_b32_e32 v16, 16, v24
	v_and_b32_e32 v17, 0xffff0000, v24
	v_lshlrev_b32_e32 v18, 16, v25
	v_and_b32_e32 v19, 0xffff0000, v25
	v_lshlrev_b32_e32 v20, 16, v26
	v_and_b32_e32 v21, 0xffff0000, v26
	v_lshlrev_b32_e32 v22, 16, v27
	v_and_b32_e32 v23, 0xffff0000, v27
	v_lshlrev_b32_e32 v24, 16, v28
	v_and_b32_e32 v25, 0xffff0000, v28
	v_lshlrev_b32_e32 v26, 16, v29
	v_and_b32_e32 v27, 0xffff0000, v29
	v_lshlrev_b32_e32 v28, 16, v30
	v_and_b32_e32 v29, 0xffff0000, v30
	v_lshlrev_b32_e32 v30, 16, v31
	v_and_b32_e32 v31, 0xffff0000, v31
	s_nop 0
	v_mul_f32_e32 v120, v120, v140
	v_mul_f32_e32 v121, v121, v140
	v_mul_f32_e32 v122, v122, v140
	v_mul_f32_e32 v123, v123, v140
	v_mul_f32_e32 v124, v124, v140
	v_mul_f32_e32 v125, v125, v140
	v_mul_f32_e32 v126, v126, v140
	v_mul_f32_e32 v127, v127, v140
	v_mul_f32_e32 v128, v128, v140
	v_mul_f32_e32 v129, v129, v140
	v_mul_f32_e32 v130, v130, v140
	v_mul_f32_e32 v131, v131, v140
	v_mul_f32_e32 v132, v132, v140
	v_mul_f32_e32 v133, v133, v140
	v_mul_f32_e32 v134, v134, v140
	v_mul_f32_e32 v135, v135, v140
	v_fma_f32 v16, v120, v72, v16
	v_fma_f32 v17, v121, v73, v17
	v_fma_f32 v18, v122, v74, v18
	v_fma_f32 v19, v123, v75, v19
	v_fma_f32 v20, v124, v76, v20
	v_fma_f32 v21, v125, v77, v21
	v_fma_f32 v22, v126, v78, v22
	v_fma_f32 v23, v127, v79, v23
	v_fma_f32 v24, v128, v80, v24
	v_fma_f32 v25, v129, v81, v25
	v_fma_f32 v26, v130, v82, v26
	v_fma_f32 v27, v131, v83, v27
	v_fma_f32 v28, v132, v84, v28
	v_fma_f32 v29, v133, v85, v29
	v_fma_f32 v30, v134, v86, v30
	v_fma_f32 v31, v135, v87, v31
	v_cvt_pk_bf16_f32 v156, v16, v17
	v_cvt_pk_bf16_f32 v157, v18, v19
	v_cvt_pk_bf16_f32 v158, v20, v21
	v_cvt_pk_bf16_f32 v159, v22, v23
	v_cvt_pk_bf16_f32 v160, v24, v25
	v_cvt_pk_bf16_f32 v161, v26, v27
	v_cvt_pk_bf16_f32 v162, v28, v29
	v_cvt_pk_bf16_f32 v163, v30, v31
	s_lshl_b32 vcc_lo, s19, 11
	s_add_u32 vcc_lo, vcc_lo, 0x1c00000
	s_add_u32 s100, s16, vcc_lo
	s_addc_u32 s101, s17, 0
	global_store_dwordx2 v137, v[156:157], s[100:101] offset:0
	global_store_dwordx2 v137, v[158:159], s[100:101] offset:512
	global_store_dwordx2 v137, v[160:161], s[100:101] offset:1024
	global_store_dwordx2 v137, v[162:163], s[100:101] offset:1536
	v_mul_f32_e32 v138, v16, v16
	v_mul_f32_e32 v149, v17, v17
	v_mul_f32_e32 v150, v18, v18
	v_mul_f32_e32 v154, v19, v19
	v_fma_f32 v138, v20, v20, v138
	v_fma_f32 v149, v21, v21, v149
	v_fma_f32 v150, v22, v22, v150
	v_fma_f32 v154, v23, v23, v154
	v_fma_f32 v138, v24, v24, v138
	v_fma_f32 v149, v25, v25, v149
	v_fma_f32 v150, v26, v26, v150
	v_fma_f32 v154, v27, v27, v154
	v_fma_f32 v138, v28, v28, v138
	v_fma_f32 v149, v29, v29, v149
	v_fma_f32 v150, v30, v30, v150
	v_fma_f32 v154, v31, v31, v154
	v_add_f32_e32 v138, v138, v149
	v_add_f32_e32 v150, v150, v154
	v_add_f32_e32 v138, v138, v150
	s_nop 1
	v_add_f32_dpp v138, v138, v138 quad_perm:[1,0,3,2] row_mask:0xf bank_mask:0xf
	s_nop 1
	v_add_f32_dpp v138, v138, v138 quad_perm:[2,3,0,1] row_mask:0xf bank_mask:0xf
	s_nop 1
	v_add_f32_dpp v138, v138, v138 row_half_mirror row_mask:0xf bank_mask:0xf
	s_nop 1
	v_add_f32_dpp v138, v138, v138 row_mirror row_mask:0xf bank_mask:0xf
	v_mov_b32_e32 v139, v138
	s_nop 1
	v_permlane16_swap_b32_e32 v138, v139
	v_add_f32_e32 v138, v138, v139
	v_mov_b32_e32 v139, v138
	s_nop 1
	v_permlane32_swap_b32_e32 v138, v139
	v_add_f32_e32 v138, v138, v139
	v_mul_f32_e32 v138, 0x3a800000, v138
	v_add_f32_e32 v138, 0x358637bd, v138
	v_rsq_f32_e32 v140, v138
	s_nop 0
	v_mul_f32_e32 v120, v16, v140
	v_mul_f32_e32 v121, v17, v140
	v_mul_f32_e32 v122, v18, v140
	v_mul_f32_e32 v123, v19, v140
	v_mul_f32_e32 v124, v20, v140
	v_mul_f32_e32 v125, v21, v140
	v_mul_f32_e32 v126, v22, v140
	v_mul_f32_e32 v127, v23, v140
	v_mul_f32_e32 v128, v24, v140
	v_mul_f32_e32 v129, v25, v140
	v_mul_f32_e32 v130, v26, v140
; __device__ __forceinline__ void row_phase(const Params& P, int glayer, int layer, int xsrc, bool hasY, int gate_idx, const float* gpost,
;                           int xdst, bool doH, const float* gpre, int sh_idx, int nrows) {
;     ...
;         const int mi = row < N_X ? (row >> 13) : 4;
;         const float* modp = P.mod + (long)(layer * 5 + mi) * 6144;
;         const float* modg = P.mod + (long)(glayer * 5 + mi) * 6144;
;     ...
;         if (hasY) {
;           float4 yv[4];
;           float ss = 0.f;
; #pragma unroll
;           for (int i = 0; i < 4; ++i) {
;             const uint2 raw = yy[u][i];
;             yv[i].x = bf2f((u16)(raw.x & 0xffff)); yv[i].y = bf2f((u16)(raw.x >> 16));
;             yv[i].z = bf2f((u16)(raw.y & 0xffff)); yv[i].w = bf2f((u16)(raw.y >> 16));
;             ss += yv[i].x * yv[i].x + yv[i].y * yv[i].y + yv[i].z * yv[i].z + yv[i].w * yv[i].w;
;           }
;           ss = wave_sum(ss);
;           const float rstd = __builtin_amdgcn_rsqf(ss * (1.f / 1024.f) + EPSF);
; #pragma unroll
;           for (int i = 0; i < 4; ++i) {
;             const int col = (i * 64 + lane) * 4;
;             const float4 gt = *reinterpret_cast<const float4*>(modg + gate_idx * 1024 + col);
;             const float4 gp = *reinterpret_cast<const float4*>(gpost + col);
;             xv[i].x += gt.x * (yv[i].x * rstd * gp.x); xv[i].y += gt.y * (yv[i].y * rstd * gp.y);
;             xv[i].z += gt.z * (yv[i].z * rstd * gp.z); xv[i].w += gt.w * (yv[i].w * rstd * gp.w);
;           }
;         }
;         if (xdst == 3 || (xdst == 1 && row >= N_X)) {
;           float* xout = (xdst == 3) ? P.out + (long)row * 1024 : P.xc + (long)(row - N_X) * 1024;
; #pragma unroll
;           for (int i = 0; i < 4; ++i) *reinterpret_cast<float4*>(xout + (i * 64 + lane) * 4) = xv[i];
;         } else if (xdst != 0) {
;           u16* xo = ((xdst == 1) ? resA : P.zf) + (long)row * 1024;
; #pragma unroll
;           for (int i = 0; i < 4; ++i) {
;             const unsigned b0 = f2bf(xv[i].x), b1 = f2bf(xv[i].y), b2 = f2bf(xv[i].z), b3 = f2bf(xv[i].w);
;             *reinterpret_cast<uint2*>(xo + (i * 64 + lane) * 4) = make_uint2(b0 | (b1 << 16), b2 | (b3 << 16));
;           }
;         }
;         if (doH) {
;           float ss = 0.f;
; #pragma unroll
;           for (int i = 0; i < 4; ++i) ss += xv[i].x * xv[i].x + xv[i].y * xv[i].y + xv[i].z * xv[i].z + xv[i].w * xv[i].w;
	v_mul_f32_e32 v131, v27, v140
	v_mul_f32_e32 v132, v28, v140
	v_mul_f32_e32 v133, v29, v140
	v_mul_f32_e32 v134, v30, v140
	v_mul_f32_e32 v135, v31, v140
	v_fma_f32 v120, v120, v88, v104
	v_fma_f32 v121, v121, v89, v105
	v_fma_f32 v122, v122, v90, v106
	v_fma_f32 v123, v123, v91, v107
	v_fma_f32 v124, v124, v92, v108
	v_fma_f32 v125, v125, v93, v109
	v_fma_f32 v126, v126, v94, v110
	v_fma_f32 v127, v127, v95, v111
	v_fma_f32 v128, v128, v96, v112
	v_fma_f32 v129, v129, v97, v113
	v_fma_f32 v130, v130, v98, v114
	v_fma_f32 v131, v131, v99, v115
	v_fma_f32 v132, v132, v100, v116
	v_fma_f32 v133, v133, v101, v117
	v_fma_f32 v134, v134, v102, v118
	v_fma_f32 v135, v135, v103, v119
	v_cvt_pk_bf16_f32 v156, v120, v121
	v_cvt_pk_bf16_f32 v157, v122, v123
	v_cvt_pk_bf16_f32 v158, v124, v125
	v_cvt_pk_bf16_f32 v159, v126, v127
	v_cvt_pk_bf16_f32 v160, v128, v129
	v_cvt_pk_bf16_f32 v161, v130, v131
	v_cvt_pk_bf16_f32 v162, v132, v133
	v_cvt_pk_bf16_f32 v163, v134, v135
	s_lshl_b32 vcc_lo, s19, 11
	s_add_u32 vcc_lo, vcc_lo, 0x1c00000
	s_add_u32 s100, s14, vcc_lo
	s_addc_u32 s101, s15, 0
	global_store_dwordx2 v137, v[156:157], s[100:101] offset:0
	global_store_dwordx2 v137, v[158:159], s[100:101] offset:512
	global_store_dwordx2 v137, v[160:161], s[100:101] offset:1024
	global_store_dwordx2 v137, v[162:163], s[100:101] offset:1536
	s_add_u32 s100, s20, 0x11000
	s_addc_u32 s101, s21, 0
	global_load_dwordx4 v[72:75], v136, s[100:101] offset:0
	global_load_dwordx4 v[76:79], v136, s[100:101] offset:1024
	global_load_dwordx4 v[80:83], v136, s[100:101] offset:2048
	global_load_dwordx4 v[84:87], v136, s[100:101] offset:3072
	s_load_dwordx2 s[98:99], s[4:5], 0x48
	s_waitcnt lgkmcnt(0)
	global_load_dwordx4 v[120:123], v136, s[98:99] offset:0
	global_load_dwordx4 v[124:127], v136, s[98:99] offset:1024
	global_load_dwordx4 v[128:131], v136, s[98:99] offset:2048
	global_load_dwordx4 v[132:135], v136, s[98:99] offset:3072
	s_add_u32 s100, s20, 0x2a000
	s_addc_u32 s101, s21, 0
	global_load_dwordx4 v[104:107], v136, s[100:101] offset:0
	global_load_dwordx4 v[108:111], v136, s[100:101] offset:1024
	global_load_dwordx4 v[112:115], v136, s[100:101] offset:2048
	global_load_dwordx4 v[116:119], v136, s[100:101] offset:3072
	s_add_u32 s100, s100, 0x1000
	s_addc_u32 s101, s101, 0
	global_load_dwordx4 v[16:19], v136, s[100:101] offset:0
	global_load_dwordx4 v[20:23], v136, s[100:101] offset:1024
	global_load_dwordx4 v[24:27], v136, s[100:101] offset:2048
	global_load_dwordx4 v[28:31], v136, s[100:101] offset:3072
	s_load_dwordx2 s[98:99], s[4:5], 0x30
	s_waitcnt lgkmcnt(0)
	s_add_u32 s98, s98, 0x1000
	s_addc_u32 s99, s99, 0
	global_load_dwordx4 v[88:91], v136, s[98:99] offset:0
	global_load_dwordx4 v[92:95], v136, s[98:99] offset:1024
	global_load_dwordx4 v[96:99], v136, s[98:99] offset:2048
	global_load_dwordx4 v[100:103], v136, s[98:99] offset:3072
	s_waitcnt vmcnt(0)
	v_mul_f32_e32 v72, v72, v120
	v_mul_f32_e32 v73, v73, v121
	v_mul_f32_e32 v74, v74, v122
	v_mul_f32_e32 v75, v75, v123
	v_mul_f32_e32 v76, v76, v124
	v_mul_f32_e32 v77, v77, v125
	v_mul_f32_e32 v78, v78, v126
	v_mul_f32_e32 v79, v79, v127
	v_mul_f32_e32 v80, v80, v128
	v_mul_f32_e32 v81, v81, v129
	v_mul_f32_e32 v82, v82, v130
	v_mul_f32_e32 v83, v83, v131
	v_mul_f32_e32 v84, v84, v132
	v_mul_f32_e32 v85, v85, v133
	v_mul_f32_e32 v86, v86, v134
	v_mul_f32_e32 v87, v87, v135
	v_fma_f32 v88, v88, v16, v88
	v_fma_f32 v89, v89, v17, v89
	v_fma_f32 v90, v90, v18, v90
	v_fma_f32 v91, v91, v19, v91
	v_fma_f32 v92, v92, v20, v92
	v_fma_f32 v93, v93, v21, v93
	v_fma_f32 v94, v94, v22, v94
	v_fma_f32 v95, v95, v23, v95
	v_fma_f32 v96, v96, v24, v96
	v_fma_f32 v97, v97, v25, v97
	v_fma_f32 v98, v98, v26, v98
	v_fma_f32 v99, v99, v27, v99
	v_fma_f32 v100, v100, v28, v100
	v_fma_f32 v101, v101, v29, v101
	v_fma_f32 v102, v102, v30, v102
	v_fma_f32 v103, v103, v31, v103
	s_lshl_b32 vcc_lo, s19, 11
	s_add_u32 vcc_lo, vcc_lo, 0x2800000
	s_add_u32 s100, s12, vcc_lo
	s_addc_u32 s101, s13, 0
	global_load_dwordx2 v[24:25], v137, s[100:101] offset:0
	global_load_dwordx2 v[26:27], v137, s[100:101] offset:512
	global_load_dwordx2 v[28:29], v137, s[100:101] offset:1024
	global_load_dwordx2 v[30:31], v137, s[100:101] offset:1536
	s_lshl_b32 vcc_lo, s19, 11
	s_add_u32 vcc_lo, vcc_lo, 0x2800000
	s_add_u32 s100, s14, vcc_lo
	s_addc_u32 s101, s15, 0
	global_load_dwordx2 v[56:57], v137, s[100:101] offset:0
	global_load_dwordx2 v[58:59], v137, s[100:101] offset:512
	global_load_dwordx2 v[60:61], v137, s[100:101] offset:1024
	global_load_dwordx2 v[62:63], v137, s[100:101] offset:1536
	v_lshlrev_b32_e32 v120, 16, v64
	v_and_b32_e32 v121, 0xffff0000, v64
	v_lshlrev_b32_e32 v122, 16, v65
	v_and_b32_e32 v123, 0xffff0000, v65
	v_lshlrev_b32_e32 v124, 16, v66
	v_and_b32_e32 v125, 0xffff0000, v66
	v_lshlrev_b32_e32 v126, 16, v67
	v_and_b32_e32 v127, 0xffff0000, v67
	v_lshlrev_b32_e32 v128, 16, v68
	v_and_b32_e32 v129, 0xffff0000, v68
	v_lshlrev_b32_e32 v130, 16, v69
	v_and_b32_e32 v131, 0xffff0000, v69
	v_lshlrev_b32_e32 v132, 16, v70
	v_and_b32_e32 v133, 0xffff0000, v70
	v_lshlrev_b32_e32 v134, 16, v71
	v_and_b32_e32 v135, 0xffff0000, v71
	v_mul_f32_e32 v138, v120, v120
	v_mul_f32_e32 v149, v121, v121
	v_mul_f32_e32 v150, v122, v122
	v_mul_f32_e32 v154, v123, v123
	v_fma_f32 v138, v124, v124, v138
	v_fma_f32 v149, v125, v125, v149
	v_fma_f32 v150, v126, v126, v150
	v_fma_f32 v154, v127, v127, v154
	v_fma_f32 v138, v128, v128, v138
	v_fma_f32 v149, v129, v129, v149
	v_fma_f32 v150, v130, v130, v150
	v_fma_f32 v154, v131, v131, v154
	v_fma_f32 v138, v132, v132, v138
	v_fma_f32 v149, v133, v133, v149
	v_fma_f32 v150, v134, v134, v150
; __device__ __forceinline__ void row_phase(const Params& P, int glayer, int layer, int xsrc, bool hasY, int gate_idx, const float* gpost,
;                           int xdst, bool doH, const float* gpre, int sh_idx, int nrows) {
;     ...
;         if (hasY) {
;           float4 yv[4];
;           float ss = 0.f;
; #pragma unroll
;           for (int i = 0; i < 4; ++i) {
;             const uint2 raw = yy[u][i];
;             yv[i].x = bf2f((u16)(raw.x & 0xffff)); yv[i].y = bf2f((u16)(raw.x >> 16));
;             yv[i].z = bf2f((u16)(raw.y & 0xffff)); yv[i].w = bf2f((u16)(raw.y >> 16));
;             ss += yv[i].x * yv[i].x + yv[i].y * yv[i].y + yv[i].z * yv[i].z + yv[i].w * yv[i].w;
;           }
;           ss = wave_sum(ss);
;           const float rstd = __builtin_amdgcn_rsqf(ss * (1.f / 1024.f) + EPSF);
; #pragma unroll
;           for (int i = 0; i < 4; ++i) {
;             const int col = (i * 64 + lane) * 4;
;             const float4 gt = *reinterpret_cast<const float4*>(modg + gate_idx * 1024 + col);
;             const float4 gp = *reinterpret_cast<const float4*>(gpost + col);
;             xv[i].x += gt.x * (yv[i].x * rstd * gp.x); xv[i].y += gt.y * (yv[i].y * rstd * gp.y);
;             xv[i].z += gt.z * (yv[i].z * rstd * gp.z); xv[i].w += gt.w * (yv[i].w * rstd * gp.w);
;           }
;         }
;         if (xdst == 3 || (xdst == 1 && row >= N_X)) {
;           float* xout = (xdst == 3) ? P.out + (long)row * 1024 : P.xc + (long)(row - N_X) * 1024;
; #pragma unroll
;           for (int i = 0; i < 4; ++i) *reinterpret_cast<float4*>(xout + (i * 64 + lane) * 4) = xv[i];
;         } else if (xdst != 0) {
;           u16* xo = ((xdst == 1) ? resA : P.zf) + (long)row * 1024;
; #pragma unroll
;           for (int i = 0; i < 4; ++i) {
;             const unsigned b0 = f2bf(xv[i].x), b1 = f2bf(xv[i].y), b2 = f2bf(xv[i].z), b3 = f2bf(xv[i].w);
;             *reinterpret_cast<uint2*>(xo + (i * 64 + lane) * 4) = make_uint2(b0 | (b1 << 16), b2 | (b3 << 16));
;           }
;         }
;         if (doH) {
;           float ss = 0.f;
; #pragma unroll
;           for (int i = 0; i < 4; ++i) ss += xv[i].x * xv[i].x + xv[i].y * xv[i].y + xv[i].z * xv[i].z + xv[i].w * xv[i].w;
;           ss = wave_sum(ss);
;           const float rstd = __builtin_amdgcn_rsqf(ss * (1.f / 1024.f) + EPSF);
;           u16* h = P.hy + (long)row * 1024;
; #pragma unroll
	v_fma_f32 v154, v135, v135, v154
	v_add_f32_e32 v138, v138, v149
	v_add_f32_e32 v150, v150, v154
	v_add_f32_e32 v138, v138, v150
	s_nop 1
	v_add_f32_dpp v138, v138, v138 quad_perm:[1,0,3,2] row_mask:0xf bank_mask:0xf
	s_nop 1
	v_add_f32_dpp v138, v138, v138 quad_perm:[2,3,0,1] row_mask:0xf bank_mask:0xf
	s_nop 1
	v_add_f32_dpp v138, v138, v138 row_half_mirror row_mask:0xf bank_mask:0xf
	s_nop 1
	v_add_f32_dpp v138, v138, v138 row_mirror row_mask:0xf bank_mask:0xf
	v_mov_b32_e32 v139, v138
	s_nop 1
	v_permlane16_swap_b32_e32 v138, v139
	v_add_f32_e32 v138, v138, v139
	v_mov_b32_e32 v139, v138
	s_nop 1
	v_permlane32_swap_b32_e32 v138, v139
	v_add_f32_e32 v138, v138, v139
	v_mul_f32_e32 v138, 0x3a800000, v138
	v_add_f32_e32 v138, 0x358637bd, v138
	v_rsq_f32_e32 v140, v138
	v_lshlrev_b32_e32 v32, 16, v40
	v_and_b32_e32 v33, 0xffff0000, v40
	v_lshlrev_b32_e32 v34, 16, v41
	v_and_b32_e32 v35, 0xffff0000, v41
	v_lshlrev_b32_e32 v36, 16, v42
	v_and_b32_e32 v37, 0xffff0000, v42
	v_lshlrev_b32_e32 v38, 16, v43
	v_and_b32_e32 v39, 0xffff0000, v43
	v_lshlrev_b32_e32 v40, 16, v44
	v_and_b32_e32 v41, 0xffff0000, v44
	v_lshlrev_b32_e32 v42, 16, v45
	v_and_b32_e32 v43, 0xffff0000, v45
	v_lshlrev_b32_e32 v44, 16, v46
	v_and_b32_e32 v45, 0xffff0000, v46
	v_lshlrev_b32_e32 v46, 16, v47
	v_and_b32_e32 v47, 0xffff0000, v47
	s_nop 0
	v_mul_f32_e32 v120, v120, v140
	v_mul_f32_e32 v121, v121, v140
	v_mul_f32_e32 v122, v122, v140
	v_mul_f32_e32 v123, v123, v140
	v_mul_f32_e32 v124, v124, v140
	v_mul_f32_e32 v125, v125, v140
	v_mul_f32_e32 v126, v126, v140
	v_mul_f32_e32 v127, v127, v140
	v_mul_f32_e32 v128, v128, v140
	v_mul_f32_e32 v129, v129, v140
	v_mul_f32_e32 v130, v130, v140
	v_mul_f32_e32 v131, v131, v140
	v_mul_f32_e32 v132, v132, v140
	v_mul_f32_e32 v133, v133, v140
	v_mul_f32_e32 v134, v134, v140
	v_mul_f32_e32 v135, v135, v140
	v_fma_f32 v32, v120, v72, v32
	v_fma_f32 v33, v121, v73, v33
	v_fma_f32 v34, v122, v74, v34
	v_fma_f32 v35, v123, v75, v35
	v_fma_f32 v36, v124, v76, v36
	v_fma_f32 v37, v125, v77, v37
	v_fma_f32 v38, v126, v78, v38
	v_fma_f32 v39, v127, v79, v39
	v_fma_f32 v40, v128, v80, v40
	v_fma_f32 v41, v129, v81, v41
	v_fma_f32 v42, v130, v82, v42
	v_fma_f32 v43, v131, v83, v43
	v_fma_f32 v44, v132, v84, v44
	v_fma_f32 v45, v133, v85, v45
	v_fma_f32 v46, v134, v86, v46
	v_fma_f32 v47, v135, v87, v47
	v_cvt_pk_bf16_f32 v156, v32, v33
	v_cvt_pk_bf16_f32 v157, v34, v35
	v_cvt_pk_bf16_f32 v158, v36, v37
	v_cvt_pk_bf16_f32 v159, v38, v39
	v_cvt_pk_bf16_f32 v160, v40, v41
	v_cvt_pk_bf16_f32 v161, v42, v43
	v_cvt_pk_bf16_f32 v162, v44, v45
	v_cvt_pk_bf16_f32 v163, v46, v47
	s_lshl_b32 vcc_lo, s19, 11
	s_add_u32 vcc_lo, vcc_lo, 0x2000000
	s_add_u32 s100, s16, vcc_lo
	s_addc_u32 s101, s17, 0
	global_store_dwordx2 v137, v[156:157], s[100:101] offset:0
	global_store_dwordx2 v137, v[158:159], s[100:101] offset:512
	global_store_dwordx2 v137, v[160:161], s[100:101] offset:1024
	global_store_dwordx2 v137, v[162:163], s[100:101] offset:1536
	v_mul_f32_e32 v138, v32, v32
	v_mul_f32_e32 v149, v33, v33
	v_mul_f32_e32 v150, v34, v34
	v_mul_f32_e32 v154, v35, v35
	v_fma_f32 v138, v36, v36, v138
	v_fma_f32 v149, v37, v37, v149
	v_fma_f32 v150, v38, v38, v150
	v_fma_f32 v154, v39, v39, v154
	v_fma_f32 v138, v40, v40, v138
	v_fma_f32 v149, v41, v41, v149
	v_fma_f32 v150, v42, v42, v150
	v_fma_f32 v154, v43, v43, v154
	v_fma_f32 v138, v44, v44, v138
	v_fma_f32 v149, v45, v45, v149
	v_fma_f32 v150, v46, v46, v150
	v_fma_f32 v154, v47, v47, v154
	v_add_f32_e32 v138, v138, v149
	v_add_f32_e32 v150, v150, v154
	v_add_f32_e32 v138, v138, v150
	s_nop 1
	v_add_f32_dpp v138, v138, v138 quad_perm:[1,0,3,2] row_mask:0xf bank_mask:0xf
	s_nop 1
	v_add_f32_dpp v138, v138, v138 quad_perm:[2,3,0,1] row_mask:0xf bank_mask:0xf
	s_nop 1
	v_add_f32_dpp v138, v138, v138 row_half_mirror row_mask:0xf bank_mask:0xf
	s_nop 1
	v_add_f32_dpp v138, v138, v138 row_mirror row_mask:0xf bank_mask:0xf
	v_mov_b32_e32 v139, v138
	s_nop 1
	v_permlane16_swap_b32_e32 v138, v139
	v_add_f32_e32 v138, v138, v139
	v_mov_b32_e32 v139, v138
	s_nop 1
	v_permlane32_swap_b32_e32 v138, v139
	v_add_f32_e32 v138, v138, v139
	v_mul_f32_e32 v138, 0x3a800000, v138
	v_add_f32_e32 v138, 0x358637bd, v138
	v_rsq_f32_e32 v140, v138
	s_nop 0
	v_mul_f32_e32 v120, v32, v140
	v_mul_f32_e32 v121, v33, v140
	v_mul_f32_e32 v122, v34, v140
	v_mul_f32_e32 v123, v35, v140
	v_mul_f32_e32 v124, v36, v140
	v_mul_f32_e32 v125, v37, v140
	v_mul_f32_e32 v126, v38, v140
	v_mul_f32_e32 v127, v39, v140
	v_mul_f32_e32 v128, v40, v140
	v_mul_f32_e32 v129, v41, v140
	v_mul_f32_e32 v130, v42, v140
	v_mul_f32_e32 v131, v43, v140
	v_mul_f32_e32 v132, v44, v140
	v_mul_f32_e32 v133, v45, v140
	v_mul_f32_e32 v134, v46, v140
	v_mul_f32_e32 v135, v47, v140
	v_fma_f32 v120, v120, v88, v104
	v_fma_f32 v121, v121, v89, v105
	v_fma_f32 v122, v122, v90, v106
	v_fma_f32 v123, v123, v91, v107
	v_fma_f32 v124, v124, v92, v108
	v_fma_f32 v125, v125, v93, v109
	v_fma_f32 v126, v126, v94, v110
	v_fma_f32 v127, v127, v95, v111
	v_fma_f32 v128, v128, v96, v112
	v_fma_f32 v129, v129, v97, v113
	v_fma_f32 v130, v130, v98, v114
	v_fma_f32 v131, v131, v99, v115
	v_fma_f32 v132, v132, v100, v116
	v_fma_f32 v133, v133, v101, v117
	v_fma_f32 v134, v134, v102, v118
	v_fma_f32 v135, v135, v103, v119
	v_cvt_pk_bf16_f32 v156, v120, v121
	v_cvt_pk_bf16_f32 v157, v122, v123
	v_cvt_pk_bf16_f32 v158, v124, v125
	v_cvt_pk_bf16_f32 v159, v126, v127
	v_cvt_pk_bf16_f32 v160, v128, v129
	v_cvt_pk_bf16_f32 v161, v130, v131
	v_cvt_pk_bf16_f32 v162, v132, v133
	v_cvt_pk_bf16_f32 v163, v134, v135
	s_lshl_b32 vcc_lo, s19, 11
	s_add_u32 vcc_lo, vcc_lo, 0x2000000
	s_add_u32 s100, s14, vcc_lo
; __device__ __forceinline__ void row_phase(const Params& P, int glayer, int layer, int xsrc, bool hasY, int gate_idx, const float* gpost,
;                           int xdst, bool doH, const float* gpre, int sh_idx, int nrows) {
;     ...
;         if (hasY) {
;           float4 yv[4];
;           float ss = 0.f;
; #pragma unroll
;           for (int i = 0; i < 4; ++i) {
;             const uint2 raw = yy[u][i];
;             yv[i].x = bf2f((u16)(raw.x & 0xffff)); yv[i].y = bf2f((u16)(raw.x >> 16));
;             yv[i].z = bf2f((u16)(raw.y & 0xffff)); yv[i].w = bf2f((u16)(raw.y >> 16));
;             ss += yv[i].x * yv[i].x + yv[i].y * yv[i].y + yv[i].z * yv[i].z + yv[i].w * yv[i].w;
;           }
;           ss = wave_sum(ss);
;           const float rstd = __builtin_amdgcn_rsqf(ss * (1.f / 1024.f) + EPSF);
; #pragma unroll
;           for (int i = 0; i < 4; ++i) {
;             const int col = (i * 64 + lane) * 4;
;             const float4 gt = *reinterpret_cast<const float4*>(modg + gate_idx * 1024 + col);
;             const float4 gp = *reinterpret_cast<const float4*>(gpost + col);
;             xv[i].x += gt.x * (yv[i].x * rstd * gp.x); xv[i].y += gt.y * (yv[i].y * rstd * gp.y);
;             xv[i].z += gt.z * (yv[i].z * rstd * gp.z); xv[i].w += gt.w * (yv[i].w * rstd * gp.w);
;           }
;         }
;         if (xdst == 3 || (xdst == 1 && row >= N_X)) {
;           float* xout = (xdst == 3) ? P.out + (long)row * 1024 : P.xc + (long)(row - N_X) * 1024;
; #pragma unroll
;           for (int i = 0; i < 4; ++i) *reinterpret_cast<float4*>(xout + (i * 64 + lane) * 4) = xv[i];
;         } else if (xdst != 0) {
;           u16* xo = ((xdst == 1) ? resA : P.zf) + (long)row * 1024;
; #pragma unroll
;           for (int i = 0; i < 4; ++i) {
;             const unsigned b0 = f2bf(xv[i].x), b1 = f2bf(xv[i].y), b2 = f2bf(xv[i].z), b3 = f2bf(xv[i].w);
;             *reinterpret_cast<uint2*>(xo + (i * 64 + lane) * 4) = make_uint2(b0 | (b1 << 16), b2 | (b3 << 16));
;           }
;         }
;         if (doH) {
;           float ss = 0.f;
; #pragma unroll
;           for (int i = 0; i < 4; ++i) ss += xv[i].x * xv[i].x + xv[i].y * xv[i].y + xv[i].z * xv[i].z + xv[i].w * xv[i].w;
;           ss = wave_sum(ss);
;           const float rstd = __builtin_amdgcn_rsqf(ss * (1.f / 1024.f) + EPSF);
;           u16* h = P.hy + (long)row * 1024;
; #pragma unroll
	s_addc_u32 s101, s15, 0
	global_store_dwordx2 v137, v[156:157], s[100:101] offset:0
	global_store_dwordx2 v137, v[158:159], s[100:101] offset:512
	global_store_dwordx2 v137, v[160:161], s[100:101] offset:1024
	global_store_dwordx2 v137, v[162:163], s[100:101] offset:1536
	s_lshl_b32 vcc_lo, s19, 11
	s_add_u32 vcc_lo, vcc_lo, 0x2c00000
	s_add_u32 s100, s12, vcc_lo
	s_addc_u32 s101, s13, 0
	global_load_dwordx2 v[40:41], v137, s[100:101] offset:0
	global_load_dwordx2 v[42:43], v137, s[100:101] offset:512
	global_load_dwordx2 v[44:45], v137, s[100:101] offset:1024
	global_load_dwordx2 v[46:47], v137, s[100:101] offset:1536
	s_lshl_b32 vcc_lo, s19, 11
	s_add_u32 vcc_lo, vcc_lo, 0x2c00000
	s_add_u32 s100, s14, vcc_lo
	s_addc_u32 s101, s15, 0
	global_load_dwordx2 v[64:65], v137, s[100:101] offset:0
	global_load_dwordx2 v[66:67], v137, s[100:101] offset:512
	global_load_dwordx2 v[68:69], v137, s[100:101] offset:1024
	global_load_dwordx2 v[70:71], v137, s[100:101] offset:1536
	v_lshlrev_b32_e32 v120, 16, v48
	v_and_b32_e32 v121, 0xffff0000, v48
	v_lshlrev_b32_e32 v122, 16, v49
	v_and_b32_e32 v123, 0xffff0000, v49
	v_lshlrev_b32_e32 v124, 16, v50
	v_and_b32_e32 v125, 0xffff0000, v50
	v_lshlrev_b32_e32 v126, 16, v51
	v_and_b32_e32 v127, 0xffff0000, v51
	v_lshlrev_b32_e32 v128, 16, v52
	v_and_b32_e32 v129, 0xffff0000, v52
	v_lshlrev_b32_e32 v130, 16, v53
	v_and_b32_e32 v131, 0xffff0000, v53
	v_lshlrev_b32_e32 v132, 16, v54
	v_and_b32_e32 v133, 0xffff0000, v54
	v_lshlrev_b32_e32 v134, 16, v55
	v_and_b32_e32 v135, 0xffff0000, v55
	v_mul_f32_e32 v138, v120, v120
	v_mul_f32_e32 v149, v121, v121
	v_mul_f32_e32 v150, v122, v122
	v_mul_f32_e32 v154, v123, v123
	v_fma_f32 v138, v124, v124, v138
	v_fma_f32 v149, v125, v125, v149
	v_fma_f32 v150, v126, v126, v150
	v_fma_f32 v154, v127, v127, v154
	v_fma_f32 v138, v128, v128, v138
	v_fma_f32 v149, v129, v129, v149
	v_fma_f32 v150, v130, v130, v150
	v_fma_f32 v154, v131, v131, v154
	v_fma_f32 v138, v132, v132, v138
	v_fma_f32 v149, v133, v133, v149
	v_fma_f32 v150, v134, v134, v150
	v_fma_f32 v154, v135, v135, v154
	v_add_f32_e32 v138, v138, v149
	v_add_f32_e32 v150, v150, v154
	v_add_f32_e32 v138, v138, v150
	s_nop 1
	v_add_f32_dpp v138, v138, v138 quad_perm:[1,0,3,2] row_mask:0xf bank_mask:0xf
	s_nop 1
	v_add_f32_dpp v138, v138, v138 quad_perm:[2,3,0,1] row_mask:0xf bank_mask:0xf
	s_nop 1
	v_add_f32_dpp v138, v138, v138 row_half_mirror row_mask:0xf bank_mask:0xf
	s_nop 1
	v_add_f32_dpp v138, v138, v138 row_mirror row_mask:0xf bank_mask:0xf
	v_mov_b32_e32 v139, v138
	s_nop 1
	v_permlane16_swap_b32_e32 v138, v139
	v_add_f32_e32 v138, v138, v139
	v_mov_b32_e32 v139, v138
	s_nop 1
	v_permlane32_swap_b32_e32 v138, v139
	v_add_f32_e32 v138, v138, v139
	v_mul_f32_e32 v138, 0x3a800000, v138
	v_add_f32_e32 v138, 0x358637bd, v138
	v_rsq_f32_e32 v140, v138
	v_lshlrev_b32_e32 v0, 16, v8
	v_and_b32_e32 v1, 0xffff0000, v8
	v_lshlrev_b32_e32 v2, 16, v9
	v_and_b32_e32 v3, 0xffff0000, v9
	v_lshlrev_b32_e32 v4, 16, v10
	v_and_b32_e32 v5, 0xffff0000, v10
	v_lshlrev_b32_e32 v6, 16, v11
	v_and_b32_e32 v7, 0xffff0000, v11
	v_lshlrev_b32_e32 v8, 16, v12
	v_and_b32_e32 v9, 0xffff0000, v12
	v_lshlrev_b32_e32 v10, 16, v13
	v_and_b32_e32 v11, 0xffff0000, v13
	v_lshlrev_b32_e32 v12, 16, v14
	v_and_b32_e32 v13, 0xffff0000, v14
	v_lshlrev_b32_e32 v14, 16, v15
	v_and_b32_e32 v15, 0xffff0000, v15
	s_nop 0
	v_mul_f32_e32 v120, v120, v140
	v_mul_f32_e32 v121, v121, v140
	v_mul_f32_e32 v122, v122, v140
	v_mul_f32_e32 v123, v123, v140
	v_mul_f32_e32 v124, v124, v140
	v_mul_f32_e32 v125, v125, v140
	v_mul_f32_e32 v126, v126, v140
	v_mul_f32_e32 v127, v127, v140
	v_mul_f32_e32 v128, v128, v140
	v_mul_f32_e32 v129, v129, v140
	v_mul_f32_e32 v130, v130, v140
	v_mul_f32_e32 v131, v131, v140
	v_mul_f32_e32 v132, v132, v140
	v_mul_f32_e32 v133, v133, v140
	v_mul_f32_e32 v134, v134, v140
	v_mul_f32_e32 v135, v135, v140
	v_fma_f32 v0, v120, v72, v0
	v_fma_f32 v1, v121, v73, v1
	v_fma_f32 v2, v122, v74, v2
	v_fma_f32 v3, v123, v75, v3
	v_fma_f32 v4, v124, v76, v4
	v_fma_f32 v5, v125, v77, v5
	v_fma_f32 v6, v126, v78, v6
	v_fma_f32 v7, v127, v79, v7
	v_fma_f32 v8, v128, v80, v8
	v_fma_f32 v9, v129, v81, v9
	v_fma_f32 v10, v130, v82, v10
	v_fma_f32 v11, v131, v83, v11
	v_fma_f32 v12, v132, v84, v12
	v_fma_f32 v13, v133, v85, v13
	v_fma_f32 v14, v134, v86, v14
	v_fma_f32 v15, v135, v87, v15
	v_cvt_pk_bf16_f32 v156, v0, v1
	v_cvt_pk_bf16_f32 v157, v2, v3
	v_cvt_pk_bf16_f32 v158, v4, v5
	v_cvt_pk_bf16_f32 v159, v6, v7
	v_cvt_pk_bf16_f32 v160, v8, v9
	v_cvt_pk_bf16_f32 v161, v10, v11
	v_cvt_pk_bf16_f32 v162, v12, v13
	v_cvt_pk_bf16_f32 v163, v14, v15
	s_lshl_b32 vcc_lo, s19, 11
	s_add_u32 vcc_lo, vcc_lo, 0x2400000
	s_add_u32 s100, s16, vcc_lo
	s_addc_u32 s101, s17, 0
	global_store_dwordx2 v137, v[156:157], s[100:101] offset:0
	global_store_dwordx2 v137, v[158:159], s[100:101] offset:512
	global_store_dwordx2 v137, v[160:161], s[100:101] offset:1024
	global_store_dwordx2 v137, v[162:163], s[100:101] offset:1536
	v_mul_f32_e32 v138, v0, v0
	v_mul_f32_e32 v149, v1, v1
	v_mul_f32_e32 v150, v2, v2
	v_mul_f32_e32 v154, v3, v3
	v_fma_f32 v138, v4, v4, v138
	v_fma_f32 v149, v5, v5, v149
	v_fma_f32 v150, v6, v6, v150
	v_fma_f32 v154, v7, v7, v154
	v_fma_f32 v138, v8, v8, v138
	v_fma_f32 v149, v9, v9, v149
	v_fma_f32 v150, v10, v10, v150
	v_fma_f32 v154, v11, v11, v154
	v_fma_f32 v138, v12, v12, v138
	v_fma_f32 v149, v13, v13, v149
	v_fma_f32 v150, v14, v14, v150
	v_fma_f32 v154, v15, v15, v154
	v_add_f32_e32 v138, v138, v149
	v_add_f32_e32 v150, v150, v154
	v_add_f32_e32 v138, v138, v150
	s_nop 1
	v_add_f32_dpp v138, v138, v138 quad_perm:[1,0,3,2] row_mask:0xf bank_mask:0xf
; __device__ __forceinline__ void row_phase(const Params& P, int glayer, int layer, int xsrc, bool hasY, int gate_idx, const float* gpost,
;                           int xdst, bool doH, const float* gpre, int sh_idx, int nrows) {
;     ...
;         if (hasY) {
;           float4 yv[4];
;           float ss = 0.f;
; #pragma unroll
;           for (int i = 0; i < 4; ++i) {
;             const uint2 raw = yy[u][i];
;             yv[i].x = bf2f((u16)(raw.x & 0xffff)); yv[i].y = bf2f((u16)(raw.x >> 16));
;             yv[i].z = bf2f((u16)(raw.y & 0xffff)); yv[i].w = bf2f((u16)(raw.y >> 16));
;             ss += yv[i].x * yv[i].x + yv[i].y * yv[i].y + yv[i].z * yv[i].z + yv[i].w * yv[i].w;
;           }
;           ss = wave_sum(ss);
;           const float rstd = __builtin_amdgcn_rsqf(ss * (1.f / 1024.f) + EPSF);
; #pragma unroll
;           for (int i = 0; i < 4; ++i) {
;             const int col = (i * 64 + lane) * 4;
;             const float4 gt = *reinterpret_cast<const float4*>(modg + gate_idx * 1024 + col);
;             const float4 gp = *reinterpret_cast<const float4*>(gpost + col);
;             xv[i].x += gt.x * (yv[i].x * rstd * gp.x); xv[i].y += gt.y * (yv[i].y * rstd * gp.y);
;             xv[i].z += gt.z * (yv[i].z * rstd * gp.z); xv[i].w += gt.w * (yv[i].w * rstd * gp.w);
;           }
;         }
;         if (xdst == 3 || (xdst == 1 && row >= N_X)) {
;           float* xout = (xdst == 3) ? P.out + (long)row * 1024 : P.xc + (long)(row - N_X) * 1024;
; #pragma unroll
;           for (int i = 0; i < 4; ++i) *reinterpret_cast<float4*>(xout + (i * 64 + lane) * 4) = xv[i];
;         } else if (xdst != 0) {
;           u16* xo = ((xdst == 1) ? resA : P.zf) + (long)row * 1024;
; #pragma unroll
;           for (int i = 0; i < 4; ++i) {
;             const unsigned b0 = f2bf(xv[i].x), b1 = f2bf(xv[i].y), b2 = f2bf(xv[i].z), b3 = f2bf(xv[i].w);
;             *reinterpret_cast<uint2*>(xo + (i * 64 + lane) * 4) = make_uint2(b0 | (b1 << 16), b2 | (b3 << 16));
;           }
;         }
;         if (doH) {
;           float ss = 0.f;
; #pragma unroll
;           for (int i = 0; i < 4; ++i) ss += xv[i].x * xv[i].x + xv[i].y * xv[i].y + xv[i].z * xv[i].z + xv[i].w * xv[i].w;
;           ss = wave_sum(ss);
;           const float rstd = __builtin_amdgcn_rsqf(ss * (1.f / 1024.f) + EPSF);
;           u16* h = P.hy + (long)row * 1024;
; #pragma unroll
	s_nop 1
	v_add_f32_dpp v138, v138, v138 quad_perm:[2,3,0,1] row_mask:0xf bank_mask:0xf
	s_nop 1
	v_add_f32_dpp v138, v138, v138 row_half_mirror row_mask:0xf bank_mask:0xf
	s_nop 1
	v_add_f32_dpp v138, v138, v138 row_mirror row_mask:0xf bank_mask:0xf
	v_mov_b32_e32 v139, v138
	s_nop 1
	v_permlane16_swap_b32_e32 v138, v139
	v_add_f32_e32 v138, v138, v139
	v_mov_b32_e32 v139, v138
	s_nop 1
	v_permlane32_swap_b32_e32 v138, v139
	v_add_f32_e32 v138, v138, v139
	v_mul_f32_e32 v138, 0x3a800000, v138
	v_add_f32_e32 v138, 0x358637bd, v138
	v_rsq_f32_e32 v140, v138
	s_nop 0
	v_mul_f32_e32 v120, v0, v140
	v_mul_f32_e32 v121, v1, v140
	v_mul_f32_e32 v122, v2, v140
	v_mul_f32_e32 v123, v3, v140
	v_mul_f32_e32 v124, v4, v140
	v_mul_f32_e32 v125, v5, v140
	v_mul_f32_e32 v126, v6, v140
	v_mul_f32_e32 v127, v7, v140
	v_mul_f32_e32 v128, v8, v140
	v_mul_f32_e32 v129, v9, v140
	v_mul_f32_e32 v130, v10, v140
	v_mul_f32_e32 v131, v11, v140
	v_mul_f32_e32 v132, v12, v140
	v_mul_f32_e32 v133, v13, v140
	v_mul_f32_e32 v134, v14, v140
	v_mul_f32_e32 v135, v15, v140
	v_fma_f32 v120, v120, v88, v104
	v_fma_f32 v121, v121, v89, v105
	v_fma_f32 v122, v122, v90, v106
	v_fma_f32 v123, v123, v91, v107
	v_fma_f32 v124, v124, v92, v108
	v_fma_f32 v125, v125, v93, v109
	v_fma_f32 v126, v126, v94, v110
	v_fma_f32 v127, v127, v95, v111
	v_fma_f32 v128, v128, v96, v112
	v_fma_f32 v129, v129, v97, v113
	v_fma_f32 v130, v130, v98, v114
	v_fma_f32 v131, v131, v99, v115
	v_fma_f32 v132, v132, v100, v116
	v_fma_f32 v133, v133, v101, v117
	v_fma_f32 v134, v134, v102, v118
	v_fma_f32 v135, v135, v103, v119
	v_cvt_pk_bf16_f32 v156, v120, v121
	v_cvt_pk_bf16_f32 v157, v122, v123
	v_cvt_pk_bf16_f32 v158, v124, v125
	v_cvt_pk_bf16_f32 v159, v126, v127
	v_cvt_pk_bf16_f32 v160, v128, v129
	v_cvt_pk_bf16_f32 v161, v130, v131
	v_cvt_pk_bf16_f32 v162, v132, v133
	v_cvt_pk_bf16_f32 v163, v134, v135
	s_lshl_b32 vcc_lo, s19, 11
	s_add_u32 vcc_lo, vcc_lo, 0x2400000
	s_add_u32 s100, s14, vcc_lo
	s_addc_u32 s101, s15, 0
	global_store_dwordx2 v137, v[156:157], s[100:101] offset:0
	global_store_dwordx2 v137, v[158:159], s[100:101] offset:512
	global_store_dwordx2 v137, v[160:161], s[100:101] offset:1024
	global_store_dwordx2 v137, v[162:163], s[100:101] offset:1536
	s_lshl_b32 vcc_lo, s19, 11
	s_add_u32 vcc_lo, vcc_lo, 0x3000000
	s_add_u32 s100, s12, vcc_lo
	s_addc_u32 s101, s13, 0
	global_load_dwordx2 v[8:9], v137, s[100:101] offset:0
	global_load_dwordx2 v[10:11], v137, s[100:101] offset:512
	global_load_dwordx2 v[12:13], v137, s[100:101] offset:1024
	global_load_dwordx2 v[14:15], v137, s[100:101] offset:1536
	s_lshl_b32 vcc_lo, s19, 11
	s_add_u32 vcc_lo, vcc_lo, 0x3000000
	s_add_u32 s100, s14, vcc_lo
	s_addc_u32 s101, s15, 0
	global_load_dwordx2 v[48:49], v137, s[100:101] offset:0
	global_load_dwordx2 v[50:51], v137, s[100:101] offset:512
	global_load_dwordx2 v[52:53], v137, s[100:101] offset:1024
	global_load_dwordx2 v[54:55], v137, s[100:101] offset:1536
	s_waitcnt vmcnt(32)
	v_lshlrev_b32_e32 v120, 16, v56
	v_and_b32_e32 v121, 0xffff0000, v56
	v_lshlrev_b32_e32 v122, 16, v57
	v_and_b32_e32 v123, 0xffff0000, v57
	v_lshlrev_b32_e32 v124, 16, v58
	v_and_b32_e32 v125, 0xffff0000, v58
	v_lshlrev_b32_e32 v126, 16, v59
	v_and_b32_e32 v127, 0xffff0000, v59
	v_lshlrev_b32_e32 v128, 16, v60
	v_and_b32_e32 v129, 0xffff0000, v60
	v_lshlrev_b32_e32 v130, 16, v61
	v_and_b32_e32 v131, 0xffff0000, v61
	v_lshlrev_b32_e32 v132, 16, v62
	v_and_b32_e32 v133, 0xffff0000, v62
	v_lshlrev_b32_e32 v134, 16, v63
	v_and_b32_e32 v135, 0xffff0000, v63
	v_mul_f32_e32 v138, v120, v120
	v_mul_f32_e32 v149, v121, v121
	v_mul_f32_e32 v150, v122, v122
	v_mul_f32_e32 v154, v123, v123
	v_fma_f32 v138, v124, v124, v138
	v_fma_f32 v149, v125, v125, v149
	v_fma_f32 v150, v126, v126, v150
	v_fma_f32 v154, v127, v127, v154
	v_fma_f32 v138, v128, v128, v138
	v_fma_f32 v149, v129, v129, v149
	v_fma_f32 v150, v130, v130, v150
	v_fma_f32 v154, v131, v131, v154
	v_fma_f32 v138, v132, v132, v138
	v_fma_f32 v149, v133, v133, v149
	v_fma_f32 v150, v134, v134, v150
	v_fma_f32 v154, v135, v135, v154
	v_add_f32_e32 v138, v138, v149
	v_add_f32_e32 v150, v150, v154
	v_add_f32_e32 v138, v138, v150
	s_nop 1
	v_add_f32_dpp v138, v138, v138 quad_perm:[1,0,3,2] row_mask:0xf bank_mask:0xf
	s_nop 1
	v_add_f32_dpp v138, v138, v138 quad_perm:[2,3,0,1] row_mask:0xf bank_mask:0xf
	s_nop 1
	v_add_f32_dpp v138, v138, v138 row_half_mirror row_mask:0xf bank_mask:0xf
	s_nop 1
	v_add_f32_dpp v138, v138, v138 row_mirror row_mask:0xf bank_mask:0xf
	v_mov_b32_e32 v139, v138
	s_nop 1
	v_permlane16_swap_b32_e32 v138, v139
	v_add_f32_e32 v138, v138, v139
	v_mov_b32_e32 v139, v138
	s_nop 1
	v_permlane32_swap_b32_e32 v138, v139
	v_add_f32_e32 v138, v138, v139
	v_mul_f32_e32 v138, 0x3a800000, v138
	v_add_f32_e32 v138, 0x358637bd, v138
	v_rsq_f32_e32 v140, v138
	v_lshlrev_b32_e32 v16, 16, v24
	v_and_b32_e32 v17, 0xffff0000, v24
	v_lshlrev_b32_e32 v18, 16, v25
	v_and_b32_e32 v19, 0xffff0000, v25
	v_lshlrev_b32_e32 v20, 16, v26
	v_and_b32_e32 v21, 0xffff0000, v26
	v_lshlrev_b32_e32 v22, 16, v27
	v_and_b32_e32 v23, 0xffff0000, v27
	v_lshlrev_b32_e32 v24, 16, v28
	v_and_b32_e32 v25, 0xffff0000, v28
	v_lshlrev_b32_e32 v26, 16, v29
	v_and_b32_e32 v27, 0xffff0000, v29
	v_lshlrev_b32_e32 v28, 16, v30
	v_and_b32_e32 v29, 0xffff0000, v30
	v_lshlrev_b32_e32 v30, 16, v31
	v_and_b32_e32 v31, 0xffff0000, v31
	s_nop 0
	v_mul_f32_e32 v120, v120, v140
	v_mul_f32_e32 v121, v121, v140
	v_mul_f32_e32 v122, v122, v140
	v_mul_f32_e32 v123, v123, v140
	v_mul_f32_e32 v124, v124, v140
	v_mul_f32_e32 v125, v125, v140
	v_mul_f32_e32 v126, v126, v140
	v_mul_f32_e32 v127, v127, v140
; __device__ __forceinline__ void row_phase(const Params& P, int glayer, int layer, int xsrc, bool hasY, int gate_idx, const float* gpost,
;                           int xdst, bool doH, const float* gpre, int sh_idx, int nrows) {
;     ...
;         if (hasY) {
;           float4 yv[4];
;           float ss = 0.f;
; #pragma unroll
;           for (int i = 0; i < 4; ++i) {
;             const uint2 raw = yy[u][i];
;             yv[i].x = bf2f((u16)(raw.x & 0xffff)); yv[i].y = bf2f((u16)(raw.x >> 16));
;             yv[i].z = bf2f((u16)(raw.y & 0xffff)); yv[i].w = bf2f((u16)(raw.y >> 16));
;             ss += yv[i].x * yv[i].x + yv[i].y * yv[i].y + yv[i].z * yv[i].z + yv[i].w * yv[i].w;
;           }
;           ss = wave_sum(ss);
;           const float rstd = __builtin_amdgcn_rsqf(ss * (1.f / 1024.f) + EPSF);
; #pragma unroll
;           for (int i = 0; i < 4; ++i) {
;             const int col = (i * 64 + lane) * 4;
;             const float4 gt = *reinterpret_cast<const float4*>(modg + gate_idx * 1024 + col);
;             const float4 gp = *reinterpret_cast<const float4*>(gpost + col);
;             xv[i].x += gt.x * (yv[i].x * rstd * gp.x); xv[i].y += gt.y * (yv[i].y * rstd * gp.y);
;             xv[i].z += gt.z * (yv[i].z * rstd * gp.z); xv[i].w += gt.w * (yv[i].w * rstd * gp.w);
;           }
;         }
;         if (xdst == 3 || (xdst == 1 && row >= N_X)) {
;           float* xout = (xdst == 3) ? P.out + (long)row * 1024 : P.xc + (long)(row - N_X) * 1024;
; #pragma unroll
;           for (int i = 0; i < 4; ++i) *reinterpret_cast<float4*>(xout + (i * 64 + lane) * 4) = xv[i];
;         } else if (xdst != 0) {
;           u16* xo = ((xdst == 1) ? resA : P.zf) + (long)row * 1024;
; #pragma unroll
;           for (int i = 0; i < 4; ++i) {
;             const unsigned b0 = f2bf(xv[i].x), b1 = f2bf(xv[i].y), b2 = f2bf(xv[i].z), b3 = f2bf(xv[i].w);
;             *reinterpret_cast<uint2*>(xo + (i * 64 + lane) * 4) = make_uint2(b0 | (b1 << 16), b2 | (b3 << 16));
;           }
;         }
;         if (doH) {
;           float ss = 0.f;
; #pragma unroll
;           for (int i = 0; i < 4; ++i) ss += xv[i].x * xv[i].x + xv[i].y * xv[i].y + xv[i].z * xv[i].z + xv[i].w * xv[i].w;
;           ss = wave_sum(ss);
;           const float rstd = __builtin_amdgcn_rsqf(ss * (1.f / 1024.f) + EPSF);
;           u16* h = P.hy + (long)row * 1024;
; #pragma unroll
	v_mul_f32_e32 v128, v128, v140
	v_mul_f32_e32 v129, v129, v140
	v_mul_f32_e32 v130, v130, v140
	v_mul_f32_e32 v131, v131, v140
	v_mul_f32_e32 v132, v132, v140
	v_mul_f32_e32 v133, v133, v140
	v_mul_f32_e32 v134, v134, v140
	v_mul_f32_e32 v135, v135, v140
	v_fma_f32 v16, v120, v72, v16
	v_fma_f32 v17, v121, v73, v17
	v_fma_f32 v18, v122, v74, v18
	v_fma_f32 v19, v123, v75, v19
	v_fma_f32 v20, v124, v76, v20
	v_fma_f32 v21, v125, v77, v21
	v_fma_f32 v22, v126, v78, v22
	v_fma_f32 v23, v127, v79, v23
	v_fma_f32 v24, v128, v80, v24
	v_fma_f32 v25, v129, v81, v25
	v_fma_f32 v26, v130, v82, v26
	v_fma_f32 v27, v131, v83, v27
	v_fma_f32 v28, v132, v84, v28
	v_fma_f32 v29, v133, v85, v29
	v_fma_f32 v30, v134, v86, v30
	v_fma_f32 v31, v135, v87, v31
	v_cvt_pk_bf16_f32 v156, v16, v17
	v_cvt_pk_bf16_f32 v157, v18, v19
	v_cvt_pk_bf16_f32 v158, v20, v21
	v_cvt_pk_bf16_f32 v159, v22, v23
	v_cvt_pk_bf16_f32 v160, v24, v25
	v_cvt_pk_bf16_f32 v161, v26, v27
	v_cvt_pk_bf16_f32 v162, v28, v29
	v_cvt_pk_bf16_f32 v163, v30, v31
	s_lshl_b32 vcc_lo, s19, 11
	s_add_u32 vcc_lo, vcc_lo, 0x2800000
	s_add_u32 s100, s16, vcc_lo
	s_addc_u32 s101, s17, 0
	global_store_dwordx2 v137, v[156:157], s[100:101] offset:0
	global_store_dwordx2 v137, v[158:159], s[100:101] offset:512
	global_store_dwordx2 v137, v[160:161], s[100:101] offset:1024
	global_store_dwordx2 v137, v[162:163], s[100:101] offset:1536
	v_mul_f32_e32 v138, v16, v16
	v_mul_f32_e32 v149, v17, v17
	v_mul_f32_e32 v150, v18, v18
	v_mul_f32_e32 v154, v19, v19
	v_fma_f32 v138, v20, v20, v138
	v_fma_f32 v149, v21, v21, v149
	v_fma_f32 v150, v22, v22, v150
	v_fma_f32 v154, v23, v23, v154
	v_fma_f32 v138, v24, v24, v138
	v_fma_f32 v149, v25, v25, v149
	v_fma_f32 v150, v26, v26, v150
	v_fma_f32 v154, v27, v27, v154
	v_fma_f32 v138, v28, v28, v138
	v_fma_f32 v149, v29, v29, v149
	v_fma_f32 v150, v30, v30, v150
	v_fma_f32 v154, v31, v31, v154
	v_add_f32_e32 v138, v138, v149
	v_add_f32_e32 v150, v150, v154
	v_add_f32_e32 v138, v138, v150
	s_nop 1
	v_add_f32_dpp v138, v138, v138 quad_perm:[1,0,3,2] row_mask:0xf bank_mask:0xf
	s_nop 1
	v_add_f32_dpp v138, v138, v138 quad_perm:[2,3,0,1] row_mask:0xf bank_mask:0xf
	s_nop 1
	v_add_f32_dpp v138, v138, v138 row_half_mirror row_mask:0xf bank_mask:0xf
	s_nop 1
	v_add_f32_dpp v138, v138, v138 row_mirror row_mask:0xf bank_mask:0xf
	v_mov_b32_e32 v139, v138
	s_nop 1
	v_permlane16_swap_b32_e32 v138, v139
	v_add_f32_e32 v138, v138, v139
	v_mov_b32_e32 v139, v138
	s_nop 1
	v_permlane32_swap_b32_e32 v138, v139
	v_add_f32_e32 v138, v138, v139
	v_mul_f32_e32 v138, 0x3a800000, v138
	v_add_f32_e32 v138, 0x358637bd, v138
	v_rsq_f32_e32 v140, v138
	s_nop 0
	v_mul_f32_e32 v120, v16, v140
	v_mul_f32_e32 v121, v17, v140
	v_mul_f32_e32 v122, v18, v140
	v_mul_f32_e32 v123, v19, v140
	v_mul_f32_e32 v124, v20, v140
	v_mul_f32_e32 v125, v21, v140
	v_mul_f32_e32 v126, v22, v140
	v_mul_f32_e32 v127, v23, v140
	v_mul_f32_e32 v128, v24, v140
	v_mul_f32_e32 v129, v25, v140
	v_mul_f32_e32 v130, v26, v140
	v_mul_f32_e32 v131, v27, v140
	v_mul_f32_e32 v132, v28, v140
	v_mul_f32_e32 v133, v29, v140
	v_mul_f32_e32 v134, v30, v140
	v_mul_f32_e32 v135, v31, v140
	v_fma_f32 v120, v120, v88, v104
	v_fma_f32 v121, v121, v89, v105
	v_fma_f32 v122, v122, v90, v106
	v_fma_f32 v123, v123, v91, v107
	v_fma_f32 v124, v124, v92, v108
	v_fma_f32 v125, v125, v93, v109
	v_fma_f32 v126, v126, v94, v110
	v_fma_f32 v127, v127, v95, v111
	v_fma_f32 v128, v128, v96, v112
	v_fma_f32 v129, v129, v97, v113
	v_fma_f32 v130, v130, v98, v114
	v_fma_f32 v131, v131, v99, v115
	v_fma_f32 v132, v132, v100, v116
	v_fma_f32 v133, v133, v101, v117
	v_fma_f32 v134, v134, v102, v118
	v_fma_f32 v135, v135, v103, v119
	v_cvt_pk_bf16_f32 v156, v120, v121
	v_cvt_pk_bf16_f32 v157, v122, v123
	v_cvt_pk_bf16_f32 v158, v124, v125
	v_cvt_pk_bf16_f32 v159, v126, v127
	v_cvt_pk_bf16_f32 v160, v128, v129
	v_cvt_pk_bf16_f32 v161, v130, v131
	v_cvt_pk_bf16_f32 v162, v132, v133
	v_cvt_pk_bf16_f32 v163, v134, v135
	s_lshl_b32 vcc_lo, s19, 11
	s_add_u32 vcc_lo, vcc_lo, 0x2800000
	s_add_u32 s100, s14, vcc_lo
	s_addc_u32 s101, s15, 0
	global_store_dwordx2 v137, v[156:157], s[100:101] offset:0
	global_store_dwordx2 v137, v[158:159], s[100:101] offset:512
	global_store_dwordx2 v137, v[160:161], s[100:101] offset:1024
	global_store_dwordx2 v137, v[162:163], s[100:101] offset:1536
	s_lshl_b32 vcc_lo, s19, 11
	s_add_u32 vcc_lo, vcc_lo, 0x3400000
	s_add_u32 s100, s12, vcc_lo
	s_addc_u32 s101, s13, 0
	global_load_dwordx2 v[24:25], v137, s[100:101] offset:0
	global_load_dwordx2 v[26:27], v137, s[100:101] offset:512
	global_load_dwordx2 v[28:29], v137, s[100:101] offset:1024
	global_load_dwordx2 v[30:31], v137, s[100:101] offset:1536
	s_lshl_b32 vcc_lo, s19, 11
	s_add_u32 vcc_lo, vcc_lo, 0x3400000
	s_add_u32 s100, s14, vcc_lo
	s_addc_u32 s101, s15, 0
	global_load_dwordx2 v[56:57], v137, s[100:101] offset:0
	global_load_dwordx2 v[58:59], v137, s[100:101] offset:512
	global_load_dwordx2 v[60:61], v137, s[100:101] offset:1024
	global_load_dwordx2 v[62:63], v137, s[100:101] offset:1536
	s_waitcnt vmcnt(32)
; __device__ __forceinline__ void row_phase(const Params& P, int glayer, int layer, int xsrc, bool hasY, int gate_idx, const float* gpost,
;                           int xdst, bool doH, const float* gpre, int sh_idx, int nrows) {
;     ...
;         if (hasY) {
;           float4 yv[4];
;           float ss = 0.f;
; #pragma unroll
;           for (int i = 0; i < 4; ++i) {
;             const uint2 raw = yy[u][i];
;             yv[i].x = bf2f((u16)(raw.x & 0xffff)); yv[i].y = bf2f((u16)(raw.x >> 16));
;             yv[i].z = bf2f((u16)(raw.y & 0xffff)); yv[i].w = bf2f((u16)(raw.y >> 16));
;             ss += yv[i].x * yv[i].x + yv[i].y * yv[i].y + yv[i].z * yv[i].z + yv[i].w * yv[i].w;
;           }
;           ss = wave_sum(ss);
;           const float rstd = __builtin_amdgcn_rsqf(ss * (1.f / 1024.f) + EPSF);
; #pragma unroll
;           for (int i = 0; i < 4; ++i) {
;             const int col = (i * 64 + lane) * 4;
;             const float4 gt = *reinterpret_cast<const float4*>(modg + gate_idx * 1024 + col);
;             const float4 gp = *reinterpret_cast<const float4*>(gpost + col);
;             xv[i].x += gt.x * (yv[i].x * rstd * gp.x); xv[i].y += gt.y * (yv[i].y * rstd * gp.y);
;             xv[i].z += gt.z * (yv[i].z * rstd * gp.z); xv[i].w += gt.w * (yv[i].w * rstd * gp.w);
;           }
;         }
;         if (xdst == 3 || (xdst == 1 && row >= N_X)) {
;           float* xout = (xdst == 3) ? P.out + (long)row * 1024 : P.xc + (long)(row - N_X) * 1024;
; #pragma unroll
;           for (int i = 0; i < 4; ++i) *reinterpret_cast<float4*>(xout + (i * 64 + lane) * 4) = xv[i];
;         } else if (xdst != 0) {
;           u16* xo = ((xdst == 1) ? resA : P.zf) + (long)row * 1024;
; #pragma unroll
;           for (int i = 0; i < 4; ++i) {
;             const unsigned b0 = f2bf(xv[i].x), b1 = f2bf(xv[i].y), b2 = f2bf(xv[i].z), b3 = f2bf(xv[i].w);
;             *reinterpret_cast<uint2*>(xo + (i * 64 + lane) * 4) = make_uint2(b0 | (b1 << 16), b2 | (b3 << 16));
;           }
;         }
;         if (doH) {
;           float ss = 0.f;
; #pragma unroll
;           for (int i = 0; i < 4; ++i) ss += xv[i].x * xv[i].x + xv[i].y * xv[i].y + xv[i].z * xv[i].z + xv[i].w * xv[i].w;
;           ss = wave_sum(ss);
;           const float rstd = __builtin_amdgcn_rsqf(ss * (1.f / 1024.f) + EPSF);
;           u16* h = P.hy + (long)row * 1024;
; #pragma unroll
	v_lshlrev_b32_e32 v120, 16, v64
	v_and_b32_e32 v121, 0xffff0000, v64
	v_lshlrev_b32_e32 v122, 16, v65
	v_and_b32_e32 v123, 0xffff0000, v65
	v_lshlrev_b32_e32 v124, 16, v66
	v_and_b32_e32 v125, 0xffff0000, v66
	v_lshlrev_b32_e32 v126, 16, v67
	v_and_b32_e32 v127, 0xffff0000, v67
	v_lshlrev_b32_e32 v128, 16, v68
	v_and_b32_e32 v129, 0xffff0000, v68
	v_lshlrev_b32_e32 v130, 16, v69
	v_and_b32_e32 v131, 0xffff0000, v69
	v_lshlrev_b32_e32 v132, 16, v70
	v_and_b32_e32 v133, 0xffff0000, v70
	v_lshlrev_b32_e32 v134, 16, v71
	v_and_b32_e32 v135, 0xffff0000, v71
	v_mul_f32_e32 v138, v120, v120
	v_mul_f32_e32 v149, v121, v121
	v_mul_f32_e32 v150, v122, v122
	v_mul_f32_e32 v154, v123, v123
	v_fma_f32 v138, v124, v124, v138
	v_fma_f32 v149, v125, v125, v149
	v_fma_f32 v150, v126, v126, v150
	v_fma_f32 v154, v127, v127, v154
	v_fma_f32 v138, v128, v128, v138
	v_fma_f32 v149, v129, v129, v149
	v_fma_f32 v150, v130, v130, v150
	v_fma_f32 v154, v131, v131, v154
	v_fma_f32 v138, v132, v132, v138
	v_fma_f32 v149, v133, v133, v149
	v_fma_f32 v150, v134, v134, v150
	v_fma_f32 v154, v135, v135, v154
	v_add_f32_e32 v138, v138, v149
	v_add_f32_e32 v150, v150, v154
	v_add_f32_e32 v138, v138, v150
	s_nop 1
	v_add_f32_dpp v138, v138, v138 quad_perm:[1,0,3,2] row_mask:0xf bank_mask:0xf
	s_nop 1
	v_add_f32_dpp v138, v138, v138 quad_perm:[2,3,0,1] row_mask:0xf bank_mask:0xf
	s_nop 1
	v_add_f32_dpp v138, v138, v138 row_half_mirror row_mask:0xf bank_mask:0xf
	s_nop 1
	v_add_f32_dpp v138, v138, v138 row_mirror row_mask:0xf bank_mask:0xf
	v_mov_b32_e32 v139, v138
	s_nop 1
	v_permlane16_swap_b32_e32 v138, v139
	v_add_f32_e32 v138, v138, v139
	v_mov_b32_e32 v139, v138
	s_nop 1
	v_permlane32_swap_b32_e32 v138, v139
	v_add_f32_e32 v138, v138, v139
	v_mul_f32_e32 v138, 0x3a800000, v138
	v_add_f32_e32 v138, 0x358637bd, v138
	v_rsq_f32_e32 v140, v138
	v_lshlrev_b32_e32 v32, 16, v40
	v_and_b32_e32 v33, 0xffff0000, v40
	v_lshlrev_b32_e32 v34, 16, v41
	v_and_b32_e32 v35, 0xffff0000, v41
	v_lshlrev_b32_e32 v36, 16, v42
	v_and_b32_e32 v37, 0xffff0000, v42
	v_lshlrev_b32_e32 v38, 16, v43
	v_and_b32_e32 v39, 0xffff0000, v43
	v_lshlrev_b32_e32 v40, 16, v44
	v_and_b32_e32 v41, 0xffff0000, v44
	v_lshlrev_b32_e32 v42, 16, v45
	v_and_b32_e32 v43, 0xffff0000, v45
	v_lshlrev_b32_e32 v44, 16, v46
	v_and_b32_e32 v45, 0xffff0000, v46
	v_lshlrev_b32_e32 v46, 16, v47
	v_and_b32_e32 v47, 0xffff0000, v47
	s_nop 0
	v_mul_f32_e32 v120, v120, v140
	v_mul_f32_e32 v121, v121, v140
	v_mul_f32_e32 v122, v122, v140
	v_mul_f32_e32 v123, v123, v140
	v_mul_f32_e32 v124, v124, v140
	v_mul_f32_e32 v125, v125, v140
	v_mul_f32_e32 v126, v126, v140
	v_mul_f32_e32 v127, v127, v140
	v_mul_f32_e32 v128, v128, v140
	v_mul_f32_e32 v129, v129, v140
	v_mul_f32_e32 v130, v130, v140
	v_mul_f32_e32 v131, v131, v140
	v_mul_f32_e32 v132, v132, v140
	v_mul_f32_e32 v133, v133, v140
	v_mul_f32_e32 v134, v134, v140
	v_mul_f32_e32 v135, v135, v140
	v_fma_f32 v32, v120, v72, v32
	v_fma_f32 v33, v121, v73, v33
	v_fma_f32 v34, v122, v74, v34
	v_fma_f32 v35, v123, v75, v35
	v_fma_f32 v36, v124, v76, v36
	v_fma_f32 v37, v125, v77, v37
	v_fma_f32 v38, v126, v78, v38
	v_fma_f32 v39, v127, v79, v39
	v_fma_f32 v40, v128, v80, v40
	v_fma_f32 v41, v129, v81, v41
	v_fma_f32 v42, v130, v82, v42
	v_fma_f32 v43, v131, v83, v43
	v_fma_f32 v44, v132, v84, v44
	v_fma_f32 v45, v133, v85, v45
	v_fma_f32 v46, v134, v86, v46
	v_fma_f32 v47, v135, v87, v47
	v_cvt_pk_bf16_f32 v156, v32, v33
	v_cvt_pk_bf16_f32 v157, v34, v35
	v_cvt_pk_bf16_f32 v158, v36, v37
	v_cvt_pk_bf16_f32 v159, v38, v39
	v_cvt_pk_bf16_f32 v160, v40, v41
	v_cvt_pk_bf16_f32 v161, v42, v43
	v_cvt_pk_bf16_f32 v162, v44, v45
	v_cvt_pk_bf16_f32 v163, v46, v47
	s_lshl_b32 vcc_lo, s19, 11
	s_add_u32 vcc_lo, vcc_lo, 0x2c00000
	s_add_u32 s100, s16, vcc_lo
	s_addc_u32 s101, s17, 0
	global_store_dwordx2 v137, v[156:157], s[100:101] offset:0
	global_store_dwordx2 v137, v[158:159], s[100:101] offset:512
	global_store_dwordx2 v137, v[160:161], s[100:101] offset:1024
	global_store_dwordx2 v137, v[162:163], s[100:101] offset:1536
	v_mul_f32_e32 v138, v32, v32
	v_mul_f32_e32 v149, v33, v33
	v_mul_f32_e32 v150, v34, v34
	v_mul_f32_e32 v154, v35, v35
	v_fma_f32 v138, v36, v36, v138
	v_fma_f32 v149, v37, v37, v149
	v_fma_f32 v150, v38, v38, v150
	v_fma_f32 v154, v39, v39, v154
	v_fma_f32 v138, v40, v40, v138
	v_fma_f32 v149, v41, v41, v149
	v_fma_f32 v150, v42, v42, v150
	v_fma_f32 v154, v43, v43, v154
	v_fma_f32 v138, v44, v44, v138
	v_fma_f32 v149, v45, v45, v149
	v_fma_f32 v150, v46, v46, v150
	v_fma_f32 v154, v47, v47, v154
	v_add_f32_e32 v138, v138, v149
	v_add_f32_e32 v150, v150, v154
	v_add_f32_e32 v138, v138, v150
	s_nop 1
	v_add_f32_dpp v138, v138, v138 quad_perm:[1,0,3,2] row_mask:0xf bank_mask:0xf
	s_nop 1
	v_add_f32_dpp v138, v138, v138 quad_perm:[2,3,0,1] row_mask:0xf bank_mask:0xf
	s_nop 1
	v_add_f32_dpp v138, v138, v138 row_half_mirror row_mask:0xf bank_mask:0xf
	s_nop 1
	v_add_f32_dpp v138, v138, v138 row_mirror row_mask:0xf bank_mask:0xf
	v_mov_b32_e32 v139, v138
	s_nop 1
	v_permlane16_swap_b32_e32 v138, v139
	v_add_f32_e32 v138, v138, v139
	v_mov_b32_e32 v139, v138
	s_nop 1
	v_permlane32_swap_b32_e32 v138, v139
	v_add_f32_e32 v138, v138, v139
	v_mul_f32_e32 v138, 0x3a800000, v138
	v_add_f32_e32 v138, 0x358637bd, v138
	v_rsq_f32_e32 v140, v138
	s_nop 0
	v_mul_f32_e32 v120, v32, v140
	v_mul_f32_e32 v121, v33, v140
	v_mul_f32_e32 v122, v34, v140
	v_mul_f32_e32 v123, v35, v140
	v_mul_f32_e32 v124, v36, v140
	v_mul_f32_e32 v125, v37, v140
	v_mul_f32_e32 v126, v38, v140
	v_mul_f32_e32 v127, v39, v140
	v_mul_f32_e32 v128, v40, v140
	v_mul_f32_e32 v129, v41, v140
	v_mul_f32_e32 v130, v42, v140
; __device__ __forceinline__ void row_phase(const Params& P, int glayer, int layer, int xsrc, bool hasY, int gate_idx, const float* gpost,
;                           int xdst, bool doH, const float* gpre, int sh_idx, int nrows) {
;     ...
;         const int mi = row < N_X ? (row >> 13) : 4;
;         const float* modp = P.mod + (long)(layer * 5 + mi) * 6144;
;         const float* modg = P.mod + (long)(glayer * 5 + mi) * 6144;
;     ...
;         if (hasY) {
;           float4 yv[4];
;           float ss = 0.f;
; #pragma unroll
;           for (int i = 0; i < 4; ++i) {
;             const uint2 raw = yy[u][i];
;             yv[i].x = bf2f((u16)(raw.x & 0xffff)); yv[i].y = bf2f((u16)(raw.x >> 16));
;             yv[i].z = bf2f((u16)(raw.y & 0xffff)); yv[i].w = bf2f((u16)(raw.y >> 16));
;             ss += yv[i].x * yv[i].x + yv[i].y * yv[i].y + yv[i].z * yv[i].z + yv[i].w * yv[i].w;
;           }
;           ss = wave_sum(ss);
;           const float rstd = __builtin_amdgcn_rsqf(ss * (1.f / 1024.f) + EPSF);
; #pragma unroll
;           for (int i = 0; i < 4; ++i) {
;             const int col = (i * 64 + lane) * 4;
;             const float4 gt = *reinterpret_cast<const float4*>(modg + gate_idx * 1024 + col);
;             const float4 gp = *reinterpret_cast<const float4*>(gpost + col);
;             xv[i].x += gt.x * (yv[i].x * rstd * gp.x); xv[i].y += gt.y * (yv[i].y * rstd * gp.y);
;             xv[i].z += gt.z * (yv[i].z * rstd * gp.z); xv[i].w += gt.w * (yv[i].w * rstd * gp.w);
;           }
;         }
;         if (xdst == 3 || (xdst == 1 && row >= N_X)) {
;           float* xout = (xdst == 3) ? P.out + (long)row * 1024 : P.xc + (long)(row - N_X) * 1024;
; #pragma unroll
;           for (int i = 0; i < 4; ++i) *reinterpret_cast<float4*>(xout + (i * 64 + lane) * 4) = xv[i];
;         } else if (xdst != 0) {
;           u16* xo = ((xdst == 1) ? resA : P.zf) + (long)row * 1024;
; #pragma unroll
;           for (int i = 0; i < 4; ++i) {
;             const unsigned b0 = f2bf(xv[i].x), b1 = f2bf(xv[i].y), b2 = f2bf(xv[i].z), b3 = f2bf(xv[i].w);
;             *reinterpret_cast<uint2*>(xo + (i * 64 + lane) * 4) = make_uint2(b0 | (b1 << 16), b2 | (b3 << 16));
;           }
;         }
;         if (doH) {
;           float ss = 0.f;
; #pragma unroll
;           for (int i = 0; i < 4; ++i) ss += xv[i].x * xv[i].x + xv[i].y * xv[i].y + xv[i].z * xv[i].z + xv[i].w * xv[i].w;
	v_mul_f32_e32 v131, v43, v140
	v_mul_f32_e32 v132, v44, v140
	v_mul_f32_e32 v133, v45, v140
	v_mul_f32_e32 v134, v46, v140
	v_mul_f32_e32 v135, v47, v140
	v_fma_f32 v120, v120, v88, v104
	v_fma_f32 v121, v121, v89, v105
	v_fma_f32 v122, v122, v90, v106
	v_fma_f32 v123, v123, v91, v107
	v_fma_f32 v124, v124, v92, v108
	v_fma_f32 v125, v125, v93, v109
	v_fma_f32 v126, v126, v94, v110
	v_fma_f32 v127, v127, v95, v111
	v_fma_f32 v128, v128, v96, v112
	v_fma_f32 v129, v129, v97, v113
	v_fma_f32 v130, v130, v98, v114
	v_fma_f32 v131, v131, v99, v115
	v_fma_f32 v132, v132, v100, v116
	v_fma_f32 v133, v133, v101, v117
	v_fma_f32 v134, v134, v102, v118
	v_fma_f32 v135, v135, v103, v119
	v_cvt_pk_bf16_f32 v156, v120, v121
	v_cvt_pk_bf16_f32 v157, v122, v123
	v_cvt_pk_bf16_f32 v158, v124, v125
	v_cvt_pk_bf16_f32 v159, v126, v127
	v_cvt_pk_bf16_f32 v160, v128, v129
	v_cvt_pk_bf16_f32 v161, v130, v131
	v_cvt_pk_bf16_f32 v162, v132, v133
	v_cvt_pk_bf16_f32 v163, v134, v135
	s_lshl_b32 vcc_lo, s19, 11
	s_add_u32 vcc_lo, vcc_lo, 0x2c00000
	s_add_u32 s100, s14, vcc_lo
	s_addc_u32 s101, s15, 0
	global_store_dwordx2 v137, v[156:157], s[100:101] offset:0
	global_store_dwordx2 v137, v[158:159], s[100:101] offset:512
	global_store_dwordx2 v137, v[160:161], s[100:101] offset:1024
	global_store_dwordx2 v137, v[162:163], s[100:101] offset:1536
	s_add_u32 s100, s20, 0x17000
	s_addc_u32 s101, s21, 0
	global_load_dwordx4 v[72:75], v136, s[100:101] offset:0
	global_load_dwordx4 v[76:79], v136, s[100:101] offset:1024
	global_load_dwordx4 v[80:83], v136, s[100:101] offset:2048
	global_load_dwordx4 v[84:87], v136, s[100:101] offset:3072
	s_load_dwordx2 s[98:99], s[4:5], 0x48
	s_waitcnt lgkmcnt(0)
	global_load_dwordx4 v[120:123], v136, s[98:99] offset:0
	global_load_dwordx4 v[124:127], v136, s[98:99] offset:1024
	global_load_dwordx4 v[128:131], v136, s[98:99] offset:2048
	global_load_dwordx4 v[132:135], v136, s[98:99] offset:3072
	s_add_u32 s100, s20, 0x30000
	s_addc_u32 s101, s21, 0
	global_load_dwordx4 v[104:107], v136, s[100:101] offset:0
	global_load_dwordx4 v[108:111], v136, s[100:101] offset:1024
	global_load_dwordx4 v[112:115], v136, s[100:101] offset:2048
	global_load_dwordx4 v[116:119], v136, s[100:101] offset:3072
	s_add_u32 s100, s100, 0x1000
	s_addc_u32 s101, s101, 0
	global_load_dwordx4 v[32:35], v136, s[100:101] offset:0
	global_load_dwordx4 v[36:39], v136, s[100:101] offset:1024
	global_load_dwordx4 v[40:43], v136, s[100:101] offset:2048
	global_load_dwordx4 v[44:47], v136, s[100:101] offset:3072
	s_load_dwordx2 s[98:99], s[4:5], 0x30
	s_waitcnt lgkmcnt(0)
	s_add_u32 s98, s98, 0x1000
	s_addc_u32 s99, s99, 0
	global_load_dwordx4 v[88:91], v136, s[98:99] offset:0
	global_load_dwordx4 v[92:95], v136, s[98:99] offset:1024
	global_load_dwordx4 v[96:99], v136, s[98:99] offset:2048
	global_load_dwordx4 v[100:103], v136, s[98:99] offset:3072
	s_waitcnt vmcnt(0)
	v_mul_f32_e32 v72, v72, v120
	v_mul_f32_e32 v73, v73, v121
	v_mul_f32_e32 v74, v74, v122
	v_mul_f32_e32 v75, v75, v123
	v_mul_f32_e32 v76, v76, v124
	v_mul_f32_e32 v77, v77, v125
	v_mul_f32_e32 v78, v78, v126
	v_mul_f32_e32 v79, v79, v127
	v_mul_f32_e32 v80, v80, v128
	v_mul_f32_e32 v81, v81, v129
	v_mul_f32_e32 v82, v82, v130
	v_mul_f32_e32 v83, v83, v131
	v_mul_f32_e32 v84, v84, v132
	v_mul_f32_e32 v85, v85, v133
	v_mul_f32_e32 v86, v86, v134
	v_mul_f32_e32 v87, v87, v135
	v_fma_f32 v88, v88, v32, v88
	v_fma_f32 v89, v89, v33, v89
	v_fma_f32 v90, v90, v34, v90
	v_fma_f32 v91, v91, v35, v91
	v_fma_f32 v92, v92, v36, v92
	v_fma_f32 v93, v93, v37, v93
	v_fma_f32 v94, v94, v38, v94
	v_fma_f32 v95, v95, v39, v95
	v_fma_f32 v96, v96, v40, v96
	v_fma_f32 v97, v97, v41, v97
	v_fma_f32 v98, v98, v42, v98
	v_fma_f32 v99, v99, v43, v99
	v_fma_f32 v100, v100, v44, v100
	v_fma_f32 v101, v101, v45, v101
	v_fma_f32 v102, v102, v46, v102
	v_fma_f32 v103, v103, v47, v103
	s_lshl_b32 vcc_lo, s19, 11
	s_add_u32 vcc_lo, vcc_lo, 0x3800000
	s_add_u32 s100, s12, vcc_lo
	s_addc_u32 s101, s13, 0
	global_load_dwordx2 v[40:41], v137, s[100:101] offset:0
	global_load_dwordx2 v[42:43], v137, s[100:101] offset:512
	global_load_dwordx2 v[44:45], v137, s[100:101] offset:1024
	global_load_dwordx2 v[46:47], v137, s[100:101] offset:1536
	s_lshl_b32 vcc_lo, s19, 11
	s_add_u32 vcc_lo, vcc_lo, 0x3800000
	s_add_u32 s100, s14, vcc_lo
	s_addc_u32 s101, s15, 0
	global_load_dwordx2 v[64:65], v137, s[100:101] offset:0
	global_load_dwordx2 v[66:67], v137, s[100:101] offset:512
	global_load_dwordx2 v[68:69], v137, s[100:101] offset:1024
	global_load_dwordx2 v[70:71], v137, s[100:101] offset:1536
	v_lshlrev_b32_e32 v120, 16, v48
	v_and_b32_e32 v121, 0xffff0000, v48
	v_lshlrev_b32_e32 v122, 16, v49
	v_and_b32_e32 v123, 0xffff0000, v49
	v_lshlrev_b32_e32 v124, 16, v50
	v_and_b32_e32 v125, 0xffff0000, v50
	v_lshlrev_b32_e32 v126, 16, v51
	v_and_b32_e32 v127, 0xffff0000, v51
	v_lshlrev_b32_e32 v128, 16, v52
	v_and_b32_e32 v129, 0xffff0000, v52
	v_lshlrev_b32_e32 v130, 16, v53
	v_and_b32_e32 v131, 0xffff0000, v53
	v_lshlrev_b32_e32 v132, 16, v54
	v_and_b32_e32 v133, 0xffff0000, v54
	v_lshlrev_b32_e32 v134, 16, v55
	v_and_b32_e32 v135, 0xffff0000, v55
	v_mul_f32_e32 v138, v120, v120
	v_mul_f32_e32 v149, v121, v121
	v_mul_f32_e32 v150, v122, v122
	v_mul_f32_e32 v154, v123, v123
	v_fma_f32 v138, v124, v124, v138
	v_fma_f32 v149, v125, v125, v149
	v_fma_f32 v150, v126, v126, v150
	v_fma_f32 v154, v127, v127, v154
	v_fma_f32 v138, v128, v128, v138
	v_fma_f32 v149, v129, v129, v149
	v_fma_f32 v150, v130, v130, v150
	v_fma_f32 v154, v131, v131, v154
	v_fma_f32 v138, v132, v132, v138
	v_fma_f32 v149, v133, v133, v149
	v_fma_f32 v150, v134, v134, v150
; __device__ __forceinline__ void row_phase(const Params& P, int glayer, int layer, int xsrc, bool hasY, int gate_idx, const float* gpost,
;                           int xdst, bool doH, const float* gpre, int sh_idx, int nrows) {
;     ...
;         if (hasY) {
;           float4 yv[4];
;           float ss = 0.f;
; #pragma unroll
;           for (int i = 0; i < 4; ++i) {
;             const uint2 raw = yy[u][i];
;             yv[i].x = bf2f((u16)(raw.x & 0xffff)); yv[i].y = bf2f((u16)(raw.x >> 16));
;             yv[i].z = bf2f((u16)(raw.y & 0xffff)); yv[i].w = bf2f((u16)(raw.y >> 16));
;             ss += yv[i].x * yv[i].x + yv[i].y * yv[i].y + yv[i].z * yv[i].z + yv[i].w * yv[i].w;
;           }
;           ss = wave_sum(ss);
;           const float rstd = __builtin_amdgcn_rsqf(ss * (1.f / 1024.f) + EPSF);
; #pragma unroll
;           for (int i = 0; i < 4; ++i) {
;             const int col = (i * 64 + lane) * 4;
;             const float4 gt = *reinterpret_cast<const float4*>(modg + gate_idx * 1024 + col);
;             const float4 gp = *reinterpret_cast<const float4*>(gpost + col);
;             xv[i].x += gt.x * (yv[i].x * rstd * gp.x); xv[i].y += gt.y * (yv[i].y * rstd * gp.y);
;             xv[i].z += gt.z * (yv[i].z * rstd * gp.z); xv[i].w += gt.w * (yv[i].w * rstd * gp.w);
;           }
;         }
;         if (xdst == 3 || (xdst == 1 && row >= N_X)) {
;           float* xout = (xdst == 3) ? P.out + (long)row * 1024 : P.xc + (long)(row - N_X) * 1024;
; #pragma unroll
;           for (int i = 0; i < 4; ++i) *reinterpret_cast<float4*>(xout + (i * 64 + lane) * 4) = xv[i];
;         } else if (xdst != 0) {
;           u16* xo = ((xdst == 1) ? resA : P.zf) + (long)row * 1024;
; #pragma unroll
;           for (int i = 0; i < 4; ++i) {
;             const unsigned b0 = f2bf(xv[i].x), b1 = f2bf(xv[i].y), b2 = f2bf(xv[i].z), b3 = f2bf(xv[i].w);
;             *reinterpret_cast<uint2*>(xo + (i * 64 + lane) * 4) = make_uint2(b0 | (b1 << 16), b2 | (b3 << 16));
;           }
;         }
;         if (doH) {
;           float ss = 0.f;
; #pragma unroll
;           for (int i = 0; i < 4; ++i) ss += xv[i].x * xv[i].x + xv[i].y * xv[i].y + xv[i].z * xv[i].z + xv[i].w * xv[i].w;
;           ss = wave_sum(ss);
;           const float rstd = __builtin_amdgcn_rsqf(ss * (1.f / 1024.f) + EPSF);
;           u16* h = P.hy + (long)row * 1024;
; #pragma unroll
	v_fma_f32 v154, v135, v135, v154
	v_add_f32_e32 v138, v138, v149
	v_add_f32_e32 v150, v150, v154
	v_add_f32_e32 v138, v138, v150
	s_nop 1
	v_add_f32_dpp v138, v138, v138 quad_perm:[1,0,3,2] row_mask:0xf bank_mask:0xf
	s_nop 1
	v_add_f32_dpp v138, v138, v138 quad_perm:[2,3,0,1] row_mask:0xf bank_mask:0xf
	s_nop 1
	v_add_f32_dpp v138, v138, v138 row_half_mirror row_mask:0xf bank_mask:0xf
	s_nop 1
	v_add_f32_dpp v138, v138, v138 row_mirror row_mask:0xf bank_mask:0xf
	v_mov_b32_e32 v139, v138
	s_nop 1
	v_permlane16_swap_b32_e32 v138, v139
	v_add_f32_e32 v138, v138, v139
	v_mov_b32_e32 v139, v138
	s_nop 1
	v_permlane32_swap_b32_e32 v138, v139
	v_add_f32_e32 v138, v138, v139
	v_mul_f32_e32 v138, 0x3a800000, v138
	v_add_f32_e32 v138, 0x358637bd, v138
	v_rsq_f32_e32 v140, v138
	v_lshlrev_b32_e32 v0, 16, v8
	v_and_b32_e32 v1, 0xffff0000, v8
	v_lshlrev_b32_e32 v2, 16, v9
	v_and_b32_e32 v3, 0xffff0000, v9
	v_lshlrev_b32_e32 v4, 16, v10
	v_and_b32_e32 v5, 0xffff0000, v10
	v_lshlrev_b32_e32 v6, 16, v11
	v_and_b32_e32 v7, 0xffff0000, v11
	v_lshlrev_b32_e32 v8, 16, v12
	v_and_b32_e32 v9, 0xffff0000, v12
	v_lshlrev_b32_e32 v10, 16, v13
	v_and_b32_e32 v11, 0xffff0000, v13
	v_lshlrev_b32_e32 v12, 16, v14
	v_and_b32_e32 v13, 0xffff0000, v14
	v_lshlrev_b32_e32 v14, 16, v15
	v_and_b32_e32 v15, 0xffff0000, v15
	s_nop 0
	v_mul_f32_e32 v120, v120, v140
	v_mul_f32_e32 v121, v121, v140
	v_mul_f32_e32 v122, v122, v140
	v_mul_f32_e32 v123, v123, v140
	v_mul_f32_e32 v124, v124, v140
	v_mul_f32_e32 v125, v125, v140
	v_mul_f32_e32 v126, v126, v140
	v_mul_f32_e32 v127, v127, v140
	v_mul_f32_e32 v128, v128, v140
	v_mul_f32_e32 v129, v129, v140
	v_mul_f32_e32 v130, v130, v140
	v_mul_f32_e32 v131, v131, v140
	v_mul_f32_e32 v132, v132, v140
	v_mul_f32_e32 v133, v133, v140
	v_mul_f32_e32 v134, v134, v140
	v_mul_f32_e32 v135, v135, v140
	v_fma_f32 v0, v120, v72, v0
	v_fma_f32 v1, v121, v73, v1
	v_fma_f32 v2, v122, v74, v2
	v_fma_f32 v3, v123, v75, v3
	v_fma_f32 v4, v124, v76, v4
	v_fma_f32 v5, v125, v77, v5
	v_fma_f32 v6, v126, v78, v6
	v_fma_f32 v7, v127, v79, v7
	v_fma_f32 v8, v128, v80, v8
	v_fma_f32 v9, v129, v81, v9
	v_fma_f32 v10, v130, v82, v10
	v_fma_f32 v11, v131, v83, v11
	v_fma_f32 v12, v132, v84, v12
	v_fma_f32 v13, v133, v85, v13
	v_fma_f32 v14, v134, v86, v14
	v_fma_f32 v15, v135, v87, v15
	v_cvt_pk_bf16_f32 v156, v0, v1
	v_cvt_pk_bf16_f32 v157, v2, v3
	v_cvt_pk_bf16_f32 v158, v4, v5
	v_cvt_pk_bf16_f32 v159, v6, v7
	v_cvt_pk_bf16_f32 v160, v8, v9
	v_cvt_pk_bf16_f32 v161, v10, v11
	v_cvt_pk_bf16_f32 v162, v12, v13
	v_cvt_pk_bf16_f32 v163, v14, v15
	s_lshl_b32 vcc_lo, s19, 11
	s_add_u32 vcc_lo, vcc_lo, 0x3000000
	s_add_u32 s100, s16, vcc_lo
	s_addc_u32 s101, s17, 0
	global_store_dwordx2 v137, v[156:157], s[100:101] offset:0
	global_store_dwordx2 v137, v[158:159], s[100:101] offset:512
	global_store_dwordx2 v137, v[160:161], s[100:101] offset:1024
	global_store_dwordx2 v137, v[162:163], s[100:101] offset:1536
	v_mul_f32_e32 v138, v0, v0
	v_mul_f32_e32 v149, v1, v1
	v_mul_f32_e32 v150, v2, v2
	v_mul_f32_e32 v154, v3, v3
	v_fma_f32 v138, v4, v4, v138
	v_fma_f32 v149, v5, v5, v149
	v_fma_f32 v150, v6, v6, v150
	v_fma_f32 v154, v7, v7, v154
	v_fma_f32 v138, v8, v8, v138
	v_fma_f32 v149, v9, v9, v149
	v_fma_f32 v150, v10, v10, v150
	v_fma_f32 v154, v11, v11, v154
	v_fma_f32 v138, v12, v12, v138
	v_fma_f32 v149, v13, v13, v149
	v_fma_f32 v150, v14, v14, v150
	v_fma_f32 v154, v15, v15, v154
	v_add_f32_e32 v138, v138, v149
	v_add_f32_e32 v150, v150, v154
	v_add_f32_e32 v138, v138, v150
	s_nop 1
	v_add_f32_dpp v138, v138, v138 quad_perm:[1,0,3,2] row_mask:0xf bank_mask:0xf
	s_nop 1
	v_add_f32_dpp v138, v138, v138 quad_perm:[2,3,0,1] row_mask:0xf bank_mask:0xf
	s_nop 1
	v_add_f32_dpp v138, v138, v138 row_half_mirror row_mask:0xf bank_mask:0xf
	s_nop 1
	v_add_f32_dpp v138, v138, v138 row_mirror row_mask:0xf bank_mask:0xf
	v_mov_b32_e32 v139, v138
	s_nop 1
	v_permlane16_swap_b32_e32 v138, v139
	v_add_f32_e32 v138, v138, v139
	v_mov_b32_e32 v139, v138
	s_nop 1
	v_permlane32_swap_b32_e32 v138, v139
	v_add_f32_e32 v138, v138, v139
	v_mul_f32_e32 v138, 0x3a800000, v138
	v_add_f32_e32 v138, 0x358637bd, v138
	v_rsq_f32_e32 v140, v138
	s_nop 0
	v_mul_f32_e32 v120, v0, v140
	v_mul_f32_e32 v121, v1, v140
	v_mul_f32_e32 v122, v2, v140
	v_mul_f32_e32 v123, v3, v140
	v_mul_f32_e32 v124, v4, v140
	v_mul_f32_e32 v125, v5, v140
	v_mul_f32_e32 v126, v6, v140
	v_mul_f32_e32 v127, v7, v140
	v_mul_f32_e32 v128, v8, v140
	v_mul_f32_e32 v129, v9, v140
	v_mul_f32_e32 v130, v10, v140
	v_mul_f32_e32 v131, v11, v140
	v_mul_f32_e32 v132, v12, v140
	v_mul_f32_e32 v133, v13, v140
	v_mul_f32_e32 v134, v14, v140
	v_mul_f32_e32 v135, v15, v140
	v_fma_f32 v120, v120, v88, v104
	v_fma_f32 v121, v121, v89, v105
	v_fma_f32 v122, v122, v90, v106
	v_fma_f32 v123, v123, v91, v107
	v_fma_f32 v124, v124, v92, v108
	v_fma_f32 v125, v125, v93, v109
	v_fma_f32 v126, v126, v94, v110
	v_fma_f32 v127, v127, v95, v111
	v_fma_f32 v128, v128, v96, v112
	v_fma_f32 v129, v129, v97, v113
	v_fma_f32 v130, v130, v98, v114
	v_fma_f32 v131, v131, v99, v115
	v_fma_f32 v132, v132, v100, v116
	v_fma_f32 v133, v133, v101, v117
	v_fma_f32 v134, v134, v102, v118
	v_fma_f32 v135, v135, v103, v119
	v_cvt_pk_bf16_f32 v156, v120, v121
	v_cvt_pk_bf16_f32 v157, v122, v123
	v_cvt_pk_bf16_f32 v158, v124, v125
	v_cvt_pk_bf16_f32 v159, v126, v127
	v_cvt_pk_bf16_f32 v160, v128, v129
	v_cvt_pk_bf16_f32 v161, v130, v131
	v_cvt_pk_bf16_f32 v162, v132, v133
	v_cvt_pk_bf16_f32 v163, v134, v135
	s_lshl_b32 vcc_lo, s19, 11
	s_add_u32 vcc_lo, vcc_lo, 0x3000000
	s_add_u32 s100, s14, vcc_lo
	s_addc_u32 s101, s15, 0
	global_store_dwordx2 v137, v[156:157], s[100:101] offset:0
; __device__ __forceinline__ void row_phase(const Params& P, int glayer, int layer, int xsrc, bool hasY, int gate_idx, const float* gpost,
;                           int xdst, bool doH, const float* gpre, int sh_idx, int nrows) {
;     ...
;         if (hasY) {
;           float4 yv[4];
;           float ss = 0.f;
; #pragma unroll
;           for (int i = 0; i < 4; ++i) {
;             const uint2 raw = yy[u][i];
;             yv[i].x = bf2f((u16)(raw.x & 0xffff)); yv[i].y = bf2f((u16)(raw.x >> 16));
;             yv[i].z = bf2f((u16)(raw.y & 0xffff)); yv[i].w = bf2f((u16)(raw.y >> 16));
;             ss += yv[i].x * yv[i].x + yv[i].y * yv[i].y + yv[i].z * yv[i].z + yv[i].w * yv[i].w;
;           }
;           ss = wave_sum(ss);
;           const float rstd = __builtin_amdgcn_rsqf(ss * (1.f / 1024.f) + EPSF);
; #pragma unroll
;           for (int i = 0; i < 4; ++i) {
;             const int col = (i * 64 + lane) * 4;
;             const float4 gt = *reinterpret_cast<const float4*>(modg + gate_idx * 1024 + col);
;             const float4 gp = *reinterpret_cast<const float4*>(gpost + col);
;             xv[i].x += gt.x * (yv[i].x * rstd * gp.x); xv[i].y += gt.y * (yv[i].y * rstd * gp.y);
;             xv[i].z += gt.z * (yv[i].z * rstd * gp.z); xv[i].w += gt.w * (yv[i].w * rstd * gp.w);
;           }
;         }
;         if (xdst == 3 || (xdst == 1 && row >= N_X)) {
;           float* xout = (xdst == 3) ? P.out + (long)row * 1024 : P.xc + (long)(row - N_X) * 1024;
; #pragma unroll
;           for (int i = 0; i < 4; ++i) *reinterpret_cast<float4*>(xout + (i * 64 + lane) * 4) = xv[i];
;         } else if (xdst != 0) {
;           u16* xo = ((xdst == 1) ? resA : P.zf) + (long)row * 1024;
; #pragma unroll
;           for (int i = 0; i < 4; ++i) {
;             const unsigned b0 = f2bf(xv[i].x), b1 = f2bf(xv[i].y), b2 = f2bf(xv[i].z), b3 = f2bf(xv[i].w);
;             *reinterpret_cast<uint2*>(xo + (i * 64 + lane) * 4) = make_uint2(b0 | (b1 << 16), b2 | (b3 << 16));
;           }
;         }
;         if (doH) {
;           float ss = 0.f;
; #pragma unroll
;           for (int i = 0; i < 4; ++i) ss += xv[i].x * xv[i].x + xv[i].y * xv[i].y + xv[i].z * xv[i].z + xv[i].w * xv[i].w;
;           ss = wave_sum(ss);
;           const float rstd = __builtin_amdgcn_rsqf(ss * (1.f / 1024.f) + EPSF);
;           u16* h = P.hy + (long)row * 1024;
; #pragma unroll
	global_store_dwordx2 v137, v[158:159], s[100:101] offset:512
	global_store_dwordx2 v137, v[160:161], s[100:101] offset:1024
	global_store_dwordx2 v137, v[162:163], s[100:101] offset:1536
	s_lshl_b32 vcc_lo, s19, 11
	s_add_u32 vcc_lo, vcc_lo, 0x3c00000
	s_add_u32 s100, s12, vcc_lo
	s_addc_u32 s101, s13, 0
	global_load_dwordx2 v[8:9], v137, s[100:101] offset:0
	global_load_dwordx2 v[10:11], v137, s[100:101] offset:512
	global_load_dwordx2 v[12:13], v137, s[100:101] offset:1024
	global_load_dwordx2 v[14:15], v137, s[100:101] offset:1536
	s_lshl_b32 vcc_lo, s19, 11
	s_add_u32 vcc_lo, vcc_lo, 0x3c00000
	s_add_u32 s100, s14, vcc_lo
	s_addc_u32 s101, s15, 0
	global_load_dwordx2 v[48:49], v137, s[100:101] offset:0
	global_load_dwordx2 v[50:51], v137, s[100:101] offset:512
	global_load_dwordx2 v[52:53], v137, s[100:101] offset:1024
	global_load_dwordx2 v[54:55], v137, s[100:101] offset:1536
	v_lshlrev_b32_e32 v120, 16, v56
	v_and_b32_e32 v121, 0xffff0000, v56
	v_lshlrev_b32_e32 v122, 16, v57
	v_and_b32_e32 v123, 0xffff0000, v57
	v_lshlrev_b32_e32 v124, 16, v58
	v_and_b32_e32 v125, 0xffff0000, v58
	v_lshlrev_b32_e32 v126, 16, v59
	v_and_b32_e32 v127, 0xffff0000, v59
	v_lshlrev_b32_e32 v128, 16, v60
	v_and_b32_e32 v129, 0xffff0000, v60
	v_lshlrev_b32_e32 v130, 16, v61
	v_and_b32_e32 v131, 0xffff0000, v61
	v_lshlrev_b32_e32 v132, 16, v62
	v_and_b32_e32 v133, 0xffff0000, v62
	v_lshlrev_b32_e32 v134, 16, v63
	v_and_b32_e32 v135, 0xffff0000, v63
	v_mul_f32_e32 v138, v120, v120
	v_mul_f32_e32 v149, v121, v121
	v_mul_f32_e32 v150, v122, v122
	v_mul_f32_e32 v154, v123, v123
	v_fma_f32 v138, v124, v124, v138
	v_fma_f32 v149, v125, v125, v149
	v_fma_f32 v150, v126, v126, v150
	v_fma_f32 v154, v127, v127, v154
	v_fma_f32 v138, v128, v128, v138
	v_fma_f32 v149, v129, v129, v149
	v_fma_f32 v150, v130, v130, v150
	v_fma_f32 v154, v131, v131, v154
	v_fma_f32 v138, v132, v132, v138
	v_fma_f32 v149, v133, v133, v149
	v_fma_f32 v150, v134, v134, v150
	v_fma_f32 v154, v135, v135, v154
	v_add_f32_e32 v138, v138, v149
	v_add_f32_e32 v150, v150, v154
	v_add_f32_e32 v138, v138, v150
	s_nop 1
	v_add_f32_dpp v138, v138, v138 quad_perm:[1,0,3,2] row_mask:0xf bank_mask:0xf
	s_nop 1
	v_add_f32_dpp v138, v138, v138 quad_perm:[2,3,0,1] row_mask:0xf bank_mask:0xf
	s_nop 1
	v_add_f32_dpp v138, v138, v138 row_half_mirror row_mask:0xf bank_mask:0xf
	s_nop 1
	v_add_f32_dpp v138, v138, v138 row_mirror row_mask:0xf bank_mask:0xf
	v_mov_b32_e32 v139, v138
	s_nop 1
	v_permlane16_swap_b32_e32 v138, v139
	v_add_f32_e32 v138, v138, v139
	v_mov_b32_e32 v139, v138
	s_nop 1
	v_permlane32_swap_b32_e32 v138, v139
	v_add_f32_e32 v138, v138, v139
	v_mul_f32_e32 v138, 0x3a800000, v138
	v_add_f32_e32 v138, 0x358637bd, v138
	v_rsq_f32_e32 v140, v138
	v_lshlrev_b32_e32 v16, 16, v24
	v_and_b32_e32 v17, 0xffff0000, v24
	v_lshlrev_b32_e32 v18, 16, v25
	v_and_b32_e32 v19, 0xffff0000, v25
	v_lshlrev_b32_e32 v20, 16, v26
	v_and_b32_e32 v21, 0xffff0000, v26
	v_lshlrev_b32_e32 v22, 16, v27
	v_and_b32_e32 v23, 0xffff0000, v27
	v_lshlrev_b32_e32 v24, 16, v28
	v_and_b32_e32 v25, 0xffff0000, v28
	v_lshlrev_b32_e32 v26, 16, v29
	v_and_b32_e32 v27, 0xffff0000, v29
	v_lshlrev_b32_e32 v28, 16, v30
	v_and_b32_e32 v29, 0xffff0000, v30
	v_lshlrev_b32_e32 v30, 16, v31
	v_and_b32_e32 v31, 0xffff0000, v31
	s_nop 0
	v_mul_f32_e32 v120, v120, v140
	v_mul_f32_e32 v121, v121, v140
	v_mul_f32_e32 v122, v122, v140
	v_mul_f32_e32 v123, v123, v140
	v_mul_f32_e32 v124, v124, v140
	v_mul_f32_e32 v125, v125, v140
	v_mul_f32_e32 v126, v126, v140
	v_mul_f32_e32 v127, v127, v140
	v_mul_f32_e32 v128, v128, v140
	v_mul_f32_e32 v129, v129, v140
	v_mul_f32_e32 v130, v130, v140
	v_mul_f32_e32 v131, v131, v140
	v_mul_f32_e32 v132, v132, v140
	v_mul_f32_e32 v133, v133, v140
	v_mul_f32_e32 v134, v134, v140
	v_mul_f32_e32 v135, v135, v140
	v_fma_f32 v16, v120, v72, v16
	v_fma_f32 v17, v121, v73, v17
	v_fma_f32 v18, v122, v74, v18
	v_fma_f32 v19, v123, v75, v19
	v_fma_f32 v20, v124, v76, v20
	v_fma_f32 v21, v125, v77, v21
	v_fma_f32 v22, v126, v78, v22
	v_fma_f32 v23, v127, v79, v23
	v_fma_f32 v24, v128, v80, v24
	v_fma_f32 v25, v129, v81, v25
	v_fma_f32 v26, v130, v82, v26
	v_fma_f32 v27, v131, v83, v27
	v_fma_f32 v28, v132, v84, v28
	v_fma_f32 v29, v133, v85, v29
	v_fma_f32 v30, v134, v86, v30
	v_fma_f32 v31, v135, v87, v31
	v_cvt_pk_bf16_f32 v156, v16, v17
	v_cvt_pk_bf16_f32 v157, v18, v19
	v_cvt_pk_bf16_f32 v158, v20, v21
	v_cvt_pk_bf16_f32 v159, v22, v23
	v_cvt_pk_bf16_f32 v160, v24, v25
	v_cvt_pk_bf16_f32 v161, v26, v27
	v_cvt_pk_bf16_f32 v162, v28, v29
	v_cvt_pk_bf16_f32 v163, v30, v31
	s_lshl_b32 vcc_lo, s19, 11
	s_add_u32 vcc_lo, vcc_lo, 0x3400000
	s_add_u32 s100, s16, vcc_lo
	s_addc_u32 s101, s17, 0
	global_store_dwordx2 v137, v[156:157], s[100:101] offset:0
	global_store_dwordx2 v137, v[158:159], s[100:101] offset:512
	global_store_dwordx2 v137, v[160:161], s[100:101] offset:1024
	global_store_dwordx2 v137, v[162:163], s[100:101] offset:1536
	v_mul_f32_e32 v138, v16, v16
	v_mul_f32_e32 v149, v17, v17
	v_mul_f32_e32 v150, v18, v18
	v_mul_f32_e32 v154, v19, v19
	v_fma_f32 v138, v20, v20, v138
	v_fma_f32 v149, v21, v21, v149
	v_fma_f32 v150, v22, v22, v150
	v_fma_f32 v154, v23, v23, v154
	v_fma_f32 v138, v24, v24, v138
	v_fma_f32 v149, v25, v25, v149
	v_fma_f32 v150, v26, v26, v150
	v_fma_f32 v154, v27, v27, v154
	v_fma_f32 v138, v28, v28, v138
	v_fma_f32 v149, v29, v29, v149
	v_fma_f32 v150, v30, v30, v150
	v_fma_f32 v154, v31, v31, v154
	v_add_f32_e32 v138, v138, v149
	v_add_f32_e32 v150, v150, v154
	v_add_f32_e32 v138, v138, v150
	s_nop 1
	v_add_f32_dpp v138, v138, v138 quad_perm:[1,0,3,2] row_mask:0xf bank_mask:0xf
	s_nop 1
; __device__ __forceinline__ void row_phase(const Params& P, int glayer, int layer, int xsrc, bool hasY, int gate_idx, const float* gpost,
;                           int xdst, bool doH, const float* gpre, int sh_idx, int nrows) {
;     ...
;         if (hasY) {
;           float4 yv[4];
;           float ss = 0.f;
; #pragma unroll
;           for (int i = 0; i < 4; ++i) {
;             const uint2 raw = yy[u][i];
;             yv[i].x = bf2f((u16)(raw.x & 0xffff)); yv[i].y = bf2f((u16)(raw.x >> 16));
;             yv[i].z = bf2f((u16)(raw.y & 0xffff)); yv[i].w = bf2f((u16)(raw.y >> 16));
;             ss += yv[i].x * yv[i].x + yv[i].y * yv[i].y + yv[i].z * yv[i].z + yv[i].w * yv[i].w;
;           }
;           ss = wave_sum(ss);
;           const float rstd = __builtin_amdgcn_rsqf(ss * (1.f / 1024.f) + EPSF);
; #pragma unroll
;           for (int i = 0; i < 4; ++i) {
;             const int col = (i * 64 + lane) * 4;
;             const float4 gt = *reinterpret_cast<const float4*>(modg + gate_idx * 1024 + col);
;             const float4 gp = *reinterpret_cast<const float4*>(gpost + col);
;             xv[i].x += gt.x * (yv[i].x * rstd * gp.x); xv[i].y += gt.y * (yv[i].y * rstd * gp.y);
;             xv[i].z += gt.z * (yv[i].z * rstd * gp.z); xv[i].w += gt.w * (yv[i].w * rstd * gp.w);
;           }
;         }
;         if (xdst == 3 || (xdst == 1 && row >= N_X)) {
;           float* xout = (xdst == 3) ? P.out + (long)row * 1024 : P.xc + (long)(row - N_X) * 1024;
; #pragma unroll
;           for (int i = 0; i < 4; ++i) *reinterpret_cast<float4*>(xout + (i * 64 + lane) * 4) = xv[i];
;         } else if (xdst != 0) {
;           u16* xo = ((xdst == 1) ? resA : P.zf) + (long)row * 1024;
; #pragma unroll
;           for (int i = 0; i < 4; ++i) {
;             const unsigned b0 = f2bf(xv[i].x), b1 = f2bf(xv[i].y), b2 = f2bf(xv[i].z), b3 = f2bf(xv[i].w);
;             *reinterpret_cast<uint2*>(xo + (i * 64 + lane) * 4) = make_uint2(b0 | (b1 << 16), b2 | (b3 << 16));
;           }
;         }
;         if (doH) {
;           float ss = 0.f;
; #pragma unroll
;           for (int i = 0; i < 4; ++i) ss += xv[i].x * xv[i].x + xv[i].y * xv[i].y + xv[i].z * xv[i].z + xv[i].w * xv[i].w;
;           ss = wave_sum(ss);
;           const float rstd = __builtin_amdgcn_rsqf(ss * (1.f / 1024.f) + EPSF);
;           u16* h = P.hy + (long)row * 1024;
; #pragma unroll
	v_add_f32_dpp v138, v138, v138 quad_perm:[2,3,0,1] row_mask:0xf bank_mask:0xf
	s_nop 1
	v_add_f32_dpp v138, v138, v138 row_half_mirror row_mask:0xf bank_mask:0xf
	s_nop 1
	v_add_f32_dpp v138, v138, v138 row_mirror row_mask:0xf bank_mask:0xf
	v_mov_b32_e32 v139, v138
	s_nop 1
	v_permlane16_swap_b32_e32 v138, v139
	v_add_f32_e32 v138, v138, v139
	v_mov_b32_e32 v139, v138
	s_nop 1
	v_permlane32_swap_b32_e32 v138, v139
	v_add_f32_e32 v138, v138, v139
	v_mul_f32_e32 v138, 0x3a800000, v138
	v_add_f32_e32 v138, 0x358637bd, v138
	v_rsq_f32_e32 v140, v138
	s_nop 0
	v_mul_f32_e32 v120, v16, v140
	v_mul_f32_e32 v121, v17, v140
	v_mul_f32_e32 v122, v18, v140
	v_mul_f32_e32 v123, v19, v140
	v_mul_f32_e32 v124, v20, v140
	v_mul_f32_e32 v125, v21, v140
	v_mul_f32_e32 v126, v22, v140
	v_mul_f32_e32 v127, v23, v140
	v_mul_f32_e32 v128, v24, v140
	v_mul_f32_e32 v129, v25, v140
	v_mul_f32_e32 v130, v26, v140
	v_mul_f32_e32 v131, v27, v140
	v_mul_f32_e32 v132, v28, v140
	v_mul_f32_e32 v133, v29, v140
	v_mul_f32_e32 v134, v30, v140
	v_mul_f32_e32 v135, v31, v140
	v_fma_f32 v120, v120, v88, v104
	v_fma_f32 v121, v121, v89, v105
	v_fma_f32 v122, v122, v90, v106
	v_fma_f32 v123, v123, v91, v107
	v_fma_f32 v124, v124, v92, v108
	v_fma_f32 v125, v125, v93, v109
	v_fma_f32 v126, v126, v94, v110
	v_fma_f32 v127, v127, v95, v111
	v_fma_f32 v128, v128, v96, v112
	v_fma_f32 v129, v129, v97, v113
	v_fma_f32 v130, v130, v98, v114
	v_fma_f32 v131, v131, v99, v115
	v_fma_f32 v132, v132, v100, v116
	v_fma_f32 v133, v133, v101, v117
	v_fma_f32 v134, v134, v102, v118
	v_fma_f32 v135, v135, v103, v119
	v_cvt_pk_bf16_f32 v156, v120, v121
	v_cvt_pk_bf16_f32 v157, v122, v123
	v_cvt_pk_bf16_f32 v158, v124, v125
	v_cvt_pk_bf16_f32 v159, v126, v127
	v_cvt_pk_bf16_f32 v160, v128, v129
	v_cvt_pk_bf16_f32 v161, v130, v131
	v_cvt_pk_bf16_f32 v162, v132, v133
	v_cvt_pk_bf16_f32 v163, v134, v135
	s_lshl_b32 vcc_lo, s19, 11
	s_add_u32 vcc_lo, vcc_lo, 0x3400000
	s_add_u32 s100, s14, vcc_lo
	s_addc_u32 s101, s15, 0
	global_store_dwordx2 v137, v[156:157], s[100:101] offset:0
	global_store_dwordx2 v137, v[158:159], s[100:101] offset:512
	global_store_dwordx2 v137, v[160:161], s[100:101] offset:1024
	global_store_dwordx2 v137, v[162:163], s[100:101] offset:1536
	s_waitcnt vmcnt(24)
	v_lshlrev_b32_e32 v120, 16, v64
	v_and_b32_e32 v121, 0xffff0000, v64
	v_lshlrev_b32_e32 v122, 16, v65
	v_and_b32_e32 v123, 0xffff0000, v65
	v_lshlrev_b32_e32 v124, 16, v66
	v_and_b32_e32 v125, 0xffff0000, v66
	v_lshlrev_b32_e32 v126, 16, v67
	v_and_b32_e32 v127, 0xffff0000, v67
	v_lshlrev_b32_e32 v128, 16, v68
	v_and_b32_e32 v129, 0xffff0000, v68
	v_lshlrev_b32_e32 v130, 16, v69
	v_and_b32_e32 v131, 0xffff0000, v69
	v_lshlrev_b32_e32 v132, 16, v70
	v_and_b32_e32 v133, 0xffff0000, v70
	v_lshlrev_b32_e32 v134, 16, v71
	v_and_b32_e32 v135, 0xffff0000, v71
	v_mul_f32_e32 v138, v120, v120
	v_mul_f32_e32 v149, v121, v121
	v_mul_f32_e32 v150, v122, v122
	v_mul_f32_e32 v154, v123, v123
	v_fma_f32 v138, v124, v124, v138
	v_fma_f32 v149, v125, v125, v149
	v_fma_f32 v150, v126, v126, v150
	v_fma_f32 v154, v127, v127, v154
	v_fma_f32 v138, v128, v128, v138
	v_fma_f32 v149, v129, v129, v149
	v_fma_f32 v150, v130, v130, v150
	v_fma_f32 v154, v131, v131, v154
	v_fma_f32 v138, v132, v132, v138
	v_fma_f32 v149, v133, v133, v149
	v_fma_f32 v150, v134, v134, v150
	v_fma_f32 v154, v135, v135, v154
	v_add_f32_e32 v138, v138, v149
	v_add_f32_e32 v150, v150, v154
	v_add_f32_e32 v138, v138, v150
	s_nop 1
	v_add_f32_dpp v138, v138, v138 quad_perm:[1,0,3,2] row_mask:0xf bank_mask:0xf
	s_nop 1
	v_add_f32_dpp v138, v138, v138 quad_perm:[2,3,0,1] row_mask:0xf bank_mask:0xf
	s_nop 1
	v_add_f32_dpp v138, v138, v138 row_half_mirror row_mask:0xf bank_mask:0xf
	s_nop 1
	v_add_f32_dpp v138, v138, v138 row_mirror row_mask:0xf bank_mask:0xf
	v_mov_b32_e32 v139, v138
	s_nop 1
	v_permlane16_swap_b32_e32 v138, v139
	v_add_f32_e32 v138, v138, v139
	v_mov_b32_e32 v139, v138
	s_nop 1
	v_permlane32_swap_b32_e32 v138, v139
	v_add_f32_e32 v138, v138, v139
	v_mul_f32_e32 v138, 0x3a800000, v138
	v_add_f32_e32 v138, 0x358637bd, v138
	v_rsq_f32_e32 v140, v138
	v_lshlrev_b32_e32 v32, 16, v40
	v_and_b32_e32 v33, 0xffff0000, v40
	v_lshlrev_b32_e32 v34, 16, v41
	v_and_b32_e32 v35, 0xffff0000, v41
	v_lshlrev_b32_e32 v36, 16, v42
	v_and_b32_e32 v37, 0xffff0000, v42
	v_lshlrev_b32_e32 v38, 16, v43
	v_and_b32_e32 v39, 0xffff0000, v43
	v_lshlrev_b32_e32 v40, 16, v44
	v_and_b32_e32 v41, 0xffff0000, v44
	v_lshlrev_b32_e32 v42, 16, v45
	v_and_b32_e32 v43, 0xffff0000, v45
	v_lshlrev_b32_e32 v44, 16, v46
	v_and_b32_e32 v45, 0xffff0000, v46
	v_lshlrev_b32_e32 v46, 16, v47
	v_and_b32_e32 v47, 0xffff0000, v47
	s_nop 0
	v_mul_f32_e32 v120, v120, v140
	v_mul_f32_e32 v121, v121, v140
	v_mul_f32_e32 v122, v122, v140
	v_mul_f32_e32 v123, v123, v140
	v_mul_f32_e32 v124, v124, v140
	v_mul_f32_e32 v125, v125, v140
	v_mul_f32_e32 v126, v126, v140
	v_mul_f32_e32 v127, v127, v140
	v_mul_f32_e32 v128, v128, v140
	v_mul_f32_e32 v129, v129, v140
	v_mul_f32_e32 v130, v130, v140
	v_mul_f32_e32 v131, v131, v140
	v_mul_f32_e32 v132, v132, v140
	v_mul_f32_e32 v133, v133, v140
	v_mul_f32_e32 v134, v134, v140
	v_mul_f32_e32 v135, v135, v140
	v_fma_f32 v32, v120, v72, v32
	v_fma_f32 v33, v121, v73, v33
	v_fma_f32 v34, v122, v74, v34
	v_fma_f32 v35, v123, v75, v35
	v_fma_f32 v36, v124, v76, v36
	v_fma_f32 v37, v125, v77, v37
	v_fma_f32 v38, v126, v78, v38
	v_fma_f32 v39, v127, v79, v39
	v_fma_f32 v40, v128, v80, v40
	v_fma_f32 v41, v129, v81, v41
	v_fma_f32 v42, v130, v82, v42
	v_fma_f32 v43, v131, v83, v43
	v_fma_f32 v44, v132, v84, v44
	v_fma_f32 v45, v133, v85, v45
	v_fma_f32 v46, v134, v86, v46
; __device__ __forceinline__ void row_phase(const Params& P, int glayer, int layer, int xsrc, bool hasY, int gate_idx, const float* gpost,
;                           int xdst, bool doH, const float* gpre, int sh_idx, int nrows) {
;     ...
;         if (hasY) {
;           float4 yv[4];
;           float ss = 0.f;
; #pragma unroll
;           for (int i = 0; i < 4; ++i) {
;             const uint2 raw = yy[u][i];
;             yv[i].x = bf2f((u16)(raw.x & 0xffff)); yv[i].y = bf2f((u16)(raw.x >> 16));
;             yv[i].z = bf2f((u16)(raw.y & 0xffff)); yv[i].w = bf2f((u16)(raw.y >> 16));
;             ss += yv[i].x * yv[i].x + yv[i].y * yv[i].y + yv[i].z * yv[i].z + yv[i].w * yv[i].w;
;           }
;           ss = wave_sum(ss);
;           const float rstd = __builtin_amdgcn_rsqf(ss * (1.f / 1024.f) + EPSF);
; #pragma unroll
;           for (int i = 0; i < 4; ++i) {
;             const int col = (i * 64 + lane) * 4;
;             const float4 gt = *reinterpret_cast<const float4*>(modg + gate_idx * 1024 + col);
;             const float4 gp = *reinterpret_cast<const float4*>(gpost + col);
;             xv[i].x += gt.x * (yv[i].x * rstd * gp.x); xv[i].y += gt.y * (yv[i].y * rstd * gp.y);
;             xv[i].z += gt.z * (yv[i].z * rstd * gp.z); xv[i].w += gt.w * (yv[i].w * rstd * gp.w);
;           }
;         }
;         if (xdst == 3 || (xdst == 1 && row >= N_X)) {
;           float* xout = (xdst == 3) ? P.out + (long)row * 1024 : P.xc + (long)(row - N_X) * 1024;
; #pragma unroll
;           for (int i = 0; i < 4; ++i) *reinterpret_cast<float4*>(xout + (i * 64 + lane) * 4) = xv[i];
;         } else if (xdst != 0) {
;           u16* xo = ((xdst == 1) ? resA : P.zf) + (long)row * 1024;
; #pragma unroll
;           for (int i = 0; i < 4; ++i) {
;             const unsigned b0 = f2bf(xv[i].x), b1 = f2bf(xv[i].y), b2 = f2bf(xv[i].z), b3 = f2bf(xv[i].w);
;             *reinterpret_cast<uint2*>(xo + (i * 64 + lane) * 4) = make_uint2(b0 | (b1 << 16), b2 | (b3 << 16));
;           }
;         }
;         if (doH) {
;           float ss = 0.f;
; #pragma unroll
;           for (int i = 0; i < 4; ++i) ss += xv[i].x * xv[i].x + xv[i].y * xv[i].y + xv[i].z * xv[i].z + xv[i].w * xv[i].w;
;           ss = wave_sum(ss);
;           const float rstd = __builtin_amdgcn_rsqf(ss * (1.f / 1024.f) + EPSF);
;           u16* h = P.hy + (long)row * 1024;
; #pragma unroll
	v_fma_f32 v47, v135, v87, v47
	v_cvt_pk_bf16_f32 v156, v32, v33
	v_cvt_pk_bf16_f32 v157, v34, v35
	v_cvt_pk_bf16_f32 v158, v36, v37
	v_cvt_pk_bf16_f32 v159, v38, v39
	v_cvt_pk_bf16_f32 v160, v40, v41
	v_cvt_pk_bf16_f32 v161, v42, v43
	v_cvt_pk_bf16_f32 v162, v44, v45
	v_cvt_pk_bf16_f32 v163, v46, v47
	s_lshl_b32 vcc_lo, s19, 11
	s_add_u32 vcc_lo, vcc_lo, 0x3800000
	s_add_u32 s100, s16, vcc_lo
	s_addc_u32 s101, s17, 0
	global_store_dwordx2 v137, v[156:157], s[100:101] offset:0
	global_store_dwordx2 v137, v[158:159], s[100:101] offset:512
	global_store_dwordx2 v137, v[160:161], s[100:101] offset:1024
	global_store_dwordx2 v137, v[162:163], s[100:101] offset:1536
	v_mul_f32_e32 v138, v32, v32
	v_mul_f32_e32 v149, v33, v33
	v_mul_f32_e32 v150, v34, v34
	v_mul_f32_e32 v154, v35, v35
	v_fma_f32 v138, v36, v36, v138
	v_fma_f32 v149, v37, v37, v149
	v_fma_f32 v150, v38, v38, v150
	v_fma_f32 v154, v39, v39, v154
	v_fma_f32 v138, v40, v40, v138
	v_fma_f32 v149, v41, v41, v149
	v_fma_f32 v150, v42, v42, v150
	v_fma_f32 v154, v43, v43, v154
	v_fma_f32 v138, v44, v44, v138
	v_fma_f32 v149, v45, v45, v149
	v_fma_f32 v150, v46, v46, v150
	v_fma_f32 v154, v47, v47, v154
	v_add_f32_e32 v138, v138, v149
	v_add_f32_e32 v150, v150, v154
	v_add_f32_e32 v138, v138, v150
	s_nop 1
	v_add_f32_dpp v138, v138, v138 quad_perm:[1,0,3,2] row_mask:0xf bank_mask:0xf
	s_nop 1
	v_add_f32_dpp v138, v138, v138 quad_perm:[2,3,0,1] row_mask:0xf bank_mask:0xf
	s_nop 1
	v_add_f32_dpp v138, v138, v138 row_half_mirror row_mask:0xf bank_mask:0xf
	s_nop 1
	v_add_f32_dpp v138, v138, v138 row_mirror row_mask:0xf bank_mask:0xf
	v_mov_b32_e32 v139, v138
	s_nop 1
	v_permlane16_swap_b32_e32 v138, v139
	v_add_f32_e32 v138, v138, v139
	v_mov_b32_e32 v139, v138
	s_nop 1
	v_permlane32_swap_b32_e32 v138, v139
	v_add_f32_e32 v138, v138, v139
	v_mul_f32_e32 v138, 0x3a800000, v138
	v_add_f32_e32 v138, 0x358637bd, v138
	v_rsq_f32_e32 v140, v138
	s_nop 0
	v_mul_f32_e32 v120, v32, v140
	v_mul_f32_e32 v121, v33, v140
	v_mul_f32_e32 v122, v34, v140
	v_mul_f32_e32 v123, v35, v140
	v_mul_f32_e32 v124, v36, v140
	v_mul_f32_e32 v125, v37, v140
	v_mul_f32_e32 v126, v38, v140
	v_mul_f32_e32 v127, v39, v140
	v_mul_f32_e32 v128, v40, v140
	v_mul_f32_e32 v129, v41, v140
	v_mul_f32_e32 v130, v42, v140
	v_mul_f32_e32 v131, v43, v140
	v_mul_f32_e32 v132, v44, v140
	v_mul_f32_e32 v133, v45, v140
	v_mul_f32_e32 v134, v46, v140
	v_mul_f32_e32 v135, v47, v140
	v_fma_f32 v120, v120, v88, v104
	v_fma_f32 v121, v121, v89, v105
	v_fma_f32 v122, v122, v90, v106
	v_fma_f32 v123, v123, v91, v107
	v_fma_f32 v124, v124, v92, v108
	v_fma_f32 v125, v125, v93, v109
	v_fma_f32 v126, v126, v94, v110
	v_fma_f32 v127, v127, v95, v111
	v_fma_f32 v128, v128, v96, v112
	v_fma_f32 v129, v129, v97, v113
	v_fma_f32 v130, v130, v98, v114
	v_fma_f32 v131, v131, v99, v115
	v_fma_f32 v132, v132, v100, v116
	v_fma_f32 v133, v133, v101, v117
	v_fma_f32 v134, v134, v102, v118
	v_fma_f32 v135, v135, v103, v119
	v_cvt_pk_bf16_f32 v156, v120, v121
	v_cvt_pk_bf16_f32 v157, v122, v123
	v_cvt_pk_bf16_f32 v158, v124, v125
	v_cvt_pk_bf16_f32 v159, v126, v127
	v_cvt_pk_bf16_f32 v160, v128, v129
	v_cvt_pk_bf16_f32 v161, v130, v131
	v_cvt_pk_bf16_f32 v162, v132, v133
	v_cvt_pk_bf16_f32 v163, v134, v135
	s_lshl_b32 vcc_lo, s19, 11
	s_add_u32 vcc_lo, vcc_lo, 0x3800000
	s_add_u32 s100, s14, vcc_lo
	s_addc_u32 s101, s15, 0
	global_store_dwordx2 v137, v[156:157], s[100:101] offset:0
	global_store_dwordx2 v137, v[158:159], s[100:101] offset:512
	global_store_dwordx2 v137, v[160:161], s[100:101] offset:1024
	global_store_dwordx2 v137, v[162:163], s[100:101] offset:1536
	s_waitcnt vmcnt(16)
	v_lshlrev_b32_e32 v120, 16, v48
	v_and_b32_e32 v121, 0xffff0000, v48
	v_lshlrev_b32_e32 v122, 16, v49
	v_and_b32_e32 v123, 0xffff0000, v49
	v_lshlrev_b32_e32 v124, 16, v50
	v_and_b32_e32 v125, 0xffff0000, v50
	v_lshlrev_b32_e32 v126, 16, v51
	v_and_b32_e32 v127, 0xffff0000, v51
	v_lshlrev_b32_e32 v128, 16, v52
	v_and_b32_e32 v129, 0xffff0000, v52
	v_lshlrev_b32_e32 v130, 16, v53
	v_and_b32_e32 v131, 0xffff0000, v53
	v_lshlrev_b32_e32 v132, 16, v54
	v_and_b32_e32 v133, 0xffff0000, v54
	v_lshlrev_b32_e32 v134, 16, v55
	v_and_b32_e32 v135, 0xffff0000, v55
	v_mul_f32_e32 v138, v120, v120
	v_mul_f32_e32 v149, v121, v121
	v_mul_f32_e32 v150, v122, v122
	v_mul_f32_e32 v154, v123, v123
	v_fma_f32 v138, v124, v124, v138
	v_fma_f32 v149, v125, v125, v149
	v_fma_f32 v150, v126, v126, v150
	v_fma_f32 v154, v127, v127, v154
	v_fma_f32 v138, v128, v128, v138
	v_fma_f32 v149, v129, v129, v149
	v_fma_f32 v150, v130, v130, v150
	v_fma_f32 v154, v131, v131, v154
	v_fma_f32 v138, v132, v132, v138
	v_fma_f32 v149, v133, v133, v149
	v_fma_f32 v150, v134, v134, v150
	v_fma_f32 v154, v135, v135, v154
	v_add_f32_e32 v138, v138, v149
	v_add_f32_e32 v150, v150, v154
	v_add_f32_e32 v138, v138, v150
	s_nop 1
	v_add_f32_dpp v138, v138, v138 quad_perm:[1,0,3,2] row_mask:0xf bank_mask:0xf
	s_nop 1
	v_add_f32_dpp v138, v138, v138 quad_perm:[2,3,0,1] row_mask:0xf bank_mask:0xf
	s_nop 1
	v_add_f32_dpp v138, v138, v138 row_half_mirror row_mask:0xf bank_mask:0xf
	s_nop 1
	v_add_f32_dpp v138, v138, v138 row_mirror row_mask:0xf bank_mask:0xf
	v_mov_b32_e32 v139, v138
	s_nop 1
	v_permlane16_swap_b32_e32 v138, v139
	v_add_f32_e32 v138, v138, v139
	v_mov_b32_e32 v139, v138
	s_nop 1
	v_permlane32_swap_b32_e32 v138, v139
	v_add_f32_e32 v138, v138, v139
	v_mul_f32_e32 v138, 0x3a800000, v138
	v_add_f32_e32 v138, 0x358637bd, v138
	v_rsq_f32_e32 v140, v138
	v_lshlrev_b32_e32 v0, 16, v8
	v_and_b32_e32 v1, 0xffff0000, v8
	v_lshlrev_b32_e32 v2, 16, v9
	v_and_b32_e32 v3, 0xffff0000, v9
	v_lshlrev_b32_e32 v4, 16, v10
; __device__ __forceinline__ void row_phase(const Params& P, int glayer, int layer, int xsrc, bool hasY, int gate_idx, const float* gpost,
;                           int xdst, bool doH, const float* gpre, int sh_idx, int nrows) {
;     ...
;         if (hasY) {
;           float4 yv[4];
;           float ss = 0.f;
; #pragma unroll
;           for (int i = 0; i < 4; ++i) {
;             const uint2 raw = yy[u][i];
;             yv[i].x = bf2f((u16)(raw.x & 0xffff)); yv[i].y = bf2f((u16)(raw.x >> 16));
;             yv[i].z = bf2f((u16)(raw.y & 0xffff)); yv[i].w = bf2f((u16)(raw.y >> 16));
;             ss += yv[i].x * yv[i].x + yv[i].y * yv[i].y + yv[i].z * yv[i].z + yv[i].w * yv[i].w;
;           }
;           ss = wave_sum(ss);
;           const float rstd = __builtin_amdgcn_rsqf(ss * (1.f / 1024.f) + EPSF);
; #pragma unroll
;           for (int i = 0; i < 4; ++i) {
;             const int col = (i * 64 + lane) * 4;
;             const float4 gt = *reinterpret_cast<const float4*>(modg + gate_idx * 1024 + col);
;             const float4 gp = *reinterpret_cast<const float4*>(gpost + col);
;             xv[i].x += gt.x * (yv[i].x * rstd * gp.x); xv[i].y += gt.y * (yv[i].y * rstd * gp.y);
;             xv[i].z += gt.z * (yv[i].z * rstd * gp.z); xv[i].w += gt.w * (yv[i].w * rstd * gp.w);
;           }
;         }
;         if (xdst == 3 || (xdst == 1 && row >= N_X)) {
;           float* xout = (xdst == 3) ? P.out + (long)row * 1024 : P.xc + (long)(row - N_X) * 1024;
; #pragma unroll
;           for (int i = 0; i < 4; ++i) *reinterpret_cast<float4*>(xout + (i * 64 + lane) * 4) = xv[i];
;         } else if (xdst != 0) {
;           u16* xo = ((xdst == 1) ? resA : P.zf) + (long)row * 1024;
; #pragma unroll
;           for (int i = 0; i < 4; ++i) {
;             const unsigned b0 = f2bf(xv[i].x), b1 = f2bf(xv[i].y), b2 = f2bf(xv[i].z), b3 = f2bf(xv[i].w);
;             *reinterpret_cast<uint2*>(xo + (i * 64 + lane) * 4) = make_uint2(b0 | (b1 << 16), b2 | (b3 << 16));
;           }
;         }
;         if (doH) {
;           float ss = 0.f;
; #pragma unroll
;           for (int i = 0; i < 4; ++i) ss += xv[i].x * xv[i].x + xv[i].y * xv[i].y + xv[i].z * xv[i].z + xv[i].w * xv[i].w;
;           ss = wave_sum(ss);
;           const float rstd = __builtin_amdgcn_rsqf(ss * (1.f / 1024.f) + EPSF);
;           u16* h = P.hy + (long)row * 1024;
; #pragma unroll
	v_and_b32_e32 v5, 0xffff0000, v10
	v_lshlrev_b32_e32 v6, 16, v11
	v_and_b32_e32 v7, 0xffff0000, v11
	v_lshlrev_b32_e32 v8, 16, v12
	v_and_b32_e32 v9, 0xffff0000, v12
	v_lshlrev_b32_e32 v10, 16, v13
	v_and_b32_e32 v11, 0xffff0000, v13
	v_lshlrev_b32_e32 v12, 16, v14
	v_and_b32_e32 v13, 0xffff0000, v14
	v_lshlrev_b32_e32 v14, 16, v15
	v_and_b32_e32 v15, 0xffff0000, v15
	s_nop 0
	v_mul_f32_e32 v120, v120, v140
	v_mul_f32_e32 v121, v121, v140
	v_mul_f32_e32 v122, v122, v140
	v_mul_f32_e32 v123, v123, v140
	v_mul_f32_e32 v124, v124, v140
	v_mul_f32_e32 v125, v125, v140
	v_mul_f32_e32 v126, v126, v140
	v_mul_f32_e32 v127, v127, v140
	v_mul_f32_e32 v128, v128, v140
	v_mul_f32_e32 v129, v129, v140
	v_mul_f32_e32 v130, v130, v140
	v_mul_f32_e32 v131, v131, v140
	v_mul_f32_e32 v132, v132, v140
	v_mul_f32_e32 v133, v133, v140
	v_mul_f32_e32 v134, v134, v140
	v_mul_f32_e32 v135, v135, v140
	v_fma_f32 v0, v120, v72, v0
	v_fma_f32 v1, v121, v73, v1
	v_fma_f32 v2, v122, v74, v2
	v_fma_f32 v3, v123, v75, v3
	v_fma_f32 v4, v124, v76, v4
	v_fma_f32 v5, v125, v77, v5
	v_fma_f32 v6, v126, v78, v6
	v_fma_f32 v7, v127, v79, v7
	v_fma_f32 v8, v128, v80, v8
	v_fma_f32 v9, v129, v81, v9
	v_fma_f32 v10, v130, v82, v10
	v_fma_f32 v11, v131, v83, v11
	v_fma_f32 v12, v132, v84, v12
	v_fma_f32 v13, v133, v85, v13
	v_fma_f32 v14, v134, v86, v14
	v_fma_f32 v15, v135, v87, v15
	v_cvt_pk_bf16_f32 v156, v0, v1
	v_cvt_pk_bf16_f32 v157, v2, v3
	v_cvt_pk_bf16_f32 v158, v4, v5
	v_cvt_pk_bf16_f32 v159, v6, v7
	v_cvt_pk_bf16_f32 v160, v8, v9
	v_cvt_pk_bf16_f32 v161, v10, v11
	v_cvt_pk_bf16_f32 v162, v12, v13
	v_cvt_pk_bf16_f32 v163, v14, v15
	s_lshl_b32 vcc_lo, s19, 11
	s_add_u32 vcc_lo, vcc_lo, 0x3c00000
	s_add_u32 s100, s16, vcc_lo
	s_addc_u32 s101, s17, 0
	global_store_dwordx2 v137, v[156:157], s[100:101] offset:0
	global_store_dwordx2 v137, v[158:159], s[100:101] offset:512
	global_store_dwordx2 v137, v[160:161], s[100:101] offset:1024
	global_store_dwordx2 v137, v[162:163], s[100:101] offset:1536
	v_mul_f32_e32 v138, v0, v0
	v_mul_f32_e32 v149, v1, v1
	v_mul_f32_e32 v150, v2, v2
	v_mul_f32_e32 v154, v3, v3
	v_fma_f32 v138, v4, v4, v138
	v_fma_f32 v149, v5, v5, v149
	v_fma_f32 v150, v6, v6, v150
	v_fma_f32 v154, v7, v7, v154
	v_fma_f32 v138, v8, v8, v138
	v_fma_f32 v149, v9, v9, v149
	v_fma_f32 v150, v10, v10, v150
	v_fma_f32 v154, v11, v11, v154
	v_fma_f32 v138, v12, v12, v138
	v_fma_f32 v149, v13, v13, v149
	v_fma_f32 v150, v14, v14, v150
	v_fma_f32 v154, v15, v15, v154
	v_add_f32_e32 v138, v138, v149
	v_add_f32_e32 v150, v150, v154
	v_add_f32_e32 v138, v138, v150
	s_nop 1
	v_add_f32_dpp v138, v138, v138 quad_perm:[1,0,3,2] row_mask:0xf bank_mask:0xf
	s_nop 1
	v_add_f32_dpp v138, v138, v138 quad_perm:[2,3,0,1] row_mask:0xf bank_mask:0xf
	s_nop 1
	v_add_f32_dpp v138, v138, v138 row_half_mirror row_mask:0xf bank_mask:0xf
	s_nop 1
	v_add_f32_dpp v138, v138, v138 row_mirror row_mask:0xf bank_mask:0xf
	v_mov_b32_e32 v139, v138
	s_nop 1
	v_permlane16_swap_b32_e32 v138, v139
	v_add_f32_e32 v138, v138, v139
	v_mov_b32_e32 v139, v138
	s_nop 1
	v_permlane32_swap_b32_e32 v138, v139
	v_add_f32_e32 v138, v138, v139
	v_mul_f32_e32 v138, 0x3a800000, v138
	v_add_f32_e32 v138, 0x358637bd, v138
	v_rsq_f32_e32 v140, v138
	s_nop 0
	v_mul_f32_e32 v120, v0, v140
	v_mul_f32_e32 v121, v1, v140
	v_mul_f32_e32 v122, v2, v140
	v_mul_f32_e32 v123, v3, v140
	v_mul_f32_e32 v124, v4, v140
	v_mul_f32_e32 v125, v5, v140
	v_mul_f32_e32 v126, v6, v140
	v_mul_f32_e32 v127, v7, v140
	v_mul_f32_e32 v128, v8, v140
	v_mul_f32_e32 v129, v9, v140
	v_mul_f32_e32 v130, v10, v140
	v_mul_f32_e32 v131, v11, v140
	v_mul_f32_e32 v132, v12, v140
	v_mul_f32_e32 v133, v13, v140
	v_mul_f32_e32 v134, v14, v140
	v_mul_f32_e32 v135, v15, v140
	v_fma_f32 v120, v120, v88, v104
	v_fma_f32 v121, v121, v89, v105
	v_fma_f32 v122, v122, v90, v106
	v_fma_f32 v123, v123, v91, v107
	v_fma_f32 v124, v124, v92, v108
	v_fma_f32 v125, v125, v93, v109
	v_fma_f32 v126, v126, v94, v110
	v_fma_f32 v127, v127, v95, v111
	v_fma_f32 v128, v128, v96, v112
	v_fma_f32 v129, v129, v97, v113
	v_fma_f32 v130, v130, v98, v114
	v_fma_f32 v131, v131, v99, v115
	v_fma_f32 v132, v132, v100, v116
	v_fma_f32 v133, v133, v101, v117
	v_fma_f32 v134, v134, v102, v118
	v_fma_f32 v135, v135, v103, v119
	v_cvt_pk_bf16_f32 v156, v120, v121
	v_cvt_pk_bf16_f32 v157, v122, v123
	v_cvt_pk_bf16_f32 v158, v124, v125
	v_cvt_pk_bf16_f32 v159, v126, v127
	v_cvt_pk_bf16_f32 v160, v128, v129
	v_cvt_pk_bf16_f32 v161, v130, v131
	v_cvt_pk_bf16_f32 v162, v132, v133
	v_cvt_pk_bf16_f32 v163, v134, v135
	s_lshl_b32 vcc_lo, s19, 11
	s_add_u32 vcc_lo, vcc_lo, 0x3c00000
	s_add_u32 s100, s14, vcc_lo
	s_addc_u32 s101, s15, 0
	global_store_dwordx2 v137, v[156:157], s[100:101] offset:0
	global_store_dwordx2 v137, v[158:159], s[100:101] offset:512
	global_store_dwordx2 v137, v[160:161], s[100:101] offset:1024
	global_store_dwordx2 v137, v[162:163], s[100:101] offset:1536
	s_waitcnt vmcnt(0)
	s_cmp_lt_u32 s19, 0x400
	s_cbranch_scc0 .Lmy_r10_done
; __device__ __forceinline__ void row_phase(const Params& P, int glayer, int layer, int xsrc, bool hasY, int gate_idx, const float* gpost,
;                           int xdst, bool doH, const float* gpre, int sh_idx, int nrows) {
;     ...
;           const float* xin_;
;           if (xsrc == 0) xin_ = R < N_X ? P.x + (long)R * 1024 : P.ctx + (long)(R - N_X) * 1024;
;           else           xin_ = P.xc + (long)(R - N_X) * 1024;
; #pragma unroll
;           for (int i = 0; i < 4; ++i) xr[u][i] = *reinterpret_cast<const uint4*>(xin_ + (i * 64 + lane) * 4);
;         }
;         if (hasY) {
;           const u16* y_ = P.hy + (long)R * 1024;
; #pragma unroll
;           for (int i = 0; i < 4; ++i) yy[u][i] = *reinterpret_cast<const uint2*>(y_ + (i * 64 + lane) * 4);
;     ...
; #pragma unroll
;           for (int i = 0; i < 4; ++i) {
;             const int col = (i * 64 + lane) * 4;
;             const float4 gt = *reinterpret_cast<const float4*>(modg + gate_idx * 1024 + col);
;             const float4 gp = *reinterpret_cast<const float4*>(gpost + col);
;             xv[i].x += gt.x * (yv[i].x * rstd * gp.x); xv[i].y += gt.y * (yv[i].y * rstd * gp.y);
;             xv[i].z += gt.z * (yv[i].z * rstd * gp.z); xv[i].w += gt.w * (yv[i].w * rstd * gp.w);
;           }
;         }
;         if (xdst == 3 || (xdst == 1 && row >= N_X)) {
;           float* xout = (xdst == 3) ? P.out + (long)row * 1024 : P.xc + (long)(row - N_X) * 1024;
; #pragma unroll
;           for (int i = 0; i < 4; ++i) *reinterpret_cast<float4*>(xout + (i * 64 + lane) * 4) = xv[i];
;         } else if (xdst != 0) {
;           u16* xo = ((xdst == 1) ? resA : P.zf) + (long)row * 1024;
; #pragma unroll
;           for (int i = 0; i < 4; ++i) {
;             const unsigned b0 = f2bf(xv[i].x), b1 = f2bf(xv[i].y), b2 = f2bf(xv[i].z), b3 = f2bf(xv[i].w);
;             *reinterpret_cast<uint2*>(xo + (i * 64 + lane) * 4) = make_uint2(b0 | (b1 << 16), b2 | (b3 << 16));
;           }
;         }
;         if (doH) {
;           float ss = 0.f;
; #pragma unroll
;           for (int i = 0; i < 4; ++i) ss += xv[i].x * xv[i].x + xv[i].y * xv[i].y + xv[i].z * xv[i].z + xv[i].w * xv[i].w;
;           ss = wave_sum(ss);
;           const float rstd = __builtin_amdgcn_rsqf(ss * (1.f / 1024.f) + EPSF);
;           u16* h = P.hy + (long)row * 1024;
; #pragma unroll
;           for (int i = 0; i < 4; ++i) {
	s_load_dwordx2 s[12:13], s[4:5], 0x138
	s_waitcnt lgkmcnt(0)
	s_add_u32 s100, s20, 0x1d000
	s_addc_u32 s101, s21, 0
	global_load_dwordx4 v[72:75], v136, s[100:101] offset:0
	global_load_dwordx4 v[76:79], v136, s[100:101] offset:1024
	global_load_dwordx4 v[80:83], v136, s[100:101] offset:2048
	global_load_dwordx4 v[84:87], v136, s[100:101] offset:3072
	s_load_dwordx2 s[98:99], s[4:5], 0x48
	s_waitcnt lgkmcnt(0)
	global_load_dwordx4 v[120:123], v136, s[98:99] offset:0
	global_load_dwordx4 v[124:127], v136, s[98:99] offset:1024
	global_load_dwordx4 v[128:131], v136, s[98:99] offset:2048
	global_load_dwordx4 v[132:135], v136, s[98:99] offset:3072
	s_add_u32 s100, s20, 0x36000
	s_addc_u32 s101, s21, 0
	global_load_dwordx4 v[104:107], v136, s[100:101] offset:0
	global_load_dwordx4 v[108:111], v136, s[100:101] offset:1024
	global_load_dwordx4 v[112:115], v136, s[100:101] offset:2048
	global_load_dwordx4 v[116:119], v136, s[100:101] offset:3072
	s_add_u32 s100, s100, 0x1000
	s_addc_u32 s101, s101, 0
	global_load_dwordx4 v[16:19], v136, s[100:101] offset:0
	global_load_dwordx4 v[20:23], v136, s[100:101] offset:1024
	global_load_dwordx4 v[24:27], v136, s[100:101] offset:2048
	global_load_dwordx4 v[28:31], v136, s[100:101] offset:3072
	s_load_dwordx2 s[98:99], s[4:5], 0x30
	s_waitcnt lgkmcnt(0)
	s_add_u32 s98, s98, 0x1000
	s_addc_u32 s99, s99, 0
	global_load_dwordx4 v[88:91], v136, s[98:99] offset:0
	global_load_dwordx4 v[92:95], v136, s[98:99] offset:1024
	global_load_dwordx4 v[96:99], v136, s[98:99] offset:2048
	global_load_dwordx4 v[100:103], v136, s[98:99] offset:3072
	s_waitcnt vmcnt(0)
	v_mul_f32_e32 v72, v72, v120
	v_mul_f32_e32 v73, v73, v121
	v_mul_f32_e32 v74, v74, v122
	v_mul_f32_e32 v75, v75, v123
	v_mul_f32_e32 v76, v76, v124
	v_mul_f32_e32 v77, v77, v125
	v_mul_f32_e32 v78, v78, v126
	v_mul_f32_e32 v79, v79, v127
	v_mul_f32_e32 v80, v80, v128
	v_mul_f32_e32 v81, v81, v129
	v_mul_f32_e32 v82, v82, v130
	v_mul_f32_e32 v83, v83, v131
	v_mul_f32_e32 v84, v84, v132
	v_mul_f32_e32 v85, v85, v133
	v_mul_f32_e32 v86, v86, v134
	v_mul_f32_e32 v87, v87, v135
	v_fma_f32 v88, v88, v16, v88
	v_fma_f32 v89, v89, v17, v89
	v_fma_f32 v90, v90, v18, v90
	v_fma_f32 v91, v91, v19, v91
	v_fma_f32 v92, v92, v20, v92
	v_fma_f32 v93, v93, v21, v93
	v_fma_f32 v94, v94, v22, v94
	v_fma_f32 v95, v95, v23, v95
	v_fma_f32 v96, v96, v24, v96
	v_fma_f32 v97, v97, v25, v97
	v_fma_f32 v98, v98, v26, v98
	v_fma_f32 v99, v99, v27, v99
	v_fma_f32 v100, v100, v28, v100
	v_fma_f32 v101, v101, v29, v101
	v_fma_f32 v102, v102, v30, v102
	v_fma_f32 v103, v103, v31, v103
	s_lshl_b32 vcc_lo, s19, 12
	s_add_u32 s100, s12, vcc_lo
	s_addc_u32 s101, s13, 0
	global_load_dwordx4 v[0:3], v136, s[100:101] offset:0
	global_load_dwordx4 v[4:7], v136, s[100:101] offset:1024
	global_load_dwordx4 v[8:11], v136, s[100:101] offset:2048
	global_load_dwordx4 v[12:15], v136, s[100:101] offset:3072
	s_lshl_b32 vcc_lo, s19, 11
	s_add_u32 vcc_lo, vcc_lo, 0x4000000
	s_add_u32 s100, s14, vcc_lo
	s_addc_u32 s101, s15, 0
	global_load_dwordx2 v[48:49], v137, s[100:101] offset:0
	global_load_dwordx2 v[50:51], v137, s[100:101] offset:512
	global_load_dwordx2 v[52:53], v137, s[100:101] offset:1024
	global_load_dwordx2 v[54:55], v137, s[100:101] offset:1536
	s_waitcnt vmcnt(0)
; __device__ __forceinline__ void row_phase(const Params& P, int glayer, int layer, int xsrc, bool hasY, int gate_idx, const float* gpost,
;                           int xdst, bool doH, const float* gpre, int sh_idx, int nrows) {
;     ...
;         if (hasY) {
;           float4 yv[4];
;           float ss = 0.f;
; #pragma unroll
;           for (int i = 0; i < 4; ++i) {
;             const uint2 raw = yy[u][i];
;             yv[i].x = bf2f((u16)(raw.x & 0xffff)); yv[i].y = bf2f((u16)(raw.x >> 16));
;             yv[i].z = bf2f((u16)(raw.y & 0xffff)); yv[i].w = bf2f((u16)(raw.y >> 16));
;             ss += yv[i].x * yv[i].x + yv[i].y * yv[i].y + yv[i].z * yv[i].z + yv[i].w * yv[i].w;
;           }
;           ss = wave_sum(ss);
;           const float rstd = __builtin_amdgcn_rsqf(ss * (1.f / 1024.f) + EPSF);
; #pragma unroll
;           for (int i = 0; i < 4; ++i) {
;             const int col = (i * 64 + lane) * 4;
;             const float4 gt = *reinterpret_cast<const float4*>(modg + gate_idx * 1024 + col);
;             const float4 gp = *reinterpret_cast<const float4*>(gpost + col);
;             xv[i].x += gt.x * (yv[i].x * rstd * gp.x); xv[i].y += gt.y * (yv[i].y * rstd * gp.y);
;             xv[i].z += gt.z * (yv[i].z * rstd * gp.z); xv[i].w += gt.w * (yv[i].w * rstd * gp.w);
;           }
;         }
;         if (xdst == 3 || (xdst == 1 && row >= N_X)) {
;           float* xout = (xdst == 3) ? P.out + (long)row * 1024 : P.xc + (long)(row - N_X) * 1024;
; #pragma unroll
;           for (int i = 0; i < 4; ++i) *reinterpret_cast<float4*>(xout + (i * 64 + lane) * 4) = xv[i];
;         } else if (xdst != 0) {
;           u16* xo = ((xdst == 1) ? resA : P.zf) + (long)row * 1024;
; #pragma unroll
;           for (int i = 0; i < 4; ++i) {
;             const unsigned b0 = f2bf(xv[i].x), b1 = f2bf(xv[i].y), b2 = f2bf(xv[i].z), b3 = f2bf(xv[i].w);
;             *reinterpret_cast<uint2*>(xo + (i * 64 + lane) * 4) = make_uint2(b0 | (b1 << 16), b2 | (b3 << 16));
;           }
;         }
;         if (doH) {
;           float ss = 0.f;
; #pragma unroll
;           for (int i = 0; i < 4; ++i) ss += xv[i].x * xv[i].x + xv[i].y * xv[i].y + xv[i].z * xv[i].z + xv[i].w * xv[i].w;
;           ss = wave_sum(ss);
;           const float rstd = __builtin_amdgcn_rsqf(ss * (1.f / 1024.f) + EPSF);
;           u16* h = P.hy + (long)row * 1024;
; #pragma unroll
	v_lshlrev_b32_e32 v120, 16, v48
	v_and_b32_e32 v121, 0xffff0000, v48
	v_lshlrev_b32_e32 v122, 16, v49
	v_and_b32_e32 v123, 0xffff0000, v49
	v_lshlrev_b32_e32 v124, 16, v50
	v_and_b32_e32 v125, 0xffff0000, v50
	v_lshlrev_b32_e32 v126, 16, v51
	v_and_b32_e32 v127, 0xffff0000, v51
	v_lshlrev_b32_e32 v128, 16, v52
	v_and_b32_e32 v129, 0xffff0000, v52
	v_lshlrev_b32_e32 v130, 16, v53
	v_and_b32_e32 v131, 0xffff0000, v53
	v_lshlrev_b32_e32 v132, 16, v54
	v_and_b32_e32 v133, 0xffff0000, v54
	v_lshlrev_b32_e32 v134, 16, v55
	v_and_b32_e32 v135, 0xffff0000, v55
	v_mul_f32_e32 v138, v120, v120
	v_mul_f32_e32 v149, v121, v121
	v_mul_f32_e32 v150, v122, v122
	v_mul_f32_e32 v154, v123, v123
	v_fma_f32 v138, v124, v124, v138
	v_fma_f32 v149, v125, v125, v149
	v_fma_f32 v150, v126, v126, v150
	v_fma_f32 v154, v127, v127, v154
	v_fma_f32 v138, v128, v128, v138
	v_fma_f32 v149, v129, v129, v149
	v_fma_f32 v150, v130, v130, v150
	v_fma_f32 v154, v131, v131, v154
	v_fma_f32 v138, v132, v132, v138
	v_fma_f32 v149, v133, v133, v149
	v_fma_f32 v150, v134, v134, v150
	v_fma_f32 v154, v135, v135, v154
	v_add_f32_e32 v138, v138, v149
	v_add_f32_e32 v150, v150, v154
	v_add_f32_e32 v138, v138, v150
	s_nop 1
	v_add_f32_dpp v138, v138, v138 quad_perm:[1,0,3,2] row_mask:0xf bank_mask:0xf
	s_nop 1
	v_add_f32_dpp v138, v138, v138 quad_perm:[2,3,0,1] row_mask:0xf bank_mask:0xf
	s_nop 1
	v_add_f32_dpp v138, v138, v138 row_half_mirror row_mask:0xf bank_mask:0xf
	s_nop 1
	v_add_f32_dpp v138, v138, v138 row_mirror row_mask:0xf bank_mask:0xf
	v_mov_b32_e32 v139, v138
	s_nop 1
	v_permlane16_swap_b32_e32 v138, v139
	v_add_f32_e32 v138, v138, v139
	v_mov_b32_e32 v139, v138
	s_nop 1
	v_permlane32_swap_b32_e32 v138, v139
	v_add_f32_e32 v138, v138, v139
	v_mul_f32_e32 v138, 0x3a800000, v138
	v_add_f32_e32 v138, 0x358637bd, v138
	v_rsq_f32_e32 v140, v138
	s_nop 0
	v_mul_f32_e32 v120, v120, v140
	v_mul_f32_e32 v121, v121, v140
	v_mul_f32_e32 v122, v122, v140
	v_mul_f32_e32 v123, v123, v140
	v_mul_f32_e32 v124, v124, v140
	v_mul_f32_e32 v125, v125, v140
	v_mul_f32_e32 v126, v126, v140
	v_mul_f32_e32 v127, v127, v140
	v_mul_f32_e32 v128, v128, v140
	v_mul_f32_e32 v129, v129, v140
	v_mul_f32_e32 v130, v130, v140
	v_mul_f32_e32 v131, v131, v140
	v_mul_f32_e32 v132, v132, v140
	v_mul_f32_e32 v133, v133, v140
	v_mul_f32_e32 v134, v134, v140
	v_mul_f32_e32 v135, v135, v140
	v_fma_f32 v0, v120, v72, v0
	v_fma_f32 v1, v121, v73, v1
	v_fma_f32 v2, v122, v74, v2
	v_fma_f32 v3, v123, v75, v3
	v_fma_f32 v4, v124, v76, v4
	v_fma_f32 v5, v125, v77, v5
	v_fma_f32 v6, v126, v78, v6
	v_fma_f32 v7, v127, v79, v7
	v_fma_f32 v8, v128, v80, v8
	v_fma_f32 v9, v129, v81, v9
	v_fma_f32 v10, v130, v82, v10
	v_fma_f32 v11, v131, v83, v11
	v_fma_f32 v12, v132, v84, v12
	v_fma_f32 v13, v133, v85, v13
	v_fma_f32 v14, v134, v86, v14
	v_fma_f32 v15, v135, v87, v15
	s_load_dwordx2 s[98:99], s[4:5], 0x138
	s_waitcnt lgkmcnt(0)
	s_lshl_b32 vcc_lo, s19, 12
	s_add_u32 s100, s98, vcc_lo
	s_addc_u32 s101, s99, 0
	global_store_dwordx4 v136, v[0:3], s[100:101] offset:0
	global_store_dwordx4 v136, v[4:7], s[100:101] offset:1024
	global_store_dwordx4 v136, v[8:11], s[100:101] offset:2048
	global_store_dwordx4 v136, v[12:15], s[100:101] offset:3072
	v_mul_f32_e32 v138, v0, v0
	v_mul_f32_e32 v149, v1, v1
	v_mul_f32_e32 v150, v2, v2
	v_mul_f32_e32 v154, v3, v3
	v_fma_f32 v138, v4, v4, v138
	v_fma_f32 v149, v5, v5, v149
	v_fma_f32 v150, v6, v6, v150
	v_fma_f32 v154, v7, v7, v154
	v_fma_f32 v138, v8, v8, v138
	v_fma_f32 v149, v9, v9, v149
	v_fma_f32 v150, v10, v10, v150
	v_fma_f32 v154, v11, v11, v154
	v_fma_f32 v138, v12, v12, v138
	v_fma_f32 v149, v13, v13, v149
	v_fma_f32 v150, v14, v14, v150
	v_fma_f32 v154, v15, v15, v154
	v_add_f32_e32 v138, v138, v149
	v_add_f32_e32 v150, v150, v154
	v_add_f32_e32 v138, v138, v150
	s_nop 1
	v_add_f32_dpp v138, v138, v138 quad_perm:[1,0,3,2] row_mask:0xf bank_mask:0xf
	s_nop 1
	v_add_f32_dpp v138, v138, v138 quad_perm:[2,3,0,1] row_mask:0xf bank_mask:0xf
	s_nop 1
	v_add_f32_dpp v138, v138, v138 row_half_mirror row_mask:0xf bank_mask:0xf
	s_nop 1
	v_add_f32_dpp v138, v138, v138 row_mirror row_mask:0xf bank_mask:0xf
	v_mov_b32_e32 v139, v138
	s_nop 1
	v_permlane16_swap_b32_e32 v138, v139
	v_add_f32_e32 v138, v138, v139
	v_mov_b32_e32 v139, v138
	s_nop 1
	v_permlane32_swap_b32_e32 v138, v139
	v_add_f32_e32 v138, v138, v139
	v_mul_f32_e32 v138, 0x3a800000, v138
	v_add_f32_e32 v138, 0x358637bd, v138
	v_rsq_f32_e32 v140, v138
	s_nop 0
	v_mul_f32_e32 v120, v0, v140
	v_mul_f32_e32 v121, v1, v140
	v_mul_f32_e32 v122, v2, v140
	v_mul_f32_e32 v123, v3, v140
	v_mul_f32_e32 v124, v4, v140
	v_mul_f32_e32 v125, v5, v140
	v_mul_f32_e32 v126, v6, v140
	v_mul_f32_e32 v127, v7, v140
	v_mul_f32_e32 v128, v8, v140
	v_mul_f32_e32 v129, v9, v140
	v_mul_f32_e32 v130, v10, v140
	v_mul_f32_e32 v131, v11, v140
	v_mul_f32_e32 v132, v12, v140
	v_mul_f32_e32 v133, v13, v140
	v_mul_f32_e32 v134, v14, v140
	v_mul_f32_e32 v135, v15, v140
	v_fma_f32 v120, v120, v88, v104
	v_fma_f32 v121, v121, v89, v105
	v_fma_f32 v122, v122, v90, v106
	v_fma_f32 v123, v123, v91, v107
	v_fma_f32 v124, v124, v92, v108
	v_fma_f32 v125, v125, v93, v109
	v_fma_f32 v126, v126, v94, v110
	v_fma_f32 v127, v127, v95, v111
	v_fma_f32 v128, v128, v96, v112
	v_fma_f32 v129, v129, v97, v113
	v_fma_f32 v130, v130, v98, v114
	v_fma_f32 v131, v131, v99, v115
	v_fma_f32 v132, v132, v100, v116
	v_fma_f32 v133, v133, v101, v117
	v_fma_f32 v134, v134, v102, v118
	v_fma_f32 v135, v135, v103, v119
	v_cvt_pk_bf16_f32 v156, v120, v121
	v_cvt_pk_bf16_f32 v157, v122, v123
	v_cvt_pk_bf16_f32 v158, v124, v125
	v_cvt_pk_bf16_f32 v159, v126, v127
	v_cvt_pk_bf16_f32 v160, v128, v129
	v_cvt_pk_bf16_f32 v161, v130, v131
	v_cvt_pk_bf16_f32 v162, v132, v133
	v_cvt_pk_bf16_f32 v163, v134, v135
	s_lshl_b32 vcc_lo, s19, 11
	s_add_u32 vcc_lo, vcc_lo, 0x4000000
	s_add_u32 s100, s14, vcc_lo
	s_addc_u32 s101, s15, 0
	global_store_dwordx2 v137, v[156:157], s[100:101] offset:0
	global_store_dwordx2 v137, v[158:159], s[100:101] offset:512
	global_store_dwordx2 v137, v[160:161], s[100:101] offset:1024
	global_store_dwordx2 v137, v[162:163], s[100:101] offset:1536

; __device__ __forceinline__ void row_phase(const Params& P, int glayer, int layer, int xsrc, bool hasY, int gate_idx, const float* gpost,
;                           int xdst, bool doH, const float* gpre, int sh_idx, int nrows) {
;   const int lane = threadIdx.x & 63, wid = threadIdx.x >> 6;
;   const int stride = gridDim.x * 8;
;   u16* resA = reinterpret_cast<u16*>(P.out);
;   for (int rb = blockIdx.x * 8 + wid; rb < nrows; rb += 4 * stride) {
;     uint4 xr[4][4];
;     uint2 yy[4][4];
; #pragma unroll
;     for (int u = 0; u < 4; ++u) {
;       const int R = rb + u * stride;
;       if (R < nrows) {
;         if (xsrc != 0 && R < N_X) {
;           const u16* xs_ = ((xsrc == 1) ? resA : P.zf) + (long)R * 1024;
; #pragma unroll
;           for (int i = 0; i < 4; ++i) {
;             const uint2 t2 = *reinterpret_cast<const uint2*>(xs_ + (i * 64 + lane) * 4);
;             xr[u][i].x = t2.x; xr[u][i].y = t2.y;
;           }
;         } else {
;           const float* xin_;
;           if (xsrc == 0) xin_ = R < N_X ? P.x + (long)R * 1024 : P.ctx + (long)(R - N_X) * 1024;
;           else           xin_ = P.xc + (long)(R - N_X) * 1024;
; #pragma unroll
;           for (int i = 0; i < 4; ++i) xr[u][i] = *reinterpret_cast<const uint4*>(xin_ + (i * 64 + lane) * 4);
;         }
;         if (hasY) {
;           const u16* y_ = P.hy + (long)R * 1024;
; #pragma unroll
;           for (int i = 0; i < 4; ++i) yy[u][i] = *reinterpret_cast<const uint2*>(y_ + (i * 64 + lane) * 4);
;         }
;     ...
;           for (int i = 0; i < 4; ++i) {
;             const int col = (i * 64 + lane) * 4;
;             const float4 gt = *reinterpret_cast<const float4*>(modg + gate_idx * 1024 + col);
;             const float4 gp = *reinterpret_cast<const float4*>(gpost + col);
;             xv[i].x += gt.x * (yv[i].x * rstd * gp.x); xv[i].y += gt.y * (yv[i].y * rstd * gp.y);
;             xv[i].z += gt.z * (yv[i].z * rstd * gp.z); xv[i].w += gt.w * (yv[i].w * rstd * gp.w);
;           }
;         }
;         if (xdst == 3 || (xdst == 1 && row >= N_X)) {
;           float* xout = (xdst == 3) ? P.out + (long)row * 1024 : P.xc + (long)(row - N_X) * 1024;
; #pragma unroll
;           for (int i = 0; i < 4; ++i) *reinterpret_cast<float4*>(xout + (i * 64 + lane) * 4) = xv[i];
;         } else if (xdst != 0) {
;           u16* xo = ((xdst == 1) ? resA : P.zf) + (long)row * 1024;
; #pragma unroll
.LBB0_1662:
	s_cmp_gt_i32 s34, 14
	s_cselect_b64 s[0:1], -1, 0
	s_cmp_lt_i32 s35, 15
	s_cselect_b64 s[4:5], -1, 0
	s_or_b64 s[0:1], s[0:1], s[4:5]
	s_and_b64 vcc, exec, s[0:1]
	s_cbranch_vccnz .LBB0_1732
	s_waitcnt vmcnt(16)
	v_mov_b32_e32 v0, v153
	s_mov_b32 s3, 0x8000
	v_lshl_add_u32 v0, s2, 3, v204
	v_cmp_gt_i32_e32 vcc, s3, v0
	s_and_saveexec_b64 s[6:7], vcc
	s_cbranch_execz .LBB0_1678
	v_readlane_b32 s4, v252, 0
	v_readlane_b32 s5, v252, 1
	v_readfirstlane_b32 s19, v204
	s_nop 3
	s_sub_u32 s4, s4, 0x170
	s_subb_u32 s5, s5, 0
	s_load_dwordx2 s[12:13], s[4:5], 0xc8
	s_load_dwordx2 s[14:15], s[4:5], 0x140
	s_load_dwordx2 s[16:17], s[4:5], 0x150
	s_load_dwordx2 s[20:21], s[4:5], 0x100
	s_lshl_b32 s98, s2, 3
	s_add_u32 s19, s98, s19
	v_and_b32_e32 v136, 63, v152
	v_lshlrev_b32_e32 v137, 3, v136
	v_lshlrev_b32_e32 v136, 4, v136
	s_waitcnt lgkmcnt(0)
	s_lshl_b32 vcc_lo, s19, 11
	s_add_u32 s100, s12, vcc_lo
	s_addc_u32 s101, s13, 0
	global_load_dwordx2 v[8:9], v137, s[100:101] offset:0
	global_load_dwordx2 v[10:11], v137, s[100:101] offset:512
	global_load_dwordx2 v[12:13], v137, s[100:101] offset:1024
	global_load_dwordx2 v[14:15], v137, s[100:101] offset:1536
	s_lshl_b32 vcc_lo, s19, 11
	s_add_u32 s100, s14, vcc_lo
	s_addc_u32 s101, s15, 0
	global_load_dwordx2 v[48:49], v137, s[100:101] offset:0
	global_load_dwordx2 v[50:51], v137, s[100:101] offset:512
	global_load_dwordx2 v[52:53], v137, s[100:101] offset:1024
	global_load_dwordx2 v[54:55], v137, s[100:101] offset:1536
	s_lshl_b32 vcc_lo, s19, 11
	s_add_u32 vcc_lo, vcc_lo, 0x400000
	s_add_u32 s100, s12, vcc_lo
	s_addc_u32 s101, s13, 0
	global_load_dwordx2 v[24:25], v137, s[100:101] offset:0
	global_load_dwordx2 v[26:27], v137, s[100:101] offset:512
	global_load_dwordx2 v[28:29], v137, s[100:101] offset:1024
	global_load_dwordx2 v[30:31], v137, s[100:101] offset:1536
	s_lshl_b32 vcc_lo, s19, 11
	s_add_u32 vcc_lo, vcc_lo, 0x400000
	s_add_u32 s100, s14, vcc_lo
	s_addc_u32 s101, s15, 0
	global_load_dwordx2 v[56:57], v137, s[100:101] offset:0
	global_load_dwordx2 v[58:59], v137, s[100:101] offset:512
	global_load_dwordx2 v[60:61], v137, s[100:101] offset:1024
	global_load_dwordx2 v[62:63], v137, s[100:101] offset:1536
	s_add_u32 s100, s20, 0x20000
	s_addc_u32 s101, s21, 0
	global_load_dwordx4 v[72:75], v136, s[100:101] offset:0
	global_load_dwordx4 v[76:79], v136, s[100:101] offset:1024
	global_load_dwordx4 v[80:83], v136, s[100:101] offset:2048
	global_load_dwordx4 v[84:87], v136, s[100:101] offset:3072
	s_load_dwordx2 s[98:99], s[4:5], 0x38
	s_waitcnt lgkmcnt(0)
	s_add_u32 s98, s98, 0x1000
	s_addc_u32 s99, s99, 0
	global_load_dwordx4 v[120:123], v136, s[98:99] offset:0
	global_load_dwordx4 v[124:127], v136, s[98:99] offset:1024
	global_load_dwordx4 v[128:131], v136, s[98:99] offset:2048
	global_load_dwordx4 v[132:135], v136, s[98:99] offset:3072
	s_add_u32 s100, s20, 0x21000
	s_addc_u32 s101, s21, 0
	global_load_dwordx4 v[104:107], v136, s[100:101] offset:0
	global_load_dwordx4 v[108:111], v136, s[100:101] offset:1024
	global_load_dwordx4 v[112:115], v136, s[100:101] offset:2048
	global_load_dwordx4 v[116:119], v136, s[100:101] offset:3072
	s_add_u32 s100, s100, 0x1000
	s_addc_u32 s101, s101, 0
	global_load_dwordx4 v[32:35], v136, s[100:101] offset:0
	global_load_dwordx4 v[36:39], v136, s[100:101] offset:1024
	global_load_dwordx4 v[40:43], v136, s[100:101] offset:2048
	global_load_dwordx4 v[44:47], v136, s[100:101] offset:3072
	s_load_dwordx2 s[98:99], s[4:5], 0x40
	s_waitcnt lgkmcnt(0)
	s_add_u32 s98, s98, 0x1000
	s_addc_u32 s99, s99, 0
	global_load_dwordx4 v[88:91], v136, s[98:99] offset:0
	global_load_dwordx4 v[92:95], v136, s[98:99] offset:1024
	global_load_dwordx4 v[96:99], v136, s[98:99] offset:2048
	global_load_dwordx4 v[100:103], v136, s[98:99] offset:3072
	s_waitcnt vmcnt(0)
	v_mul_f32_e32 v72, v72, v120
	v_mul_f32_e32 v73, v73, v121
	v_mul_f32_e32 v74, v74, v122
	v_mul_f32_e32 v75, v75, v123
	v_mul_f32_e32 v76, v76, v124
	v_mul_f32_e32 v77, v77, v125
	v_mul_f32_e32 v78, v78, v126
	v_mul_f32_e32 v79, v79, v127
	v_mul_f32_e32 v80, v80, v128
	v_mul_f32_e32 v81, v81, v129
	v_mul_f32_e32 v82, v82, v130
	v_mul_f32_e32 v83, v83, v131
	v_mul_f32_e32 v84, v84, v132
	v_mul_f32_e32 v85, v85, v133
	v_mul_f32_e32 v86, v86, v134
	v_mul_f32_e32 v87, v87, v135
	v_fma_f32 v88, v88, v32, v88
	v_fma_f32 v89, v89, v33, v89
	v_fma_f32 v90, v90, v34, v90
	v_fma_f32 v91, v91, v35, v91
	v_fma_f32 v92, v92, v36, v92
	v_fma_f32 v93, v93, v37, v93
	v_fma_f32 v94, v94, v38, v94
	v_fma_f32 v95, v95, v39, v95
	v_fma_f32 v96, v96, v40, v96
	v_fma_f32 v97, v97, v41, v97
	v_fma_f32 v98, v98, v42, v98
	v_fma_f32 v99, v99, v43, v99
	v_fma_f32 v100, v100, v44, v100
	v_fma_f32 v101, v101, v45, v101
	v_fma_f32 v102, v102, v46, v102
	v_fma_f32 v103, v103, v47, v103
	s_lshl_b32 vcc_lo, s19, 11
	s_add_u32 vcc_lo, vcc_lo, 0x800000
	s_add_u32 s100, s12, vcc_lo
	s_addc_u32 s101, s13, 0
	global_load_dwordx2 v[40:41], v137, s[100:101] offset:0
	global_load_dwordx2 v[42:43], v137, s[100:101] offset:512
	global_load_dwordx2 v[44:45], v137, s[100:101] offset:1024
	global_load_dwordx2 v[46:47], v137, s[100:101] offset:1536
	s_lshl_b32 vcc_lo, s19, 11
	s_add_u32 vcc_lo, vcc_lo, 0x800000
	s_add_u32 s100, s14, vcc_lo
	s_addc_u32 s101, s15, 0
	global_load_dwordx2 v[64:65], v137, s[100:101] offset:0
	global_load_dwordx2 v[66:67], v137, s[100:101] offset:512
	global_load_dwordx2 v[68:69], v137, s[100:101] offset:1024
	global_load_dwordx2 v[70:71], v137, s[100:101] offset:1536
	v_lshlrev_b32_e32 v120, 16, v48
	v_and_b32_e32 v121, 0xffff0000, v48
	v_lshlrev_b32_e32 v122, 16, v49
	v_and_b32_e32 v123, 0xffff0000, v49
	v_lshlrev_b32_e32 v124, 16, v50
; __device__ __forceinline__ void row_phase(const Params& P, int glayer, int layer, int xsrc, bool hasY, int gate_idx, const float* gpost,
;                           int xdst, bool doH, const float* gpre, int sh_idx, int nrows) {
;     ...
;         if (hasY) {
;           float4 yv[4];
;           float ss = 0.f;
; #pragma unroll
;           for (int i = 0; i < 4; ++i) {
;             const uint2 raw = yy[u][i];
;             yv[i].x = bf2f((u16)(raw.x & 0xffff)); yv[i].y = bf2f((u16)(raw.x >> 16));
;             yv[i].z = bf2f((u16)(raw.y & 0xffff)); yv[i].w = bf2f((u16)(raw.y >> 16));
;             ss += yv[i].x * yv[i].x + yv[i].y * yv[i].y + yv[i].z * yv[i].z + yv[i].w * yv[i].w;
;           }
;           ss = wave_sum(ss);
;           const float rstd = __builtin_amdgcn_rsqf(ss * (1.f / 1024.f) + EPSF);
; #pragma unroll
;           for (int i = 0; i < 4; ++i) {
;             const int col = (i * 64 + lane) * 4;
;             const float4 gt = *reinterpret_cast<const float4*>(modg + gate_idx * 1024 + col);
;             const float4 gp = *reinterpret_cast<const float4*>(gpost + col);
;             xv[i].x += gt.x * (yv[i].x * rstd * gp.x); xv[i].y += gt.y * (yv[i].y * rstd * gp.y);
;             xv[i].z += gt.z * (yv[i].z * rstd * gp.z); xv[i].w += gt.w * (yv[i].w * rstd * gp.w);
;           }
;         }
;         if (xdst == 3 || (xdst == 1 && row >= N_X)) {
;           float* xout = (xdst == 3) ? P.out + (long)row * 1024 : P.xc + (long)(row - N_X) * 1024;
; #pragma unroll
;           for (int i = 0; i < 4; ++i) *reinterpret_cast<float4*>(xout + (i * 64 + lane) * 4) = xv[i];
;         } else if (xdst != 0) {
;           u16* xo = ((xdst == 1) ? resA : P.zf) + (long)row * 1024;
; #pragma unroll
;           for (int i = 0; i < 4; ++i) {
;             const unsigned b0 = f2bf(xv[i].x), b1 = f2bf(xv[i].y), b2 = f2bf(xv[i].z), b3 = f2bf(xv[i].w);
;             *reinterpret_cast<uint2*>(xo + (i * 64 + lane) * 4) = make_uint2(b0 | (b1 << 16), b2 | (b3 << 16));
;           }
;         }
;         if (doH) {
;           float ss = 0.f;
; #pragma unroll
;           for (int i = 0; i < 4; ++i) ss += xv[i].x * xv[i].x + xv[i].y * xv[i].y + xv[i].z * xv[i].z + xv[i].w * xv[i].w;
;           ss = wave_sum(ss);
;           const float rstd = __builtin_amdgcn_rsqf(ss * (1.f / 1024.f) + EPSF);
;           u16* h = P.hy + (long)row * 1024;
; #pragma unroll
	v_and_b32_e32 v125, 0xffff0000, v50
	v_lshlrev_b32_e32 v126, 16, v51
	v_and_b32_e32 v127, 0xffff0000, v51
	v_lshlrev_b32_e32 v128, 16, v52
	v_and_b32_e32 v129, 0xffff0000, v52
	v_lshlrev_b32_e32 v130, 16, v53
	v_and_b32_e32 v131, 0xffff0000, v53
	v_lshlrev_b32_e32 v132, 16, v54
	v_and_b32_e32 v133, 0xffff0000, v54
	v_lshlrev_b32_e32 v134, 16, v55
	v_and_b32_e32 v135, 0xffff0000, v55
	v_mul_f32_e32 v138, v120, v120
	v_mul_f32_e32 v149, v121, v121
	v_mul_f32_e32 v150, v122, v122
	v_mul_f32_e32 v154, v123, v123
	v_fma_f32 v138, v124, v124, v138
	v_fma_f32 v149, v125, v125, v149
	v_fma_f32 v150, v126, v126, v150
	v_fma_f32 v154, v127, v127, v154
	v_fma_f32 v138, v128, v128, v138
	v_fma_f32 v149, v129, v129, v149
	v_fma_f32 v150, v130, v130, v150
	v_fma_f32 v154, v131, v131, v154
	v_fma_f32 v138, v132, v132, v138
	v_fma_f32 v149, v133, v133, v149
	v_fma_f32 v150, v134, v134, v150
	v_fma_f32 v154, v135, v135, v154
	v_add_f32_e32 v138, v138, v149
	v_add_f32_e32 v150, v150, v154
	v_add_f32_e32 v138, v138, v150
	s_nop 1
	v_add_f32_dpp v138, v138, v138 quad_perm:[1,0,3,2] row_mask:0xf bank_mask:0xf
	s_nop 1
	v_add_f32_dpp v138, v138, v138 quad_perm:[2,3,0,1] row_mask:0xf bank_mask:0xf
	s_nop 1
	v_add_f32_dpp v138, v138, v138 row_half_mirror row_mask:0xf bank_mask:0xf
	s_nop 1
	v_add_f32_dpp v138, v138, v138 row_mirror row_mask:0xf bank_mask:0xf
	v_mov_b32_e32 v139, v138
	s_nop 1
	v_permlane16_swap_b32_e32 v138, v139
	v_add_f32_e32 v138, v138, v139
	v_mov_b32_e32 v139, v138
	s_nop 1
	v_permlane32_swap_b32_e32 v138, v139
	v_add_f32_e32 v138, v138, v139
	v_mul_f32_e32 v138, 0x3a800000, v138
	v_add_f32_e32 v138, 0x358637bd, v138
	v_rsq_f32_e32 v140, v138
	v_lshlrev_b32_e32 v0, 16, v8
	v_and_b32_e32 v1, 0xffff0000, v8
	v_lshlrev_b32_e32 v2, 16, v9
	v_and_b32_e32 v3, 0xffff0000, v9
	v_lshlrev_b32_e32 v4, 16, v10
	v_and_b32_e32 v5, 0xffff0000, v10
	v_lshlrev_b32_e32 v6, 16, v11
	v_and_b32_e32 v7, 0xffff0000, v11
	v_lshlrev_b32_e32 v8, 16, v12
	v_and_b32_e32 v9, 0xffff0000, v12
	v_lshlrev_b32_e32 v10, 16, v13
	v_and_b32_e32 v11, 0xffff0000, v13
	v_lshlrev_b32_e32 v12, 16, v14
	v_and_b32_e32 v13, 0xffff0000, v14
	v_lshlrev_b32_e32 v14, 16, v15
	v_and_b32_e32 v15, 0xffff0000, v15
	s_nop 0
	v_mul_f32_e32 v120, v120, v140
	v_mul_f32_e32 v121, v121, v140
	v_mul_f32_e32 v122, v122, v140
	v_mul_f32_e32 v123, v123, v140
	v_mul_f32_e32 v124, v124, v140
	v_mul_f32_e32 v125, v125, v140
	v_mul_f32_e32 v126, v126, v140
	v_mul_f32_e32 v127, v127, v140
	v_mul_f32_e32 v128, v128, v140
	v_mul_f32_e32 v129, v129, v140
	v_mul_f32_e32 v130, v130, v140
	v_mul_f32_e32 v131, v131, v140
	v_mul_f32_e32 v132, v132, v140
	v_mul_f32_e32 v133, v133, v140
	v_mul_f32_e32 v134, v134, v140
	v_mul_f32_e32 v135, v135, v140
	v_fma_f32 v0, v120, v72, v0
	v_fma_f32 v1, v121, v73, v1
	v_fma_f32 v2, v122, v74, v2
	v_fma_f32 v3, v123, v75, v3
	v_fma_f32 v4, v124, v76, v4
	v_fma_f32 v5, v125, v77, v5
	v_fma_f32 v6, v126, v78, v6
	v_fma_f32 v7, v127, v79, v7
	v_fma_f32 v8, v128, v80, v8
	v_fma_f32 v9, v129, v81, v9
	v_fma_f32 v10, v130, v82, v10
	v_fma_f32 v11, v131, v83, v11
	v_fma_f32 v12, v132, v84, v12
	v_fma_f32 v13, v133, v85, v13
	v_fma_f32 v14, v134, v86, v14
	v_fma_f32 v15, v135, v87, v15
	v_cvt_pk_bf16_f32 v156, v0, v1
	v_cvt_pk_bf16_f32 v157, v2, v3
	v_cvt_pk_bf16_f32 v158, v4, v5
	v_cvt_pk_bf16_f32 v159, v6, v7
	v_cvt_pk_bf16_f32 v160, v8, v9
	v_cvt_pk_bf16_f32 v161, v10, v11
	v_cvt_pk_bf16_f32 v162, v12, v13
	v_cvt_pk_bf16_f32 v163, v14, v15
	s_lshl_b32 vcc_lo, s19, 11
	s_add_u32 s100, s16, vcc_lo
	s_addc_u32 s101, s17, 0
	global_store_dwordx2 v137, v[156:157], s[100:101] offset:0
	global_store_dwordx2 v137, v[158:159], s[100:101] offset:512
	global_store_dwordx2 v137, v[160:161], s[100:101] offset:1024
	global_store_dwordx2 v137, v[162:163], s[100:101] offset:1536
	v_mul_f32_e32 v138, v0, v0
	v_mul_f32_e32 v149, v1, v1
	v_mul_f32_e32 v150, v2, v2
	v_mul_f32_e32 v154, v3, v3
	v_fma_f32 v138, v4, v4, v138
	v_fma_f32 v149, v5, v5, v149
	v_fma_f32 v150, v6, v6, v150
	v_fma_f32 v154, v7, v7, v154
	v_fma_f32 v138, v8, v8, v138
	v_fma_f32 v149, v9, v9, v149
	v_fma_f32 v150, v10, v10, v150
	v_fma_f32 v154, v11, v11, v154
	v_fma_f32 v138, v12, v12, v138
	v_fma_f32 v149, v13, v13, v149
	v_fma_f32 v150, v14, v14, v150
	v_fma_f32 v154, v15, v15, v154
	v_add_f32_e32 v138, v138, v149
	v_add_f32_e32 v150, v150, v154
	v_add_f32_e32 v138, v138, v150
	s_nop 1
	v_add_f32_dpp v138, v138, v138 quad_perm:[1,0,3,2] row_mask:0xf bank_mask:0xf
	s_nop 1
	v_add_f32_dpp v138, v138, v138 quad_perm:[2,3,0,1] row_mask:0xf bank_mask:0xf
	s_nop 1
	v_add_f32_dpp v138, v138, v138 row_half_mirror row_mask:0xf bank_mask:0xf
	s_nop 1
	v_add_f32_dpp v138, v138, v138 row_mirror row_mask:0xf bank_mask:0xf
	v_mov_b32_e32 v139, v138
	s_nop 1
	v_permlane16_swap_b32_e32 v138, v139
	v_add_f32_e32 v138, v138, v139
	v_mov_b32_e32 v139, v138
	s_nop 1
	v_permlane32_swap_b32_e32 v138, v139
	v_add_f32_e32 v138, v138, v139
	v_mul_f32_e32 v138, 0x3a800000, v138
	v_add_f32_e32 v138, 0x358637bd, v138
	v_rsq_f32_e32 v140, v138
	s_nop 0
	v_mul_f32_e32 v120, v0, v140
	v_mul_f32_e32 v121, v1, v140
	v_mul_f32_e32 v122, v2, v140
	v_mul_f32_e32 v123, v3, v140
	v_mul_f32_e32 v124, v4, v140
	v_mul_f32_e32 v125, v5, v140
	v_mul_f32_e32 v126, v6, v140
	v_mul_f32_e32 v127, v7, v140
	v_mul_f32_e32 v128, v8, v140
	v_mul_f32_e32 v129, v9, v140
	v_mul_f32_e32 v130, v10, v140
	v_mul_f32_e32 v131, v11, v140
	v_mul_f32_e32 v132, v12, v140
	v_mul_f32_e32 v133, v13, v140
	v_mul_f32_e32 v134, v14, v140
	v_mul_f32_e32 v135, v15, v140
	v_fma_f32 v120, v120, v88, v104
	v_fma_f32 v121, v121, v89, v105
	v_fma_f32 v122, v122, v90, v106
	v_fma_f32 v123, v123, v91, v107
; __device__ __forceinline__ void row_phase(const Params& P, int glayer, int layer, int xsrc, bool hasY, int gate_idx, const float* gpost,
;                           int xdst, bool doH, const float* gpre, int sh_idx, int nrows) {
;     ...
;         if (hasY) {
;           float4 yv[4];
;           float ss = 0.f;
; #pragma unroll
;           for (int i = 0; i < 4; ++i) {
;             const uint2 raw = yy[u][i];
;             yv[i].x = bf2f((u16)(raw.x & 0xffff)); yv[i].y = bf2f((u16)(raw.x >> 16));
;             yv[i].z = bf2f((u16)(raw.y & 0xffff)); yv[i].w = bf2f((u16)(raw.y >> 16));
;             ss += yv[i].x * yv[i].x + yv[i].y * yv[i].y + yv[i].z * yv[i].z + yv[i].w * yv[i].w;
;           }
;           ss = wave_sum(ss);
;           const float rstd = __builtin_amdgcn_rsqf(ss * (1.f / 1024.f) + EPSF);
; #pragma unroll
;           for (int i = 0; i < 4; ++i) {
;             const int col = (i * 64 + lane) * 4;
;             const float4 gt = *reinterpret_cast<const float4*>(modg + gate_idx * 1024 + col);
;             const float4 gp = *reinterpret_cast<const float4*>(gpost + col);
;             xv[i].x += gt.x * (yv[i].x * rstd * gp.x); xv[i].y += gt.y * (yv[i].y * rstd * gp.y);
;             xv[i].z += gt.z * (yv[i].z * rstd * gp.z); xv[i].w += gt.w * (yv[i].w * rstd * gp.w);
;           }
;         }
;         if (xdst == 3 || (xdst == 1 && row >= N_X)) {
;           float* xout = (xdst == 3) ? P.out + (long)row * 1024 : P.xc + (long)(row - N_X) * 1024;
; #pragma unroll
;           for (int i = 0; i < 4; ++i) *reinterpret_cast<float4*>(xout + (i * 64 + lane) * 4) = xv[i];
;         } else if (xdst != 0) {
;           u16* xo = ((xdst == 1) ? resA : P.zf) + (long)row * 1024;
; #pragma unroll
;           for (int i = 0; i < 4; ++i) {
;             const unsigned b0 = f2bf(xv[i].x), b1 = f2bf(xv[i].y), b2 = f2bf(xv[i].z), b3 = f2bf(xv[i].w);
;             *reinterpret_cast<uint2*>(xo + (i * 64 + lane) * 4) = make_uint2(b0 | (b1 << 16), b2 | (b3 << 16));
;           }
;         }
;         if (doH) {
;           float ss = 0.f;
; #pragma unroll
;           for (int i = 0; i < 4; ++i) ss += xv[i].x * xv[i].x + xv[i].y * xv[i].y + xv[i].z * xv[i].z + xv[i].w * xv[i].w;
;           ss = wave_sum(ss);
;           const float rstd = __builtin_amdgcn_rsqf(ss * (1.f / 1024.f) + EPSF);
;           u16* h = P.hy + (long)row * 1024;
; #pragma unroll
	v_fma_f32 v124, v124, v92, v108
	v_fma_f32 v125, v125, v93, v109
	v_fma_f32 v126, v126, v94, v110
	v_fma_f32 v127, v127, v95, v111
	v_fma_f32 v128, v128, v96, v112
	v_fma_f32 v129, v129, v97, v113
	v_fma_f32 v130, v130, v98, v114
	v_fma_f32 v131, v131, v99, v115
	v_fma_f32 v132, v132, v100, v116
	v_fma_f32 v133, v133, v101, v117
	v_fma_f32 v134, v134, v102, v118
	v_fma_f32 v135, v135, v103, v119
	v_cvt_pk_bf16_f32 v156, v120, v121
	v_cvt_pk_bf16_f32 v157, v122, v123
	v_cvt_pk_bf16_f32 v158, v124, v125
	v_cvt_pk_bf16_f32 v159, v126, v127
	v_cvt_pk_bf16_f32 v160, v128, v129
	v_cvt_pk_bf16_f32 v161, v130, v131
	v_cvt_pk_bf16_f32 v162, v132, v133
	v_cvt_pk_bf16_f32 v163, v134, v135
	s_lshl_b32 vcc_lo, s19, 11
	s_add_u32 s100, s14, vcc_lo
	s_addc_u32 s101, s15, 0
	global_store_dwordx2 v137, v[156:157], s[100:101] offset:0
	global_store_dwordx2 v137, v[158:159], s[100:101] offset:512
	global_store_dwordx2 v137, v[160:161], s[100:101] offset:1024
	global_store_dwordx2 v137, v[162:163], s[100:101] offset:1536
	s_lshl_b32 vcc_lo, s19, 11
	s_add_u32 vcc_lo, vcc_lo, 0xc00000
	s_add_u32 s100, s12, vcc_lo
	s_addc_u32 s101, s13, 0
	global_load_dwordx2 v[8:9], v137, s[100:101] offset:0
	global_load_dwordx2 v[10:11], v137, s[100:101] offset:512
	global_load_dwordx2 v[12:13], v137, s[100:101] offset:1024
	global_load_dwordx2 v[14:15], v137, s[100:101] offset:1536
	s_lshl_b32 vcc_lo, s19, 11
	s_add_u32 vcc_lo, vcc_lo, 0xc00000
	s_add_u32 s100, s14, vcc_lo
	s_addc_u32 s101, s15, 0
	global_load_dwordx2 v[48:49], v137, s[100:101] offset:0
	global_load_dwordx2 v[50:51], v137, s[100:101] offset:512
	global_load_dwordx2 v[52:53], v137, s[100:101] offset:1024
	global_load_dwordx2 v[54:55], v137, s[100:101] offset:1536
	v_lshlrev_b32_e32 v120, 16, v56
	v_and_b32_e32 v121, 0xffff0000, v56
	v_lshlrev_b32_e32 v122, 16, v57
	v_and_b32_e32 v123, 0xffff0000, v57
	v_lshlrev_b32_e32 v124, 16, v58
	v_and_b32_e32 v125, 0xffff0000, v58
	v_lshlrev_b32_e32 v126, 16, v59
	v_and_b32_e32 v127, 0xffff0000, v59
	v_lshlrev_b32_e32 v128, 16, v60
	v_and_b32_e32 v129, 0xffff0000, v60
	v_lshlrev_b32_e32 v130, 16, v61
	v_and_b32_e32 v131, 0xffff0000, v61
	v_lshlrev_b32_e32 v132, 16, v62
	v_and_b32_e32 v133, 0xffff0000, v62
	v_lshlrev_b32_e32 v134, 16, v63
	v_and_b32_e32 v135, 0xffff0000, v63
	v_mul_f32_e32 v138, v120, v120
	v_mul_f32_e32 v149, v121, v121
	v_mul_f32_e32 v150, v122, v122
	v_mul_f32_e32 v154, v123, v123
	v_fma_f32 v138, v124, v124, v138
	v_fma_f32 v149, v125, v125, v149
	v_fma_f32 v150, v126, v126, v150
	v_fma_f32 v154, v127, v127, v154
	v_fma_f32 v138, v128, v128, v138
	v_fma_f32 v149, v129, v129, v149
	v_fma_f32 v150, v130, v130, v150
	v_fma_f32 v154, v131, v131, v154
	v_fma_f32 v138, v132, v132, v138
	v_fma_f32 v149, v133, v133, v149
	v_fma_f32 v150, v134, v134, v150
	v_fma_f32 v154, v135, v135, v154
	v_add_f32_e32 v138, v138, v149
	v_add_f32_e32 v150, v150, v154
	v_add_f32_e32 v138, v138, v150
	s_nop 1
	v_add_f32_dpp v138, v138, v138 quad_perm:[1,0,3,2] row_mask:0xf bank_mask:0xf
	s_nop 1
	v_add_f32_dpp v138, v138, v138 quad_perm:[2,3,0,1] row_mask:0xf bank_mask:0xf
	s_nop 1
	v_add_f32_dpp v138, v138, v138 row_half_mirror row_mask:0xf bank_mask:0xf
	s_nop 1
	v_add_f32_dpp v138, v138, v138 row_mirror row_mask:0xf bank_mask:0xf
	v_mov_b32_e32 v139, v138
	s_nop 1
	v_permlane16_swap_b32_e32 v138, v139
	v_add_f32_e32 v138, v138, v139
	v_mov_b32_e32 v139, v138
	s_nop 1
	v_permlane32_swap_b32_e32 v138, v139
	v_add_f32_e32 v138, v138, v139
	v_mul_f32_e32 v138, 0x3a800000, v138
	v_add_f32_e32 v138, 0x358637bd, v138
	v_rsq_f32_e32 v140, v138
	v_lshlrev_b32_e32 v16, 16, v24
	v_and_b32_e32 v17, 0xffff0000, v24
	v_lshlrev_b32_e32 v18, 16, v25
	v_and_b32_e32 v19, 0xffff0000, v25
	v_lshlrev_b32_e32 v20, 16, v26
	v_and_b32_e32 v21, 0xffff0000, v26
	v_lshlrev_b32_e32 v22, 16, v27
	v_and_b32_e32 v23, 0xffff0000, v27
	v_lshlrev_b32_e32 v24, 16, v28
	v_and_b32_e32 v25, 0xffff0000, v28
	v_lshlrev_b32_e32 v26, 16, v29
	v_and_b32_e32 v27, 0xffff0000, v29
	v_lshlrev_b32_e32 v28, 16, v30
	v_and_b32_e32 v29, 0xffff0000, v30
	v_lshlrev_b32_e32 v30, 16, v31
	v_and_b32_e32 v31, 0xffff0000, v31
	s_nop 0
	v_mul_f32_e32 v120, v120, v140
	v_mul_f32_e32 v121, v121, v140
	v_mul_f32_e32 v122, v122, v140
	v_mul_f32_e32 v123, v123, v140
	v_mul_f32_e32 v124, v124, v140
	v_mul_f32_e32 v125, v125, v140
	v_mul_f32_e32 v126, v126, v140
	v_mul_f32_e32 v127, v127, v140
	v_mul_f32_e32 v128, v128, v140
	v_mul_f32_e32 v129, v129, v140
	v_mul_f32_e32 v130, v130, v140
	v_mul_f32_e32 v131, v131, v140
	v_mul_f32_e32 v132, v132, v140
	v_mul_f32_e32 v133, v133, v140
	v_mul_f32_e32 v134, v134, v140
	v_mul_f32_e32 v135, v135, v140
	v_fma_f32 v16, v120, v72, v16
	v_fma_f32 v17, v121, v73, v17
	v_fma_f32 v18, v122, v74, v18
	v_fma_f32 v19, v123, v75, v19
	v_fma_f32 v20, v124, v76, v20
	v_fma_f32 v21, v125, v77, v21
	v_fma_f32 v22, v126, v78, v22
	v_fma_f32 v23, v127, v79, v23
	v_fma_f32 v24, v128, v80, v24
	v_fma_f32 v25, v129, v81, v25
	v_fma_f32 v26, v130, v82, v26
	v_fma_f32 v27, v131, v83, v27
	v_fma_f32 v28, v132, v84, v28
	v_fma_f32 v29, v133, v85, v29
	v_fma_f32 v30, v134, v86, v30
	v_fma_f32 v31, v135, v87, v31
	v_cvt_pk_bf16_f32 v156, v16, v17
	v_cvt_pk_bf16_f32 v157, v18, v19
	v_cvt_pk_bf16_f32 v158, v20, v21
	v_cvt_pk_bf16_f32 v159, v22, v23
	v_cvt_pk_bf16_f32 v160, v24, v25
	v_cvt_pk_bf16_f32 v161, v26, v27
	v_cvt_pk_bf16_f32 v162, v28, v29
	v_cvt_pk_bf16_f32 v163, v30, v31
	s_lshl_b32 vcc_lo, s19, 11
	s_add_u32 vcc_lo, vcc_lo, 0x400000
	s_add_u32 s100, s16, vcc_lo
	s_addc_u32 s101, s17, 0
	global_store_dwordx2 v137, v[156:157], s[100:101] offset:0
	global_store_dwordx2 v137, v[158:159], s[100:101] offset:512
; __device__ __forceinline__ void row_phase(const Params& P, int glayer, int layer, int xsrc, bool hasY, int gate_idx, const float* gpost,
;                           int xdst, bool doH, const float* gpre, int sh_idx, int nrows) {
;     ...
;         if (hasY) {
;           float4 yv[4];
;           float ss = 0.f;
; #pragma unroll
;           for (int i = 0; i < 4; ++i) {
;             const uint2 raw = yy[u][i];
;             yv[i].x = bf2f((u16)(raw.x & 0xffff)); yv[i].y = bf2f((u16)(raw.x >> 16));
;             yv[i].z = bf2f((u16)(raw.y & 0xffff)); yv[i].w = bf2f((u16)(raw.y >> 16));
;             ss += yv[i].x * yv[i].x + yv[i].y * yv[i].y + yv[i].z * yv[i].z + yv[i].w * yv[i].w;
;           }
;           ss = wave_sum(ss);
;           const float rstd = __builtin_amdgcn_rsqf(ss * (1.f / 1024.f) + EPSF);
; #pragma unroll
;           for (int i = 0; i < 4; ++i) {
;             const int col = (i * 64 + lane) * 4;
;             const float4 gt = *reinterpret_cast<const float4*>(modg + gate_idx * 1024 + col);
;             const float4 gp = *reinterpret_cast<const float4*>(gpost + col);
;             xv[i].x += gt.x * (yv[i].x * rstd * gp.x); xv[i].y += gt.y * (yv[i].y * rstd * gp.y);
;             xv[i].z += gt.z * (yv[i].z * rstd * gp.z); xv[i].w += gt.w * (yv[i].w * rstd * gp.w);
;           }
;         }
;         if (xdst == 3 || (xdst == 1 && row >= N_X)) {
;           float* xout = (xdst == 3) ? P.out + (long)row * 1024 : P.xc + (long)(row - N_X) * 1024;
; #pragma unroll
;           for (int i = 0; i < 4; ++i) *reinterpret_cast<float4*>(xout + (i * 64 + lane) * 4) = xv[i];
;         } else if (xdst != 0) {
;           u16* xo = ((xdst == 1) ? resA : P.zf) + (long)row * 1024;
; #pragma unroll
;           for (int i = 0; i < 4; ++i) {
;             const unsigned b0 = f2bf(xv[i].x), b1 = f2bf(xv[i].y), b2 = f2bf(xv[i].z), b3 = f2bf(xv[i].w);
;             *reinterpret_cast<uint2*>(xo + (i * 64 + lane) * 4) = make_uint2(b0 | (b1 << 16), b2 | (b3 << 16));
;           }
;         }
;         if (doH) {
;           float ss = 0.f;
; #pragma unroll
;           for (int i = 0; i < 4; ++i) ss += xv[i].x * xv[i].x + xv[i].y * xv[i].y + xv[i].z * xv[i].z + xv[i].w * xv[i].w;
;           ss = wave_sum(ss);
;           const float rstd = __builtin_amdgcn_rsqf(ss * (1.f / 1024.f) + EPSF);
;           u16* h = P.hy + (long)row * 1024;
; #pragma unroll
	global_store_dwordx2 v137, v[160:161], s[100:101] offset:1024
	global_store_dwordx2 v137, v[162:163], s[100:101] offset:1536
	v_mul_f32_e32 v138, v16, v16
	v_mul_f32_e32 v149, v17, v17
	v_mul_f32_e32 v150, v18, v18
	v_mul_f32_e32 v154, v19, v19
	v_fma_f32 v138, v20, v20, v138
	v_fma_f32 v149, v21, v21, v149
	v_fma_f32 v150, v22, v22, v150
	v_fma_f32 v154, v23, v23, v154
	v_fma_f32 v138, v24, v24, v138
	v_fma_f32 v149, v25, v25, v149
	v_fma_f32 v150, v26, v26, v150
	v_fma_f32 v154, v27, v27, v154
	v_fma_f32 v138, v28, v28, v138
	v_fma_f32 v149, v29, v29, v149
	v_fma_f32 v150, v30, v30, v150
	v_fma_f32 v154, v31, v31, v154
	v_add_f32_e32 v138, v138, v149
	v_add_f32_e32 v150, v150, v154
	v_add_f32_e32 v138, v138, v150
	s_nop 1
	v_add_f32_dpp v138, v138, v138 quad_perm:[1,0,3,2] row_mask:0xf bank_mask:0xf
	s_nop 1
	v_add_f32_dpp v138, v138, v138 quad_perm:[2,3,0,1] row_mask:0xf bank_mask:0xf
	s_nop 1
	v_add_f32_dpp v138, v138, v138 row_half_mirror row_mask:0xf bank_mask:0xf
	s_nop 1
	v_add_f32_dpp v138, v138, v138 row_mirror row_mask:0xf bank_mask:0xf
	v_mov_b32_e32 v139, v138
	s_nop 1
	v_permlane16_swap_b32_e32 v138, v139
	v_add_f32_e32 v138, v138, v139
	v_mov_b32_e32 v139, v138
	s_nop 1
	v_permlane32_swap_b32_e32 v138, v139
	v_add_f32_e32 v138, v138, v139
	v_mul_f32_e32 v138, 0x3a800000, v138
	v_add_f32_e32 v138, 0x358637bd, v138
	v_rsq_f32_e32 v140, v138
	s_nop 0
	v_mul_f32_e32 v120, v16, v140
	v_mul_f32_e32 v121, v17, v140
	v_mul_f32_e32 v122, v18, v140
	v_mul_f32_e32 v123, v19, v140
	v_mul_f32_e32 v124, v20, v140
	v_mul_f32_e32 v125, v21, v140
	v_mul_f32_e32 v126, v22, v140
	v_mul_f32_e32 v127, v23, v140
	v_mul_f32_e32 v128, v24, v140
	v_mul_f32_e32 v129, v25, v140
	v_mul_f32_e32 v130, v26, v140
	v_mul_f32_e32 v131, v27, v140
	v_mul_f32_e32 v132, v28, v140
	v_mul_f32_e32 v133, v29, v140
	v_mul_f32_e32 v134, v30, v140
	v_mul_f32_e32 v135, v31, v140
	v_fma_f32 v120, v120, v88, v104
	v_fma_f32 v121, v121, v89, v105
	v_fma_f32 v122, v122, v90, v106
	v_fma_f32 v123, v123, v91, v107
	v_fma_f32 v124, v124, v92, v108
	v_fma_f32 v125, v125, v93, v109
	v_fma_f32 v126, v126, v94, v110
	v_fma_f32 v127, v127, v95, v111
	v_fma_f32 v128, v128, v96, v112
	v_fma_f32 v129, v129, v97, v113
	v_fma_f32 v130, v130, v98, v114
	v_fma_f32 v131, v131, v99, v115
	v_fma_f32 v132, v132, v100, v116
	v_fma_f32 v133, v133, v101, v117
	v_fma_f32 v134, v134, v102, v118
	v_fma_f32 v135, v135, v103, v119
	v_cvt_pk_bf16_f32 v156, v120, v121
	v_cvt_pk_bf16_f32 v157, v122, v123
	v_cvt_pk_bf16_f32 v158, v124, v125
	v_cvt_pk_bf16_f32 v159, v126, v127
	v_cvt_pk_bf16_f32 v160, v128, v129
	v_cvt_pk_bf16_f32 v161, v130, v131
	v_cvt_pk_bf16_f32 v162, v132, v133
	v_cvt_pk_bf16_f32 v163, v134, v135
	s_lshl_b32 vcc_lo, s19, 11
	s_add_u32 vcc_lo, vcc_lo, 0x400000
	s_add_u32 s100, s14, vcc_lo
	s_addc_u32 s101, s15, 0
	global_store_dwordx2 v137, v[156:157], s[100:101] offset:0
	global_store_dwordx2 v137, v[158:159], s[100:101] offset:512
	global_store_dwordx2 v137, v[160:161], s[100:101] offset:1024
	global_store_dwordx2 v137, v[162:163], s[100:101] offset:1536
	s_lshl_b32 vcc_lo, s19, 11
	s_add_u32 vcc_lo, vcc_lo, 0x1000000
	s_add_u32 s100, s12, vcc_lo
	s_addc_u32 s101, s13, 0
	global_load_dwordx2 v[24:25], v137, s[100:101] offset:0
	global_load_dwordx2 v[26:27], v137, s[100:101] offset:512
	global_load_dwordx2 v[28:29], v137, s[100:101] offset:1024
	global_load_dwordx2 v[30:31], v137, s[100:101] offset:1536
	s_lshl_b32 vcc_lo, s19, 11
	s_add_u32 vcc_lo, vcc_lo, 0x1000000
	s_add_u32 s100, s14, vcc_lo
	s_addc_u32 s101, s15, 0
	global_load_dwordx2 v[56:57], v137, s[100:101] offset:0
	global_load_dwordx2 v[58:59], v137, s[100:101] offset:512
	global_load_dwordx2 v[60:61], v137, s[100:101] offset:1024
	global_load_dwordx2 v[62:63], v137, s[100:101] offset:1536
	s_waitcnt vmcnt(32)
	v_lshlrev_b32_e32 v120, 16, v64
	v_and_b32_e32 v121, 0xffff0000, v64
	v_lshlrev_b32_e32 v122, 16, v65
	v_and_b32_e32 v123, 0xffff0000, v65
	v_lshlrev_b32_e32 v124, 16, v66
	v_and_b32_e32 v125, 0xffff0000, v66
	v_lshlrev_b32_e32 v126, 16, v67
	v_and_b32_e32 v127, 0xffff0000, v67
	v_lshlrev_b32_e32 v128, 16, v68
	v_and_b32_e32 v129, 0xffff0000, v68
	v_lshlrev_b32_e32 v130, 16, v69
	v_and_b32_e32 v131, 0xffff0000, v69
	v_lshlrev_b32_e32 v132, 16, v70
	v_and_b32_e32 v133, 0xffff0000, v70
	v_lshlrev_b32_e32 v134, 16, v71
	v_and_b32_e32 v135, 0xffff0000, v71
	v_mul_f32_e32 v138, v120, v120
	v_mul_f32_e32 v149, v121, v121
	v_mul_f32_e32 v150, v122, v122
	v_mul_f32_e32 v154, v123, v123
	v_fma_f32 v138, v124, v124, v138
	v_fma_f32 v149, v125, v125, v149
	v_fma_f32 v150, v126, v126, v150
	v_fma_f32 v154, v127, v127, v154
	v_fma_f32 v138, v128, v128, v138
	v_fma_f32 v149, v129, v129, v149
	v_fma_f32 v150, v130, v130, v150
	v_fma_f32 v154, v131, v131, v154
	v_fma_f32 v138, v132, v132, v138
	v_fma_f32 v149, v133, v133, v149
	v_fma_f32 v150, v134, v134, v150
	v_fma_f32 v154, v135, v135, v154
	v_add_f32_e32 v138, v138, v149
	v_add_f32_e32 v150, v150, v154
	v_add_f32_e32 v138, v138, v150
	s_nop 1
	v_add_f32_dpp v138, v138, v138 quad_perm:[1,0,3,2] row_mask:0xf bank_mask:0xf
	s_nop 1
	v_add_f32_dpp v138, v138, v138 quad_perm:[2,3,0,1] row_mask:0xf bank_mask:0xf
	s_nop 1
	v_add_f32_dpp v138, v138, v138 row_half_mirror row_mask:0xf bank_mask:0xf
	s_nop 1
	v_add_f32_dpp v138, v138, v138 row_mirror row_mask:0xf bank_mask:0xf
	v_mov_b32_e32 v139, v138
	s_nop 1
	v_permlane16_swap_b32_e32 v138, v139
	v_add_f32_e32 v138, v138, v139
	v_mov_b32_e32 v139, v138
	s_nop 1
	v_permlane32_swap_b32_e32 v138, v139
	v_add_f32_e32 v138, v138, v139
	v_mul_f32_e32 v138, 0x3a800000, v138
	v_add_f32_e32 v138, 0x358637bd, v138
	v_rsq_f32_e32 v140, v138
; __device__ __forceinline__ void row_phase(const Params& P, int glayer, int layer, int xsrc, bool hasY, int gate_idx, const float* gpost,
;                           int xdst, bool doH, const float* gpre, int sh_idx, int nrows) {
;     ...
;         if (hasY) {
;           float4 yv[4];
;           float ss = 0.f;
; #pragma unroll
;           for (int i = 0; i < 4; ++i) {
;             const uint2 raw = yy[u][i];
;             yv[i].x = bf2f((u16)(raw.x & 0xffff)); yv[i].y = bf2f((u16)(raw.x >> 16));
;             yv[i].z = bf2f((u16)(raw.y & 0xffff)); yv[i].w = bf2f((u16)(raw.y >> 16));
;             ss += yv[i].x * yv[i].x + yv[i].y * yv[i].y + yv[i].z * yv[i].z + yv[i].w * yv[i].w;
;           }
;           ss = wave_sum(ss);
;           const float rstd = __builtin_amdgcn_rsqf(ss * (1.f / 1024.f) + EPSF);
; #pragma unroll
;           for (int i = 0; i < 4; ++i) {
;             const int col = (i * 64 + lane) * 4;
;             const float4 gt = *reinterpret_cast<const float4*>(modg + gate_idx * 1024 + col);
;             const float4 gp = *reinterpret_cast<const float4*>(gpost + col);
;             xv[i].x += gt.x * (yv[i].x * rstd * gp.x); xv[i].y += gt.y * (yv[i].y * rstd * gp.y);
;             xv[i].z += gt.z * (yv[i].z * rstd * gp.z); xv[i].w += gt.w * (yv[i].w * rstd * gp.w);
;           }
;         }
;         if (xdst == 3 || (xdst == 1 && row >= N_X)) {
;           float* xout = (xdst == 3) ? P.out + (long)row * 1024 : P.xc + (long)(row - N_X) * 1024;
; #pragma unroll
;           for (int i = 0; i < 4; ++i) *reinterpret_cast<float4*>(xout + (i * 64 + lane) * 4) = xv[i];
;         } else if (xdst != 0) {
;           u16* xo = ((xdst == 1) ? resA : P.zf) + (long)row * 1024;
; #pragma unroll
;           for (int i = 0; i < 4; ++i) {
;             const unsigned b0 = f2bf(xv[i].x), b1 = f2bf(xv[i].y), b2 = f2bf(xv[i].z), b3 = f2bf(xv[i].w);
;             *reinterpret_cast<uint2*>(xo + (i * 64 + lane) * 4) = make_uint2(b0 | (b1 << 16), b2 | (b3 << 16));
;           }
;         }
;         if (doH) {
;           float ss = 0.f;
; #pragma unroll
;           for (int i = 0; i < 4; ++i) ss += xv[i].x * xv[i].x + xv[i].y * xv[i].y + xv[i].z * xv[i].z + xv[i].w * xv[i].w;
;           ss = wave_sum(ss);
;           const float rstd = __builtin_amdgcn_rsqf(ss * (1.f / 1024.f) + EPSF);
;           u16* h = P.hy + (long)row * 1024;
; #pragma unroll
	v_lshlrev_b32_e32 v32, 16, v40
	v_and_b32_e32 v33, 0xffff0000, v40
	v_lshlrev_b32_e32 v34, 16, v41
	v_and_b32_e32 v35, 0xffff0000, v41
	v_lshlrev_b32_e32 v36, 16, v42
	v_and_b32_e32 v37, 0xffff0000, v42
	v_lshlrev_b32_e32 v38, 16, v43
	v_and_b32_e32 v39, 0xffff0000, v43
	v_lshlrev_b32_e32 v40, 16, v44
	v_and_b32_e32 v41, 0xffff0000, v44
	v_lshlrev_b32_e32 v42, 16, v45
	v_and_b32_e32 v43, 0xffff0000, v45
	v_lshlrev_b32_e32 v44, 16, v46
	v_and_b32_e32 v45, 0xffff0000, v46
	v_lshlrev_b32_e32 v46, 16, v47
	v_and_b32_e32 v47, 0xffff0000, v47
	s_nop 0
	v_mul_f32_e32 v120, v120, v140
	v_mul_f32_e32 v121, v121, v140
	v_mul_f32_e32 v122, v122, v140
	v_mul_f32_e32 v123, v123, v140
	v_mul_f32_e32 v124, v124, v140
	v_mul_f32_e32 v125, v125, v140
	v_mul_f32_e32 v126, v126, v140
	v_mul_f32_e32 v127, v127, v140
	v_mul_f32_e32 v128, v128, v140
	v_mul_f32_e32 v129, v129, v140
	v_mul_f32_e32 v130, v130, v140
	v_mul_f32_e32 v131, v131, v140
	v_mul_f32_e32 v132, v132, v140
	v_mul_f32_e32 v133, v133, v140
	v_mul_f32_e32 v134, v134, v140
	v_mul_f32_e32 v135, v135, v140
	v_fma_f32 v32, v120, v72, v32
	v_fma_f32 v33, v121, v73, v33
	v_fma_f32 v34, v122, v74, v34
	v_fma_f32 v35, v123, v75, v35
	v_fma_f32 v36, v124, v76, v36
	v_fma_f32 v37, v125, v77, v37
	v_fma_f32 v38, v126, v78, v38
	v_fma_f32 v39, v127, v79, v39
	v_fma_f32 v40, v128, v80, v40
	v_fma_f32 v41, v129, v81, v41
	v_fma_f32 v42, v130, v82, v42
	v_fma_f32 v43, v131, v83, v43
	v_fma_f32 v44, v132, v84, v44
	v_fma_f32 v45, v133, v85, v45
	v_fma_f32 v46, v134, v86, v46
	v_fma_f32 v47, v135, v87, v47
	v_cvt_pk_bf16_f32 v156, v32, v33
	v_cvt_pk_bf16_f32 v157, v34, v35
	v_cvt_pk_bf16_f32 v158, v36, v37
	v_cvt_pk_bf16_f32 v159, v38, v39
	v_cvt_pk_bf16_f32 v160, v40, v41
	v_cvt_pk_bf16_f32 v161, v42, v43
	v_cvt_pk_bf16_f32 v162, v44, v45
	v_cvt_pk_bf16_f32 v163, v46, v47
	s_lshl_b32 vcc_lo, s19, 11
	s_add_u32 vcc_lo, vcc_lo, 0x800000
	s_add_u32 s100, s16, vcc_lo
	s_addc_u32 s101, s17, 0
	global_store_dwordx2 v137, v[156:157], s[100:101] offset:0
	global_store_dwordx2 v137, v[158:159], s[100:101] offset:512
	global_store_dwordx2 v137, v[160:161], s[100:101] offset:1024
	global_store_dwordx2 v137, v[162:163], s[100:101] offset:1536
	v_mul_f32_e32 v138, v32, v32
	v_mul_f32_e32 v149, v33, v33
	v_mul_f32_e32 v150, v34, v34
	v_mul_f32_e32 v154, v35, v35
	v_fma_f32 v138, v36, v36, v138
	v_fma_f32 v149, v37, v37, v149
	v_fma_f32 v150, v38, v38, v150
	v_fma_f32 v154, v39, v39, v154
	v_fma_f32 v138, v40, v40, v138
	v_fma_f32 v149, v41, v41, v149
	v_fma_f32 v150, v42, v42, v150
	v_fma_f32 v154, v43, v43, v154
	v_fma_f32 v138, v44, v44, v138
	v_fma_f32 v149, v45, v45, v149
	v_fma_f32 v150, v46, v46, v150
	v_fma_f32 v154, v47, v47, v154
	v_add_f32_e32 v138, v138, v149
	v_add_f32_e32 v150, v150, v154
	v_add_f32_e32 v138, v138, v150
	s_nop 1
	v_add_f32_dpp v138, v138, v138 quad_perm:[1,0,3,2] row_mask:0xf bank_mask:0xf
	s_nop 1
	v_add_f32_dpp v138, v138, v138 quad_perm:[2,3,0,1] row_mask:0xf bank_mask:0xf
	s_nop 1
	v_add_f32_dpp v138, v138, v138 row_half_mirror row_mask:0xf bank_mask:0xf
	s_nop 1
	v_add_f32_dpp v138, v138, v138 row_mirror row_mask:0xf bank_mask:0xf
	v_mov_b32_e32 v139, v138
	s_nop 1
	v_permlane16_swap_b32_e32 v138, v139
	v_add_f32_e32 v138, v138, v139
	v_mov_b32_e32 v139, v138
	s_nop 1
	v_permlane32_swap_b32_e32 v138, v139
	v_add_f32_e32 v138, v138, v139
	v_mul_f32_e32 v138, 0x3a800000, v138
	v_add_f32_e32 v138, 0x358637bd, v138
	v_rsq_f32_e32 v140, v138
	s_nop 0
	v_mul_f32_e32 v120, v32, v140
	v_mul_f32_e32 v121, v33, v140
	v_mul_f32_e32 v122, v34, v140
	v_mul_f32_e32 v123, v35, v140
	v_mul_f32_e32 v124, v36, v140
	v_mul_f32_e32 v125, v37, v140
	v_mul_f32_e32 v126, v38, v140
	v_mul_f32_e32 v127, v39, v140
	v_mul_f32_e32 v128, v40, v140
	v_mul_f32_e32 v129, v41, v140
	v_mul_f32_e32 v130, v42, v140
	v_mul_f32_e32 v131, v43, v140
	v_mul_f32_e32 v132, v44, v140
	v_mul_f32_e32 v133, v45, v140
	v_mul_f32_e32 v134, v46, v140
	v_mul_f32_e32 v135, v47, v140
	v_fma_f32 v120, v120, v88, v104
	v_fma_f32 v121, v121, v89, v105
	v_fma_f32 v122, v122, v90, v106
	v_fma_f32 v123, v123, v91, v107
	v_fma_f32 v124, v124, v92, v108
	v_fma_f32 v125, v125, v93, v109
	v_fma_f32 v126, v126, v94, v110
	v_fma_f32 v127, v127, v95, v111
	v_fma_f32 v128, v128, v96, v112
	v_fma_f32 v129, v129, v97, v113
	v_fma_f32 v130, v130, v98, v114
	v_fma_f32 v131, v131, v99, v115
	v_fma_f32 v132, v132, v100, v116
	v_fma_f32 v133, v133, v101, v117
	v_fma_f32 v134, v134, v102, v118
	v_fma_f32 v135, v135, v103, v119
	v_cvt_pk_bf16_f32 v156, v120, v121
	v_cvt_pk_bf16_f32 v157, v122, v123
	v_cvt_pk_bf16_f32 v158, v124, v125
	v_cvt_pk_bf16_f32 v159, v126, v127
	v_cvt_pk_bf16_f32 v160, v128, v129
	v_cvt_pk_bf16_f32 v161, v130, v131
	v_cvt_pk_bf16_f32 v162, v132, v133
	v_cvt_pk_bf16_f32 v163, v134, v135
	s_lshl_b32 vcc_lo, s19, 11
	s_add_u32 vcc_lo, vcc_lo, 0x800000
	s_add_u32 s100, s14, vcc_lo
	s_addc_u32 s101, s15, 0
	global_store_dwordx2 v137, v[156:157], s[100:101] offset:0
	global_store_dwordx2 v137, v[158:159], s[100:101] offset:512
	global_store_dwordx2 v137, v[160:161], s[100:101] offset:1024
	global_store_dwordx2 v137, v[162:163], s[100:101] offset:1536
	s_lshl_b32 vcc_lo, s19, 11
	s_add_u32 vcc_lo, vcc_lo, 0x1400000
	s_add_u32 s100, s12, vcc_lo
	s_addc_u32 s101, s13, 0
	global_load_dwordx2 v[40:41], v137, s[100:101] offset:0
	global_load_dwordx2 v[42:43], v137, s[100:101] offset:512
	global_load_dwordx2 v[44:45], v137, s[100:101] offset:1024
	global_load_dwordx2 v[46:47], v137, s[100:101] offset:1536
	s_lshl_b32 vcc_lo, s19, 11
	s_add_u32 vcc_lo, vcc_lo, 0x1400000
	s_add_u32 s100, s14, vcc_lo
	s_addc_u32 s101, s15, 0
	global_load_dwordx2 v[64:65], v137, s[100:101] offset:0
	global_load_dwordx2 v[66:67], v137, s[100:101] offset:512
	global_load_dwordx2 v[68:69], v137, s[100:101] offset:1024
	global_load_dwordx2 v[70:71], v137, s[100:101] offset:1536
	s_waitcnt vmcnt(32)
; __device__ __forceinline__ void row_phase(const Params& P, int glayer, int layer, int xsrc, bool hasY, int gate_idx, const float* gpost,
;                           int xdst, bool doH, const float* gpre, int sh_idx, int nrows) {
;     ...
;         if (hasY) {
;           float4 yv[4];
;           float ss = 0.f;
; #pragma unroll
;           for (int i = 0; i < 4; ++i) {
;             const uint2 raw = yy[u][i];
;             yv[i].x = bf2f((u16)(raw.x & 0xffff)); yv[i].y = bf2f((u16)(raw.x >> 16));
;             yv[i].z = bf2f((u16)(raw.y & 0xffff)); yv[i].w = bf2f((u16)(raw.y >> 16));
;             ss += yv[i].x * yv[i].x + yv[i].y * yv[i].y + yv[i].z * yv[i].z + yv[i].w * yv[i].w;
;           }
;           ss = wave_sum(ss);
;           const float rstd = __builtin_amdgcn_rsqf(ss * (1.f / 1024.f) + EPSF);
; #pragma unroll
;           for (int i = 0; i < 4; ++i) {
;             const int col = (i * 64 + lane) * 4;
;             const float4 gt = *reinterpret_cast<const float4*>(modg + gate_idx * 1024 + col);
;             const float4 gp = *reinterpret_cast<const float4*>(gpost + col);
;             xv[i].x += gt.x * (yv[i].x * rstd * gp.x); xv[i].y += gt.y * (yv[i].y * rstd * gp.y);
;             xv[i].z += gt.z * (yv[i].z * rstd * gp.z); xv[i].w += gt.w * (yv[i].w * rstd * gp.w);
;           }
;         }
;         if (xdst == 3 || (xdst == 1 && row >= N_X)) {
;           float* xout = (xdst == 3) ? P.out + (long)row * 1024 : P.xc + (long)(row - N_X) * 1024;
; #pragma unroll
;           for (int i = 0; i < 4; ++i) *reinterpret_cast<float4*>(xout + (i * 64 + lane) * 4) = xv[i];
;         } else if (xdst != 0) {
;           u16* xo = ((xdst == 1) ? resA : P.zf) + (long)row * 1024;
; #pragma unroll
;           for (int i = 0; i < 4; ++i) {
;             const unsigned b0 = f2bf(xv[i].x), b1 = f2bf(xv[i].y), b2 = f2bf(xv[i].z), b3 = f2bf(xv[i].w);
;             *reinterpret_cast<uint2*>(xo + (i * 64 + lane) * 4) = make_uint2(b0 | (b1 << 16), b2 | (b3 << 16));
;           }
;         }
;         if (doH) {
;           float ss = 0.f;
; #pragma unroll
;           for (int i = 0; i < 4; ++i) ss += xv[i].x * xv[i].x + xv[i].y * xv[i].y + xv[i].z * xv[i].z + xv[i].w * xv[i].w;
;           ss = wave_sum(ss);
;           const float rstd = __builtin_amdgcn_rsqf(ss * (1.f / 1024.f) + EPSF);
;           u16* h = P.hy + (long)row * 1024;
; #pragma unroll
	v_lshlrev_b32_e32 v120, 16, v48
	v_and_b32_e32 v121, 0xffff0000, v48
	v_lshlrev_b32_e32 v122, 16, v49
	v_and_b32_e32 v123, 0xffff0000, v49
	v_lshlrev_b32_e32 v124, 16, v50
	v_and_b32_e32 v125, 0xffff0000, v50
	v_lshlrev_b32_e32 v126, 16, v51
	v_and_b32_e32 v127, 0xffff0000, v51
	v_lshlrev_b32_e32 v128, 16, v52
	v_and_b32_e32 v129, 0xffff0000, v52
	v_lshlrev_b32_e32 v130, 16, v53
	v_and_b32_e32 v131, 0xffff0000, v53
	v_lshlrev_b32_e32 v132, 16, v54
	v_and_b32_e32 v133, 0xffff0000, v54
	v_lshlrev_b32_e32 v134, 16, v55
	v_and_b32_e32 v135, 0xffff0000, v55
	v_mul_f32_e32 v138, v120, v120
	v_mul_f32_e32 v149, v121, v121
	v_mul_f32_e32 v150, v122, v122
	v_mul_f32_e32 v154, v123, v123
	v_fma_f32 v138, v124, v124, v138
	v_fma_f32 v149, v125, v125, v149
	v_fma_f32 v150, v126, v126, v150
	v_fma_f32 v154, v127, v127, v154
	v_fma_f32 v138, v128, v128, v138
	v_fma_f32 v149, v129, v129, v149
	v_fma_f32 v150, v130, v130, v150
	v_fma_f32 v154, v131, v131, v154
	v_fma_f32 v138, v132, v132, v138
	v_fma_f32 v149, v133, v133, v149
	v_fma_f32 v150, v134, v134, v150
	v_fma_f32 v154, v135, v135, v154
	v_add_f32_e32 v138, v138, v149
	v_add_f32_e32 v150, v150, v154
	v_add_f32_e32 v138, v138, v150
	s_nop 1
	v_add_f32_dpp v138, v138, v138 quad_perm:[1,0,3,2] row_mask:0xf bank_mask:0xf
	s_nop 1
	v_add_f32_dpp v138, v138, v138 quad_perm:[2,3,0,1] row_mask:0xf bank_mask:0xf
	s_nop 1
	v_add_f32_dpp v138, v138, v138 row_half_mirror row_mask:0xf bank_mask:0xf
	s_nop 1
	v_add_f32_dpp v138, v138, v138 row_mirror row_mask:0xf bank_mask:0xf
	v_mov_b32_e32 v139, v138
	s_nop 1
	v_permlane16_swap_b32_e32 v138, v139
	v_add_f32_e32 v138, v138, v139
	v_mov_b32_e32 v139, v138
	s_nop 1
	v_permlane32_swap_b32_e32 v138, v139
	v_add_f32_e32 v138, v138, v139
	v_mul_f32_e32 v138, 0x3a800000, v138
	v_add_f32_e32 v138, 0x358637bd, v138
	v_rsq_f32_e32 v140, v138
	v_lshlrev_b32_e32 v0, 16, v8
	v_and_b32_e32 v1, 0xffff0000, v8
	v_lshlrev_b32_e32 v2, 16, v9
	v_and_b32_e32 v3, 0xffff0000, v9
	v_lshlrev_b32_e32 v4, 16, v10
	v_and_b32_e32 v5, 0xffff0000, v10
	v_lshlrev_b32_e32 v6, 16, v11
	v_and_b32_e32 v7, 0xffff0000, v11
	v_lshlrev_b32_e32 v8, 16, v12
	v_and_b32_e32 v9, 0xffff0000, v12
	v_lshlrev_b32_e32 v10, 16, v13
	v_and_b32_e32 v11, 0xffff0000, v13
	v_lshlrev_b32_e32 v12, 16, v14
	v_and_b32_e32 v13, 0xffff0000, v14
	v_lshlrev_b32_e32 v14, 16, v15
	v_and_b32_e32 v15, 0xffff0000, v15
	s_nop 0
	v_mul_f32_e32 v120, v120, v140
	v_mul_f32_e32 v121, v121, v140
	v_mul_f32_e32 v122, v122, v140
	v_mul_f32_e32 v123, v123, v140
	v_mul_f32_e32 v124, v124, v140
	v_mul_f32_e32 v125, v125, v140
	v_mul_f32_e32 v126, v126, v140
	v_mul_f32_e32 v127, v127, v140
	v_mul_f32_e32 v128, v128, v140
	v_mul_f32_e32 v129, v129, v140
	v_mul_f32_e32 v130, v130, v140
	v_mul_f32_e32 v131, v131, v140
	v_mul_f32_e32 v132, v132, v140
	v_mul_f32_e32 v133, v133, v140
	v_mul_f32_e32 v134, v134, v140
	v_mul_f32_e32 v135, v135, v140
	v_fma_f32 v0, v120, v72, v0
	v_fma_f32 v1, v121, v73, v1
	v_fma_f32 v2, v122, v74, v2
	v_fma_f32 v3, v123, v75, v3
	v_fma_f32 v4, v124, v76, v4
	v_fma_f32 v5, v125, v77, v5
	v_fma_f32 v6, v126, v78, v6
	v_fma_f32 v7, v127, v79, v7
	v_fma_f32 v8, v128, v80, v8
	v_fma_f32 v9, v129, v81, v9
	v_fma_f32 v10, v130, v82, v10
	v_fma_f32 v11, v131, v83, v11
	v_fma_f32 v12, v132, v84, v12
	v_fma_f32 v13, v133, v85, v13
	v_fma_f32 v14, v134, v86, v14
	v_fma_f32 v15, v135, v87, v15
	v_cvt_pk_bf16_f32 v156, v0, v1
	v_cvt_pk_bf16_f32 v157, v2, v3
	v_cvt_pk_bf16_f32 v158, v4, v5
	v_cvt_pk_bf16_f32 v159, v6, v7
	v_cvt_pk_bf16_f32 v160, v8, v9
	v_cvt_pk_bf16_f32 v161, v10, v11
	v_cvt_pk_bf16_f32 v162, v12, v13
	v_cvt_pk_bf16_f32 v163, v14, v15
	s_lshl_b32 vcc_lo, s19, 11
	s_add_u32 vcc_lo, vcc_lo, 0xc00000
	s_add_u32 s100, s16, vcc_lo
	s_addc_u32 s101, s17, 0
	global_store_dwordx2 v137, v[156:157], s[100:101] offset:0
	global_store_dwordx2 v137, v[158:159], s[100:101] offset:512
	global_store_dwordx2 v137, v[160:161], s[100:101] offset:1024
	global_store_dwordx2 v137, v[162:163], s[100:101] offset:1536
	v_mul_f32_e32 v138, v0, v0
	v_mul_f32_e32 v149, v1, v1
	v_mul_f32_e32 v150, v2, v2
	v_mul_f32_e32 v154, v3, v3
	v_fma_f32 v138, v4, v4, v138
	v_fma_f32 v149, v5, v5, v149
	v_fma_f32 v150, v6, v6, v150
	v_fma_f32 v154, v7, v7, v154
	v_fma_f32 v138, v8, v8, v138
	v_fma_f32 v149, v9, v9, v149
	v_fma_f32 v150, v10, v10, v150
	v_fma_f32 v154, v11, v11, v154
	v_fma_f32 v138, v12, v12, v138
	v_fma_f32 v149, v13, v13, v149
	v_fma_f32 v150, v14, v14, v150
	v_fma_f32 v154, v15, v15, v154
	v_add_f32_e32 v138, v138, v149
	v_add_f32_e32 v150, v150, v154
	v_add_f32_e32 v138, v138, v150
	s_nop 1
	v_add_f32_dpp v138, v138, v138 quad_perm:[1,0,3,2] row_mask:0xf bank_mask:0xf
	s_nop 1
	v_add_f32_dpp v138, v138, v138 quad_perm:[2,3,0,1] row_mask:0xf bank_mask:0xf
	s_nop 1
	v_add_f32_dpp v138, v138, v138 row_half_mirror row_mask:0xf bank_mask:0xf
	s_nop 1
	v_add_f32_dpp v138, v138, v138 row_mirror row_mask:0xf bank_mask:0xf
	v_mov_b32_e32 v139, v138
	s_nop 1
	v_permlane16_swap_b32_e32 v138, v139
	v_add_f32_e32 v138, v138, v139
	v_mov_b32_e32 v139, v138
	s_nop 1
	v_permlane32_swap_b32_e32 v138, v139
	v_add_f32_e32 v138, v138, v139
	v_mul_f32_e32 v138, 0x3a800000, v138
	v_add_f32_e32 v138, 0x358637bd, v138
	v_rsq_f32_e32 v140, v138
	s_nop 0
	v_mul_f32_e32 v120, v0, v140
	v_mul_f32_e32 v121, v1, v140
	v_mul_f32_e32 v122, v2, v140
	v_mul_f32_e32 v123, v3, v140
	v_mul_f32_e32 v124, v4, v140
	v_mul_f32_e32 v125, v5, v140
	v_mul_f32_e32 v126, v6, v140
	v_mul_f32_e32 v127, v7, v140
	v_mul_f32_e32 v128, v8, v140
	v_mul_f32_e32 v129, v9, v140
	v_mul_f32_e32 v130, v10, v140
	v_mul_f32_e32 v131, v11, v140
	v_mul_f32_e32 v132, v12, v140
; __device__ __forceinline__ void row_phase(const Params& P, int glayer, int layer, int xsrc, bool hasY, int gate_idx, const float* gpost,
;                           int xdst, bool doH, const float* gpre, int sh_idx, int nrows) {
;     ...
;         if (hasY) {
;           float4 yv[4];
;           float ss = 0.f;
; #pragma unroll
;           for (int i = 0; i < 4; ++i) {
;             const uint2 raw = yy[u][i];
;             yv[i].x = bf2f((u16)(raw.x & 0xffff)); yv[i].y = bf2f((u16)(raw.x >> 16));
;             yv[i].z = bf2f((u16)(raw.y & 0xffff)); yv[i].w = bf2f((u16)(raw.y >> 16));
;             ss += yv[i].x * yv[i].x + yv[i].y * yv[i].y + yv[i].z * yv[i].z + yv[i].w * yv[i].w;
;           }
;           ss = wave_sum(ss);
;           const float rstd = __builtin_amdgcn_rsqf(ss * (1.f / 1024.f) + EPSF);
; #pragma unroll
;           for (int i = 0; i < 4; ++i) {
;             const int col = (i * 64 + lane) * 4;
;             const float4 gt = *reinterpret_cast<const float4*>(modg + gate_idx * 1024 + col);
;             const float4 gp = *reinterpret_cast<const float4*>(gpost + col);
;             xv[i].x += gt.x * (yv[i].x * rstd * gp.x); xv[i].y += gt.y * (yv[i].y * rstd * gp.y);
;             xv[i].z += gt.z * (yv[i].z * rstd * gp.z); xv[i].w += gt.w * (yv[i].w * rstd * gp.w);
;           }
;         }
;         if (xdst == 3 || (xdst == 1 && row >= N_X)) {
;           float* xout = (xdst == 3) ? P.out + (long)row * 1024 : P.xc + (long)(row - N_X) * 1024;
; #pragma unroll
;           for (int i = 0; i < 4; ++i) *reinterpret_cast<float4*>(xout + (i * 64 + lane) * 4) = xv[i];
;         } else if (xdst != 0) {
;           u16* xo = ((xdst == 1) ? resA : P.zf) + (long)row * 1024;
; #pragma unroll
;           for (int i = 0; i < 4; ++i) {
;             const unsigned b0 = f2bf(xv[i].x), b1 = f2bf(xv[i].y), b2 = f2bf(xv[i].z), b3 = f2bf(xv[i].w);
;             *reinterpret_cast<uint2*>(xo + (i * 64 + lane) * 4) = make_uint2(b0 | (b1 << 16), b2 | (b3 << 16));
;           }
;         }
;         if (doH) {
;           float ss = 0.f;
; #pragma unroll
;           for (int i = 0; i < 4; ++i) ss += xv[i].x * xv[i].x + xv[i].y * xv[i].y + xv[i].z * xv[i].z + xv[i].w * xv[i].w;
;           ss = wave_sum(ss);
;           const float rstd = __builtin_amdgcn_rsqf(ss * (1.f / 1024.f) + EPSF);
;           u16* h = P.hy + (long)row * 1024;
; #pragma unroll
	v_mul_f32_e32 v133, v13, v140
	v_mul_f32_e32 v134, v14, v140
	v_mul_f32_e32 v135, v15, v140
	v_fma_f32 v120, v120, v88, v104
	v_fma_f32 v121, v121, v89, v105
	v_fma_f32 v122, v122, v90, v106
	v_fma_f32 v123, v123, v91, v107
	v_fma_f32 v124, v124, v92, v108
	v_fma_f32 v125, v125, v93, v109
	v_fma_f32 v126, v126, v94, v110
	v_fma_f32 v127, v127, v95, v111
	v_fma_f32 v128, v128, v96, v112
	v_fma_f32 v129, v129, v97, v113
	v_fma_f32 v130, v130, v98, v114
	v_fma_f32 v131, v131, v99, v115
	v_fma_f32 v132, v132, v100, v116
	v_fma_f32 v133, v133, v101, v117
	v_fma_f32 v134, v134, v102, v118
	v_fma_f32 v135, v135, v103, v119
	v_cvt_pk_bf16_f32 v156, v120, v121
	v_cvt_pk_bf16_f32 v157, v122, v123
	v_cvt_pk_bf16_f32 v158, v124, v125
	v_cvt_pk_bf16_f32 v159, v126, v127
	v_cvt_pk_bf16_f32 v160, v128, v129
	v_cvt_pk_bf16_f32 v161, v130, v131
	v_cvt_pk_bf16_f32 v162, v132, v133
	v_cvt_pk_bf16_f32 v163, v134, v135
	s_lshl_b32 vcc_lo, s19, 11
	s_add_u32 vcc_lo, vcc_lo, 0xc00000
	s_add_u32 s100, s14, vcc_lo
	s_addc_u32 s101, s15, 0
	global_store_dwordx2 v137, v[156:157], s[100:101] offset:0
	global_store_dwordx2 v137, v[158:159], s[100:101] offset:512
	global_store_dwordx2 v137, v[160:161], s[100:101] offset:1024
	global_store_dwordx2 v137, v[162:163], s[100:101] offset:1536
	s_add_u32 s100, s20, 0x26000
	s_addc_u32 s101, s21, 0
	global_load_dwordx4 v[72:75], v136, s[100:101] offset:0
	global_load_dwordx4 v[76:79], v136, s[100:101] offset:1024
	global_load_dwordx4 v[80:83], v136, s[100:101] offset:2048
	global_load_dwordx4 v[84:87], v136, s[100:101] offset:3072
	s_load_dwordx2 s[98:99], s[4:5], 0x38
	s_waitcnt lgkmcnt(0)
	s_add_u32 s98, s98, 0x1000
	s_addc_u32 s99, s99, 0
	global_load_dwordx4 v[120:123], v136, s[98:99] offset:0
	global_load_dwordx4 v[124:127], v136, s[98:99] offset:1024
	global_load_dwordx4 v[128:131], v136, s[98:99] offset:2048
	global_load_dwordx4 v[132:135], v136, s[98:99] offset:3072
	s_add_u32 s100, s20, 0x27000
	s_addc_u32 s101, s21, 0
	global_load_dwordx4 v[104:107], v136, s[100:101] offset:0
	global_load_dwordx4 v[108:111], v136, s[100:101] offset:1024
	global_load_dwordx4 v[112:115], v136, s[100:101] offset:2048
	global_load_dwordx4 v[116:119], v136, s[100:101] offset:3072
	s_add_u32 s100, s100, 0x1000
	s_addc_u32 s101, s101, 0
	global_load_dwordx4 v[0:3], v136, s[100:101] offset:0
	global_load_dwordx4 v[4:7], v136, s[100:101] offset:1024
	global_load_dwordx4 v[8:11], v136, s[100:101] offset:2048
	global_load_dwordx4 v[12:15], v136, s[100:101] offset:3072
	s_load_dwordx2 s[98:99], s[4:5], 0x40
	s_waitcnt lgkmcnt(0)
	s_add_u32 s98, s98, 0x1000
	s_addc_u32 s99, s99, 0
	global_load_dwordx4 v[88:91], v136, s[98:99] offset:0
	global_load_dwordx4 v[92:95], v136, s[98:99] offset:1024
	global_load_dwordx4 v[96:99], v136, s[98:99] offset:2048
	global_load_dwordx4 v[100:103], v136, s[98:99] offset:3072
	s_waitcnt vmcnt(0)
	v_mul_f32_e32 v72, v72, v120
	v_mul_f32_e32 v73, v73, v121
	v_mul_f32_e32 v74, v74, v122
	v_mul_f32_e32 v75, v75, v123
	v_mul_f32_e32 v76, v76, v124
	v_mul_f32_e32 v77, v77, v125
	v_mul_f32_e32 v78, v78, v126
	v_mul_f32_e32 v79, v79, v127
	v_mul_f32_e32 v80, v80, v128
	v_mul_f32_e32 v81, v81, v129
	v_mul_f32_e32 v82, v82, v130
	v_mul_f32_e32 v83, v83, v131
	v_mul_f32_e32 v84, v84, v132
	v_mul_f32_e32 v85, v85, v133
	v_mul_f32_e32 v86, v86, v134
	v_mul_f32_e32 v87, v87, v135
	v_fma_f32 v88, v88, v0, v88
	v_fma_f32 v89, v89, v1, v89
	v_fma_f32 v90, v90, v2, v90
	v_fma_f32 v91, v91, v3, v91
	v_fma_f32 v92, v92, v4, v92
	v_fma_f32 v93, v93, v5, v93
	v_fma_f32 v94, v94, v6, v94
	v_fma_f32 v95, v95, v7, v95
	v_fma_f32 v96, v96, v8, v96
	v_fma_f32 v97, v97, v9, v97
	v_fma_f32 v98, v98, v10, v98
	v_fma_f32 v99, v99, v11, v99
	v_fma_f32 v100, v100, v12, v100
	v_fma_f32 v101, v101, v13, v101
	v_fma_f32 v102, v102, v14, v102
	v_fma_f32 v103, v103, v15, v103
	s_lshl_b32 vcc_lo, s19, 11
	s_add_u32 vcc_lo, vcc_lo, 0x1800000
	s_add_u32 s100, s12, vcc_lo
	s_addc_u32 s101, s13, 0
	global_load_dwordx2 v[8:9], v137, s[100:101] offset:0
	global_load_dwordx2 v[10:11], v137, s[100:101] offset:512
	global_load_dwordx2 v[12:13], v137, s[100:101] offset:1024
	global_load_dwordx2 v[14:15], v137, s[100:101] offset:1536
	s_lshl_b32 vcc_lo, s19, 11
	s_add_u32 vcc_lo, vcc_lo, 0x1800000
	s_add_u32 s100, s14, vcc_lo
	s_addc_u32 s101, s15, 0
	global_load_dwordx2 v[48:49], v137, s[100:101] offset:0
	global_load_dwordx2 v[50:51], v137, s[100:101] offset:512
	global_load_dwordx2 v[52:53], v137, s[100:101] offset:1024
	global_load_dwordx2 v[54:55], v137, s[100:101] offset:1536
	v_lshlrev_b32_e32 v120, 16, v56
	v_and_b32_e32 v121, 0xffff0000, v56
	v_lshlrev_b32_e32 v122, 16, v57
	v_and_b32_e32 v123, 0xffff0000, v57
	v_lshlrev_b32_e32 v124, 16, v58
	v_and_b32_e32 v125, 0xffff0000, v58
	v_lshlrev_b32_e32 v126, 16, v59
	v_and_b32_e32 v127, 0xffff0000, v59
	v_lshlrev_b32_e32 v128, 16, v60
	v_and_b32_e32 v129, 0xffff0000, v60
	v_lshlrev_b32_e32 v130, 16, v61
	v_and_b32_e32 v131, 0xffff0000, v61
	v_lshlrev_b32_e32 v132, 16, v62
	v_and_b32_e32 v133, 0xffff0000, v62
	v_lshlrev_b32_e32 v134, 16, v63
	v_and_b32_e32 v135, 0xffff0000, v63
	v_mul_f32_e32 v138, v120, v120
	v_mul_f32_e32 v149, v121, v121
	v_mul_f32_e32 v150, v122, v122
	v_mul_f32_e32 v154, v123, v123
	v_fma_f32 v138, v124, v124, v138
	v_fma_f32 v149, v125, v125, v149
	v_fma_f32 v150, v126, v126, v150
	v_fma_f32 v154, v127, v127, v154
	v_fma_f32 v138, v128, v128, v138
	v_fma_f32 v149, v129, v129, v149
	v_fma_f32 v150, v130, v130, v150
	v_fma_f32 v154, v131, v131, v154
	v_fma_f32 v138, v132, v132, v138
	v_fma_f32 v149, v133, v133, v149
	v_fma_f32 v150, v134, v134, v150
	v_fma_f32 v154, v135, v135, v154
; __device__ __forceinline__ void row_phase(const Params& P, int glayer, int layer, int xsrc, bool hasY, int gate_idx, const float* gpost,
;                           int xdst, bool doH, const float* gpre, int sh_idx, int nrows) {
;     ...
;         if (hasY) {
;           float4 yv[4];
;           float ss = 0.f;
; #pragma unroll
;           for (int i = 0; i < 4; ++i) {
;             const uint2 raw = yy[u][i];
;             yv[i].x = bf2f((u16)(raw.x & 0xffff)); yv[i].y = bf2f((u16)(raw.x >> 16));
;             yv[i].z = bf2f((u16)(raw.y & 0xffff)); yv[i].w = bf2f((u16)(raw.y >> 16));
;             ss += yv[i].x * yv[i].x + yv[i].y * yv[i].y + yv[i].z * yv[i].z + yv[i].w * yv[i].w;
;           }
;           ss = wave_sum(ss);
;           const float rstd = __builtin_amdgcn_rsqf(ss * (1.f / 1024.f) + EPSF);
; #pragma unroll
;           for (int i = 0; i < 4; ++i) {
;             const int col = (i * 64 + lane) * 4;
;             const float4 gt = *reinterpret_cast<const float4*>(modg + gate_idx * 1024 + col);
;             const float4 gp = *reinterpret_cast<const float4*>(gpost + col);
;             xv[i].x += gt.x * (yv[i].x * rstd * gp.x); xv[i].y += gt.y * (yv[i].y * rstd * gp.y);
;             xv[i].z += gt.z * (yv[i].z * rstd * gp.z); xv[i].w += gt.w * (yv[i].w * rstd * gp.w);
;           }
;         }
;         if (xdst == 3 || (xdst == 1 && row >= N_X)) {
;           float* xout = (xdst == 3) ? P.out + (long)row * 1024 : P.xc + (long)(row - N_X) * 1024;
; #pragma unroll
;           for (int i = 0; i < 4; ++i) *reinterpret_cast<float4*>(xout + (i * 64 + lane) * 4) = xv[i];
;         } else if (xdst != 0) {
;           u16* xo = ((xdst == 1) ? resA : P.zf) + (long)row * 1024;
; #pragma unroll
;           for (int i = 0; i < 4; ++i) {
;             const unsigned b0 = f2bf(xv[i].x), b1 = f2bf(xv[i].y), b2 = f2bf(xv[i].z), b3 = f2bf(xv[i].w);
;             *reinterpret_cast<uint2*>(xo + (i * 64 + lane) * 4) = make_uint2(b0 | (b1 << 16), b2 | (b3 << 16));
;           }
;         }
;         if (doH) {
;           float ss = 0.f;
; #pragma unroll
;           for (int i = 0; i < 4; ++i) ss += xv[i].x * xv[i].x + xv[i].y * xv[i].y + xv[i].z * xv[i].z + xv[i].w * xv[i].w;
;           ss = wave_sum(ss);
;           const float rstd = __builtin_amdgcn_rsqf(ss * (1.f / 1024.f) + EPSF);
;           u16* h = P.hy + (long)row * 1024;
; #pragma unroll
	v_add_f32_e32 v138, v138, v149
	v_add_f32_e32 v150, v150, v154
	v_add_f32_e32 v138, v138, v150
	s_nop 1
	v_add_f32_dpp v138, v138, v138 quad_perm:[1,0,3,2] row_mask:0xf bank_mask:0xf
	s_nop 1
	v_add_f32_dpp v138, v138, v138 quad_perm:[2,3,0,1] row_mask:0xf bank_mask:0xf
	s_nop 1
	v_add_f32_dpp v138, v138, v138 row_half_mirror row_mask:0xf bank_mask:0xf
	s_nop 1
	v_add_f32_dpp v138, v138, v138 row_mirror row_mask:0xf bank_mask:0xf
	v_mov_b32_e32 v139, v138
	s_nop 1
	v_permlane16_swap_b32_e32 v138, v139
	v_add_f32_e32 v138, v138, v139
	v_mov_b32_e32 v139, v138
	s_nop 1
	v_permlane32_swap_b32_e32 v138, v139
	v_add_f32_e32 v138, v138, v139
	v_mul_f32_e32 v138, 0x3a800000, v138
	v_add_f32_e32 v138, 0x358637bd, v138
	v_rsq_f32_e32 v140, v138
	v_lshlrev_b32_e32 v16, 16, v24
	v_and_b32_e32 v17, 0xffff0000, v24
	v_lshlrev_b32_e32 v18, 16, v25
	v_and_b32_e32 v19, 0xffff0000, v25
	v_lshlrev_b32_e32 v20, 16, v26
	v_and_b32_e32 v21, 0xffff0000, v26
	v_lshlrev_b32_e32 v22, 16, v27
	v_and_b32_e32 v23, 0xffff0000, v27
	v_lshlrev_b32_e32 v24, 16, v28
	v_and_b32_e32 v25, 0xffff0000, v28
	v_lshlrev_b32_e32 v26, 16, v29
	v_and_b32_e32 v27, 0xffff0000, v29
	v_lshlrev_b32_e32 v28, 16, v30
	v_and_b32_e32 v29, 0xffff0000, v30
	v_lshlrev_b32_e32 v30, 16, v31
	v_and_b32_e32 v31, 0xffff0000, v31
	s_nop 0
	v_mul_f32_e32 v120, v120, v140
	v_mul_f32_e32 v121, v121, v140
	v_mul_f32_e32 v122, v122, v140
	v_mul_f32_e32 v123, v123, v140
	v_mul_f32_e32 v124, v124, v140
	v_mul_f32_e32 v125, v125, v140
	v_mul_f32_e32 v126, v126, v140
	v_mul_f32_e32 v127, v127, v140
	v_mul_f32_e32 v128, v128, v140
	v_mul_f32_e32 v129, v129, v140
	v_mul_f32_e32 v130, v130, v140
	v_mul_f32_e32 v131, v131, v140
	v_mul_f32_e32 v132, v132, v140
	v_mul_f32_e32 v133, v133, v140
	v_mul_f32_e32 v134, v134, v140
	v_mul_f32_e32 v135, v135, v140
	v_fma_f32 v16, v120, v72, v16
	v_fma_f32 v17, v121, v73, v17
	v_fma_f32 v18, v122, v74, v18
	v_fma_f32 v19, v123, v75, v19
	v_fma_f32 v20, v124, v76, v20
	v_fma_f32 v21, v125, v77, v21
	v_fma_f32 v22, v126, v78, v22
	v_fma_f32 v23, v127, v79, v23
	v_fma_f32 v24, v128, v80, v24
	v_fma_f32 v25, v129, v81, v25
	v_fma_f32 v26, v130, v82, v26
	v_fma_f32 v27, v131, v83, v27
	v_fma_f32 v28, v132, v84, v28
	v_fma_f32 v29, v133, v85, v29
	v_fma_f32 v30, v134, v86, v30
	v_fma_f32 v31, v135, v87, v31
	v_cvt_pk_bf16_f32 v156, v16, v17
	v_cvt_pk_bf16_f32 v157, v18, v19
	v_cvt_pk_bf16_f32 v158, v20, v21
	v_cvt_pk_bf16_f32 v159, v22, v23
	v_cvt_pk_bf16_f32 v160, v24, v25
	v_cvt_pk_bf16_f32 v161, v26, v27
	v_cvt_pk_bf16_f32 v162, v28, v29
	v_cvt_pk_bf16_f32 v163, v30, v31
	s_lshl_b32 vcc_lo, s19, 11
	s_add_u32 vcc_lo, vcc_lo, 0x1000000
	s_add_u32 s100, s16, vcc_lo
	s_addc_u32 s101, s17, 0
	global_store_dwordx2 v137, v[156:157], s[100:101] offset:0
	global_store_dwordx2 v137, v[158:159], s[100:101] offset:512
	global_store_dwordx2 v137, v[160:161], s[100:101] offset:1024
	global_store_dwordx2 v137, v[162:163], s[100:101] offset:1536
	v_mul_f32_e32 v138, v16, v16
	v_mul_f32_e32 v149, v17, v17
	v_mul_f32_e32 v150, v18, v18
	v_mul_f32_e32 v154, v19, v19
	v_fma_f32 v138, v20, v20, v138
	v_fma_f32 v149, v21, v21, v149
	v_fma_f32 v150, v22, v22, v150
	v_fma_f32 v154, v23, v23, v154
	v_fma_f32 v138, v24, v24, v138
	v_fma_f32 v149, v25, v25, v149
	v_fma_f32 v150, v26, v26, v150
	v_fma_f32 v154, v27, v27, v154
	v_fma_f32 v138, v28, v28, v138
	v_fma_f32 v149, v29, v29, v149
	v_fma_f32 v150, v30, v30, v150
	v_fma_f32 v154, v31, v31, v154
	v_add_f32_e32 v138, v138, v149
	v_add_f32_e32 v150, v150, v154
	v_add_f32_e32 v138, v138, v150
	s_nop 1
	v_add_f32_dpp v138, v138, v138 quad_perm:[1,0,3,2] row_mask:0xf bank_mask:0xf
	s_nop 1
	v_add_f32_dpp v138, v138, v138 quad_perm:[2,3,0,1] row_mask:0xf bank_mask:0xf
	s_nop 1
	v_add_f32_dpp v138, v138, v138 row_half_mirror row_mask:0xf bank_mask:0xf
	s_nop 1
	v_add_f32_dpp v138, v138, v138 row_mirror row_mask:0xf bank_mask:0xf
	v_mov_b32_e32 v139, v138
	s_nop 1
	v_permlane16_swap_b32_e32 v138, v139
	v_add_f32_e32 v138, v138, v139
	v_mov_b32_e32 v139, v138
	s_nop 1
	v_permlane32_swap_b32_e32 v138, v139
	v_add_f32_e32 v138, v138, v139
	v_mul_f32_e32 v138, 0x3a800000, v138
	v_add_f32_e32 v138, 0x358637bd, v138
	v_rsq_f32_e32 v140, v138
	s_nop 0
	v_mul_f32_e32 v120, v16, v140
	v_mul_f32_e32 v121, v17, v140
	v_mul_f32_e32 v122, v18, v140
	v_mul_f32_e32 v123, v19, v140
	v_mul_f32_e32 v124, v20, v140
	v_mul_f32_e32 v125, v21, v140
	v_mul_f32_e32 v126, v22, v140
	v_mul_f32_e32 v127, v23, v140
	v_mul_f32_e32 v128, v24, v140
	v_mul_f32_e32 v129, v25, v140
	v_mul_f32_e32 v130, v26, v140
	v_mul_f32_e32 v131, v27, v140
	v_mul_f32_e32 v132, v28, v140
	v_mul_f32_e32 v133, v29, v140
	v_mul_f32_e32 v134, v30, v140
	v_mul_f32_e32 v135, v31, v140
	v_fma_f32 v120, v120, v88, v104
	v_fma_f32 v121, v121, v89, v105
	v_fma_f32 v122, v122, v90, v106
	v_fma_f32 v123, v123, v91, v107
	v_fma_f32 v124, v124, v92, v108
	v_fma_f32 v125, v125, v93, v109
	v_fma_f32 v126, v126, v94, v110
	v_fma_f32 v127, v127, v95, v111
	v_fma_f32 v128, v128, v96, v112
	v_fma_f32 v129, v129, v97, v113
	v_fma_f32 v130, v130, v98, v114
	v_fma_f32 v131, v131, v99, v115
	v_fma_f32 v132, v132, v100, v116
	v_fma_f32 v133, v133, v101, v117
	v_fma_f32 v134, v134, v102, v118
	v_fma_f32 v135, v135, v103, v119
	v_cvt_pk_bf16_f32 v156, v120, v121
	v_cvt_pk_bf16_f32 v157, v122, v123
	v_cvt_pk_bf16_f32 v158, v124, v125
	v_cvt_pk_bf16_f32 v159, v126, v127
	v_cvt_pk_bf16_f32 v160, v128, v129
	v_cvt_pk_bf16_f32 v161, v130, v131
	v_cvt_pk_bf16_f32 v162, v132, v133
	v_cvt_pk_bf16_f32 v163, v134, v135
	s_lshl_b32 vcc_lo, s19, 11
	s_add_u32 vcc_lo, vcc_lo, 0x1000000
	s_add_u32 s100, s14, vcc_lo
	s_addc_u32 s101, s15, 0
; __device__ __forceinline__ void row_phase(const Params& P, int glayer, int layer, int xsrc, bool hasY, int gate_idx, const float* gpost,
;                           int xdst, bool doH, const float* gpre, int sh_idx, int nrows) {
;     ...
;         if (hasY) {
;           float4 yv[4];
;           float ss = 0.f;
; #pragma unroll
;           for (int i = 0; i < 4; ++i) {
;             const uint2 raw = yy[u][i];
;             yv[i].x = bf2f((u16)(raw.x & 0xffff)); yv[i].y = bf2f((u16)(raw.x >> 16));
;             yv[i].z = bf2f((u16)(raw.y & 0xffff)); yv[i].w = bf2f((u16)(raw.y >> 16));
;             ss += yv[i].x * yv[i].x + yv[i].y * yv[i].y + yv[i].z * yv[i].z + yv[i].w * yv[i].w;
;           }
;           ss = wave_sum(ss);
;           const float rstd = __builtin_amdgcn_rsqf(ss * (1.f / 1024.f) + EPSF);
; #pragma unroll
;           for (int i = 0; i < 4; ++i) {
;             const int col = (i * 64 + lane) * 4;
;             const float4 gt = *reinterpret_cast<const float4*>(modg + gate_idx * 1024 + col);
;             const float4 gp = *reinterpret_cast<const float4*>(gpost + col);
;             xv[i].x += gt.x * (yv[i].x * rstd * gp.x); xv[i].y += gt.y * (yv[i].y * rstd * gp.y);
;             xv[i].z += gt.z * (yv[i].z * rstd * gp.z); xv[i].w += gt.w * (yv[i].w * rstd * gp.w);
;           }
;         }
;         if (xdst == 3 || (xdst == 1 && row >= N_X)) {
;           float* xout = (xdst == 3) ? P.out + (long)row * 1024 : P.xc + (long)(row - N_X) * 1024;
; #pragma unroll
;           for (int i = 0; i < 4; ++i) *reinterpret_cast<float4*>(xout + (i * 64 + lane) * 4) = xv[i];
;         } else if (xdst != 0) {
;           u16* xo = ((xdst == 1) ? resA : P.zf) + (long)row * 1024;
; #pragma unroll
;           for (int i = 0; i < 4; ++i) {
;             const unsigned b0 = f2bf(xv[i].x), b1 = f2bf(xv[i].y), b2 = f2bf(xv[i].z), b3 = f2bf(xv[i].w);
;             *reinterpret_cast<uint2*>(xo + (i * 64 + lane) * 4) = make_uint2(b0 | (b1 << 16), b2 | (b3 << 16));
;           }
;         }
;         if (doH) {
;           float ss = 0.f;
; #pragma unroll
;           for (int i = 0; i < 4; ++i) ss += xv[i].x * xv[i].x + xv[i].y * xv[i].y + xv[i].z * xv[i].z + xv[i].w * xv[i].w;
;           ss = wave_sum(ss);
;           const float rstd = __builtin_amdgcn_rsqf(ss * (1.f / 1024.f) + EPSF);
;           u16* h = P.hy + (long)row * 1024;
; #pragma unroll
	global_store_dwordx2 v137, v[156:157], s[100:101] offset:0
	global_store_dwordx2 v137, v[158:159], s[100:101] offset:512
	global_store_dwordx2 v137, v[160:161], s[100:101] offset:1024
	global_store_dwordx2 v137, v[162:163], s[100:101] offset:1536
	s_lshl_b32 vcc_lo, s19, 11
	s_add_u32 vcc_lo, vcc_lo, 0x1c00000
	s_add_u32 s100, s12, vcc_lo
	s_addc_u32 s101, s13, 0
	global_load_dwordx2 v[24:25], v137, s[100:101] offset:0
	global_load_dwordx2 v[26:27], v137, s[100:101] offset:512
	global_load_dwordx2 v[28:29], v137, s[100:101] offset:1024
	global_load_dwordx2 v[30:31], v137, s[100:101] offset:1536
	s_lshl_b32 vcc_lo, s19, 11
	s_add_u32 vcc_lo, vcc_lo, 0x1c00000
	s_add_u32 s100, s14, vcc_lo
	s_addc_u32 s101, s15, 0
	global_load_dwordx2 v[56:57], v137, s[100:101] offset:0
	global_load_dwordx2 v[58:59], v137, s[100:101] offset:512
	global_load_dwordx2 v[60:61], v137, s[100:101] offset:1024
	global_load_dwordx2 v[62:63], v137, s[100:101] offset:1536
	v_lshlrev_b32_e32 v120, 16, v64
	v_and_b32_e32 v121, 0xffff0000, v64
	v_lshlrev_b32_e32 v122, 16, v65
	v_and_b32_e32 v123, 0xffff0000, v65
	v_lshlrev_b32_e32 v124, 16, v66
	v_and_b32_e32 v125, 0xffff0000, v66
	v_lshlrev_b32_e32 v126, 16, v67
	v_and_b32_e32 v127, 0xffff0000, v67
	v_lshlrev_b32_e32 v128, 16, v68
	v_and_b32_e32 v129, 0xffff0000, v68
	v_lshlrev_b32_e32 v130, 16, v69
	v_and_b32_e32 v131, 0xffff0000, v69
	v_lshlrev_b32_e32 v132, 16, v70
	v_and_b32_e32 v133, 0xffff0000, v70
	v_lshlrev_b32_e32 v134, 16, v71
	v_and_b32_e32 v135, 0xffff0000, v71
	v_mul_f32_e32 v138, v120, v120
	v_mul_f32_e32 v149, v121, v121
	v_mul_f32_e32 v150, v122, v122
	v_mul_f32_e32 v154, v123, v123
	v_fma_f32 v138, v124, v124, v138
	v_fma_f32 v149, v125, v125, v149
	v_fma_f32 v150, v126, v126, v150
	v_fma_f32 v154, v127, v127, v154
	v_fma_f32 v138, v128, v128, v138
	v_fma_f32 v149, v129, v129, v149
	v_fma_f32 v150, v130, v130, v150
	v_fma_f32 v154, v131, v131, v154
	v_fma_f32 v138, v132, v132, v138
	v_fma_f32 v149, v133, v133, v149
	v_fma_f32 v150, v134, v134, v150
	v_fma_f32 v154, v135, v135, v154
	v_add_f32_e32 v138, v138, v149
	v_add_f32_e32 v150, v150, v154
	v_add_f32_e32 v138, v138, v150
	s_nop 1
	v_add_f32_dpp v138, v138, v138 quad_perm:[1,0,3,2] row_mask:0xf bank_mask:0xf
	s_nop 1
	v_add_f32_dpp v138, v138, v138 quad_perm:[2,3,0,1] row_mask:0xf bank_mask:0xf
	s_nop 1
	v_add_f32_dpp v138, v138, v138 row_half_mirror row_mask:0xf bank_mask:0xf
	s_nop 1
	v_add_f32_dpp v138, v138, v138 row_mirror row_mask:0xf bank_mask:0xf
	v_mov_b32_e32 v139, v138
	s_nop 1
	v_permlane16_swap_b32_e32 v138, v139
	v_add_f32_e32 v138, v138, v139
	v_mov_b32_e32 v139, v138
	s_nop 1
	v_permlane32_swap_b32_e32 v138, v139
	v_add_f32_e32 v138, v138, v139
	v_mul_f32_e32 v138, 0x3a800000, v138
	v_add_f32_e32 v138, 0x358637bd, v138
	v_rsq_f32_e32 v140, v138
	v_lshlrev_b32_e32 v32, 16, v40
	v_and_b32_e32 v33, 0xffff0000, v40
	v_lshlrev_b32_e32 v34, 16, v41
	v_and_b32_e32 v35, 0xffff0000, v41
	v_lshlrev_b32_e32 v36, 16, v42
	v_and_b32_e32 v37, 0xffff0000, v42
	v_lshlrev_b32_e32 v38, 16, v43
	v_and_b32_e32 v39, 0xffff0000, v43
	v_lshlrev_b32_e32 v40, 16, v44
	v_and_b32_e32 v41, 0xffff0000, v44
	v_lshlrev_b32_e32 v42, 16, v45
	v_and_b32_e32 v43, 0xffff0000, v45
	v_lshlrev_b32_e32 v44, 16, v46
	v_and_b32_e32 v45, 0xffff0000, v46
	v_lshlrev_b32_e32 v46, 16, v47
	v_and_b32_e32 v47, 0xffff0000, v47
	s_nop 0
	v_mul_f32_e32 v120, v120, v140
	v_mul_f32_e32 v121, v121, v140
	v_mul_f32_e32 v122, v122, v140
	v_mul_f32_e32 v123, v123, v140
	v_mul_f32_e32 v124, v124, v140
	v_mul_f32_e32 v125, v125, v140
	v_mul_f32_e32 v126, v126, v140
	v_mul_f32_e32 v127, v127, v140
	v_mul_f32_e32 v128, v128, v140
	v_mul_f32_e32 v129, v129, v140
	v_mul_f32_e32 v130, v130, v140
	v_mul_f32_e32 v131, v131, v140
	v_mul_f32_e32 v132, v132, v140
	v_mul_f32_e32 v133, v133, v140
	v_mul_f32_e32 v134, v134, v140
	v_mul_f32_e32 v135, v135, v140
	v_fma_f32 v32, v120, v72, v32
	v_fma_f32 v33, v121, v73, v33
	v_fma_f32 v34, v122, v74, v34
	v_fma_f32 v35, v123, v75, v35
	v_fma_f32 v36, v124, v76, v36
	v_fma_f32 v37, v125, v77, v37
	v_fma_f32 v38, v126, v78, v38
	v_fma_f32 v39, v127, v79, v39
	v_fma_f32 v40, v128, v80, v40
	v_fma_f32 v41, v129, v81, v41
	v_fma_f32 v42, v130, v82, v42
	v_fma_f32 v43, v131, v83, v43
	v_fma_f32 v44, v132, v84, v44
	v_fma_f32 v45, v133, v85, v45
	v_fma_f32 v46, v134, v86, v46
	v_fma_f32 v47, v135, v87, v47
	v_cvt_pk_bf16_f32 v156, v32, v33
	v_cvt_pk_bf16_f32 v157, v34, v35
	v_cvt_pk_bf16_f32 v158, v36, v37
	v_cvt_pk_bf16_f32 v159, v38, v39
	v_cvt_pk_bf16_f32 v160, v40, v41
	v_cvt_pk_bf16_f32 v161, v42, v43
	v_cvt_pk_bf16_f32 v162, v44, v45
	v_cvt_pk_bf16_f32 v163, v46, v47
	s_lshl_b32 vcc_lo, s19, 11
	s_add_u32 vcc_lo, vcc_lo, 0x1400000
	s_add_u32 s100, s16, vcc_lo
	s_addc_u32 s101, s17, 0
	global_store_dwordx2 v137, v[156:157], s[100:101] offset:0
	global_store_dwordx2 v137, v[158:159], s[100:101] offset:512
	global_store_dwordx2 v137, v[160:161], s[100:101] offset:1024
	global_store_dwordx2 v137, v[162:163], s[100:101] offset:1536
	v_mul_f32_e32 v138, v32, v32
	v_mul_f32_e32 v149, v33, v33
	v_mul_f32_e32 v150, v34, v34
	v_mul_f32_e32 v154, v35, v35
	v_fma_f32 v138, v36, v36, v138
	v_fma_f32 v149, v37, v37, v149
	v_fma_f32 v150, v38, v38, v150
	v_fma_f32 v154, v39, v39, v154
	v_fma_f32 v138, v40, v40, v138
	v_fma_f32 v149, v41, v41, v149
	v_fma_f32 v150, v42, v42, v150
	v_fma_f32 v154, v43, v43, v154
	v_fma_f32 v138, v44, v44, v138
	v_fma_f32 v149, v45, v45, v149
	v_fma_f32 v150, v46, v46, v150
	v_fma_f32 v154, v47, v47, v154
	v_add_f32_e32 v138, v138, v149
	v_add_f32_e32 v150, v150, v154
	v_add_f32_e32 v138, v138, v150
	s_nop 1
; __device__ __forceinline__ void row_phase(const Params& P, int glayer, int layer, int xsrc, bool hasY, int gate_idx, const float* gpost,
;                           int xdst, bool doH, const float* gpre, int sh_idx, int nrows) {
;     ...
;         if (hasY) {
;           float4 yv[4];
;           float ss = 0.f;
; #pragma unroll
;           for (int i = 0; i < 4; ++i) {
;             const uint2 raw = yy[u][i];
;             yv[i].x = bf2f((u16)(raw.x & 0xffff)); yv[i].y = bf2f((u16)(raw.x >> 16));
;             yv[i].z = bf2f((u16)(raw.y & 0xffff)); yv[i].w = bf2f((u16)(raw.y >> 16));
;             ss += yv[i].x * yv[i].x + yv[i].y * yv[i].y + yv[i].z * yv[i].z + yv[i].w * yv[i].w;
;           }
;           ss = wave_sum(ss);
;           const float rstd = __builtin_amdgcn_rsqf(ss * (1.f / 1024.f) + EPSF);
; #pragma unroll
;           for (int i = 0; i < 4; ++i) {
;             const int col = (i * 64 + lane) * 4;
;             const float4 gt = *reinterpret_cast<const float4*>(modg + gate_idx * 1024 + col);
;             const float4 gp = *reinterpret_cast<const float4*>(gpost + col);
;             xv[i].x += gt.x * (yv[i].x * rstd * gp.x); xv[i].y += gt.y * (yv[i].y * rstd * gp.y);
;             xv[i].z += gt.z * (yv[i].z * rstd * gp.z); xv[i].w += gt.w * (yv[i].w * rstd * gp.w);
;           }
;         }
;         if (xdst == 3 || (xdst == 1 && row >= N_X)) {
;           float* xout = (xdst == 3) ? P.out + (long)row * 1024 : P.xc + (long)(row - N_X) * 1024;
; #pragma unroll
;           for (int i = 0; i < 4; ++i) *reinterpret_cast<float4*>(xout + (i * 64 + lane) * 4) = xv[i];
;         } else if (xdst != 0) {
;           u16* xo = ((xdst == 1) ? resA : P.zf) + (long)row * 1024;
; #pragma unroll
;           for (int i = 0; i < 4; ++i) {
;             const unsigned b0 = f2bf(xv[i].x), b1 = f2bf(xv[i].y), b2 = f2bf(xv[i].z), b3 = f2bf(xv[i].w);
;             *reinterpret_cast<uint2*>(xo + (i * 64 + lane) * 4) = make_uint2(b0 | (b1 << 16), b2 | (b3 << 16));
;           }
;         }
;         if (doH) {
;           float ss = 0.f;
; #pragma unroll
;           for (int i = 0; i < 4; ++i) ss += xv[i].x * xv[i].x + xv[i].y * xv[i].y + xv[i].z * xv[i].z + xv[i].w * xv[i].w;
;           ss = wave_sum(ss);
;           const float rstd = __builtin_amdgcn_rsqf(ss * (1.f / 1024.f) + EPSF);
;           u16* h = P.hy + (long)row * 1024;
; #pragma unroll
	v_add_f32_dpp v138, v138, v138 quad_perm:[1,0,3,2] row_mask:0xf bank_mask:0xf
	s_nop 1
	v_add_f32_dpp v138, v138, v138 quad_perm:[2,3,0,1] row_mask:0xf bank_mask:0xf
	s_nop 1
	v_add_f32_dpp v138, v138, v138 row_half_mirror row_mask:0xf bank_mask:0xf
	s_nop 1
	v_add_f32_dpp v138, v138, v138 row_mirror row_mask:0xf bank_mask:0xf
	v_mov_b32_e32 v139, v138
	s_nop 1
	v_permlane16_swap_b32_e32 v138, v139
	v_add_f32_e32 v138, v138, v139
	v_mov_b32_e32 v139, v138
	s_nop 1
	v_permlane32_swap_b32_e32 v138, v139
	v_add_f32_e32 v138, v138, v139
	v_mul_f32_e32 v138, 0x3a800000, v138
	v_add_f32_e32 v138, 0x358637bd, v138
	v_rsq_f32_e32 v140, v138
	s_nop 0
	v_mul_f32_e32 v120, v32, v140
	v_mul_f32_e32 v121, v33, v140
	v_mul_f32_e32 v122, v34, v140
	v_mul_f32_e32 v123, v35, v140
	v_mul_f32_e32 v124, v36, v140
	v_mul_f32_e32 v125, v37, v140
	v_mul_f32_e32 v126, v38, v140
	v_mul_f32_e32 v127, v39, v140
	v_mul_f32_e32 v128, v40, v140
	v_mul_f32_e32 v129, v41, v140
	v_mul_f32_e32 v130, v42, v140
	v_mul_f32_e32 v131, v43, v140
	v_mul_f32_e32 v132, v44, v140
	v_mul_f32_e32 v133, v45, v140
	v_mul_f32_e32 v134, v46, v140
	v_mul_f32_e32 v135, v47, v140
	v_fma_f32 v120, v120, v88, v104
	v_fma_f32 v121, v121, v89, v105
	v_fma_f32 v122, v122, v90, v106
	v_fma_f32 v123, v123, v91, v107
	v_fma_f32 v124, v124, v92, v108
	v_fma_f32 v125, v125, v93, v109
	v_fma_f32 v126, v126, v94, v110
	v_fma_f32 v127, v127, v95, v111
	v_fma_f32 v128, v128, v96, v112
	v_fma_f32 v129, v129, v97, v113
	v_fma_f32 v130, v130, v98, v114
	v_fma_f32 v131, v131, v99, v115
	v_fma_f32 v132, v132, v100, v116
	v_fma_f32 v133, v133, v101, v117
	v_fma_f32 v134, v134, v102, v118
	v_fma_f32 v135, v135, v103, v119
	v_cvt_pk_bf16_f32 v156, v120, v121
	v_cvt_pk_bf16_f32 v157, v122, v123
	v_cvt_pk_bf16_f32 v158, v124, v125
	v_cvt_pk_bf16_f32 v159, v126, v127
	v_cvt_pk_bf16_f32 v160, v128, v129
	v_cvt_pk_bf16_f32 v161, v130, v131
	v_cvt_pk_bf16_f32 v162, v132, v133
	v_cvt_pk_bf16_f32 v163, v134, v135
	s_lshl_b32 vcc_lo, s19, 11
	s_add_u32 vcc_lo, vcc_lo, 0x1400000
	s_add_u32 s100, s14, vcc_lo
	s_addc_u32 s101, s15, 0
	global_store_dwordx2 v137, v[156:157], s[100:101] offset:0
	global_store_dwordx2 v137, v[158:159], s[100:101] offset:512
	global_store_dwordx2 v137, v[160:161], s[100:101] offset:1024
	global_store_dwordx2 v137, v[162:163], s[100:101] offset:1536
	s_lshl_b32 vcc_lo, s19, 11
	s_add_u32 vcc_lo, vcc_lo, 0x2000000
	s_add_u32 s100, s12, vcc_lo
	s_addc_u32 s101, s13, 0
	global_load_dwordx2 v[40:41], v137, s[100:101] offset:0
	global_load_dwordx2 v[42:43], v137, s[100:101] offset:512
	global_load_dwordx2 v[44:45], v137, s[100:101] offset:1024
	global_load_dwordx2 v[46:47], v137, s[100:101] offset:1536
	s_lshl_b32 vcc_lo, s19, 11
	s_add_u32 vcc_lo, vcc_lo, 0x2000000
	s_add_u32 s100, s14, vcc_lo
	s_addc_u32 s101, s15, 0
	global_load_dwordx2 v[64:65], v137, s[100:101] offset:0
	global_load_dwordx2 v[66:67], v137, s[100:101] offset:512
	global_load_dwordx2 v[68:69], v137, s[100:101] offset:1024
	global_load_dwordx2 v[70:71], v137, s[100:101] offset:1536
	s_waitcnt vmcnt(32)
	v_lshlrev_b32_e32 v120, 16, v48
	v_and_b32_e32 v121, 0xffff0000, v48
	v_lshlrev_b32_e32 v122, 16, v49
	v_and_b32_e32 v123, 0xffff0000, v49
	v_lshlrev_b32_e32 v124, 16, v50
	v_and_b32_e32 v125, 0xffff0000, v50
	v_lshlrev_b32_e32 v126, 16, v51
	v_and_b32_e32 v127, 0xffff0000, v51
	v_lshlrev_b32_e32 v128, 16, v52
	v_and_b32_e32 v129, 0xffff0000, v52
	v_lshlrev_b32_e32 v130, 16, v53
	v_and_b32_e32 v131, 0xffff0000, v53
	v_lshlrev_b32_e32 v132, 16, v54
	v_and_b32_e32 v133, 0xffff0000, v54
	v_lshlrev_b32_e32 v134, 16, v55
	v_and_b32_e32 v135, 0xffff0000, v55
	v_mul_f32_e32 v138, v120, v120
	v_mul_f32_e32 v149, v121, v121
	v_mul_f32_e32 v150, v122, v122
	v_mul_f32_e32 v154, v123, v123
	v_fma_f32 v138, v124, v124, v138
	v_fma_f32 v149, v125, v125, v149
	v_fma_f32 v150, v126, v126, v150
	v_fma_f32 v154, v127, v127, v154
	v_fma_f32 v138, v128, v128, v138
	v_fma_f32 v149, v129, v129, v149
	v_fma_f32 v150, v130, v130, v150
	v_fma_f32 v154, v131, v131, v154
	v_fma_f32 v138, v132, v132, v138
	v_fma_f32 v149, v133, v133, v149
	v_fma_f32 v150, v134, v134, v150
	v_fma_f32 v154, v135, v135, v154
	v_add_f32_e32 v138, v138, v149
	v_add_f32_e32 v150, v150, v154
	v_add_f32_e32 v138, v138, v150
	s_nop 1
	v_add_f32_dpp v138, v138, v138 quad_perm:[1,0,3,2] row_mask:0xf bank_mask:0xf
	s_nop 1
	v_add_f32_dpp v138, v138, v138 quad_perm:[2,3,0,1] row_mask:0xf bank_mask:0xf
	s_nop 1
	v_add_f32_dpp v138, v138, v138 row_half_mirror row_mask:0xf bank_mask:0xf
	s_nop 1
	v_add_f32_dpp v138, v138, v138 row_mirror row_mask:0xf bank_mask:0xf
	v_mov_b32_e32 v139, v138
	s_nop 1
	v_permlane16_swap_b32_e32 v138, v139
	v_add_f32_e32 v138, v138, v139
	v_mov_b32_e32 v139, v138
	s_nop 1
	v_permlane32_swap_b32_e32 v138, v139
	v_add_f32_e32 v138, v138, v139
	v_mul_f32_e32 v138, 0x3a800000, v138
	v_add_f32_e32 v138, 0x358637bd, v138
	v_rsq_f32_e32 v140, v138
	v_lshlrev_b32_e32 v0, 16, v8
	v_and_b32_e32 v1, 0xffff0000, v8
	v_lshlrev_b32_e32 v2, 16, v9
	v_and_b32_e32 v3, 0xffff0000, v9
	v_lshlrev_b32_e32 v4, 16, v10
	v_and_b32_e32 v5, 0xffff0000, v10
	v_lshlrev_b32_e32 v6, 16, v11
	v_and_b32_e32 v7, 0xffff0000, v11
	v_lshlrev_b32_e32 v8, 16, v12
	v_and_b32_e32 v9, 0xffff0000, v12
	v_lshlrev_b32_e32 v10, 16, v13
	v_and_b32_e32 v11, 0xffff0000, v13
	v_lshlrev_b32_e32 v12, 16, v14
	v_and_b32_e32 v13, 0xffff0000, v14
	v_lshlrev_b32_e32 v14, 16, v15
	v_and_b32_e32 v15, 0xffff0000, v15
	s_nop 0
	v_mul_f32_e32 v120, v120, v140
	v_mul_f32_e32 v121, v121, v140
	v_mul_f32_e32 v122, v122, v140
	v_mul_f32_e32 v123, v123, v140
	v_mul_f32_e32 v124, v124, v140
	v_mul_f32_e32 v125, v125, v140
; __device__ __forceinline__ void row_phase(const Params& P, int glayer, int layer, int xsrc, bool hasY, int gate_idx, const float* gpost,
;                           int xdst, bool doH, const float* gpre, int sh_idx, int nrows) {
;     ...
;         if (hasY) {
;           float4 yv[4];
;           float ss = 0.f;
; #pragma unroll
;           for (int i = 0; i < 4; ++i) {
;             const uint2 raw = yy[u][i];
;             yv[i].x = bf2f((u16)(raw.x & 0xffff)); yv[i].y = bf2f((u16)(raw.x >> 16));
;             yv[i].z = bf2f((u16)(raw.y & 0xffff)); yv[i].w = bf2f((u16)(raw.y >> 16));
;             ss += yv[i].x * yv[i].x + yv[i].y * yv[i].y + yv[i].z * yv[i].z + yv[i].w * yv[i].w;
;           }
;           ss = wave_sum(ss);
;           const float rstd = __builtin_amdgcn_rsqf(ss * (1.f / 1024.f) + EPSF);
; #pragma unroll
;           for (int i = 0; i < 4; ++i) {
;             const int col = (i * 64 + lane) * 4;
;             const float4 gt = *reinterpret_cast<const float4*>(modg + gate_idx * 1024 + col);
;             const float4 gp = *reinterpret_cast<const float4*>(gpost + col);
;             xv[i].x += gt.x * (yv[i].x * rstd * gp.x); xv[i].y += gt.y * (yv[i].y * rstd * gp.y);
;             xv[i].z += gt.z * (yv[i].z * rstd * gp.z); xv[i].w += gt.w * (yv[i].w * rstd * gp.w);
;           }
;         }
;         if (xdst == 3 || (xdst == 1 && row >= N_X)) {
;           float* xout = (xdst == 3) ? P.out + (long)row * 1024 : P.xc + (long)(row - N_X) * 1024;
; #pragma unroll
;           for (int i = 0; i < 4; ++i) *reinterpret_cast<float4*>(xout + (i * 64 + lane) * 4) = xv[i];
;         } else if (xdst != 0) {
;           u16* xo = ((xdst == 1) ? resA : P.zf) + (long)row * 1024;
; #pragma unroll
;           for (int i = 0; i < 4; ++i) {
;             const unsigned b0 = f2bf(xv[i].x), b1 = f2bf(xv[i].y), b2 = f2bf(xv[i].z), b3 = f2bf(xv[i].w);
;             *reinterpret_cast<uint2*>(xo + (i * 64 + lane) * 4) = make_uint2(b0 | (b1 << 16), b2 | (b3 << 16));
;           }
;         }
;         if (doH) {
;           float ss = 0.f;
; #pragma unroll
;           for (int i = 0; i < 4; ++i) ss += xv[i].x * xv[i].x + xv[i].y * xv[i].y + xv[i].z * xv[i].z + xv[i].w * xv[i].w;
;           ss = wave_sum(ss);
;           const float rstd = __builtin_amdgcn_rsqf(ss * (1.f / 1024.f) + EPSF);
;           u16* h = P.hy + (long)row * 1024;
; #pragma unroll
	v_mul_f32_e32 v126, v126, v140
	v_mul_f32_e32 v127, v127, v140
	v_mul_f32_e32 v128, v128, v140
	v_mul_f32_e32 v129, v129, v140
	v_mul_f32_e32 v130, v130, v140
	v_mul_f32_e32 v131, v131, v140
	v_mul_f32_e32 v132, v132, v140
	v_mul_f32_e32 v133, v133, v140
	v_mul_f32_e32 v134, v134, v140
	v_mul_f32_e32 v135, v135, v140
	v_fma_f32 v0, v120, v72, v0
	v_fma_f32 v1, v121, v73, v1
	v_fma_f32 v2, v122, v74, v2
	v_fma_f32 v3, v123, v75, v3
	v_fma_f32 v4, v124, v76, v4
	v_fma_f32 v5, v125, v77, v5
	v_fma_f32 v6, v126, v78, v6
	v_fma_f32 v7, v127, v79, v7
	v_fma_f32 v8, v128, v80, v8
	v_fma_f32 v9, v129, v81, v9
	v_fma_f32 v10, v130, v82, v10
	v_fma_f32 v11, v131, v83, v11
	v_fma_f32 v12, v132, v84, v12
	v_fma_f32 v13, v133, v85, v13
	v_fma_f32 v14, v134, v86, v14
	v_fma_f32 v15, v135, v87, v15
	v_cvt_pk_bf16_f32 v156, v0, v1
	v_cvt_pk_bf16_f32 v157, v2, v3
	v_cvt_pk_bf16_f32 v158, v4, v5
	v_cvt_pk_bf16_f32 v159, v6, v7
	v_cvt_pk_bf16_f32 v160, v8, v9
	v_cvt_pk_bf16_f32 v161, v10, v11
	v_cvt_pk_bf16_f32 v162, v12, v13
	v_cvt_pk_bf16_f32 v163, v14, v15
	s_lshl_b32 vcc_lo, s19, 11
	s_add_u32 vcc_lo, vcc_lo, 0x1800000
	s_add_u32 s100, s16, vcc_lo
	s_addc_u32 s101, s17, 0
	global_store_dwordx2 v137, v[156:157], s[100:101] offset:0
	global_store_dwordx2 v137, v[158:159], s[100:101] offset:512
	global_store_dwordx2 v137, v[160:161], s[100:101] offset:1024
	global_store_dwordx2 v137, v[162:163], s[100:101] offset:1536
	v_mul_f32_e32 v138, v0, v0
	v_mul_f32_e32 v149, v1, v1
	v_mul_f32_e32 v150, v2, v2
	v_mul_f32_e32 v154, v3, v3
	v_fma_f32 v138, v4, v4, v138
	v_fma_f32 v149, v5, v5, v149
	v_fma_f32 v150, v6, v6, v150
	v_fma_f32 v154, v7, v7, v154
	v_fma_f32 v138, v8, v8, v138
	v_fma_f32 v149, v9, v9, v149
	v_fma_f32 v150, v10, v10, v150
	v_fma_f32 v154, v11, v11, v154
	v_fma_f32 v138, v12, v12, v138
	v_fma_f32 v149, v13, v13, v149
	v_fma_f32 v150, v14, v14, v150
	v_fma_f32 v154, v15, v15, v154
	v_add_f32_e32 v138, v138, v149
	v_add_f32_e32 v150, v150, v154
	v_add_f32_e32 v138, v138, v150
	s_nop 1
	v_add_f32_dpp v138, v138, v138 quad_perm:[1,0,3,2] row_mask:0xf bank_mask:0xf
	s_nop 1
	v_add_f32_dpp v138, v138, v138 quad_perm:[2,3,0,1] row_mask:0xf bank_mask:0xf
	s_nop 1
	v_add_f32_dpp v138, v138, v138 row_half_mirror row_mask:0xf bank_mask:0xf
	s_nop 1
	v_add_f32_dpp v138, v138, v138 row_mirror row_mask:0xf bank_mask:0xf
	v_mov_b32_e32 v139, v138
	s_nop 1
	v_permlane16_swap_b32_e32 v138, v139
	v_add_f32_e32 v138, v138, v139
	v_mov_b32_e32 v139, v138
	s_nop 1
	v_permlane32_swap_b32_e32 v138, v139
	v_add_f32_e32 v138, v138, v139
	v_mul_f32_e32 v138, 0x3a800000, v138
	v_add_f32_e32 v138, 0x358637bd, v138
	v_rsq_f32_e32 v140, v138
	s_nop 0
	v_mul_f32_e32 v120, v0, v140
	v_mul_f32_e32 v121, v1, v140
	v_mul_f32_e32 v122, v2, v140
	v_mul_f32_e32 v123, v3, v140
	v_mul_f32_e32 v124, v4, v140
	v_mul_f32_e32 v125, v5, v140
	v_mul_f32_e32 v126, v6, v140
	v_mul_f32_e32 v127, v7, v140
	v_mul_f32_e32 v128, v8, v140
	v_mul_f32_e32 v129, v9, v140
	v_mul_f32_e32 v130, v10, v140
	v_mul_f32_e32 v131, v11, v140
	v_mul_f32_e32 v132, v12, v140
	v_mul_f32_e32 v133, v13, v140
	v_mul_f32_e32 v134, v14, v140
	v_mul_f32_e32 v135, v15, v140
	v_fma_f32 v120, v120, v88, v104
	v_fma_f32 v121, v121, v89, v105
	v_fma_f32 v122, v122, v90, v106
	v_fma_f32 v123, v123, v91, v107
	v_fma_f32 v124, v124, v92, v108
	v_fma_f32 v125, v125, v93, v109
	v_fma_f32 v126, v126, v94, v110
	v_fma_f32 v127, v127, v95, v111
	v_fma_f32 v128, v128, v96, v112
	v_fma_f32 v129, v129, v97, v113
	v_fma_f32 v130, v130, v98, v114
	v_fma_f32 v131, v131, v99, v115
	v_fma_f32 v132, v132, v100, v116
	v_fma_f32 v133, v133, v101, v117
	v_fma_f32 v134, v134, v102, v118
	v_fma_f32 v135, v135, v103, v119
	v_cvt_pk_bf16_f32 v156, v120, v121
	v_cvt_pk_bf16_f32 v157, v122, v123
	v_cvt_pk_bf16_f32 v158, v124, v125
	v_cvt_pk_bf16_f32 v159, v126, v127
	v_cvt_pk_bf16_f32 v160, v128, v129
	v_cvt_pk_bf16_f32 v161, v130, v131
	v_cvt_pk_bf16_f32 v162, v132, v133
	v_cvt_pk_bf16_f32 v163, v134, v135
	s_lshl_b32 vcc_lo, s19, 11
	s_add_u32 vcc_lo, vcc_lo, 0x1800000
	s_add_u32 s100, s14, vcc_lo
	s_addc_u32 s101, s15, 0
	global_store_dwordx2 v137, v[156:157], s[100:101] offset:0
	global_store_dwordx2 v137, v[158:159], s[100:101] offset:512
	global_store_dwordx2 v137, v[160:161], s[100:101] offset:1024
	global_store_dwordx2 v137, v[162:163], s[100:101] offset:1536
	s_lshl_b32 vcc_lo, s19, 11
	s_add_u32 vcc_lo, vcc_lo, 0x2400000
	s_add_u32 s100, s12, vcc_lo
	s_addc_u32 s101, s13, 0
	global_load_dwordx2 v[8:9], v137, s[100:101] offset:0
	global_load_dwordx2 v[10:11], v137, s[100:101] offset:512
	global_load_dwordx2 v[12:13], v137, s[100:101] offset:1024
	global_load_dwordx2 v[14:15], v137, s[100:101] offset:1536
	s_lshl_b32 vcc_lo, s19, 11
	s_add_u32 vcc_lo, vcc_lo, 0x2400000
	s_add_u32 s100, s14, vcc_lo
	s_addc_u32 s101, s15, 0
	global_load_dwordx2 v[48:49], v137, s[100:101] offset:0
	global_load_dwordx2 v[50:51], v137, s[100:101] offset:512
	global_load_dwordx2 v[52:53], v137, s[100:101] offset:1024
	global_load_dwordx2 v[54:55], v137, s[100:101] offset:1536
	s_waitcnt vmcnt(32)
; __device__ __forceinline__ void row_phase(const Params& P, int glayer, int layer, int xsrc, bool hasY, int gate_idx, const float* gpost,
;                           int xdst, bool doH, const float* gpre, int sh_idx, int nrows) {
;     ...
;         if (hasY) {
;           float4 yv[4];
;           float ss = 0.f;
; #pragma unroll
;           for (int i = 0; i < 4; ++i) {
;             const uint2 raw = yy[u][i];
;             yv[i].x = bf2f((u16)(raw.x & 0xffff)); yv[i].y = bf2f((u16)(raw.x >> 16));
;             yv[i].z = bf2f((u16)(raw.y & 0xffff)); yv[i].w = bf2f((u16)(raw.y >> 16));
;             ss += yv[i].x * yv[i].x + yv[i].y * yv[i].y + yv[i].z * yv[i].z + yv[i].w * yv[i].w;
;           }
;           ss = wave_sum(ss);
;           const float rstd = __builtin_amdgcn_rsqf(ss * (1.f / 1024.f) + EPSF);
; #pragma unroll
;           for (int i = 0; i < 4; ++i) {
;             const int col = (i * 64 + lane) * 4;
;             const float4 gt = *reinterpret_cast<const float4*>(modg + gate_idx * 1024 + col);
;             const float4 gp = *reinterpret_cast<const float4*>(gpost + col);
;             xv[i].x += gt.x * (yv[i].x * rstd * gp.x); xv[i].y += gt.y * (yv[i].y * rstd * gp.y);
;             xv[i].z += gt.z * (yv[i].z * rstd * gp.z); xv[i].w += gt.w * (yv[i].w * rstd * gp.w);
;           }
;         }
;         if (xdst == 3 || (xdst == 1 && row >= N_X)) {
;           float* xout = (xdst == 3) ? P.out + (long)row * 1024 : P.xc + (long)(row - N_X) * 1024;
; #pragma unroll
;           for (int i = 0; i < 4; ++i) *reinterpret_cast<float4*>(xout + (i * 64 + lane) * 4) = xv[i];
;         } else if (xdst != 0) {
;           u16* xo = ((xdst == 1) ? resA : P.zf) + (long)row * 1024;
; #pragma unroll
;           for (int i = 0; i < 4; ++i) {
;             const unsigned b0 = f2bf(xv[i].x), b1 = f2bf(xv[i].y), b2 = f2bf(xv[i].z), b3 = f2bf(xv[i].w);
;             *reinterpret_cast<uint2*>(xo + (i * 64 + lane) * 4) = make_uint2(b0 | (b1 << 16), b2 | (b3 << 16));
;           }
;         }
;         if (doH) {
;           float ss = 0.f;
; #pragma unroll
;           for (int i = 0; i < 4; ++i) ss += xv[i].x * xv[i].x + xv[i].y * xv[i].y + xv[i].z * xv[i].z + xv[i].w * xv[i].w;
;           ss = wave_sum(ss);
;           const float rstd = __builtin_amdgcn_rsqf(ss * (1.f / 1024.f) + EPSF);
;           u16* h = P.hy + (long)row * 1024;
; #pragma unroll
	v_lshlrev_b32_e32 v120, 16, v56
	v_and_b32_e32 v121, 0xffff0000, v56
	v_lshlrev_b32_e32 v122, 16, v57
	v_and_b32_e32 v123, 0xffff0000, v57
	v_lshlrev_b32_e32 v124, 16, v58
	v_and_b32_e32 v125, 0xffff0000, v58
	v_lshlrev_b32_e32 v126, 16, v59
	v_and_b32_e32 v127, 0xffff0000, v59
	v_lshlrev_b32_e32 v128, 16, v60
	v_and_b32_e32 v129, 0xffff0000, v60
	v_lshlrev_b32_e32 v130, 16, v61
	v_and_b32_e32 v131, 0xffff0000, v61
	v_lshlrev_b32_e32 v132, 16, v62
	v_and_b32_e32 v133, 0xffff0000, v62
	v_lshlrev_b32_e32 v134, 16, v63
	v_and_b32_e32 v135, 0xffff0000, v63
	v_mul_f32_e32 v138, v120, v120
	v_mul_f32_e32 v149, v121, v121
	v_mul_f32_e32 v150, v122, v122
	v_mul_f32_e32 v154, v123, v123
	v_fma_f32 v138, v124, v124, v138
	v_fma_f32 v149, v125, v125, v149
	v_fma_f32 v150, v126, v126, v150
	v_fma_f32 v154, v127, v127, v154
	v_fma_f32 v138, v128, v128, v138
	v_fma_f32 v149, v129, v129, v149
	v_fma_f32 v150, v130, v130, v150
	v_fma_f32 v154, v131, v131, v154
	v_fma_f32 v138, v132, v132, v138
	v_fma_f32 v149, v133, v133, v149
	v_fma_f32 v150, v134, v134, v150
	v_fma_f32 v154, v135, v135, v154
	v_add_f32_e32 v138, v138, v149
	v_add_f32_e32 v150, v150, v154
	v_add_f32_e32 v138, v138, v150
	s_nop 1
	v_add_f32_dpp v138, v138, v138 quad_perm:[1,0,3,2] row_mask:0xf bank_mask:0xf
	s_nop 1
	v_add_f32_dpp v138, v138, v138 quad_perm:[2,3,0,1] row_mask:0xf bank_mask:0xf
	s_nop 1
	v_add_f32_dpp v138, v138, v138 row_half_mirror row_mask:0xf bank_mask:0xf
	s_nop 1
	v_add_f32_dpp v138, v138, v138 row_mirror row_mask:0xf bank_mask:0xf
	v_mov_b32_e32 v139, v138
	s_nop 1
	v_permlane16_swap_b32_e32 v138, v139
	v_add_f32_e32 v138, v138, v139
	v_mov_b32_e32 v139, v138
	s_nop 1
	v_permlane32_swap_b32_e32 v138, v139
	v_add_f32_e32 v138, v138, v139
	v_mul_f32_e32 v138, 0x3a800000, v138
	v_add_f32_e32 v138, 0x358637bd, v138
	v_rsq_f32_e32 v140, v138
	v_lshlrev_b32_e32 v16, 16, v24
	v_and_b32_e32 v17, 0xffff0000, v24
	v_lshlrev_b32_e32 v18, 16, v25
	v_and_b32_e32 v19, 0xffff0000, v25
	v_lshlrev_b32_e32 v20, 16, v26
	v_and_b32_e32 v21, 0xffff0000, v26
	v_lshlrev_b32_e32 v22, 16, v27
	v_and_b32_e32 v23, 0xffff0000, v27
	v_lshlrev_b32_e32 v24, 16, v28
	v_and_b32_e32 v25, 0xffff0000, v28
	v_lshlrev_b32_e32 v26, 16, v29
	v_and_b32_e32 v27, 0xffff0000, v29
	v_lshlrev_b32_e32 v28, 16, v30
	v_and_b32_e32 v29, 0xffff0000, v30
	v_lshlrev_b32_e32 v30, 16, v31
	v_and_b32_e32 v31, 0xffff0000, v31
	s_nop 0
	v_mul_f32_e32 v120, v120, v140
	v_mul_f32_e32 v121, v121, v140
	v_mul_f32_e32 v122, v122, v140
	v_mul_f32_e32 v123, v123, v140
	v_mul_f32_e32 v124, v124, v140
	v_mul_f32_e32 v125, v125, v140
	v_mul_f32_e32 v126, v126, v140
	v_mul_f32_e32 v127, v127, v140
	v_mul_f32_e32 v128, v128, v140
	v_mul_f32_e32 v129, v129, v140
	v_mul_f32_e32 v130, v130, v140
	v_mul_f32_e32 v131, v131, v140
	v_mul_f32_e32 v132, v132, v140
	v_mul_f32_e32 v133, v133, v140
	v_mul_f32_e32 v134, v134, v140
	v_mul_f32_e32 v135, v135, v140
	v_fma_f32 v16, v120, v72, v16
	v_fma_f32 v17, v121, v73, v17
	v_fma_f32 v18, v122, v74, v18
	v_fma_f32 v19, v123, v75, v19
	v_fma_f32 v20, v124, v76, v20
	v_fma_f32 v21, v125, v77, v21
	v_fma_f32 v22, v126, v78, v22
	v_fma_f32 v23, v127, v79, v23
	v_fma_f32 v24, v128, v80, v24
	v_fma_f32 v25, v129, v81, v25
	v_fma_f32 v26, v130, v82, v26
	v_fma_f32 v27, v131, v83, v27
	v_fma_f32 v28, v132, v84, v28
	v_fma_f32 v29, v133, v85, v29
	v_fma_f32 v30, v134, v86, v30
	v_fma_f32 v31, v135, v87, v31
	v_cvt_pk_bf16_f32 v156, v16, v17
	v_cvt_pk_bf16_f32 v157, v18, v19
	v_cvt_pk_bf16_f32 v158, v20, v21
	v_cvt_pk_bf16_f32 v159, v22, v23
	v_cvt_pk_bf16_f32 v160, v24, v25
	v_cvt_pk_bf16_f32 v161, v26, v27
	v_cvt_pk_bf16_f32 v162, v28, v29
	v_cvt_pk_bf16_f32 v163, v30, v31
	s_lshl_b32 vcc_lo, s19, 11
	s_add_u32 vcc_lo, vcc_lo, 0x1c00000
	s_add_u32 s100, s16, vcc_lo
	s_addc_u32 s101, s17, 0
	global_store_dwordx2 v137, v[156:157], s[100:101] offset:0
	global_store_dwordx2 v137, v[158:159], s[100:101] offset:512
	global_store_dwordx2 v137, v[160:161], s[100:101] offset:1024
	global_store_dwordx2 v137, v[162:163], s[100:101] offset:1536
	v_mul_f32_e32 v138, v16, v16
	v_mul_f32_e32 v149, v17, v17
	v_mul_f32_e32 v150, v18, v18
	v_mul_f32_e32 v154, v19, v19
	v_fma_f32 v138, v20, v20, v138
	v_fma_f32 v149, v21, v21, v149
	v_fma_f32 v150, v22, v22, v150
	v_fma_f32 v154, v23, v23, v154
	v_fma_f32 v138, v24, v24, v138
	v_fma_f32 v149, v25, v25, v149
	v_fma_f32 v150, v26, v26, v150
	v_fma_f32 v154, v27, v27, v154
	v_fma_f32 v138, v28, v28, v138
	v_fma_f32 v149, v29, v29, v149
	v_fma_f32 v150, v30, v30, v150
	v_fma_f32 v154, v31, v31, v154
	v_add_f32_e32 v138, v138, v149
	v_add_f32_e32 v150, v150, v154
	v_add_f32_e32 v138, v138, v150
	s_nop 1
	v_add_f32_dpp v138, v138, v138 quad_perm:[1,0,3,2] row_mask:0xf bank_mask:0xf
	s_nop 1
	v_add_f32_dpp v138, v138, v138 quad_perm:[2,3,0,1] row_mask:0xf bank_mask:0xf
	s_nop 1
	v_add_f32_dpp v138, v138, v138 row_half_mirror row_mask:0xf bank_mask:0xf
	s_nop 1
	v_add_f32_dpp v138, v138, v138 row_mirror row_mask:0xf bank_mask:0xf
	v_mov_b32_e32 v139, v138
	s_nop 1
	v_permlane16_swap_b32_e32 v138, v139
	v_add_f32_e32 v138, v138, v139
	v_mov_b32_e32 v139, v138
	s_nop 1
	v_permlane32_swap_b32_e32 v138, v139
	v_add_f32_e32 v138, v138, v139
	v_mul_f32_e32 v138, 0x3a800000, v138
	v_add_f32_e32 v138, 0x358637bd, v138
	v_rsq_f32_e32 v140, v138
	s_nop 0
	v_mul_f32_e32 v120, v16, v140
	v_mul_f32_e32 v121, v17, v140
	v_mul_f32_e32 v122, v18, v140
	v_mul_f32_e32 v123, v19, v140
	v_mul_f32_e32 v124, v20, v140
	v_mul_f32_e32 v125, v21, v140
	v_mul_f32_e32 v126, v22, v140
	v_mul_f32_e32 v127, v23, v140
	v_mul_f32_e32 v128, v24, v140
	v_mul_f32_e32 v129, v25, v140
	v_mul_f32_e32 v130, v26, v140
; __device__ __forceinline__ void row_phase(const Params& P, int glayer, int layer, int xsrc, bool hasY, int gate_idx, const float* gpost,
;                           int xdst, bool doH, const float* gpre, int sh_idx, int nrows) {
;     ...
;         if (hasY) {
;           float4 yv[4];
;           float ss = 0.f;
; #pragma unroll
;           for (int i = 0; i < 4; ++i) {
;             const uint2 raw = yy[u][i];
;             yv[i].x = bf2f((u16)(raw.x & 0xffff)); yv[i].y = bf2f((u16)(raw.x >> 16));
;             yv[i].z = bf2f((u16)(raw.y & 0xffff)); yv[i].w = bf2f((u16)(raw.y >> 16));
;             ss += yv[i].x * yv[i].x + yv[i].y * yv[i].y + yv[i].z * yv[i].z + yv[i].w * yv[i].w;
;           }
;           ss = wave_sum(ss);
;           const float rstd = __builtin_amdgcn_rsqf(ss * (1.f / 1024.f) + EPSF);
; #pragma unroll
;           for (int i = 0; i < 4; ++i) {
;             const int col = (i * 64 + lane) * 4;
;             const float4 gt = *reinterpret_cast<const float4*>(modg + gate_idx * 1024 + col);
;             const float4 gp = *reinterpret_cast<const float4*>(gpost + col);
;             xv[i].x += gt.x * (yv[i].x * rstd * gp.x); xv[i].y += gt.y * (yv[i].y * rstd * gp.y);
;             xv[i].z += gt.z * (yv[i].z * rstd * gp.z); xv[i].w += gt.w * (yv[i].w * rstd * gp.w);
;           }
;         }
;         if (xdst == 3 || (xdst == 1 && row >= N_X)) {
;           float* xout = (xdst == 3) ? P.out + (long)row * 1024 : P.xc + (long)(row - N_X) * 1024;
; #pragma unroll
;           for (int i = 0; i < 4; ++i) *reinterpret_cast<float4*>(xout + (i * 64 + lane) * 4) = xv[i];
;         } else if (xdst != 0) {
;           u16* xo = ((xdst == 1) ? resA : P.zf) + (long)row * 1024;
; #pragma unroll
;           for (int i = 0; i < 4; ++i) {
;             const unsigned b0 = f2bf(xv[i].x), b1 = f2bf(xv[i].y), b2 = f2bf(xv[i].z), b3 = f2bf(xv[i].w);
;             *reinterpret_cast<uint2*>(xo + (i * 64 + lane) * 4) = make_uint2(b0 | (b1 << 16), b2 | (b3 << 16));
;           }
;         }
;         if (doH) {
;           float ss = 0.f;
; #pragma unroll
;           for (int i = 0; i < 4; ++i) ss += xv[i].x * xv[i].x + xv[i].y * xv[i].y + xv[i].z * xv[i].z + xv[i].w * xv[i].w;
;           ss = wave_sum(ss);
;           const float rstd = __builtin_amdgcn_rsqf(ss * (1.f / 1024.f) + EPSF);
;           u16* h = P.hy + (long)row * 1024;
; #pragma unroll
	v_mul_f32_e32 v131, v27, v140
	v_mul_f32_e32 v132, v28, v140
	v_mul_f32_e32 v133, v29, v140
	v_mul_f32_e32 v134, v30, v140
	v_mul_f32_e32 v135, v31, v140
	v_fma_f32 v120, v120, v88, v104
	v_fma_f32 v121, v121, v89, v105
	v_fma_f32 v122, v122, v90, v106
	v_fma_f32 v123, v123, v91, v107
	v_fma_f32 v124, v124, v92, v108
	v_fma_f32 v125, v125, v93, v109
	v_fma_f32 v126, v126, v94, v110
	v_fma_f32 v127, v127, v95, v111
	v_fma_f32 v128, v128, v96, v112
	v_fma_f32 v129, v129, v97, v113
	v_fma_f32 v130, v130, v98, v114
	v_fma_f32 v131, v131, v99, v115
	v_fma_f32 v132, v132, v100, v116
	v_fma_f32 v133, v133, v101, v117
	v_fma_f32 v134, v134, v102, v118
	v_fma_f32 v135, v135, v103, v119
	v_cvt_pk_bf16_f32 v156, v120, v121
	v_cvt_pk_bf16_f32 v157, v122, v123
	v_cvt_pk_bf16_f32 v158, v124, v125
	v_cvt_pk_bf16_f32 v159, v126, v127
	v_cvt_pk_bf16_f32 v160, v128, v129
	v_cvt_pk_bf16_f32 v161, v130, v131
	v_cvt_pk_bf16_f32 v162, v132, v133
	v_cvt_pk_bf16_f32 v163, v134, v135
	s_lshl_b32 vcc_lo, s19, 11
	s_add_u32 vcc_lo, vcc_lo, 0x1c00000
	s_add_u32 s100, s14, vcc_lo
	s_addc_u32 s101, s15, 0
	global_store_dwordx2 v137, v[156:157], s[100:101] offset:0
	global_store_dwordx2 v137, v[158:159], s[100:101] offset:512
	global_store_dwordx2 v137, v[160:161], s[100:101] offset:1024
	global_store_dwordx2 v137, v[162:163], s[100:101] offset:1536
	s_add_u32 s100, s20, 0x2c000
	s_addc_u32 s101, s21, 0
	global_load_dwordx4 v[72:75], v136, s[100:101] offset:0
	global_load_dwordx4 v[76:79], v136, s[100:101] offset:1024
	global_load_dwordx4 v[80:83], v136, s[100:101] offset:2048
	global_load_dwordx4 v[84:87], v136, s[100:101] offset:3072
	s_load_dwordx2 s[98:99], s[4:5], 0x38
	s_waitcnt lgkmcnt(0)
	s_add_u32 s98, s98, 0x1000
	s_addc_u32 s99, s99, 0
	global_load_dwordx4 v[120:123], v136, s[98:99] offset:0
	global_load_dwordx4 v[124:127], v136, s[98:99] offset:1024
	global_load_dwordx4 v[128:131], v136, s[98:99] offset:2048
	global_load_dwordx4 v[132:135], v136, s[98:99] offset:3072
	s_add_u32 s100, s20, 0x2d000
	s_addc_u32 s101, s21, 0
	global_load_dwordx4 v[104:107], v136, s[100:101] offset:0
	global_load_dwordx4 v[108:111], v136, s[100:101] offset:1024
	global_load_dwordx4 v[112:115], v136, s[100:101] offset:2048
	global_load_dwordx4 v[116:119], v136, s[100:101] offset:3072
	s_add_u32 s100, s100, 0x1000
	s_addc_u32 s101, s101, 0
	global_load_dwordx4 v[16:19], v136, s[100:101] offset:0
	global_load_dwordx4 v[20:23], v136, s[100:101] offset:1024
	global_load_dwordx4 v[24:27], v136, s[100:101] offset:2048
	global_load_dwordx4 v[28:31], v136, s[100:101] offset:3072
	s_load_dwordx2 s[98:99], s[4:5], 0x40
	s_waitcnt lgkmcnt(0)
	s_add_u32 s98, s98, 0x1000
	s_addc_u32 s99, s99, 0
	global_load_dwordx4 v[88:91], v136, s[98:99] offset:0
	global_load_dwordx4 v[92:95], v136, s[98:99] offset:1024
	global_load_dwordx4 v[96:99], v136, s[98:99] offset:2048
	global_load_dwordx4 v[100:103], v136, s[98:99] offset:3072
	s_waitcnt vmcnt(0)
	v_mul_f32_e32 v72, v72, v120
	v_mul_f32_e32 v73, v73, v121
	v_mul_f32_e32 v74, v74, v122
	v_mul_f32_e32 v75, v75, v123
	v_mul_f32_e32 v76, v76, v124
	v_mul_f32_e32 v77, v77, v125
	v_mul_f32_e32 v78, v78, v126
	v_mul_f32_e32 v79, v79, v127
	v_mul_f32_e32 v80, v80, v128
	v_mul_f32_e32 v81, v81, v129
	v_mul_f32_e32 v82, v82, v130
	v_mul_f32_e32 v83, v83, v131
	v_mul_f32_e32 v84, v84, v132
	v_mul_f32_e32 v85, v85, v133
	v_mul_f32_e32 v86, v86, v134
	v_mul_f32_e32 v87, v87, v135
	v_fma_f32 v88, v88, v16, v88
	v_fma_f32 v89, v89, v17, v89
	v_fma_f32 v90, v90, v18, v90
	v_fma_f32 v91, v91, v19, v91
	v_fma_f32 v92, v92, v20, v92
	v_fma_f32 v93, v93, v21, v93
	v_fma_f32 v94, v94, v22, v94
	v_fma_f32 v95, v95, v23, v95
	v_fma_f32 v96, v96, v24, v96
	v_fma_f32 v97, v97, v25, v97
	v_fma_f32 v98, v98, v26, v98
	v_fma_f32 v99, v99, v27, v99
	v_fma_f32 v100, v100, v28, v100
	v_fma_f32 v101, v101, v29, v101
	v_fma_f32 v102, v102, v30, v102
	v_fma_f32 v103, v103, v31, v103
	s_lshl_b32 vcc_lo, s19, 11
	s_add_u32 vcc_lo, vcc_lo, 0x2800000
	s_add_u32 s100, s12, vcc_lo
	s_addc_u32 s101, s13, 0
	global_load_dwordx2 v[24:25], v137, s[100:101] offset:0
	global_load_dwordx2 v[26:27], v137, s[100:101] offset:512
	global_load_dwordx2 v[28:29], v137, s[100:101] offset:1024
	global_load_dwordx2 v[30:31], v137, s[100:101] offset:1536
	s_lshl_b32 vcc_lo, s19, 11
	s_add_u32 vcc_lo, vcc_lo, 0x2800000
	s_add_u32 s100, s14, vcc_lo
	s_addc_u32 s101, s15, 0
	global_load_dwordx2 v[56:57], v137, s[100:101] offset:0
	global_load_dwordx2 v[58:59], v137, s[100:101] offset:512
	global_load_dwordx2 v[60:61], v137, s[100:101] offset:1024
	global_load_dwordx2 v[62:63], v137, s[100:101] offset:1536
	v_lshlrev_b32_e32 v120, 16, v64
	v_and_b32_e32 v121, 0xffff0000, v64
	v_lshlrev_b32_e32 v122, 16, v65
	v_and_b32_e32 v123, 0xffff0000, v65
	v_lshlrev_b32_e32 v124, 16, v66
	v_and_b32_e32 v125, 0xffff0000, v66
	v_lshlrev_b32_e32 v126, 16, v67
	v_and_b32_e32 v127, 0xffff0000, v67
	v_lshlrev_b32_e32 v128, 16, v68
	v_and_b32_e32 v129, 0xffff0000, v68
	v_lshlrev_b32_e32 v130, 16, v69
	v_and_b32_e32 v131, 0xffff0000, v69
	v_lshlrev_b32_e32 v132, 16, v70
	v_and_b32_e32 v133, 0xffff0000, v70
	v_lshlrev_b32_e32 v134, 16, v71
	v_and_b32_e32 v135, 0xffff0000, v71
	v_mul_f32_e32 v138, v120, v120
	v_mul_f32_e32 v149, v121, v121
	v_mul_f32_e32 v150, v122, v122
	v_mul_f32_e32 v154, v123, v123
	v_fma_f32 v138, v124, v124, v138
	v_fma_f32 v149, v125, v125, v149
	v_fma_f32 v150, v126, v126, v150
	v_fma_f32 v154, v127, v127, v154
	v_fma_f32 v138, v128, v128, v138
	v_fma_f32 v149, v129, v129, v149
	v_fma_f32 v150, v130, v130, v150
	v_fma_f32 v154, v131, v131, v154
	v_fma_f32 v138, v132, v132, v138
	v_fma_f32 v149, v133, v133, v149
; __device__ __forceinline__ void row_phase(const Params& P, int glayer, int layer, int xsrc, bool hasY, int gate_idx, const float* gpost,
;                           int xdst, bool doH, const float* gpre, int sh_idx, int nrows) {
;     ...
;         if (hasY) {
;           float4 yv[4];
;           float ss = 0.f;
; #pragma unroll
;           for (int i = 0; i < 4; ++i) {
;             const uint2 raw = yy[u][i];
;             yv[i].x = bf2f((u16)(raw.x & 0xffff)); yv[i].y = bf2f((u16)(raw.x >> 16));
;             yv[i].z = bf2f((u16)(raw.y & 0xffff)); yv[i].w = bf2f((u16)(raw.y >> 16));
;             ss += yv[i].x * yv[i].x + yv[i].y * yv[i].y + yv[i].z * yv[i].z + yv[i].w * yv[i].w;
;           }
;           ss = wave_sum(ss);
;           const float rstd = __builtin_amdgcn_rsqf(ss * (1.f / 1024.f) + EPSF);
; #pragma unroll
;           for (int i = 0; i < 4; ++i) {
;             const int col = (i * 64 + lane) * 4;
;             const float4 gt = *reinterpret_cast<const float4*>(modg + gate_idx * 1024 + col);
;             const float4 gp = *reinterpret_cast<const float4*>(gpost + col);
;             xv[i].x += gt.x * (yv[i].x * rstd * gp.x); xv[i].y += gt.y * (yv[i].y * rstd * gp.y);
;             xv[i].z += gt.z * (yv[i].z * rstd * gp.z); xv[i].w += gt.w * (yv[i].w * rstd * gp.w);
;           }
;         }
;         if (xdst == 3 || (xdst == 1 && row >= N_X)) {
;           float* xout = (xdst == 3) ? P.out + (long)row * 1024 : P.xc + (long)(row - N_X) * 1024;
; #pragma unroll
;           for (int i = 0; i < 4; ++i) *reinterpret_cast<float4*>(xout + (i * 64 + lane) * 4) = xv[i];
;         } else if (xdst != 0) {
;           u16* xo = ((xdst == 1) ? resA : P.zf) + (long)row * 1024;
; #pragma unroll
;           for (int i = 0; i < 4; ++i) {
;             const unsigned b0 = f2bf(xv[i].x), b1 = f2bf(xv[i].y), b2 = f2bf(xv[i].z), b3 = f2bf(xv[i].w);
;             *reinterpret_cast<uint2*>(xo + (i * 64 + lane) * 4) = make_uint2(b0 | (b1 << 16), b2 | (b3 << 16));
;           }
;         }
;         if (doH) {
;           float ss = 0.f;
; #pragma unroll
;           for (int i = 0; i < 4; ++i) ss += xv[i].x * xv[i].x + xv[i].y * xv[i].y + xv[i].z * xv[i].z + xv[i].w * xv[i].w;
;           ss = wave_sum(ss);
;           const float rstd = __builtin_amdgcn_rsqf(ss * (1.f / 1024.f) + EPSF);
;           u16* h = P.hy + (long)row * 1024;
; #pragma unroll
	v_fma_f32 v150, v134, v134, v150
	v_fma_f32 v154, v135, v135, v154
	v_add_f32_e32 v138, v138, v149
	v_add_f32_e32 v150, v150, v154
	v_add_f32_e32 v138, v138, v150
	s_nop 1
	v_add_f32_dpp v138, v138, v138 quad_perm:[1,0,3,2] row_mask:0xf bank_mask:0xf
	s_nop 1
	v_add_f32_dpp v138, v138, v138 quad_perm:[2,3,0,1] row_mask:0xf bank_mask:0xf
	s_nop 1
	v_add_f32_dpp v138, v138, v138 row_half_mirror row_mask:0xf bank_mask:0xf
	s_nop 1
	v_add_f32_dpp v138, v138, v138 row_mirror row_mask:0xf bank_mask:0xf
	v_mov_b32_e32 v139, v138
	s_nop 1
	v_permlane16_swap_b32_e32 v138, v139
	v_add_f32_e32 v138, v138, v139
	v_mov_b32_e32 v139, v138
	s_nop 1
	v_permlane32_swap_b32_e32 v138, v139
	v_add_f32_e32 v138, v138, v139
	v_mul_f32_e32 v138, 0x3a800000, v138
	v_add_f32_e32 v138, 0x358637bd, v138
	v_rsq_f32_e32 v140, v138
	v_lshlrev_b32_e32 v32, 16, v40
	v_and_b32_e32 v33, 0xffff0000, v40
	v_lshlrev_b32_e32 v34, 16, v41
	v_and_b32_e32 v35, 0xffff0000, v41
	v_lshlrev_b32_e32 v36, 16, v42
	v_and_b32_e32 v37, 0xffff0000, v42
	v_lshlrev_b32_e32 v38, 16, v43
	v_and_b32_e32 v39, 0xffff0000, v43
	v_lshlrev_b32_e32 v40, 16, v44
	v_and_b32_e32 v41, 0xffff0000, v44
	v_lshlrev_b32_e32 v42, 16, v45
	v_and_b32_e32 v43, 0xffff0000, v45
	v_lshlrev_b32_e32 v44, 16, v46
	v_and_b32_e32 v45, 0xffff0000, v46
	v_lshlrev_b32_e32 v46, 16, v47
	v_and_b32_e32 v47, 0xffff0000, v47
	s_nop 0
	v_mul_f32_e32 v120, v120, v140
	v_mul_f32_e32 v121, v121, v140
	v_mul_f32_e32 v122, v122, v140
	v_mul_f32_e32 v123, v123, v140
	v_mul_f32_e32 v124, v124, v140
	v_mul_f32_e32 v125, v125, v140
	v_mul_f32_e32 v126, v126, v140
	v_mul_f32_e32 v127, v127, v140
	v_mul_f32_e32 v128, v128, v140
	v_mul_f32_e32 v129, v129, v140
	v_mul_f32_e32 v130, v130, v140
	v_mul_f32_e32 v131, v131, v140
	v_mul_f32_e32 v132, v132, v140
	v_mul_f32_e32 v133, v133, v140
	v_mul_f32_e32 v134, v134, v140
	v_mul_f32_e32 v135, v135, v140
	v_fma_f32 v32, v120, v72, v32
	v_fma_f32 v33, v121, v73, v33
	v_fma_f32 v34, v122, v74, v34
	v_fma_f32 v35, v123, v75, v35
	v_fma_f32 v36, v124, v76, v36
	v_fma_f32 v37, v125, v77, v37
	v_fma_f32 v38, v126, v78, v38
	v_fma_f32 v39, v127, v79, v39
	v_fma_f32 v40, v128, v80, v40
	v_fma_f32 v41, v129, v81, v41
	v_fma_f32 v42, v130, v82, v42
	v_fma_f32 v43, v131, v83, v43
	v_fma_f32 v44, v132, v84, v44
	v_fma_f32 v45, v133, v85, v45
	v_fma_f32 v46, v134, v86, v46
	v_fma_f32 v47, v135, v87, v47
	v_cvt_pk_bf16_f32 v156, v32, v33
	v_cvt_pk_bf16_f32 v157, v34, v35
	v_cvt_pk_bf16_f32 v158, v36, v37
	v_cvt_pk_bf16_f32 v159, v38, v39
	v_cvt_pk_bf16_f32 v160, v40, v41
	v_cvt_pk_bf16_f32 v161, v42, v43
	v_cvt_pk_bf16_f32 v162, v44, v45
	v_cvt_pk_bf16_f32 v163, v46, v47
	s_lshl_b32 vcc_lo, s19, 11
	s_add_u32 vcc_lo, vcc_lo, 0x2000000
	s_add_u32 s100, s16, vcc_lo
	s_addc_u32 s101, s17, 0
	global_store_dwordx2 v137, v[156:157], s[100:101] offset:0
	global_store_dwordx2 v137, v[158:159], s[100:101] offset:512
	global_store_dwordx2 v137, v[160:161], s[100:101] offset:1024
	global_store_dwordx2 v137, v[162:163], s[100:101] offset:1536
	v_mul_f32_e32 v138, v32, v32
	v_mul_f32_e32 v149, v33, v33
	v_mul_f32_e32 v150, v34, v34
	v_mul_f32_e32 v154, v35, v35
	v_fma_f32 v138, v36, v36, v138
	v_fma_f32 v149, v37, v37, v149
	v_fma_f32 v150, v38, v38, v150
	v_fma_f32 v154, v39, v39, v154
	v_fma_f32 v138, v40, v40, v138
	v_fma_f32 v149, v41, v41, v149
	v_fma_f32 v150, v42, v42, v150
	v_fma_f32 v154, v43, v43, v154
	v_fma_f32 v138, v44, v44, v138
	v_fma_f32 v149, v45, v45, v149
	v_fma_f32 v150, v46, v46, v150
	v_fma_f32 v154, v47, v47, v154
	v_add_f32_e32 v138, v138, v149
	v_add_f32_e32 v150, v150, v154
	v_add_f32_e32 v138, v138, v150
	s_nop 1
	v_add_f32_dpp v138, v138, v138 quad_perm:[1,0,3,2] row_mask:0xf bank_mask:0xf
	s_nop 1
	v_add_f32_dpp v138, v138, v138 quad_perm:[2,3,0,1] row_mask:0xf bank_mask:0xf
	s_nop 1
	v_add_f32_dpp v138, v138, v138 row_half_mirror row_mask:0xf bank_mask:0xf
	s_nop 1
	v_add_f32_dpp v138, v138, v138 row_mirror row_mask:0xf bank_mask:0xf
	v_mov_b32_e32 v139, v138
	s_nop 1
	v_permlane16_swap_b32_e32 v138, v139
	v_add_f32_e32 v138, v138, v139
	v_mov_b32_e32 v139, v138
	s_nop 1
	v_permlane32_swap_b32_e32 v138, v139
	v_add_f32_e32 v138, v138, v139
	v_mul_f32_e32 v138, 0x3a800000, v138
	v_add_f32_e32 v138, 0x358637bd, v138
	v_rsq_f32_e32 v140, v138
	s_nop 0
	v_mul_f32_e32 v120, v32, v140
	v_mul_f32_e32 v121, v33, v140
	v_mul_f32_e32 v122, v34, v140
	v_mul_f32_e32 v123, v35, v140
	v_mul_f32_e32 v124, v36, v140
	v_mul_f32_e32 v125, v37, v140
	v_mul_f32_e32 v126, v38, v140
	v_mul_f32_e32 v127, v39, v140
	v_mul_f32_e32 v128, v40, v140
	v_mul_f32_e32 v129, v41, v140
	v_mul_f32_e32 v130, v42, v140
	v_mul_f32_e32 v131, v43, v140
	v_mul_f32_e32 v132, v44, v140
	v_mul_f32_e32 v133, v45, v140
	v_mul_f32_e32 v134, v46, v140
	v_mul_f32_e32 v135, v47, v140
	v_fma_f32 v120, v120, v88, v104
	v_fma_f32 v121, v121, v89, v105
	v_fma_f32 v122, v122, v90, v106
	v_fma_f32 v123, v123, v91, v107
	v_fma_f32 v124, v124, v92, v108
	v_fma_f32 v125, v125, v93, v109
	v_fma_f32 v126, v126, v94, v110
	v_fma_f32 v127, v127, v95, v111
	v_fma_f32 v128, v128, v96, v112
	v_fma_f32 v129, v129, v97, v113
	v_fma_f32 v130, v130, v98, v114
	v_fma_f32 v131, v131, v99, v115
	v_fma_f32 v132, v132, v100, v116
	v_fma_f32 v133, v133, v101, v117
	v_fma_f32 v134, v134, v102, v118
	v_fma_f32 v135, v135, v103, v119
	v_cvt_pk_bf16_f32 v156, v120, v121
	v_cvt_pk_bf16_f32 v157, v122, v123
	v_cvt_pk_bf16_f32 v158, v124, v125
	v_cvt_pk_bf16_f32 v159, v126, v127
	v_cvt_pk_bf16_f32 v160, v128, v129
	v_cvt_pk_bf16_f32 v161, v130, v131
	v_cvt_pk_bf16_f32 v162, v132, v133
	v_cvt_pk_bf16_f32 v163, v134, v135
	s_lshl_b32 vcc_lo, s19, 11
	s_add_u32 vcc_lo, vcc_lo, 0x2000000
; __device__ __forceinline__ void row_phase(const Params& P, int glayer, int layer, int xsrc, bool hasY, int gate_idx, const float* gpost,
;                           int xdst, bool doH, const float* gpre, int sh_idx, int nrows) {
;     ...
;         if (hasY) {
;           float4 yv[4];
;           float ss = 0.f;
; #pragma unroll
;           for (int i = 0; i < 4; ++i) {
;             const uint2 raw = yy[u][i];
;             yv[i].x = bf2f((u16)(raw.x & 0xffff)); yv[i].y = bf2f((u16)(raw.x >> 16));
;             yv[i].z = bf2f((u16)(raw.y & 0xffff)); yv[i].w = bf2f((u16)(raw.y >> 16));
;             ss += yv[i].x * yv[i].x + yv[i].y * yv[i].y + yv[i].z * yv[i].z + yv[i].w * yv[i].w;
;           }
;           ss = wave_sum(ss);
;           const float rstd = __builtin_amdgcn_rsqf(ss * (1.f / 1024.f) + EPSF);
; #pragma unroll
;           for (int i = 0; i < 4; ++i) {
;             const int col = (i * 64 + lane) * 4;
;             const float4 gt = *reinterpret_cast<const float4*>(modg + gate_idx * 1024 + col);
;             const float4 gp = *reinterpret_cast<const float4*>(gpost + col);
;             xv[i].x += gt.x * (yv[i].x * rstd * gp.x); xv[i].y += gt.y * (yv[i].y * rstd * gp.y);
;             xv[i].z += gt.z * (yv[i].z * rstd * gp.z); xv[i].w += gt.w * (yv[i].w * rstd * gp.w);
;           }
;         }
;         if (xdst == 3 || (xdst == 1 && row >= N_X)) {
;           float* xout = (xdst == 3) ? P.out + (long)row * 1024 : P.xc + (long)(row - N_X) * 1024;
; #pragma unroll
;           for (int i = 0; i < 4; ++i) *reinterpret_cast<float4*>(xout + (i * 64 + lane) * 4) = xv[i];
;         } else if (xdst != 0) {
;           u16* xo = ((xdst == 1) ? resA : P.zf) + (long)row * 1024;
; #pragma unroll
;           for (int i = 0; i < 4; ++i) {
;             const unsigned b0 = f2bf(xv[i].x), b1 = f2bf(xv[i].y), b2 = f2bf(xv[i].z), b3 = f2bf(xv[i].w);
;             *reinterpret_cast<uint2*>(xo + (i * 64 + lane) * 4) = make_uint2(b0 | (b1 << 16), b2 | (b3 << 16));
;           }
;         }
;         if (doH) {
;           float ss = 0.f;
; #pragma unroll
;           for (int i = 0; i < 4; ++i) ss += xv[i].x * xv[i].x + xv[i].y * xv[i].y + xv[i].z * xv[i].z + xv[i].w * xv[i].w;
;           ss = wave_sum(ss);
;           const float rstd = __builtin_amdgcn_rsqf(ss * (1.f / 1024.f) + EPSF);
;           u16* h = P.hy + (long)row * 1024;
; #pragma unroll
	s_add_u32 s100, s14, vcc_lo
	s_addc_u32 s101, s15, 0
	global_store_dwordx2 v137, v[156:157], s[100:101] offset:0
	global_store_dwordx2 v137, v[158:159], s[100:101] offset:512
	global_store_dwordx2 v137, v[160:161], s[100:101] offset:1024
	global_store_dwordx2 v137, v[162:163], s[100:101] offset:1536
	s_lshl_b32 vcc_lo, s19, 11
	s_add_u32 vcc_lo, vcc_lo, 0x2c00000
	s_add_u32 s100, s12, vcc_lo
	s_addc_u32 s101, s13, 0
	global_load_dwordx2 v[40:41], v137, s[100:101] offset:0
	global_load_dwordx2 v[42:43], v137, s[100:101] offset:512
	global_load_dwordx2 v[44:45], v137, s[100:101] offset:1024
	global_load_dwordx2 v[46:47], v137, s[100:101] offset:1536
	s_lshl_b32 vcc_lo, s19, 11
	s_add_u32 vcc_lo, vcc_lo, 0x2c00000
	s_add_u32 s100, s14, vcc_lo
	s_addc_u32 s101, s15, 0
	global_load_dwordx2 v[64:65], v137, s[100:101] offset:0
	global_load_dwordx2 v[66:67], v137, s[100:101] offset:512
	global_load_dwordx2 v[68:69], v137, s[100:101] offset:1024
	global_load_dwordx2 v[70:71], v137, s[100:101] offset:1536
	v_lshlrev_b32_e32 v120, 16, v48
	v_and_b32_e32 v121, 0xffff0000, v48
	v_lshlrev_b32_e32 v122, 16, v49
	v_and_b32_e32 v123, 0xffff0000, v49
	v_lshlrev_b32_e32 v124, 16, v50
	v_and_b32_e32 v125, 0xffff0000, v50
	v_lshlrev_b32_e32 v126, 16, v51
	v_and_b32_e32 v127, 0xffff0000, v51
	v_lshlrev_b32_e32 v128, 16, v52
	v_and_b32_e32 v129, 0xffff0000, v52
	v_lshlrev_b32_e32 v130, 16, v53
	v_and_b32_e32 v131, 0xffff0000, v53
	v_lshlrev_b32_e32 v132, 16, v54
	v_and_b32_e32 v133, 0xffff0000, v54
	v_lshlrev_b32_e32 v134, 16, v55
	v_and_b32_e32 v135, 0xffff0000, v55
	v_mul_f32_e32 v138, v120, v120
	v_mul_f32_e32 v149, v121, v121
	v_mul_f32_e32 v150, v122, v122
	v_mul_f32_e32 v154, v123, v123
	v_fma_f32 v138, v124, v124, v138
	v_fma_f32 v149, v125, v125, v149
	v_fma_f32 v150, v126, v126, v150
	v_fma_f32 v154, v127, v127, v154
	v_fma_f32 v138, v128, v128, v138
	v_fma_f32 v149, v129, v129, v149
	v_fma_f32 v150, v130, v130, v150
	v_fma_f32 v154, v131, v131, v154
	v_fma_f32 v138, v132, v132, v138
	v_fma_f32 v149, v133, v133, v149
	v_fma_f32 v150, v134, v134, v150
	v_fma_f32 v154, v135, v135, v154
	v_add_f32_e32 v138, v138, v149
	v_add_f32_e32 v150, v150, v154
	v_add_f32_e32 v138, v138, v150
	s_nop 1
	v_add_f32_dpp v138, v138, v138 quad_perm:[1,0,3,2] row_mask:0xf bank_mask:0xf
	s_nop 1
	v_add_f32_dpp v138, v138, v138 quad_perm:[2,3,0,1] row_mask:0xf bank_mask:0xf
	s_nop 1
	v_add_f32_dpp v138, v138, v138 row_half_mirror row_mask:0xf bank_mask:0xf
	s_nop 1
	v_add_f32_dpp v138, v138, v138 row_mirror row_mask:0xf bank_mask:0xf
	v_mov_b32_e32 v139, v138
	s_nop 1
	v_permlane16_swap_b32_e32 v138, v139
	v_add_f32_e32 v138, v138, v139
	v_mov_b32_e32 v139, v138
	s_nop 1
	v_permlane32_swap_b32_e32 v138, v139
	v_add_f32_e32 v138, v138, v139
	v_mul_f32_e32 v138, 0x3a800000, v138
	v_add_f32_e32 v138, 0x358637bd, v138
	v_rsq_f32_e32 v140, v138
	v_lshlrev_b32_e32 v0, 16, v8
	v_and_b32_e32 v1, 0xffff0000, v8
	v_lshlrev_b32_e32 v2, 16, v9
	v_and_b32_e32 v3, 0xffff0000, v9
	v_lshlrev_b32_e32 v4, 16, v10
	v_and_b32_e32 v5, 0xffff0000, v10
	v_lshlrev_b32_e32 v6, 16, v11
	v_and_b32_e32 v7, 0xffff0000, v11
	v_lshlrev_b32_e32 v8, 16, v12
	v_and_b32_e32 v9, 0xffff0000, v12
	v_lshlrev_b32_e32 v10, 16, v13
	v_and_b32_e32 v11, 0xffff0000, v13
	v_lshlrev_b32_e32 v12, 16, v14
	v_and_b32_e32 v13, 0xffff0000, v14
	v_lshlrev_b32_e32 v14, 16, v15
	v_and_b32_e32 v15, 0xffff0000, v15
	s_nop 0
	v_mul_f32_e32 v120, v120, v140
	v_mul_f32_e32 v121, v121, v140
	v_mul_f32_e32 v122, v122, v140
	v_mul_f32_e32 v123, v123, v140
	v_mul_f32_e32 v124, v124, v140
	v_mul_f32_e32 v125, v125, v140
	v_mul_f32_e32 v126, v126, v140
	v_mul_f32_e32 v127, v127, v140
	v_mul_f32_e32 v128, v128, v140
	v_mul_f32_e32 v129, v129, v140
	v_mul_f32_e32 v130, v130, v140
	v_mul_f32_e32 v131, v131, v140
	v_mul_f32_e32 v132, v132, v140
	v_mul_f32_e32 v133, v133, v140
	v_mul_f32_e32 v134, v134, v140
	v_mul_f32_e32 v135, v135, v140
	v_fma_f32 v0, v120, v72, v0
	v_fma_f32 v1, v121, v73, v1
	v_fma_f32 v2, v122, v74, v2
	v_fma_f32 v3, v123, v75, v3
	v_fma_f32 v4, v124, v76, v4
	v_fma_f32 v5, v125, v77, v5
	v_fma_f32 v6, v126, v78, v6
	v_fma_f32 v7, v127, v79, v7
	v_fma_f32 v8, v128, v80, v8
	v_fma_f32 v9, v129, v81, v9
	v_fma_f32 v10, v130, v82, v10
	v_fma_f32 v11, v131, v83, v11
	v_fma_f32 v12, v132, v84, v12
	v_fma_f32 v13, v133, v85, v13
	v_fma_f32 v14, v134, v86, v14
	v_fma_f32 v15, v135, v87, v15
	v_cvt_pk_bf16_f32 v156, v0, v1
	v_cvt_pk_bf16_f32 v157, v2, v3
	v_cvt_pk_bf16_f32 v158, v4, v5
	v_cvt_pk_bf16_f32 v159, v6, v7
	v_cvt_pk_bf16_f32 v160, v8, v9
	v_cvt_pk_bf16_f32 v161, v10, v11
	v_cvt_pk_bf16_f32 v162, v12, v13
	v_cvt_pk_bf16_f32 v163, v14, v15
	s_lshl_b32 vcc_lo, s19, 11
	s_add_u32 vcc_lo, vcc_lo, 0x2400000
	s_add_u32 s100, s16, vcc_lo
	s_addc_u32 s101, s17, 0
	global_store_dwordx2 v137, v[156:157], s[100:101] offset:0
	global_store_dwordx2 v137, v[158:159], s[100:101] offset:512
	global_store_dwordx2 v137, v[160:161], s[100:101] offset:1024
	global_store_dwordx2 v137, v[162:163], s[100:101] offset:1536
	v_mul_f32_e32 v138, v0, v0
	v_mul_f32_e32 v149, v1, v1
	v_mul_f32_e32 v150, v2, v2
	v_mul_f32_e32 v154, v3, v3
	v_fma_f32 v138, v4, v4, v138
	v_fma_f32 v149, v5, v5, v149
	v_fma_f32 v150, v6, v6, v150
	v_fma_f32 v154, v7, v7, v154
	v_fma_f32 v138, v8, v8, v138
	v_fma_f32 v149, v9, v9, v149
	v_fma_f32 v150, v10, v10, v150
	v_fma_f32 v154, v11, v11, v154
	v_fma_f32 v138, v12, v12, v138
	v_fma_f32 v149, v13, v13, v149
	v_fma_f32 v150, v14, v14, v150
	v_fma_f32 v154, v15, v15, v154
	v_add_f32_e32 v138, v138, v149
	v_add_f32_e32 v150, v150, v154
	v_add_f32_e32 v138, v138, v150
	s_nop 1
	v_add_f32_dpp v138, v138, v138 quad_perm:[1,0,3,2] row_mask:0xf bank_mask:0xf
; __device__ __forceinline__ void row_phase(const Params& P, int glayer, int layer, int xsrc, bool hasY, int gate_idx, const float* gpost,
;                           int xdst, bool doH, const float* gpre, int sh_idx, int nrows) {
;     ...
;         if (hasY) {
;           float4 yv[4];
;           float ss = 0.f;
; #pragma unroll
;           for (int i = 0; i < 4; ++i) {
;             const uint2 raw = yy[u][i];
;             yv[i].x = bf2f((u16)(raw.x & 0xffff)); yv[i].y = bf2f((u16)(raw.x >> 16));
;             yv[i].z = bf2f((u16)(raw.y & 0xffff)); yv[i].w = bf2f((u16)(raw.y >> 16));
;             ss += yv[i].x * yv[i].x + yv[i].y * yv[i].y + yv[i].z * yv[i].z + yv[i].w * yv[i].w;
;           }
;           ss = wave_sum(ss);
;           const float rstd = __builtin_amdgcn_rsqf(ss * (1.f / 1024.f) + EPSF);
; #pragma unroll
;           for (int i = 0; i < 4; ++i) {
;             const int col = (i * 64 + lane) * 4;
;             const float4 gt = *reinterpret_cast<const float4*>(modg + gate_idx * 1024 + col);
;             const float4 gp = *reinterpret_cast<const float4*>(gpost + col);
;             xv[i].x += gt.x * (yv[i].x * rstd * gp.x); xv[i].y += gt.y * (yv[i].y * rstd * gp.y);
;             xv[i].z += gt.z * (yv[i].z * rstd * gp.z); xv[i].w += gt.w * (yv[i].w * rstd * gp.w);
;           }
;         }
;         if (xdst == 3 || (xdst == 1 && row >= N_X)) {
;           float* xout = (xdst == 3) ? P.out + (long)row * 1024 : P.xc + (long)(row - N_X) * 1024;
; #pragma unroll
;           for (int i = 0; i < 4; ++i) *reinterpret_cast<float4*>(xout + (i * 64 + lane) * 4) = xv[i];
;         } else if (xdst != 0) {
;           u16* xo = ((xdst == 1) ? resA : P.zf) + (long)row * 1024;
; #pragma unroll
;           for (int i = 0; i < 4; ++i) {
;             const unsigned b0 = f2bf(xv[i].x), b1 = f2bf(xv[i].y), b2 = f2bf(xv[i].z), b3 = f2bf(xv[i].w);
;             *reinterpret_cast<uint2*>(xo + (i * 64 + lane) * 4) = make_uint2(b0 | (b1 << 16), b2 | (b3 << 16));
;           }
;         }
;         if (doH) {
;           float ss = 0.f;
; #pragma unroll
;           for (int i = 0; i < 4; ++i) ss += xv[i].x * xv[i].x + xv[i].y * xv[i].y + xv[i].z * xv[i].z + xv[i].w * xv[i].w;
;           ss = wave_sum(ss);
;           const float rstd = __builtin_amdgcn_rsqf(ss * (1.f / 1024.f) + EPSF);
;           u16* h = P.hy + (long)row * 1024;
; #pragma unroll
	s_nop 1
	v_add_f32_dpp v138, v138, v138 quad_perm:[2,3,0,1] row_mask:0xf bank_mask:0xf
	s_nop 1
	v_add_f32_dpp v138, v138, v138 row_half_mirror row_mask:0xf bank_mask:0xf
	s_nop 1
	v_add_f32_dpp v138, v138, v138 row_mirror row_mask:0xf bank_mask:0xf
	v_mov_b32_e32 v139, v138
	s_nop 1
	v_permlane16_swap_b32_e32 v138, v139
	v_add_f32_e32 v138, v138, v139
	v_mov_b32_e32 v139, v138
	s_nop 1
	v_permlane32_swap_b32_e32 v138, v139
	v_add_f32_e32 v138, v138, v139
	v_mul_f32_e32 v138, 0x3a800000, v138
	v_add_f32_e32 v138, 0x358637bd, v138
	v_rsq_f32_e32 v140, v138
	s_nop 0
	v_mul_f32_e32 v120, v0, v140
	v_mul_f32_e32 v121, v1, v140
	v_mul_f32_e32 v122, v2, v140
	v_mul_f32_e32 v123, v3, v140
	v_mul_f32_e32 v124, v4, v140
	v_mul_f32_e32 v125, v5, v140
	v_mul_f32_e32 v126, v6, v140
	v_mul_f32_e32 v127, v7, v140
	v_mul_f32_e32 v128, v8, v140
	v_mul_f32_e32 v129, v9, v140
	v_mul_f32_e32 v130, v10, v140
	v_mul_f32_e32 v131, v11, v140
	v_mul_f32_e32 v132, v12, v140
	v_mul_f32_e32 v133, v13, v140
	v_mul_f32_e32 v134, v14, v140
	v_mul_f32_e32 v135, v15, v140
	v_fma_f32 v120, v120, v88, v104
	v_fma_f32 v121, v121, v89, v105
	v_fma_f32 v122, v122, v90, v106
	v_fma_f32 v123, v123, v91, v107
	v_fma_f32 v124, v124, v92, v108
	v_fma_f32 v125, v125, v93, v109
	v_fma_f32 v126, v126, v94, v110
	v_fma_f32 v127, v127, v95, v111
	v_fma_f32 v128, v128, v96, v112
	v_fma_f32 v129, v129, v97, v113
	v_fma_f32 v130, v130, v98, v114
	v_fma_f32 v131, v131, v99, v115
	v_fma_f32 v132, v132, v100, v116
	v_fma_f32 v133, v133, v101, v117
	v_fma_f32 v134, v134, v102, v118
	v_fma_f32 v135, v135, v103, v119
	v_cvt_pk_bf16_f32 v156, v120, v121
	v_cvt_pk_bf16_f32 v157, v122, v123
	v_cvt_pk_bf16_f32 v158, v124, v125
	v_cvt_pk_bf16_f32 v159, v126, v127
	v_cvt_pk_bf16_f32 v160, v128, v129
	v_cvt_pk_bf16_f32 v161, v130, v131
	v_cvt_pk_bf16_f32 v162, v132, v133
	v_cvt_pk_bf16_f32 v163, v134, v135
	s_lshl_b32 vcc_lo, s19, 11
	s_add_u32 vcc_lo, vcc_lo, 0x2400000
	s_add_u32 s100, s14, vcc_lo
	s_addc_u32 s101, s15, 0
	global_store_dwordx2 v137, v[156:157], s[100:101] offset:0
	global_store_dwordx2 v137, v[158:159], s[100:101] offset:512
	global_store_dwordx2 v137, v[160:161], s[100:101] offset:1024
	global_store_dwordx2 v137, v[162:163], s[100:101] offset:1536
	s_lshl_b32 vcc_lo, s19, 11
	s_add_u32 vcc_lo, vcc_lo, 0x3000000
	s_add_u32 s100, s12, vcc_lo
	s_addc_u32 s101, s13, 0
	global_load_dwordx2 v[8:9], v137, s[100:101] offset:0
	global_load_dwordx2 v[10:11], v137, s[100:101] offset:512
	global_load_dwordx2 v[12:13], v137, s[100:101] offset:1024
	global_load_dwordx2 v[14:15], v137, s[100:101] offset:1536
	s_lshl_b32 vcc_lo, s19, 11
	s_add_u32 vcc_lo, vcc_lo, 0x3000000
	s_add_u32 s100, s14, vcc_lo
	s_addc_u32 s101, s15, 0
	global_load_dwordx2 v[48:49], v137, s[100:101] offset:0
	global_load_dwordx2 v[50:51], v137, s[100:101] offset:512
	global_load_dwordx2 v[52:53], v137, s[100:101] offset:1024
	global_load_dwordx2 v[54:55], v137, s[100:101] offset:1536
	s_waitcnt vmcnt(32)
	v_lshlrev_b32_e32 v120, 16, v56
	v_and_b32_e32 v121, 0xffff0000, v56
	v_lshlrev_b32_e32 v122, 16, v57
	v_and_b32_e32 v123, 0xffff0000, v57
	v_lshlrev_b32_e32 v124, 16, v58
	v_and_b32_e32 v125, 0xffff0000, v58
	v_lshlrev_b32_e32 v126, 16, v59
	v_and_b32_e32 v127, 0xffff0000, v59
	v_lshlrev_b32_e32 v128, 16, v60
	v_and_b32_e32 v129, 0xffff0000, v60
	v_lshlrev_b32_e32 v130, 16, v61
	v_and_b32_e32 v131, 0xffff0000, v61
	v_lshlrev_b32_e32 v132, 16, v62
	v_and_b32_e32 v133, 0xffff0000, v62
	v_lshlrev_b32_e32 v134, 16, v63
	v_and_b32_e32 v135, 0xffff0000, v63
	v_mul_f32_e32 v138, v120, v120
	v_mul_f32_e32 v149, v121, v121
	v_mul_f32_e32 v150, v122, v122
	v_mul_f32_e32 v154, v123, v123
	v_fma_f32 v138, v124, v124, v138
	v_fma_f32 v149, v125, v125, v149
	v_fma_f32 v150, v126, v126, v150
	v_fma_f32 v154, v127, v127, v154
	v_fma_f32 v138, v128, v128, v138
	v_fma_f32 v149, v129, v129, v149
	v_fma_f32 v150, v130, v130, v150
	v_fma_f32 v154, v131, v131, v154
	v_fma_f32 v138, v132, v132, v138
	v_fma_f32 v149, v133, v133, v149
	v_fma_f32 v150, v134, v134, v150
	v_fma_f32 v154, v135, v135, v154
	v_add_f32_e32 v138, v138, v149
	v_add_f32_e32 v150, v150, v154
	v_add_f32_e32 v138, v138, v150
	s_nop 1
	v_add_f32_dpp v138, v138, v138 quad_perm:[1,0,3,2] row_mask:0xf bank_mask:0xf
	s_nop 1
	v_add_f32_dpp v138, v138, v138 quad_perm:[2,3,0,1] row_mask:0xf bank_mask:0xf
	s_nop 1
	v_add_f32_dpp v138, v138, v138 row_half_mirror row_mask:0xf bank_mask:0xf
	s_nop 1
	v_add_f32_dpp v138, v138, v138 row_mirror row_mask:0xf bank_mask:0xf
	v_mov_b32_e32 v139, v138
	s_nop 1
	v_permlane16_swap_b32_e32 v138, v139
	v_add_f32_e32 v138, v138, v139
	v_mov_b32_e32 v139, v138
	s_nop 1
	v_permlane32_swap_b32_e32 v138, v139
	v_add_f32_e32 v138, v138, v139
	v_mul_f32_e32 v138, 0x3a800000, v138
	v_add_f32_e32 v138, 0x358637bd, v138
	v_rsq_f32_e32 v140, v138
	v_lshlrev_b32_e32 v16, 16, v24
	v_and_b32_e32 v17, 0xffff0000, v24
	v_lshlrev_b32_e32 v18, 16, v25
	v_and_b32_e32 v19, 0xffff0000, v25
	v_lshlrev_b32_e32 v20, 16, v26
	v_and_b32_e32 v21, 0xffff0000, v26
	v_lshlrev_b32_e32 v22, 16, v27
	v_and_b32_e32 v23, 0xffff0000, v27
	v_lshlrev_b32_e32 v24, 16, v28
	v_and_b32_e32 v25, 0xffff0000, v28
	v_lshlrev_b32_e32 v26, 16, v29
	v_and_b32_e32 v27, 0xffff0000, v29
	v_lshlrev_b32_e32 v28, 16, v30
	v_and_b32_e32 v29, 0xffff0000, v30
	v_lshlrev_b32_e32 v30, 16, v31
	v_and_b32_e32 v31, 0xffff0000, v31
	s_nop 0
	v_mul_f32_e32 v120, v120, v140
	v_mul_f32_e32 v121, v121, v140
	v_mul_f32_e32 v122, v122, v140
	v_mul_f32_e32 v123, v123, v140
	v_mul_f32_e32 v124, v124, v140
	v_mul_f32_e32 v125, v125, v140
	v_mul_f32_e32 v126, v126, v140
	v_mul_f32_e32 v127, v127, v140
; __device__ __forceinline__ void row_phase(const Params& P, int glayer, int layer, int xsrc, bool hasY, int gate_idx, const float* gpost,
;                           int xdst, bool doH, const float* gpre, int sh_idx, int nrows) {
;     ...
;         if (hasY) {
;           float4 yv[4];
;           float ss = 0.f;
; #pragma unroll
;           for (int i = 0; i < 4; ++i) {
;             const uint2 raw = yy[u][i];
;             yv[i].x = bf2f((u16)(raw.x & 0xffff)); yv[i].y = bf2f((u16)(raw.x >> 16));
;             yv[i].z = bf2f((u16)(raw.y & 0xffff)); yv[i].w = bf2f((u16)(raw.y >> 16));
;             ss += yv[i].x * yv[i].x + yv[i].y * yv[i].y + yv[i].z * yv[i].z + yv[i].w * yv[i].w;
;           }
;           ss = wave_sum(ss);
;           const float rstd = __builtin_amdgcn_rsqf(ss * (1.f / 1024.f) + EPSF);
; #pragma unroll
;           for (int i = 0; i < 4; ++i) {
;             const int col = (i * 64 + lane) * 4;
;             const float4 gt = *reinterpret_cast<const float4*>(modg + gate_idx * 1024 + col);
;             const float4 gp = *reinterpret_cast<const float4*>(gpost + col);
;             xv[i].x += gt.x * (yv[i].x * rstd * gp.x); xv[i].y += gt.y * (yv[i].y * rstd * gp.y);
;             xv[i].z += gt.z * (yv[i].z * rstd * gp.z); xv[i].w += gt.w * (yv[i].w * rstd * gp.w);
;           }
;         }
;         if (xdst == 3 || (xdst == 1 && row >= N_X)) {
;           float* xout = (xdst == 3) ? P.out + (long)row * 1024 : P.xc + (long)(row - N_X) * 1024;
; #pragma unroll
;           for (int i = 0; i < 4; ++i) *reinterpret_cast<float4*>(xout + (i * 64 + lane) * 4) = xv[i];
;         } else if (xdst != 0) {
;           u16* xo = ((xdst == 1) ? resA : P.zf) + (long)row * 1024;
; #pragma unroll
;           for (int i = 0; i < 4; ++i) {
;             const unsigned b0 = f2bf(xv[i].x), b1 = f2bf(xv[i].y), b2 = f2bf(xv[i].z), b3 = f2bf(xv[i].w);
;             *reinterpret_cast<uint2*>(xo + (i * 64 + lane) * 4) = make_uint2(b0 | (b1 << 16), b2 | (b3 << 16));
;           }
;         }
;         if (doH) {
;           float ss = 0.f;
; #pragma unroll
;           for (int i = 0; i < 4; ++i) ss += xv[i].x * xv[i].x + xv[i].y * xv[i].y + xv[i].z * xv[i].z + xv[i].w * xv[i].w;
;           ss = wave_sum(ss);
;           const float rstd = __builtin_amdgcn_rsqf(ss * (1.f / 1024.f) + EPSF);
;           u16* h = P.hy + (long)row * 1024;
; #pragma unroll
	v_mul_f32_e32 v128, v128, v140
	v_mul_f32_e32 v129, v129, v140
	v_mul_f32_e32 v130, v130, v140
	v_mul_f32_e32 v131, v131, v140
	v_mul_f32_e32 v132, v132, v140
	v_mul_f32_e32 v133, v133, v140
	v_mul_f32_e32 v134, v134, v140
	v_mul_f32_e32 v135, v135, v140
	v_fma_f32 v16, v120, v72, v16
	v_fma_f32 v17, v121, v73, v17
	v_fma_f32 v18, v122, v74, v18
	v_fma_f32 v19, v123, v75, v19
	v_fma_f32 v20, v124, v76, v20
	v_fma_f32 v21, v125, v77, v21
	v_fma_f32 v22, v126, v78, v22
	v_fma_f32 v23, v127, v79, v23
	v_fma_f32 v24, v128, v80, v24
	v_fma_f32 v25, v129, v81, v25
	v_fma_f32 v26, v130, v82, v26
	v_fma_f32 v27, v131, v83, v27
	v_fma_f32 v28, v132, v84, v28
	v_fma_f32 v29, v133, v85, v29
	v_fma_f32 v30, v134, v86, v30
	v_fma_f32 v31, v135, v87, v31
	v_cvt_pk_bf16_f32 v156, v16, v17
	v_cvt_pk_bf16_f32 v157, v18, v19
	v_cvt_pk_bf16_f32 v158, v20, v21
	v_cvt_pk_bf16_f32 v159, v22, v23
	v_cvt_pk_bf16_f32 v160, v24, v25
	v_cvt_pk_bf16_f32 v161, v26, v27
	v_cvt_pk_bf16_f32 v162, v28, v29
	v_cvt_pk_bf16_f32 v163, v30, v31
	s_lshl_b32 vcc_lo, s19, 11
	s_add_u32 vcc_lo, vcc_lo, 0x2800000
	s_add_u32 s100, s16, vcc_lo
	s_addc_u32 s101, s17, 0
	global_store_dwordx2 v137, v[156:157], s[100:101] offset:0
	global_store_dwordx2 v137, v[158:159], s[100:101] offset:512
	global_store_dwordx2 v137, v[160:161], s[100:101] offset:1024
	global_store_dwordx2 v137, v[162:163], s[100:101] offset:1536
	v_mul_f32_e32 v138, v16, v16
	v_mul_f32_e32 v149, v17, v17
	v_mul_f32_e32 v150, v18, v18
	v_mul_f32_e32 v154, v19, v19
	v_fma_f32 v138, v20, v20, v138
	v_fma_f32 v149, v21, v21, v149
	v_fma_f32 v150, v22, v22, v150
	v_fma_f32 v154, v23, v23, v154
	v_fma_f32 v138, v24, v24, v138
	v_fma_f32 v149, v25, v25, v149
	v_fma_f32 v150, v26, v26, v150
	v_fma_f32 v154, v27, v27, v154
	v_fma_f32 v138, v28, v28, v138
	v_fma_f32 v149, v29, v29, v149
	v_fma_f32 v150, v30, v30, v150
	v_fma_f32 v154, v31, v31, v154
	v_add_f32_e32 v138, v138, v149
	v_add_f32_e32 v150, v150, v154
	v_add_f32_e32 v138, v138, v150
	s_nop 1
	v_add_f32_dpp v138, v138, v138 quad_perm:[1,0,3,2] row_mask:0xf bank_mask:0xf
	s_nop 1
	v_add_f32_dpp v138, v138, v138 quad_perm:[2,3,0,1] row_mask:0xf bank_mask:0xf
	s_nop 1
	v_add_f32_dpp v138, v138, v138 row_half_mirror row_mask:0xf bank_mask:0xf
	s_nop 1
	v_add_f32_dpp v138, v138, v138 row_mirror row_mask:0xf bank_mask:0xf
	v_mov_b32_e32 v139, v138
	s_nop 1
	v_permlane16_swap_b32_e32 v138, v139
	v_add_f32_e32 v138, v138, v139
	v_mov_b32_e32 v139, v138
	s_nop 1
	v_permlane32_swap_b32_e32 v138, v139
	v_add_f32_e32 v138, v138, v139
	v_mul_f32_e32 v138, 0x3a800000, v138
	v_add_f32_e32 v138, 0x358637bd, v138
	v_rsq_f32_e32 v140, v138
	s_nop 0
	v_mul_f32_e32 v120, v16, v140
	v_mul_f32_e32 v121, v17, v140
	v_mul_f32_e32 v122, v18, v140
	v_mul_f32_e32 v123, v19, v140
	v_mul_f32_e32 v124, v20, v140
	v_mul_f32_e32 v125, v21, v140
	v_mul_f32_e32 v126, v22, v140
	v_mul_f32_e32 v127, v23, v140
	v_mul_f32_e32 v128, v24, v140
	v_mul_f32_e32 v129, v25, v140
	v_mul_f32_e32 v130, v26, v140
	v_mul_f32_e32 v131, v27, v140
	v_mul_f32_e32 v132, v28, v140
	v_mul_f32_e32 v133, v29, v140
	v_mul_f32_e32 v134, v30, v140
	v_mul_f32_e32 v135, v31, v140
	v_fma_f32 v120, v120, v88, v104
	v_fma_f32 v121, v121, v89, v105
	v_fma_f32 v122, v122, v90, v106
	v_fma_f32 v123, v123, v91, v107
	v_fma_f32 v124, v124, v92, v108
	v_fma_f32 v125, v125, v93, v109
	v_fma_f32 v126, v126, v94, v110
	v_fma_f32 v127, v127, v95, v111
	v_fma_f32 v128, v128, v96, v112
	v_fma_f32 v129, v129, v97, v113
	v_fma_f32 v130, v130, v98, v114
	v_fma_f32 v131, v131, v99, v115
	v_fma_f32 v132, v132, v100, v116
	v_fma_f32 v133, v133, v101, v117
	v_fma_f32 v134, v134, v102, v118
	v_fma_f32 v135, v135, v103, v119
	v_cvt_pk_bf16_f32 v156, v120, v121
	v_cvt_pk_bf16_f32 v157, v122, v123
	v_cvt_pk_bf16_f32 v158, v124, v125
	v_cvt_pk_bf16_f32 v159, v126, v127
	v_cvt_pk_bf16_f32 v160, v128, v129
	v_cvt_pk_bf16_f32 v161, v130, v131
	v_cvt_pk_bf16_f32 v162, v132, v133
	v_cvt_pk_bf16_f32 v163, v134, v135
	s_lshl_b32 vcc_lo, s19, 11
	s_add_u32 vcc_lo, vcc_lo, 0x2800000
	s_add_u32 s100, s14, vcc_lo
	s_addc_u32 s101, s15, 0
	global_store_dwordx2 v137, v[156:157], s[100:101] offset:0
	global_store_dwordx2 v137, v[158:159], s[100:101] offset:512
	global_store_dwordx2 v137, v[160:161], s[100:101] offset:1024
	global_store_dwordx2 v137, v[162:163], s[100:101] offset:1536
	s_lshl_b32 vcc_lo, s19, 11
	s_add_u32 vcc_lo, vcc_lo, 0x3400000
	s_add_u32 s100, s12, vcc_lo
	s_addc_u32 s101, s13, 0
	global_load_dwordx2 v[24:25], v137, s[100:101] offset:0
	global_load_dwordx2 v[26:27], v137, s[100:101] offset:512
	global_load_dwordx2 v[28:29], v137, s[100:101] offset:1024
	global_load_dwordx2 v[30:31], v137, s[100:101] offset:1536
	s_lshl_b32 vcc_lo, s19, 11
	s_add_u32 vcc_lo, vcc_lo, 0x3400000
	s_add_u32 s100, s14, vcc_lo
	s_addc_u32 s101, s15, 0
	global_load_dwordx2 v[56:57], v137, s[100:101] offset:0
	global_load_dwordx2 v[58:59], v137, s[100:101] offset:512
	global_load_dwordx2 v[60:61], v137, s[100:101] offset:1024
	global_load_dwordx2 v[62:63], v137, s[100:101] offset:1536
	s_waitcnt vmcnt(32)
; __device__ __forceinline__ void row_phase(const Params& P, int glayer, int layer, int xsrc, bool hasY, int gate_idx, const float* gpost,
;                           int xdst, bool doH, const float* gpre, int sh_idx, int nrows) {
;     ...
;         if (hasY) {
;           float4 yv[4];
;           float ss = 0.f;
; #pragma unroll
;           for (int i = 0; i < 4; ++i) {
;             const uint2 raw = yy[u][i];
;             yv[i].x = bf2f((u16)(raw.x & 0xffff)); yv[i].y = bf2f((u16)(raw.x >> 16));
;             yv[i].z = bf2f((u16)(raw.y & 0xffff)); yv[i].w = bf2f((u16)(raw.y >> 16));
;             ss += yv[i].x * yv[i].x + yv[i].y * yv[i].y + yv[i].z * yv[i].z + yv[i].w * yv[i].w;
;           }
;           ss = wave_sum(ss);
;           const float rstd = __builtin_amdgcn_rsqf(ss * (1.f / 1024.f) + EPSF);
; #pragma unroll
;           for (int i = 0; i < 4; ++i) {
;             const int col = (i * 64 + lane) * 4;
;             const float4 gt = *reinterpret_cast<const float4*>(modg + gate_idx * 1024 + col);
;             const float4 gp = *reinterpret_cast<const float4*>(gpost + col);
;             xv[i].x += gt.x * (yv[i].x * rstd * gp.x); xv[i].y += gt.y * (yv[i].y * rstd * gp.y);
;             xv[i].z += gt.z * (yv[i].z * rstd * gp.z); xv[i].w += gt.w * (yv[i].w * rstd * gp.w);
;           }
;         }
;         if (xdst == 3 || (xdst == 1 && row >= N_X)) {
;           float* xout = (xdst == 3) ? P.out + (long)row * 1024 : P.xc + (long)(row - N_X) * 1024;
; #pragma unroll
;           for (int i = 0; i < 4; ++i) *reinterpret_cast<float4*>(xout + (i * 64 + lane) * 4) = xv[i];
;         } else if (xdst != 0) {
;           u16* xo = ((xdst == 1) ? resA : P.zf) + (long)row * 1024;
; #pragma unroll
;           for (int i = 0; i < 4; ++i) {
;             const unsigned b0 = f2bf(xv[i].x), b1 = f2bf(xv[i].y), b2 = f2bf(xv[i].z), b3 = f2bf(xv[i].w);
;             *reinterpret_cast<uint2*>(xo + (i * 64 + lane) * 4) = make_uint2(b0 | (b1 << 16), b2 | (b3 << 16));
;           }
;         }
;         if (doH) {
;           float ss = 0.f;
; #pragma unroll
;           for (int i = 0; i < 4; ++i) ss += xv[i].x * xv[i].x + xv[i].y * xv[i].y + xv[i].z * xv[i].z + xv[i].w * xv[i].w;
;           ss = wave_sum(ss);
;           const float rstd = __builtin_amdgcn_rsqf(ss * (1.f / 1024.f) + EPSF);
	v_lshlrev_b32_e32 v120, 16, v64
	v_and_b32_e32 v121, 0xffff0000, v64
	v_lshlrev_b32_e32 v122, 16, v65
	v_and_b32_e32 v123, 0xffff0000, v65
	v_lshlrev_b32_e32 v124, 16, v66
	v_and_b32_e32 v125, 0xffff0000, v66
	v_lshlrev_b32_e32 v126, 16, v67
	v_and_b32_e32 v127, 0xffff0000, v67
	v_lshlrev_b32_e32 v128, 16, v68
	v_and_b32_e32 v129, 0xffff0000, v68
	v_lshlrev_b32_e32 v130, 16, v69
	v_and_b32_e32 v131, 0xffff0000, v69
	v_lshlrev_b32_e32 v132, 16, v70
	v_and_b32_e32 v133, 0xffff0000, v70
	v_lshlrev_b32_e32 v134, 16, v71
	v_and_b32_e32 v135, 0xffff0000, v71
	v_mul_f32_e32 v138, v120, v120
	v_mul_f32_e32 v149, v121, v121
	v_mul_f32_e32 v150, v122, v122
	v_mul_f32_e32 v154, v123, v123
	v_fma_f32 v138, v124, v124, v138
	v_fma_f32 v149, v125, v125, v149
	v_fma_f32 v150, v126, v126, v150
	v_fma_f32 v154, v127, v127, v154
	v_fma_f32 v138, v128, v128, v138
	v_fma_f32 v149, v129, v129, v149
	v_fma_f32 v150, v130, v130, v150
	v_fma_f32 v154, v131, v131, v154
	v_fma_f32 v138, v132, v132, v138
	v_fma_f32 v149, v133, v133, v149
	v_fma_f32 v150, v134, v134, v150
	v_fma_f32 v154, v135, v135, v154
	v_add_f32_e32 v138, v138, v149
	v_add_f32_e32 v150, v150, v154
	v_add_f32_e32 v138, v138, v150
	s_nop 1
	v_add_f32_dpp v138, v138, v138 quad_perm:[1,0,3,2] row_mask:0xf bank_mask:0xf
	s_nop 1
	v_add_f32_dpp v138, v138, v138 quad_perm:[2,3,0,1] row_mask:0xf bank_mask:0xf
	s_nop 1
	v_add_f32_dpp v138, v138, v138 row_half_mirror row_mask:0xf bank_mask:0xf
	s_nop 1
	v_add_f32_dpp v138, v138, v138 row_mirror row_mask:0xf bank_mask:0xf
	v_mov_b32_e32 v139, v138
	s_nop 1
	v_permlane16_swap_b32_e32 v138, v139
	v_add_f32_e32 v138, v138, v139
	v_mov_b32_e32 v139, v138
	s_nop 1
	v_permlane32_swap_b32_e32 v138, v139
	v_add_f32_e32 v138, v138, v139
	v_mul_f32_e32 v138, 0x3a800000, v138
	v_add_f32_e32 v138, 0x358637bd, v138
	v_rsq_f32_e32 v140, v138
	v_lshlrev_b32_e32 v32, 16, v40
	v_and_b32_e32 v33, 0xffff0000, v40
	v_lshlrev_b32_e32 v34, 16, v41
	v_and_b32_e32 v35, 0xffff0000, v41
	v_lshlrev_b32_e32 v36, 16, v42
	v_and_b32_e32 v37, 0xffff0000, v42
	v_lshlrev_b32_e32 v38, 16, v43
	v_and_b32_e32 v39, 0xffff0000, v43
	v_lshlrev_b32_e32 v40, 16, v44
	v_and_b32_e32 v41, 0xffff0000, v44
	v_lshlrev_b32_e32 v42, 16, v45
	v_and_b32_e32 v43, 0xffff0000, v45
	v_lshlrev_b32_e32 v44, 16, v46
	v_and_b32_e32 v45, 0xffff0000, v46
	v_lshlrev_b32_e32 v46, 16, v47
	v_and_b32_e32 v47, 0xffff0000, v47
	s_nop 0
	v_mul_f32_e32 v120, v120, v140
	v_mul_f32_e32 v121, v121, v140
	v_mul_f32_e32 v122, v122, v140
	v_mul_f32_e32 v123, v123, v140
	v_mul_f32_e32 v124, v124, v140
	v_mul_f32_e32 v125, v125, v140
	v_mul_f32_e32 v126, v126, v140
	v_mul_f32_e32 v127, v127, v140
	v_mul_f32_e32 v128, v128, v140
	v_mul_f32_e32 v129, v129, v140
	v_mul_f32_e32 v130, v130, v140
	v_mul_f32_e32 v131, v131, v140
	v_mul_f32_e32 v132, v132, v140
	v_mul_f32_e32 v133, v133, v140
	v_mul_f32_e32 v134, v134, v140
	v_mul_f32_e32 v135, v135, v140
	v_fma_f32 v32, v120, v72, v32
	v_fma_f32 v33, v121, v73, v33
	v_fma_f32 v34, v122, v74, v34
	v_fma_f32 v35, v123, v75, v35
	v_fma_f32 v36, v124, v76, v36
	v_fma_f32 v37, v125, v77, v37
	v_fma_f32 v38, v126, v78, v38
	v_fma_f32 v39, v127, v79, v39
	v_fma_f32 v40, v128, v80, v40
	v_fma_f32 v41, v129, v81, v41
	v_fma_f32 v42, v130, v82, v42
	v_fma_f32 v43, v131, v83, v43
	v_fma_f32 v44, v132, v84, v44
	v_fma_f32 v45, v133, v85, v45
	v_fma_f32 v46, v134, v86, v46
	v_fma_f32 v47, v135, v87, v47
	v_cvt_pk_bf16_f32 v156, v32, v33
	v_cvt_pk_bf16_f32 v157, v34, v35
	v_cvt_pk_bf16_f32 v158, v36, v37
	v_cvt_pk_bf16_f32 v159, v38, v39
	v_cvt_pk_bf16_f32 v160, v40, v41
	v_cvt_pk_bf16_f32 v161, v42, v43
	v_cvt_pk_bf16_f32 v162, v44, v45
	v_cvt_pk_bf16_f32 v163, v46, v47
	s_lshl_b32 vcc_lo, s19, 11
	s_add_u32 vcc_lo, vcc_lo, 0x2c00000
	s_add_u32 s100, s16, vcc_lo
	s_addc_u32 s101, s17, 0
	global_store_dwordx2 v137, v[156:157], s[100:101] offset:0
	global_store_dwordx2 v137, v[158:159], s[100:101] offset:512
	global_store_dwordx2 v137, v[160:161], s[100:101] offset:1024
	global_store_dwordx2 v137, v[162:163], s[100:101] offset:1536
	v_mul_f32_e32 v138, v32, v32
	v_mul_f32_e32 v149, v33, v33
	v_mul_f32_e32 v150, v34, v34
	v_mul_f32_e32 v154, v35, v35
	v_fma_f32 v138, v36, v36, v138
	v_fma_f32 v149, v37, v37, v149
	v_fma_f32 v150, v38, v38, v150
	v_fma_f32 v154, v39, v39, v154
	v_fma_f32 v138, v40, v40, v138
	v_fma_f32 v149, v41, v41, v149
	v_fma_f32 v150, v42, v42, v150
	v_fma_f32 v154, v43, v43, v154
	v_fma_f32 v138, v44, v44, v138
	v_fma_f32 v149, v45, v45, v149
	v_fma_f32 v150, v46, v46, v150
	v_fma_f32 v154, v47, v47, v154
	v_add_f32_e32 v138, v138, v149
	v_add_f32_e32 v150, v150, v154
	v_add_f32_e32 v138, v138, v150
	s_nop 1
	v_add_f32_dpp v138, v138, v138 quad_perm:[1,0,3,2] row_mask:0xf bank_mask:0xf
	s_nop 1
	v_add_f32_dpp v138, v138, v138 quad_perm:[2,3,0,1] row_mask:0xf bank_mask:0xf
	s_nop 1
	v_add_f32_dpp v138, v138, v138 row_half_mirror row_mask:0xf bank_mask:0xf
	s_nop 1
	v_add_f32_dpp v138, v138, v138 row_mirror row_mask:0xf bank_mask:0xf
	v_mov_b32_e32 v139, v138
	s_nop 1
	v_permlane16_swap_b32_e32 v138, v139
	v_add_f32_e32 v138, v138, v139
	v_mov_b32_e32 v139, v138
	s_nop 1
	v_permlane32_swap_b32_e32 v138, v139
	v_add_f32_e32 v138, v138, v139
	v_mul_f32_e32 v138, 0x3a800000, v138
	v_add_f32_e32 v138, 0x358637bd, v138
	v_rsq_f32_e32 v140, v138
	s_nop 0
	v_mul_f32_e32 v120, v32, v140
	v_mul_f32_e32 v121, v33, v140
	v_mul_f32_e32 v122, v34, v140
	v_mul_f32_e32 v123, v35, v140
	v_mul_f32_e32 v124, v36, v140
	v_mul_f32_e32 v125, v37, v140
	v_mul_f32_e32 v126, v38, v140
	v_mul_f32_e32 v127, v39, v140
	v_mul_f32_e32 v128, v40, v140
	v_mul_f32_e32 v129, v41, v140
	v_mul_f32_e32 v130, v42, v140
; __device__ __forceinline__ void row_phase(const Params& P, int glayer, int layer, int xsrc, bool hasY, int gate_idx, const float* gpost,
;                           int xdst, bool doH, const float* gpre, int sh_idx, int nrows) {
;     ...
; #pragma unroll
;           for (int i = 0; i < 4; ++i) {
;             const int col = (i * 64 + lane) * 4;
;             const float4 gt = *reinterpret_cast<const float4*>(modg + gate_idx * 1024 + col);
;             const float4 gp = *reinterpret_cast<const float4*>(gpost + col);
;             xv[i].x += gt.x * (yv[i].x * rstd * gp.x); xv[i].y += gt.y * (yv[i].y * rstd * gp.y);
;             xv[i].z += gt.z * (yv[i].z * rstd * gp.z); xv[i].w += gt.w * (yv[i].w * rstd * gp.w);
;           }
;         }
;         if (xdst == 3 || (xdst == 1 && row >= N_X)) {
;           float* xout = (xdst == 3) ? P.out + (long)row * 1024 : P.xc + (long)(row - N_X) * 1024;
; #pragma unroll
;           for (int i = 0; i < 4; ++i) *reinterpret_cast<float4*>(xout + (i * 64 + lane) * 4) = xv[i];
;         } else if (xdst != 0) {
;           u16* xo = ((xdst == 1) ? resA : P.zf) + (long)row * 1024;
; #pragma unroll
;           for (int i = 0; i < 4; ++i) {
;             const unsigned b0 = f2bf(xv[i].x), b1 = f2bf(xv[i].y), b2 = f2bf(xv[i].z), b3 = f2bf(xv[i].w);
;             *reinterpret_cast<uint2*>(xo + (i * 64 + lane) * 4) = make_uint2(b0 | (b1 << 16), b2 | (b3 << 16));
;           }
;         }
;         if (doH) {
;           float ss = 0.f;
; #pragma unroll
;           for (int i = 0; i < 4; ++i) ss += xv[i].x * xv[i].x + xv[i].y * xv[i].y + xv[i].z * xv[i].z + xv[i].w * xv[i].w;
;           ss = wave_sum(ss);
;           const float rstd = __builtin_amdgcn_rsqf(ss * (1.f / 1024.f) + EPSF);
;           u16* h = P.hy + (long)row * 1024;
; #pragma unroll
;           for (int i = 0; i < 4; ++i) {
;             const int col = (i * 64 + lane) * 4;
;             const float4 g = *reinterpret_cast<const float4*>(gpre + col);
;             const float4 sh = *reinterpret_cast<const float4*>(modp + sh_idx * 1024 + col);
;             const float4 sc = *reinterpret_cast<const float4*>(modp + (sh_idx + 1) * 1024 + col);
;             const unsigned h0 = f2bf(xv[i].x * rstd * g.x * (1.f + sc.x) + sh.x);
;             const unsigned h1 = f2bf(xv[i].y * rstd * g.y * (1.f + sc.y) + sh.y);
	v_mul_f32_e32 v131, v43, v140
	v_mul_f32_e32 v132, v44, v140
	v_mul_f32_e32 v133, v45, v140
	v_mul_f32_e32 v134, v46, v140
	v_mul_f32_e32 v135, v47, v140
	v_fma_f32 v120, v120, v88, v104
	v_fma_f32 v121, v121, v89, v105
	v_fma_f32 v122, v122, v90, v106
	v_fma_f32 v123, v123, v91, v107
	v_fma_f32 v124, v124, v92, v108
	v_fma_f32 v125, v125, v93, v109
	v_fma_f32 v126, v126, v94, v110
	v_fma_f32 v127, v127, v95, v111
	v_fma_f32 v128, v128, v96, v112
	v_fma_f32 v129, v129, v97, v113
	v_fma_f32 v130, v130, v98, v114
	v_fma_f32 v131, v131, v99, v115
	v_fma_f32 v132, v132, v100, v116
	v_fma_f32 v133, v133, v101, v117
	v_fma_f32 v134, v134, v102, v118
	v_fma_f32 v135, v135, v103, v119
	v_cvt_pk_bf16_f32 v156, v120, v121
	v_cvt_pk_bf16_f32 v157, v122, v123
	v_cvt_pk_bf16_f32 v158, v124, v125
	v_cvt_pk_bf16_f32 v159, v126, v127
	v_cvt_pk_bf16_f32 v160, v128, v129
	v_cvt_pk_bf16_f32 v161, v130, v131
	v_cvt_pk_bf16_f32 v162, v132, v133
	v_cvt_pk_bf16_f32 v163, v134, v135
	s_lshl_b32 vcc_lo, s19, 11
	s_add_u32 vcc_lo, vcc_lo, 0x2c00000
	s_add_u32 s100, s14, vcc_lo
	s_addc_u32 s101, s15, 0
	global_store_dwordx2 v137, v[156:157], s[100:101] offset:0
	global_store_dwordx2 v137, v[158:159], s[100:101] offset:512
	global_store_dwordx2 v137, v[160:161], s[100:101] offset:1024
	global_store_dwordx2 v137, v[162:163], s[100:101] offset:1536
	s_add_u32 s100, s20, 0x32000
	s_addc_u32 s101, s21, 0
	global_load_dwordx4 v[72:75], v136, s[100:101] offset:0
	global_load_dwordx4 v[76:79], v136, s[100:101] offset:1024
	global_load_dwordx4 v[80:83], v136, s[100:101] offset:2048
	global_load_dwordx4 v[84:87], v136, s[100:101] offset:3072
	s_load_dwordx2 s[98:99], s[4:5], 0x38
	s_waitcnt lgkmcnt(0)
	s_add_u32 s98, s98, 0x1000
	s_addc_u32 s99, s99, 0
	global_load_dwordx4 v[120:123], v136, s[98:99] offset:0
	global_load_dwordx4 v[124:127], v136, s[98:99] offset:1024
	global_load_dwordx4 v[128:131], v136, s[98:99] offset:2048
	global_load_dwordx4 v[132:135], v136, s[98:99] offset:3072
	s_add_u32 s100, s20, 0x33000
	s_addc_u32 s101, s21, 0
	global_load_dwordx4 v[104:107], v136, s[100:101] offset:0
	global_load_dwordx4 v[108:111], v136, s[100:101] offset:1024
	global_load_dwordx4 v[112:115], v136, s[100:101] offset:2048
	global_load_dwordx4 v[116:119], v136, s[100:101] offset:3072
	s_add_u32 s100, s100, 0x1000
	s_addc_u32 s101, s101, 0
	global_load_dwordx4 v[32:35], v136, s[100:101] offset:0
	global_load_dwordx4 v[36:39], v136, s[100:101] offset:1024
	global_load_dwordx4 v[40:43], v136, s[100:101] offset:2048
	global_load_dwordx4 v[44:47], v136, s[100:101] offset:3072
	s_load_dwordx2 s[98:99], s[4:5], 0x40
	s_waitcnt lgkmcnt(0)
	s_add_u32 s98, s98, 0x1000
	s_addc_u32 s99, s99, 0
	global_load_dwordx4 v[88:91], v136, s[98:99] offset:0
	global_load_dwordx4 v[92:95], v136, s[98:99] offset:1024
	global_load_dwordx4 v[96:99], v136, s[98:99] offset:2048
	global_load_dwordx4 v[100:103], v136, s[98:99] offset:3072
	s_waitcnt vmcnt(0)
	v_mul_f32_e32 v72, v72, v120
	v_mul_f32_e32 v73, v73, v121
	v_mul_f32_e32 v74, v74, v122
	v_mul_f32_e32 v75, v75, v123
	v_mul_f32_e32 v76, v76, v124
	v_mul_f32_e32 v77, v77, v125
	v_mul_f32_e32 v78, v78, v126
	v_mul_f32_e32 v79, v79, v127
	v_mul_f32_e32 v80, v80, v128
	v_mul_f32_e32 v81, v81, v129
	v_mul_f32_e32 v82, v82, v130
	v_mul_f32_e32 v83, v83, v131
	v_mul_f32_e32 v84, v84, v132
	v_mul_f32_e32 v85, v85, v133
	v_mul_f32_e32 v86, v86, v134
	v_mul_f32_e32 v87, v87, v135
	v_fma_f32 v88, v88, v32, v88
	v_fma_f32 v89, v89, v33, v89
	v_fma_f32 v90, v90, v34, v90
	v_fma_f32 v91, v91, v35, v91
	v_fma_f32 v92, v92, v36, v92
	v_fma_f32 v93, v93, v37, v93
	v_fma_f32 v94, v94, v38, v94
	v_fma_f32 v95, v95, v39, v95
	v_fma_f32 v96, v96, v40, v96
	v_fma_f32 v97, v97, v41, v97
	v_fma_f32 v98, v98, v42, v98
	v_fma_f32 v99, v99, v43, v99
	v_fma_f32 v100, v100, v44, v100
	v_fma_f32 v101, v101, v45, v101
	v_fma_f32 v102, v102, v46, v102
	v_fma_f32 v103, v103, v47, v103
	s_lshl_b32 vcc_lo, s19, 11
	s_add_u32 vcc_lo, vcc_lo, 0x3800000
	s_add_u32 s100, s12, vcc_lo
	s_addc_u32 s101, s13, 0
	global_load_dwordx2 v[40:41], v137, s[100:101] offset:0
	global_load_dwordx2 v[42:43], v137, s[100:101] offset:512
	global_load_dwordx2 v[44:45], v137, s[100:101] offset:1024
	global_load_dwordx2 v[46:47], v137, s[100:101] offset:1536
	s_lshl_b32 vcc_lo, s19, 11
	s_add_u32 vcc_lo, vcc_lo, 0x3800000
	s_add_u32 s100, s14, vcc_lo
	s_addc_u32 s101, s15, 0
	global_load_dwordx2 v[64:65], v137, s[100:101] offset:0
	global_load_dwordx2 v[66:67], v137, s[100:101] offset:512
	global_load_dwordx2 v[68:69], v137, s[100:101] offset:1024
	global_load_dwordx2 v[70:71], v137, s[100:101] offset:1536
	v_lshlrev_b32_e32 v120, 16, v48
	v_and_b32_e32 v121, 0xffff0000, v48
	v_lshlrev_b32_e32 v122, 16, v49
	v_and_b32_e32 v123, 0xffff0000, v49
	v_lshlrev_b32_e32 v124, 16, v50
	v_and_b32_e32 v125, 0xffff0000, v50
	v_lshlrev_b32_e32 v126, 16, v51
	v_and_b32_e32 v127, 0xffff0000, v51
	v_lshlrev_b32_e32 v128, 16, v52
	v_and_b32_e32 v129, 0xffff0000, v52
	v_lshlrev_b32_e32 v130, 16, v53
	v_and_b32_e32 v131, 0xffff0000, v53
	v_lshlrev_b32_e32 v132, 16, v54
	v_and_b32_e32 v133, 0xffff0000, v54
	v_lshlrev_b32_e32 v134, 16, v55
	v_and_b32_e32 v135, 0xffff0000, v55
	v_mul_f32_e32 v138, v120, v120
	v_mul_f32_e32 v149, v121, v121
	v_mul_f32_e32 v150, v122, v122
	v_mul_f32_e32 v154, v123, v123
	v_fma_f32 v138, v124, v124, v138
	v_fma_f32 v149, v125, v125, v149
	v_fma_f32 v150, v126, v126, v150
	v_fma_f32 v154, v127, v127, v154
	v_fma_f32 v138, v128, v128, v138
	v_fma_f32 v149, v129, v129, v149
	v_fma_f32 v150, v130, v130, v150
	v_fma_f32 v154, v131, v131, v154
	v_fma_f32 v138, v132, v132, v138
	v_fma_f32 v149, v133, v133, v149
; __device__ __forceinline__ void row_phase(const Params& P, int glayer, int layer, int xsrc, bool hasY, int gate_idx, const float* gpost,
;                           int xdst, bool doH, const float* gpre, int sh_idx, int nrows) {
;     ...
;         if (hasY) {
;           float4 yv[4];
;           float ss = 0.f;
; #pragma unroll
;           for (int i = 0; i < 4; ++i) {
;             const uint2 raw = yy[u][i];
;             yv[i].x = bf2f((u16)(raw.x & 0xffff)); yv[i].y = bf2f((u16)(raw.x >> 16));
;             yv[i].z = bf2f((u16)(raw.y & 0xffff)); yv[i].w = bf2f((u16)(raw.y >> 16));
;             ss += yv[i].x * yv[i].x + yv[i].y * yv[i].y + yv[i].z * yv[i].z + yv[i].w * yv[i].w;
;           }
;           ss = wave_sum(ss);
;           const float rstd = __builtin_amdgcn_rsqf(ss * (1.f / 1024.f) + EPSF);
; #pragma unroll
;           for (int i = 0; i < 4; ++i) {
;             const int col = (i * 64 + lane) * 4;
;             const float4 gt = *reinterpret_cast<const float4*>(modg + gate_idx * 1024 + col);
;             const float4 gp = *reinterpret_cast<const float4*>(gpost + col);
;             xv[i].x += gt.x * (yv[i].x * rstd * gp.x); xv[i].y += gt.y * (yv[i].y * rstd * gp.y);
;             xv[i].z += gt.z * (yv[i].z * rstd * gp.z); xv[i].w += gt.w * (yv[i].w * rstd * gp.w);
;           }
;         }
;         if (xdst == 3 || (xdst == 1 && row >= N_X)) {
;           float* xout = (xdst == 3) ? P.out + (long)row * 1024 : P.xc + (long)(row - N_X) * 1024;
; #pragma unroll
;           for (int i = 0; i < 4; ++i) *reinterpret_cast<float4*>(xout + (i * 64 + lane) * 4) = xv[i];
;         } else if (xdst != 0) {
;           u16* xo = ((xdst == 1) ? resA : P.zf) + (long)row * 1024;
; #pragma unroll
;           for (int i = 0; i < 4; ++i) {
;             const unsigned b0 = f2bf(xv[i].x), b1 = f2bf(xv[i].y), b2 = f2bf(xv[i].z), b3 = f2bf(xv[i].w);
;             *reinterpret_cast<uint2*>(xo + (i * 64 + lane) * 4) = make_uint2(b0 | (b1 << 16), b2 | (b3 << 16));
;           }
;         }
;         if (doH) {
;           float ss = 0.f;
; #pragma unroll
;           for (int i = 0; i < 4; ++i) ss += xv[i].x * xv[i].x + xv[i].y * xv[i].y + xv[i].z * xv[i].z + xv[i].w * xv[i].w;
;           ss = wave_sum(ss);
;           const float rstd = __builtin_amdgcn_rsqf(ss * (1.f / 1024.f) + EPSF);
;           u16* h = P.hy + (long)row * 1024;
; #pragma unroll
	v_fma_f32 v150, v134, v134, v150
	v_fma_f32 v154, v135, v135, v154
	v_add_f32_e32 v138, v138, v149
	v_add_f32_e32 v150, v150, v154
	v_add_f32_e32 v138, v138, v150
	s_nop 1
	v_add_f32_dpp v138, v138, v138 quad_perm:[1,0,3,2] row_mask:0xf bank_mask:0xf
	s_nop 1
	v_add_f32_dpp v138, v138, v138 quad_perm:[2,3,0,1] row_mask:0xf bank_mask:0xf
	s_nop 1
	v_add_f32_dpp v138, v138, v138 row_half_mirror row_mask:0xf bank_mask:0xf
	s_nop 1
	v_add_f32_dpp v138, v138, v138 row_mirror row_mask:0xf bank_mask:0xf
	v_mov_b32_e32 v139, v138
	s_nop 1
	v_permlane16_swap_b32_e32 v138, v139
	v_add_f32_e32 v138, v138, v139
	v_mov_b32_e32 v139, v138
	s_nop 1
	v_permlane32_swap_b32_e32 v138, v139
	v_add_f32_e32 v138, v138, v139
	v_mul_f32_e32 v138, 0x3a800000, v138
	v_add_f32_e32 v138, 0x358637bd, v138
	v_rsq_f32_e32 v140, v138
	v_lshlrev_b32_e32 v0, 16, v8
	v_and_b32_e32 v1, 0xffff0000, v8
	v_lshlrev_b32_e32 v2, 16, v9
	v_and_b32_e32 v3, 0xffff0000, v9
	v_lshlrev_b32_e32 v4, 16, v10
	v_and_b32_e32 v5, 0xffff0000, v10
	v_lshlrev_b32_e32 v6, 16, v11
	v_and_b32_e32 v7, 0xffff0000, v11
	v_lshlrev_b32_e32 v8, 16, v12
	v_and_b32_e32 v9, 0xffff0000, v12
	v_lshlrev_b32_e32 v10, 16, v13
	v_and_b32_e32 v11, 0xffff0000, v13
	v_lshlrev_b32_e32 v12, 16, v14
	v_and_b32_e32 v13, 0xffff0000, v14
	v_lshlrev_b32_e32 v14, 16, v15
	v_and_b32_e32 v15, 0xffff0000, v15
	s_nop 0
	v_mul_f32_e32 v120, v120, v140
	v_mul_f32_e32 v121, v121, v140
	v_mul_f32_e32 v122, v122, v140
	v_mul_f32_e32 v123, v123, v140
	v_mul_f32_e32 v124, v124, v140
	v_mul_f32_e32 v125, v125, v140
	v_mul_f32_e32 v126, v126, v140
	v_mul_f32_e32 v127, v127, v140
	v_mul_f32_e32 v128, v128, v140
	v_mul_f32_e32 v129, v129, v140
	v_mul_f32_e32 v130, v130, v140
	v_mul_f32_e32 v131, v131, v140
	v_mul_f32_e32 v132, v132, v140
	v_mul_f32_e32 v133, v133, v140
	v_mul_f32_e32 v134, v134, v140
	v_mul_f32_e32 v135, v135, v140
	v_fma_f32 v0, v120, v72, v0
	v_fma_f32 v1, v121, v73, v1
	v_fma_f32 v2, v122, v74, v2
	v_fma_f32 v3, v123, v75, v3
	v_fma_f32 v4, v124, v76, v4
	v_fma_f32 v5, v125, v77, v5
	v_fma_f32 v6, v126, v78, v6
	v_fma_f32 v7, v127, v79, v7
	v_fma_f32 v8, v128, v80, v8
	v_fma_f32 v9, v129, v81, v9
	v_fma_f32 v10, v130, v82, v10
	v_fma_f32 v11, v131, v83, v11
	v_fma_f32 v12, v132, v84, v12
	v_fma_f32 v13, v133, v85, v13
	v_fma_f32 v14, v134, v86, v14
	v_fma_f32 v15, v135, v87, v15
	v_cvt_pk_bf16_f32 v156, v0, v1
	v_cvt_pk_bf16_f32 v157, v2, v3
	v_cvt_pk_bf16_f32 v158, v4, v5
	v_cvt_pk_bf16_f32 v159, v6, v7
	v_cvt_pk_bf16_f32 v160, v8, v9
	v_cvt_pk_bf16_f32 v161, v10, v11
	v_cvt_pk_bf16_f32 v162, v12, v13
	v_cvt_pk_bf16_f32 v163, v14, v15
	s_lshl_b32 vcc_lo, s19, 11
	s_add_u32 vcc_lo, vcc_lo, 0x3000000
	s_add_u32 s100, s16, vcc_lo
	s_addc_u32 s101, s17, 0
	global_store_dwordx2 v137, v[156:157], s[100:101] offset:0
	global_store_dwordx2 v137, v[158:159], s[100:101] offset:512
	global_store_dwordx2 v137, v[160:161], s[100:101] offset:1024
	global_store_dwordx2 v137, v[162:163], s[100:101] offset:1536
	v_mul_f32_e32 v138, v0, v0
	v_mul_f32_e32 v149, v1, v1
	v_mul_f32_e32 v150, v2, v2
	v_mul_f32_e32 v154, v3, v3
	v_fma_f32 v138, v4, v4, v138
	v_fma_f32 v149, v5, v5, v149
	v_fma_f32 v150, v6, v6, v150
	v_fma_f32 v154, v7, v7, v154
	v_fma_f32 v138, v8, v8, v138
	v_fma_f32 v149, v9, v9, v149
	v_fma_f32 v150, v10, v10, v150
	v_fma_f32 v154, v11, v11, v154
	v_fma_f32 v138, v12, v12, v138
	v_fma_f32 v149, v13, v13, v149
	v_fma_f32 v150, v14, v14, v150
	v_fma_f32 v154, v15, v15, v154
	v_add_f32_e32 v138, v138, v149
	v_add_f32_e32 v150, v150, v154
	v_add_f32_e32 v138, v138, v150
	s_nop 1
	v_add_f32_dpp v138, v138, v138 quad_perm:[1,0,3,2] row_mask:0xf bank_mask:0xf
	s_nop 1
	v_add_f32_dpp v138, v138, v138 quad_perm:[2,3,0,1] row_mask:0xf bank_mask:0xf
	s_nop 1
	v_add_f32_dpp v138, v138, v138 row_half_mirror row_mask:0xf bank_mask:0xf
	s_nop 1
	v_add_f32_dpp v138, v138, v138 row_mirror row_mask:0xf bank_mask:0xf
	v_mov_b32_e32 v139, v138
	s_nop 1
	v_permlane16_swap_b32_e32 v138, v139
	v_add_f32_e32 v138, v138, v139
	v_mov_b32_e32 v139, v138
	s_nop 1
	v_permlane32_swap_b32_e32 v138, v139
	v_add_f32_e32 v138, v138, v139
	v_mul_f32_e32 v138, 0x3a800000, v138
	v_add_f32_e32 v138, 0x358637bd, v138
	v_rsq_f32_e32 v140, v138
	s_nop 0
	v_mul_f32_e32 v120, v0, v140
	v_mul_f32_e32 v121, v1, v140
	v_mul_f32_e32 v122, v2, v140
	v_mul_f32_e32 v123, v3, v140
	v_mul_f32_e32 v124, v4, v140
	v_mul_f32_e32 v125, v5, v140
	v_mul_f32_e32 v126, v6, v140
	v_mul_f32_e32 v127, v7, v140
	v_mul_f32_e32 v128, v8, v140
	v_mul_f32_e32 v129, v9, v140
	v_mul_f32_e32 v130, v10, v140
	v_mul_f32_e32 v131, v11, v140
	v_mul_f32_e32 v132, v12, v140
	v_mul_f32_e32 v133, v13, v140
	v_mul_f32_e32 v134, v14, v140
	v_mul_f32_e32 v135, v15, v140
	v_fma_f32 v120, v120, v88, v104
	v_fma_f32 v121, v121, v89, v105
	v_fma_f32 v122, v122, v90, v106
	v_fma_f32 v123, v123, v91, v107
	v_fma_f32 v124, v124, v92, v108
	v_fma_f32 v125, v125, v93, v109
	v_fma_f32 v126, v126, v94, v110
	v_fma_f32 v127, v127, v95, v111
	v_fma_f32 v128, v128, v96, v112
	v_fma_f32 v129, v129, v97, v113
	v_fma_f32 v130, v130, v98, v114
	v_fma_f32 v131, v131, v99, v115
	v_fma_f32 v132, v132, v100, v116
	v_fma_f32 v133, v133, v101, v117
	v_fma_f32 v134, v134, v102, v118
	v_fma_f32 v135, v135, v103, v119
	v_cvt_pk_bf16_f32 v156, v120, v121
	v_cvt_pk_bf16_f32 v157, v122, v123
	v_cvt_pk_bf16_f32 v158, v124, v125
	v_cvt_pk_bf16_f32 v159, v126, v127
	v_cvt_pk_bf16_f32 v160, v128, v129
	v_cvt_pk_bf16_f32 v161, v130, v131
	v_cvt_pk_bf16_f32 v162, v132, v133
	v_cvt_pk_bf16_f32 v163, v134, v135
	s_lshl_b32 vcc_lo, s19, 11
	s_add_u32 vcc_lo, vcc_lo, 0x3000000
	s_add_u32 s100, s14, vcc_lo
	s_addc_u32 s101, s15, 0
; __device__ __forceinline__ void row_phase(const Params& P, int glayer, int layer, int xsrc, bool hasY, int gate_idx, const float* gpost,
;                           int xdst, bool doH, const float* gpre, int sh_idx, int nrows) {
;     ...
;         if (hasY) {
;           float4 yv[4];
;           float ss = 0.f;
; #pragma unroll
;           for (int i = 0; i < 4; ++i) {
;             const uint2 raw = yy[u][i];
;             yv[i].x = bf2f((u16)(raw.x & 0xffff)); yv[i].y = bf2f((u16)(raw.x >> 16));
;             yv[i].z = bf2f((u16)(raw.y & 0xffff)); yv[i].w = bf2f((u16)(raw.y >> 16));
;             ss += yv[i].x * yv[i].x + yv[i].y * yv[i].y + yv[i].z * yv[i].z + yv[i].w * yv[i].w;
;           }
;           ss = wave_sum(ss);
;           const float rstd = __builtin_amdgcn_rsqf(ss * (1.f / 1024.f) + EPSF);
; #pragma unroll
;           for (int i = 0; i < 4; ++i) {
;             const int col = (i * 64 + lane) * 4;
;             const float4 gt = *reinterpret_cast<const float4*>(modg + gate_idx * 1024 + col);
;             const float4 gp = *reinterpret_cast<const float4*>(gpost + col);
;             xv[i].x += gt.x * (yv[i].x * rstd * gp.x); xv[i].y += gt.y * (yv[i].y * rstd * gp.y);
;             xv[i].z += gt.z * (yv[i].z * rstd * gp.z); xv[i].w += gt.w * (yv[i].w * rstd * gp.w);
;           }
;         }
;         if (xdst == 3 || (xdst == 1 && row >= N_X)) {
;           float* xout = (xdst == 3) ? P.out + (long)row * 1024 : P.xc + (long)(row - N_X) * 1024;
; #pragma unroll
;           for (int i = 0; i < 4; ++i) *reinterpret_cast<float4*>(xout + (i * 64 + lane) * 4) = xv[i];
;         } else if (xdst != 0) {
;           u16* xo = ((xdst == 1) ? resA : P.zf) + (long)row * 1024;
; #pragma unroll
;           for (int i = 0; i < 4; ++i) {
;             const unsigned b0 = f2bf(xv[i].x), b1 = f2bf(xv[i].y), b2 = f2bf(xv[i].z), b3 = f2bf(xv[i].w);
;             *reinterpret_cast<uint2*>(xo + (i * 64 + lane) * 4) = make_uint2(b0 | (b1 << 16), b2 | (b3 << 16));
;           }
;         }
;         if (doH) {
;           float ss = 0.f;
; #pragma unroll
;           for (int i = 0; i < 4; ++i) ss += xv[i].x * xv[i].x + xv[i].y * xv[i].y + xv[i].z * xv[i].z + xv[i].w * xv[i].w;
;           ss = wave_sum(ss);
;           const float rstd = __builtin_amdgcn_rsqf(ss * (1.f / 1024.f) + EPSF);
;           u16* h = P.hy + (long)row * 1024;
; #pragma unroll
	global_store_dwordx2 v137, v[156:157], s[100:101] offset:0
	global_store_dwordx2 v137, v[158:159], s[100:101] offset:512
	global_store_dwordx2 v137, v[160:161], s[100:101] offset:1024
	global_store_dwordx2 v137, v[162:163], s[100:101] offset:1536
	s_lshl_b32 vcc_lo, s19, 11
	s_add_u32 vcc_lo, vcc_lo, 0x3c00000
	s_add_u32 s100, s12, vcc_lo
	s_addc_u32 s101, s13, 0
	global_load_dwordx2 v[8:9], v137, s[100:101] offset:0
	global_load_dwordx2 v[10:11], v137, s[100:101] offset:512
	global_load_dwordx2 v[12:13], v137, s[100:101] offset:1024
	global_load_dwordx2 v[14:15], v137, s[100:101] offset:1536
	s_lshl_b32 vcc_lo, s19, 11
	s_add_u32 vcc_lo, vcc_lo, 0x3c00000
	s_add_u32 s100, s14, vcc_lo
	s_addc_u32 s101, s15, 0
	global_load_dwordx2 v[48:49], v137, s[100:101] offset:0
	global_load_dwordx2 v[50:51], v137, s[100:101] offset:512
	global_load_dwordx2 v[52:53], v137, s[100:101] offset:1024
	global_load_dwordx2 v[54:55], v137, s[100:101] offset:1536
	v_lshlrev_b32_e32 v120, 16, v56
	v_and_b32_e32 v121, 0xffff0000, v56
	v_lshlrev_b32_e32 v122, 16, v57
	v_and_b32_e32 v123, 0xffff0000, v57
	v_lshlrev_b32_e32 v124, 16, v58
	v_and_b32_e32 v125, 0xffff0000, v58
	v_lshlrev_b32_e32 v126, 16, v59
	v_and_b32_e32 v127, 0xffff0000, v59
	v_lshlrev_b32_e32 v128, 16, v60
	v_and_b32_e32 v129, 0xffff0000, v60
	v_lshlrev_b32_e32 v130, 16, v61
	v_and_b32_e32 v131, 0xffff0000, v61
	v_lshlrev_b32_e32 v132, 16, v62
	v_and_b32_e32 v133, 0xffff0000, v62
	v_lshlrev_b32_e32 v134, 16, v63
	v_and_b32_e32 v135, 0xffff0000, v63
	v_mul_f32_e32 v138, v120, v120
	v_mul_f32_e32 v149, v121, v121
	v_mul_f32_e32 v150, v122, v122
	v_mul_f32_e32 v154, v123, v123
	v_fma_f32 v138, v124, v124, v138
	v_fma_f32 v149, v125, v125, v149
	v_fma_f32 v150, v126, v126, v150
	v_fma_f32 v154, v127, v127, v154
	v_fma_f32 v138, v128, v128, v138
	v_fma_f32 v149, v129, v129, v149
	v_fma_f32 v150, v130, v130, v150
	v_fma_f32 v154, v131, v131, v154
	v_fma_f32 v138, v132, v132, v138
	v_fma_f32 v149, v133, v133, v149
	v_fma_f32 v150, v134, v134, v150
	v_fma_f32 v154, v135, v135, v154
	v_add_f32_e32 v138, v138, v149
	v_add_f32_e32 v150, v150, v154
	v_add_f32_e32 v138, v138, v150
	s_nop 1
	v_add_f32_dpp v138, v138, v138 quad_perm:[1,0,3,2] row_mask:0xf bank_mask:0xf
	s_nop 1
	v_add_f32_dpp v138, v138, v138 quad_perm:[2,3,0,1] row_mask:0xf bank_mask:0xf
	s_nop 1
	v_add_f32_dpp v138, v138, v138 row_half_mirror row_mask:0xf bank_mask:0xf
	s_nop 1
	v_add_f32_dpp v138, v138, v138 row_mirror row_mask:0xf bank_mask:0xf
	v_mov_b32_e32 v139, v138
	s_nop 1
	v_permlane16_swap_b32_e32 v138, v139
	v_add_f32_e32 v138, v138, v139
	v_mov_b32_e32 v139, v138
	s_nop 1
	v_permlane32_swap_b32_e32 v138, v139
	v_add_f32_e32 v138, v138, v139
	v_mul_f32_e32 v138, 0x3a800000, v138
	v_add_f32_e32 v138, 0x358637bd, v138
	v_rsq_f32_e32 v140, v138
	v_lshlrev_b32_e32 v16, 16, v24
	v_and_b32_e32 v17, 0xffff0000, v24
	v_lshlrev_b32_e32 v18, 16, v25
	v_and_b32_e32 v19, 0xffff0000, v25
	v_lshlrev_b32_e32 v20, 16, v26
	v_and_b32_e32 v21, 0xffff0000, v26
	v_lshlrev_b32_e32 v22, 16, v27
	v_and_b32_e32 v23, 0xffff0000, v27
	v_lshlrev_b32_e32 v24, 16, v28
	v_and_b32_e32 v25, 0xffff0000, v28
	v_lshlrev_b32_e32 v26, 16, v29
	v_and_b32_e32 v27, 0xffff0000, v29
	v_lshlrev_b32_e32 v28, 16, v30
	v_and_b32_e32 v29, 0xffff0000, v30
	v_lshlrev_b32_e32 v30, 16, v31
	v_and_b32_e32 v31, 0xffff0000, v31
	s_nop 0
	v_mul_f32_e32 v120, v120, v140
	v_mul_f32_e32 v121, v121, v140
	v_mul_f32_e32 v122, v122, v140
	v_mul_f32_e32 v123, v123, v140
	v_mul_f32_e32 v124, v124, v140
	v_mul_f32_e32 v125, v125, v140
	v_mul_f32_e32 v126, v126, v140
	v_mul_f32_e32 v127, v127, v140
	v_mul_f32_e32 v128, v128, v140
	v_mul_f32_e32 v129, v129, v140
	v_mul_f32_e32 v130, v130, v140
	v_mul_f32_e32 v131, v131, v140
	v_mul_f32_e32 v132, v132, v140
	v_mul_f32_e32 v133, v133, v140
	v_mul_f32_e32 v134, v134, v140
	v_mul_f32_e32 v135, v135, v140
	v_fma_f32 v16, v120, v72, v16
	v_fma_f32 v17, v121, v73, v17
	v_fma_f32 v18, v122, v74, v18
	v_fma_f32 v19, v123, v75, v19
	v_fma_f32 v20, v124, v76, v20
	v_fma_f32 v21, v125, v77, v21
	v_fma_f32 v22, v126, v78, v22
	v_fma_f32 v23, v127, v79, v23
	v_fma_f32 v24, v128, v80, v24
	v_fma_f32 v25, v129, v81, v25
	v_fma_f32 v26, v130, v82, v26
	v_fma_f32 v27, v131, v83, v27
	v_fma_f32 v28, v132, v84, v28
	v_fma_f32 v29, v133, v85, v29
	v_fma_f32 v30, v134, v86, v30
	v_fma_f32 v31, v135, v87, v31
	v_cvt_pk_bf16_f32 v156, v16, v17
	v_cvt_pk_bf16_f32 v157, v18, v19
	v_cvt_pk_bf16_f32 v158, v20, v21
	v_cvt_pk_bf16_f32 v159, v22, v23
	v_cvt_pk_bf16_f32 v160, v24, v25
	v_cvt_pk_bf16_f32 v161, v26, v27
	v_cvt_pk_bf16_f32 v162, v28, v29
	v_cvt_pk_bf16_f32 v163, v30, v31
	s_lshl_b32 vcc_lo, s19, 11
	s_add_u32 vcc_lo, vcc_lo, 0x3400000
	s_add_u32 s100, s16, vcc_lo
	s_addc_u32 s101, s17, 0
	global_store_dwordx2 v137, v[156:157], s[100:101] offset:0
	global_store_dwordx2 v137, v[158:159], s[100:101] offset:512
	global_store_dwordx2 v137, v[160:161], s[100:101] offset:1024
	global_store_dwordx2 v137, v[162:163], s[100:101] offset:1536
	v_mul_f32_e32 v138, v16, v16
	v_mul_f32_e32 v149, v17, v17
	v_mul_f32_e32 v150, v18, v18
	v_mul_f32_e32 v154, v19, v19
	v_fma_f32 v138, v20, v20, v138
	v_fma_f32 v149, v21, v21, v149
	v_fma_f32 v150, v22, v22, v150
	v_fma_f32 v154, v23, v23, v154
	v_fma_f32 v138, v24, v24, v138
	v_fma_f32 v149, v25, v25, v149
	v_fma_f32 v150, v26, v26, v150
	v_fma_f32 v154, v27, v27, v154
	v_fma_f32 v138, v28, v28, v138
	v_fma_f32 v149, v29, v29, v149
	v_fma_f32 v150, v30, v30, v150
	v_fma_f32 v154, v31, v31, v154
	v_add_f32_e32 v138, v138, v149
	v_add_f32_e32 v150, v150, v154
	v_add_f32_e32 v138, v138, v150
	s_nop 1
; __device__ __forceinline__ void row_phase(const Params& P, int glayer, int layer, int xsrc, bool hasY, int gate_idx, const float* gpost,
;                           int xdst, bool doH, const float* gpre, int sh_idx, int nrows) {
;     ...
;         if (hasY) {
;           float4 yv[4];
;           float ss = 0.f;
; #pragma unroll
;           for (int i = 0; i < 4; ++i) {
;             const uint2 raw = yy[u][i];
;             yv[i].x = bf2f((u16)(raw.x & 0xffff)); yv[i].y = bf2f((u16)(raw.x >> 16));
;             yv[i].z = bf2f((u16)(raw.y & 0xffff)); yv[i].w = bf2f((u16)(raw.y >> 16));
;             ss += yv[i].x * yv[i].x + yv[i].y * yv[i].y + yv[i].z * yv[i].z + yv[i].w * yv[i].w;
;           }
;           ss = wave_sum(ss);
;           const float rstd = __builtin_amdgcn_rsqf(ss * (1.f / 1024.f) + EPSF);
; #pragma unroll
;           for (int i = 0; i < 4; ++i) {
;             const int col = (i * 64 + lane) * 4;
;             const float4 gt = *reinterpret_cast<const float4*>(modg + gate_idx * 1024 + col);
;             const float4 gp = *reinterpret_cast<const float4*>(gpost + col);
;             xv[i].x += gt.x * (yv[i].x * rstd * gp.x); xv[i].y += gt.y * (yv[i].y * rstd * gp.y);
;             xv[i].z += gt.z * (yv[i].z * rstd * gp.z); xv[i].w += gt.w * (yv[i].w * rstd * gp.w);
;           }
;         }
;         if (xdst == 3 || (xdst == 1 && row >= N_X)) {
;           float* xout = (xdst == 3) ? P.out + (long)row * 1024 : P.xc + (long)(row - N_X) * 1024;
; #pragma unroll
;           for (int i = 0; i < 4; ++i) *reinterpret_cast<float4*>(xout + (i * 64 + lane) * 4) = xv[i];
;         } else if (xdst != 0) {
;           u16* xo = ((xdst == 1) ? resA : P.zf) + (long)row * 1024;
; #pragma unroll
;           for (int i = 0; i < 4; ++i) {
;             const unsigned b0 = f2bf(xv[i].x), b1 = f2bf(xv[i].y), b2 = f2bf(xv[i].z), b3 = f2bf(xv[i].w);
;             *reinterpret_cast<uint2*>(xo + (i * 64 + lane) * 4) = make_uint2(b0 | (b1 << 16), b2 | (b3 << 16));
;           }
;         }
;         if (doH) {
;           float ss = 0.f;
; #pragma unroll
;           for (int i = 0; i < 4; ++i) ss += xv[i].x * xv[i].x + xv[i].y * xv[i].y + xv[i].z * xv[i].z + xv[i].w * xv[i].w;
;           ss = wave_sum(ss);
;           const float rstd = __builtin_amdgcn_rsqf(ss * (1.f / 1024.f) + EPSF);
;           u16* h = P.hy + (long)row * 1024;
; #pragma unroll
	v_add_f32_dpp v138, v138, v138 quad_perm:[1,0,3,2] row_mask:0xf bank_mask:0xf
	s_nop 1
	v_add_f32_dpp v138, v138, v138 quad_perm:[2,3,0,1] row_mask:0xf bank_mask:0xf
	s_nop 1
	v_add_f32_dpp v138, v138, v138 row_half_mirror row_mask:0xf bank_mask:0xf
	s_nop 1
	v_add_f32_dpp v138, v138, v138 row_mirror row_mask:0xf bank_mask:0xf
	v_mov_b32_e32 v139, v138
	s_nop 1
	v_permlane16_swap_b32_e32 v138, v139
	v_add_f32_e32 v138, v138, v139
	v_mov_b32_e32 v139, v138
	s_nop 1
	v_permlane32_swap_b32_e32 v138, v139
	v_add_f32_e32 v138, v138, v139
	v_mul_f32_e32 v138, 0x3a800000, v138
	v_add_f32_e32 v138, 0x358637bd, v138
	v_rsq_f32_e32 v140, v138
	s_nop 0
	v_mul_f32_e32 v120, v16, v140
	v_mul_f32_e32 v121, v17, v140
	v_mul_f32_e32 v122, v18, v140
	v_mul_f32_e32 v123, v19, v140
	v_mul_f32_e32 v124, v20, v140
	v_mul_f32_e32 v125, v21, v140
	v_mul_f32_e32 v126, v22, v140
	v_mul_f32_e32 v127, v23, v140
	v_mul_f32_e32 v128, v24, v140
	v_mul_f32_e32 v129, v25, v140
	v_mul_f32_e32 v130, v26, v140
	v_mul_f32_e32 v131, v27, v140
	v_mul_f32_e32 v132, v28, v140
	v_mul_f32_e32 v133, v29, v140
	v_mul_f32_e32 v134, v30, v140
	v_mul_f32_e32 v135, v31, v140
	v_fma_f32 v120, v120, v88, v104
	v_fma_f32 v121, v121, v89, v105
	v_fma_f32 v122, v122, v90, v106
	v_fma_f32 v123, v123, v91, v107
	v_fma_f32 v124, v124, v92, v108
	v_fma_f32 v125, v125, v93, v109
	v_fma_f32 v126, v126, v94, v110
	v_fma_f32 v127, v127, v95, v111
	v_fma_f32 v128, v128, v96, v112
	v_fma_f32 v129, v129, v97, v113
	v_fma_f32 v130, v130, v98, v114
	v_fma_f32 v131, v131, v99, v115
	v_fma_f32 v132, v132, v100, v116
	v_fma_f32 v133, v133, v101, v117
	v_fma_f32 v134, v134, v102, v118
	v_fma_f32 v135, v135, v103, v119
	v_cvt_pk_bf16_f32 v156, v120, v121
	v_cvt_pk_bf16_f32 v157, v122, v123
	v_cvt_pk_bf16_f32 v158, v124, v125
	v_cvt_pk_bf16_f32 v159, v126, v127
	v_cvt_pk_bf16_f32 v160, v128, v129
	v_cvt_pk_bf16_f32 v161, v130, v131
	v_cvt_pk_bf16_f32 v162, v132, v133
	v_cvt_pk_bf16_f32 v163, v134, v135
	s_lshl_b32 vcc_lo, s19, 11
	s_add_u32 vcc_lo, vcc_lo, 0x3400000
	s_add_u32 s100, s14, vcc_lo
	s_addc_u32 s101, s15, 0
	global_store_dwordx2 v137, v[156:157], s[100:101] offset:0
	global_store_dwordx2 v137, v[158:159], s[100:101] offset:512
	global_store_dwordx2 v137, v[160:161], s[100:101] offset:1024
	global_store_dwordx2 v137, v[162:163], s[100:101] offset:1536
	s_waitcnt vmcnt(24)
	v_lshlrev_b32_e32 v120, 16, v64
	v_and_b32_e32 v121, 0xffff0000, v64
	v_lshlrev_b32_e32 v122, 16, v65
	v_and_b32_e32 v123, 0xffff0000, v65
	v_lshlrev_b32_e32 v124, 16, v66
	v_and_b32_e32 v125, 0xffff0000, v66
	v_lshlrev_b32_e32 v126, 16, v67
	v_and_b32_e32 v127, 0xffff0000, v67
	v_lshlrev_b32_e32 v128, 16, v68
	v_and_b32_e32 v129, 0xffff0000, v68
	v_lshlrev_b32_e32 v130, 16, v69
	v_and_b32_e32 v131, 0xffff0000, v69
	v_lshlrev_b32_e32 v132, 16, v70
	v_and_b32_e32 v133, 0xffff0000, v70
	v_lshlrev_b32_e32 v134, 16, v71
	v_and_b32_e32 v135, 0xffff0000, v71
	v_mul_f32_e32 v138, v120, v120
	v_mul_f32_e32 v149, v121, v121
	v_mul_f32_e32 v150, v122, v122
	v_mul_f32_e32 v154, v123, v123
	v_fma_f32 v138, v124, v124, v138
	v_fma_f32 v149, v125, v125, v149
	v_fma_f32 v150, v126, v126, v150
	v_fma_f32 v154, v127, v127, v154
	v_fma_f32 v138, v128, v128, v138
	v_fma_f32 v149, v129, v129, v149
	v_fma_f32 v150, v130, v130, v150
	v_fma_f32 v154, v131, v131, v154
	v_fma_f32 v138, v132, v132, v138
	v_fma_f32 v149, v133, v133, v149
	v_fma_f32 v150, v134, v134, v150
	v_fma_f32 v154, v135, v135, v154
	v_add_f32_e32 v138, v138, v149
	v_add_f32_e32 v150, v150, v154
	v_add_f32_e32 v138, v138, v150
	s_nop 1
	v_add_f32_dpp v138, v138, v138 quad_perm:[1,0,3,2] row_mask:0xf bank_mask:0xf
	s_nop 1
	v_add_f32_dpp v138, v138, v138 quad_perm:[2,3,0,1] row_mask:0xf bank_mask:0xf
	s_nop 1
	v_add_f32_dpp v138, v138, v138 row_half_mirror row_mask:0xf bank_mask:0xf
	s_nop 1
	v_add_f32_dpp v138, v138, v138 row_mirror row_mask:0xf bank_mask:0xf
	v_mov_b32_e32 v139, v138
	s_nop 1
	v_permlane16_swap_b32_e32 v138, v139
	v_add_f32_e32 v138, v138, v139
	v_mov_b32_e32 v139, v138
	s_nop 1
	v_permlane32_swap_b32_e32 v138, v139
	v_add_f32_e32 v138, v138, v139
	v_mul_f32_e32 v138, 0x3a800000, v138
	v_add_f32_e32 v138, 0x358637bd, v138
	v_rsq_f32_e32 v140, v138
	v_lshlrev_b32_e32 v32, 16, v40
	v_and_b32_e32 v33, 0xffff0000, v40
	v_lshlrev_b32_e32 v34, 16, v41
	v_and_b32_e32 v35, 0xffff0000, v41
	v_lshlrev_b32_e32 v36, 16, v42
	v_and_b32_e32 v37, 0xffff0000, v42
	v_lshlrev_b32_e32 v38, 16, v43
	v_and_b32_e32 v39, 0xffff0000, v43
	v_lshlrev_b32_e32 v40, 16, v44
	v_and_b32_e32 v41, 0xffff0000, v44
	v_lshlrev_b32_e32 v42, 16, v45
	v_and_b32_e32 v43, 0xffff0000, v45
	v_lshlrev_b32_e32 v44, 16, v46
	v_and_b32_e32 v45, 0xffff0000, v46
	v_lshlrev_b32_e32 v46, 16, v47
	v_and_b32_e32 v47, 0xffff0000, v47
	s_nop 0
	v_mul_f32_e32 v120, v120, v140
	v_mul_f32_e32 v121, v121, v140
	v_mul_f32_e32 v122, v122, v140
	v_mul_f32_e32 v123, v123, v140
	v_mul_f32_e32 v124, v124, v140
	v_mul_f32_e32 v125, v125, v140
	v_mul_f32_e32 v126, v126, v140
	v_mul_f32_e32 v127, v127, v140
	v_mul_f32_e32 v128, v128, v140
	v_mul_f32_e32 v129, v129, v140
	v_mul_f32_e32 v130, v130, v140
	v_mul_f32_e32 v131, v131, v140
	v_mul_f32_e32 v132, v132, v140
	v_mul_f32_e32 v133, v133, v140
	v_mul_f32_e32 v134, v134, v140
	v_mul_f32_e32 v135, v135, v140
	v_fma_f32 v32, v120, v72, v32
	v_fma_f32 v33, v121, v73, v33
	v_fma_f32 v34, v122, v74, v34
	v_fma_f32 v35, v123, v75, v35
	v_fma_f32 v36, v124, v76, v36
	v_fma_f32 v37, v125, v77, v37
	v_fma_f32 v38, v126, v78, v38
	v_fma_f32 v39, v127, v79, v39
	v_fma_f32 v40, v128, v80, v40
	v_fma_f32 v41, v129, v81, v41
	v_fma_f32 v42, v130, v82, v42
	v_fma_f32 v43, v131, v83, v43
; __device__ __forceinline__ void row_phase(const Params& P, int glayer, int layer, int xsrc, bool hasY, int gate_idx, const float* gpost,
;                           int xdst, bool doH, const float* gpre, int sh_idx, int nrows) {
;     ...
; #pragma unroll
;           for (int i = 0; i < 4; ++i) {
;             const int col = (i * 64 + lane) * 4;
;             const float4 gt = *reinterpret_cast<const float4*>(modg + gate_idx * 1024 + col);
;             const float4 gp = *reinterpret_cast<const float4*>(gpost + col);
;             xv[i].x += gt.x * (yv[i].x * rstd * gp.x); xv[i].y += gt.y * (yv[i].y * rstd * gp.y);
;             xv[i].z += gt.z * (yv[i].z * rstd * gp.z); xv[i].w += gt.w * (yv[i].w * rstd * gp.w);
;           }
;         }
;         if (xdst == 3 || (xdst == 1 && row >= N_X)) {
;           float* xout = (xdst == 3) ? P.out + (long)row * 1024 : P.xc + (long)(row - N_X) * 1024;
; #pragma unroll
;           for (int i = 0; i < 4; ++i) *reinterpret_cast<float4*>(xout + (i * 64 + lane) * 4) = xv[i];
;         } else if (xdst != 0) {
;           u16* xo = ((xdst == 1) ? resA : P.zf) + (long)row * 1024;
; #pragma unroll
;           for (int i = 0; i < 4; ++i) {
;             const unsigned b0 = f2bf(xv[i].x), b1 = f2bf(xv[i].y), b2 = f2bf(xv[i].z), b3 = f2bf(xv[i].w);
;             *reinterpret_cast<uint2*>(xo + (i * 64 + lane) * 4) = make_uint2(b0 | (b1 << 16), b2 | (b3 << 16));
;           }
;         }
;         if (doH) {
;           float ss = 0.f;
; #pragma unroll
;           for (int i = 0; i < 4; ++i) ss += xv[i].x * xv[i].x + xv[i].y * xv[i].y + xv[i].z * xv[i].z + xv[i].w * xv[i].w;
;           ss = wave_sum(ss);
;           const float rstd = __builtin_amdgcn_rsqf(ss * (1.f / 1024.f) + EPSF);
;           u16* h = P.hy + (long)row * 1024;
; #pragma unroll
;           for (int i = 0; i < 4; ++i) {
;             const int col = (i * 64 + lane) * 4;
;             const float4 g = *reinterpret_cast<const float4*>(gpre + col);
;             const float4 sh = *reinterpret_cast<const float4*>(modp + sh_idx * 1024 + col);
;             const float4 sc = *reinterpret_cast<const float4*>(modp + (sh_idx + 1) * 1024 + col);
;             const unsigned h0 = f2bf(xv[i].x * rstd * g.x * (1.f + sc.x) + sh.x);
;             const unsigned h1 = f2bf(xv[i].y * rstd * g.y * (1.f + sc.y) + sh.y);
	v_fma_f32 v44, v132, v84, v44
	v_fma_f32 v45, v133, v85, v45
	v_fma_f32 v46, v134, v86, v46
	v_fma_f32 v47, v135, v87, v47
	v_cvt_pk_bf16_f32 v156, v32, v33
	v_cvt_pk_bf16_f32 v157, v34, v35
	v_cvt_pk_bf16_f32 v158, v36, v37
	v_cvt_pk_bf16_f32 v159, v38, v39
	v_cvt_pk_bf16_f32 v160, v40, v41
	v_cvt_pk_bf16_f32 v161, v42, v43
	v_cvt_pk_bf16_f32 v162, v44, v45
	v_cvt_pk_bf16_f32 v163, v46, v47
	s_lshl_b32 vcc_lo, s19, 11
	s_add_u32 vcc_lo, vcc_lo, 0x3800000
	s_add_u32 s100, s16, vcc_lo
	s_addc_u32 s101, s17, 0
	global_store_dwordx2 v137, v[156:157], s[100:101] offset:0
	global_store_dwordx2 v137, v[158:159], s[100:101] offset:512
	global_store_dwordx2 v137, v[160:161], s[100:101] offset:1024
	global_store_dwordx2 v137, v[162:163], s[100:101] offset:1536
	v_mul_f32_e32 v138, v32, v32
	v_mul_f32_e32 v149, v33, v33
	v_mul_f32_e32 v150, v34, v34
	v_mul_f32_e32 v154, v35, v35
	v_fma_f32 v138, v36, v36, v138
	v_fma_f32 v149, v37, v37, v149
	v_fma_f32 v150, v38, v38, v150
	v_fma_f32 v154, v39, v39, v154
	v_fma_f32 v138, v40, v40, v138
	v_fma_f32 v149, v41, v41, v149
	v_fma_f32 v150, v42, v42, v150
	v_fma_f32 v154, v43, v43, v154
	v_fma_f32 v138, v44, v44, v138
	v_fma_f32 v149, v45, v45, v149
	v_fma_f32 v150, v46, v46, v150
	v_fma_f32 v154, v47, v47, v154
	v_add_f32_e32 v138, v138, v149
	v_add_f32_e32 v150, v150, v154
	v_add_f32_e32 v138, v138, v150
	s_nop 1
	v_add_f32_dpp v138, v138, v138 quad_perm:[1,0,3,2] row_mask:0xf bank_mask:0xf
	s_nop 1
	v_add_f32_dpp v138, v138, v138 quad_perm:[2,3,0,1] row_mask:0xf bank_mask:0xf
	s_nop 1
	v_add_f32_dpp v138, v138, v138 row_half_mirror row_mask:0xf bank_mask:0xf
	s_nop 1
	v_add_f32_dpp v138, v138, v138 row_mirror row_mask:0xf bank_mask:0xf
	v_mov_b32_e32 v139, v138
	s_nop 1
	v_permlane16_swap_b32_e32 v138, v139
	v_add_f32_e32 v138, v138, v139
	v_mov_b32_e32 v139, v138
	s_nop 1
	v_permlane32_swap_b32_e32 v138, v139
	v_add_f32_e32 v138, v138, v139
	v_mul_f32_e32 v138, 0x3a800000, v138
	v_add_f32_e32 v138, 0x358637bd, v138
	v_rsq_f32_e32 v140, v138
	s_nop 0
	v_mul_f32_e32 v120, v32, v140
	v_mul_f32_e32 v121, v33, v140
	v_mul_f32_e32 v122, v34, v140
	v_mul_f32_e32 v123, v35, v140
	v_mul_f32_e32 v124, v36, v140
	v_mul_f32_e32 v125, v37, v140
	v_mul_f32_e32 v126, v38, v140
	v_mul_f32_e32 v127, v39, v140
	v_mul_f32_e32 v128, v40, v140
	v_mul_f32_e32 v129, v41, v140
	v_mul_f32_e32 v130, v42, v140
	v_mul_f32_e32 v131, v43, v140
	v_mul_f32_e32 v132, v44, v140
	v_mul_f32_e32 v133, v45, v140
	v_mul_f32_e32 v134, v46, v140
	v_mul_f32_e32 v135, v47, v140
	v_fma_f32 v120, v120, v88, v104
	v_fma_f32 v121, v121, v89, v105
	v_fma_f32 v122, v122, v90, v106
	v_fma_f32 v123, v123, v91, v107
	v_fma_f32 v124, v124, v92, v108
	v_fma_f32 v125, v125, v93, v109
	v_fma_f32 v126, v126, v94, v110
	v_fma_f32 v127, v127, v95, v111
	v_fma_f32 v128, v128, v96, v112
	v_fma_f32 v129, v129, v97, v113
	v_fma_f32 v130, v130, v98, v114
	v_fma_f32 v131, v131, v99, v115
	v_fma_f32 v132, v132, v100, v116
	v_fma_f32 v133, v133, v101, v117
	v_fma_f32 v134, v134, v102, v118
	v_fma_f32 v135, v135, v103, v119
	v_cvt_pk_bf16_f32 v156, v120, v121
	v_cvt_pk_bf16_f32 v157, v122, v123
	v_cvt_pk_bf16_f32 v158, v124, v125
	v_cvt_pk_bf16_f32 v159, v126, v127
	v_cvt_pk_bf16_f32 v160, v128, v129
	v_cvt_pk_bf16_f32 v161, v130, v131
	v_cvt_pk_bf16_f32 v162, v132, v133
	v_cvt_pk_bf16_f32 v163, v134, v135
	s_lshl_b32 vcc_lo, s19, 11
	s_add_u32 vcc_lo, vcc_lo, 0x3800000
	s_add_u32 s100, s14, vcc_lo
	s_addc_u32 s101, s15, 0
	global_store_dwordx2 v137, v[156:157], s[100:101] offset:0
	global_store_dwordx2 v137, v[158:159], s[100:101] offset:512
	global_store_dwordx2 v137, v[160:161], s[100:101] offset:1024
	global_store_dwordx2 v137, v[162:163], s[100:101] offset:1536
	s_waitcnt vmcnt(16)
; __device__ __forceinline__ void row_phase(const Params& P, int glayer, int layer, int xsrc, bool hasY, int gate_idx, const float* gpost,
;                           int xdst, bool doH, const float* gpre, int sh_idx, int nrows) {
;     ...
;         if (hasY) {
;           float4 yv[4];
;           float ss = 0.f;
; #pragma unroll
;           for (int i = 0; i < 4; ++i) {
;             const uint2 raw = yy[u][i];
;             yv[i].x = bf2f((u16)(raw.x & 0xffff)); yv[i].y = bf2f((u16)(raw.x >> 16));
;             yv[i].z = bf2f((u16)(raw.y & 0xffff)); yv[i].w = bf2f((u16)(raw.y >> 16));
;             ss += yv[i].x * yv[i].x + yv[i].y * yv[i].y + yv[i].z * yv[i].z + yv[i].w * yv[i].w;
;           }
;           ss = wave_sum(ss);
;           const float rstd = __builtin_amdgcn_rsqf(ss * (1.f / 1024.f) + EPSF);
; #pragma unroll
;           for (int i = 0; i < 4; ++i) {
;             const int col = (i * 64 + lane) * 4;
;             const float4 gt = *reinterpret_cast<const float4*>(modg + gate_idx * 1024 + col);
;             const float4 gp = *reinterpret_cast<const float4*>(gpost + col);
;             xv[i].x += gt.x * (yv[i].x * rstd * gp.x); xv[i].y += gt.y * (yv[i].y * rstd * gp.y);
;             xv[i].z += gt.z * (yv[i].z * rstd * gp.z); xv[i].w += gt.w * (yv[i].w * rstd * gp.w);
;           }
;         }
;         if (xdst == 3 || (xdst == 1 && row >= N_X)) {
;           float* xout = (xdst == 3) ? P.out + (long)row * 1024 : P.xc + (long)(row - N_X) * 1024;
; #pragma unroll
;           for (int i = 0; i < 4; ++i) *reinterpret_cast<float4*>(xout + (i * 64 + lane) * 4) = xv[i];
;         } else if (xdst != 0) {
;           u16* xo = ((xdst == 1) ? resA : P.zf) + (long)row * 1024;
; #pragma unroll
;           for (int i = 0; i < 4; ++i) {
;             const unsigned b0 = f2bf(xv[i].x), b1 = f2bf(xv[i].y), b2 = f2bf(xv[i].z), b3 = f2bf(xv[i].w);
;             *reinterpret_cast<uint2*>(xo + (i * 64 + lane) * 4) = make_uint2(b0 | (b1 << 16), b2 | (b3 << 16));
;           }
;         }
;         if (doH) {
;           float ss = 0.f;
; #pragma unroll
;           for (int i = 0; i < 4; ++i) ss += xv[i].x * xv[i].x + xv[i].y * xv[i].y + xv[i].z * xv[i].z + xv[i].w * xv[i].w;
;           ss = wave_sum(ss);
;           const float rstd = __builtin_amdgcn_rsqf(ss * (1.f / 1024.f) + EPSF);
;           u16* h = P.hy + (long)row * 1024;
; #pragma unroll
	v_lshlrev_b32_e32 v120, 16, v48
	v_and_b32_e32 v121, 0xffff0000, v48
	v_lshlrev_b32_e32 v122, 16, v49
	v_and_b32_e32 v123, 0xffff0000, v49
	v_lshlrev_b32_e32 v124, 16, v50
	v_and_b32_e32 v125, 0xffff0000, v50
	v_lshlrev_b32_e32 v126, 16, v51
	v_and_b32_e32 v127, 0xffff0000, v51
	v_lshlrev_b32_e32 v128, 16, v52
	v_and_b32_e32 v129, 0xffff0000, v52
	v_lshlrev_b32_e32 v130, 16, v53
	v_and_b32_e32 v131, 0xffff0000, v53
	v_lshlrev_b32_e32 v132, 16, v54
	v_and_b32_e32 v133, 0xffff0000, v54
	v_lshlrev_b32_e32 v134, 16, v55
	v_and_b32_e32 v135, 0xffff0000, v55
	v_mul_f32_e32 v138, v120, v120
	v_mul_f32_e32 v149, v121, v121
	v_mul_f32_e32 v150, v122, v122
	v_mul_f32_e32 v154, v123, v123
	v_fma_f32 v138, v124, v124, v138
	v_fma_f32 v149, v125, v125, v149
	v_fma_f32 v150, v126, v126, v150
	v_fma_f32 v154, v127, v127, v154
	v_fma_f32 v138, v128, v128, v138
	v_fma_f32 v149, v129, v129, v149
	v_fma_f32 v150, v130, v130, v150
	v_fma_f32 v154, v131, v131, v154
	v_fma_f32 v138, v132, v132, v138
	v_fma_f32 v149, v133, v133, v149
	v_fma_f32 v150, v134, v134, v150
	v_fma_f32 v154, v135, v135, v154
	v_add_f32_e32 v138, v138, v149
	v_add_f32_e32 v150, v150, v154
	v_add_f32_e32 v138, v138, v150
	s_nop 1
	v_add_f32_dpp v138, v138, v138 quad_perm:[1,0,3,2] row_mask:0xf bank_mask:0xf
	s_nop 1
	v_add_f32_dpp v138, v138, v138 quad_perm:[2,3,0,1] row_mask:0xf bank_mask:0xf
	s_nop 1
	v_add_f32_dpp v138, v138, v138 row_half_mirror row_mask:0xf bank_mask:0xf
	s_nop 1
	v_add_f32_dpp v138, v138, v138 row_mirror row_mask:0xf bank_mask:0xf
	v_mov_b32_e32 v139, v138
	s_nop 1
	v_permlane16_swap_b32_e32 v138, v139
	v_add_f32_e32 v138, v138, v139
	v_mov_b32_e32 v139, v138
	s_nop 1
	v_permlane32_swap_b32_e32 v138, v139
	v_add_f32_e32 v138, v138, v139
	v_mul_f32_e32 v138, 0x3a800000, v138
	v_add_f32_e32 v138, 0x358637bd, v138
	v_rsq_f32_e32 v140, v138
	v_lshlrev_b32_e32 v0, 16, v8
	v_and_b32_e32 v1, 0xffff0000, v8
	v_lshlrev_b32_e32 v2, 16, v9
	v_and_b32_e32 v3, 0xffff0000, v9
	v_lshlrev_b32_e32 v4, 16, v10
	v_and_b32_e32 v5, 0xffff0000, v10
	v_lshlrev_b32_e32 v6, 16, v11
	v_and_b32_e32 v7, 0xffff0000, v11
	v_lshlrev_b32_e32 v8, 16, v12
	v_and_b32_e32 v9, 0xffff0000, v12
	v_lshlrev_b32_e32 v10, 16, v13
	v_and_b32_e32 v11, 0xffff0000, v13
	v_lshlrev_b32_e32 v12, 16, v14
	v_and_b32_e32 v13, 0xffff0000, v14
	v_lshlrev_b32_e32 v14, 16, v15
	v_and_b32_e32 v15, 0xffff0000, v15
	s_nop 0
	v_mul_f32_e32 v120, v120, v140
	v_mul_f32_e32 v121, v121, v140
	v_mul_f32_e32 v122, v122, v140
	v_mul_f32_e32 v123, v123, v140
	v_mul_f32_e32 v124, v124, v140
	v_mul_f32_e32 v125, v125, v140
	v_mul_f32_e32 v126, v126, v140
	v_mul_f32_e32 v127, v127, v140
	v_mul_f32_e32 v128, v128, v140
	v_mul_f32_e32 v129, v129, v140
	v_mul_f32_e32 v130, v130, v140
	v_mul_f32_e32 v131, v131, v140
	v_mul_f32_e32 v132, v132, v140
	v_mul_f32_e32 v133, v133, v140
	v_mul_f32_e32 v134, v134, v140
	v_mul_f32_e32 v135, v135, v140
	v_fma_f32 v0, v120, v72, v0
	v_fma_f32 v1, v121, v73, v1
	v_fma_f32 v2, v122, v74, v2
	v_fma_f32 v3, v123, v75, v3
	v_fma_f32 v4, v124, v76, v4
	v_fma_f32 v5, v125, v77, v5
	v_fma_f32 v6, v126, v78, v6
	v_fma_f32 v7, v127, v79, v7
	v_fma_f32 v8, v128, v80, v8
	v_fma_f32 v9, v129, v81, v9
	v_fma_f32 v10, v130, v82, v10
	v_fma_f32 v11, v131, v83, v11
	v_fma_f32 v12, v132, v84, v12
	v_fma_f32 v13, v133, v85, v13
	v_fma_f32 v14, v134, v86, v14
	v_fma_f32 v15, v135, v87, v15
	v_cvt_pk_bf16_f32 v156, v0, v1
	v_cvt_pk_bf16_f32 v157, v2, v3
	v_cvt_pk_bf16_f32 v158, v4, v5
	v_cvt_pk_bf16_f32 v159, v6, v7
	v_cvt_pk_bf16_f32 v160, v8, v9
	v_cvt_pk_bf16_f32 v161, v10, v11
	v_cvt_pk_bf16_f32 v162, v12, v13
	v_cvt_pk_bf16_f32 v163, v14, v15
	s_lshl_b32 vcc_lo, s19, 11
	s_add_u32 vcc_lo, vcc_lo, 0x3c00000
	s_add_u32 s100, s16, vcc_lo
	s_addc_u32 s101, s17, 0
	global_store_dwordx2 v137, v[156:157], s[100:101] offset:0
	global_store_dwordx2 v137, v[158:159], s[100:101] offset:512
	global_store_dwordx2 v137, v[160:161], s[100:101] offset:1024
	global_store_dwordx2 v137, v[162:163], s[100:101] offset:1536
	v_mul_f32_e32 v138, v0, v0
	v_mul_f32_e32 v149, v1, v1
	v_mul_f32_e32 v150, v2, v2
	v_mul_f32_e32 v154, v3, v3
	v_fma_f32 v138, v4, v4, v138
	v_fma_f32 v149, v5, v5, v149
	v_fma_f32 v150, v6, v6, v150
	v_fma_f32 v154, v7, v7, v154
	v_fma_f32 v138, v8, v8, v138
	v_fma_f32 v149, v9, v9, v149
	v_fma_f32 v150, v10, v10, v150
	v_fma_f32 v154, v11, v11, v154
	v_fma_f32 v138, v12, v12, v138
	v_fma_f32 v149, v13, v13, v149
	v_fma_f32 v150, v14, v14, v150
	v_fma_f32 v154, v15, v15, v154
	v_add_f32_e32 v138, v138, v149
	v_add_f32_e32 v150, v150, v154
	v_add_f32_e32 v138, v138, v150
	s_nop 1
	v_add_f32_dpp v138, v138, v138 quad_perm:[1,0,3,2] row_mask:0xf bank_mask:0xf
	s_nop 1
	v_add_f32_dpp v138, v138, v138 quad_perm:[2,3,0,1] row_mask:0xf bank_mask:0xf
	s_nop 1
	v_add_f32_dpp v138, v138, v138 row_half_mirror row_mask:0xf bank_mask:0xf
	s_nop 1
	v_add_f32_dpp v138, v138, v138 row_mirror row_mask:0xf bank_mask:0xf
	v_mov_b32_e32 v139, v138
	s_nop 1
	v_permlane16_swap_b32_e32 v138, v139
	v_add_f32_e32 v138, v138, v139
	v_mov_b32_e32 v139, v138
	s_nop 1
	v_permlane32_swap_b32_e32 v138, v139
	v_add_f32_e32 v138, v138, v139
	v_mul_f32_e32 v138, 0x3a800000, v138
	v_add_f32_e32 v138, 0x358637bd, v138
	v_rsq_f32_e32 v140, v138
	s_nop 0
	v_mul_f32_e32 v120, v0, v140
	v_mul_f32_e32 v121, v1, v140
	v_mul_f32_e32 v122, v2, v140
	v_mul_f32_e32 v123, v3, v140
	v_mul_f32_e32 v124, v4, v140
	v_mul_f32_e32 v125, v5, v140
	v_mul_f32_e32 v126, v6, v140
	v_mul_f32_e32 v127, v7, v140
	v_mul_f32_e32 v128, v8, v140
	v_mul_f32_e32 v129, v9, v140
	v_mul_f32_e32 v130, v10, v140
	v_mul_f32_e32 v131, v11, v140
	v_mul_f32_e32 v132, v12, v140
	v_mul_f32_e32 v133, v13, v140
	v_mul_f32_e32 v134, v14, v140
	v_mul_f32_e32 v135, v15, v140
	v_fma_f32 v120, v120, v88, v104
	v_fma_f32 v121, v121, v89, v105
	v_fma_f32 v122, v122, v90, v106
	v_fma_f32 v123, v123, v91, v107
	v_fma_f32 v124, v124, v92, v108
	v_fma_f32 v125, v125, v93, v109
	v_fma_f32 v126, v126, v94, v110
	v_fma_f32 v127, v127, v95, v111
	v_fma_f32 v128, v128, v96, v112
	v_fma_f32 v129, v129, v97, v113
	v_fma_f32 v130, v130, v98, v114
	v_fma_f32 v131, v131, v99, v115
	v_fma_f32 v132, v132, v100, v116
	v_fma_f32 v133, v133, v101, v117
	v_fma_f32 v134, v134, v102, v118
	v_fma_f32 v135, v135, v103, v119
	v_cvt_pk_bf16_f32 v156, v120, v121
	v_cvt_pk_bf16_f32 v157, v122, v123
	v_cvt_pk_bf16_f32 v158, v124, v125
	v_cvt_pk_bf16_f32 v159, v126, v127
	v_cvt_pk_bf16_f32 v160, v128, v129
	v_cvt_pk_bf16_f32 v161, v130, v131
	v_cvt_pk_bf16_f32 v162, v132, v133
	v_cvt_pk_bf16_f32 v163, v134, v135
	s_lshl_b32 vcc_lo, s19, 11
	s_add_u32 vcc_lo, vcc_lo, 0x3c00000
	s_add_u32 s100, s14, vcc_lo
	s_addc_u32 s101, s15, 0
	global_store_dwordx2 v137, v[156:157], s[100:101] offset:0
	global_store_dwordx2 v137, v[158:159], s[100:101] offset:512
	global_store_dwordx2 v137, v[160:161], s[100:101] offset:1024
	global_store_dwordx2 v137, v[162:163], s[100:101] offset:1536
	s_branch .LBB0_1678

; __device__ __forceinline__ void row_phase(const Params& P, int glayer, int layer, int xsrc, bool hasY, int gate_idx, const float* gpost,
;                           int xdst, bool doH, const float* gpre, int sh_idx, int nrows) {
;     ...
;   for (int rb = blockIdx.x * 8 + wid; rb < nrows; rb += 4 * stride) {
;     uint4 xr[4][4];
;     uint2 yy[4][4];
; #pragma unroll
;     for (int u = 0; u < 4; ++u) {
;       const int R = rb + u * stride;
;       if (R < nrows) {
;         if (xsrc != 0 && R < N_X) {
;           const u16* xs_ = ((xsrc == 1) ? resA : P.zf) + (long)R * 1024;
; #pragma unroll
;           for (int i = 0; i < 4; ++i) {
;             const uint2 t2 = *reinterpret_cast<const uint2*>(xs_ + (i * 64 + lane) * 4);
;             xr[u][i].x = t2.x; xr[u][i].y = t2.y;
;           }
;         } else {
;           const float* xin_;
;           if (xsrc == 0) xin_ = R < N_X ? P.x + (long)R * 1024 : P.ctx + (long)(R - N_X) * 1024;
;           else           xin_ = P.xc + (long)(R - N_X) * 1024;
; #pragma unroll
;           for (int i = 0; i < 4; ++i) xr[u][i] = *reinterpret_cast<const uint4*>(xin_ + (i * 64 + lane) * 4);
;         }
;         if (hasY) {
;           const u16* y_ = P.hy + (long)R * 1024;
; #pragma unroll
;           for (int i = 0; i < 4; ++i) yy[u][i] = *reinterpret_cast<const uint2*>(y_ + (i * 64 + lane) * 4);
;         }
;       }
;     }
;     ...
;           ss = wave_sum(ss);
;           const float rstd = __builtin_amdgcn_rsqf(ss * (1.f / 1024.f) + EPSF);
; #pragma unroll
;           for (int i = 0; i < 4; ++i) {
;             const int col = (i * 64 + lane) * 4;
;             const float4 gt = *reinterpret_cast<const float4*>(modg + gate_idx * 1024 + col);
;             const float4 gp = *reinterpret_cast<const float4*>(gpost + col);
;             xv[i].x += gt.x * (yv[i].x * rstd * gp.x); xv[i].y += gt.y * (yv[i].y * rstd * gp.y);
;             xv[i].z += gt.z * (yv[i].z * rstd * gp.z); xv[i].w += gt.w * (yv[i].w * rstd * gp.w);
;           }
.LBB0_1946:
	s_cmp_gt_i32 s34, 17
	s_cselect_b64 s[0:1], -1, 0
	s_cmp_lt_i32 s35, 18
	s_cselect_b64 s[4:5], -1, 0
	s_or_b64 s[0:1], s[0:1], s[4:5]
	s_and_b64 vcc, exec, s[0:1]
	s_cbranch_vccnz .LBB0_2016
	s_waitcnt vmcnt(16)
	v_lshl_add_u32 v0, s2, 3, v204
	s_mov_b32 s18, 0x8000
	v_cmp_gt_i32_e32 vcc, s18, v0
	s_and_saveexec_b64 s[0:1], vcc
	s_cbranch_execz .LBB0_1962
	v_readlane_b32 s4, v252, 0
	v_readlane_b32 s5, v252, 1
	v_readfirstlane_b32 s19, v204
	s_nop 3
	s_sub_u32 s4, s4, 0x170
	s_subb_u32 s5, s5, 0
	s_load_dwordx2 s[12:13], s[4:5], 0x150
	s_load_dwordx2 s[14:15], s[4:5], 0x140
	s_load_dwordx2 s[16:17], s[4:5], 0xc8
	s_load_dwordx2 s[20:21], s[4:5], 0x100
	s_lshl_b32 s98, s2, 3
	s_add_u32 s19, s98, s19
	v_and_b32_e32 v136, 63, v152
	v_lshlrev_b32_e32 v137, 3, v136
	v_lshlrev_b32_e32 v136, 4, v136
	s_waitcnt lgkmcnt(0)
	s_lshl_b32 vcc_lo, s19, 11
	s_add_u32 s100, s12, vcc_lo
	s_addc_u32 s101, s13, 0
	global_load_dwordx2 v[8:9], v137, s[100:101] offset:0
	global_load_dwordx2 v[10:11], v137, s[100:101] offset:512
	global_load_dwordx2 v[12:13], v137, s[100:101] offset:1024
	global_load_dwordx2 v[14:15], v137, s[100:101] offset:1536
	s_lshl_b32 vcc_lo, s19, 11
	s_add_u32 s100, s14, vcc_lo
	s_addc_u32 s101, s15, 0
	global_load_dwordx2 v[48:49], v137, s[100:101] offset:0
	global_load_dwordx2 v[50:51], v137, s[100:101] offset:512
	global_load_dwordx2 v[52:53], v137, s[100:101] offset:1024
	global_load_dwordx2 v[54:55], v137, s[100:101] offset:1536
	s_lshl_b32 vcc_lo, s19, 11
	s_add_u32 vcc_lo, vcc_lo, 0x400000
	s_add_u32 s100, s12, vcc_lo
	s_addc_u32 s101, s13, 0
	global_load_dwordx2 v[24:25], v137, s[100:101] offset:0
	global_load_dwordx2 v[26:27], v137, s[100:101] offset:512
	global_load_dwordx2 v[28:29], v137, s[100:101] offset:1024
	global_load_dwordx2 v[30:31], v137, s[100:101] offset:1536
	s_lshl_b32 vcc_lo, s19, 11
	s_add_u32 vcc_lo, vcc_lo, 0x400000
	s_add_u32 s100, s14, vcc_lo
	s_addc_u32 s101, s15, 0
	global_load_dwordx2 v[56:57], v137, s[100:101] offset:0
	global_load_dwordx2 v[58:59], v137, s[100:101] offset:512
	global_load_dwordx2 v[60:61], v137, s[100:101] offset:1024
	global_load_dwordx2 v[62:63], v137, s[100:101] offset:1536
	s_add_u32 s100, s20, 0x23000
	s_addc_u32 s101, s21, 0
	global_load_dwordx4 v[72:75], v136, s[100:101] offset:0
	global_load_dwordx4 v[76:79], v136, s[100:101] offset:1024
	global_load_dwordx4 v[80:83], v136, s[100:101] offset:2048
	global_load_dwordx4 v[84:87], v136, s[100:101] offset:3072
	s_load_dwordx2 s[98:99], s[4:5], 0x48
	s_waitcnt lgkmcnt(0)
	s_add_u32 s98, s98, 0x1000
	s_addc_u32 s99, s99, 0
	global_load_dwordx4 v[120:123], v136, s[98:99] offset:0
	global_load_dwordx4 v[124:127], v136, s[98:99] offset:1024
	global_load_dwordx4 v[128:131], v136, s[98:99] offset:2048
	global_load_dwordx4 v[132:135], v136, s[98:99] offset:3072
	s_waitcnt vmcnt(0)
	v_mul_f32_e32 v72, v72, v120
	v_mul_f32_e32 v73, v73, v121
	v_mul_f32_e32 v74, v74, v122
	v_mul_f32_e32 v75, v75, v123
	v_mul_f32_e32 v76, v76, v124
	v_mul_f32_e32 v77, v77, v125
	v_mul_f32_e32 v78, v78, v126
	v_mul_f32_e32 v79, v79, v127
	v_mul_f32_e32 v80, v80, v128
	v_mul_f32_e32 v81, v81, v129
	v_mul_f32_e32 v82, v82, v130
	v_mul_f32_e32 v83, v83, v131
	v_mul_f32_e32 v84, v84, v132
	v_mul_f32_e32 v85, v85, v133
	v_mul_f32_e32 v86, v86, v134
	v_mul_f32_e32 v87, v87, v135
	s_lshl_b32 vcc_lo, s19, 11
	s_add_u32 vcc_lo, vcc_lo, 0x800000
	s_add_u32 s100, s12, vcc_lo
	s_addc_u32 s101, s13, 0
	global_load_dwordx2 v[40:41], v137, s[100:101] offset:0
	global_load_dwordx2 v[42:43], v137, s[100:101] offset:512
	global_load_dwordx2 v[44:45], v137, s[100:101] offset:1024
	global_load_dwordx2 v[46:47], v137, s[100:101] offset:1536
	s_lshl_b32 vcc_lo, s19, 11
	s_add_u32 vcc_lo, vcc_lo, 0x800000
	s_add_u32 s100, s14, vcc_lo
	s_addc_u32 s101, s15, 0
	global_load_dwordx2 v[64:65], v137, s[100:101] offset:0
	global_load_dwordx2 v[66:67], v137, s[100:101] offset:512
	global_load_dwordx2 v[68:69], v137, s[100:101] offset:1024
	global_load_dwordx2 v[70:71], v137, s[100:101] offset:1536
	v_lshlrev_b32_e32 v120, 16, v48
	v_and_b32_e32 v121, 0xffff0000, v48
	v_lshlrev_b32_e32 v122, 16, v49
	v_and_b32_e32 v123, 0xffff0000, v49
	v_lshlrev_b32_e32 v124, 16, v50
	v_and_b32_e32 v125, 0xffff0000, v50
	v_lshlrev_b32_e32 v126, 16, v51
	v_and_b32_e32 v127, 0xffff0000, v51
	v_lshlrev_b32_e32 v128, 16, v52
	v_and_b32_e32 v129, 0xffff0000, v52
	v_lshlrev_b32_e32 v130, 16, v53
	v_and_b32_e32 v131, 0xffff0000, v53
	v_lshlrev_b32_e32 v132, 16, v54
	v_and_b32_e32 v133, 0xffff0000, v54
	v_lshlrev_b32_e32 v134, 16, v55
	v_and_b32_e32 v135, 0xffff0000, v55
	v_mul_f32_e32 v138, v120, v120
	v_mul_f32_e32 v149, v121, v121
	v_mul_f32_e32 v150, v122, v122
	v_mul_f32_e32 v154, v123, v123
	v_fma_f32 v138, v124, v124, v138
	v_fma_f32 v149, v125, v125, v149
	v_fma_f32 v150, v126, v126, v150
	v_fma_f32 v154, v127, v127, v154
	v_fma_f32 v138, v128, v128, v138
	v_fma_f32 v149, v129, v129, v149
	v_fma_f32 v150, v130, v130, v150
	v_fma_f32 v154, v131, v131, v154
	v_fma_f32 v138, v132, v132, v138
	v_fma_f32 v149, v133, v133, v149
	v_fma_f32 v150, v134, v134, v150
	v_fma_f32 v154, v135, v135, v154
	v_add_f32_e32 v138, v138, v149
	v_add_f32_e32 v150, v150, v154
	v_add_f32_e32 v138, v138, v150
	s_nop 1
	v_add_f32_dpp v138, v138, v138 quad_perm:[1,0,3,2] row_mask:0xf bank_mask:0xf
	s_nop 1
	v_add_f32_dpp v138, v138, v138 quad_perm:[2,3,0,1] row_mask:0xf bank_mask:0xf
	s_nop 1
	v_add_f32_dpp v138, v138, v138 row_half_mirror row_mask:0xf bank_mask:0xf
	s_nop 1
	v_add_f32_dpp v138, v138, v138 row_mirror row_mask:0xf bank_mask:0xf
	v_mov_b32_e32 v139, v138
	s_nop 1
	v_permlane16_swap_b32_e32 v138, v139
; __device__ __forceinline__ float bf2f(u16 h) { return __uint_as_float(((unsigned)h) << 16); }
; __device__ __forceinline__ void row_phase(const Params& P, int glayer, int layer, int xsrc, bool hasY, int gate_idx, const float* gpost,
;                           int xdst, bool doH, const float* gpre, int sh_idx, int nrows) {
;     ...
;         if (xsrc != 0 && row < N_X) {
; #pragma unroll
;           for (int i = 0; i < 4; ++i) {
;             const uint4 raw = xr[u][i];
;             xv[i].x = bf2f((u16)(raw.x & 0xffff)); xv[i].y = bf2f((u16)(raw.x >> 16));
;             xv[i].z = bf2f((u16)(raw.y & 0xffff)); xv[i].w = bf2f((u16)(raw.y >> 16));
;           }
;         } else {
; #pragma unroll
;           for (int i = 0; i < 4; ++i) {
;             xv[i].x = __uint_as_float(xr[u][i].x); xv[i].y = __uint_as_float(xr[u][i].y);
;             xv[i].z = __uint_as_float(xr[u][i].z); xv[i].w = __uint_as_float(xr[u][i].w);
;           }
;         }
;         if (hasY) {
;           float4 yv[4];
;           float ss = 0.f;
; #pragma unroll
;           for (int i = 0; i < 4; ++i) {
;             const uint2 raw = yy[u][i];
;             yv[i].x = bf2f((u16)(raw.x & 0xffff)); yv[i].y = bf2f((u16)(raw.x >> 16));
;             yv[i].z = bf2f((u16)(raw.y & 0xffff)); yv[i].w = bf2f((u16)(raw.y >> 16));
;             ss += yv[i].x * yv[i].x + yv[i].y * yv[i].y + yv[i].z * yv[i].z + yv[i].w * yv[i].w;
;           }
;           ss = wave_sum(ss);
;           const float rstd = __builtin_amdgcn_rsqf(ss * (1.f / 1024.f) + EPSF);
; #pragma unroll
;           for (int i = 0; i < 4; ++i) {
;             const int col = (i * 64 + lane) * 4;
;             const float4 gt = *reinterpret_cast<const float4*>(modg + gate_idx * 1024 + col);
;             const float4 gp = *reinterpret_cast<const float4*>(gpost + col);
;             xv[i].x += gt.x * (yv[i].x * rstd * gp.x); xv[i].y += gt.y * (yv[i].y * rstd * gp.y);
;             xv[i].z += gt.z * (yv[i].z * rstd * gp.z); xv[i].w += gt.w * (yv[i].w * rstd * gp.w);
;           }
;         }
;         if (xdst == 3 || (xdst == 1 && row >= N_X)) {
;           float* xout = (xdst == 3) ? P.out + (long)row * 1024 : P.xc + (long)(row - N_X) * 1024;
; #pragma unroll
;           for (int i = 0; i < 4; ++i) *reinterpret_cast<float4*>(xout + (i * 64 + lane) * 4) = xv[i];
	v_add_f32_e32 v138, v138, v139
	v_mov_b32_e32 v139, v138
	s_nop 1
	v_permlane32_swap_b32_e32 v138, v139
	v_add_f32_e32 v138, v138, v139
	v_mul_f32_e32 v138, 0x3a800000, v138
	v_add_f32_e32 v138, 0x358637bd, v138
	v_rsq_f32_e32 v140, v138
	v_lshlrev_b32_e32 v0, 16, v8
	v_and_b32_e32 v1, 0xffff0000, v8
	v_lshlrev_b32_e32 v2, 16, v9
	v_and_b32_e32 v3, 0xffff0000, v9
	v_lshlrev_b32_e32 v4, 16, v10
	v_and_b32_e32 v5, 0xffff0000, v10
	v_lshlrev_b32_e32 v6, 16, v11
	v_and_b32_e32 v7, 0xffff0000, v11
	v_lshlrev_b32_e32 v8, 16, v12
	v_and_b32_e32 v9, 0xffff0000, v12
	v_lshlrev_b32_e32 v10, 16, v13
	v_and_b32_e32 v11, 0xffff0000, v13
	v_lshlrev_b32_e32 v12, 16, v14
	v_and_b32_e32 v13, 0xffff0000, v14
	v_lshlrev_b32_e32 v14, 16, v15
	v_and_b32_e32 v15, 0xffff0000, v15
	s_nop 0
	v_mul_f32_e32 v120, v120, v140
	v_mul_f32_e32 v121, v121, v140
	v_mul_f32_e32 v122, v122, v140
	v_mul_f32_e32 v123, v123, v140
	v_mul_f32_e32 v124, v124, v140
	v_mul_f32_e32 v125, v125, v140
	v_mul_f32_e32 v126, v126, v140
	v_mul_f32_e32 v127, v127, v140
	v_mul_f32_e32 v128, v128, v140
	v_mul_f32_e32 v129, v129, v140
	v_mul_f32_e32 v130, v130, v140
	v_mul_f32_e32 v131, v131, v140
	v_mul_f32_e32 v132, v132, v140
	v_mul_f32_e32 v133, v133, v140
	v_mul_f32_e32 v134, v134, v140
	v_mul_f32_e32 v135, v135, v140
	v_fma_f32 v0, v120, v72, v0
	v_fma_f32 v1, v121, v73, v1
	v_fma_f32 v2, v122, v74, v2
	v_fma_f32 v3, v123, v75, v3
	v_fma_f32 v4, v124, v76, v4
	v_fma_f32 v5, v125, v77, v5
	v_fma_f32 v6, v126, v78, v6
	v_fma_f32 v7, v127, v79, v7
	v_fma_f32 v8, v128, v80, v8
	v_fma_f32 v9, v129, v81, v9
	v_fma_f32 v10, v130, v82, v10
	v_fma_f32 v11, v131, v83, v11
	v_fma_f32 v12, v132, v84, v12
	v_fma_f32 v13, v133, v85, v13
	v_fma_f32 v14, v134, v86, v14
	v_fma_f32 v15, v135, v87, v15
	s_lshl_b32 vcc_lo, s19, 12
	s_add_u32 s100, s16, vcc_lo
	s_addc_u32 s101, s17, 0
	global_store_dwordx4 v136, v[0:3], s[100:101] offset:0
	global_store_dwordx4 v136, v[4:7], s[100:101] offset:1024
	global_store_dwordx4 v136, v[8:11], s[100:101] offset:2048
	global_store_dwordx4 v136, v[12:15], s[100:101] offset:3072
	s_lshl_b32 vcc_lo, s19, 11
	s_add_u32 vcc_lo, vcc_lo, 0xc00000
	s_add_u32 s100, s12, vcc_lo
	s_addc_u32 s101, s13, 0
	global_load_dwordx2 v[8:9], v137, s[100:101] offset:0
	global_load_dwordx2 v[10:11], v137, s[100:101] offset:512
	global_load_dwordx2 v[12:13], v137, s[100:101] offset:1024
	global_load_dwordx2 v[14:15], v137, s[100:101] offset:1536
	s_lshl_b32 vcc_lo, s19, 11
	s_add_u32 vcc_lo, vcc_lo, 0xc00000
	s_add_u32 s100, s14, vcc_lo
	s_addc_u32 s101, s15, 0
	global_load_dwordx2 v[48:49], v137, s[100:101] offset:0
	global_load_dwordx2 v[50:51], v137, s[100:101] offset:512
	global_load_dwordx2 v[52:53], v137, s[100:101] offset:1024
	global_load_dwordx2 v[54:55], v137, s[100:101] offset:1536
	v_lshlrev_b32_e32 v120, 16, v56
	v_and_b32_e32 v121, 0xffff0000, v56
	v_lshlrev_b32_e32 v122, 16, v57
	v_and_b32_e32 v123, 0xffff0000, v57
	v_lshlrev_b32_e32 v124, 16, v58
	v_and_b32_e32 v125, 0xffff0000, v58
	v_lshlrev_b32_e32 v126, 16, v59
	v_and_b32_e32 v127, 0xffff0000, v59
	v_lshlrev_b32_e32 v128, 16, v60
	v_and_b32_e32 v129, 0xffff0000, v60
	v_lshlrev_b32_e32 v130, 16, v61
	v_and_b32_e32 v131, 0xffff0000, v61
	v_lshlrev_b32_e32 v132, 16, v62
	v_and_b32_e32 v133, 0xffff0000, v62
	v_lshlrev_b32_e32 v134, 16, v63
	v_and_b32_e32 v135, 0xffff0000, v63
	v_mul_f32_e32 v138, v120, v120
	v_mul_f32_e32 v149, v121, v121
	v_mul_f32_e32 v150, v122, v122
	v_mul_f32_e32 v154, v123, v123
	v_fma_f32 v138, v124, v124, v138
	v_fma_f32 v149, v125, v125, v149
	v_fma_f32 v150, v126, v126, v150
	v_fma_f32 v154, v127, v127, v154
	v_fma_f32 v138, v128, v128, v138
	v_fma_f32 v149, v129, v129, v149
	v_fma_f32 v150, v130, v130, v150
	v_fma_f32 v154, v131, v131, v154
	v_fma_f32 v138, v132, v132, v138
	v_fma_f32 v149, v133, v133, v149
	v_fma_f32 v150, v134, v134, v150
	v_fma_f32 v154, v135, v135, v154
	v_add_f32_e32 v138, v138, v149
	v_add_f32_e32 v150, v150, v154
	v_add_f32_e32 v138, v138, v150
	s_nop 1
	v_add_f32_dpp v138, v138, v138 quad_perm:[1,0,3,2] row_mask:0xf bank_mask:0xf
	s_nop 1
	v_add_f32_dpp v138, v138, v138 quad_perm:[2,3,0,1] row_mask:0xf bank_mask:0xf
	s_nop 1
	v_add_f32_dpp v138, v138, v138 row_half_mirror row_mask:0xf bank_mask:0xf
	s_nop 1
	v_add_f32_dpp v138, v138, v138 row_mirror row_mask:0xf bank_mask:0xf
	v_mov_b32_e32 v139, v138
	s_nop 1
	v_permlane16_swap_b32_e32 v138, v139
	v_add_f32_e32 v138, v138, v139
	v_mov_b32_e32 v139, v138
	s_nop 1
	v_permlane32_swap_b32_e32 v138, v139
	v_add_f32_e32 v138, v138, v139
	v_mul_f32_e32 v138, 0x3a800000, v138
	v_add_f32_e32 v138, 0x358637bd, v138
	v_rsq_f32_e32 v140, v138
	v_lshlrev_b32_e32 v16, 16, v24
	v_and_b32_e32 v17, 0xffff0000, v24
	v_lshlrev_b32_e32 v18, 16, v25
	v_and_b32_e32 v19, 0xffff0000, v25
	v_lshlrev_b32_e32 v20, 16, v26
	v_and_b32_e32 v21, 0xffff0000, v26
	v_lshlrev_b32_e32 v22, 16, v27
	v_and_b32_e32 v23, 0xffff0000, v27
	v_lshlrev_b32_e32 v24, 16, v28
	v_and_b32_e32 v25, 0xffff0000, v28
	v_lshlrev_b32_e32 v26, 16, v29
	v_and_b32_e32 v27, 0xffff0000, v29
	v_lshlrev_b32_e32 v28, 16, v30
	v_and_b32_e32 v29, 0xffff0000, v30
	v_lshlrev_b32_e32 v30, 16, v31
	v_and_b32_e32 v31, 0xffff0000, v31
	s_nop 0
	v_mul_f32_e32 v120, v120, v140
	v_mul_f32_e32 v121, v121, v140
	v_mul_f32_e32 v122, v122, v140
	v_mul_f32_e32 v123, v123, v140
	v_mul_f32_e32 v124, v124, v140
	v_mul_f32_e32 v125, v125, v140
	v_mul_f32_e32 v126, v126, v140
	v_mul_f32_e32 v127, v127, v140
	v_mul_f32_e32 v128, v128, v140
	v_mul_f32_e32 v129, v129, v140
	v_mul_f32_e32 v130, v130, v140
	v_mul_f32_e32 v131, v131, v140
	v_mul_f32_e32 v132, v132, v140
	v_mul_f32_e32 v133, v133, v140
; __device__ __forceinline__ float bf2f(u16 h) { return __uint_as_float(((unsigned)h) << 16); }
; __device__ __forceinline__ void row_phase(const Params& P, int glayer, int layer, int xsrc, bool hasY, int gate_idx, const float* gpost,
;                           int xdst, bool doH, const float* gpre, int sh_idx, int nrows) {
;     ...
;         if (xsrc != 0 && row < N_X) {
; #pragma unroll
;           for (int i = 0; i < 4; ++i) {
;             const uint4 raw = xr[u][i];
;             xv[i].x = bf2f((u16)(raw.x & 0xffff)); xv[i].y = bf2f((u16)(raw.x >> 16));
;             xv[i].z = bf2f((u16)(raw.y & 0xffff)); xv[i].w = bf2f((u16)(raw.y >> 16));
;           }
;         } else {
; #pragma unroll
;           for (int i = 0; i < 4; ++i) {
;             xv[i].x = __uint_as_float(xr[u][i].x); xv[i].y = __uint_as_float(xr[u][i].y);
;             xv[i].z = __uint_as_float(xr[u][i].z); xv[i].w = __uint_as_float(xr[u][i].w);
;           }
;         }
;         if (hasY) {
;           float4 yv[4];
;           float ss = 0.f;
; #pragma unroll
;           for (int i = 0; i < 4; ++i) {
;             const uint2 raw = yy[u][i];
;             yv[i].x = bf2f((u16)(raw.x & 0xffff)); yv[i].y = bf2f((u16)(raw.x >> 16));
;             yv[i].z = bf2f((u16)(raw.y & 0xffff)); yv[i].w = bf2f((u16)(raw.y >> 16));
;             ss += yv[i].x * yv[i].x + yv[i].y * yv[i].y + yv[i].z * yv[i].z + yv[i].w * yv[i].w;
;           }
;           ss = wave_sum(ss);
;           const float rstd = __builtin_amdgcn_rsqf(ss * (1.f / 1024.f) + EPSF);
; #pragma unroll
;           for (int i = 0; i < 4; ++i) {
;             const int col = (i * 64 + lane) * 4;
;             const float4 gt = *reinterpret_cast<const float4*>(modg + gate_idx * 1024 + col);
;             const float4 gp = *reinterpret_cast<const float4*>(gpost + col);
;             xv[i].x += gt.x * (yv[i].x * rstd * gp.x); xv[i].y += gt.y * (yv[i].y * rstd * gp.y);
;             xv[i].z += gt.z * (yv[i].z * rstd * gp.z); xv[i].w += gt.w * (yv[i].w * rstd * gp.w);
;           }
;         }
;         if (xdst == 3 || (xdst == 1 && row >= N_X)) {
;           float* xout = (xdst == 3) ? P.out + (long)row * 1024 : P.xc + (long)(row - N_X) * 1024;
; #pragma unroll
;           for (int i = 0; i < 4; ++i) *reinterpret_cast<float4*>(xout + (i * 64 + lane) * 4) = xv[i];
	v_mul_f32_e32 v134, v134, v140
	v_mul_f32_e32 v135, v135, v140
	v_fma_f32 v16, v120, v72, v16
	v_fma_f32 v17, v121, v73, v17
	v_fma_f32 v18, v122, v74, v18
	v_fma_f32 v19, v123, v75, v19
	v_fma_f32 v20, v124, v76, v20
	v_fma_f32 v21, v125, v77, v21
	v_fma_f32 v22, v126, v78, v22
	v_fma_f32 v23, v127, v79, v23
	v_fma_f32 v24, v128, v80, v24
	v_fma_f32 v25, v129, v81, v25
	v_fma_f32 v26, v130, v82, v26
	v_fma_f32 v27, v131, v83, v27
	v_fma_f32 v28, v132, v84, v28
	v_fma_f32 v29, v133, v85, v29
	v_fma_f32 v30, v134, v86, v30
	v_fma_f32 v31, v135, v87, v31
	s_lshl_b32 vcc_lo, s19, 12
	s_add_u32 vcc_lo, vcc_lo, 0x800000
	s_add_u32 s100, s16, vcc_lo
	s_addc_u32 s101, s17, 0
	global_store_dwordx4 v136, v[16:19], s[100:101] offset:0
	global_store_dwordx4 v136, v[20:23], s[100:101] offset:1024
	global_store_dwordx4 v136, v[24:27], s[100:101] offset:2048
	global_store_dwordx4 v136, v[28:31], s[100:101] offset:3072
	s_lshl_b32 vcc_lo, s19, 11
	s_add_u32 vcc_lo, vcc_lo, 0x1000000
	s_add_u32 s100, s12, vcc_lo
	s_addc_u32 s101, s13, 0
	global_load_dwordx2 v[24:25], v137, s[100:101] offset:0
	global_load_dwordx2 v[26:27], v137, s[100:101] offset:512
	global_load_dwordx2 v[28:29], v137, s[100:101] offset:1024
	global_load_dwordx2 v[30:31], v137, s[100:101] offset:1536
	s_lshl_b32 vcc_lo, s19, 11
	s_add_u32 vcc_lo, vcc_lo, 0x1000000
	s_add_u32 s100, s14, vcc_lo
	s_addc_u32 s101, s15, 0
	global_load_dwordx2 v[56:57], v137, s[100:101] offset:0
	global_load_dwordx2 v[58:59], v137, s[100:101] offset:512
	global_load_dwordx2 v[60:61], v137, s[100:101] offset:1024
	global_load_dwordx2 v[62:63], v137, s[100:101] offset:1536
	s_waitcnt vmcnt(24)
	v_lshlrev_b32_e32 v120, 16, v64
	v_and_b32_e32 v121, 0xffff0000, v64
	v_lshlrev_b32_e32 v122, 16, v65
	v_and_b32_e32 v123, 0xffff0000, v65
	v_lshlrev_b32_e32 v124, 16, v66
	v_and_b32_e32 v125, 0xffff0000, v66
	v_lshlrev_b32_e32 v126, 16, v67
	v_and_b32_e32 v127, 0xffff0000, v67
	v_lshlrev_b32_e32 v128, 16, v68
	v_and_b32_e32 v129, 0xffff0000, v68
	v_lshlrev_b32_e32 v130, 16, v69
	v_and_b32_e32 v131, 0xffff0000, v69
	v_lshlrev_b32_e32 v132, 16, v70
	v_and_b32_e32 v133, 0xffff0000, v70
	v_lshlrev_b32_e32 v134, 16, v71
	v_and_b32_e32 v135, 0xffff0000, v71
	v_mul_f32_e32 v138, v120, v120
	v_mul_f32_e32 v149, v121, v121
	v_mul_f32_e32 v150, v122, v122
	v_mul_f32_e32 v154, v123, v123
	v_fma_f32 v138, v124, v124, v138
	v_fma_f32 v149, v125, v125, v149
	v_fma_f32 v150, v126, v126, v150
	v_fma_f32 v154, v127, v127, v154
	v_fma_f32 v138, v128, v128, v138
	v_fma_f32 v149, v129, v129, v149
	v_fma_f32 v150, v130, v130, v150
	v_fma_f32 v154, v131, v131, v154
	v_fma_f32 v138, v132, v132, v138
	v_fma_f32 v149, v133, v133, v149
	v_fma_f32 v150, v134, v134, v150
	v_fma_f32 v154, v135, v135, v154
	v_add_f32_e32 v138, v138, v149
	v_add_f32_e32 v150, v150, v154
	v_add_f32_e32 v138, v138, v150
	s_nop 1
	v_add_f32_dpp v138, v138, v138 quad_perm:[1,0,3,2] row_mask:0xf bank_mask:0xf
	s_nop 1
	v_add_f32_dpp v138, v138, v138 quad_perm:[2,3,0,1] row_mask:0xf bank_mask:0xf
	s_nop 1
	v_add_f32_dpp v138, v138, v138 row_half_mirror row_mask:0xf bank_mask:0xf
	s_nop 1
	v_add_f32_dpp v138, v138, v138 row_mirror row_mask:0xf bank_mask:0xf
	v_mov_b32_e32 v139, v138
	s_nop 1
	v_permlane16_swap_b32_e32 v138, v139
	v_add_f32_e32 v138, v138, v139
	v_mov_b32_e32 v139, v138
	s_nop 1
	v_permlane32_swap_b32_e32 v138, v139
	v_add_f32_e32 v138, v138, v139
	v_mul_f32_e32 v138, 0x3a800000, v138
	v_add_f32_e32 v138, 0x358637bd, v138
	v_rsq_f32_e32 v140, v138
	v_lshlrev_b32_e32 v32, 16, v40
	v_and_b32_e32 v33, 0xffff0000, v40
	v_lshlrev_b32_e32 v34, 16, v41
	v_and_b32_e32 v35, 0xffff0000, v41
	v_lshlrev_b32_e32 v36, 16, v42
	v_and_b32_e32 v37, 0xffff0000, v42
	v_lshlrev_b32_e32 v38, 16, v43
	v_and_b32_e32 v39, 0xffff0000, v43
	v_lshlrev_b32_e32 v40, 16, v44
	v_and_b32_e32 v41, 0xffff0000, v44
	v_lshlrev_b32_e32 v42, 16, v45
	v_and_b32_e32 v43, 0xffff0000, v45
	v_lshlrev_b32_e32 v44, 16, v46
	v_and_b32_e32 v45, 0xffff0000, v46
	v_lshlrev_b32_e32 v46, 16, v47
	v_and_b32_e32 v47, 0xffff0000, v47
	s_nop 0
	v_mul_f32_e32 v120, v120, v140
	v_mul_f32_e32 v121, v121, v140
	v_mul_f32_e32 v122, v122, v140
	v_mul_f32_e32 v123, v123, v140
	v_mul_f32_e32 v124, v124, v140
	v_mul_f32_e32 v125, v125, v140
	v_mul_f32_e32 v126, v126, v140
	v_mul_f32_e32 v127, v127, v140
	v_mul_f32_e32 v128, v128, v140
	v_mul_f32_e32 v129, v129, v140
	v_mul_f32_e32 v130, v130, v140
	v_mul_f32_e32 v131, v131, v140
	v_mul_f32_e32 v132, v132, v140
	v_mul_f32_e32 v133, v133, v140
	v_mul_f32_e32 v134, v134, v140
	v_mul_f32_e32 v135, v135, v140
	v_fma_f32 v32, v120, v72, v32
	v_fma_f32 v33, v121, v73, v33
	v_fma_f32 v34, v122, v74, v34
	v_fma_f32 v35, v123, v75, v35
	v_fma_f32 v36, v124, v76, v36
	v_fma_f32 v37, v125, v77, v37
	v_fma_f32 v38, v126, v78, v38
	v_fma_f32 v39, v127, v79, v39
	v_fma_f32 v40, v128, v80, v40
	v_fma_f32 v41, v129, v81, v41
	v_fma_f32 v42, v130, v82, v42
	v_fma_f32 v43, v131, v83, v43
	v_fma_f32 v44, v132, v84, v44
	v_fma_f32 v45, v133, v85, v45
	v_fma_f32 v46, v134, v86, v46
	v_fma_f32 v47, v135, v87, v47
	s_lshl_b32 vcc_lo, s19, 12
	s_add_u32 vcc_lo, vcc_lo, 0x1000000
	s_add_u32 s100, s16, vcc_lo
	s_addc_u32 s101, s17, 0
	global_store_dwordx4 v136, v[32:35], s[100:101] offset:0
	global_store_dwordx4 v136, v[36:39], s[100:101] offset:1024
	global_store_dwordx4 v136, v[40:43], s[100:101] offset:2048
	global_store_dwordx4 v136, v[44:47], s[100:101] offset:3072
	s_lshl_b32 vcc_lo, s19, 11
	s_add_u32 vcc_lo, vcc_lo, 0x1400000
	s_add_u32 s100, s12, vcc_lo
	s_addc_u32 s101, s13, 0
	global_load_dwordx2 v[40:41], v137, s[100:101] offset:0
	global_load_dwordx2 v[42:43], v137, s[100:101] offset:512
	global_load_dwordx2 v[44:45], v137, s[100:101] offset:1024
	global_load_dwordx2 v[46:47], v137, s[100:101] offset:1536
	s_lshl_b32 vcc_lo, s19, 11
	s_add_u32 vcc_lo, vcc_lo, 0x1400000
	s_add_u32 s100, s14, vcc_lo
	s_addc_u32 s101, s15, 0
	global_load_dwordx2 v[64:65], v137, s[100:101] offset:0
	global_load_dwordx2 v[66:67], v137, s[100:101] offset:512
	global_load_dwordx2 v[68:69], v137, s[100:101] offset:1024
	global_load_dwordx2 v[70:71], v137, s[100:101] offset:1536
	s_waitcnt vmcnt(24)
; __device__ __forceinline__ float bf2f(u16 h) { return __uint_as_float(((unsigned)h) << 16); }
; __device__ __forceinline__ void row_phase(const Params& P, int glayer, int layer, int xsrc, bool hasY, int gate_idx, const float* gpost,
;                           int xdst, bool doH, const float* gpre, int sh_idx, int nrows) {
;     ...
;         if (xsrc != 0 && row < N_X) {
; #pragma unroll
;           for (int i = 0; i < 4; ++i) {
;             const uint4 raw = xr[u][i];
;             xv[i].x = bf2f((u16)(raw.x & 0xffff)); xv[i].y = bf2f((u16)(raw.x >> 16));
;             xv[i].z = bf2f((u16)(raw.y & 0xffff)); xv[i].w = bf2f((u16)(raw.y >> 16));
;           }
;         } else {
; #pragma unroll
;           for (int i = 0; i < 4; ++i) {
;             xv[i].x = __uint_as_float(xr[u][i].x); xv[i].y = __uint_as_float(xr[u][i].y);
;             xv[i].z = __uint_as_float(xr[u][i].z); xv[i].w = __uint_as_float(xr[u][i].w);
;           }
;         }
;         if (hasY) {
;           float4 yv[4];
;           float ss = 0.f;
; #pragma unroll
;           for (int i = 0; i < 4; ++i) {
;             const uint2 raw = yy[u][i];
;             yv[i].x = bf2f((u16)(raw.x & 0xffff)); yv[i].y = bf2f((u16)(raw.x >> 16));
;             yv[i].z = bf2f((u16)(raw.y & 0xffff)); yv[i].w = bf2f((u16)(raw.y >> 16));
;             ss += yv[i].x * yv[i].x + yv[i].y * yv[i].y + yv[i].z * yv[i].z + yv[i].w * yv[i].w;
;           }
;           ss = wave_sum(ss);
;           const float rstd = __builtin_amdgcn_rsqf(ss * (1.f / 1024.f) + EPSF);
; #pragma unroll
;           for (int i = 0; i < 4; ++i) {
;             const int col = (i * 64 + lane) * 4;
;             const float4 gt = *reinterpret_cast<const float4*>(modg + gate_idx * 1024 + col);
;             const float4 gp = *reinterpret_cast<const float4*>(gpost + col);
;             xv[i].x += gt.x * (yv[i].x * rstd * gp.x); xv[i].y += gt.y * (yv[i].y * rstd * gp.y);
;             xv[i].z += gt.z * (yv[i].z * rstd * gp.z); xv[i].w += gt.w * (yv[i].w * rstd * gp.w);
;           }
;         }
;         if (xdst == 3 || (xdst == 1 && row >= N_X)) {
;           float* xout = (xdst == 3) ? P.out + (long)row * 1024 : P.xc + (long)(row - N_X) * 1024;
; #pragma unroll
;           for (int i = 0; i < 4; ++i) *reinterpret_cast<float4*>(xout + (i * 64 + lane) * 4) = xv[i];
	v_lshlrev_b32_e32 v120, 16, v48
	v_and_b32_e32 v121, 0xffff0000, v48
	v_lshlrev_b32_e32 v122, 16, v49
	v_and_b32_e32 v123, 0xffff0000, v49
	v_lshlrev_b32_e32 v124, 16, v50
	v_and_b32_e32 v125, 0xffff0000, v50
	v_lshlrev_b32_e32 v126, 16, v51
	v_and_b32_e32 v127, 0xffff0000, v51
	v_lshlrev_b32_e32 v128, 16, v52
	v_and_b32_e32 v129, 0xffff0000, v52
	v_lshlrev_b32_e32 v130, 16, v53
	v_and_b32_e32 v131, 0xffff0000, v53
	v_lshlrev_b32_e32 v132, 16, v54
	v_and_b32_e32 v133, 0xffff0000, v54
	v_lshlrev_b32_e32 v134, 16, v55
	v_and_b32_e32 v135, 0xffff0000, v55
	v_mul_f32_e32 v138, v120, v120
	v_mul_f32_e32 v149, v121, v121
	v_mul_f32_e32 v150, v122, v122
	v_mul_f32_e32 v154, v123, v123
	v_fma_f32 v138, v124, v124, v138
	v_fma_f32 v149, v125, v125, v149
	v_fma_f32 v150, v126, v126, v150
	v_fma_f32 v154, v127, v127, v154
	v_fma_f32 v138, v128, v128, v138
	v_fma_f32 v149, v129, v129, v149
	v_fma_f32 v150, v130, v130, v150
	v_fma_f32 v154, v131, v131, v154
	v_fma_f32 v138, v132, v132, v138
	v_fma_f32 v149, v133, v133, v149
	v_fma_f32 v150, v134, v134, v150
	v_fma_f32 v154, v135, v135, v154
	v_add_f32_e32 v138, v138, v149
	v_add_f32_e32 v150, v150, v154
	v_add_f32_e32 v138, v138, v150
	s_nop 1
	v_add_f32_dpp v138, v138, v138 quad_perm:[1,0,3,2] row_mask:0xf bank_mask:0xf
	s_nop 1
	v_add_f32_dpp v138, v138, v138 quad_perm:[2,3,0,1] row_mask:0xf bank_mask:0xf
	s_nop 1
	v_add_f32_dpp v138, v138, v138 row_half_mirror row_mask:0xf bank_mask:0xf
	s_nop 1
	v_add_f32_dpp v138, v138, v138 row_mirror row_mask:0xf bank_mask:0xf
	v_mov_b32_e32 v139, v138
	s_nop 1
	v_permlane16_swap_b32_e32 v138, v139
	v_add_f32_e32 v138, v138, v139
	v_mov_b32_e32 v139, v138
	s_nop 1
	v_permlane32_swap_b32_e32 v138, v139
	v_add_f32_e32 v138, v138, v139
	v_mul_f32_e32 v138, 0x3a800000, v138
	v_add_f32_e32 v138, 0x358637bd, v138
	v_rsq_f32_e32 v140, v138
	v_lshlrev_b32_e32 v0, 16, v8
	v_and_b32_e32 v1, 0xffff0000, v8
	v_lshlrev_b32_e32 v2, 16, v9
	v_and_b32_e32 v3, 0xffff0000, v9
	v_lshlrev_b32_e32 v4, 16, v10
	v_and_b32_e32 v5, 0xffff0000, v10
	v_lshlrev_b32_e32 v6, 16, v11
	v_and_b32_e32 v7, 0xffff0000, v11
	v_lshlrev_b32_e32 v8, 16, v12
	v_and_b32_e32 v9, 0xffff0000, v12
	v_lshlrev_b32_e32 v10, 16, v13
	v_and_b32_e32 v11, 0xffff0000, v13
	v_lshlrev_b32_e32 v12, 16, v14
	v_and_b32_e32 v13, 0xffff0000, v14
	v_lshlrev_b32_e32 v14, 16, v15
	v_and_b32_e32 v15, 0xffff0000, v15
	s_nop 0
	v_mul_f32_e32 v120, v120, v140
	v_mul_f32_e32 v121, v121, v140
	v_mul_f32_e32 v122, v122, v140
	v_mul_f32_e32 v123, v123, v140
	v_mul_f32_e32 v124, v124, v140
	v_mul_f32_e32 v125, v125, v140
	v_mul_f32_e32 v126, v126, v140
	v_mul_f32_e32 v127, v127, v140
	v_mul_f32_e32 v128, v128, v140
	v_mul_f32_e32 v129, v129, v140
	v_mul_f32_e32 v130, v130, v140
	v_mul_f32_e32 v131, v131, v140
	v_mul_f32_e32 v132, v132, v140
	v_mul_f32_e32 v133, v133, v140
	v_mul_f32_e32 v134, v134, v140
	v_mul_f32_e32 v135, v135, v140
	v_fma_f32 v0, v120, v72, v0
	v_fma_f32 v1, v121, v73, v1
	v_fma_f32 v2, v122, v74, v2
	v_fma_f32 v3, v123, v75, v3
	v_fma_f32 v4, v124, v76, v4
	v_fma_f32 v5, v125, v77, v5
	v_fma_f32 v6, v126, v78, v6
	v_fma_f32 v7, v127, v79, v7
	v_fma_f32 v8, v128, v80, v8
	v_fma_f32 v9, v129, v81, v9
	v_fma_f32 v10, v130, v82, v10
	v_fma_f32 v11, v131, v83, v11
	v_fma_f32 v12, v132, v84, v12
	v_fma_f32 v13, v133, v85, v13
	v_fma_f32 v14, v134, v86, v14
	v_fma_f32 v15, v135, v87, v15
	s_lshl_b32 vcc_lo, s19, 12
	s_add_u32 vcc_lo, vcc_lo, 0x1800000
	s_add_u32 s100, s16, vcc_lo
	s_addc_u32 s101, s17, 0
	global_store_dwordx4 v136, v[0:3], s[100:101] offset:0
	global_store_dwordx4 v136, v[4:7], s[100:101] offset:1024
	global_store_dwordx4 v136, v[8:11], s[100:101] offset:2048
	global_store_dwordx4 v136, v[12:15], s[100:101] offset:3072
	s_add_u32 s100, s20, 0x29000
	s_addc_u32 s101, s21, 0
	global_load_dwordx4 v[72:75], v136, s[100:101] offset:0
	global_load_dwordx4 v[76:79], v136, s[100:101] offset:1024
	global_load_dwordx4 v[80:83], v136, s[100:101] offset:2048
	global_load_dwordx4 v[84:87], v136, s[100:101] offset:3072
	s_load_dwordx2 s[98:99], s[4:5], 0x48
	s_waitcnt lgkmcnt(0)
	s_add_u32 s98, s98, 0x1000
	s_addc_u32 s99, s99, 0
	global_load_dwordx4 v[120:123], v136, s[98:99] offset:0
	global_load_dwordx4 v[124:127], v136, s[98:99] offset:1024
	global_load_dwordx4 v[128:131], v136, s[98:99] offset:2048
	global_load_dwordx4 v[132:135], v136, s[98:99] offset:3072
	s_waitcnt vmcnt(0)
; __device__ __forceinline__ float bf2f(u16 h) { return __uint_as_float(((unsigned)h) << 16); }
; __device__ __forceinline__ void row_phase(const Params& P, int glayer, int layer, int xsrc, bool hasY, int gate_idx, const float* gpost,
;                           int xdst, bool doH, const float* gpre, int sh_idx, int nrows) {
;     ...
;         if (xsrc != 0 && row < N_X) {
; #pragma unroll
;           for (int i = 0; i < 4; ++i) {
;             const uint4 raw = xr[u][i];
;             xv[i].x = bf2f((u16)(raw.x & 0xffff)); xv[i].y = bf2f((u16)(raw.x >> 16));
;             xv[i].z = bf2f((u16)(raw.y & 0xffff)); xv[i].w = bf2f((u16)(raw.y >> 16));
;           }
;         } else {
; #pragma unroll
;           for (int i = 0; i < 4; ++i) {
;             xv[i].x = __uint_as_float(xr[u][i].x); xv[i].y = __uint_as_float(xr[u][i].y);
;             xv[i].z = __uint_as_float(xr[u][i].z); xv[i].w = __uint_as_float(xr[u][i].w);
;           }
;         }
;         if (hasY) {
;           float4 yv[4];
;           float ss = 0.f;
; #pragma unroll
;           for (int i = 0; i < 4; ++i) {
;             const uint2 raw = yy[u][i];
;             yv[i].x = bf2f((u16)(raw.x & 0xffff)); yv[i].y = bf2f((u16)(raw.x >> 16));
;             yv[i].z = bf2f((u16)(raw.y & 0xffff)); yv[i].w = bf2f((u16)(raw.y >> 16));
;             ss += yv[i].x * yv[i].x + yv[i].y * yv[i].y + yv[i].z * yv[i].z + yv[i].w * yv[i].w;
;           }
;           ss = wave_sum(ss);
;           const float rstd = __builtin_amdgcn_rsqf(ss * (1.f / 1024.f) + EPSF);
; #pragma unroll
;           for (int i = 0; i < 4; ++i) {
;             const int col = (i * 64 + lane) * 4;
;             const float4 gt = *reinterpret_cast<const float4*>(modg + gate_idx * 1024 + col);
;             const float4 gp = *reinterpret_cast<const float4*>(gpost + col);
;             xv[i].x += gt.x * (yv[i].x * rstd * gp.x); xv[i].y += gt.y * (yv[i].y * rstd * gp.y);
;             xv[i].z += gt.z * (yv[i].z * rstd * gp.z); xv[i].w += gt.w * (yv[i].w * rstd * gp.w);
;           }
;         }
;         if (xdst == 3 || (xdst == 1 && row >= N_X)) {
;           float* xout = (xdst == 3) ? P.out + (long)row * 1024 : P.xc + (long)(row - N_X) * 1024;
; #pragma unroll
;           for (int i = 0; i < 4; ++i) *reinterpret_cast<float4*>(xout + (i * 64 + lane) * 4) = xv[i];
	v_mul_f32_e32 v72, v72, v120
	v_mul_f32_e32 v73, v73, v121
	v_mul_f32_e32 v74, v74, v122
	v_mul_f32_e32 v75, v75, v123
	v_mul_f32_e32 v76, v76, v124
	v_mul_f32_e32 v77, v77, v125
	v_mul_f32_e32 v78, v78, v126
	v_mul_f32_e32 v79, v79, v127
	v_mul_f32_e32 v80, v80, v128
	v_mul_f32_e32 v81, v81, v129
	v_mul_f32_e32 v82, v82, v130
	v_mul_f32_e32 v83, v83, v131
	v_mul_f32_e32 v84, v84, v132
	v_mul_f32_e32 v85, v85, v133
	v_mul_f32_e32 v86, v86, v134
	v_mul_f32_e32 v87, v87, v135
	s_lshl_b32 vcc_lo, s19, 11
	s_add_u32 vcc_lo, vcc_lo, 0x1800000
	s_add_u32 s100, s12, vcc_lo
	s_addc_u32 s101, s13, 0
	global_load_dwordx2 v[8:9], v137, s[100:101] offset:0
	global_load_dwordx2 v[10:11], v137, s[100:101] offset:512
	global_load_dwordx2 v[12:13], v137, s[100:101] offset:1024
	global_load_dwordx2 v[14:15], v137, s[100:101] offset:1536
	s_lshl_b32 vcc_lo, s19, 11
	s_add_u32 vcc_lo, vcc_lo, 0x1800000
	s_add_u32 s100, s14, vcc_lo
	s_addc_u32 s101, s15, 0
	global_load_dwordx2 v[48:49], v137, s[100:101] offset:0
	global_load_dwordx2 v[50:51], v137, s[100:101] offset:512
	global_load_dwordx2 v[52:53], v137, s[100:101] offset:1024
	global_load_dwordx2 v[54:55], v137, s[100:101] offset:1536
	v_lshlrev_b32_e32 v120, 16, v56
	v_and_b32_e32 v121, 0xffff0000, v56
	v_lshlrev_b32_e32 v122, 16, v57
	v_and_b32_e32 v123, 0xffff0000, v57
	v_lshlrev_b32_e32 v124, 16, v58
	v_and_b32_e32 v125, 0xffff0000, v58
	v_lshlrev_b32_e32 v126, 16, v59
	v_and_b32_e32 v127, 0xffff0000, v59
	v_lshlrev_b32_e32 v128, 16, v60
	v_and_b32_e32 v129, 0xffff0000, v60
	v_lshlrev_b32_e32 v130, 16, v61
	v_and_b32_e32 v131, 0xffff0000, v61
	v_lshlrev_b32_e32 v132, 16, v62
	v_and_b32_e32 v133, 0xffff0000, v62
	v_lshlrev_b32_e32 v134, 16, v63
	v_and_b32_e32 v135, 0xffff0000, v63
	v_mul_f32_e32 v138, v120, v120
	v_mul_f32_e32 v149, v121, v121
	v_mul_f32_e32 v150, v122, v122
	v_mul_f32_e32 v154, v123, v123
	v_fma_f32 v138, v124, v124, v138
	v_fma_f32 v149, v125, v125, v149
	v_fma_f32 v150, v126, v126, v150
	v_fma_f32 v154, v127, v127, v154
	v_fma_f32 v138, v128, v128, v138
	v_fma_f32 v149, v129, v129, v149
	v_fma_f32 v150, v130, v130, v150
	v_fma_f32 v154, v131, v131, v154
	v_fma_f32 v138, v132, v132, v138
	v_fma_f32 v149, v133, v133, v149
	v_fma_f32 v150, v134, v134, v150
	v_fma_f32 v154, v135, v135, v154
	v_add_f32_e32 v138, v138, v149
	v_add_f32_e32 v150, v150, v154
	v_add_f32_e32 v138, v138, v150
	s_nop 1
	v_add_f32_dpp v138, v138, v138 quad_perm:[1,0,3,2] row_mask:0xf bank_mask:0xf
	s_nop 1
	v_add_f32_dpp v138, v138, v138 quad_perm:[2,3,0,1] row_mask:0xf bank_mask:0xf
	s_nop 1
	v_add_f32_dpp v138, v138, v138 row_half_mirror row_mask:0xf bank_mask:0xf
	s_nop 1
	v_add_f32_dpp v138, v138, v138 row_mirror row_mask:0xf bank_mask:0xf
	v_mov_b32_e32 v139, v138
	s_nop 1
	v_permlane16_swap_b32_e32 v138, v139
	v_add_f32_e32 v138, v138, v139
	v_mov_b32_e32 v139, v138
	s_nop 1
	v_permlane32_swap_b32_e32 v138, v139
	v_add_f32_e32 v138, v138, v139
	v_mul_f32_e32 v138, 0x3a800000, v138
	v_add_f32_e32 v138, 0x358637bd, v138
	v_rsq_f32_e32 v140, v138
	v_lshlrev_b32_e32 v16, 16, v24
	v_and_b32_e32 v17, 0xffff0000, v24
	v_lshlrev_b32_e32 v18, 16, v25
	v_and_b32_e32 v19, 0xffff0000, v25
	v_lshlrev_b32_e32 v20, 16, v26
	v_and_b32_e32 v21, 0xffff0000, v26
	v_lshlrev_b32_e32 v22, 16, v27
	v_and_b32_e32 v23, 0xffff0000, v27
	v_lshlrev_b32_e32 v24, 16, v28
	v_and_b32_e32 v25, 0xffff0000, v28
	v_lshlrev_b32_e32 v26, 16, v29
	v_and_b32_e32 v27, 0xffff0000, v29
	v_lshlrev_b32_e32 v28, 16, v30
	v_and_b32_e32 v29, 0xffff0000, v30
	v_lshlrev_b32_e32 v30, 16, v31
	v_and_b32_e32 v31, 0xffff0000, v31
	s_nop 0
	v_mul_f32_e32 v120, v120, v140
	v_mul_f32_e32 v121, v121, v140
	v_mul_f32_e32 v122, v122, v140
	v_mul_f32_e32 v123, v123, v140
	v_mul_f32_e32 v124, v124, v140
	v_mul_f32_e32 v125, v125, v140
	v_mul_f32_e32 v126, v126, v140
	v_mul_f32_e32 v127, v127, v140
	v_mul_f32_e32 v128, v128, v140
	v_mul_f32_e32 v129, v129, v140
	v_mul_f32_e32 v130, v130, v140
	v_mul_f32_e32 v131, v131, v140
	v_mul_f32_e32 v132, v132, v140
	v_mul_f32_e32 v133, v133, v140
	v_mul_f32_e32 v134, v134, v140
	v_mul_f32_e32 v135, v135, v140
	v_fma_f32 v16, v120, v72, v16
	v_fma_f32 v17, v121, v73, v17
	v_fma_f32 v18, v122, v74, v18
	v_fma_f32 v19, v123, v75, v19
	v_fma_f32 v20, v124, v76, v20
	v_fma_f32 v21, v125, v77, v21
	v_fma_f32 v22, v126, v78, v22
	v_fma_f32 v23, v127, v79, v23
	v_fma_f32 v24, v128, v80, v24
	v_fma_f32 v25, v129, v81, v25
	v_fma_f32 v26, v130, v82, v26
	v_fma_f32 v27, v131, v83, v27
	v_fma_f32 v28, v132, v84, v28
	v_fma_f32 v29, v133, v85, v29
	v_fma_f32 v30, v134, v86, v30
	v_fma_f32 v31, v135, v87, v31
	s_lshl_b32 vcc_lo, s19, 12
	s_add_u32 vcc_lo, vcc_lo, 0x2000000
	s_add_u32 s100, s16, vcc_lo
	s_addc_u32 s101, s17, 0
	global_store_dwordx4 v136, v[16:19], s[100:101] offset:0
	global_store_dwordx4 v136, v[20:23], s[100:101] offset:1024
	global_store_dwordx4 v136, v[24:27], s[100:101] offset:2048
	global_store_dwordx4 v136, v[28:31], s[100:101] offset:3072
	s_lshl_b32 vcc_lo, s19, 11
	s_add_u32 vcc_lo, vcc_lo, 0x1c00000
	s_add_u32 s100, s12, vcc_lo
	s_addc_u32 s101, s13, 0
	global_load_dwordx2 v[24:25], v137, s[100:101] offset:0
	global_load_dwordx2 v[26:27], v137, s[100:101] offset:512
	global_load_dwordx2 v[28:29], v137, s[100:101] offset:1024
	global_load_dwordx2 v[30:31], v137, s[100:101] offset:1536
	s_lshl_b32 vcc_lo, s19, 11
	s_add_u32 vcc_lo, vcc_lo, 0x1c00000
	s_add_u32 s100, s14, vcc_lo
	s_addc_u32 s101, s15, 0
	global_load_dwordx2 v[56:57], v137, s[100:101] offset:0
	global_load_dwordx2 v[58:59], v137, s[100:101] offset:512
	global_load_dwordx2 v[60:61], v137, s[100:101] offset:1024
	global_load_dwordx2 v[62:63], v137, s[100:101] offset:1536
; __device__ __forceinline__ float bf2f(u16 h) { return __uint_as_float(((unsigned)h) << 16); }
; __device__ __forceinline__ void row_phase(const Params& P, int glayer, int layer, int xsrc, bool hasY, int gate_idx, const float* gpost,
;                           int xdst, bool doH, const float* gpre, int sh_idx, int nrows) {
;     ...
;         if (xsrc != 0 && row < N_X) {
; #pragma unroll
;           for (int i = 0; i < 4; ++i) {
;             const uint4 raw = xr[u][i];
;             xv[i].x = bf2f((u16)(raw.x & 0xffff)); xv[i].y = bf2f((u16)(raw.x >> 16));
;             xv[i].z = bf2f((u16)(raw.y & 0xffff)); xv[i].w = bf2f((u16)(raw.y >> 16));
;           }
;         } else {
; #pragma unroll
;           for (int i = 0; i < 4; ++i) {
;             xv[i].x = __uint_as_float(xr[u][i].x); xv[i].y = __uint_as_float(xr[u][i].y);
;             xv[i].z = __uint_as_float(xr[u][i].z); xv[i].w = __uint_as_float(xr[u][i].w);
;           }
;         }
;         if (hasY) {
;           float4 yv[4];
;           float ss = 0.f;
; #pragma unroll
;           for (int i = 0; i < 4; ++i) {
;             const uint2 raw = yy[u][i];
;             yv[i].x = bf2f((u16)(raw.x & 0xffff)); yv[i].y = bf2f((u16)(raw.x >> 16));
;             yv[i].z = bf2f((u16)(raw.y & 0xffff)); yv[i].w = bf2f((u16)(raw.y >> 16));
;             ss += yv[i].x * yv[i].x + yv[i].y * yv[i].y + yv[i].z * yv[i].z + yv[i].w * yv[i].w;
;           }
;           ss = wave_sum(ss);
;           const float rstd = __builtin_amdgcn_rsqf(ss * (1.f / 1024.f) + EPSF);
; #pragma unroll
;           for (int i = 0; i < 4; ++i) {
;             const int col = (i * 64 + lane) * 4;
;             const float4 gt = *reinterpret_cast<const float4*>(modg + gate_idx * 1024 + col);
;             const float4 gp = *reinterpret_cast<const float4*>(gpost + col);
;             xv[i].x += gt.x * (yv[i].x * rstd * gp.x); xv[i].y += gt.y * (yv[i].y * rstd * gp.y);
;             xv[i].z += gt.z * (yv[i].z * rstd * gp.z); xv[i].w += gt.w * (yv[i].w * rstd * gp.w);
;           }
;         }
;         if (xdst == 3 || (xdst == 1 && row >= N_X)) {
;           float* xout = (xdst == 3) ? P.out + (long)row * 1024 : P.xc + (long)(row - N_X) * 1024;
; #pragma unroll
;           for (int i = 0; i < 4; ++i) *reinterpret_cast<float4*>(xout + (i * 64 + lane) * 4) = xv[i];
	v_lshlrev_b32_e32 v120, 16, v64
	v_and_b32_e32 v121, 0xffff0000, v64
	v_lshlrev_b32_e32 v122, 16, v65
	v_and_b32_e32 v123, 0xffff0000, v65
	v_lshlrev_b32_e32 v124, 16, v66
	v_and_b32_e32 v125, 0xffff0000, v66
	v_lshlrev_b32_e32 v126, 16, v67
	v_and_b32_e32 v127, 0xffff0000, v67
	v_lshlrev_b32_e32 v128, 16, v68
	v_and_b32_e32 v129, 0xffff0000, v68
	v_lshlrev_b32_e32 v130, 16, v69
	v_and_b32_e32 v131, 0xffff0000, v69
	v_lshlrev_b32_e32 v132, 16, v70
	v_and_b32_e32 v133, 0xffff0000, v70
	v_lshlrev_b32_e32 v134, 16, v71
	v_and_b32_e32 v135, 0xffff0000, v71
	v_mul_f32_e32 v138, v120, v120
	v_mul_f32_e32 v149, v121, v121
	v_mul_f32_e32 v150, v122, v122
	v_mul_f32_e32 v154, v123, v123
	v_fma_f32 v138, v124, v124, v138
	v_fma_f32 v149, v125, v125, v149
	v_fma_f32 v150, v126, v126, v150
	v_fma_f32 v154, v127, v127, v154
	v_fma_f32 v138, v128, v128, v138
	v_fma_f32 v149, v129, v129, v149
	v_fma_f32 v150, v130, v130, v150
	v_fma_f32 v154, v131, v131, v154
	v_fma_f32 v138, v132, v132, v138
	v_fma_f32 v149, v133, v133, v149
	v_fma_f32 v150, v134, v134, v150
	v_fma_f32 v154, v135, v135, v154
	v_add_f32_e32 v138, v138, v149
	v_add_f32_e32 v150, v150, v154
	v_add_f32_e32 v138, v138, v150
	s_nop 1
	v_add_f32_dpp v138, v138, v138 quad_perm:[1,0,3,2] row_mask:0xf bank_mask:0xf
	s_nop 1
	v_add_f32_dpp v138, v138, v138 quad_perm:[2,3,0,1] row_mask:0xf bank_mask:0xf
	s_nop 1
	v_add_f32_dpp v138, v138, v138 row_half_mirror row_mask:0xf bank_mask:0xf
	s_nop 1
	v_add_f32_dpp v138, v138, v138 row_mirror row_mask:0xf bank_mask:0xf
	v_mov_b32_e32 v139, v138
	s_nop 1
	v_permlane16_swap_b32_e32 v138, v139
	v_add_f32_e32 v138, v138, v139
	v_mov_b32_e32 v139, v138
	s_nop 1
	v_permlane32_swap_b32_e32 v138, v139
	v_add_f32_e32 v138, v138, v139
	v_mul_f32_e32 v138, 0x3a800000, v138
	v_add_f32_e32 v138, 0x358637bd, v138
	v_rsq_f32_e32 v140, v138
	v_lshlrev_b32_e32 v32, 16, v40
	v_and_b32_e32 v33, 0xffff0000, v40
	v_lshlrev_b32_e32 v34, 16, v41
	v_and_b32_e32 v35, 0xffff0000, v41
	v_lshlrev_b32_e32 v36, 16, v42
	v_and_b32_e32 v37, 0xffff0000, v42
	v_lshlrev_b32_e32 v38, 16, v43
	v_and_b32_e32 v39, 0xffff0000, v43
	v_lshlrev_b32_e32 v40, 16, v44
	v_and_b32_e32 v41, 0xffff0000, v44
	v_lshlrev_b32_e32 v42, 16, v45
	v_and_b32_e32 v43, 0xffff0000, v45
	v_lshlrev_b32_e32 v44, 16, v46
	v_and_b32_e32 v45, 0xffff0000, v46
	v_lshlrev_b32_e32 v46, 16, v47
	v_and_b32_e32 v47, 0xffff0000, v47
	s_nop 0
	v_mul_f32_e32 v120, v120, v140
	v_mul_f32_e32 v121, v121, v140
	v_mul_f32_e32 v122, v122, v140
	v_mul_f32_e32 v123, v123, v140
	v_mul_f32_e32 v124, v124, v140
	v_mul_f32_e32 v125, v125, v140
	v_mul_f32_e32 v126, v126, v140
	v_mul_f32_e32 v127, v127, v140
	v_mul_f32_e32 v128, v128, v140
	v_mul_f32_e32 v129, v129, v140
	v_mul_f32_e32 v130, v130, v140
	v_mul_f32_e32 v131, v131, v140
	v_mul_f32_e32 v132, v132, v140
	v_mul_f32_e32 v133, v133, v140
	v_mul_f32_e32 v134, v134, v140
	v_mul_f32_e32 v135, v135, v140
	v_fma_f32 v32, v120, v72, v32
	v_fma_f32 v33, v121, v73, v33
	v_fma_f32 v34, v122, v74, v34
	v_fma_f32 v35, v123, v75, v35
	v_fma_f32 v36, v124, v76, v36
	v_fma_f32 v37, v125, v77, v37
	v_fma_f32 v38, v126, v78, v38
	v_fma_f32 v39, v127, v79, v39
	v_fma_f32 v40, v128, v80, v40
	v_fma_f32 v41, v129, v81, v41
	v_fma_f32 v42, v130, v82, v42
	v_fma_f32 v43, v131, v83, v43
	v_fma_f32 v44, v132, v84, v44
	v_fma_f32 v45, v133, v85, v45
	v_fma_f32 v46, v134, v86, v46
	v_fma_f32 v47, v135, v87, v47
	s_lshl_b32 vcc_lo, s19, 12
	s_add_u32 vcc_lo, vcc_lo, 0x2800000
	s_add_u32 s100, s16, vcc_lo
	s_addc_u32 s101, s17, 0
	global_store_dwordx4 v136, v[32:35], s[100:101] offset:0
	global_store_dwordx4 v136, v[36:39], s[100:101] offset:1024
	global_store_dwordx4 v136, v[40:43], s[100:101] offset:2048
	global_store_dwordx4 v136, v[44:47], s[100:101] offset:3072
	s_lshl_b32 vcc_lo, s19, 11
	s_add_u32 vcc_lo, vcc_lo, 0x2000000
	s_add_u32 s100, s12, vcc_lo
	s_addc_u32 s101, s13, 0
	global_load_dwordx2 v[40:41], v137, s[100:101] offset:0
	global_load_dwordx2 v[42:43], v137, s[100:101] offset:512
	global_load_dwordx2 v[44:45], v137, s[100:101] offset:1024
	global_load_dwordx2 v[46:47], v137, s[100:101] offset:1536
	s_lshl_b32 vcc_lo, s19, 11
	s_add_u32 vcc_lo, vcc_lo, 0x2000000
	s_add_u32 s100, s14, vcc_lo
	s_addc_u32 s101, s15, 0
	global_load_dwordx2 v[64:65], v137, s[100:101] offset:0
	global_load_dwordx2 v[66:67], v137, s[100:101] offset:512
	global_load_dwordx2 v[68:69], v137, s[100:101] offset:1024
	global_load_dwordx2 v[70:71], v137, s[100:101] offset:1536
	s_waitcnt vmcnt(24)
; __device__ __forceinline__ float bf2f(u16 h) { return __uint_as_float(((unsigned)h) << 16); }
; __device__ __forceinline__ void row_phase(const Params& P, int glayer, int layer, int xsrc, bool hasY, int gate_idx, const float* gpost,
;                           int xdst, bool doH, const float* gpre, int sh_idx, int nrows) {
;     ...
;         if (xsrc != 0 && row < N_X) {
; #pragma unroll
;           for (int i = 0; i < 4; ++i) {
;             const uint4 raw = xr[u][i];
;             xv[i].x = bf2f((u16)(raw.x & 0xffff)); xv[i].y = bf2f((u16)(raw.x >> 16));
;             xv[i].z = bf2f((u16)(raw.y & 0xffff)); xv[i].w = bf2f((u16)(raw.y >> 16));
;           }
;         } else {
; #pragma unroll
;           for (int i = 0; i < 4; ++i) {
;             xv[i].x = __uint_as_float(xr[u][i].x); xv[i].y = __uint_as_float(xr[u][i].y);
;             xv[i].z = __uint_as_float(xr[u][i].z); xv[i].w = __uint_as_float(xr[u][i].w);
;           }
;         }
;         if (hasY) {
;           float4 yv[4];
;           float ss = 0.f;
; #pragma unroll
;           for (int i = 0; i < 4; ++i) {
;             const uint2 raw = yy[u][i];
;             yv[i].x = bf2f((u16)(raw.x & 0xffff)); yv[i].y = bf2f((u16)(raw.x >> 16));
;             yv[i].z = bf2f((u16)(raw.y & 0xffff)); yv[i].w = bf2f((u16)(raw.y >> 16));
;             ss += yv[i].x * yv[i].x + yv[i].y * yv[i].y + yv[i].z * yv[i].z + yv[i].w * yv[i].w;
;           }
;           ss = wave_sum(ss);
;           const float rstd = __builtin_amdgcn_rsqf(ss * (1.f / 1024.f) + EPSF);
; #pragma unroll
;           for (int i = 0; i < 4; ++i) {
;             const int col = (i * 64 + lane) * 4;
;             const float4 gt = *reinterpret_cast<const float4*>(modg + gate_idx * 1024 + col);
;             const float4 gp = *reinterpret_cast<const float4*>(gpost + col);
;             xv[i].x += gt.x * (yv[i].x * rstd * gp.x); xv[i].y += gt.y * (yv[i].y * rstd * gp.y);
;             xv[i].z += gt.z * (yv[i].z * rstd * gp.z); xv[i].w += gt.w * (yv[i].w * rstd * gp.w);
;           }
;         }
;         if (xdst == 3 || (xdst == 1 && row >= N_X)) {
;           float* xout = (xdst == 3) ? P.out + (long)row * 1024 : P.xc + (long)(row - N_X) * 1024;
; #pragma unroll
;           for (int i = 0; i < 4; ++i) *reinterpret_cast<float4*>(xout + (i * 64 + lane) * 4) = xv[i];
	v_lshlrev_b32_e32 v120, 16, v48
	v_and_b32_e32 v121, 0xffff0000, v48
	v_lshlrev_b32_e32 v122, 16, v49
	v_and_b32_e32 v123, 0xffff0000, v49
	v_lshlrev_b32_e32 v124, 16, v50
	v_and_b32_e32 v125, 0xffff0000, v50
	v_lshlrev_b32_e32 v126, 16, v51
	v_and_b32_e32 v127, 0xffff0000, v51
	v_lshlrev_b32_e32 v128, 16, v52
	v_and_b32_e32 v129, 0xffff0000, v52
	v_lshlrev_b32_e32 v130, 16, v53
	v_and_b32_e32 v131, 0xffff0000, v53
	v_lshlrev_b32_e32 v132, 16, v54
	v_and_b32_e32 v133, 0xffff0000, v54
	v_lshlrev_b32_e32 v134, 16, v55
	v_and_b32_e32 v135, 0xffff0000, v55
	v_mul_f32_e32 v138, v120, v120
	v_mul_f32_e32 v149, v121, v121
	v_mul_f32_e32 v150, v122, v122
	v_mul_f32_e32 v154, v123, v123
	v_fma_f32 v138, v124, v124, v138
	v_fma_f32 v149, v125, v125, v149
	v_fma_f32 v150, v126, v126, v150
	v_fma_f32 v154, v127, v127, v154
	v_fma_f32 v138, v128, v128, v138
	v_fma_f32 v149, v129, v129, v149
	v_fma_f32 v150, v130, v130, v150
	v_fma_f32 v154, v131, v131, v154
	v_fma_f32 v138, v132, v132, v138
	v_fma_f32 v149, v133, v133, v149
	v_fma_f32 v150, v134, v134, v150
	v_fma_f32 v154, v135, v135, v154
	v_add_f32_e32 v138, v138, v149
	v_add_f32_e32 v150, v150, v154
	v_add_f32_e32 v138, v138, v150
	s_nop 1
	v_add_f32_dpp v138, v138, v138 quad_perm:[1,0,3,2] row_mask:0xf bank_mask:0xf
	s_nop 1
	v_add_f32_dpp v138, v138, v138 quad_perm:[2,3,0,1] row_mask:0xf bank_mask:0xf
	s_nop 1
	v_add_f32_dpp v138, v138, v138 row_half_mirror row_mask:0xf bank_mask:0xf
	s_nop 1
	v_add_f32_dpp v138, v138, v138 row_mirror row_mask:0xf bank_mask:0xf
	v_mov_b32_e32 v139, v138
	s_nop 1
	v_permlane16_swap_b32_e32 v138, v139
	v_add_f32_e32 v138, v138, v139
	v_mov_b32_e32 v139, v138
	s_nop 1
	v_permlane32_swap_b32_e32 v138, v139
	v_add_f32_e32 v138, v138, v139
	v_mul_f32_e32 v138, 0x3a800000, v138
	v_add_f32_e32 v138, 0x358637bd, v138
	v_rsq_f32_e32 v140, v138
	v_lshlrev_b32_e32 v0, 16, v8
	v_and_b32_e32 v1, 0xffff0000, v8
	v_lshlrev_b32_e32 v2, 16, v9
	v_and_b32_e32 v3, 0xffff0000, v9
	v_lshlrev_b32_e32 v4, 16, v10
	v_and_b32_e32 v5, 0xffff0000, v10
	v_lshlrev_b32_e32 v6, 16, v11
	v_and_b32_e32 v7, 0xffff0000, v11
	v_lshlrev_b32_e32 v8, 16, v12
	v_and_b32_e32 v9, 0xffff0000, v12
	v_lshlrev_b32_e32 v10, 16, v13
	v_and_b32_e32 v11, 0xffff0000, v13
	v_lshlrev_b32_e32 v12, 16, v14
	v_and_b32_e32 v13, 0xffff0000, v14
	v_lshlrev_b32_e32 v14, 16, v15
	v_and_b32_e32 v15, 0xffff0000, v15
	s_nop 0
	v_mul_f32_e32 v120, v120, v140
	v_mul_f32_e32 v121, v121, v140
	v_mul_f32_e32 v122, v122, v140
	v_mul_f32_e32 v123, v123, v140
	v_mul_f32_e32 v124, v124, v140
	v_mul_f32_e32 v125, v125, v140
	v_mul_f32_e32 v126, v126, v140
	v_mul_f32_e32 v127, v127, v140
	v_mul_f32_e32 v128, v128, v140
	v_mul_f32_e32 v129, v129, v140
	v_mul_f32_e32 v130, v130, v140
	v_mul_f32_e32 v131, v131, v140
	v_mul_f32_e32 v132, v132, v140
	v_mul_f32_e32 v133, v133, v140
	v_mul_f32_e32 v134, v134, v140
	v_mul_f32_e32 v135, v135, v140
	v_fma_f32 v0, v120, v72, v0
	v_fma_f32 v1, v121, v73, v1
	v_fma_f32 v2, v122, v74, v2
	v_fma_f32 v3, v123, v75, v3
	v_fma_f32 v4, v124, v76, v4
	v_fma_f32 v5, v125, v77, v5
	v_fma_f32 v6, v126, v78, v6
	v_fma_f32 v7, v127, v79, v7
	v_fma_f32 v8, v128, v80, v8
	v_fma_f32 v9, v129, v81, v9
	v_fma_f32 v10, v130, v82, v10
	v_fma_f32 v11, v131, v83, v11
	v_fma_f32 v12, v132, v84, v12
	v_fma_f32 v13, v133, v85, v13
	v_fma_f32 v14, v134, v86, v14
	v_fma_f32 v15, v135, v87, v15
	s_lshl_b32 vcc_lo, s19, 12
	s_add_u32 vcc_lo, vcc_lo, 0x3000000
	s_add_u32 s100, s16, vcc_lo
	s_addc_u32 s101, s17, 0
	global_store_dwordx4 v136, v[0:3], s[100:101] offset:0
	global_store_dwordx4 v136, v[4:7], s[100:101] offset:1024
	global_store_dwordx4 v136, v[8:11], s[100:101] offset:2048
	global_store_dwordx4 v136, v[12:15], s[100:101] offset:3072
	s_lshl_b32 vcc_lo, s19, 11
	s_add_u32 vcc_lo, vcc_lo, 0x2400000
	s_add_u32 s100, s12, vcc_lo
	s_addc_u32 s101, s13, 0
	global_load_dwordx2 v[8:9], v137, s[100:101] offset:0
	global_load_dwordx2 v[10:11], v137, s[100:101] offset:512
	global_load_dwordx2 v[12:13], v137, s[100:101] offset:1024
	global_load_dwordx2 v[14:15], v137, s[100:101] offset:1536
	s_lshl_b32 vcc_lo, s19, 11
	s_add_u32 vcc_lo, vcc_lo, 0x2400000
	s_add_u32 s100, s14, vcc_lo
	s_addc_u32 s101, s15, 0
	global_load_dwordx2 v[48:49], v137, s[100:101] offset:0
	global_load_dwordx2 v[50:51], v137, s[100:101] offset:512
	global_load_dwordx2 v[52:53], v137, s[100:101] offset:1024
	global_load_dwordx2 v[54:55], v137, s[100:101] offset:1536
	s_waitcnt vmcnt(24)
; __device__ __forceinline__ float bf2f(u16 h) { return __uint_as_float(((unsigned)h) << 16); }
; __device__ __forceinline__ void row_phase(const Params& P, int glayer, int layer, int xsrc, bool hasY, int gate_idx, const float* gpost,
;                           int xdst, bool doH, const float* gpre, int sh_idx, int nrows) {
;     ...
;         if (xsrc != 0 && row < N_X) {
; #pragma unroll
;           for (int i = 0; i < 4; ++i) {
;             const uint4 raw = xr[u][i];
;             xv[i].x = bf2f((u16)(raw.x & 0xffff)); xv[i].y = bf2f((u16)(raw.x >> 16));
;             xv[i].z = bf2f((u16)(raw.y & 0xffff)); xv[i].w = bf2f((u16)(raw.y >> 16));
;           }
;         } else {
; #pragma unroll
;           for (int i = 0; i < 4; ++i) {
;             xv[i].x = __uint_as_float(xr[u][i].x); xv[i].y = __uint_as_float(xr[u][i].y);
;             xv[i].z = __uint_as_float(xr[u][i].z); xv[i].w = __uint_as_float(xr[u][i].w);
;           }
;         }
;         if (hasY) {
;           float4 yv[4];
;           float ss = 0.f;
; #pragma unroll
;           for (int i = 0; i < 4; ++i) {
;             const uint2 raw = yy[u][i];
;             yv[i].x = bf2f((u16)(raw.x & 0xffff)); yv[i].y = bf2f((u16)(raw.x >> 16));
;             yv[i].z = bf2f((u16)(raw.y & 0xffff)); yv[i].w = bf2f((u16)(raw.y >> 16));
;             ss += yv[i].x * yv[i].x + yv[i].y * yv[i].y + yv[i].z * yv[i].z + yv[i].w * yv[i].w;
;           }
;           ss = wave_sum(ss);
;           const float rstd = __builtin_amdgcn_rsqf(ss * (1.f / 1024.f) + EPSF);
; #pragma unroll
;           for (int i = 0; i < 4; ++i) {
;             const int col = (i * 64 + lane) * 4;
;             const float4 gt = *reinterpret_cast<const float4*>(modg + gate_idx * 1024 + col);
;             const float4 gp = *reinterpret_cast<const float4*>(gpost + col);
;             xv[i].x += gt.x * (yv[i].x * rstd * gp.x); xv[i].y += gt.y * (yv[i].y * rstd * gp.y);
;             xv[i].z += gt.z * (yv[i].z * rstd * gp.z); xv[i].w += gt.w * (yv[i].w * rstd * gp.w);
;           }
;         }
;         if (xdst == 3 || (xdst == 1 && row >= N_X)) {
;           float* xout = (xdst == 3) ? P.out + (long)row * 1024 : P.xc + (long)(row - N_X) * 1024;
; #pragma unroll
;           for (int i = 0; i < 4; ++i) *reinterpret_cast<float4*>(xout + (i * 64 + lane) * 4) = xv[i];
	v_lshlrev_b32_e32 v120, 16, v56
	v_and_b32_e32 v121, 0xffff0000, v56
	v_lshlrev_b32_e32 v122, 16, v57
	v_and_b32_e32 v123, 0xffff0000, v57
	v_lshlrev_b32_e32 v124, 16, v58
	v_and_b32_e32 v125, 0xffff0000, v58
	v_lshlrev_b32_e32 v126, 16, v59
	v_and_b32_e32 v127, 0xffff0000, v59
	v_lshlrev_b32_e32 v128, 16, v60
	v_and_b32_e32 v129, 0xffff0000, v60
	v_lshlrev_b32_e32 v130, 16, v61
	v_and_b32_e32 v131, 0xffff0000, v61
	v_lshlrev_b32_e32 v132, 16, v62
	v_and_b32_e32 v133, 0xffff0000, v62
	v_lshlrev_b32_e32 v134, 16, v63
	v_and_b32_e32 v135, 0xffff0000, v63
	v_mul_f32_e32 v138, v120, v120
	v_mul_f32_e32 v149, v121, v121
	v_mul_f32_e32 v150, v122, v122
	v_mul_f32_e32 v154, v123, v123
	v_fma_f32 v138, v124, v124, v138
	v_fma_f32 v149, v125, v125, v149
	v_fma_f32 v150, v126, v126, v150
	v_fma_f32 v154, v127, v127, v154
	v_fma_f32 v138, v128, v128, v138
	v_fma_f32 v149, v129, v129, v149
	v_fma_f32 v150, v130, v130, v150
	v_fma_f32 v154, v131, v131, v154
	v_fma_f32 v138, v132, v132, v138
	v_fma_f32 v149, v133, v133, v149
	v_fma_f32 v150, v134, v134, v150
	v_fma_f32 v154, v135, v135, v154
	v_add_f32_e32 v138, v138, v149
	v_add_f32_e32 v150, v150, v154
	v_add_f32_e32 v138, v138, v150
	s_nop 1
	v_add_f32_dpp v138, v138, v138 quad_perm:[1,0,3,2] row_mask:0xf bank_mask:0xf
	s_nop 1
	v_add_f32_dpp v138, v138, v138 quad_perm:[2,3,0,1] row_mask:0xf bank_mask:0xf
	s_nop 1
	v_add_f32_dpp v138, v138, v138 row_half_mirror row_mask:0xf bank_mask:0xf
	s_nop 1
	v_add_f32_dpp v138, v138, v138 row_mirror row_mask:0xf bank_mask:0xf
	v_mov_b32_e32 v139, v138
	s_nop 1
	v_permlane16_swap_b32_e32 v138, v139
	v_add_f32_e32 v138, v138, v139
	v_mov_b32_e32 v139, v138
	s_nop 1
	v_permlane32_swap_b32_e32 v138, v139
	v_add_f32_e32 v138, v138, v139
	v_mul_f32_e32 v138, 0x3a800000, v138
	v_add_f32_e32 v138, 0x358637bd, v138
	v_rsq_f32_e32 v140, v138
	v_lshlrev_b32_e32 v16, 16, v24
	v_and_b32_e32 v17, 0xffff0000, v24
	v_lshlrev_b32_e32 v18, 16, v25
	v_and_b32_e32 v19, 0xffff0000, v25
	v_lshlrev_b32_e32 v20, 16, v26
	v_and_b32_e32 v21, 0xffff0000, v26
	v_lshlrev_b32_e32 v22, 16, v27
	v_and_b32_e32 v23, 0xffff0000, v27
	v_lshlrev_b32_e32 v24, 16, v28
	v_and_b32_e32 v25, 0xffff0000, v28
	v_lshlrev_b32_e32 v26, 16, v29
	v_and_b32_e32 v27, 0xffff0000, v29
	v_lshlrev_b32_e32 v28, 16, v30
	v_and_b32_e32 v29, 0xffff0000, v30
	v_lshlrev_b32_e32 v30, 16, v31
	v_and_b32_e32 v31, 0xffff0000, v31
	s_nop 0
	v_mul_f32_e32 v120, v120, v140
	v_mul_f32_e32 v121, v121, v140
	v_mul_f32_e32 v122, v122, v140
	v_mul_f32_e32 v123, v123, v140
	v_mul_f32_e32 v124, v124, v140
	v_mul_f32_e32 v125, v125, v140
	v_mul_f32_e32 v126, v126, v140
	v_mul_f32_e32 v127, v127, v140
	v_mul_f32_e32 v128, v128, v140
	v_mul_f32_e32 v129, v129, v140
	v_mul_f32_e32 v130, v130, v140
	v_mul_f32_e32 v131, v131, v140
	v_mul_f32_e32 v132, v132, v140
	v_mul_f32_e32 v133, v133, v140
	v_mul_f32_e32 v134, v134, v140
	v_mul_f32_e32 v135, v135, v140
	v_fma_f32 v16, v120, v72, v16
	v_fma_f32 v17, v121, v73, v17
	v_fma_f32 v18, v122, v74, v18
	v_fma_f32 v19, v123, v75, v19
	v_fma_f32 v20, v124, v76, v20
	v_fma_f32 v21, v125, v77, v21
	v_fma_f32 v22, v126, v78, v22
	v_fma_f32 v23, v127, v79, v23
	v_fma_f32 v24, v128, v80, v24
	v_fma_f32 v25, v129, v81, v25
	v_fma_f32 v26, v130, v82, v26
	v_fma_f32 v27, v131, v83, v27
	v_fma_f32 v28, v132, v84, v28
	v_fma_f32 v29, v133, v85, v29
	v_fma_f32 v30, v134, v86, v30
	v_fma_f32 v31, v135, v87, v31
	s_lshl_b32 vcc_lo, s19, 12
	s_add_u32 vcc_lo, vcc_lo, 0x3800000
	s_add_u32 s100, s16, vcc_lo
	s_addc_u32 s101, s17, 0
	global_store_dwordx4 v136, v[16:19], s[100:101] offset:0
	global_store_dwordx4 v136, v[20:23], s[100:101] offset:1024
	global_store_dwordx4 v136, v[24:27], s[100:101] offset:2048
	global_store_dwordx4 v136, v[28:31], s[100:101] offset:3072
	s_add_u32 s100, s20, 0x2f000
	s_addc_u32 s101, s21, 0
	global_load_dwordx4 v[72:75], v136, s[100:101] offset:0
	global_load_dwordx4 v[76:79], v136, s[100:101] offset:1024
	global_load_dwordx4 v[80:83], v136, s[100:101] offset:2048
	global_load_dwordx4 v[84:87], v136, s[100:101] offset:3072
	s_load_dwordx2 s[98:99], s[4:5], 0x48
	s_waitcnt lgkmcnt(0)
	s_add_u32 s98, s98, 0x1000
	s_addc_u32 s99, s99, 0
	global_load_dwordx4 v[120:123], v136, s[98:99] offset:0
	global_load_dwordx4 v[124:127], v136, s[98:99] offset:1024
	global_load_dwordx4 v[128:131], v136, s[98:99] offset:2048
	global_load_dwordx4 v[132:135], v136, s[98:99] offset:3072
	s_waitcnt vmcnt(0)
; __device__ __forceinline__ float bf2f(u16 h) { return __uint_as_float(((unsigned)h) << 16); }
; __device__ __forceinline__ void row_phase(const Params& P, int glayer, int layer, int xsrc, bool hasY, int gate_idx, const float* gpost,
;                           int xdst, bool doH, const float* gpre, int sh_idx, int nrows) {
;     ...
;         if (xsrc != 0 && row < N_X) {
; #pragma unroll
;           for (int i = 0; i < 4; ++i) {
;             const uint4 raw = xr[u][i];
;             xv[i].x = bf2f((u16)(raw.x & 0xffff)); xv[i].y = bf2f((u16)(raw.x >> 16));
;             xv[i].z = bf2f((u16)(raw.y & 0xffff)); xv[i].w = bf2f((u16)(raw.y >> 16));
;           }
;         } else {
; #pragma unroll
;           for (int i = 0; i < 4; ++i) {
;             xv[i].x = __uint_as_float(xr[u][i].x); xv[i].y = __uint_as_float(xr[u][i].y);
;             xv[i].z = __uint_as_float(xr[u][i].z); xv[i].w = __uint_as_float(xr[u][i].w);
;           }
;         }
;         if (hasY) {
;           float4 yv[4];
;           float ss = 0.f;
; #pragma unroll
;           for (int i = 0; i < 4; ++i) {
;             const uint2 raw = yy[u][i];
;             yv[i].x = bf2f((u16)(raw.x & 0xffff)); yv[i].y = bf2f((u16)(raw.x >> 16));
;             yv[i].z = bf2f((u16)(raw.y & 0xffff)); yv[i].w = bf2f((u16)(raw.y >> 16));
;             ss += yv[i].x * yv[i].x + yv[i].y * yv[i].y + yv[i].z * yv[i].z + yv[i].w * yv[i].w;
;           }
;           ss = wave_sum(ss);
;           const float rstd = __builtin_amdgcn_rsqf(ss * (1.f / 1024.f) + EPSF);
; #pragma unroll
;           for (int i = 0; i < 4; ++i) {
;             const int col = (i * 64 + lane) * 4;
;             const float4 gt = *reinterpret_cast<const float4*>(modg + gate_idx * 1024 + col);
;             const float4 gp = *reinterpret_cast<const float4*>(gpost + col);
;             xv[i].x += gt.x * (yv[i].x * rstd * gp.x); xv[i].y += gt.y * (yv[i].y * rstd * gp.y);
;             xv[i].z += gt.z * (yv[i].z * rstd * gp.z); xv[i].w += gt.w * (yv[i].w * rstd * gp.w);
;           }
;         }
;         if (xdst == 3 || (xdst == 1 && row >= N_X)) {
;           float* xout = (xdst == 3) ? P.out + (long)row * 1024 : P.xc + (long)(row - N_X) * 1024;
; #pragma unroll
;           for (int i = 0; i < 4; ++i) *reinterpret_cast<float4*>(xout + (i * 64 + lane) * 4) = xv[i];
	v_mul_f32_e32 v72, v72, v120
	v_mul_f32_e32 v73, v73, v121
	v_mul_f32_e32 v74, v74, v122
	v_mul_f32_e32 v75, v75, v123
	v_mul_f32_e32 v76, v76, v124
	v_mul_f32_e32 v77, v77, v125
	v_mul_f32_e32 v78, v78, v126
	v_mul_f32_e32 v79, v79, v127
	v_mul_f32_e32 v80, v80, v128
	v_mul_f32_e32 v81, v81, v129
	v_mul_f32_e32 v82, v82, v130
	v_mul_f32_e32 v83, v83, v131
	v_mul_f32_e32 v84, v84, v132
	v_mul_f32_e32 v85, v85, v133
	v_mul_f32_e32 v86, v86, v134
	v_mul_f32_e32 v87, v87, v135
	s_lshl_b32 vcc_lo, s19, 11
	s_add_u32 vcc_lo, vcc_lo, 0x2800000
	s_add_u32 s100, s12, vcc_lo
	s_addc_u32 s101, s13, 0
	global_load_dwordx2 v[24:25], v137, s[100:101] offset:0
	global_load_dwordx2 v[26:27], v137, s[100:101] offset:512
	global_load_dwordx2 v[28:29], v137, s[100:101] offset:1024
	global_load_dwordx2 v[30:31], v137, s[100:101] offset:1536
	s_lshl_b32 vcc_lo, s19, 11
	s_add_u32 vcc_lo, vcc_lo, 0x2800000
	s_add_u32 s100, s14, vcc_lo
	s_addc_u32 s101, s15, 0
	global_load_dwordx2 v[56:57], v137, s[100:101] offset:0
	global_load_dwordx2 v[58:59], v137, s[100:101] offset:512
	global_load_dwordx2 v[60:61], v137, s[100:101] offset:1024
	global_load_dwordx2 v[62:63], v137, s[100:101] offset:1536
	v_lshlrev_b32_e32 v120, 16, v64
	v_and_b32_e32 v121, 0xffff0000, v64
	v_lshlrev_b32_e32 v122, 16, v65
	v_and_b32_e32 v123, 0xffff0000, v65
	v_lshlrev_b32_e32 v124, 16, v66
	v_and_b32_e32 v125, 0xffff0000, v66
	v_lshlrev_b32_e32 v126, 16, v67
	v_and_b32_e32 v127, 0xffff0000, v67
	v_lshlrev_b32_e32 v128, 16, v68
	v_and_b32_e32 v129, 0xffff0000, v68
	v_lshlrev_b32_e32 v130, 16, v69
	v_and_b32_e32 v131, 0xffff0000, v69
	v_lshlrev_b32_e32 v132, 16, v70
	v_and_b32_e32 v133, 0xffff0000, v70
	v_lshlrev_b32_e32 v134, 16, v71
	v_and_b32_e32 v135, 0xffff0000, v71
	v_mul_f32_e32 v138, v120, v120
	v_mul_f32_e32 v149, v121, v121
	v_mul_f32_e32 v150, v122, v122
	v_mul_f32_e32 v154, v123, v123
	v_fma_f32 v138, v124, v124, v138
	v_fma_f32 v149, v125, v125, v149
	v_fma_f32 v150, v126, v126, v150
	v_fma_f32 v154, v127, v127, v154
	v_fma_f32 v138, v128, v128, v138
	v_fma_f32 v149, v129, v129, v149
	v_fma_f32 v150, v130, v130, v150
	v_fma_f32 v154, v131, v131, v154
	v_fma_f32 v138, v132, v132, v138
	v_fma_f32 v149, v133, v133, v149
	v_fma_f32 v150, v134, v134, v150
	v_fma_f32 v154, v135, v135, v154
	v_add_f32_e32 v138, v138, v149
	v_add_f32_e32 v150, v150, v154
	v_add_f32_e32 v138, v138, v150
	s_nop 1
	v_add_f32_dpp v138, v138, v138 quad_perm:[1,0,3,2] row_mask:0xf bank_mask:0xf
	s_nop 1
	v_add_f32_dpp v138, v138, v138 quad_perm:[2,3,0,1] row_mask:0xf bank_mask:0xf
	s_nop 1
	v_add_f32_dpp v138, v138, v138 row_half_mirror row_mask:0xf bank_mask:0xf
	s_nop 1
	v_add_f32_dpp v138, v138, v138 row_mirror row_mask:0xf bank_mask:0xf
	v_mov_b32_e32 v139, v138
	s_nop 1
	v_permlane16_swap_b32_e32 v138, v139
	v_add_f32_e32 v138, v138, v139
	v_mov_b32_e32 v139, v138
	s_nop 1
	v_permlane32_swap_b32_e32 v138, v139
	v_add_f32_e32 v138, v138, v139
	v_mul_f32_e32 v138, 0x3a800000, v138
	v_add_f32_e32 v138, 0x358637bd, v138
	v_rsq_f32_e32 v140, v138
	v_lshlrev_b32_e32 v32, 16, v40
	v_and_b32_e32 v33, 0xffff0000, v40
	v_lshlrev_b32_e32 v34, 16, v41
	v_and_b32_e32 v35, 0xffff0000, v41
	v_lshlrev_b32_e32 v36, 16, v42
	v_and_b32_e32 v37, 0xffff0000, v42
	v_lshlrev_b32_e32 v38, 16, v43
	v_and_b32_e32 v39, 0xffff0000, v43
	v_lshlrev_b32_e32 v40, 16, v44
	v_and_b32_e32 v41, 0xffff0000, v44
	v_lshlrev_b32_e32 v42, 16, v45
	v_and_b32_e32 v43, 0xffff0000, v45
	v_lshlrev_b32_e32 v44, 16, v46
	v_and_b32_e32 v45, 0xffff0000, v46
	v_lshlrev_b32_e32 v46, 16, v47
	v_and_b32_e32 v47, 0xffff0000, v47
	s_nop 0
	v_mul_f32_e32 v120, v120, v140
	v_mul_f32_e32 v121, v121, v140
	v_mul_f32_e32 v122, v122, v140
	v_mul_f32_e32 v123, v123, v140
	v_mul_f32_e32 v124, v124, v140
	v_mul_f32_e32 v125, v125, v140
	v_mul_f32_e32 v126, v126, v140
	v_mul_f32_e32 v127, v127, v140
	v_mul_f32_e32 v128, v128, v140
	v_mul_f32_e32 v129, v129, v140
	v_mul_f32_e32 v130, v130, v140
	v_mul_f32_e32 v131, v131, v140
	v_mul_f32_e32 v132, v132, v140
	v_mul_f32_e32 v133, v133, v140
	v_mul_f32_e32 v134, v134, v140
	v_mul_f32_e32 v135, v135, v140
	v_fma_f32 v32, v120, v72, v32
	v_fma_f32 v33, v121, v73, v33
	v_fma_f32 v34, v122, v74, v34
	v_fma_f32 v35, v123, v75, v35
	v_fma_f32 v36, v124, v76, v36
	v_fma_f32 v37, v125, v77, v37
	v_fma_f32 v38, v126, v78, v38
	v_fma_f32 v39, v127, v79, v39
	v_fma_f32 v40, v128, v80, v40
	v_fma_f32 v41, v129, v81, v41
	v_fma_f32 v42, v130, v82, v42
	v_fma_f32 v43, v131, v83, v43
	v_fma_f32 v44, v132, v84, v44
	v_fma_f32 v45, v133, v85, v45
	v_fma_f32 v46, v134, v86, v46
	v_fma_f32 v47, v135, v87, v47
	s_lshl_b32 vcc_lo, s19, 12
	s_add_u32 vcc_lo, vcc_lo, 0x4000000
	s_add_u32 s100, s16, vcc_lo
	s_addc_u32 s101, s17, 0
	global_store_dwordx4 v136, v[32:35], s[100:101] offset:0
	global_store_dwordx4 v136, v[36:39], s[100:101] offset:1024
	global_store_dwordx4 v136, v[40:43], s[100:101] offset:2048
	global_store_dwordx4 v136, v[44:47], s[100:101] offset:3072
	s_lshl_b32 vcc_lo, s19, 11
	s_add_u32 vcc_lo, vcc_lo, 0x2c00000
	s_add_u32 s100, s12, vcc_lo
	s_addc_u32 s101, s13, 0
	global_load_dwordx2 v[40:41], v137, s[100:101] offset:0
	global_load_dwordx2 v[42:43], v137, s[100:101] offset:512
	global_load_dwordx2 v[44:45], v137, s[100:101] offset:1024
	global_load_dwordx2 v[46:47], v137, s[100:101] offset:1536
	s_lshl_b32 vcc_lo, s19, 11
	s_add_u32 vcc_lo, vcc_lo, 0x2c00000
	s_add_u32 s100, s14, vcc_lo
	s_addc_u32 s101, s15, 0
	global_load_dwordx2 v[64:65], v137, s[100:101] offset:0
	global_load_dwordx2 v[66:67], v137, s[100:101] offset:512
	global_load_dwordx2 v[68:69], v137, s[100:101] offset:1024
	global_load_dwordx2 v[70:71], v137, s[100:101] offset:1536
; __device__ __forceinline__ float bf2f(u16 h) { return __uint_as_float(((unsigned)h) << 16); }
; __device__ __forceinline__ void row_phase(const Params& P, int glayer, int layer, int xsrc, bool hasY, int gate_idx, const float* gpost,
;                           int xdst, bool doH, const float* gpre, int sh_idx, int nrows) {
;     ...
;         if (xsrc != 0 && row < N_X) {
; #pragma unroll
;           for (int i = 0; i < 4; ++i) {
;             const uint4 raw = xr[u][i];
;             xv[i].x = bf2f((u16)(raw.x & 0xffff)); xv[i].y = bf2f((u16)(raw.x >> 16));
;             xv[i].z = bf2f((u16)(raw.y & 0xffff)); xv[i].w = bf2f((u16)(raw.y >> 16));
;           }
;         } else {
; #pragma unroll
;           for (int i = 0; i < 4; ++i) {
;             xv[i].x = __uint_as_float(xr[u][i].x); xv[i].y = __uint_as_float(xr[u][i].y);
;             xv[i].z = __uint_as_float(xr[u][i].z); xv[i].w = __uint_as_float(xr[u][i].w);
;           }
;         }
;         if (hasY) {
;           float4 yv[4];
;           float ss = 0.f;
; #pragma unroll
;           for (int i = 0; i < 4; ++i) {
;             const uint2 raw = yy[u][i];
;             yv[i].x = bf2f((u16)(raw.x & 0xffff)); yv[i].y = bf2f((u16)(raw.x >> 16));
;             yv[i].z = bf2f((u16)(raw.y & 0xffff)); yv[i].w = bf2f((u16)(raw.y >> 16));
;             ss += yv[i].x * yv[i].x + yv[i].y * yv[i].y + yv[i].z * yv[i].z + yv[i].w * yv[i].w;
;           }
;           ss = wave_sum(ss);
;           const float rstd = __builtin_amdgcn_rsqf(ss * (1.f / 1024.f) + EPSF);
; #pragma unroll
;           for (int i = 0; i < 4; ++i) {
;             const int col = (i * 64 + lane) * 4;
;             const float4 gt = *reinterpret_cast<const float4*>(modg + gate_idx * 1024 + col);
;             const float4 gp = *reinterpret_cast<const float4*>(gpost + col);
;             xv[i].x += gt.x * (yv[i].x * rstd * gp.x); xv[i].y += gt.y * (yv[i].y * rstd * gp.y);
;             xv[i].z += gt.z * (yv[i].z * rstd * gp.z); xv[i].w += gt.w * (yv[i].w * rstd * gp.w);
;           }
;         }
;         if (xdst == 3 || (xdst == 1 && row >= N_X)) {
;           float* xout = (xdst == 3) ? P.out + (long)row * 1024 : P.xc + (long)(row - N_X) * 1024;
; #pragma unroll
;           for (int i = 0; i < 4; ++i) *reinterpret_cast<float4*>(xout + (i * 64 + lane) * 4) = xv[i];
	v_lshlrev_b32_e32 v120, 16, v48
	v_and_b32_e32 v121, 0xffff0000, v48
	v_lshlrev_b32_e32 v122, 16, v49
	v_and_b32_e32 v123, 0xffff0000, v49
	v_lshlrev_b32_e32 v124, 16, v50
	v_and_b32_e32 v125, 0xffff0000, v50
	v_lshlrev_b32_e32 v126, 16, v51
	v_and_b32_e32 v127, 0xffff0000, v51
	v_lshlrev_b32_e32 v128, 16, v52
	v_and_b32_e32 v129, 0xffff0000, v52
	v_lshlrev_b32_e32 v130, 16, v53
	v_and_b32_e32 v131, 0xffff0000, v53
	v_lshlrev_b32_e32 v132, 16, v54
	v_and_b32_e32 v133, 0xffff0000, v54
	v_lshlrev_b32_e32 v134, 16, v55
	v_and_b32_e32 v135, 0xffff0000, v55
	v_mul_f32_e32 v138, v120, v120
	v_mul_f32_e32 v149, v121, v121
	v_mul_f32_e32 v150, v122, v122
	v_mul_f32_e32 v154, v123, v123
	v_fma_f32 v138, v124, v124, v138
	v_fma_f32 v149, v125, v125, v149
	v_fma_f32 v150, v126, v126, v150
	v_fma_f32 v154, v127, v127, v154
	v_fma_f32 v138, v128, v128, v138
	v_fma_f32 v149, v129, v129, v149
	v_fma_f32 v150, v130, v130, v150
	v_fma_f32 v154, v131, v131, v154
	v_fma_f32 v138, v132, v132, v138
	v_fma_f32 v149, v133, v133, v149
	v_fma_f32 v150, v134, v134, v150
	v_fma_f32 v154, v135, v135, v154
	v_add_f32_e32 v138, v138, v149
	v_add_f32_e32 v150, v150, v154
	v_add_f32_e32 v138, v138, v150
	s_nop 1
	v_add_f32_dpp v138, v138, v138 quad_perm:[1,0,3,2] row_mask:0xf bank_mask:0xf
	s_nop 1
	v_add_f32_dpp v138, v138, v138 quad_perm:[2,3,0,1] row_mask:0xf bank_mask:0xf
	s_nop 1
	v_add_f32_dpp v138, v138, v138 row_half_mirror row_mask:0xf bank_mask:0xf
	s_nop 1
	v_add_f32_dpp v138, v138, v138 row_mirror row_mask:0xf bank_mask:0xf
	v_mov_b32_e32 v139, v138
	s_nop 1
	v_permlane16_swap_b32_e32 v138, v139
	v_add_f32_e32 v138, v138, v139
	v_mov_b32_e32 v139, v138
	s_nop 1
	v_permlane32_swap_b32_e32 v138, v139
	v_add_f32_e32 v138, v138, v139
	v_mul_f32_e32 v138, 0x3a800000, v138
	v_add_f32_e32 v138, 0x358637bd, v138
	v_rsq_f32_e32 v140, v138
	v_lshlrev_b32_e32 v0, 16, v8
	v_and_b32_e32 v1, 0xffff0000, v8
	v_lshlrev_b32_e32 v2, 16, v9
	v_and_b32_e32 v3, 0xffff0000, v9
	v_lshlrev_b32_e32 v4, 16, v10
	v_and_b32_e32 v5, 0xffff0000, v10
	v_lshlrev_b32_e32 v6, 16, v11
	v_and_b32_e32 v7, 0xffff0000, v11
	v_lshlrev_b32_e32 v8, 16, v12
	v_and_b32_e32 v9, 0xffff0000, v12
	v_lshlrev_b32_e32 v10, 16, v13
	v_and_b32_e32 v11, 0xffff0000, v13
	v_lshlrev_b32_e32 v12, 16, v14
	v_and_b32_e32 v13, 0xffff0000, v14
	v_lshlrev_b32_e32 v14, 16, v15
	v_and_b32_e32 v15, 0xffff0000, v15
	s_nop 0
	v_mul_f32_e32 v120, v120, v140
	v_mul_f32_e32 v121, v121, v140
	v_mul_f32_e32 v122, v122, v140
	v_mul_f32_e32 v123, v123, v140
	v_mul_f32_e32 v124, v124, v140
	v_mul_f32_e32 v125, v125, v140
	v_mul_f32_e32 v126, v126, v140
	v_mul_f32_e32 v127, v127, v140
	v_mul_f32_e32 v128, v128, v140
	v_mul_f32_e32 v129, v129, v140
	v_mul_f32_e32 v130, v130, v140
	v_mul_f32_e32 v131, v131, v140
	v_mul_f32_e32 v132, v132, v140
	v_mul_f32_e32 v133, v133, v140
	v_mul_f32_e32 v134, v134, v140
	v_mul_f32_e32 v135, v135, v140
	v_fma_f32 v0, v120, v72, v0
	v_fma_f32 v1, v121, v73, v1
	v_fma_f32 v2, v122, v74, v2
	v_fma_f32 v3, v123, v75, v3
	v_fma_f32 v4, v124, v76, v4
	v_fma_f32 v5, v125, v77, v5
	v_fma_f32 v6, v126, v78, v6
	v_fma_f32 v7, v127, v79, v7
	v_fma_f32 v8, v128, v80, v8
	v_fma_f32 v9, v129, v81, v9
	v_fma_f32 v10, v130, v82, v10
	v_fma_f32 v11, v131, v83, v11
	v_fma_f32 v12, v132, v84, v12
	v_fma_f32 v13, v133, v85, v13
	v_fma_f32 v14, v134, v86, v14
	v_fma_f32 v15, v135, v87, v15
	s_lshl_b32 vcc_lo, s19, 12
	s_add_u32 vcc_lo, vcc_lo, 0x4800000
	s_add_u32 s100, s16, vcc_lo
	s_addc_u32 s101, s17, 0
	global_store_dwordx4 v136, v[0:3], s[100:101] offset:0
	global_store_dwordx4 v136, v[4:7], s[100:101] offset:1024
	global_store_dwordx4 v136, v[8:11], s[100:101] offset:2048
	global_store_dwordx4 v136, v[12:15], s[100:101] offset:3072
	s_lshl_b32 vcc_lo, s19, 11
	s_add_u32 vcc_lo, vcc_lo, 0x3000000
	s_add_u32 s100, s12, vcc_lo
	s_addc_u32 s101, s13, 0
	global_load_dwordx2 v[8:9], v137, s[100:101] offset:0
	global_load_dwordx2 v[10:11], v137, s[100:101] offset:512
	global_load_dwordx2 v[12:13], v137, s[100:101] offset:1024
	global_load_dwordx2 v[14:15], v137, s[100:101] offset:1536
	s_lshl_b32 vcc_lo, s19, 11
	s_add_u32 vcc_lo, vcc_lo, 0x3000000
	s_add_u32 s100, s14, vcc_lo
	s_addc_u32 s101, s15, 0
	global_load_dwordx2 v[48:49], v137, s[100:101] offset:0
	global_load_dwordx2 v[50:51], v137, s[100:101] offset:512
	global_load_dwordx2 v[52:53], v137, s[100:101] offset:1024
	global_load_dwordx2 v[54:55], v137, s[100:101] offset:1536
	s_waitcnt vmcnt(24)
; __device__ __forceinline__ float bf2f(u16 h) { return __uint_as_float(((unsigned)h) << 16); }
; __device__ __forceinline__ void row_phase(const Params& P, int glayer, int layer, int xsrc, bool hasY, int gate_idx, const float* gpost,
;                           int xdst, bool doH, const float* gpre, int sh_idx, int nrows) {
;     ...
;         if (xsrc != 0 && row < N_X) {
; #pragma unroll
;           for (int i = 0; i < 4; ++i) {
;             const uint4 raw = xr[u][i];
;             xv[i].x = bf2f((u16)(raw.x & 0xffff)); xv[i].y = bf2f((u16)(raw.x >> 16));
;             xv[i].z = bf2f((u16)(raw.y & 0xffff)); xv[i].w = bf2f((u16)(raw.y >> 16));
;           }
;         } else {
; #pragma unroll
;           for (int i = 0; i < 4; ++i) {
;             xv[i].x = __uint_as_float(xr[u][i].x); xv[i].y = __uint_as_float(xr[u][i].y);
;             xv[i].z = __uint_as_float(xr[u][i].z); xv[i].w = __uint_as_float(xr[u][i].w);
;           }
;         }
;         if (hasY) {
;           float4 yv[4];
;           float ss = 0.f;
; #pragma unroll
;           for (int i = 0; i < 4; ++i) {
;             const uint2 raw = yy[u][i];
;             yv[i].x = bf2f((u16)(raw.x & 0xffff)); yv[i].y = bf2f((u16)(raw.x >> 16));
;             yv[i].z = bf2f((u16)(raw.y & 0xffff)); yv[i].w = bf2f((u16)(raw.y >> 16));
;             ss += yv[i].x * yv[i].x + yv[i].y * yv[i].y + yv[i].z * yv[i].z + yv[i].w * yv[i].w;
;           }
;           ss = wave_sum(ss);
;           const float rstd = __builtin_amdgcn_rsqf(ss * (1.f / 1024.f) + EPSF);
; #pragma unroll
;           for (int i = 0; i < 4; ++i) {
;             const int col = (i * 64 + lane) * 4;
;             const float4 gt = *reinterpret_cast<const float4*>(modg + gate_idx * 1024 + col);
;             const float4 gp = *reinterpret_cast<const float4*>(gpost + col);
;             xv[i].x += gt.x * (yv[i].x * rstd * gp.x); xv[i].y += gt.y * (yv[i].y * rstd * gp.y);
;             xv[i].z += gt.z * (yv[i].z * rstd * gp.z); xv[i].w += gt.w * (yv[i].w * rstd * gp.w);
;           }
;         }
;         if (xdst == 3 || (xdst == 1 && row >= N_X)) {
;           float* xout = (xdst == 3) ? P.out + (long)row * 1024 : P.xc + (long)(row - N_X) * 1024;
; #pragma unroll
;           for (int i = 0; i < 4; ++i) *reinterpret_cast<float4*>(xout + (i * 64 + lane) * 4) = xv[i];
	v_lshlrev_b32_e32 v120, 16, v56
	v_and_b32_e32 v121, 0xffff0000, v56
	v_lshlrev_b32_e32 v122, 16, v57
	v_and_b32_e32 v123, 0xffff0000, v57
	v_lshlrev_b32_e32 v124, 16, v58
	v_and_b32_e32 v125, 0xffff0000, v58
	v_lshlrev_b32_e32 v126, 16, v59
	v_and_b32_e32 v127, 0xffff0000, v59
	v_lshlrev_b32_e32 v128, 16, v60
	v_and_b32_e32 v129, 0xffff0000, v60
	v_lshlrev_b32_e32 v130, 16, v61
	v_and_b32_e32 v131, 0xffff0000, v61
	v_lshlrev_b32_e32 v132, 16, v62
	v_and_b32_e32 v133, 0xffff0000, v62
	v_lshlrev_b32_e32 v134, 16, v63
	v_and_b32_e32 v135, 0xffff0000, v63
	v_mul_f32_e32 v138, v120, v120
	v_mul_f32_e32 v149, v121, v121
	v_mul_f32_e32 v150, v122, v122
	v_mul_f32_e32 v154, v123, v123
	v_fma_f32 v138, v124, v124, v138
	v_fma_f32 v149, v125, v125, v149
	v_fma_f32 v150, v126, v126, v150
	v_fma_f32 v154, v127, v127, v154
	v_fma_f32 v138, v128, v128, v138
	v_fma_f32 v149, v129, v129, v149
	v_fma_f32 v150, v130, v130, v150
	v_fma_f32 v154, v131, v131, v154
	v_fma_f32 v138, v132, v132, v138
	v_fma_f32 v149, v133, v133, v149
	v_fma_f32 v150, v134, v134, v150
	v_fma_f32 v154, v135, v135, v154
	v_add_f32_e32 v138, v138, v149
	v_add_f32_e32 v150, v150, v154
	v_add_f32_e32 v138, v138, v150
	s_nop 1
	v_add_f32_dpp v138, v138, v138 quad_perm:[1,0,3,2] row_mask:0xf bank_mask:0xf
	s_nop 1
	v_add_f32_dpp v138, v138, v138 quad_perm:[2,3,0,1] row_mask:0xf bank_mask:0xf
	s_nop 1
	v_add_f32_dpp v138, v138, v138 row_half_mirror row_mask:0xf bank_mask:0xf
	s_nop 1
	v_add_f32_dpp v138, v138, v138 row_mirror row_mask:0xf bank_mask:0xf
	v_mov_b32_e32 v139, v138
	s_nop 1
	v_permlane16_swap_b32_e32 v138, v139
	v_add_f32_e32 v138, v138, v139
	v_mov_b32_e32 v139, v138
	s_nop 1
	v_permlane32_swap_b32_e32 v138, v139
	v_add_f32_e32 v138, v138, v139
	v_mul_f32_e32 v138, 0x3a800000, v138
	v_add_f32_e32 v138, 0x358637bd, v138
	v_rsq_f32_e32 v140, v138
	v_lshlrev_b32_e32 v16, 16, v24
	v_and_b32_e32 v17, 0xffff0000, v24
	v_lshlrev_b32_e32 v18, 16, v25
	v_and_b32_e32 v19, 0xffff0000, v25
	v_lshlrev_b32_e32 v20, 16, v26
	v_and_b32_e32 v21, 0xffff0000, v26
	v_lshlrev_b32_e32 v22, 16, v27
	v_and_b32_e32 v23, 0xffff0000, v27
	v_lshlrev_b32_e32 v24, 16, v28
	v_and_b32_e32 v25, 0xffff0000, v28
	v_lshlrev_b32_e32 v26, 16, v29
	v_and_b32_e32 v27, 0xffff0000, v29
	v_lshlrev_b32_e32 v28, 16, v30
	v_and_b32_e32 v29, 0xffff0000, v30
	v_lshlrev_b32_e32 v30, 16, v31
	v_and_b32_e32 v31, 0xffff0000, v31
	s_nop 0
	v_mul_f32_e32 v120, v120, v140
	v_mul_f32_e32 v121, v121, v140
	v_mul_f32_e32 v122, v122, v140
	v_mul_f32_e32 v123, v123, v140
	v_mul_f32_e32 v124, v124, v140
	v_mul_f32_e32 v125, v125, v140
	v_mul_f32_e32 v126, v126, v140
	v_mul_f32_e32 v127, v127, v140
	v_mul_f32_e32 v128, v128, v140
	v_mul_f32_e32 v129, v129, v140
	v_mul_f32_e32 v130, v130, v140
	v_mul_f32_e32 v131, v131, v140
	v_mul_f32_e32 v132, v132, v140
	v_mul_f32_e32 v133, v133, v140
	v_mul_f32_e32 v134, v134, v140
	v_mul_f32_e32 v135, v135, v140
	v_fma_f32 v16, v120, v72, v16
	v_fma_f32 v17, v121, v73, v17
	v_fma_f32 v18, v122, v74, v18
	v_fma_f32 v19, v123, v75, v19
	v_fma_f32 v20, v124, v76, v20
	v_fma_f32 v21, v125, v77, v21
	v_fma_f32 v22, v126, v78, v22
	v_fma_f32 v23, v127, v79, v23
	v_fma_f32 v24, v128, v80, v24
	v_fma_f32 v25, v129, v81, v25
	v_fma_f32 v26, v130, v82, v26
	v_fma_f32 v27, v131, v83, v27
	v_fma_f32 v28, v132, v84, v28
	v_fma_f32 v29, v133, v85, v29
	v_fma_f32 v30, v134, v86, v30
	v_fma_f32 v31, v135, v87, v31
	s_lshl_b32 vcc_lo, s19, 12
	s_add_u32 vcc_lo, vcc_lo, 0x5000000
	s_add_u32 s100, s16, vcc_lo
	s_addc_u32 s101, s17, 0
	global_store_dwordx4 v136, v[16:19], s[100:101] offset:0
	global_store_dwordx4 v136, v[20:23], s[100:101] offset:1024
	global_store_dwordx4 v136, v[24:27], s[100:101] offset:2048
	global_store_dwordx4 v136, v[28:31], s[100:101] offset:3072
	s_lshl_b32 vcc_lo, s19, 11
	s_add_u32 vcc_lo, vcc_lo, 0x3400000
	s_add_u32 s100, s12, vcc_lo
	s_addc_u32 s101, s13, 0
	global_load_dwordx2 v[24:25], v137, s[100:101] offset:0
	global_load_dwordx2 v[26:27], v137, s[100:101] offset:512
	global_load_dwordx2 v[28:29], v137, s[100:101] offset:1024
	global_load_dwordx2 v[30:31], v137, s[100:101] offset:1536
	s_lshl_b32 vcc_lo, s19, 11
	s_add_u32 vcc_lo, vcc_lo, 0x3400000
	s_add_u32 s100, s14, vcc_lo
	s_addc_u32 s101, s15, 0
	global_load_dwordx2 v[56:57], v137, s[100:101] offset:0
	global_load_dwordx2 v[58:59], v137, s[100:101] offset:512
	global_load_dwordx2 v[60:61], v137, s[100:101] offset:1024
	global_load_dwordx2 v[62:63], v137, s[100:101] offset:1536
	s_waitcnt vmcnt(24)
; __device__ __forceinline__ float bf2f(u16 h) { return __uint_as_float(((unsigned)h) << 16); }
; __device__ __forceinline__ void row_phase(const Params& P, int glayer, int layer, int xsrc, bool hasY, int gate_idx, const float* gpost,
;                           int xdst, bool doH, const float* gpre, int sh_idx, int nrows) {
;     ...
;         if (hasY) {
;           float4 yv[4];
;           float ss = 0.f;
; #pragma unroll
;           for (int i = 0; i < 4; ++i) {
;             const uint2 raw = yy[u][i];
;             yv[i].x = bf2f((u16)(raw.x & 0xffff)); yv[i].y = bf2f((u16)(raw.x >> 16));
;             yv[i].z = bf2f((u16)(raw.y & 0xffff)); yv[i].w = bf2f((u16)(raw.y >> 16));
;             ss += yv[i].x * yv[i].x + yv[i].y * yv[i].y + yv[i].z * yv[i].z + yv[i].w * yv[i].w;
;           }
;           ss = wave_sum(ss);
;           const float rstd = __builtin_amdgcn_rsqf(ss * (1.f / 1024.f) + EPSF);
; #pragma unroll
;           for (int i = 0; i < 4; ++i) {
;             const int col = (i * 64 + lane) * 4;
;             const float4 gt = *reinterpret_cast<const float4*>(modg + gate_idx * 1024 + col);
;             const float4 gp = *reinterpret_cast<const float4*>(gpost + col);
;             xv[i].x += gt.x * (yv[i].x * rstd * gp.x); xv[i].y += gt.y * (yv[i].y * rstd * gp.y);
;             xv[i].z += gt.z * (yv[i].z * rstd * gp.z); xv[i].w += gt.w * (yv[i].w * rstd * gp.w);
;           }
;         }
;         if (xdst == 3 || (xdst == 1 && row >= N_X)) {
;           float* xout = (xdst == 3) ? P.out + (long)row * 1024 : P.xc + (long)(row - N_X) * 1024;
; #pragma unroll
;           for (int i = 0; i < 4; ++i) *reinterpret_cast<float4*>(xout + (i * 64 + lane) * 4) = xv[i];
	v_lshlrev_b32_e32 v120, 16, v64
	v_and_b32_e32 v121, 0xffff0000, v64
	v_lshlrev_b32_e32 v122, 16, v65
	v_and_b32_e32 v123, 0xffff0000, v65
	v_lshlrev_b32_e32 v124, 16, v66
	v_and_b32_e32 v125, 0xffff0000, v66
	v_lshlrev_b32_e32 v126, 16, v67
	v_and_b32_e32 v127, 0xffff0000, v67
	v_lshlrev_b32_e32 v128, 16, v68
	v_and_b32_e32 v129, 0xffff0000, v68
	v_lshlrev_b32_e32 v130, 16, v69
	v_and_b32_e32 v131, 0xffff0000, v69
	v_lshlrev_b32_e32 v132, 16, v70
	v_and_b32_e32 v133, 0xffff0000, v70
	v_lshlrev_b32_e32 v134, 16, v71
	v_and_b32_e32 v135, 0xffff0000, v71
	v_mul_f32_e32 v138, v120, v120
	v_mul_f32_e32 v149, v121, v121
	v_mul_f32_e32 v150, v122, v122
	v_mul_f32_e32 v154, v123, v123
	v_fma_f32 v138, v124, v124, v138
	v_fma_f32 v149, v125, v125, v149
	v_fma_f32 v150, v126, v126, v150
	v_fma_f32 v154, v127, v127, v154
	v_fma_f32 v138, v128, v128, v138
	v_fma_f32 v149, v129, v129, v149
	v_fma_f32 v150, v130, v130, v150
	v_fma_f32 v154, v131, v131, v154
	v_fma_f32 v138, v132, v132, v138
	v_fma_f32 v149, v133, v133, v149
	v_fma_f32 v150, v134, v134, v150
	v_fma_f32 v154, v135, v135, v154
	v_add_f32_e32 v138, v138, v149
	v_add_f32_e32 v150, v150, v154
	v_add_f32_e32 v138, v138, v150
	s_nop 1
	v_add_f32_dpp v138, v138, v138 quad_perm:[1,0,3,2] row_mask:0xf bank_mask:0xf
	s_nop 1
	v_add_f32_dpp v138, v138, v138 quad_perm:[2,3,0,1] row_mask:0xf bank_mask:0xf
	s_nop 1
	v_add_f32_dpp v138, v138, v138 row_half_mirror row_mask:0xf bank_mask:0xf
	s_nop 1
	v_add_f32_dpp v138, v138, v138 row_mirror row_mask:0xf bank_mask:0xf
	v_mov_b32_e32 v139, v138
	s_nop 1
	v_permlane16_swap_b32_e32 v138, v139
	v_add_f32_e32 v138, v138, v139
	v_mov_b32_e32 v139, v138
	s_nop 1
	v_permlane32_swap_b32_e32 v138, v139
	v_add_f32_e32 v138, v138, v139
	v_mul_f32_e32 v138, 0x3a800000, v138
	v_add_f32_e32 v138, 0x358637bd, v138
	v_rsq_f32_e32 v140, v138
	v_lshlrev_b32_e32 v32, 16, v40
	v_and_b32_e32 v33, 0xffff0000, v40
	v_lshlrev_b32_e32 v34, 16, v41
	v_and_b32_e32 v35, 0xffff0000, v41
	v_lshlrev_b32_e32 v36, 16, v42
	v_and_b32_e32 v37, 0xffff0000, v42
	v_lshlrev_b32_e32 v38, 16, v43
	v_and_b32_e32 v39, 0xffff0000, v43
	v_lshlrev_b32_e32 v40, 16, v44
	v_and_b32_e32 v41, 0xffff0000, v44
	v_lshlrev_b32_e32 v42, 16, v45
	v_and_b32_e32 v43, 0xffff0000, v45
	v_lshlrev_b32_e32 v44, 16, v46
	v_and_b32_e32 v45, 0xffff0000, v46
	v_lshlrev_b32_e32 v46, 16, v47
	v_and_b32_e32 v47, 0xffff0000, v47
	s_nop 0
	v_mul_f32_e32 v120, v120, v140
	v_mul_f32_e32 v121, v121, v140
	v_mul_f32_e32 v122, v122, v140
	v_mul_f32_e32 v123, v123, v140
	v_mul_f32_e32 v124, v124, v140
	v_mul_f32_e32 v125, v125, v140
	v_mul_f32_e32 v126, v126, v140
	v_mul_f32_e32 v127, v127, v140
	v_mul_f32_e32 v128, v128, v140
	v_mul_f32_e32 v129, v129, v140
	v_mul_f32_e32 v130, v130, v140
	v_mul_f32_e32 v131, v131, v140
	v_mul_f32_e32 v132, v132, v140
	v_mul_f32_e32 v133, v133, v140
	v_mul_f32_e32 v134, v134, v140
	v_mul_f32_e32 v135, v135, v140
	v_fma_f32 v32, v120, v72, v32
	v_fma_f32 v33, v121, v73, v33
	v_fma_f32 v34, v122, v74, v34
	v_fma_f32 v35, v123, v75, v35
	v_fma_f32 v36, v124, v76, v36
	v_fma_f32 v37, v125, v77, v37
	v_fma_f32 v38, v126, v78, v38
	v_fma_f32 v39, v127, v79, v39
	v_fma_f32 v40, v128, v80, v40
	v_fma_f32 v41, v129, v81, v41
	v_fma_f32 v42, v130, v82, v42
	v_fma_f32 v43, v131, v83, v43
	v_fma_f32 v44, v132, v84, v44
	v_fma_f32 v45, v133, v85, v45
	v_fma_f32 v46, v134, v86, v46
	v_fma_f32 v47, v135, v87, v47
	s_lshl_b32 vcc_lo, s19, 12
	s_add_u32 vcc_lo, vcc_lo, 0x5800000
	s_add_u32 s100, s16, vcc_lo
	s_addc_u32 s101, s17, 0
	global_store_dwordx4 v136, v[32:35], s[100:101] offset:0
	global_store_dwordx4 v136, v[36:39], s[100:101] offset:1024
	global_store_dwordx4 v136, v[40:43], s[100:101] offset:2048
	global_store_dwordx4 v136, v[44:47], s[100:101] offset:3072
	s_add_u32 s100, s20, 0x35000
	s_addc_u32 s101, s21, 0
	global_load_dwordx4 v[72:75], v136, s[100:101] offset:0
	global_load_dwordx4 v[76:79], v136, s[100:101] offset:1024
	global_load_dwordx4 v[80:83], v136, s[100:101] offset:2048
	global_load_dwordx4 v[84:87], v136, s[100:101] offset:3072
	s_load_dwordx2 s[98:99], s[4:5], 0x48
	s_waitcnt lgkmcnt(0)
	s_add_u32 s98, s98, 0x1000
	s_addc_u32 s99, s99, 0
	global_load_dwordx4 v[120:123], v136, s[98:99] offset:0
	global_load_dwordx4 v[124:127], v136, s[98:99] offset:1024
	global_load_dwordx4 v[128:131], v136, s[98:99] offset:2048
	global_load_dwordx4 v[132:135], v136, s[98:99] offset:3072
	s_waitcnt vmcnt(0)
; __device__ __forceinline__ float bf2f(u16 h) { return __uint_as_float(((unsigned)h) << 16); }
; __device__ __forceinline__ void row_phase(const Params& P, int glayer, int layer, int xsrc, bool hasY, int gate_idx, const float* gpost,
;                           int xdst, bool doH, const float* gpre, int sh_idx, int nrows) {
;     ...
;         if (hasY) {
;           const u16* y_ = P.hy + (long)R * 1024;
; #pragma unroll
;           for (int i = 0; i < 4; ++i) yy[u][i] = *reinterpret_cast<const uint2*>(y_ + (i * 64 + lane) * 4);
;         }
;     ...
;         if (hasY) {
;           float4 yv[4];
;           float ss = 0.f;
; #pragma unroll
;           for (int i = 0; i < 4; ++i) {
;             const uint2 raw = yy[u][i];
;             yv[i].x = bf2f((u16)(raw.x & 0xffff)); yv[i].y = bf2f((u16)(raw.x >> 16));
;             yv[i].z = bf2f((u16)(raw.y & 0xffff)); yv[i].w = bf2f((u16)(raw.y >> 16));
;             ss += yv[i].x * yv[i].x + yv[i].y * yv[i].y + yv[i].z * yv[i].z + yv[i].w * yv[i].w;
;           }
;           ss = wave_sum(ss);
;           const float rstd = __builtin_amdgcn_rsqf(ss * (1.f / 1024.f) + EPSF);
; #pragma unroll
;           for (int i = 0; i < 4; ++i) {
;             const int col = (i * 64 + lane) * 4;
;             const float4 gt = *reinterpret_cast<const float4*>(modg + gate_idx * 1024 + col);
;             const float4 gp = *reinterpret_cast<const float4*>(gpost + col);
;             xv[i].x += gt.x * (yv[i].x * rstd * gp.x); xv[i].y += gt.y * (yv[i].y * rstd * gp.y);
;             xv[i].z += gt.z * (yv[i].z * rstd * gp.z); xv[i].w += gt.w * (yv[i].w * rstd * gp.w);
;           }
;         }
;         if (xdst == 3 || (xdst == 1 && row >= N_X)) {
;           float* xout = (xdst == 3) ? P.out + (long)row * 1024 : P.xc + (long)(row - N_X) * 1024;
; #pragma unroll
;           for (int i = 0; i < 4; ++i) *reinterpret_cast<float4*>(xout + (i * 64 + lane) * 4) = xv[i];
	v_mul_f32_e32 v72, v72, v120
	v_mul_f32_e32 v73, v73, v121
	v_mul_f32_e32 v74, v74, v122
	v_mul_f32_e32 v75, v75, v123
	v_mul_f32_e32 v76, v76, v124
	v_mul_f32_e32 v77, v77, v125
	v_mul_f32_e32 v78, v78, v126
	v_mul_f32_e32 v79, v79, v127
	v_mul_f32_e32 v80, v80, v128
	v_mul_f32_e32 v81, v81, v129
	v_mul_f32_e32 v82, v82, v130
	v_mul_f32_e32 v83, v83, v131
	v_mul_f32_e32 v84, v84, v132
	v_mul_f32_e32 v85, v85, v133
	v_mul_f32_e32 v86, v86, v134
	v_mul_f32_e32 v87, v87, v135
	s_lshl_b32 vcc_lo, s19, 11
	s_add_u32 vcc_lo, vcc_lo, 0x3800000
	s_add_u32 s100, s12, vcc_lo
	s_addc_u32 s101, s13, 0
	global_load_dwordx2 v[40:41], v137, s[100:101] offset:0
	global_load_dwordx2 v[42:43], v137, s[100:101] offset:512
	global_load_dwordx2 v[44:45], v137, s[100:101] offset:1024
	global_load_dwordx2 v[46:47], v137, s[100:101] offset:1536
	s_lshl_b32 vcc_lo, s19, 11
	s_add_u32 vcc_lo, vcc_lo, 0x3800000
	s_add_u32 s100, s14, vcc_lo
	s_addc_u32 s101, s15, 0
	global_load_dwordx2 v[64:65], v137, s[100:101] offset:0
	global_load_dwordx2 v[66:67], v137, s[100:101] offset:512
	global_load_dwordx2 v[68:69], v137, s[100:101] offset:1024
	global_load_dwordx2 v[70:71], v137, s[100:101] offset:1536
	v_lshlrev_b32_e32 v120, 16, v48
	v_and_b32_e32 v121, 0xffff0000, v48
	v_lshlrev_b32_e32 v122, 16, v49
	v_and_b32_e32 v123, 0xffff0000, v49
	v_lshlrev_b32_e32 v124, 16, v50
	v_and_b32_e32 v125, 0xffff0000, v50
	v_lshlrev_b32_e32 v126, 16, v51
	v_and_b32_e32 v127, 0xffff0000, v51
	v_lshlrev_b32_e32 v128, 16, v52
	v_and_b32_e32 v129, 0xffff0000, v52
	v_lshlrev_b32_e32 v130, 16, v53
	v_and_b32_e32 v131, 0xffff0000, v53
	v_lshlrev_b32_e32 v132, 16, v54
	v_and_b32_e32 v133, 0xffff0000, v54
	v_lshlrev_b32_e32 v134, 16, v55
	v_and_b32_e32 v135, 0xffff0000, v55
	v_mul_f32_e32 v138, v120, v120
	v_mul_f32_e32 v149, v121, v121
	v_mul_f32_e32 v150, v122, v122
	v_mul_f32_e32 v154, v123, v123
	v_fma_f32 v138, v124, v124, v138
	v_fma_f32 v149, v125, v125, v149
	v_fma_f32 v150, v126, v126, v150
	v_fma_f32 v154, v127, v127, v154
	v_fma_f32 v138, v128, v128, v138
	v_fma_f32 v149, v129, v129, v149
	v_fma_f32 v150, v130, v130, v150
	v_fma_f32 v154, v131, v131, v154
	v_fma_f32 v138, v132, v132, v138
	v_fma_f32 v149, v133, v133, v149
	v_fma_f32 v150, v134, v134, v150
	v_fma_f32 v154, v135, v135, v154
	v_add_f32_e32 v138, v138, v149
	v_add_f32_e32 v150, v150, v154
	v_add_f32_e32 v138, v138, v150
	s_nop 1
	v_add_f32_dpp v138, v138, v138 quad_perm:[1,0,3,2] row_mask:0xf bank_mask:0xf
	s_nop 1
	v_add_f32_dpp v138, v138, v138 quad_perm:[2,3,0,1] row_mask:0xf bank_mask:0xf
	s_nop 1
	v_add_f32_dpp v138, v138, v138 row_half_mirror row_mask:0xf bank_mask:0xf
	s_nop 1
	v_add_f32_dpp v138, v138, v138 row_mirror row_mask:0xf bank_mask:0xf
	v_mov_b32_e32 v139, v138
	s_nop 1
	v_permlane16_swap_b32_e32 v138, v139
	v_add_f32_e32 v138, v138, v139
	v_mov_b32_e32 v139, v138
	s_nop 1
	v_permlane32_swap_b32_e32 v138, v139
	v_add_f32_e32 v138, v138, v139
	v_mul_f32_e32 v138, 0x3a800000, v138
	v_add_f32_e32 v138, 0x358637bd, v138
	v_rsq_f32_e32 v140, v138
	v_lshlrev_b32_e32 v0, 16, v8
	v_and_b32_e32 v1, 0xffff0000, v8
	v_lshlrev_b32_e32 v2, 16, v9
	v_and_b32_e32 v3, 0xffff0000, v9
	v_lshlrev_b32_e32 v4, 16, v10
	v_and_b32_e32 v5, 0xffff0000, v10
	v_lshlrev_b32_e32 v6, 16, v11
	v_and_b32_e32 v7, 0xffff0000, v11
	v_lshlrev_b32_e32 v8, 16, v12
	v_and_b32_e32 v9, 0xffff0000, v12
	v_lshlrev_b32_e32 v10, 16, v13
	v_and_b32_e32 v11, 0xffff0000, v13
	v_lshlrev_b32_e32 v12, 16, v14
	v_and_b32_e32 v13, 0xffff0000, v14
	v_lshlrev_b32_e32 v14, 16, v15
	v_and_b32_e32 v15, 0xffff0000, v15
	s_nop 0
	v_mul_f32_e32 v120, v120, v140
	v_mul_f32_e32 v121, v121, v140
	v_mul_f32_e32 v122, v122, v140
	v_mul_f32_e32 v123, v123, v140
	v_mul_f32_e32 v124, v124, v140
	v_mul_f32_e32 v125, v125, v140
	v_mul_f32_e32 v126, v126, v140
	v_mul_f32_e32 v127, v127, v140
	v_mul_f32_e32 v128, v128, v140
	v_mul_f32_e32 v129, v129, v140
	v_mul_f32_e32 v130, v130, v140
	v_mul_f32_e32 v131, v131, v140
	v_mul_f32_e32 v132, v132, v140
	v_mul_f32_e32 v133, v133, v140
	v_mul_f32_e32 v134, v134, v140
	v_mul_f32_e32 v135, v135, v140
	v_fma_f32 v0, v120, v72, v0
	v_fma_f32 v1, v121, v73, v1
	v_fma_f32 v2, v122, v74, v2
	v_fma_f32 v3, v123, v75, v3
	v_fma_f32 v4, v124, v76, v4
	v_fma_f32 v5, v125, v77, v5
	v_fma_f32 v6, v126, v78, v6
	v_fma_f32 v7, v127, v79, v7
	v_fma_f32 v8, v128, v80, v8
	v_fma_f32 v9, v129, v81, v9
	v_fma_f32 v10, v130, v82, v10
	v_fma_f32 v11, v131, v83, v11
	v_fma_f32 v12, v132, v84, v12
	v_fma_f32 v13, v133, v85, v13
	v_fma_f32 v14, v134, v86, v14
	v_fma_f32 v15, v135, v87, v15
	s_lshl_b32 vcc_lo, s19, 12
	s_add_u32 vcc_lo, vcc_lo, 0x6000000
	s_add_u32 s100, s16, vcc_lo
	s_addc_u32 s101, s17, 0
	global_store_dwordx4 v136, v[0:3], s[100:101] offset:0
	global_store_dwordx4 v136, v[4:7], s[100:101] offset:1024
	global_store_dwordx4 v136, v[8:11], s[100:101] offset:2048
	global_store_dwordx4 v136, v[12:15], s[100:101] offset:3072
	s_lshl_b32 vcc_lo, s19, 11
	s_add_u32 vcc_lo, vcc_lo, 0x3c00000
	s_add_u32 s100, s12, vcc_lo
	s_addc_u32 s101, s13, 0
	global_load_dwordx2 v[8:9], v137, s[100:101] offset:0
	global_load_dwordx2 v[10:11], v137, s[100:101] offset:512
	global_load_dwordx2 v[12:13], v137, s[100:101] offset:1024
	global_load_dwordx2 v[14:15], v137, s[100:101] offset:1536
	s_lshl_b32 vcc_lo, s19, 11
	s_add_u32 vcc_lo, vcc_lo, 0x3c00000
	s_add_u32 s100, s14, vcc_lo
	s_addc_u32 s101, s15, 0
	global_load_dwordx2 v[48:49], v137, s[100:101] offset:0
	global_load_dwordx2 v[50:51], v137, s[100:101] offset:512
	global_load_dwordx2 v[52:53], v137, s[100:101] offset:1024
	global_load_dwordx2 v[54:55], v137, s[100:101] offset:1536
	v_lshlrev_b32_e32 v120, 16, v56
; __device__ __forceinline__ float bf2f(u16 h) { return __uint_as_float(((unsigned)h) << 16); }
; __device__ __forceinline__ void row_phase(const Params& P, int glayer, int layer, int xsrc, bool hasY, int gate_idx, const float* gpost,
;                           int xdst, bool doH, const float* gpre, int sh_idx, int nrows) {
;     ...
;         if (hasY) {
;           float4 yv[4];
;           float ss = 0.f;
; #pragma unroll
;           for (int i = 0; i < 4; ++i) {
;             const uint2 raw = yy[u][i];
;             yv[i].x = bf2f((u16)(raw.x & 0xffff)); yv[i].y = bf2f((u16)(raw.x >> 16));
;             yv[i].z = bf2f((u16)(raw.y & 0xffff)); yv[i].w = bf2f((u16)(raw.y >> 16));
;             ss += yv[i].x * yv[i].x + yv[i].y * yv[i].y + yv[i].z * yv[i].z + yv[i].w * yv[i].w;
;           }
;           ss = wave_sum(ss);
;           const float rstd = __builtin_amdgcn_rsqf(ss * (1.f / 1024.f) + EPSF);
; #pragma unroll
;           for (int i = 0; i < 4; ++i) {
;             const int col = (i * 64 + lane) * 4;
;             const float4 gt = *reinterpret_cast<const float4*>(modg + gate_idx * 1024 + col);
;             const float4 gp = *reinterpret_cast<const float4*>(gpost + col);
;             xv[i].x += gt.x * (yv[i].x * rstd * gp.x); xv[i].y += gt.y * (yv[i].y * rstd * gp.y);
;             xv[i].z += gt.z * (yv[i].z * rstd * gp.z); xv[i].w += gt.w * (yv[i].w * rstd * gp.w);
;           }
;         }
;         if (xdst == 3 || (xdst == 1 && row >= N_X)) {
;           float* xout = (xdst == 3) ? P.out + (long)row * 1024 : P.xc + (long)(row - N_X) * 1024;
; #pragma unroll
;           for (int i = 0; i < 4; ++i) *reinterpret_cast<float4*>(xout + (i * 64 + lane) * 4) = xv[i];
	v_and_b32_e32 v121, 0xffff0000, v56
	v_lshlrev_b32_e32 v122, 16, v57
	v_and_b32_e32 v123, 0xffff0000, v57
	v_lshlrev_b32_e32 v124, 16, v58
	v_and_b32_e32 v125, 0xffff0000, v58
	v_lshlrev_b32_e32 v126, 16, v59
	v_and_b32_e32 v127, 0xffff0000, v59
	v_lshlrev_b32_e32 v128, 16, v60
	v_and_b32_e32 v129, 0xffff0000, v60
	v_lshlrev_b32_e32 v130, 16, v61
	v_and_b32_e32 v131, 0xffff0000, v61
	v_lshlrev_b32_e32 v132, 16, v62
	v_and_b32_e32 v133, 0xffff0000, v62
	v_lshlrev_b32_e32 v134, 16, v63
	v_and_b32_e32 v135, 0xffff0000, v63
	v_mul_f32_e32 v138, v120, v120
	v_mul_f32_e32 v149, v121, v121
	v_mul_f32_e32 v150, v122, v122
	v_mul_f32_e32 v154, v123, v123
	v_fma_f32 v138, v124, v124, v138
	v_fma_f32 v149, v125, v125, v149
	v_fma_f32 v150, v126, v126, v150
	v_fma_f32 v154, v127, v127, v154
	v_fma_f32 v138, v128, v128, v138
	v_fma_f32 v149, v129, v129, v149
	v_fma_f32 v150, v130, v130, v150
	v_fma_f32 v154, v131, v131, v154
	v_fma_f32 v138, v132, v132, v138
	v_fma_f32 v149, v133, v133, v149
	v_fma_f32 v150, v134, v134, v150
	v_fma_f32 v154, v135, v135, v154
	v_add_f32_e32 v138, v138, v149
	v_add_f32_e32 v150, v150, v154
	v_add_f32_e32 v138, v138, v150
	s_nop 1
	v_add_f32_dpp v138, v138, v138 quad_perm:[1,0,3,2] row_mask:0xf bank_mask:0xf
	s_nop 1
	v_add_f32_dpp v138, v138, v138 quad_perm:[2,3,0,1] row_mask:0xf bank_mask:0xf
	s_nop 1
	v_add_f32_dpp v138, v138, v138 row_half_mirror row_mask:0xf bank_mask:0xf
	s_nop 1
	v_add_f32_dpp v138, v138, v138 row_mirror row_mask:0xf bank_mask:0xf
	v_mov_b32_e32 v139, v138
	s_nop 1
	v_permlane16_swap_b32_e32 v138, v139
	v_add_f32_e32 v138, v138, v139
	v_mov_b32_e32 v139, v138
	s_nop 1
	v_permlane32_swap_b32_e32 v138, v139
	v_add_f32_e32 v138, v138, v139
	v_mul_f32_e32 v138, 0x3a800000, v138
	v_add_f32_e32 v138, 0x358637bd, v138
	v_rsq_f32_e32 v140, v138
	v_lshlrev_b32_e32 v16, 16, v24
	v_and_b32_e32 v17, 0xffff0000, v24
	v_lshlrev_b32_e32 v18, 16, v25
	v_and_b32_e32 v19, 0xffff0000, v25
	v_lshlrev_b32_e32 v20, 16, v26
	v_and_b32_e32 v21, 0xffff0000, v26
	v_lshlrev_b32_e32 v22, 16, v27
	v_and_b32_e32 v23, 0xffff0000, v27
	v_lshlrev_b32_e32 v24, 16, v28
	v_and_b32_e32 v25, 0xffff0000, v28
	v_lshlrev_b32_e32 v26, 16, v29
	v_and_b32_e32 v27, 0xffff0000, v29
	v_lshlrev_b32_e32 v28, 16, v30
	v_and_b32_e32 v29, 0xffff0000, v30
	v_lshlrev_b32_e32 v30, 16, v31
	v_and_b32_e32 v31, 0xffff0000, v31
	s_nop 0
	v_mul_f32_e32 v120, v120, v140
	v_mul_f32_e32 v121, v121, v140
	v_mul_f32_e32 v122, v122, v140
	v_mul_f32_e32 v123, v123, v140
	v_mul_f32_e32 v124, v124, v140
	v_mul_f32_e32 v125, v125, v140
	v_mul_f32_e32 v126, v126, v140
	v_mul_f32_e32 v127, v127, v140
	v_mul_f32_e32 v128, v128, v140
	v_mul_f32_e32 v129, v129, v140
	v_mul_f32_e32 v130, v130, v140
	v_mul_f32_e32 v131, v131, v140
	v_mul_f32_e32 v132, v132, v140
	v_mul_f32_e32 v133, v133, v140
	v_mul_f32_e32 v134, v134, v140
	v_mul_f32_e32 v135, v135, v140
	v_fma_f32 v16, v120, v72, v16
	v_fma_f32 v17, v121, v73, v17
	v_fma_f32 v18, v122, v74, v18
	v_fma_f32 v19, v123, v75, v19
	v_fma_f32 v20, v124, v76, v20
	v_fma_f32 v21, v125, v77, v21
	v_fma_f32 v22, v126, v78, v22
	v_fma_f32 v23, v127, v79, v23
	v_fma_f32 v24, v128, v80, v24
	v_fma_f32 v25, v129, v81, v25
	v_fma_f32 v26, v130, v82, v26
	v_fma_f32 v27, v131, v83, v27
	v_fma_f32 v28, v132, v84, v28
	v_fma_f32 v29, v133, v85, v29
	v_fma_f32 v30, v134, v86, v30
	v_fma_f32 v31, v135, v87, v31
	s_lshl_b32 vcc_lo, s19, 12
	s_add_u32 vcc_lo, vcc_lo, 0x6800000
	s_add_u32 s100, s16, vcc_lo
	s_addc_u32 s101, s17, 0
	global_store_dwordx4 v136, v[16:19], s[100:101] offset:0
	global_store_dwordx4 v136, v[20:23], s[100:101] offset:1024
	global_store_dwordx4 v136, v[24:27], s[100:101] offset:2048
	global_store_dwordx4 v136, v[28:31], s[100:101] offset:3072
	s_waitcnt vmcnt(16)
	v_lshlrev_b32_e32 v120, 16, v64
	v_and_b32_e32 v121, 0xffff0000, v64
	v_lshlrev_b32_e32 v122, 16, v65
	v_and_b32_e32 v123, 0xffff0000, v65
	v_lshlrev_b32_e32 v124, 16, v66
	v_and_b32_e32 v125, 0xffff0000, v66
	v_lshlrev_b32_e32 v126, 16, v67
	v_and_b32_e32 v127, 0xffff0000, v67
	v_lshlrev_b32_e32 v128, 16, v68
	v_and_b32_e32 v129, 0xffff0000, v68
	v_lshlrev_b32_e32 v130, 16, v69
	v_and_b32_e32 v131, 0xffff0000, v69
	v_lshlrev_b32_e32 v132, 16, v70
	v_and_b32_e32 v133, 0xffff0000, v70
	v_lshlrev_b32_e32 v134, 16, v71
	v_and_b32_e32 v135, 0xffff0000, v71
	v_mul_f32_e32 v138, v120, v120
	v_mul_f32_e32 v149, v121, v121
	v_mul_f32_e32 v150, v122, v122
	v_mul_f32_e32 v154, v123, v123
	v_fma_f32 v138, v124, v124, v138
	v_fma_f32 v149, v125, v125, v149
	v_fma_f32 v150, v126, v126, v150
	v_fma_f32 v154, v127, v127, v154
	v_fma_f32 v138, v128, v128, v138
	v_fma_f32 v149, v129, v129, v149
	v_fma_f32 v150, v130, v130, v150
	v_fma_f32 v154, v131, v131, v154
	v_fma_f32 v138, v132, v132, v138
	v_fma_f32 v149, v133, v133, v149
	v_fma_f32 v150, v134, v134, v150
	v_fma_f32 v154, v135, v135, v154
	v_add_f32_e32 v138, v138, v149
	v_add_f32_e32 v150, v150, v154
	v_add_f32_e32 v138, v138, v150
	s_nop 1
	v_add_f32_dpp v138, v138, v138 quad_perm:[1,0,3,2] row_mask:0xf bank_mask:0xf
	s_nop 1
	v_add_f32_dpp v138, v138, v138 quad_perm:[2,3,0,1] row_mask:0xf bank_mask:0xf
	s_nop 1
	v_add_f32_dpp v138, v138, v138 row_half_mirror row_mask:0xf bank_mask:0xf
	s_nop 1
	v_add_f32_dpp v138, v138, v138 row_mirror row_mask:0xf bank_mask:0xf
	v_mov_b32_e32 v139, v138
	s_nop 1
	v_permlane16_swap_b32_e32 v138, v139
	v_add_f32_e32 v138, v138, v139
	v_mov_b32_e32 v139, v138
	s_nop 1
	v_permlane32_swap_b32_e32 v138, v139
	v_add_f32_e32 v138, v138, v139
	v_mul_f32_e32 v138, 0x3a800000, v138
	v_add_f32_e32 v138, 0x358637bd, v138
	v_rsq_f32_e32 v140, v138
	v_lshlrev_b32_e32 v32, 16, v40
; __device__ __forceinline__ float bf2f(u16 h) { return __uint_as_float(((unsigned)h) << 16); }
; __device__ __forceinline__ void row_phase(const Params& P, int glayer, int layer, int xsrc, bool hasY, int gate_idx, const float* gpost,
;                           int xdst, bool doH, const float* gpre, int sh_idx, int nrows) {
;     ...
;         if (hasY) {
;           float4 yv[4];
;           float ss = 0.f;
; #pragma unroll
;           for (int i = 0; i < 4; ++i) {
;             const uint2 raw = yy[u][i];
;             yv[i].x = bf2f((u16)(raw.x & 0xffff)); yv[i].y = bf2f((u16)(raw.x >> 16));
;             yv[i].z = bf2f((u16)(raw.y & 0xffff)); yv[i].w = bf2f((u16)(raw.y >> 16));
;             ss += yv[i].x * yv[i].x + yv[i].y * yv[i].y + yv[i].z * yv[i].z + yv[i].w * yv[i].w;
;           }
;           ss = wave_sum(ss);
;           const float rstd = __builtin_amdgcn_rsqf(ss * (1.f / 1024.f) + EPSF);
; #pragma unroll
;           for (int i = 0; i < 4; ++i) {
;             const int col = (i * 64 + lane) * 4;
;             const float4 gt = *reinterpret_cast<const float4*>(modg + gate_idx * 1024 + col);
;             const float4 gp = *reinterpret_cast<const float4*>(gpost + col);
;             xv[i].x += gt.x * (yv[i].x * rstd * gp.x); xv[i].y += gt.y * (yv[i].y * rstd * gp.y);
;             xv[i].z += gt.z * (yv[i].z * rstd * gp.z); xv[i].w += gt.w * (yv[i].w * rstd * gp.w);
;           }
;         }
;         if (xdst == 3 || (xdst == 1 && row >= N_X)) {
;           float* xout = (xdst == 3) ? P.out + (long)row * 1024 : P.xc + (long)(row - N_X) * 1024;
; #pragma unroll
;           for (int i = 0; i < 4; ++i) *reinterpret_cast<float4*>(xout + (i * 64 + lane) * 4) = xv[i];
	v_and_b32_e32 v33, 0xffff0000, v40
	v_lshlrev_b32_e32 v34, 16, v41
	v_and_b32_e32 v35, 0xffff0000, v41
	v_lshlrev_b32_e32 v36, 16, v42
	v_and_b32_e32 v37, 0xffff0000, v42
	v_lshlrev_b32_e32 v38, 16, v43
	v_and_b32_e32 v39, 0xffff0000, v43
	v_lshlrev_b32_e32 v40, 16, v44
	v_and_b32_e32 v41, 0xffff0000, v44
	v_lshlrev_b32_e32 v42, 16, v45
	v_and_b32_e32 v43, 0xffff0000, v45
	v_lshlrev_b32_e32 v44, 16, v46
	v_and_b32_e32 v45, 0xffff0000, v46
	v_lshlrev_b32_e32 v46, 16, v47
	v_and_b32_e32 v47, 0xffff0000, v47
	s_nop 0
	v_mul_f32_e32 v120, v120, v140
	v_mul_f32_e32 v121, v121, v140
	v_mul_f32_e32 v122, v122, v140
	v_mul_f32_e32 v123, v123, v140
	v_mul_f32_e32 v124, v124, v140
	v_mul_f32_e32 v125, v125, v140
	v_mul_f32_e32 v126, v126, v140
	v_mul_f32_e32 v127, v127, v140
	v_mul_f32_e32 v128, v128, v140
	v_mul_f32_e32 v129, v129, v140
	v_mul_f32_e32 v130, v130, v140
	v_mul_f32_e32 v131, v131, v140
	v_mul_f32_e32 v132, v132, v140
	v_mul_f32_e32 v133, v133, v140
	v_mul_f32_e32 v134, v134, v140
	v_mul_f32_e32 v135, v135, v140
	v_fma_f32 v32, v120, v72, v32
	v_fma_f32 v33, v121, v73, v33
	v_fma_f32 v34, v122, v74, v34
	v_fma_f32 v35, v123, v75, v35
	v_fma_f32 v36, v124, v76, v36
	v_fma_f32 v37, v125, v77, v37
	v_fma_f32 v38, v126, v78, v38
	v_fma_f32 v39, v127, v79, v39
	v_fma_f32 v40, v128, v80, v40
	v_fma_f32 v41, v129, v81, v41
	v_fma_f32 v42, v130, v82, v42
	v_fma_f32 v43, v131, v83, v43
	v_fma_f32 v44, v132, v84, v44
	v_fma_f32 v45, v133, v85, v45
	v_fma_f32 v46, v134, v86, v46
	v_fma_f32 v47, v135, v87, v47
	s_lshl_b32 vcc_lo, s19, 12
	s_add_u32 vcc_lo, vcc_lo, 0x7000000
	s_add_u32 s100, s16, vcc_lo
	s_addc_u32 s101, s17, 0
	global_store_dwordx4 v136, v[32:35], s[100:101] offset:0
	global_store_dwordx4 v136, v[36:39], s[100:101] offset:1024
	global_store_dwordx4 v136, v[40:43], s[100:101] offset:2048
	global_store_dwordx4 v136, v[44:47], s[100:101] offset:3072
	s_waitcnt vmcnt(8)
	v_lshlrev_b32_e32 v120, 16, v48
	v_and_b32_e32 v121, 0xffff0000, v48
	v_lshlrev_b32_e32 v122, 16, v49
	v_and_b32_e32 v123, 0xffff0000, v49
	v_lshlrev_b32_e32 v124, 16, v50
	v_and_b32_e32 v125, 0xffff0000, v50
	v_lshlrev_b32_e32 v126, 16, v51
	v_and_b32_e32 v127, 0xffff0000, v51
	v_lshlrev_b32_e32 v128, 16, v52
	v_and_b32_e32 v129, 0xffff0000, v52
	v_lshlrev_b32_e32 v130, 16, v53
	v_and_b32_e32 v131, 0xffff0000, v53
	v_lshlrev_b32_e32 v132, 16, v54
	v_and_b32_e32 v133, 0xffff0000, v54
	v_lshlrev_b32_e32 v134, 16, v55
	v_and_b32_e32 v135, 0xffff0000, v55
	v_mul_f32_e32 v138, v120, v120
	v_mul_f32_e32 v149, v121, v121
	v_mul_f32_e32 v150, v122, v122
	v_mul_f32_e32 v154, v123, v123
	v_fma_f32 v138, v124, v124, v138
	v_fma_f32 v149, v125, v125, v149
	v_fma_f32 v150, v126, v126, v150
	v_fma_f32 v154, v127, v127, v154
	v_fma_f32 v138, v128, v128, v138
	v_fma_f32 v149, v129, v129, v149
	v_fma_f32 v150, v130, v130, v150
	v_fma_f32 v154, v131, v131, v154
	v_fma_f32 v138, v132, v132, v138
	v_fma_f32 v149, v133, v133, v149
	v_fma_f32 v150, v134, v134, v150
	v_fma_f32 v154, v135, v135, v154
	v_add_f32_e32 v138, v138, v149
	v_add_f32_e32 v150, v150, v154
	v_add_f32_e32 v138, v138, v150
	s_nop 1
	v_add_f32_dpp v138, v138, v138 quad_perm:[1,0,3,2] row_mask:0xf bank_mask:0xf
	s_nop 1
	v_add_f32_dpp v138, v138, v138 quad_perm:[2,3,0,1] row_mask:0xf bank_mask:0xf
	s_nop 1
	v_add_f32_dpp v138, v138, v138 row_half_mirror row_mask:0xf bank_mask:0xf
	s_nop 1
	v_add_f32_dpp v138, v138, v138 row_mirror row_mask:0xf bank_mask:0xf
	v_mov_b32_e32 v139, v138
	s_nop 1
	v_permlane16_swap_b32_e32 v138, v139
	v_add_f32_e32 v138, v138, v139
	v_mov_b32_e32 v139, v138
	s_nop 1
	v_permlane32_swap_b32_e32 v138, v139
	v_add_f32_e32 v138, v138, v139
	v_mul_f32_e32 v138, 0x3a800000, v138
	v_add_f32_e32 v138, 0x358637bd, v138
	v_rsq_f32_e32 v140, v138
	v_lshlrev_b32_e32 v0, 16, v8
	v_and_b32_e32 v1, 0xffff0000, v8
	v_lshlrev_b32_e32 v2, 16, v9
	v_and_b32_e32 v3, 0xffff0000, v9
	v_lshlrev_b32_e32 v4, 16, v10
	v_and_b32_e32 v5, 0xffff0000, v10
	v_lshlrev_b32_e32 v6, 16, v11
	v_and_b32_e32 v7, 0xffff0000, v11
	v_lshlrev_b32_e32 v8, 16, v12
	v_and_b32_e32 v9, 0xffff0000, v12
	v_lshlrev_b32_e32 v10, 16, v13
	v_and_b32_e32 v11, 0xffff0000, v13
	v_lshlrev_b32_e32 v12, 16, v14
	v_and_b32_e32 v13, 0xffff0000, v14
	v_lshlrev_b32_e32 v14, 16, v15
	v_and_b32_e32 v15, 0xffff0000, v15
	s_nop 0
	v_mul_f32_e32 v120, v120, v140
	v_mul_f32_e32 v121, v121, v140
	v_mul_f32_e32 v122, v122, v140
	v_mul_f32_e32 v123, v123, v140
	v_mul_f32_e32 v124, v124, v140
	v_mul_f32_e32 v125, v125, v140
	v_mul_f32_e32 v126, v126, v140
	v_mul_f32_e32 v127, v127, v140
	v_mul_f32_e32 v128, v128, v140
	v_mul_f32_e32 v129, v129, v140
	v_mul_f32_e32 v130, v130, v140
	v_mul_f32_e32 v131, v131, v140
	v_mul_f32_e32 v132, v132, v140
	v_mul_f32_e32 v133, v133, v140
	v_mul_f32_e32 v134, v134, v140
	v_mul_f32_e32 v135, v135, v140
	v_fma_f32 v0, v120, v72, v0
	v_fma_f32 v1, v121, v73, v1
	v_fma_f32 v2, v122, v74, v2
	v_fma_f32 v3, v123, v75, v3
	v_fma_f32 v4, v124, v76, v4
	v_fma_f32 v5, v125, v77, v5
	v_fma_f32 v6, v126, v78, v6
	v_fma_f32 v7, v127, v79, v7
	v_fma_f32 v8, v128, v80, v8
	v_fma_f32 v9, v129, v81, v9
	v_fma_f32 v10, v130, v82, v10
	v_fma_f32 v11, v131, v83, v11
	v_fma_f32 v12, v132, v84, v12
	v_fma_f32 v13, v133, v85, v13
	v_fma_f32 v14, v134, v86, v14
	v_fma_f32 v15, v135, v87, v15
	s_lshl_b32 vcc_lo, s19, 12
	s_add_u32 vcc_lo, vcc_lo, 0x7800000
	s_add_u32 s100, s16, vcc_lo
	s_addc_u32 s101, s17, 0
	global_store_dwordx4 v136, v[0:3], s[100:101] offset:0
	global_store_dwordx4 v136, v[4:7], s[100:101] offset:1024
	global_store_dwordx4 v136, v[8:11], s[100:101] offset:2048
	global_store_dwordx4 v136, v[12:15], s[100:101] offset:3072
	s_branch .LBB0_1962
